# GEMM loops: per-phase counted DMA waits one stage deeper (vmcnt 8, and 10 in phase 4) instead of 10/12; otherwise as the ych version
# baseline (speedup 1.0000x reference)
; #define PG8_STAGE(bufoff, gbase, voff) do { _Pragma("unroll") for (int _i = 0; _i < 2; ++_i) \
;         __builtin_amdgcn_global_load_lds((const unsigned*)((const char*)(gbase) + (voff)[_i]), (LAS unsigned*)(lds + (bufoff) + ldsw + _i * 8192), 16, 0, 0); } while (0)
; #define PG8_LDA(dst, b, h) do { _Pragma("unroll") for (int m = 0; m < 4; ++m) _Pragma("unroll") for (int k = 0; k < 2; ++k) dst[m][k] = *(const LAS bf16x8*)(lds + PG8_SA(b, h) + aoff + m * 2048 + k * 1024); } while (0)
; #define PG8_LDB(dst, b, h) do { _Pragma("unroll") for (int n = 0; n < 2; ++n) _Pragma("unroll") for (int k = 0; k < 2; ++k) dst[n][k] = *(const LAS bf16x8*)(lds + PG8_SB(b, h) + boff + n * 2048 + k * 1024); } while (0)
; #define PG8_MMA(ai, bj, At, Bt) do { __builtin_amdgcn_s_setprio(1); _Pragma("unroll") for (int m = 0; m < 4; ++m) _Pragma("unroll") for (int n = 0; n < 2; ++n) _Pragma("unroll") for (int k = 0; k < 2; ++k) \
;         acc[ai][bj][m][n] = __builtin_amdgcn_mfma_f32_16x16x32_bf16(Bt[n][k], At[m][k], acc[ai][bj][m][n], 0, 0, 0); __builtin_amdgcn_s_setprio(0); } while (0)
; #define PG8_WAIT_L(n) asm volatile("s_waitcnt lgkmcnt(" #n ")" ::: "memory")
; template <class Epi, class Sched>
; __device__ __forceinline__ void gemm_phase(LAS unsigned char* lds, const Gemm g, const Sched& S, const Epi& E) {
;     ...
;     for (;;) {
;         const bool has_next = S.next(ui + 1, nxt);
;         const char* nA = has_next ? (const char*)g.A + (size_t)nxt.pm * tstep : cA; const char* nB = has_next ? (const char*)g.Bt + (size_t)nxt.pn * tstep : cB;
;         for (int t = 0; t < nt; t += 2) {
;             const bool last = (t == nt - 2);
;             const char* a1 = cA + (size_t)(t + 1) * kstep;
;             const char* a2 = last ? nA : cA + (size_t)(t + 2) * kstep; const char* b2 = last ? nB : cB + (size_t)(t + 2) * kstep;
;             const char* a3 = a2 + kstep; const char* b3 = b2 + kstep;
;             PG8_LDB(B0, 0, 0); PG8_SCHED; PG8_LDA(At, 0, 0); PG8_STAGE(PG8_SA(1, 1), a1 + hstep, voffA);
;             PG8_WAIT_L(8); PG8_BAR; PG8_WAIT_L(0); PG8_MMA(0, 0, At, B0); PG8_BAR; PG8_SCHED;
;             PG8_LDB(B1, 0, 1); PG8_STAGE(PG8_SB(0, 0), b2, voffB);
;             PG8_BAR; PG8_WAIT_L(0); PG8_MMA(0, 1, At, B1); PG8_BAR;
;             PG8_LDA(At, 0, 1); PG8_STAGE(PG8_SA(0, 0), a2, voffA);
;             PG8_BAR; PG8_WAIT_L(0); PG8_MMA(1, 0, At, B0); PG8_BAR; PG8_SCHED;
.LBB0_234:
	s_ashr_i32 s7, s6, 31
	v_cmp_lt_i64_e32 vcc, s[8:9], v[140:141]
	s_lshl_b64 s[8:9], s[6:7], 19
	s_add_u32 s8, s96, s8
	s_addc_u32 s9, s97, s9
	s_and_b64 s[10:11], vcc, exec
	s_cselect_b32 s7, s9, s15
	s_cselect_b32 s44, s8, s14
	s_ashr_i32 s5, s4, 31
	s_lshl_b64 s[10:11], s[4:5], 19
	s_add_u32 s10, s72, s10
	s_addc_u32 s11, s73, s11
	s_and_b64 s[16:17], vcc, exec
	s_cselect_b32 s5, s11, s19
	s_cselect_b32 s45, s10, s18
	s_add_u32 s14, s14, 0x40080
	s_addc_u32 s15, s15, 0
	s_add_u32 s46, s18, 0x100
	s_addc_u32 s47, s19, 0
	s_mov_b32 s48, -2
	ds_read_b128 v[150:153], v147
	ds_read_b128 v[154:157], v147 offset:1024
	ds_read_b128 v[158:161], v147 offset:2048
	ds_read_b128 v[162:165], v147 offset:3072
	s_add_u32 s16, s14, 0xfffc0080
	s_addc_u32 s17, s15, -1
	s_cmp_eq_u32 s48, 12
	s_cselect_b32 s23, s7, s17
	s_cselect_b32 s22, s44, s16
	s_cselect_b32 s19, s5, s47
	s_cselect_b32 s18, s45, s46
	s_add_i32 m0, s13, 0xc000
	ds_read_b128 v[166:169], v148
	ds_read_b128 v[170:173], v148 offset:1024
	ds_read_b128 v[174:177], v148 offset:2048
	ds_read_b128 v[178:181], v148 offset:3072
	ds_read_b128 v[182:185], v148 offset:4096
	ds_read_b128 v[186:189], v148 offset:5120
	ds_read_b128 v[190:193], v148 offset:6144
	ds_read_b128 v[194:197], v148 offset:7168
	global_load_lds_dwordx4 v136, s[14:15]
	s_add_i32 m0, s13, 0xe000
	s_nop 0
	global_load_lds_dwordx4 v138, s[14:15]
	s_waitcnt lgkmcnt(8)
	s_waitcnt vmcnt(8)
	s_barrier
	s_waitcnt lgkmcnt(0)
	s_setprio 1
	s_waitcnt lgkmcnt(0)
	v_mfma_f32_16x16x32_bf16 v[124:127], v[150:153], v[166:169], 0
	v_mfma_f32_16x16x32_bf16 v[116:119], v[158:161], v[166:169], 0
	v_mfma_f32_16x16x32_bf16 v[108:111], v[150:153], v[174:177], 0
	v_mfma_f32_16x16x32_bf16 v[100:103], v[158:161], v[174:177], 0
	v_mfma_f32_16x16x32_bf16 v[92:95], v[150:153], v[182:185], 0
	v_mfma_f32_16x16x32_bf16 v[84:87], v[158:161], v[182:185], 0
	v_mfma_f32_16x16x32_bf16 v[76:79], v[150:153], v[190:193], 0
	v_mfma_f32_16x16x32_bf16 v[68:71], v[158:161], v[190:193], 0
	v_mfma_f32_16x16x32_bf16 v[124:127], v[154:157], v[170:173], v[124:127]
	v_mfma_f32_16x16x32_bf16 v[116:119], v[162:165], v[170:173], v[116:119]
	v_mfma_f32_16x16x32_bf16 v[108:111], v[154:157], v[178:181], v[108:111]
	v_mfma_f32_16x16x32_bf16 v[100:103], v[162:165], v[178:181], v[100:103]
	v_mfma_f32_16x16x32_bf16 v[92:95], v[154:157], v[186:189], v[92:95]
	v_mfma_f32_16x16x32_bf16 v[84:87], v[162:165], v[186:189], v[84:87]
	v_mfma_f32_16x16x32_bf16 v[76:79], v[154:157], v[194:197], v[76:79]
	v_mfma_f32_16x16x32_bf16 v[68:71], v[162:165], v[194:197], v[68:71]
	s_setprio 0
	s_barrier
	s_add_i32 s16, s40, s25
	s_mov_b32 m0, s16
	ds_read_b128 v[202:205], v149
	ds_read_b128 v[206:209], v149 offset:1024
	ds_read_b128 v[210:213], v149 offset:2048
	ds_read_b128 v[214:217], v149 offset:3072
	global_load_lds_dwordx4 v132, s[18:19]
	s_add_i32 m0, s16, 0x2000
	s_nop 0
	global_load_lds_dwordx4 v128, s[18:19]
	s_waitcnt vmcnt(8)
	s_barrier
	s_waitcnt lgkmcnt(0)
	s_setprio 1
	s_waitcnt lgkmcnt(0)
	v_mfma_f32_16x16x32_bf16 v[120:123], v[202:205], v[166:169], 0
	v_mfma_f32_16x16x32_bf16 v[112:115], v[210:213], v[166:169], 0
	v_mfma_f32_16x16x32_bf16 v[104:107], v[202:205], v[174:177], 0
	v_mfma_f32_16x16x32_bf16 v[96:99], v[210:213], v[174:177], 0
	v_mfma_f32_16x16x32_bf16 v[88:91], v[202:205], v[182:185], 0
	v_mfma_f32_16x16x32_bf16 v[80:83], v[210:213], v[182:185], 0
	v_mfma_f32_16x16x32_bf16 v[72:75], v[202:205], v[190:193], 0
	v_mfma_f32_16x16x32_bf16 v[64:67], v[210:213], v[190:193], 0
	v_mfma_f32_16x16x32_bf16 v[120:123], v[206:209], v[170:173], v[120:123]
	v_mfma_f32_16x16x32_bf16 v[112:115], v[214:217], v[170:173], v[112:115]
	v_mfma_f32_16x16x32_bf16 v[104:107], v[206:209], v[178:181], v[104:107]
	v_mfma_f32_16x16x32_bf16 v[96:99], v[214:217], v[178:181], v[96:99]
	v_mfma_f32_16x16x32_bf16 v[88:91], v[206:209], v[186:189], v[88:91]
	v_mfma_f32_16x16x32_bf16 v[80:83], v[214:217], v[186:189], v[80:83]
	v_mfma_f32_16x16x32_bf16 v[72:75], v[206:209], v[194:197], v[72:75]
	v_mfma_f32_16x16x32_bf16 v[64:67], v[214:217], v[194:197], v[64:67]
	s_setprio 0
	s_mov_b32 m0, s13
	s_barrier
	ds_read_b128 v[166:169], v148 offset:16384
	ds_read_b128 v[170:173], v148 offset:17408
	ds_read_b128 v[174:177], v148 offset:18432
	ds_read_b128 v[178:181], v148 offset:19456
	ds_read_b128 v[182:185], v148 offset:20480
	ds_read_b128 v[186:189], v148 offset:21504
	ds_read_b128 v[190:193], v148 offset:22528
	ds_read_b128 v[194:197], v148 offset:23552
	global_load_lds_dwordx4 v134, s[22:23]
	s_mov_b32 m0, s28
	s_nop 0
	global_load_lds_dwordx4 v130, s[22:23]
	s_barrier
	s_waitcnt lgkmcnt(0)
	s_setprio 1
	s_waitcnt lgkmcnt(0)
	v_mfma_f32_16x16x32_bf16 v[60:63], v[150:153], v[166:169], 0
	v_mfma_f32_16x16x32_bf16 v[56:59], v[158:161], v[166:169], 0
	v_mfma_f32_16x16x32_bf16 v[44:47], v[150:153], v[174:177], 0
	v_mfma_f32_16x16x32_bf16 v[40:43], v[158:161], v[174:177], 0
	v_mfma_f32_16x16x32_bf16 v[28:31], v[150:153], v[182:185], 0
	v_mfma_f32_16x16x32_bf16 v[24:27], v[158:161], v[182:185], 0
	v_mfma_f32_16x16x32_bf16 v[12:15], v[150:153], v[190:193], 0
	v_mfma_f32_16x16x32_bf16 v[8:11], v[158:161], v[190:193], 0
	v_mfma_f32_16x16x32_bf16 v[60:63], v[154:157], v[170:173], v[60:63]
	v_mfma_f32_16x16x32_bf16 v[56:59], v[162:165], v[170:173], v[56:59]
	v_mfma_f32_16x16x32_bf16 v[44:47], v[154:157], v[178:181], v[44:47]
	v_mfma_f32_16x16x32_bf16 v[40:43], v[162:165], v[178:181], v[40:43]
	v_mfma_f32_16x16x32_bf16 v[28:31], v[154:157], v[186:189], v[28:31]
	v_mfma_f32_16x16x32_bf16 v[24:27], v[162:165], v[186:189], v[24:27]
	v_mfma_f32_16x16x32_bf16 v[12:15], v[154:157], v[194:197], v[12:15]
	v_mfma_f32_16x16x32_bf16 v[8:11], v[162:165], v[194:197], v[8:11]
	s_setprio 0
	s_barrier
; #define PG8_STAGE(bufoff, gbase, voff) do { _Pragma("unroll") for (int _i = 0; _i < 2; ++_i) \
;         __builtin_amdgcn_global_load_lds((const unsigned*)((const char*)(gbase) + (voff)[_i]), (LAS unsigned*)(lds + (bufoff) + ldsw + _i * 8192), 16, 0, 0); } while (0)
; #define PG8_LDA(dst, b, h) do { _Pragma("unroll") for (int m = 0; m < 4; ++m) _Pragma("unroll") for (int k = 0; k < 2; ++k) dst[m][k] = *(const LAS bf16x8*)(lds + PG8_SA(b, h) + aoff + m * 2048 + k * 1024); } while (0)
; #define PG8_LDB(dst, b, h) do { _Pragma("unroll") for (int n = 0; n < 2; ++n) _Pragma("unroll") for (int k = 0; k < 2; ++k) dst[n][k] = *(const LAS bf16x8*)(lds + PG8_SB(b, h) + boff + n * 2048 + k * 1024); } while (0)
; #define PG8_MMA(ai, bj, At, Bt) do { __builtin_amdgcn_s_setprio(1); _Pragma("unroll") for (int m = 0; m < 4; ++m) _Pragma("unroll") for (int n = 0; n < 2; ++n) _Pragma("unroll") for (int k = 0; k < 2; ++k) \
;         acc[ai][bj][m][n] = __builtin_amdgcn_mfma_f32_16x16x32_bf16(Bt[n][k], At[m][k], acc[ai][bj][m][n], 0, 0, 0); __builtin_amdgcn_s_setprio(0); } while (0)
; #define PG8_WAIT_V(n) asm volatile("s_waitcnt vmcnt(" #n ")" ::: "memory")
; #define PG8_WAIT_L(n) asm volatile("s_waitcnt lgkmcnt(" #n ")" ::: "memory")
; #define PG8_BAR __builtin_amdgcn_s_barrier()
; #define PG8_SCHED __builtin_amdgcn_sched_barrier(0)
; template <class Epi, class Sched>
; __device__ __forceinline__ void gemm_phase(LAS unsigned char* lds, const Gemm g, const Sched& S, const Epi& E) {
;     ...
;             PG8_STAGE(PG8_SB(0, 1), b2 + hstep, voffB);
;             PG8_WAIT_V(6); PG8_BAR; PG8_MMA(1, 1, At, B1); PG8_BAR;
;             PG8_LDB(B0, 1, 0); PG8_SCHED; PG8_LDA(At, 1, 0); PG8_STAGE(PG8_SA(0, 1), a2 + hstep, voffA);
;             PG8_WAIT_L(8); PG8_BAR; PG8_WAIT_L(0); PG8_MMA(0, 0, At, B0); PG8_BAR; PG8_SCHED;
;             PG8_LDB(B1, 1, 1); PG8_STAGE(PG8_SB(1, 0), b3, voffB);
;             PG8_BAR; PG8_WAIT_L(0); PG8_MMA(0, 1, At, B1); PG8_BAR;
;             PG8_LDA(At, 1, 1); PG8_STAGE(PG8_SA(1, 0), a3, voffA);
;             PG8_BAR; PG8_WAIT_L(0); PG8_MMA(1, 0, At, B0); PG8_BAR; PG8_SCHED;
;             PG8_STAGE(PG8_SB(1, 1), b3 + hstep, voffB);
;             PG8_WAIT_V(6); PG8_BAR; PG8_MMA(1, 1, At, B1); PG8_BAR;
	s_add_u32 s16, s18, 0x40000
	s_addc_u32 s17, s19, 0
	s_add_i32 s20, s41, s25
	s_mov_b32 m0, s20
	s_nop 0
	global_load_lds_dwordx4 v132, s[16:17]
	s_add_i32 m0, s20, 0x2000
	s_nop 0
	global_load_lds_dwordx4 v128, s[16:17]
	s_add_u32 s16, s22, 0x40000
	s_addc_u32 s17, s23, 0
	s_mov_b32 m0, s29
	s_nop 0
	global_load_lds_dwordx4 v134, s[16:17]
	s_mov_b32 m0, s33
	s_nop 0
	global_load_lds_dwordx4 v130, s[16:17]
	s_waitcnt vmcnt(10)
	s_barrier
	s_setprio 1
	v_mfma_f32_16x16x32_bf16 v[52:55], v[202:205], v[166:169], 0
	v_mfma_f32_16x16x32_bf16 v[48:51], v[210:213], v[166:169], 0
	v_mfma_f32_16x16x32_bf16 v[36:39], v[202:205], v[174:177], 0
	v_mfma_f32_16x16x32_bf16 v[32:35], v[210:213], v[174:177], 0
	v_mfma_f32_16x16x32_bf16 v[20:23], v[202:205], v[182:185], 0
	v_mfma_f32_16x16x32_bf16 v[16:19], v[210:213], v[182:185], 0
	v_mfma_f32_16x16x32_bf16 v[4:7], v[202:205], v[190:193], 0
	v_mfma_f32_16x16x32_bf16 v[0:3], v[210:213], v[190:193], 0
	v_mfma_f32_16x16x32_bf16 v[52:55], v[206:209], v[170:173], v[52:55]
	v_mfma_f32_16x16x32_bf16 v[48:51], v[214:217], v[170:173], v[48:51]
	v_mfma_f32_16x16x32_bf16 v[36:39], v[206:209], v[178:181], v[36:39]
	v_mfma_f32_16x16x32_bf16 v[32:35], v[214:217], v[178:181], v[32:35]
	v_mfma_f32_16x16x32_bf16 v[20:23], v[206:209], v[186:189], v[20:23]
	v_mfma_f32_16x16x32_bf16 v[16:19], v[214:217], v[186:189], v[16:19]
	v_mfma_f32_16x16x32_bf16 v[4:7], v[206:209], v[194:197], v[4:7]
	v_mfma_f32_16x16x32_bf16 v[0:3], v[214:217], v[194:197], v[0:3]
	s_setprio 0
	s_add_i32 s20, 0, 0x18000
	v_add_u32_e32 v162, s20, v146
	s_barrier
	ds_read_b128 v[150:153], v162
	ds_read_b128 v[154:157], v162 offset:1024
	ds_read_b128 v[158:161], v162 offset:2048
	ds_read_b128 v[162:165], v162 offset:3072
	ds_read_b128 v[166:169], v148 offset:32768
	ds_read_b128 v[170:173], v148 offset:33792
	ds_read_b128 v[174:177], v148 offset:34816
	ds_read_b128 v[178:181], v148 offset:35840
	ds_read_b128 v[182:185], v148 offset:36864
	ds_read_b128 v[186:189], v148 offset:37888
	ds_read_b128 v[190:193], v148 offset:38912
	ds_read_b128 v[194:197], v148 offset:39936
	s_waitcnt lgkmcnt(8)
	s_waitcnt vmcnt(8)
	s_barrier
	s_waitcnt lgkmcnt(0)
	s_setprio 1
	s_waitcnt lgkmcnt(0)
	v_mfma_f32_16x16x32_bf16 v[124:127], v[150:153], v[166:169], v[124:127]
	v_mfma_f32_16x16x32_bf16 v[116:119], v[158:161], v[166:169], v[116:119]
	v_mfma_f32_16x16x32_bf16 v[108:111], v[150:153], v[174:177], v[108:111]
	v_mfma_f32_16x16x32_bf16 v[100:103], v[158:161], v[174:177], v[100:103]
	v_mfma_f32_16x16x32_bf16 v[92:95], v[150:153], v[182:185], v[92:95]
	v_mfma_f32_16x16x32_bf16 v[84:87], v[158:161], v[182:185], v[84:87]
	v_mfma_f32_16x16x32_bf16 v[76:79], v[150:153], v[190:193], v[76:79]
	v_mfma_f32_16x16x32_bf16 v[68:71], v[158:161], v[190:193], v[68:71]
	v_mfma_f32_16x16x32_bf16 v[124:127], v[154:157], v[170:173], v[124:127]
	v_mfma_f32_16x16x32_bf16 v[116:119], v[162:165], v[170:173], v[116:119]
	v_mfma_f32_16x16x32_bf16 v[108:111], v[154:157], v[178:181], v[108:111]
	v_mfma_f32_16x16x32_bf16 v[100:103], v[162:165], v[178:181], v[100:103]
	v_mfma_f32_16x16x32_bf16 v[92:95], v[154:157], v[186:189], v[92:95]
	v_mfma_f32_16x16x32_bf16 v[84:87], v[162:165], v[186:189], v[84:87]
	v_mfma_f32_16x16x32_bf16 v[76:79], v[154:157], v[194:197], v[76:79]
	v_mfma_f32_16x16x32_bf16 v[68:71], v[162:165], v[194:197], v[68:71]
	s_setprio 0
	s_barrier
	s_add_i32 s21, 0, 0x1c000
	s_add_i32 s16, s20, s25
	v_add_u32_e32 v214, s21, v146
	s_add_u32 s0, s18, 0x80
	s_addc_u32 s1, s19, 0
	s_mov_b32 m0, s16
	ds_read_b128 v[202:205], v214
	ds_read_b128 v[206:209], v214 offset:1024
	ds_read_b128 v[210:213], v214 offset:2048
	ds_read_b128 v[214:217], v214 offset:3072
	global_load_lds_dwordx4 v132, s[0:1]
	s_add_i32 m0, s16, 0x2000
	s_nop 0
	global_load_lds_dwordx4 v128, s[0:1]
	s_waitcnt vmcnt(8)
	s_barrier
	s_waitcnt lgkmcnt(0)
	s_setprio 1
	s_waitcnt lgkmcnt(0)
	v_mfma_f32_16x16x32_bf16 v[120:123], v[202:205], v[166:169], v[120:123]
	v_mfma_f32_16x16x32_bf16 v[112:115], v[210:213], v[166:169], v[112:115]
	v_mfma_f32_16x16x32_bf16 v[104:107], v[202:205], v[174:177], v[104:107]
	v_mfma_f32_16x16x32_bf16 v[96:99], v[210:213], v[174:177], v[96:99]
	v_mfma_f32_16x16x32_bf16 v[88:91], v[202:205], v[182:185], v[88:91]
	v_mfma_f32_16x16x32_bf16 v[80:83], v[210:213], v[182:185], v[80:83]
	v_mfma_f32_16x16x32_bf16 v[72:75], v[202:205], v[190:193], v[72:75]
	v_mfma_f32_16x16x32_bf16 v[64:67], v[210:213], v[190:193], v[64:67]
	v_mfma_f32_16x16x32_bf16 v[120:123], v[206:209], v[170:173], v[120:123]
	v_mfma_f32_16x16x32_bf16 v[112:115], v[214:217], v[170:173], v[112:115]
	v_mfma_f32_16x16x32_bf16 v[104:107], v[206:209], v[178:181], v[104:107]
	v_mfma_f32_16x16x32_bf16 v[96:99], v[214:217], v[178:181], v[96:99]
	v_mfma_f32_16x16x32_bf16 v[88:91], v[206:209], v[186:189], v[88:91]
	v_mfma_f32_16x16x32_bf16 v[80:83], v[214:217], v[186:189], v[80:83]
	v_mfma_f32_16x16x32_bf16 v[72:75], v[206:209], v[194:197], v[72:75]
	v_mfma_f32_16x16x32_bf16 v[64:67], v[214:217], v[194:197], v[64:67]
	s_setprio 0
	s_mov_b32 m0, s36
	s_add_u32 s0, s22, 0x80
	s_addc_u32 s1, s23, 0
	s_barrier
	ds_read_b128 v[166:169], v148 offset:49152
	ds_read_b128 v[170:173], v148 offset:50176
	ds_read_b128 v[174:177], v148 offset:51200
	ds_read_b128 v[178:181], v148 offset:52224
	ds_read_b128 v[182:185], v148 offset:53248
	ds_read_b128 v[186:189], v148 offset:54272
	ds_read_b128 v[190:193], v148 offset:55296
	ds_read_b128 v[194:197], v148 offset:56320
	global_load_lds_dwordx4 v134, s[0:1]
	s_mov_b32 m0, s37
	s_nop 0
	global_load_lds_dwordx4 v130, s[0:1]
	s_barrier
; #define PG8_STAGE(bufoff, gbase, voff) do { _Pragma("unroll") for (int _i = 0; _i < 2; ++_i) \
;         __builtin_amdgcn_global_load_lds((const unsigned*)((const char*)(gbase) + (voff)[_i]), (LAS unsigned*)(lds + (bufoff) + ldsw + _i * 8192), 16, 0, 0); } while (0)
; #define PG8_LDA(dst, b, h) do { _Pragma("unroll") for (int m = 0; m < 4; ++m) _Pragma("unroll") for (int k = 0; k < 2; ++k) dst[m][k] = *(const LAS bf16x8*)(lds + PG8_SA(b, h) + aoff + m * 2048 + k * 1024); } while (0)
; #define PG8_LDB(dst, b, h) do { _Pragma("unroll") for (int n = 0; n < 2; ++n) _Pragma("unroll") for (int k = 0; k < 2; ++k) dst[n][k] = *(const LAS bf16x8*)(lds + PG8_SB(b, h) + boff + n * 2048 + k * 1024); } while (0)
; #define PG8_WAIT_V(n) asm volatile("s_waitcnt vmcnt(" #n ")" ::: "memory")
; #define PG8_WAIT_L(n) asm volatile("s_waitcnt lgkmcnt(" #n ")" ::: "memory")
; #define PG8_BAR __builtin_amdgcn_s_barrier()
; #define PG8_SCHED __builtin_amdgcn_sched_barrier(0)
; template <class Epi, class Sched>
; __device__ __forceinline__ void gemm_phase(LAS unsigned char* lds, const Gemm g, const Sched& S, const Epi& E) {
;     ...
;             PG8_LDB(B0, 0, 0); PG8_SCHED; PG8_LDA(At, 0, 0); PG8_STAGE(PG8_SA(1, 1), a1 + hstep, voffA);
;             PG8_WAIT_L(8); PG8_BAR; PG8_WAIT_L(0); PG8_MMA(0, 0, At, B0); PG8_BAR; PG8_SCHED;
;             PG8_LDB(B1, 0, 1); PG8_STAGE(PG8_SB(0, 0), b2, voffB);
;             PG8_BAR; PG8_WAIT_L(0); PG8_MMA(0, 1, At, B1); PG8_BAR;
;             PG8_LDA(At, 0, 1); PG8_STAGE(PG8_SA(0, 0), a2, voffA);
;             PG8_BAR; PG8_WAIT_L(0); PG8_MMA(1, 0, At, B0); PG8_BAR; PG8_SCHED;
;             PG8_STAGE(PG8_SB(0, 1), b2 + hstep, voffB);
;             PG8_WAIT_V(6); PG8_BAR; PG8_MMA(1, 1, At, B1); PG8_BAR;
;             PG8_LDB(B0, 1, 0); PG8_SCHED; PG8_LDA(At, 1, 0); PG8_STAGE(PG8_SA(0, 1), a2 + hstep, voffA);
;             PG8_WAIT_L(8); PG8_BAR; PG8_WAIT_L(0); PG8_MMA(0, 0, At, B0); PG8_BAR; PG8_SCHED;
;             PG8_LDB(B1, 1, 1); PG8_STAGE(PG8_SB(1, 0), b3, voffB);
;             PG8_BAR; PG8_WAIT_L(0); PG8_MMA(0, 1, At, B1); PG8_BAR;
;             PG8_LDA(At, 1, 1); PG8_STAGE(PG8_SA(1, 0), a3, voffA);
;             PG8_BAR; PG8_WAIT_L(0); PG8_MMA(1, 0, At, B0); PG8_BAR; PG8_SCHED;
;             PG8_STAGE(PG8_SB(1, 1), b3 + hstep, voffB);
;             PG8_WAIT_V(6); PG8_BAR; PG8_MMA(1, 1, At, B1); PG8_BAR;
	s_waitcnt lgkmcnt(0)
	s_setprio 1
	s_waitcnt lgkmcnt(0)
	v_mfma_f32_16x16x32_bf16 v[60:63], v[150:153], v[166:169], v[60:63]
	v_mfma_f32_16x16x32_bf16 v[56:59], v[158:161], v[166:169], v[56:59]
	v_mfma_f32_16x16x32_bf16 v[44:47], v[150:153], v[174:177], v[44:47]
	v_mfma_f32_16x16x32_bf16 v[40:43], v[158:161], v[174:177], v[40:43]
	v_mfma_f32_16x16x32_bf16 v[28:31], v[150:153], v[182:185], v[28:31]
	v_mfma_f32_16x16x32_bf16 v[24:27], v[158:161], v[182:185], v[24:27]
	v_mfma_f32_16x16x32_bf16 v[12:15], v[150:153], v[190:193], v[12:15]
	v_mfma_f32_16x16x32_bf16 v[8:11], v[158:161], v[190:193], v[8:11]
	v_mfma_f32_16x16x32_bf16 v[60:63], v[154:157], v[170:173], v[60:63]
	v_mfma_f32_16x16x32_bf16 v[56:59], v[162:165], v[170:173], v[56:59]
	v_mfma_f32_16x16x32_bf16 v[44:47], v[154:157], v[178:181], v[44:47]
	v_mfma_f32_16x16x32_bf16 v[40:43], v[162:165], v[178:181], v[40:43]
	v_mfma_f32_16x16x32_bf16 v[28:31], v[154:157], v[186:189], v[28:31]
	v_mfma_f32_16x16x32_bf16 v[24:27], v[162:165], v[186:189], v[24:27]
	v_mfma_f32_16x16x32_bf16 v[12:15], v[154:157], v[194:197], v[12:15]
	v_mfma_f32_16x16x32_bf16 v[8:11], v[162:165], v[194:197], v[8:11]
	s_setprio 0
	s_barrier
	s_add_u32 s16, s18, 0x40080
	s_addc_u32 s17, s19, 0
	s_add_i32 s18, s21, s25
	s_mov_b32 m0, s18
	s_nop 0
	global_load_lds_dwordx4 v132, s[16:17]
	s_add_i32 m0, s18, 0x2000
	s_nop 0
	global_load_lds_dwordx4 v128, s[16:17]
	s_waitcnt vmcnt(8)
	s_barrier
	s_setprio 1
	v_mfma_f32_16x16x32_bf16 v[52:55], v[202:205], v[166:169], v[52:55]
	v_mfma_f32_16x16x32_bf16 v[48:51], v[210:213], v[166:169], v[48:51]
	v_mfma_f32_16x16x32_bf16 v[36:39], v[202:205], v[174:177], v[36:39]
	v_mfma_f32_16x16x32_bf16 v[32:35], v[210:213], v[174:177], v[32:35]
	v_mfma_f32_16x16x32_bf16 v[20:23], v[202:205], v[182:185], v[20:23]
	v_mfma_f32_16x16x32_bf16 v[16:19], v[210:213], v[182:185], v[16:19]
	v_mfma_f32_16x16x32_bf16 v[4:7], v[202:205], v[190:193], v[4:7]
	v_mfma_f32_16x16x32_bf16 v[0:3], v[210:213], v[190:193], v[0:3]
	v_mfma_f32_16x16x32_bf16 v[52:55], v[206:209], v[170:173], v[52:55]
	v_mfma_f32_16x16x32_bf16 v[48:51], v[214:217], v[170:173], v[48:51]
	v_mfma_f32_16x16x32_bf16 v[36:39], v[206:209], v[178:181], v[36:39]
	v_mfma_f32_16x16x32_bf16 v[32:35], v[214:217], v[178:181], v[32:35]
	v_mfma_f32_16x16x32_bf16 v[20:23], v[206:209], v[186:189], v[20:23]
	v_mfma_f32_16x16x32_bf16 v[16:19], v[214:217], v[186:189], v[16:19]
	v_mfma_f32_16x16x32_bf16 v[4:7], v[206:209], v[194:197], v[4:7]
	v_mfma_f32_16x16x32_bf16 v[0:3], v[214:217], v[194:197], v[0:3]
	s_setprio 0
	s_add_i32 s48, s48, 2
	s_add_u32 s14, s14, 0x100
	s_addc_u32 s15, s15, 0
	s_add_u32 s46, s46, 0x100
	s_addc_u32 s47, s47, 0
	s_cmp_gt_u32 s48, 13
	s_barrier
.LBB0_235:
	ds_read_b128 v[150:153], v147
	ds_read_b128 v[154:157], v147 offset:1024
	ds_read_b128 v[158:161], v147 offset:2048
	ds_read_b128 v[162:165], v147 offset:3072
	s_add_u32 s16, s14, 0xfffc0080
	s_addc_u32 s17, s15, -1
	s_cmp_eq_u32 s48, 12
	s_cselect_b32 s23, s7, s17
	s_cselect_b32 s22, s44, s16
	s_cselect_b32 s19, s5, s47
	s_cselect_b32 s18, s45, s46
	s_add_i32 m0, s13, 0xc000
	ds_read_b128 v[166:169], v148
	ds_read_b128 v[170:173], v148 offset:1024
	ds_read_b128 v[174:177], v148 offset:2048
	ds_read_b128 v[178:181], v148 offset:3072
	ds_read_b128 v[182:185], v148 offset:4096
	ds_read_b128 v[186:189], v148 offset:5120
	ds_read_b128 v[190:193], v148 offset:6144
	ds_read_b128 v[194:197], v148 offset:7168
	global_load_lds_dwordx4 v136, s[14:15]
	s_add_i32 m0, s13, 0xe000
	s_nop 0
	global_load_lds_dwordx4 v138, s[14:15]
	s_waitcnt lgkmcnt(8)
	s_waitcnt vmcnt(8)
	s_barrier
	s_waitcnt lgkmcnt(0)
	s_setprio 1
	s_waitcnt lgkmcnt(0)
	v_mfma_f32_16x16x32_bf16 v[124:127], v[150:153], v[166:169], v[124:127]
	v_mfma_f32_16x16x32_bf16 v[116:119], v[158:161], v[166:169], v[116:119]
	v_mfma_f32_16x16x32_bf16 v[108:111], v[150:153], v[174:177], v[108:111]
	v_mfma_f32_16x16x32_bf16 v[100:103], v[158:161], v[174:177], v[100:103]
	v_mfma_f32_16x16x32_bf16 v[92:95], v[150:153], v[182:185], v[92:95]
	v_mfma_f32_16x16x32_bf16 v[84:87], v[158:161], v[182:185], v[84:87]
	v_mfma_f32_16x16x32_bf16 v[76:79], v[150:153], v[190:193], v[76:79]
	v_mfma_f32_16x16x32_bf16 v[68:71], v[158:161], v[190:193], v[68:71]
	v_mfma_f32_16x16x32_bf16 v[124:127], v[154:157], v[170:173], v[124:127]
	v_mfma_f32_16x16x32_bf16 v[116:119], v[162:165], v[170:173], v[116:119]
	v_mfma_f32_16x16x32_bf16 v[108:111], v[154:157], v[178:181], v[108:111]
	v_mfma_f32_16x16x32_bf16 v[100:103], v[162:165], v[178:181], v[100:103]
	v_mfma_f32_16x16x32_bf16 v[92:95], v[154:157], v[186:189], v[92:95]
	v_mfma_f32_16x16x32_bf16 v[84:87], v[162:165], v[186:189], v[84:87]
	v_mfma_f32_16x16x32_bf16 v[76:79], v[154:157], v[194:197], v[76:79]
	v_mfma_f32_16x16x32_bf16 v[68:71], v[162:165], v[194:197], v[68:71]
	s_setprio 0
	s_barrier
	s_add_i32 s16, s40, s25
	s_mov_b32 m0, s16
	ds_read_b128 v[202:205], v149
	ds_read_b128 v[206:209], v149 offset:1024
	ds_read_b128 v[210:213], v149 offset:2048
	ds_read_b128 v[214:217], v149 offset:3072
	global_load_lds_dwordx4 v132, s[18:19]
	s_add_i32 m0, s16, 0x2000
	s_nop 0
	global_load_lds_dwordx4 v128, s[18:19]
	s_waitcnt vmcnt(8)
	s_barrier
; #define PG8_STAGE(bufoff, gbase, voff) do { _Pragma("unroll") for (int _i = 0; _i < 2; ++_i) \
;         __builtin_amdgcn_global_load_lds((const unsigned*)((const char*)(gbase) + (voff)[_i]), (LAS unsigned*)(lds + (bufoff) + ldsw + _i * 8192), 16, 0, 0); } while (0)
; #define PG8_LDA(dst, b, h) do { _Pragma("unroll") for (int m = 0; m < 4; ++m) _Pragma("unroll") for (int k = 0; k < 2; ++k) dst[m][k] = *(const LAS bf16x8*)(lds + PG8_SA(b, h) + aoff + m * 2048 + k * 1024); } while (0)
; #define PG8_LDB(dst, b, h) do { _Pragma("unroll") for (int n = 0; n < 2; ++n) _Pragma("unroll") for (int k = 0; k < 2; ++k) dst[n][k] = *(const LAS bf16x8*)(lds + PG8_SB(b, h) + boff + n * 2048 + k * 1024); } while (0)
; #define PG8_MMA(ai, bj, At, Bt) do { __builtin_amdgcn_s_setprio(1); _Pragma("unroll") for (int m = 0; m < 4; ++m) _Pragma("unroll") for (int n = 0; n < 2; ++n) _Pragma("unroll") for (int k = 0; k < 2; ++k) \
;         acc[ai][bj][m][n] = __builtin_amdgcn_mfma_f32_16x16x32_bf16(Bt[n][k], At[m][k], acc[ai][bj][m][n], 0, 0, 0); __builtin_amdgcn_s_setprio(0); } while (0)
; #define PG8_WAIT_V(n) asm volatile("s_waitcnt vmcnt(" #n ")" ::: "memory")
; #define PG8_WAIT_L(n) asm volatile("s_waitcnt lgkmcnt(" #n ")" ::: "memory")
; #define PG8_BAR __builtin_amdgcn_s_barrier()
; #define PG8_SCHED __builtin_amdgcn_sched_barrier(0)
; template <class Epi, class Sched>
; __device__ __forceinline__ void gemm_phase(LAS unsigned char* lds, const Gemm g, const Sched& S, const Epi& E) {
;     ...
;             PG8_LDA(At, 0, 1); PG8_STAGE(PG8_SA(0, 0), a2, voffA);
;             PG8_BAR; PG8_WAIT_L(0); PG8_MMA(1, 0, At, B0); PG8_BAR; PG8_SCHED;
;             PG8_STAGE(PG8_SB(0, 1), b2 + hstep, voffB);
;             PG8_WAIT_V(6); PG8_BAR; PG8_MMA(1, 1, At, B1); PG8_BAR;
;             PG8_LDB(B0, 1, 0); PG8_SCHED; PG8_LDA(At, 1, 0); PG8_STAGE(PG8_SA(0, 1), a2 + hstep, voffA);
;             PG8_WAIT_L(8); PG8_BAR; PG8_WAIT_L(0); PG8_MMA(0, 0, At, B0); PG8_BAR; PG8_SCHED;
	s_waitcnt lgkmcnt(0)
	s_setprio 1
	s_waitcnt lgkmcnt(0)
	v_mfma_f32_16x16x32_bf16 v[120:123], v[202:205], v[166:169], v[120:123]
	v_mfma_f32_16x16x32_bf16 v[112:115], v[210:213], v[166:169], v[112:115]
	v_mfma_f32_16x16x32_bf16 v[104:107], v[202:205], v[174:177], v[104:107]
	v_mfma_f32_16x16x32_bf16 v[96:99], v[210:213], v[174:177], v[96:99]
	v_mfma_f32_16x16x32_bf16 v[88:91], v[202:205], v[182:185], v[88:91]
	v_mfma_f32_16x16x32_bf16 v[80:83], v[210:213], v[182:185], v[80:83]
	v_mfma_f32_16x16x32_bf16 v[72:75], v[202:205], v[190:193], v[72:75]
	v_mfma_f32_16x16x32_bf16 v[64:67], v[210:213], v[190:193], v[64:67]
	v_mfma_f32_16x16x32_bf16 v[120:123], v[206:209], v[170:173], v[120:123]
	v_mfma_f32_16x16x32_bf16 v[112:115], v[214:217], v[170:173], v[112:115]
	v_mfma_f32_16x16x32_bf16 v[104:107], v[206:209], v[178:181], v[104:107]
	v_mfma_f32_16x16x32_bf16 v[96:99], v[214:217], v[178:181], v[96:99]
	v_mfma_f32_16x16x32_bf16 v[88:91], v[206:209], v[186:189], v[88:91]
	v_mfma_f32_16x16x32_bf16 v[80:83], v[214:217], v[186:189], v[80:83]
	v_mfma_f32_16x16x32_bf16 v[72:75], v[206:209], v[194:197], v[72:75]
	v_mfma_f32_16x16x32_bf16 v[64:67], v[214:217], v[194:197], v[64:67]
	s_setprio 0
	s_mov_b32 m0, s13
	s_barrier
	ds_read_b128 v[166:169], v148 offset:16384
	ds_read_b128 v[170:173], v148 offset:17408
	ds_read_b128 v[174:177], v148 offset:18432
	ds_read_b128 v[178:181], v148 offset:19456
	ds_read_b128 v[182:185], v148 offset:20480
	ds_read_b128 v[186:189], v148 offset:21504
	ds_read_b128 v[190:193], v148 offset:22528
	ds_read_b128 v[194:197], v148 offset:23552
	global_load_lds_dwordx4 v134, s[22:23]
	s_mov_b32 m0, s28
	s_nop 0
	global_load_lds_dwordx4 v130, s[22:23]
	s_barrier
	s_waitcnt lgkmcnt(0)
	s_setprio 1
	s_waitcnt lgkmcnt(0)
	v_mfma_f32_16x16x32_bf16 v[60:63], v[150:153], v[166:169], v[60:63]
	v_mfma_f32_16x16x32_bf16 v[56:59], v[158:161], v[166:169], v[56:59]
	v_mfma_f32_16x16x32_bf16 v[44:47], v[150:153], v[174:177], v[44:47]
	v_mfma_f32_16x16x32_bf16 v[40:43], v[158:161], v[174:177], v[40:43]
	v_mfma_f32_16x16x32_bf16 v[28:31], v[150:153], v[182:185], v[28:31]
	v_mfma_f32_16x16x32_bf16 v[24:27], v[158:161], v[182:185], v[24:27]
	v_mfma_f32_16x16x32_bf16 v[12:15], v[150:153], v[190:193], v[12:15]
	v_mfma_f32_16x16x32_bf16 v[8:11], v[158:161], v[190:193], v[8:11]
	v_mfma_f32_16x16x32_bf16 v[60:63], v[154:157], v[170:173], v[60:63]
	v_mfma_f32_16x16x32_bf16 v[56:59], v[162:165], v[170:173], v[56:59]
	v_mfma_f32_16x16x32_bf16 v[44:47], v[154:157], v[178:181], v[44:47]
	v_mfma_f32_16x16x32_bf16 v[40:43], v[162:165], v[178:181], v[40:43]
	v_mfma_f32_16x16x32_bf16 v[28:31], v[154:157], v[186:189], v[28:31]
	v_mfma_f32_16x16x32_bf16 v[24:27], v[162:165], v[186:189], v[24:27]
	v_mfma_f32_16x16x32_bf16 v[12:15], v[154:157], v[194:197], v[12:15]
	v_mfma_f32_16x16x32_bf16 v[8:11], v[162:165], v[194:197], v[8:11]
	s_setprio 0
	s_barrier
	s_add_u32 s16, s18, 0x40000
	s_addc_u32 s17, s19, 0
	s_add_i32 s20, s41, s25
	s_mov_b32 m0, s20
	s_nop 0
	global_load_lds_dwordx4 v132, s[16:17]
	s_add_i32 m0, s20, 0x2000
	s_nop 0
	global_load_lds_dwordx4 v128, s[16:17]
	s_add_u32 s16, s22, 0x40000
	s_addc_u32 s17, s23, 0
	s_mov_b32 m0, s29
	s_nop 0
	global_load_lds_dwordx4 v134, s[16:17]
	s_mov_b32 m0, s33
	s_nop 0
	global_load_lds_dwordx4 v130, s[16:17]
	s_waitcnt vmcnt(10)
	s_barrier
	s_setprio 1
	v_mfma_f32_16x16x32_bf16 v[52:55], v[202:205], v[166:169], v[52:55]
	v_mfma_f32_16x16x32_bf16 v[48:51], v[210:213], v[166:169], v[48:51]
	v_mfma_f32_16x16x32_bf16 v[36:39], v[202:205], v[174:177], v[36:39]
	v_mfma_f32_16x16x32_bf16 v[32:35], v[210:213], v[174:177], v[32:35]
	v_mfma_f32_16x16x32_bf16 v[20:23], v[202:205], v[182:185], v[20:23]
	v_mfma_f32_16x16x32_bf16 v[16:19], v[210:213], v[182:185], v[16:19]
	v_mfma_f32_16x16x32_bf16 v[4:7], v[202:205], v[190:193], v[4:7]
	v_mfma_f32_16x16x32_bf16 v[0:3], v[210:213], v[190:193], v[0:3]
	v_mfma_f32_16x16x32_bf16 v[52:55], v[206:209], v[170:173], v[52:55]
	v_mfma_f32_16x16x32_bf16 v[48:51], v[214:217], v[170:173], v[48:51]
	v_mfma_f32_16x16x32_bf16 v[36:39], v[206:209], v[178:181], v[36:39]
	v_mfma_f32_16x16x32_bf16 v[32:35], v[214:217], v[178:181], v[32:35]
	v_mfma_f32_16x16x32_bf16 v[20:23], v[206:209], v[186:189], v[20:23]
	v_mfma_f32_16x16x32_bf16 v[16:19], v[214:217], v[186:189], v[16:19]
	v_mfma_f32_16x16x32_bf16 v[4:7], v[206:209], v[194:197], v[4:7]
	v_mfma_f32_16x16x32_bf16 v[0:3], v[214:217], v[194:197], v[0:3]
	s_setprio 0
	s_add_i32 s20, 0, 0x18000
	v_add_u32_e32 v162, s20, v146
	s_barrier
	ds_read_b128 v[150:153], v162
	ds_read_b128 v[154:157], v162 offset:1024
	ds_read_b128 v[158:161], v162 offset:2048
	ds_read_b128 v[162:165], v162 offset:3072
	ds_read_b128 v[166:169], v148 offset:32768
	ds_read_b128 v[170:173], v148 offset:33792
	ds_read_b128 v[174:177], v148 offset:34816
	ds_read_b128 v[178:181], v148 offset:35840
	ds_read_b128 v[182:185], v148 offset:36864
	ds_read_b128 v[186:189], v148 offset:37888
	ds_read_b128 v[190:193], v148 offset:38912
	ds_read_b128 v[194:197], v148 offset:39936
	s_waitcnt lgkmcnt(8)
	s_waitcnt vmcnt(8)
	s_barrier
; #define PG8_STAGE(bufoff, gbase, voff) do { _Pragma("unroll") for (int _i = 0; _i < 2; ++_i) \
;         __builtin_amdgcn_global_load_lds((const unsigned*)((const char*)(gbase) + (voff)[_i]), (LAS unsigned*)(lds + (bufoff) + ldsw + _i * 8192), 16, 0, 0); } while (0)
; #define PG8_LDA(dst, b, h) do { _Pragma("unroll") for (int m = 0; m < 4; ++m) _Pragma("unroll") for (int k = 0; k < 2; ++k) dst[m][k] = *(const LAS bf16x8*)(lds + PG8_SA(b, h) + aoff + m * 2048 + k * 1024); } while (0)
; #define PG8_LDB(dst, b, h) do { _Pragma("unroll") for (int n = 0; n < 2; ++n) _Pragma("unroll") for (int k = 0; k < 2; ++k) dst[n][k] = *(const LAS bf16x8*)(lds + PG8_SB(b, h) + boff + n * 2048 + k * 1024); } while (0)
; #define PG8_MMA(ai, bj, At, Bt) do { __builtin_amdgcn_s_setprio(1); _Pragma("unroll") for (int m = 0; m < 4; ++m) _Pragma("unroll") for (int n = 0; n < 2; ++n) _Pragma("unroll") for (int k = 0; k < 2; ++k) \
;         acc[ai][bj][m][n] = __builtin_amdgcn_mfma_f32_16x16x32_bf16(Bt[n][k], At[m][k], acc[ai][bj][m][n], 0, 0, 0); __builtin_amdgcn_s_setprio(0); } while (0)
; #define PG8_WAIT_V(n) asm volatile("s_waitcnt vmcnt(" #n ")" ::: "memory")
; #define PG8_WAIT_L(n) asm volatile("s_waitcnt lgkmcnt(" #n ")" ::: "memory")
; #define PG8_BAR __builtin_amdgcn_s_barrier()
; #define PG8_SCHED __builtin_amdgcn_sched_barrier(0)
; template <class Epi, class Sched>
; __device__ __forceinline__ void gemm_phase(LAS unsigned char* lds, const Gemm g, const Sched& S, const Epi& E) {
;     ...
;             PG8_WAIT_L(8); PG8_BAR; PG8_WAIT_L(0); PG8_MMA(0, 0, At, B0); PG8_BAR; PG8_SCHED;
;             PG8_LDB(B1, 1, 1); PG8_STAGE(PG8_SB(1, 0), b3, voffB);
;             PG8_BAR; PG8_WAIT_L(0); PG8_MMA(0, 1, At, B1); PG8_BAR;
;             PG8_LDA(At, 1, 1); PG8_STAGE(PG8_SA(1, 0), a3, voffA);
;             PG8_BAR; PG8_WAIT_L(0); PG8_MMA(1, 0, At, B0); PG8_BAR; PG8_SCHED;
;             PG8_STAGE(PG8_SB(1, 1), b3 + hstep, voffB);
;             PG8_WAIT_V(6); PG8_BAR; PG8_MMA(1, 1, At, B1); PG8_BAR;
	s_waitcnt lgkmcnt(0)
	s_setprio 1
	s_waitcnt lgkmcnt(0)
	v_mfma_f32_16x16x32_bf16 v[124:127], v[150:153], v[166:169], v[124:127]
	v_mfma_f32_16x16x32_bf16 v[116:119], v[158:161], v[166:169], v[116:119]
	v_mfma_f32_16x16x32_bf16 v[108:111], v[150:153], v[174:177], v[108:111]
	v_mfma_f32_16x16x32_bf16 v[100:103], v[158:161], v[174:177], v[100:103]
	v_mfma_f32_16x16x32_bf16 v[92:95], v[150:153], v[182:185], v[92:95]
	v_mfma_f32_16x16x32_bf16 v[84:87], v[158:161], v[182:185], v[84:87]
	v_mfma_f32_16x16x32_bf16 v[76:79], v[150:153], v[190:193], v[76:79]
	v_mfma_f32_16x16x32_bf16 v[68:71], v[158:161], v[190:193], v[68:71]
	v_mfma_f32_16x16x32_bf16 v[124:127], v[154:157], v[170:173], v[124:127]
	v_mfma_f32_16x16x32_bf16 v[116:119], v[162:165], v[170:173], v[116:119]
	v_mfma_f32_16x16x32_bf16 v[108:111], v[154:157], v[178:181], v[108:111]
	v_mfma_f32_16x16x32_bf16 v[100:103], v[162:165], v[178:181], v[100:103]
	v_mfma_f32_16x16x32_bf16 v[92:95], v[154:157], v[186:189], v[92:95]
	v_mfma_f32_16x16x32_bf16 v[84:87], v[162:165], v[186:189], v[84:87]
	v_mfma_f32_16x16x32_bf16 v[76:79], v[154:157], v[194:197], v[76:79]
	v_mfma_f32_16x16x32_bf16 v[68:71], v[162:165], v[194:197], v[68:71]
	s_setprio 0
	s_barrier
	s_add_i32 s21, 0, 0x1c000
	s_add_i32 s16, s20, s25
	v_add_u32_e32 v214, s21, v146
	s_add_u32 s0, s18, 0x80
	s_addc_u32 s1, s19, 0
	s_mov_b32 m0, s16
	ds_read_b128 v[202:205], v214
	ds_read_b128 v[206:209], v214 offset:1024
	ds_read_b128 v[210:213], v214 offset:2048
	ds_read_b128 v[214:217], v214 offset:3072
	global_load_lds_dwordx4 v132, s[0:1]
	s_add_i32 m0, s16, 0x2000
	s_nop 0
	global_load_lds_dwordx4 v128, s[0:1]
	s_waitcnt vmcnt(8)
	s_barrier
	s_waitcnt lgkmcnt(0)
	s_setprio 1
	s_waitcnt lgkmcnt(0)
	v_mfma_f32_16x16x32_bf16 v[120:123], v[202:205], v[166:169], v[120:123]
	v_mfma_f32_16x16x32_bf16 v[112:115], v[210:213], v[166:169], v[112:115]
	v_mfma_f32_16x16x32_bf16 v[104:107], v[202:205], v[174:177], v[104:107]
	v_mfma_f32_16x16x32_bf16 v[96:99], v[210:213], v[174:177], v[96:99]
	v_mfma_f32_16x16x32_bf16 v[88:91], v[202:205], v[182:185], v[88:91]
	v_mfma_f32_16x16x32_bf16 v[80:83], v[210:213], v[182:185], v[80:83]
	v_mfma_f32_16x16x32_bf16 v[72:75], v[202:205], v[190:193], v[72:75]
	v_mfma_f32_16x16x32_bf16 v[64:67], v[210:213], v[190:193], v[64:67]
	v_mfma_f32_16x16x32_bf16 v[120:123], v[206:209], v[170:173], v[120:123]
	v_mfma_f32_16x16x32_bf16 v[112:115], v[214:217], v[170:173], v[112:115]
	v_mfma_f32_16x16x32_bf16 v[104:107], v[206:209], v[178:181], v[104:107]
	v_mfma_f32_16x16x32_bf16 v[96:99], v[214:217], v[178:181], v[96:99]
	v_mfma_f32_16x16x32_bf16 v[88:91], v[206:209], v[186:189], v[88:91]
	v_mfma_f32_16x16x32_bf16 v[80:83], v[214:217], v[186:189], v[80:83]
	v_mfma_f32_16x16x32_bf16 v[72:75], v[206:209], v[194:197], v[72:75]
	v_mfma_f32_16x16x32_bf16 v[64:67], v[214:217], v[194:197], v[64:67]
	s_setprio 0
	s_mov_b32 m0, s36
	s_add_u32 s0, s22, 0x80
	s_addc_u32 s1, s23, 0
	s_barrier
	ds_read_b128 v[166:169], v148 offset:49152
	ds_read_b128 v[170:173], v148 offset:50176
	ds_read_b128 v[174:177], v148 offset:51200
	ds_read_b128 v[178:181], v148 offset:52224
	ds_read_b128 v[182:185], v148 offset:53248
	ds_read_b128 v[186:189], v148 offset:54272
	ds_read_b128 v[190:193], v148 offset:55296
	ds_read_b128 v[194:197], v148 offset:56320
	global_load_lds_dwordx4 v134, s[0:1]
	s_mov_b32 m0, s37
	s_nop 0
	global_load_lds_dwordx4 v130, s[0:1]
	s_barrier
	s_waitcnt lgkmcnt(0)
	s_setprio 1
	s_waitcnt lgkmcnt(0)
	v_mfma_f32_16x16x32_bf16 v[60:63], v[150:153], v[166:169], v[60:63]
	v_mfma_f32_16x16x32_bf16 v[56:59], v[158:161], v[166:169], v[56:59]
	v_mfma_f32_16x16x32_bf16 v[44:47], v[150:153], v[174:177], v[44:47]
	v_mfma_f32_16x16x32_bf16 v[40:43], v[158:161], v[174:177], v[40:43]
	v_mfma_f32_16x16x32_bf16 v[28:31], v[150:153], v[182:185], v[28:31]
	v_mfma_f32_16x16x32_bf16 v[24:27], v[158:161], v[182:185], v[24:27]
	v_mfma_f32_16x16x32_bf16 v[12:15], v[150:153], v[190:193], v[12:15]
	v_mfma_f32_16x16x32_bf16 v[8:11], v[158:161], v[190:193], v[8:11]
	v_mfma_f32_16x16x32_bf16 v[60:63], v[154:157], v[170:173], v[60:63]
	v_mfma_f32_16x16x32_bf16 v[56:59], v[162:165], v[170:173], v[56:59]
	v_mfma_f32_16x16x32_bf16 v[44:47], v[154:157], v[178:181], v[44:47]
	v_mfma_f32_16x16x32_bf16 v[40:43], v[162:165], v[178:181], v[40:43]
	v_mfma_f32_16x16x32_bf16 v[28:31], v[154:157], v[186:189], v[28:31]
	v_mfma_f32_16x16x32_bf16 v[24:27], v[162:165], v[186:189], v[24:27]
	v_mfma_f32_16x16x32_bf16 v[12:15], v[154:157], v[194:197], v[12:15]
	v_mfma_f32_16x16x32_bf16 v[8:11], v[162:165], v[194:197], v[8:11]
	s_setprio 0
	s_barrier
	s_add_u32 s16, s18, 0x40080
	s_addc_u32 s17, s19, 0
	s_add_i32 s18, s21, s25
	s_mov_b32 m0, s18
	s_nop 0
	global_load_lds_dwordx4 v132, s[16:17]
	s_add_i32 m0, s18, 0x2000
	s_nop 0
	global_load_lds_dwordx4 v128, s[16:17]
	s_waitcnt vmcnt(8)
	s_barrier
	s_setprio 1
	v_mfma_f32_16x16x32_bf16 v[52:55], v[202:205], v[166:169], v[52:55]
	v_mfma_f32_16x16x32_bf16 v[48:51], v[210:213], v[166:169], v[48:51]
	v_mfma_f32_16x16x32_bf16 v[36:39], v[202:205], v[174:177], v[36:39]
	v_mfma_f32_16x16x32_bf16 v[32:35], v[210:213], v[174:177], v[32:35]
	v_mfma_f32_16x16x32_bf16 v[20:23], v[202:205], v[182:185], v[20:23]
	v_mfma_f32_16x16x32_bf16 v[16:19], v[210:213], v[182:185], v[16:19]
	v_mfma_f32_16x16x32_bf16 v[4:7], v[202:205], v[190:193], v[4:7]
	v_mfma_f32_16x16x32_bf16 v[0:3], v[210:213], v[190:193], v[0:3]
	v_mfma_f32_16x16x32_bf16 v[52:55], v[206:209], v[170:173], v[52:55]
	v_mfma_f32_16x16x32_bf16 v[48:51], v[214:217], v[170:173], v[48:51]
	v_mfma_f32_16x16x32_bf16 v[36:39], v[206:209], v[178:181], v[36:39]
	v_mfma_f32_16x16x32_bf16 v[32:35], v[214:217], v[178:181], v[32:35]
	v_mfma_f32_16x16x32_bf16 v[20:23], v[206:209], v[186:189], v[20:23]
	v_mfma_f32_16x16x32_bf16 v[16:19], v[214:217], v[186:189], v[16:19]
	v_mfma_f32_16x16x32_bf16 v[4:7], v[206:209], v[194:197], v[4:7]
	v_mfma_f32_16x16x32_bf16 v[0:3], v[214:217], v[194:197], v[0:3]
	s_setprio 0
	s_add_i32 s48, s48, 2
	s_add_u32 s14, s14, 0x100
	s_addc_u32 s15, s15, 0
	s_add_u32 s46, s46, 0x100
	s_addc_u32 s47, s47, 0
	s_cmp_gt_u32 s48, 13
	s_cbranch_scc1 .Lconc_last_g0
	s_barrier
	s_branch .LBB0_235

; #define PG8_STAGE(bufoff, gbase, voff) do { _Pragma("unroll") for (int _i = 0; _i < 2; ++_i) \
;         __builtin_amdgcn_global_load_lds((const unsigned*)((const char*)(gbase) + (voff)[_i]), (LAS unsigned*)(lds + (bufoff) + ldsw + _i * 8192), 16, 0, 0); } while (0)
; #define PG8_LDA(dst, b, h) do { _Pragma("unroll") for (int m = 0; m < 4; ++m) _Pragma("unroll") for (int k = 0; k < 2; ++k) dst[m][k] = *(const LAS bf16x8*)(lds + PG8_SA(b, h) + aoff + m * 2048 + k * 1024); } while (0)
; #define PG8_LDB(dst, b, h) do { _Pragma("unroll") for (int n = 0; n < 2; ++n) _Pragma("unroll") for (int k = 0; k < 2; ++k) dst[n][k] = *(const LAS bf16x8*)(lds + PG8_SB(b, h) + boff + n * 2048 + k * 1024); } while (0)
; #define PG8_MMA(ai, bj, At, Bt) do { __builtin_amdgcn_s_setprio(1); _Pragma("unroll") for (int m = 0; m < 4; ++m) _Pragma("unroll") for (int n = 0; n < 2; ++n) _Pragma("unroll") for (int k = 0; k < 2; ++k) \
;         acc[ai][bj][m][n] = __builtin_amdgcn_mfma_f32_16x16x32_bf16(Bt[n][k], At[m][k], acc[ai][bj][m][n], 0, 0, 0); __builtin_amdgcn_s_setprio(0); } while (0)
; #define PG8_WAIT_V(n) asm volatile("s_waitcnt vmcnt(" #n ")" ::: "memory")
; #define PG8_WAIT_L(n) asm volatile("s_waitcnt lgkmcnt(" #n ")" ::: "memory")
; template <class Epi, class Sched>
; __device__ __forceinline__ void gemm_phase(LAS unsigned char* lds, const Gemm g, const Sched& S, const Epi& E) {
;     ...
;         for (int t = 0; t < nt; t += 2) {
;             const bool last = (t == nt - 2);
;             const char* a1 = cA + (size_t)(t + 1) * kstep;
;             const char* a2 = last ? nA : cA + (size_t)(t + 2) * kstep; const char* b2 = last ? nB : cB + (size_t)(t + 2) * kstep;
;             const char* a3 = a2 + kstep; const char* b3 = b2 + kstep;
;             PG8_LDB(B0, 0, 0); PG8_SCHED; PG8_LDA(At, 0, 0); PG8_STAGE(PG8_SA(1, 1), a1 + hstep, voffA);
;             PG8_WAIT_L(8); PG8_BAR; PG8_WAIT_L(0); PG8_MMA(0, 0, At, B0); PG8_BAR; PG8_SCHED;
;             PG8_LDB(B1, 0, 1); PG8_STAGE(PG8_SB(0, 0), b2, voffB);
;             PG8_BAR; PG8_WAIT_L(0); PG8_MMA(0, 1, At, B1); PG8_BAR;
;             PG8_LDA(At, 0, 1); PG8_STAGE(PG8_SA(0, 0), a2, voffA);
;             PG8_BAR; PG8_WAIT_L(0); PG8_MMA(1, 0, At, B0); PG8_BAR; PG8_SCHED;
;             PG8_STAGE(PG8_SB(0, 1), b2 + hstep, voffB);
;             PG8_WAIT_V(6); PG8_BAR; PG8_MMA(1, 1, At, B1); PG8_BAR;
.LBB0_304:
	s_add_u32 s0, s28, 0x100
	s_addc_u32 s67, s29, 0
	s_mov_b32 s68, -2
	ds_read_b128 v[144:147], v165
	ds_read_b128 v[148:151], v165 offset:1024
	ds_read_b128 v[152:155], v165 offset:2048
	ds_read_b128 v[156:159], v165 offset:3072
	s_add_u32 s28, s26, 0x100
	s_addc_u32 s29, s27, 0
	s_cmp_eq_u32 s68, 40
	s_cselect_b32 s37, s5, s29
	s_cselect_b32 s36, s4, s28
	s_cselect_b32 s35, s7, s67
	s_cselect_b32 s34, s6, s0
	v_lshl_add_u64 v[160:161], s[26:27], 0, v[136:137]
	s_add_i32 m0, s42, 0xc000
	ds_read_b128 v[168:171], v166
	ds_read_b128 v[172:175], v166 offset:1024
	ds_read_b128 v[176:179], v166 offset:2048
	ds_read_b128 v[180:183], v166 offset:3072
	ds_read_b128 v[184:187], v166 offset:4096
	ds_read_b128 v[188:191], v166 offset:5120
	ds_read_b128 v[192:195], v166 offset:6144
	ds_read_b128 v[196:199], v166 offset:7168
	global_load_lds_dwordx4 v[160:161], off
	v_lshl_add_u64 v[160:161], s[26:27], 0, v[138:139]
	s_add_i32 m0, s42, 0xe000
	s_nop 0
	global_load_lds_dwordx4 v[160:161], off
	s_waitcnt lgkmcnt(8)
	s_waitcnt vmcnt(8)
	s_barrier
	s_waitcnt lgkmcnt(0)
	s_setprio 1
	s_waitcnt lgkmcnt(0)
	v_mfma_f32_16x16x32_bf16 v[124:127], v[144:147], v[168:171], 0
	v_mfma_f32_16x16x32_bf16 v[120:123], v[152:155], v[168:171], 0
	v_mfma_f32_16x16x32_bf16 v[116:119], v[144:147], v[176:179], 0
	v_mfma_f32_16x16x32_bf16 v[104:107], v[152:155], v[176:179], 0
	v_mfma_f32_16x16x32_bf16 v[96:99], v[144:147], v[184:187], 0
	v_mfma_f32_16x16x32_bf16 v[88:91], v[152:155], v[184:187], 0
	v_mfma_f32_16x16x32_bf16 v[80:83], v[144:147], v[192:195], 0
	v_mfma_f32_16x16x32_bf16 v[72:75], v[152:155], v[192:195], 0
	v_mfma_f32_16x16x32_bf16 v[124:127], v[148:151], v[172:175], v[124:127]
	v_mfma_f32_16x16x32_bf16 v[120:123], v[156:159], v[172:175], v[120:123]
	v_mfma_f32_16x16x32_bf16 v[116:119], v[148:151], v[180:183], v[116:119]
	v_mfma_f32_16x16x32_bf16 v[104:107], v[156:159], v[180:183], v[104:107]
	v_mfma_f32_16x16x32_bf16 v[96:99], v[148:151], v[188:191], v[96:99]
	v_mfma_f32_16x16x32_bf16 v[88:91], v[156:159], v[188:191], v[88:91]
	v_mfma_f32_16x16x32_bf16 v[80:83], v[148:151], v[196:199], v[80:83]
	v_mfma_f32_16x16x32_bf16 v[72:75], v[156:159], v[196:199], v[72:75]
	s_setprio 0
	s_barrier
	s_add_i32 s16, s58, s40
	s_mov_b32 m0, s16
	ds_read_b128 v[202:205], v167
	ds_read_b128 v[206:209], v167 offset:1024
	ds_read_b128 v[210:213], v167 offset:2048
	ds_read_b128 v[214:217], v167 offset:3072
	global_load_lds_dwordx4 v132, s[34:35]
	s_add_i32 m0, s16, 0x2000
	s_nop 0
	global_load_lds_dwordx4 v128, s[34:35]
	s_waitcnt vmcnt(8)
	s_barrier
	s_waitcnt lgkmcnt(0)
	s_setprio 1
	s_waitcnt lgkmcnt(0)
	v_mfma_f32_16x16x32_bf16 v[112:115], v[202:205], v[168:171], 0
	v_mfma_f32_16x16x32_bf16 v[108:111], v[210:213], v[168:171], 0
	v_mfma_f32_16x16x32_bf16 v[100:103], v[202:205], v[176:179], 0
	v_mfma_f32_16x16x32_bf16 v[92:95], v[210:213], v[176:179], 0
	v_mfma_f32_16x16x32_bf16 v[84:87], v[202:205], v[184:187], 0
	v_mfma_f32_16x16x32_bf16 v[76:79], v[210:213], v[184:187], 0
	v_mfma_f32_16x16x32_bf16 v[68:71], v[202:205], v[192:195], 0
	v_mfma_f32_16x16x32_bf16 v[64:67], v[210:213], v[192:195], 0
	v_mfma_f32_16x16x32_bf16 v[112:115], v[206:209], v[172:175], v[112:115]
	v_mfma_f32_16x16x32_bf16 v[108:111], v[214:217], v[172:175], v[108:111]
	v_mfma_f32_16x16x32_bf16 v[100:103], v[206:209], v[180:183], v[100:103]
	v_mfma_f32_16x16x32_bf16 v[92:95], v[214:217], v[180:183], v[92:95]
	v_mfma_f32_16x16x32_bf16 v[84:87], v[206:209], v[188:191], v[84:87]
	v_mfma_f32_16x16x32_bf16 v[76:79], v[214:217], v[188:191], v[76:79]
	v_mfma_f32_16x16x32_bf16 v[68:71], v[206:209], v[196:199], v[68:71]
	v_mfma_f32_16x16x32_bf16 v[64:67], v[214:217], v[196:199], v[64:67]
	s_setprio 0
	s_mov_b32 m0, s42
	s_barrier
	ds_read_b128 v[168:171], v166 offset:16384
	ds_read_b128 v[172:175], v166 offset:17408
	ds_read_b128 v[176:179], v166 offset:18432
	ds_read_b128 v[180:183], v166 offset:19456
	ds_read_b128 v[184:187], v166 offset:20480
	ds_read_b128 v[188:191], v166 offset:21504
	ds_read_b128 v[192:195], v166 offset:22528
	ds_read_b128 v[196:199], v166 offset:23552
	global_load_lds_dwordx4 v134, s[36:37]
	s_mov_b32 m0, s43
	s_nop 0
	global_load_lds_dwordx4 v130, s[36:37]
	s_barrier
	s_waitcnt lgkmcnt(0)
	s_setprio 1
	s_waitcnt lgkmcnt(0)
	v_mfma_f32_16x16x32_bf16 v[60:63], v[144:147], v[168:171], 0
	v_mfma_f32_16x16x32_bf16 v[56:59], v[152:155], v[168:171], 0
	v_mfma_f32_16x16x32_bf16 v[48:51], v[144:147], v[176:179], 0
	v_mfma_f32_16x16x32_bf16 v[40:43], v[152:155], v[176:179], 0
	v_mfma_f32_16x16x32_bf16 v[32:35], v[144:147], v[184:187], 0
	v_mfma_f32_16x16x32_bf16 v[24:27], v[152:155], v[184:187], 0
	v_mfma_f32_16x16x32_bf16 v[16:19], v[144:147], v[192:195], 0
	v_mfma_f32_16x16x32_bf16 v[8:11], v[152:155], v[192:195], 0
	v_mfma_f32_16x16x32_bf16 v[60:63], v[148:151], v[172:175], v[60:63]
	v_mfma_f32_16x16x32_bf16 v[56:59], v[156:159], v[172:175], v[56:59]
	v_mfma_f32_16x16x32_bf16 v[48:51], v[148:151], v[180:183], v[48:51]
	v_mfma_f32_16x16x32_bf16 v[40:43], v[156:159], v[180:183], v[40:43]
	v_mfma_f32_16x16x32_bf16 v[32:35], v[148:151], v[188:191], v[32:35]
	v_mfma_f32_16x16x32_bf16 v[24:27], v[156:159], v[188:191], v[24:27]
	v_mfma_f32_16x16x32_bf16 v[16:19], v[148:151], v[196:199], v[16:19]
	v_mfma_f32_16x16x32_bf16 v[8:11], v[156:159], v[196:199], v[8:11]
	s_setprio 0
	s_barrier
	s_add_u32 s16, s34, 0xb0000
	s_addc_u32 s17, s35, 0
	s_add_i32 s20, s59, s40
	s_mov_b32 m0, s20
	s_nop 0
	global_load_lds_dwordx4 v132, s[16:17]
	s_add_i32 m0, s20, 0x2000
	s_nop 0
	global_load_lds_dwordx4 v128, s[16:17]
	s_add_u32 s16, s36, 0xb0000
	s_addc_u32 s17, s37, 0
	s_mov_b32 m0, s44
	s_nop 0
	global_load_lds_dwordx4 v134, s[16:17]
	s_mov_b32 m0, s45
	s_nop 0
	global_load_lds_dwordx4 v130, s[16:17]
	s_waitcnt vmcnt(10)
	s_barrier
; #define PG8_STAGE(bufoff, gbase, voff) do { _Pragma("unroll") for (int _i = 0; _i < 2; ++_i) \
;         __builtin_amdgcn_global_load_lds((const unsigned*)((const char*)(gbase) + (voff)[_i]), (LAS unsigned*)(lds + (bufoff) + ldsw + _i * 8192), 16, 0, 0); } while (0)
; #define PG8_LDA(dst, b, h) do { _Pragma("unroll") for (int m = 0; m < 4; ++m) _Pragma("unroll") for (int k = 0; k < 2; ++k) dst[m][k] = *(const LAS bf16x8*)(lds + PG8_SA(b, h) + aoff + m * 2048 + k * 1024); } while (0)
; #define PG8_LDB(dst, b, h) do { _Pragma("unroll") for (int n = 0; n < 2; ++n) _Pragma("unroll") for (int k = 0; k < 2; ++k) dst[n][k] = *(const LAS bf16x8*)(lds + PG8_SB(b, h) + boff + n * 2048 + k * 1024); } while (0)
; #define PG8_MMA(ai, bj, At, Bt) do { __builtin_amdgcn_s_setprio(1); _Pragma("unroll") for (int m = 0; m < 4; ++m) _Pragma("unroll") for (int n = 0; n < 2; ++n) _Pragma("unroll") for (int k = 0; k < 2; ++k) \
;         acc[ai][bj][m][n] = __builtin_amdgcn_mfma_f32_16x16x32_bf16(Bt[n][k], At[m][k], acc[ai][bj][m][n], 0, 0, 0); __builtin_amdgcn_s_setprio(0); } while (0)
; #define PG8_WAIT_V(n) asm volatile("s_waitcnt vmcnt(" #n ")" ::: "memory")
; #define PG8_WAIT_L(n) asm volatile("s_waitcnt lgkmcnt(" #n ")" ::: "memory")
; #define PG8_BAR __builtin_amdgcn_s_barrier()
; #define PG8_SCHED __builtin_amdgcn_sched_barrier(0)
; template <class Epi, class Sched>
; __device__ __forceinline__ void gemm_phase(LAS unsigned char* lds, const Gemm g, const Sched& S, const Epi& E) {
;     ...
;             PG8_WAIT_V(6); PG8_BAR; PG8_MMA(1, 1, At, B1); PG8_BAR;
;             PG8_LDB(B0, 1, 0); PG8_SCHED; PG8_LDA(At, 1, 0); PG8_STAGE(PG8_SA(0, 1), a2 + hstep, voffA);
;             PG8_WAIT_L(8); PG8_BAR; PG8_WAIT_L(0); PG8_MMA(0, 0, At, B0); PG8_BAR; PG8_SCHED;
;             PG8_LDB(B1, 1, 1); PG8_STAGE(PG8_SB(1, 0), b3, voffB);
;             PG8_BAR; PG8_WAIT_L(0); PG8_MMA(0, 1, At, B1); PG8_BAR;
;             PG8_LDA(At, 1, 1); PG8_STAGE(PG8_SA(1, 0), a3, voffA);
;             PG8_BAR; PG8_WAIT_L(0); PG8_MMA(1, 0, At, B0); PG8_BAR; PG8_SCHED;
	s_setprio 1
	v_mfma_f32_16x16x32_bf16 v[52:55], v[202:205], v[168:171], 0
	v_mfma_f32_16x16x32_bf16 v[44:47], v[210:213], v[168:171], 0
	v_mfma_f32_16x16x32_bf16 v[36:39], v[202:205], v[176:179], 0
	v_mfma_f32_16x16x32_bf16 v[28:31], v[210:213], v[176:179], 0
	v_mfma_f32_16x16x32_bf16 v[20:23], v[202:205], v[184:187], 0
	v_mfma_f32_16x16x32_bf16 v[12:15], v[210:213], v[184:187], 0
	v_mfma_f32_16x16x32_bf16 v[4:7], v[202:205], v[192:195], 0
	v_mfma_f32_16x16x32_bf16 v[0:3], v[210:213], v[192:195], 0
	v_mfma_f32_16x16x32_bf16 v[52:55], v[206:209], v[172:175], v[52:55]
	v_mfma_f32_16x16x32_bf16 v[44:47], v[214:217], v[172:175], v[44:47]
	v_mfma_f32_16x16x32_bf16 v[36:39], v[206:209], v[180:183], v[36:39]
	v_mfma_f32_16x16x32_bf16 v[28:31], v[214:217], v[180:183], v[28:31]
	v_mfma_f32_16x16x32_bf16 v[20:23], v[206:209], v[188:191], v[20:23]
	v_mfma_f32_16x16x32_bf16 v[12:15], v[214:217], v[188:191], v[12:15]
	v_mfma_f32_16x16x32_bf16 v[4:7], v[206:209], v[196:199], v[4:7]
	v_mfma_f32_16x16x32_bf16 v[0:3], v[214:217], v[196:199], v[0:3]
	s_setprio 0
	s_add_i32 s20, 0, 0x18000
	v_add_u32_e32 v156, s20, v164
	s_barrier
	ds_read_b128 v[144:147], v156
	ds_read_b128 v[148:151], v156 offset:1024
	ds_read_b128 v[152:155], v156 offset:2048
	ds_read_b128 v[156:159], v156 offset:3072
	ds_read_b128 v[168:171], v166 offset:32768
	ds_read_b128 v[172:175], v166 offset:33792
	ds_read_b128 v[176:179], v166 offset:34816
	ds_read_b128 v[180:183], v166 offset:35840
	ds_read_b128 v[184:187], v166 offset:36864
	ds_read_b128 v[188:191], v166 offset:37888
	ds_read_b128 v[192:195], v166 offset:38912
	ds_read_b128 v[196:199], v166 offset:39936
	s_waitcnt lgkmcnt(8)
	s_waitcnt vmcnt(8)
	s_barrier
	s_waitcnt lgkmcnt(0)
	s_setprio 1
	s_waitcnt lgkmcnt(0)
	v_mfma_f32_16x16x32_bf16 v[124:127], v[144:147], v[168:171], v[124:127]
	v_mfma_f32_16x16x32_bf16 v[120:123], v[152:155], v[168:171], v[120:123]
	v_mfma_f32_16x16x32_bf16 v[116:119], v[144:147], v[176:179], v[116:119]
	v_mfma_f32_16x16x32_bf16 v[104:107], v[152:155], v[176:179], v[104:107]
	v_mfma_f32_16x16x32_bf16 v[96:99], v[144:147], v[184:187], v[96:99]
	v_mfma_f32_16x16x32_bf16 v[88:91], v[152:155], v[184:187], v[88:91]
	v_mfma_f32_16x16x32_bf16 v[80:83], v[144:147], v[192:195], v[80:83]
	v_mfma_f32_16x16x32_bf16 v[72:75], v[152:155], v[192:195], v[72:75]
	v_mfma_f32_16x16x32_bf16 v[124:127], v[148:151], v[172:175], v[124:127]
	v_mfma_f32_16x16x32_bf16 v[120:123], v[156:159], v[172:175], v[120:123]
	v_mfma_f32_16x16x32_bf16 v[116:119], v[148:151], v[180:183], v[116:119]
	v_mfma_f32_16x16x32_bf16 v[104:107], v[156:159], v[180:183], v[104:107]
	v_mfma_f32_16x16x32_bf16 v[96:99], v[148:151], v[188:191], v[96:99]
	v_mfma_f32_16x16x32_bf16 v[88:91], v[156:159], v[188:191], v[88:91]
	v_mfma_f32_16x16x32_bf16 v[80:83], v[148:151], v[196:199], v[80:83]
	v_mfma_f32_16x16x32_bf16 v[72:75], v[156:159], v[196:199], v[72:75]
	s_setprio 0
	s_barrier
	s_add_i32 s21, 0, 0x1c000
	s_add_i32 s16, s20, s40
	v_add_u32_e32 v214, s21, v164
	s_add_u32 s8, s34, 0x80
	s_addc_u32 s9, s35, 0
	s_mov_b32 m0, s16
	ds_read_b128 v[202:205], v214
	ds_read_b128 v[206:209], v214 offset:1024
	ds_read_b128 v[210:213], v214 offset:2048
	ds_read_b128 v[214:217], v214 offset:3072
	global_load_lds_dwordx4 v132, s[8:9]
	s_add_i32 m0, s16, 0x2000
	s_nop 0
	global_load_lds_dwordx4 v128, s[8:9]
	s_waitcnt vmcnt(8)
	s_barrier
	s_waitcnt lgkmcnt(0)
	s_setprio 1
	s_waitcnt lgkmcnt(0)
	v_mfma_f32_16x16x32_bf16 v[112:115], v[202:205], v[168:171], v[112:115]
	v_mfma_f32_16x16x32_bf16 v[108:111], v[210:213], v[168:171], v[108:111]
	v_mfma_f32_16x16x32_bf16 v[100:103], v[202:205], v[176:179], v[100:103]
	v_mfma_f32_16x16x32_bf16 v[92:95], v[210:213], v[176:179], v[92:95]
	v_mfma_f32_16x16x32_bf16 v[84:87], v[202:205], v[184:187], v[84:87]
	v_mfma_f32_16x16x32_bf16 v[76:79], v[210:213], v[184:187], v[76:79]
	v_mfma_f32_16x16x32_bf16 v[68:71], v[202:205], v[192:195], v[68:71]
	v_mfma_f32_16x16x32_bf16 v[64:67], v[210:213], v[192:195], v[64:67]
	v_mfma_f32_16x16x32_bf16 v[112:115], v[206:209], v[172:175], v[112:115]
	v_mfma_f32_16x16x32_bf16 v[108:111], v[214:217], v[172:175], v[108:111]
	v_mfma_f32_16x16x32_bf16 v[100:103], v[206:209], v[180:183], v[100:103]
	v_mfma_f32_16x16x32_bf16 v[92:95], v[214:217], v[180:183], v[92:95]
	v_mfma_f32_16x16x32_bf16 v[84:87], v[206:209], v[188:191], v[84:87]
	v_mfma_f32_16x16x32_bf16 v[76:79], v[214:217], v[188:191], v[76:79]
	v_mfma_f32_16x16x32_bf16 v[68:71], v[206:209], v[196:199], v[68:71]
	v_mfma_f32_16x16x32_bf16 v[64:67], v[214:217], v[196:199], v[64:67]
	s_setprio 0
	s_mov_b32 m0, s52
	s_add_u32 s8, s36, 0x80
	s_addc_u32 s9, s37, 0
	s_barrier
	ds_read_b128 v[168:171], v166 offset:49152
	ds_read_b128 v[172:175], v166 offset:50176
	ds_read_b128 v[176:179], v166 offset:51200
	ds_read_b128 v[180:183], v166 offset:52224
	ds_read_b128 v[184:187], v166 offset:53248
	ds_read_b128 v[188:191], v166 offset:54272
	ds_read_b128 v[192:195], v166 offset:55296
	ds_read_b128 v[196:199], v166 offset:56320
	global_load_lds_dwordx4 v134, s[8:9]
	s_mov_b32 m0, s53
	s_nop 0
	global_load_lds_dwordx4 v130, s[8:9]
	s_barrier
; #define PG8_STAGE(bufoff, gbase, voff) do { _Pragma("unroll") for (int _i = 0; _i < 2; ++_i) \
;         __builtin_amdgcn_global_load_lds((const unsigned*)((const char*)(gbase) + (voff)[_i]), (LAS unsigned*)(lds + (bufoff) + ldsw + _i * 8192), 16, 0, 0); } while (0)
; #define PG8_LDA(dst, b, h) do { _Pragma("unroll") for (int m = 0; m < 4; ++m) _Pragma("unroll") for (int k = 0; k < 2; ++k) dst[m][k] = *(const LAS bf16x8*)(lds + PG8_SA(b, h) + aoff + m * 2048 + k * 1024); } while (0)
; #define PG8_LDB(dst, b, h) do { _Pragma("unroll") for (int n = 0; n < 2; ++n) _Pragma("unroll") for (int k = 0; k < 2; ++k) dst[n][k] = *(const LAS bf16x8*)(lds + PG8_SB(b, h) + boff + n * 2048 + k * 1024); } while (0)
; #define PG8_MMA(ai, bj, At, Bt) do { __builtin_amdgcn_s_setprio(1); _Pragma("unroll") for (int m = 0; m < 4; ++m) _Pragma("unroll") for (int n = 0; n < 2; ++n) _Pragma("unroll") for (int k = 0; k < 2; ++k) \
;         acc[ai][bj][m][n] = __builtin_amdgcn_mfma_f32_16x16x32_bf16(Bt[n][k], At[m][k], acc[ai][bj][m][n], 0, 0, 0); __builtin_amdgcn_s_setprio(0); } while (0)
; #define PG8_WAIT_V(n) asm volatile("s_waitcnt vmcnt(" #n ")" ::: "memory")
; #define PG8_WAIT_L(n) asm volatile("s_waitcnt lgkmcnt(" #n ")" ::: "memory")
; #define PG8_BAR __builtin_amdgcn_s_barrier()
; #define PG8_SCHED __builtin_amdgcn_sched_barrier(0)
; template <class Epi, class Sched>
; __device__ __forceinline__ void gemm_phase(LAS unsigned char* lds, const Gemm g, const Sched& S, const Epi& E) {
;     ...
;             PG8_LDB(B0, 0, 0); PG8_SCHED; PG8_LDA(At, 0, 0); PG8_STAGE(PG8_SA(1, 1), a1 + hstep, voffA);
;             PG8_WAIT_L(8); PG8_BAR; PG8_WAIT_L(0); PG8_MMA(0, 0, At, B0); PG8_BAR; PG8_SCHED;
;             PG8_LDB(B1, 0, 1); PG8_STAGE(PG8_SB(0, 0), b2, voffB);
;             PG8_BAR; PG8_WAIT_L(0); PG8_MMA(0, 1, At, B1); PG8_BAR;
;             PG8_LDA(At, 0, 1); PG8_STAGE(PG8_SA(0, 0), a2, voffA);
;     ...
;             PG8_BAR; PG8_WAIT_L(0); PG8_MMA(1, 0, At, B0); PG8_BAR; PG8_SCHED;
;             PG8_STAGE(PG8_SB(1, 1), b3 + hstep, voffB);
;             PG8_WAIT_V(6); PG8_BAR; PG8_MMA(1, 1, At, B1); PG8_BAR;
	s_waitcnt lgkmcnt(0)
	s_setprio 1
	s_waitcnt lgkmcnt(0)
	v_mfma_f32_16x16x32_bf16 v[60:63], v[144:147], v[168:171], v[60:63]
	v_mfma_f32_16x16x32_bf16 v[56:59], v[152:155], v[168:171], v[56:59]
	v_mfma_f32_16x16x32_bf16 v[48:51], v[144:147], v[176:179], v[48:51]
	v_mfma_f32_16x16x32_bf16 v[40:43], v[152:155], v[176:179], v[40:43]
	v_mfma_f32_16x16x32_bf16 v[32:35], v[144:147], v[184:187], v[32:35]
	v_mfma_f32_16x16x32_bf16 v[24:27], v[152:155], v[184:187], v[24:27]
	v_mfma_f32_16x16x32_bf16 v[16:19], v[144:147], v[192:195], v[16:19]
	v_mfma_f32_16x16x32_bf16 v[8:11], v[152:155], v[192:195], v[8:11]
	v_mfma_f32_16x16x32_bf16 v[60:63], v[148:151], v[172:175], v[60:63]
	v_mfma_f32_16x16x32_bf16 v[56:59], v[156:159], v[172:175], v[56:59]
	v_mfma_f32_16x16x32_bf16 v[48:51], v[148:151], v[180:183], v[48:51]
	v_mfma_f32_16x16x32_bf16 v[40:43], v[156:159], v[180:183], v[40:43]
	v_mfma_f32_16x16x32_bf16 v[32:35], v[148:151], v[188:191], v[32:35]
	v_mfma_f32_16x16x32_bf16 v[24:27], v[156:159], v[188:191], v[24:27]
	v_mfma_f32_16x16x32_bf16 v[16:19], v[148:151], v[196:199], v[16:19]
	v_mfma_f32_16x16x32_bf16 v[8:11], v[156:159], v[196:199], v[8:11]
	s_setprio 0
	s_barrier
	s_add_u32 s16, s34, 0xb0080
	s_addc_u32 s17, s35, 0
	s_add_i32 s20, s21, s40
	s_mov_b32 m0, s20
	s_nop 0
	global_load_lds_dwordx4 v132, s[16:17]
	s_add_i32 m0, s20, 0x2000
	s_nop 0
	global_load_lds_dwordx4 v128, s[16:17]
	s_waitcnt vmcnt(8)
	s_barrier
	s_setprio 1
	v_mfma_f32_16x16x32_bf16 v[52:55], v[202:205], v[168:171], v[52:55]
	v_mfma_f32_16x16x32_bf16 v[44:47], v[210:213], v[168:171], v[44:47]
	v_mfma_f32_16x16x32_bf16 v[36:39], v[202:205], v[176:179], v[36:39]
	v_mfma_f32_16x16x32_bf16 v[28:31], v[210:213], v[176:179], v[28:31]
	v_mfma_f32_16x16x32_bf16 v[20:23], v[202:205], v[184:187], v[20:23]
	v_mfma_f32_16x16x32_bf16 v[12:15], v[210:213], v[184:187], v[12:15]
	v_mfma_f32_16x16x32_bf16 v[4:7], v[202:205], v[192:195], v[4:7]
	v_mfma_f32_16x16x32_bf16 v[0:3], v[210:213], v[192:195], v[0:3]
	v_mfma_f32_16x16x32_bf16 v[52:55], v[206:209], v[172:175], v[52:55]
	v_mfma_f32_16x16x32_bf16 v[44:47], v[214:217], v[172:175], v[44:47]
	v_mfma_f32_16x16x32_bf16 v[36:39], v[206:209], v[180:183], v[36:39]
	v_mfma_f32_16x16x32_bf16 v[28:31], v[214:217], v[180:183], v[28:31]
	v_mfma_f32_16x16x32_bf16 v[20:23], v[206:209], v[188:191], v[20:23]
	v_mfma_f32_16x16x32_bf16 v[12:15], v[214:217], v[188:191], v[12:15]
	v_mfma_f32_16x16x32_bf16 v[4:7], v[206:209], v[196:199], v[4:7]
	v_mfma_f32_16x16x32_bf16 v[0:3], v[214:217], v[196:199], v[0:3]
	s_setprio 0
	s_add_i32 s68, s68, 2
	s_add_u32 s0, s0, 0x100
	s_addc_u32 s67, s67, 0
	s_cmp_gt_u32 s68, 41
	s_mov_b64 s[26:27], s[28:29]
	s_barrier
.LBB0_305:
	ds_read_b128 v[144:147], v165
	ds_read_b128 v[148:151], v165 offset:1024
	ds_read_b128 v[152:155], v165 offset:2048
	ds_read_b128 v[156:159], v165 offset:3072
	s_add_u32 s28, s26, 0x100
	s_addc_u32 s29, s27, 0
	s_cmp_eq_u32 s68, 40
	s_cselect_b32 s37, s5, s29
	s_cselect_b32 s36, s4, s28
	s_cselect_b32 s35, s7, s67
	s_cselect_b32 s34, s6, s0
	v_lshl_add_u64 v[160:161], s[26:27], 0, v[136:137]
	s_add_i32 m0, s42, 0xc000
	ds_read_b128 v[168:171], v166
	ds_read_b128 v[172:175], v166 offset:1024
	ds_read_b128 v[176:179], v166 offset:2048
	ds_read_b128 v[180:183], v166 offset:3072
	ds_read_b128 v[184:187], v166 offset:4096
	ds_read_b128 v[188:191], v166 offset:5120
	ds_read_b128 v[192:195], v166 offset:6144
	ds_read_b128 v[196:199], v166 offset:7168
	global_load_lds_dwordx4 v[160:161], off
	v_lshl_add_u64 v[160:161], s[26:27], 0, v[138:139]
	s_add_i32 m0, s42, 0xe000
	s_nop 0
	global_load_lds_dwordx4 v[160:161], off
	s_waitcnt lgkmcnt(8)
	s_waitcnt vmcnt(8)
	s_barrier
	s_waitcnt lgkmcnt(0)
	s_setprio 1
	s_waitcnt lgkmcnt(0)
	v_mfma_f32_16x16x32_bf16 v[124:127], v[144:147], v[168:171], v[124:127]
	v_mfma_f32_16x16x32_bf16 v[120:123], v[152:155], v[168:171], v[120:123]
	v_mfma_f32_16x16x32_bf16 v[116:119], v[144:147], v[176:179], v[116:119]
	v_mfma_f32_16x16x32_bf16 v[104:107], v[152:155], v[176:179], v[104:107]
	v_mfma_f32_16x16x32_bf16 v[96:99], v[144:147], v[184:187], v[96:99]
	v_mfma_f32_16x16x32_bf16 v[88:91], v[152:155], v[184:187], v[88:91]
	v_mfma_f32_16x16x32_bf16 v[80:83], v[144:147], v[192:195], v[80:83]
	v_mfma_f32_16x16x32_bf16 v[72:75], v[152:155], v[192:195], v[72:75]
	v_mfma_f32_16x16x32_bf16 v[124:127], v[148:151], v[172:175], v[124:127]
	v_mfma_f32_16x16x32_bf16 v[120:123], v[156:159], v[172:175], v[120:123]
	v_mfma_f32_16x16x32_bf16 v[116:119], v[148:151], v[180:183], v[116:119]
	v_mfma_f32_16x16x32_bf16 v[104:107], v[156:159], v[180:183], v[104:107]
	v_mfma_f32_16x16x32_bf16 v[96:99], v[148:151], v[188:191], v[96:99]
	v_mfma_f32_16x16x32_bf16 v[88:91], v[156:159], v[188:191], v[88:91]
	v_mfma_f32_16x16x32_bf16 v[80:83], v[148:151], v[196:199], v[80:83]
	v_mfma_f32_16x16x32_bf16 v[72:75], v[156:159], v[196:199], v[72:75]
	s_setprio 0
	s_barrier
	s_add_i32 s16, s58, s40
	s_mov_b32 m0, s16
	ds_read_b128 v[202:205], v167
	ds_read_b128 v[206:209], v167 offset:1024
	ds_read_b128 v[210:213], v167 offset:2048
	ds_read_b128 v[214:217], v167 offset:3072
	global_load_lds_dwordx4 v132, s[34:35]
	s_add_i32 m0, s16, 0x2000
	s_nop 0
	global_load_lds_dwordx4 v128, s[34:35]
	s_waitcnt vmcnt(8)
	s_barrier
; #define PG8_STAGE(bufoff, gbase, voff) do { _Pragma("unroll") for (int _i = 0; _i < 2; ++_i) \
;         __builtin_amdgcn_global_load_lds((const unsigned*)((const char*)(gbase) + (voff)[_i]), (LAS unsigned*)(lds + (bufoff) + ldsw + _i * 8192), 16, 0, 0); } while (0)
; #define PG8_LDA(dst, b, h) do { _Pragma("unroll") for (int m = 0; m < 4; ++m) _Pragma("unroll") for (int k = 0; k < 2; ++k) dst[m][k] = *(const LAS bf16x8*)(lds + PG8_SA(b, h) + aoff + m * 2048 + k * 1024); } while (0)
; #define PG8_LDB(dst, b, h) do { _Pragma("unroll") for (int n = 0; n < 2; ++n) _Pragma("unroll") for (int k = 0; k < 2; ++k) dst[n][k] = *(const LAS bf16x8*)(lds + PG8_SB(b, h) + boff + n * 2048 + k * 1024); } while (0)
; #define PG8_MMA(ai, bj, At, Bt) do { __builtin_amdgcn_s_setprio(1); _Pragma("unroll") for (int m = 0; m < 4; ++m) _Pragma("unroll") for (int n = 0; n < 2; ++n) _Pragma("unroll") for (int k = 0; k < 2; ++k) \
;         acc[ai][bj][m][n] = __builtin_amdgcn_mfma_f32_16x16x32_bf16(Bt[n][k], At[m][k], acc[ai][bj][m][n], 0, 0, 0); __builtin_amdgcn_s_setprio(0); } while (0)
; #define PG8_WAIT_V(n) asm volatile("s_waitcnt vmcnt(" #n ")" ::: "memory")
; #define PG8_WAIT_L(n) asm volatile("s_waitcnt lgkmcnt(" #n ")" ::: "memory")
; #define PG8_BAR __builtin_amdgcn_s_barrier()
; #define PG8_SCHED __builtin_amdgcn_sched_barrier(0)
; template <class Epi, class Sched>
; __device__ __forceinline__ void gemm_phase(LAS unsigned char* lds, const Gemm g, const Sched& S, const Epi& E) {
;     ...
;             PG8_BAR; PG8_WAIT_L(0); PG8_MMA(1, 0, At, B0); PG8_BAR; PG8_SCHED;
;             PG8_STAGE(PG8_SB(0, 1), b2 + hstep, voffB);
;             PG8_WAIT_V(6); PG8_BAR; PG8_MMA(1, 1, At, B1); PG8_BAR;
;             PG8_LDB(B0, 1, 0); PG8_SCHED; PG8_LDA(At, 1, 0); PG8_STAGE(PG8_SA(0, 1), a2 + hstep, voffA);
;             PG8_WAIT_L(8); PG8_BAR; PG8_WAIT_L(0); PG8_MMA(0, 0, At, B0); PG8_BAR; PG8_SCHED;
	s_waitcnt lgkmcnt(0)
	s_setprio 1
	s_waitcnt lgkmcnt(0)
	v_mfma_f32_16x16x32_bf16 v[112:115], v[202:205], v[168:171], v[112:115]
	v_mfma_f32_16x16x32_bf16 v[108:111], v[210:213], v[168:171], v[108:111]
	v_mfma_f32_16x16x32_bf16 v[100:103], v[202:205], v[176:179], v[100:103]
	v_mfma_f32_16x16x32_bf16 v[92:95], v[210:213], v[176:179], v[92:95]
	v_mfma_f32_16x16x32_bf16 v[84:87], v[202:205], v[184:187], v[84:87]
	v_mfma_f32_16x16x32_bf16 v[76:79], v[210:213], v[184:187], v[76:79]
	v_mfma_f32_16x16x32_bf16 v[68:71], v[202:205], v[192:195], v[68:71]
	v_mfma_f32_16x16x32_bf16 v[64:67], v[210:213], v[192:195], v[64:67]
	v_mfma_f32_16x16x32_bf16 v[112:115], v[206:209], v[172:175], v[112:115]
	v_mfma_f32_16x16x32_bf16 v[108:111], v[214:217], v[172:175], v[108:111]
	v_mfma_f32_16x16x32_bf16 v[100:103], v[206:209], v[180:183], v[100:103]
	v_mfma_f32_16x16x32_bf16 v[92:95], v[214:217], v[180:183], v[92:95]
	v_mfma_f32_16x16x32_bf16 v[84:87], v[206:209], v[188:191], v[84:87]
	v_mfma_f32_16x16x32_bf16 v[76:79], v[214:217], v[188:191], v[76:79]
	v_mfma_f32_16x16x32_bf16 v[68:71], v[206:209], v[196:199], v[68:71]
	v_mfma_f32_16x16x32_bf16 v[64:67], v[214:217], v[196:199], v[64:67]
	s_setprio 0
	s_mov_b32 m0, s42
	s_barrier
	ds_read_b128 v[168:171], v166 offset:16384
	ds_read_b128 v[172:175], v166 offset:17408
	ds_read_b128 v[176:179], v166 offset:18432
	ds_read_b128 v[180:183], v166 offset:19456
	ds_read_b128 v[184:187], v166 offset:20480
	ds_read_b128 v[188:191], v166 offset:21504
	ds_read_b128 v[192:195], v166 offset:22528
	ds_read_b128 v[196:199], v166 offset:23552
	global_load_lds_dwordx4 v134, s[36:37]
	s_mov_b32 m0, s43
	s_nop 0
	global_load_lds_dwordx4 v130, s[36:37]
	s_barrier
	s_waitcnt lgkmcnt(0)
	s_setprio 1
	s_waitcnt lgkmcnt(0)
	v_mfma_f32_16x16x32_bf16 v[60:63], v[144:147], v[168:171], v[60:63]
	v_mfma_f32_16x16x32_bf16 v[56:59], v[152:155], v[168:171], v[56:59]
	v_mfma_f32_16x16x32_bf16 v[48:51], v[144:147], v[176:179], v[48:51]
	v_mfma_f32_16x16x32_bf16 v[40:43], v[152:155], v[176:179], v[40:43]
	v_mfma_f32_16x16x32_bf16 v[32:35], v[144:147], v[184:187], v[32:35]
	v_mfma_f32_16x16x32_bf16 v[24:27], v[152:155], v[184:187], v[24:27]
	v_mfma_f32_16x16x32_bf16 v[16:19], v[144:147], v[192:195], v[16:19]
	v_mfma_f32_16x16x32_bf16 v[8:11], v[152:155], v[192:195], v[8:11]
	v_mfma_f32_16x16x32_bf16 v[60:63], v[148:151], v[172:175], v[60:63]
	v_mfma_f32_16x16x32_bf16 v[56:59], v[156:159], v[172:175], v[56:59]
	v_mfma_f32_16x16x32_bf16 v[48:51], v[148:151], v[180:183], v[48:51]
	v_mfma_f32_16x16x32_bf16 v[40:43], v[156:159], v[180:183], v[40:43]
	v_mfma_f32_16x16x32_bf16 v[32:35], v[148:151], v[188:191], v[32:35]
	v_mfma_f32_16x16x32_bf16 v[24:27], v[156:159], v[188:191], v[24:27]
	v_mfma_f32_16x16x32_bf16 v[16:19], v[148:151], v[196:199], v[16:19]
	v_mfma_f32_16x16x32_bf16 v[8:11], v[156:159], v[196:199], v[8:11]
	s_setprio 0
	s_barrier
	s_add_u32 s16, s34, 0xb0000
	s_addc_u32 s17, s35, 0
	s_add_i32 s20, s59, s40
	s_mov_b32 m0, s20
	s_nop 0
	global_load_lds_dwordx4 v132, s[16:17]
	s_add_i32 m0, s20, 0x2000
	s_nop 0
	global_load_lds_dwordx4 v128, s[16:17]
	s_add_u32 s16, s36, 0xb0000
	s_addc_u32 s17, s37, 0
	s_mov_b32 m0, s44
	s_nop 0
	global_load_lds_dwordx4 v134, s[16:17]
	s_mov_b32 m0, s45
	s_nop 0
	global_load_lds_dwordx4 v130, s[16:17]
	s_waitcnt vmcnt(10)
	s_barrier
	s_setprio 1
	v_mfma_f32_16x16x32_bf16 v[52:55], v[202:205], v[168:171], v[52:55]
	v_mfma_f32_16x16x32_bf16 v[44:47], v[210:213], v[168:171], v[44:47]
	v_mfma_f32_16x16x32_bf16 v[36:39], v[202:205], v[176:179], v[36:39]
	v_mfma_f32_16x16x32_bf16 v[28:31], v[210:213], v[176:179], v[28:31]
	v_mfma_f32_16x16x32_bf16 v[20:23], v[202:205], v[184:187], v[20:23]
	v_mfma_f32_16x16x32_bf16 v[12:15], v[210:213], v[184:187], v[12:15]
	v_mfma_f32_16x16x32_bf16 v[4:7], v[202:205], v[192:195], v[4:7]
	v_mfma_f32_16x16x32_bf16 v[0:3], v[210:213], v[192:195], v[0:3]
	v_mfma_f32_16x16x32_bf16 v[52:55], v[206:209], v[172:175], v[52:55]
	v_mfma_f32_16x16x32_bf16 v[44:47], v[214:217], v[172:175], v[44:47]
	v_mfma_f32_16x16x32_bf16 v[36:39], v[206:209], v[180:183], v[36:39]
	v_mfma_f32_16x16x32_bf16 v[28:31], v[214:217], v[180:183], v[28:31]
	v_mfma_f32_16x16x32_bf16 v[20:23], v[206:209], v[188:191], v[20:23]
	v_mfma_f32_16x16x32_bf16 v[12:15], v[214:217], v[188:191], v[12:15]
	v_mfma_f32_16x16x32_bf16 v[4:7], v[206:209], v[196:199], v[4:7]
	v_mfma_f32_16x16x32_bf16 v[0:3], v[214:217], v[196:199], v[0:3]
	s_setprio 0
	s_add_i32 s20, 0, 0x18000
	v_add_u32_e32 v156, s20, v164
	s_barrier
	ds_read_b128 v[144:147], v156
	ds_read_b128 v[148:151], v156 offset:1024
	ds_read_b128 v[152:155], v156 offset:2048
	ds_read_b128 v[156:159], v156 offset:3072
	ds_read_b128 v[168:171], v166 offset:32768
	ds_read_b128 v[172:175], v166 offset:33792
	ds_read_b128 v[176:179], v166 offset:34816
	ds_read_b128 v[180:183], v166 offset:35840
	ds_read_b128 v[184:187], v166 offset:36864
	ds_read_b128 v[188:191], v166 offset:37888
	ds_read_b128 v[192:195], v166 offset:38912
	ds_read_b128 v[196:199], v166 offset:39936
	s_waitcnt lgkmcnt(8)
	s_waitcnt vmcnt(8)
	s_barrier
; #define PG8_STAGE(bufoff, gbase, voff) do { _Pragma("unroll") for (int _i = 0; _i < 2; ++_i) \
;         __builtin_amdgcn_global_load_lds((const unsigned*)((const char*)(gbase) + (voff)[_i]), (LAS unsigned*)(lds + (bufoff) + ldsw + _i * 8192), 16, 0, 0); } while (0)
; #define PG8_LDA(dst, b, h) do { _Pragma("unroll") for (int m = 0; m < 4; ++m) _Pragma("unroll") for (int k = 0; k < 2; ++k) dst[m][k] = *(const LAS bf16x8*)(lds + PG8_SA(b, h) + aoff + m * 2048 + k * 1024); } while (0)
; #define PG8_LDB(dst, b, h) do { _Pragma("unroll") for (int n = 0; n < 2; ++n) _Pragma("unroll") for (int k = 0; k < 2; ++k) dst[n][k] = *(const LAS bf16x8*)(lds + PG8_SB(b, h) + boff + n * 2048 + k * 1024); } while (0)
; #define PG8_MMA(ai, bj, At, Bt) do { __builtin_amdgcn_s_setprio(1); _Pragma("unroll") for (int m = 0; m < 4; ++m) _Pragma("unroll") for (int n = 0; n < 2; ++n) _Pragma("unroll") for (int k = 0; k < 2; ++k) \
;         acc[ai][bj][m][n] = __builtin_amdgcn_mfma_f32_16x16x32_bf16(Bt[n][k], At[m][k], acc[ai][bj][m][n], 0, 0, 0); __builtin_amdgcn_s_setprio(0); } while (0)
; #define PG8_WAIT_V(n) asm volatile("s_waitcnt vmcnt(" #n ")" ::: "memory")
; #define PG8_WAIT_L(n) asm volatile("s_waitcnt lgkmcnt(" #n ")" ::: "memory")
; #define PG8_BAR __builtin_amdgcn_s_barrier()
; #define PG8_SCHED __builtin_amdgcn_sched_barrier(0)
; template <class Epi, class Sched>
; __device__ __forceinline__ void gemm_phase(LAS unsigned char* lds, const Gemm g, const Sched& S, const Epi& E) {
;     ...
;             PG8_WAIT_L(8); PG8_BAR; PG8_WAIT_L(0); PG8_MMA(0, 0, At, B0); PG8_BAR; PG8_SCHED;
;             PG8_LDB(B1, 1, 1); PG8_STAGE(PG8_SB(1, 0), b3, voffB);
;             PG8_BAR; PG8_WAIT_L(0); PG8_MMA(0, 1, At, B1); PG8_BAR;
;             PG8_LDA(At, 1, 1); PG8_STAGE(PG8_SA(1, 0), a3, voffA);
;             PG8_BAR; PG8_WAIT_L(0); PG8_MMA(1, 0, At, B0); PG8_BAR; PG8_SCHED;
;             PG8_STAGE(PG8_SB(1, 1), b3 + hstep, voffB);
;             PG8_WAIT_V(6); PG8_BAR; PG8_MMA(1, 1, At, B1); PG8_BAR;
;     __device__ __forceinline__ void operator()(const AccT& acc, const Unit& u, int wr, int wc, int fr, int fq) const {
;     ...
;         const int rowt = u.pm * 256; const bool isc = rowt >= MX; const int b = isc ? 32 : (rowt >> 11);
;         const float* res = isc ? res_c + (size_t)(rowt - MX) * DM : res_x + (size_t)rowt * DM; bf16_t* out = hb + (size_t)rowt * DM;
	s_waitcnt lgkmcnt(0)
	s_setprio 1
	s_waitcnt lgkmcnt(0)
	v_mfma_f32_16x16x32_bf16 v[124:127], v[144:147], v[168:171], v[124:127]
	v_mfma_f32_16x16x32_bf16 v[120:123], v[152:155], v[168:171], v[120:123]
	v_mfma_f32_16x16x32_bf16 v[116:119], v[144:147], v[176:179], v[116:119]
	v_mfma_f32_16x16x32_bf16 v[104:107], v[152:155], v[176:179], v[104:107]
	v_mfma_f32_16x16x32_bf16 v[96:99], v[144:147], v[184:187], v[96:99]
	v_mfma_f32_16x16x32_bf16 v[88:91], v[152:155], v[184:187], v[88:91]
	v_mfma_f32_16x16x32_bf16 v[80:83], v[144:147], v[192:195], v[80:83]
	v_mfma_f32_16x16x32_bf16 v[72:75], v[152:155], v[192:195], v[72:75]
	v_mfma_f32_16x16x32_bf16 v[124:127], v[148:151], v[172:175], v[124:127]
	v_mfma_f32_16x16x32_bf16 v[120:123], v[156:159], v[172:175], v[120:123]
	v_mfma_f32_16x16x32_bf16 v[116:119], v[148:151], v[180:183], v[116:119]
	v_mfma_f32_16x16x32_bf16 v[104:107], v[156:159], v[180:183], v[104:107]
	v_mfma_f32_16x16x32_bf16 v[96:99], v[148:151], v[188:191], v[96:99]
	v_mfma_f32_16x16x32_bf16 v[88:91], v[156:159], v[188:191], v[88:91]
	v_mfma_f32_16x16x32_bf16 v[80:83], v[148:151], v[196:199], v[80:83]
	v_mfma_f32_16x16x32_bf16 v[72:75], v[156:159], v[196:199], v[72:75]
	s_setprio 0
	s_barrier
	s_add_i32 s21, 0, 0x1c000
	s_add_i32 s16, s20, s40
	v_add_u32_e32 v214, s21, v164
	s_add_u32 s8, s34, 0x80
	s_addc_u32 s9, s35, 0
	s_mov_b32 m0, s16
	ds_read_b128 v[202:205], v214
	ds_read_b128 v[206:209], v214 offset:1024
	ds_read_b128 v[210:213], v214 offset:2048
	ds_read_b128 v[214:217], v214 offset:3072
	global_load_lds_dwordx4 v132, s[8:9]
	s_add_i32 m0, s16, 0x2000
	s_nop 0
	global_load_lds_dwordx4 v128, s[8:9]
	s_waitcnt vmcnt(8)
	s_barrier
	s_waitcnt lgkmcnt(0)
	s_setprio 1
	s_waitcnt lgkmcnt(0)
	v_mfma_f32_16x16x32_bf16 v[112:115], v[202:205], v[168:171], v[112:115]
	v_mfma_f32_16x16x32_bf16 v[108:111], v[210:213], v[168:171], v[108:111]
	v_mfma_f32_16x16x32_bf16 v[100:103], v[202:205], v[176:179], v[100:103]
	v_mfma_f32_16x16x32_bf16 v[92:95], v[210:213], v[176:179], v[92:95]
	v_mfma_f32_16x16x32_bf16 v[84:87], v[202:205], v[184:187], v[84:87]
	v_mfma_f32_16x16x32_bf16 v[76:79], v[210:213], v[184:187], v[76:79]
	v_mfma_f32_16x16x32_bf16 v[68:71], v[202:205], v[192:195], v[68:71]
	v_mfma_f32_16x16x32_bf16 v[64:67], v[210:213], v[192:195], v[64:67]
	v_mfma_f32_16x16x32_bf16 v[112:115], v[206:209], v[172:175], v[112:115]
	v_mfma_f32_16x16x32_bf16 v[108:111], v[214:217], v[172:175], v[108:111]
	v_mfma_f32_16x16x32_bf16 v[100:103], v[206:209], v[180:183], v[100:103]
	v_mfma_f32_16x16x32_bf16 v[92:95], v[214:217], v[180:183], v[92:95]
	v_mfma_f32_16x16x32_bf16 v[84:87], v[206:209], v[188:191], v[84:87]
	v_mfma_f32_16x16x32_bf16 v[76:79], v[214:217], v[188:191], v[76:79]
	v_mfma_f32_16x16x32_bf16 v[68:71], v[206:209], v[196:199], v[68:71]
	v_mfma_f32_16x16x32_bf16 v[64:67], v[214:217], v[196:199], v[64:67]
	s_setprio 0
	s_mov_b32 m0, s52
	s_add_u32 s8, s36, 0x80
	s_addc_u32 s9, s37, 0
	s_barrier
	ds_read_b128 v[168:171], v166 offset:49152
	ds_read_b128 v[172:175], v166 offset:50176
	ds_read_b128 v[176:179], v166 offset:51200
	ds_read_b128 v[180:183], v166 offset:52224
	ds_read_b128 v[184:187], v166 offset:53248
	ds_read_b128 v[188:191], v166 offset:54272
	ds_read_b128 v[192:195], v166 offset:55296
	ds_read_b128 v[196:199], v166 offset:56320
	global_load_lds_dwordx4 v134, s[8:9]
	s_mov_b32 m0, s53
	s_nop 0
	global_load_lds_dwordx4 v130, s[8:9]
	s_barrier
	s_waitcnt lgkmcnt(0)
	s_setprio 1
	s_waitcnt lgkmcnt(0)
	v_mfma_f32_16x16x32_bf16 v[60:63], v[144:147], v[168:171], v[60:63]
	v_mfma_f32_16x16x32_bf16 v[56:59], v[152:155], v[168:171], v[56:59]
	v_mfma_f32_16x16x32_bf16 v[48:51], v[144:147], v[176:179], v[48:51]
	v_mfma_f32_16x16x32_bf16 v[40:43], v[152:155], v[176:179], v[40:43]
	v_mfma_f32_16x16x32_bf16 v[32:35], v[144:147], v[184:187], v[32:35]
	v_mfma_f32_16x16x32_bf16 v[24:27], v[152:155], v[184:187], v[24:27]
	v_mfma_f32_16x16x32_bf16 v[16:19], v[144:147], v[192:195], v[16:19]
	v_mfma_f32_16x16x32_bf16 v[8:11], v[152:155], v[192:195], v[8:11]
	v_mfma_f32_16x16x32_bf16 v[60:63], v[148:151], v[172:175], v[60:63]
	v_mfma_f32_16x16x32_bf16 v[56:59], v[156:159], v[172:175], v[56:59]
	v_mfma_f32_16x16x32_bf16 v[48:51], v[148:151], v[180:183], v[48:51]
	v_mfma_f32_16x16x32_bf16 v[40:43], v[156:159], v[180:183], v[40:43]
	v_mfma_f32_16x16x32_bf16 v[32:35], v[148:151], v[188:191], v[32:35]
	v_mfma_f32_16x16x32_bf16 v[24:27], v[156:159], v[188:191], v[24:27]
	v_mfma_f32_16x16x32_bf16 v[16:19], v[148:151], v[196:199], v[16:19]
	v_mfma_f32_16x16x32_bf16 v[8:11], v[156:159], v[196:199], v[8:11]
	s_setprio 0
	s_barrier
	s_add_u32 s16, s34, 0xb0080
	s_addc_u32 s17, s35, 0
	s_add_i32 s20, s21, s40
	s_mov_b32 m0, s20
	s_nop 0
	global_load_lds_dwordx4 v132, s[16:17]
	s_add_i32 m0, s20, 0x2000
	s_nop 0
	global_load_lds_dwordx4 v128, s[16:17]
	s_waitcnt vmcnt(8)
	s_barrier
	s_setprio 1
	v_mfma_f32_16x16x32_bf16 v[52:55], v[202:205], v[168:171], v[52:55]
	v_mfma_f32_16x16x32_bf16 v[44:47], v[210:213], v[168:171], v[44:47]
	v_mfma_f32_16x16x32_bf16 v[36:39], v[202:205], v[176:179], v[36:39]
	v_mfma_f32_16x16x32_bf16 v[28:31], v[210:213], v[176:179], v[28:31]
	v_mfma_f32_16x16x32_bf16 v[20:23], v[202:205], v[184:187], v[20:23]
	v_mfma_f32_16x16x32_bf16 v[12:15], v[210:213], v[184:187], v[12:15]
	v_mfma_f32_16x16x32_bf16 v[4:7], v[202:205], v[192:195], v[4:7]
	v_mfma_f32_16x16x32_bf16 v[0:3], v[210:213], v[192:195], v[0:3]
	v_mfma_f32_16x16x32_bf16 v[52:55], v[206:209], v[172:175], v[52:55]
	v_mfma_f32_16x16x32_bf16 v[44:47], v[214:217], v[172:175], v[44:47]
	v_mfma_f32_16x16x32_bf16 v[36:39], v[206:209], v[180:183], v[36:39]
	v_mfma_f32_16x16x32_bf16 v[28:31], v[214:217], v[180:183], v[28:31]
	v_mfma_f32_16x16x32_bf16 v[20:23], v[206:209], v[188:191], v[20:23]
	v_mfma_f32_16x16x32_bf16 v[12:15], v[214:217], v[188:191], v[12:15]
	v_mfma_f32_16x16x32_bf16 v[4:7], v[206:209], v[196:199], v[4:7]
	v_mfma_f32_16x16x32_bf16 v[0:3], v[214:217], v[196:199], v[0:3]
	s_setprio 0
	s_add_i32 s68, s68, 2
	s_add_u32 s0, s0, 0x100
	s_addc_u32 s67, s67, 0
	s_cmp_gt_u32 s68, 41
	s_mov_b64 s[26:27], s[28:29]
	s_barrier
	s_cbranch_scc0 .LBB0_305
	s_lshl_b32 s0, s66, 8
	v_mov_b32_e32 v145, v163
	v_mov_b32_e32 v144, v162
	s_cmpk_lt_i32 s66, 0x100
	s_cbranch_scc0 .LBB0_308
	s_ashr_i32 s29, s0, 31
	s_mov_b32 s28, s0
	s_lshl_b64 s[16:17], s[28:29], 12
	v_readlane_b32 s80, v254, 23
	v_readlane_b32 s81, v254, 24
	s_add_u32 s26, s80, s16
	v_readlane_b32 s82, v254, 25
	v_readlane_b32 s83, v254, 26
	v_readlane_b32 s84, v254, 27
	v_readlane_b32 s85, v254, 28
	v_readlane_b32 s86, v254, 29
	v_readlane_b32 s87, v254, 30
	v_readlane_b32 s88, v254, 31
	v_readlane_b32 s89, v254, 32
	v_readlane_b32 s90, v254, 33
	v_readlane_b32 s91, v254, 34
	v_readlane_b32 s92, v254, 35
	v_readlane_b32 s93, v254, 36
	v_readlane_b32 s94, v254, 37
	v_readlane_b32 s95, v254, 38
	s_addc_u32 s27, s81, s17
	s_cbranch_execnz .LBB0_297
	s_branch .LBB0_296

; #define PG8_STAGE(bufoff, gbase, voff) do { _Pragma("unroll") for (int _i = 0; _i < 2; ++_i) \
;         __builtin_amdgcn_global_load_lds((const unsigned*)((const char*)(gbase) + (voff)[_i]), (LAS unsigned*)(lds + (bufoff) + ldsw + _i * 8192), 16, 0, 0); } while (0)
; #define PG8_LDA(dst, b, h) do { _Pragma("unroll") for (int m = 0; m < 4; ++m) _Pragma("unroll") for (int k = 0; k < 2; ++k) dst[m][k] = *(const LAS bf16x8*)(lds + PG8_SA(b, h) + aoff + m * 2048 + k * 1024); } while (0)
; #define PG8_LDB(dst, b, h) do { _Pragma("unroll") for (int n = 0; n < 2; ++n) _Pragma("unroll") for (int k = 0; k < 2; ++k) dst[n][k] = *(const LAS bf16x8*)(lds + PG8_SB(b, h) + boff + n * 2048 + k * 1024); } while (0)
; #define PG8_WAIT_V(n) asm volatile("s_waitcnt vmcnt(" #n ")" ::: "memory")
; #define PG8_WAIT_L(n) asm volatile("s_waitcnt lgkmcnt(" #n ")" ::: "memory")
; #define PG8_BAR __builtin_amdgcn_s_barrier()
; #define PG8_SCHED __builtin_amdgcn_sched_barrier(0)
; template <class Epi, class Sched>
; __device__ __forceinline__ void gemm_phase(LAS unsigned char* lds, const Gemm g, const Sched& S, const Epi& E) {
;     ...
;         const bool has_next = S.next(ui + 1, nxt);
;         const char* nA = has_next ? (const char*)g.A + (size_t)nxt.pm * tstep : cA; const char* nB = has_next ? (const char*)g.Bt + (size_t)nxt.pn * tstep : cB;
;         for (int t = 0; t < nt; t += 2) {
;             const bool last = (t == nt - 2);
;             const char* a1 = cA + (size_t)(t + 1) * kstep;
;             const char* a2 = last ? nA : cA + (size_t)(t + 2) * kstep; const char* b2 = last ? nB : cB + (size_t)(t + 2) * kstep;
;             const char* a3 = a2 + kstep; const char* b3 = b2 + kstep;
;             PG8_LDB(B0, 0, 0); PG8_SCHED; PG8_LDA(At, 0, 0); PG8_STAGE(PG8_SA(1, 1), a1 + hstep, voffA);
;             PG8_WAIT_L(8); PG8_BAR; PG8_WAIT_L(0); PG8_MMA(0, 0, At, B0); PG8_BAR; PG8_SCHED;
;             PG8_LDB(B1, 0, 1); PG8_STAGE(PG8_SB(0, 0), b2, voffB);
;             PG8_BAR; PG8_WAIT_L(0); PG8_MMA(0, 1, At, B1); PG8_BAR;
;             PG8_LDA(At, 0, 1); PG8_STAGE(PG8_SA(0, 0), a2, voffA);
;             PG8_BAR; PG8_WAIT_L(0); PG8_MMA(1, 0, At, B0); PG8_BAR; PG8_SCHED;
;             PG8_STAGE(PG8_SB(0, 1), b2 + hstep, voffB);
;             PG8_WAIT_V(6); PG8_BAR; PG8_MMA(1, 1, At, B1); PG8_BAR;
.LBB0_577:
	s_ashr_i32 s21, s20, 31
	v_cmp_lt_i64_e32 vcc, s[22:23], v[156:157]
	s_lshl_b64 s[22:23], s[20:21], 19
	s_add_u32 s22, s96, s22
	s_addc_u32 s23, s97, s23
	s_and_b64 s[24:25], vcc, exec
	s_cselect_b32 s5, s23, s7
	s_cselect_b32 s21, s22, s6
	s_ashr_i32 s19, s18, 31
	s_lshl_b64 s[24:25], s[18:19], 19
	s_add_u32 s24, s31, s24
	s_addc_u32 s25, s33, s25
	s_and_b64 s[28:29], vcc, exec
	s_cselect_b32 s19, s25, s27
	s_cselect_b32 s53, s24, s26
	s_add_u32 s6, s6, 0x40080
	s_addc_u32 s7, s7, 0
	s_add_u32 s54, s26, 0x100
	s_addc_u32 s55, s27, 0
	s_mov_b32 s56, -2
	s_waitcnt lgkmcnt(0)
	ds_read_b128 v[128:131], v167
	ds_read_b128 v[132:135], v167 offset:1024
	ds_read_b128 v[136:139], v167 offset:2048
	ds_read_b128 v[160:163], v167 offset:3072
	s_add_u32 s26, s6, 0xfffc0080
	s_addc_u32 s27, s7, -1
	s_cmp_eq_u32 s56, 12
	s_cselect_b32 s29, s5, s27
	s_cselect_b32 s28, s21, s26
	s_cselect_b32 s27, s19, s55
	s_cselect_b32 s26, s53, s54
	s_add_i32 m0, s37, 0xc000
	ds_read_b128 v[170:173], v168
	ds_read_b128 v[174:177], v168 offset:1024
	ds_read_b128 v[178:181], v168 offset:2048
	ds_read_b128 v[182:185], v168 offset:3072
	ds_read_b128 v[186:189], v168 offset:4096
	ds_read_b128 v[190:193], v168 offset:5120
	ds_read_b128 v[194:197], v168 offset:6144
	ds_read_b128 v[202:205], v168 offset:7168
	global_load_lds_dwordx4 v152, s[6:7]
	s_add_i32 m0, s37, 0xe000
	s_nop 0
	global_load_lds_dwordx4 v154, s[6:7]
	s_waitcnt lgkmcnt(8)
	s_waitcnt vmcnt(8)
	s_barrier
	s_waitcnt lgkmcnt(0)
	s_setprio 1
	s_waitcnt lgkmcnt(0)
	v_mfma_f32_16x16x32_bf16 v[124:127], v[128:131], v[170:173], 0
	v_mfma_f32_16x16x32_bf16 v[120:123], v[136:139], v[170:173], 0
	v_mfma_f32_16x16x32_bf16 v[108:111], v[128:131], v[178:181], 0
	v_mfma_f32_16x16x32_bf16 v[104:107], v[136:139], v[178:181], 0
	v_mfma_f32_16x16x32_bf16 v[92:95], v[128:131], v[186:189], 0
	v_mfma_f32_16x16x32_bf16 v[88:91], v[136:139], v[186:189], 0
	v_mfma_f32_16x16x32_bf16 v[76:79], v[128:131], v[194:197], 0
	v_mfma_f32_16x16x32_bf16 v[72:75], v[136:139], v[194:197], 0
	v_mfma_f32_16x16x32_bf16 v[124:127], v[132:135], v[174:177], v[124:127]
	v_mfma_f32_16x16x32_bf16 v[120:123], v[160:163], v[174:177], v[120:123]
	v_mfma_f32_16x16x32_bf16 v[108:111], v[132:135], v[182:185], v[108:111]
	v_mfma_f32_16x16x32_bf16 v[104:107], v[160:163], v[182:185], v[104:107]
	v_mfma_f32_16x16x32_bf16 v[92:95], v[132:135], v[190:193], v[92:95]
	v_mfma_f32_16x16x32_bf16 v[88:91], v[160:163], v[190:193], v[88:91]
	v_mfma_f32_16x16x32_bf16 v[76:79], v[132:135], v[202:205], v[76:79]
	v_mfma_f32_16x16x32_bf16 v[72:75], v[160:163], v[202:205], v[72:75]
	s_setprio 0
	s_barrier
	s_add_i32 s57, s48, s34
	s_mov_b32 m0, s57
	ds_read_b128 v[206:209], v169
	ds_read_b128 v[210:213], v169 offset:1024
	ds_read_b128 v[214:217], v169 offset:2048
	ds_read_b128 v[218:221], v169 offset:3072
	global_load_lds_dwordx4 v146, s[26:27]
	s_add_i32 m0, s57, 0x2000
	s_nop 0
	global_load_lds_dwordx4 v142, s[26:27]
	s_waitcnt vmcnt(8)
	s_barrier
	s_waitcnt lgkmcnt(0)
	s_setprio 1
	s_waitcnt lgkmcnt(0)
	v_mfma_f32_16x16x32_bf16 v[116:119], v[206:209], v[170:173], 0
	v_mfma_f32_16x16x32_bf16 v[112:115], v[214:217], v[170:173], 0
	v_mfma_f32_16x16x32_bf16 v[100:103], v[206:209], v[178:181], 0
	v_mfma_f32_16x16x32_bf16 v[96:99], v[214:217], v[178:181], 0
	v_mfma_f32_16x16x32_bf16 v[84:87], v[206:209], v[186:189], 0
	v_mfma_f32_16x16x32_bf16 v[80:83], v[214:217], v[186:189], 0
	v_mfma_f32_16x16x32_bf16 v[68:71], v[206:209], v[194:197], 0
	v_mfma_f32_16x16x32_bf16 v[64:67], v[214:217], v[194:197], 0
	v_mfma_f32_16x16x32_bf16 v[116:119], v[210:213], v[174:177], v[116:119]
	v_mfma_f32_16x16x32_bf16 v[112:115], v[218:221], v[174:177], v[112:115]
	v_mfma_f32_16x16x32_bf16 v[100:103], v[210:213], v[182:185], v[100:103]
	v_mfma_f32_16x16x32_bf16 v[96:99], v[218:221], v[182:185], v[96:99]
	v_mfma_f32_16x16x32_bf16 v[84:87], v[210:213], v[190:193], v[84:87]
	v_mfma_f32_16x16x32_bf16 v[80:83], v[218:221], v[190:193], v[80:83]
	v_mfma_f32_16x16x32_bf16 v[68:71], v[210:213], v[202:205], v[68:71]
	v_mfma_f32_16x16x32_bf16 v[64:67], v[218:221], v[202:205], v[64:67]
	s_setprio 0
	s_mov_b32 m0, s37
	v_lshl_add_u64 v[222:223], s[28:29], 0, v[148:149]
	s_barrier
	ds_read_b128 v[170:173], v168 offset:16384
	ds_read_b128 v[174:177], v168 offset:17408
	ds_read_b128 v[178:181], v168 offset:18432
	ds_read_b128 v[182:185], v168 offset:19456
	ds_read_b128 v[186:189], v168 offset:20480
	ds_read_b128 v[190:193], v168 offset:21504
	ds_read_b128 v[194:197], v168 offset:22528
	ds_read_b128 v[202:205], v168 offset:23552
	global_load_lds_dwordx4 v148, s[28:29]
	v_lshl_add_u64 v[224:225], s[28:29], 0, v[144:145]
	s_mov_b32 m0, s38
	s_nop 0
	global_load_lds_dwordx4 v144, s[28:29]
	s_barrier
	s_waitcnt lgkmcnt(0)
	s_setprio 1
	s_waitcnt lgkmcnt(0)
	v_mfma_f32_16x16x32_bf16 v[60:63], v[128:131], v[170:173], 0
	v_mfma_f32_16x16x32_bf16 v[56:59], v[136:139], v[170:173], 0
	v_mfma_f32_16x16x32_bf16 v[44:47], v[128:131], v[178:181], 0
	v_mfma_f32_16x16x32_bf16 v[40:43], v[136:139], v[178:181], 0
	v_mfma_f32_16x16x32_bf16 v[28:31], v[128:131], v[186:189], 0
	v_mfma_f32_16x16x32_bf16 v[24:27], v[136:139], v[186:189], 0
	v_mfma_f32_16x16x32_bf16 v[12:15], v[128:131], v[194:197], 0
	v_mfma_f32_16x16x32_bf16 v[8:11], v[136:139], v[194:197], 0
	v_mfma_f32_16x16x32_bf16 v[60:63], v[132:135], v[174:177], v[60:63]
	v_mfma_f32_16x16x32_bf16 v[56:59], v[160:163], v[174:177], v[56:59]
	v_mfma_f32_16x16x32_bf16 v[44:47], v[132:135], v[182:185], v[44:47]
	v_mfma_f32_16x16x32_bf16 v[40:43], v[160:163], v[182:185], v[40:43]
	v_mfma_f32_16x16x32_bf16 v[28:31], v[132:135], v[190:193], v[28:31]
	v_mfma_f32_16x16x32_bf16 v[24:27], v[160:163], v[190:193], v[24:27]
	v_mfma_f32_16x16x32_bf16 v[12:15], v[132:135], v[202:205], v[12:15]
	v_mfma_f32_16x16x32_bf16 v[8:11], v[160:163], v[202:205], v[8:11]
	s_setprio 0
	s_barrier
; #define PG8_STAGE(bufoff, gbase, voff) do { _Pragma("unroll") for (int _i = 0; _i < 2; ++_i) \
;         __builtin_amdgcn_global_load_lds((const unsigned*)((const char*)(gbase) + (voff)[_i]), (LAS unsigned*)(lds + (bufoff) + ldsw + _i * 8192), 16, 0, 0); } while (0)
; #define PG8_LDA(dst, b, h) do { _Pragma("unroll") for (int m = 0; m < 4; ++m) _Pragma("unroll") for (int k = 0; k < 2; ++k) dst[m][k] = *(const LAS bf16x8*)(lds + PG8_SA(b, h) + aoff + m * 2048 + k * 1024); } while (0)
; #define PG8_LDB(dst, b, h) do { _Pragma("unroll") for (int n = 0; n < 2; ++n) _Pragma("unroll") for (int k = 0; k < 2; ++k) dst[n][k] = *(const LAS bf16x8*)(lds + PG8_SB(b, h) + boff + n * 2048 + k * 1024); } while (0)
; #define PG8_MMA(ai, bj, At, Bt) do { __builtin_amdgcn_s_setprio(1); _Pragma("unroll") for (int m = 0; m < 4; ++m) _Pragma("unroll") for (int n = 0; n < 2; ++n) _Pragma("unroll") for (int k = 0; k < 2; ++k) \
;         acc[ai][bj][m][n] = __builtin_amdgcn_mfma_f32_16x16x32_bf16(Bt[n][k], At[m][k], acc[ai][bj][m][n], 0, 0, 0); __builtin_amdgcn_s_setprio(0); } while (0)
; #define PG8_WAIT_V(n) asm volatile("s_waitcnt vmcnt(" #n ")" ::: "memory")
; #define PG8_WAIT_L(n) asm volatile("s_waitcnt lgkmcnt(" #n ")" ::: "memory")
; #define PG8_BAR __builtin_amdgcn_s_barrier()
; #define PG8_SCHED __builtin_amdgcn_sched_barrier(0)
; template <class Epi, class Sched>
; __device__ __forceinline__ void gemm_phase(LAS unsigned char* lds, const Gemm g, const Sched& S, const Epi& E) {
;     ...
;             PG8_WAIT_V(6); PG8_BAR; PG8_MMA(1, 1, At, B1); PG8_BAR;
;             PG8_LDB(B0, 1, 0); PG8_SCHED; PG8_LDA(At, 1, 0); PG8_STAGE(PG8_SA(0, 1), a2 + hstep, voffA);
;             PG8_WAIT_L(8); PG8_BAR; PG8_WAIT_L(0); PG8_MMA(0, 0, At, B0); PG8_BAR; PG8_SCHED;
;             PG8_LDB(B1, 1, 1); PG8_STAGE(PG8_SB(1, 0), b3, voffB);
;             PG8_BAR; PG8_WAIT_L(0); PG8_MMA(0, 1, At, B1); PG8_BAR;
;             PG8_LDA(At, 1, 1); PG8_STAGE(PG8_SA(1, 0), a3, voffA);
;             PG8_BAR; PG8_WAIT_L(0); PG8_MMA(1, 0, At, B0); PG8_BAR; PG8_SCHED;
	s_add_u32 s58, s26, 0x40000
	s_addc_u32 s59, s27, 0
	s_add_i32 s57, s49, s34
	s_mov_b32 m0, s57
	s_nop 0
	global_load_lds_dwordx4 v146, s[58:59]
	s_add_i32 m0, s57, 0x2000
	s_nop 0
	global_load_lds_dwordx4 v142, s[58:59]
	s_add_u32 s28, s28, 0x40000
	s_addc_u32 s29, s29, 0
	s_mov_b32 m0, s39
	s_nop 0
	global_load_lds_dwordx4 v148, s[28:29]
	s_mov_b32 m0, s40
	s_nop 0
	global_load_lds_dwordx4 v144, s[28:29]
	s_waitcnt vmcnt(10)
	s_barrier
	s_setprio 1
	v_mfma_f32_16x16x32_bf16 v[52:55], v[206:209], v[170:173], 0
	v_mfma_f32_16x16x32_bf16 v[48:51], v[214:217], v[170:173], 0
	v_mfma_f32_16x16x32_bf16 v[36:39], v[206:209], v[178:181], 0
	v_mfma_f32_16x16x32_bf16 v[32:35], v[214:217], v[178:181], 0
	v_mfma_f32_16x16x32_bf16 v[20:23], v[206:209], v[186:189], 0
	v_mfma_f32_16x16x32_bf16 v[16:19], v[214:217], v[186:189], 0
	v_mfma_f32_16x16x32_bf16 v[4:7], v[206:209], v[194:197], 0
	v_mfma_f32_16x16x32_bf16 v[0:3], v[214:217], v[194:197], 0
	v_mfma_f32_16x16x32_bf16 v[52:55], v[210:213], v[174:177], v[52:55]
	v_mfma_f32_16x16x32_bf16 v[48:51], v[218:221], v[174:177], v[48:51]
	v_mfma_f32_16x16x32_bf16 v[36:39], v[210:213], v[182:185], v[36:39]
	v_mfma_f32_16x16x32_bf16 v[32:35], v[218:221], v[182:185], v[32:35]
	v_mfma_f32_16x16x32_bf16 v[20:23], v[210:213], v[190:193], v[20:23]
	v_mfma_f32_16x16x32_bf16 v[16:19], v[218:221], v[190:193], v[16:19]
	v_mfma_f32_16x16x32_bf16 v[4:7], v[210:213], v[202:205], v[4:7]
	v_mfma_f32_16x16x32_bf16 v[0:3], v[218:221], v[202:205], v[0:3]
	s_setprio 0
	s_add_i32 s57, 0, 0x18000
	v_add_u32_e32 v150, s57, v166
	s_barrier
	ds_read_b128 v[128:131], v150
	ds_read_b128 v[132:135], v150 offset:1024
	ds_read_b128 v[136:139], v150 offset:2048
	ds_read_b128 v[160:163], v150 offset:3072
	ds_read_b128 v[170:173], v168 offset:32768
	ds_read_b128 v[174:177], v168 offset:33792
	ds_read_b128 v[178:181], v168 offset:34816
	ds_read_b128 v[182:185], v168 offset:35840
	ds_read_b128 v[186:189], v168 offset:36864
	ds_read_b128 v[190:193], v168 offset:37888
	ds_read_b128 v[194:197], v168 offset:38912
	ds_read_b128 v[202:205], v168 offset:39936
	s_waitcnt lgkmcnt(8)
	s_waitcnt vmcnt(8)
	s_barrier
	s_waitcnt lgkmcnt(0)
	s_setprio 1
	s_waitcnt lgkmcnt(0)
	v_mfma_f32_16x16x32_bf16 v[124:127], v[128:131], v[170:173], v[124:127]
	v_mfma_f32_16x16x32_bf16 v[120:123], v[136:139], v[170:173], v[120:123]
	v_mfma_f32_16x16x32_bf16 v[108:111], v[128:131], v[178:181], v[108:111]
	v_mfma_f32_16x16x32_bf16 v[104:107], v[136:139], v[178:181], v[104:107]
	v_mfma_f32_16x16x32_bf16 v[92:95], v[128:131], v[186:189], v[92:95]
	v_mfma_f32_16x16x32_bf16 v[88:91], v[136:139], v[186:189], v[88:91]
	v_mfma_f32_16x16x32_bf16 v[76:79], v[128:131], v[194:197], v[76:79]
	v_mfma_f32_16x16x32_bf16 v[72:75], v[136:139], v[194:197], v[72:75]
	v_mfma_f32_16x16x32_bf16 v[124:127], v[132:135], v[174:177], v[124:127]
	v_mfma_f32_16x16x32_bf16 v[120:123], v[160:163], v[174:177], v[120:123]
	v_mfma_f32_16x16x32_bf16 v[108:111], v[132:135], v[182:185], v[108:111]
	v_mfma_f32_16x16x32_bf16 v[104:107], v[160:163], v[182:185], v[104:107]
	v_mfma_f32_16x16x32_bf16 v[92:95], v[132:135], v[190:193], v[92:95]
	v_mfma_f32_16x16x32_bf16 v[88:91], v[160:163], v[190:193], v[88:91]
	v_mfma_f32_16x16x32_bf16 v[76:79], v[132:135], v[202:205], v[76:79]
	v_mfma_f32_16x16x32_bf16 v[72:75], v[160:163], v[202:205], v[72:75]
	s_setprio 0
	s_barrier
	s_add_i32 s28, 0, 0x1c000
	s_add_i32 s29, s57, s34
	v_add_u32_e32 v150, s28, v166
	s_add_u32 s0, s26, 0x80
	s_addc_u32 s1, s27, 0
	s_mov_b32 m0, s29
	ds_read_b128 v[206:209], v150
	ds_read_b128 v[210:213], v150 offset:1024
	ds_read_b128 v[214:217], v150 offset:2048
	ds_read_b128 v[218:221], v150 offset:3072
	global_load_lds_dwordx4 v146, s[0:1]
	s_add_i32 m0, s29, 0x2000
	s_nop 0
	global_load_lds_dwordx4 v142, s[0:1]
	s_waitcnt vmcnt(8)
	s_barrier
	s_waitcnt lgkmcnt(0)
	s_setprio 1
	s_waitcnt lgkmcnt(0)
	v_mfma_f32_16x16x32_bf16 v[116:119], v[206:209], v[170:173], v[116:119]
	v_mfma_f32_16x16x32_bf16 v[112:115], v[214:217], v[170:173], v[112:115]
	v_mfma_f32_16x16x32_bf16 v[100:103], v[206:209], v[178:181], v[100:103]
	v_mfma_f32_16x16x32_bf16 v[96:99], v[214:217], v[178:181], v[96:99]
	v_mfma_f32_16x16x32_bf16 v[84:87], v[206:209], v[186:189], v[84:87]
	v_mfma_f32_16x16x32_bf16 v[80:83], v[214:217], v[186:189], v[80:83]
	v_mfma_f32_16x16x32_bf16 v[68:71], v[206:209], v[194:197], v[68:71]
	v_mfma_f32_16x16x32_bf16 v[64:67], v[214:217], v[194:197], v[64:67]
	v_mfma_f32_16x16x32_bf16 v[116:119], v[210:213], v[174:177], v[116:119]
	v_mfma_f32_16x16x32_bf16 v[112:115], v[218:221], v[174:177], v[112:115]
	v_mfma_f32_16x16x32_bf16 v[100:103], v[210:213], v[182:185], v[100:103]
	v_mfma_f32_16x16x32_bf16 v[96:99], v[218:221], v[182:185], v[96:99]
	v_mfma_f32_16x16x32_bf16 v[84:87], v[210:213], v[190:193], v[84:87]
	v_mfma_f32_16x16x32_bf16 v[80:83], v[218:221], v[190:193], v[80:83]
	v_mfma_f32_16x16x32_bf16 v[68:71], v[210:213], v[202:205], v[68:71]
	v_mfma_f32_16x16x32_bf16 v[64:67], v[218:221], v[202:205], v[64:67]
	s_setprio 0
	s_mov_b32 m0, s44
	s_mov_b64 s[0:1], 0x80
	v_lshl_add_u64 v[140:141], v[222:223], 0, s[0:1]
	s_barrier
	ds_read_b128 v[170:173], v168 offset:49152
	ds_read_b128 v[174:177], v168 offset:50176
	ds_read_b128 v[178:181], v168 offset:51200
	ds_read_b128 v[182:185], v168 offset:52224
	ds_read_b128 v[186:189], v168 offset:53248
	ds_read_b128 v[190:193], v168 offset:54272
	ds_read_b128 v[194:197], v168 offset:55296
	ds_read_b128 v[202:205], v168 offset:56320
	global_load_lds_dwordx4 v[140:141], off
	v_lshl_add_u64 v[140:141], v[224:225], 0, s[0:1]
	s_mov_b32 m0, s45
	s_nop 0
	global_load_lds_dwordx4 v[140:141], off
	s_barrier
; #define PG8_STAGE(bufoff, gbase, voff) do { _Pragma("unroll") for (int _i = 0; _i < 2; ++_i) \
;         __builtin_amdgcn_global_load_lds((const unsigned*)((const char*)(gbase) + (voff)[_i]), (LAS unsigned*)(lds + (bufoff) + ldsw + _i * 8192), 16, 0, 0); } while (0)
; #define PG8_LDA(dst, b, h) do { _Pragma("unroll") for (int m = 0; m < 4; ++m) _Pragma("unroll") for (int k = 0; k < 2; ++k) dst[m][k] = *(const LAS bf16x8*)(lds + PG8_SA(b, h) + aoff + m * 2048 + k * 1024); } while (0)
; #define PG8_LDB(dst, b, h) do { _Pragma("unroll") for (int n = 0; n < 2; ++n) _Pragma("unroll") for (int k = 0; k < 2; ++k) dst[n][k] = *(const LAS bf16x8*)(lds + PG8_SB(b, h) + boff + n * 2048 + k * 1024); } while (0)
; #define PG8_MMA(ai, bj, At, Bt) do { __builtin_amdgcn_s_setprio(1); _Pragma("unroll") for (int m = 0; m < 4; ++m) _Pragma("unroll") for (int n = 0; n < 2; ++n) _Pragma("unroll") for (int k = 0; k < 2; ++k) \
;         acc[ai][bj][m][n] = __builtin_amdgcn_mfma_f32_16x16x32_bf16(Bt[n][k], At[m][k], acc[ai][bj][m][n], 0, 0, 0); __builtin_amdgcn_s_setprio(0); } while (0)
; #define PG8_WAIT_V(n) asm volatile("s_waitcnt vmcnt(" #n ")" ::: "memory")
; #define PG8_WAIT_L(n) asm volatile("s_waitcnt lgkmcnt(" #n ")" ::: "memory")
; #define PG8_BAR __builtin_amdgcn_s_barrier()
; #define PG8_SCHED __builtin_amdgcn_sched_barrier(0)
; template <class Epi, class Sched>
; __device__ __forceinline__ void gemm_phase(LAS unsigned char* lds, const Gemm g, const Sched& S, const Epi& E) {
;     ...
;             PG8_LDB(B0, 0, 0); PG8_SCHED; PG8_LDA(At, 0, 0); PG8_STAGE(PG8_SA(1, 1), a1 + hstep, voffA);
;             PG8_WAIT_L(8); PG8_BAR; PG8_WAIT_L(0); PG8_MMA(0, 0, At, B0); PG8_BAR; PG8_SCHED;
;             PG8_LDB(B1, 0, 1); PG8_STAGE(PG8_SB(0, 0), b2, voffB);
;             PG8_BAR; PG8_WAIT_L(0); PG8_MMA(0, 1, At, B1); PG8_BAR;
;             PG8_LDA(At, 0, 1); PG8_STAGE(PG8_SA(0, 0), a2, voffA);
;     ...
;             PG8_BAR; PG8_WAIT_L(0); PG8_MMA(1, 0, At, B0); PG8_BAR; PG8_SCHED;
;             PG8_STAGE(PG8_SB(1, 1), b3 + hstep, voffB);
;             PG8_WAIT_V(6); PG8_BAR; PG8_MMA(1, 1, At, B1); PG8_BAR;
	s_waitcnt lgkmcnt(0)
	s_setprio 1
	s_waitcnt lgkmcnt(0)
	v_mfma_f32_16x16x32_bf16 v[60:63], v[128:131], v[170:173], v[60:63]
	v_mfma_f32_16x16x32_bf16 v[56:59], v[136:139], v[170:173], v[56:59]
	v_mfma_f32_16x16x32_bf16 v[44:47], v[128:131], v[178:181], v[44:47]
	v_mfma_f32_16x16x32_bf16 v[40:43], v[136:139], v[178:181], v[40:43]
	v_mfma_f32_16x16x32_bf16 v[28:31], v[128:131], v[186:189], v[28:31]
	v_mfma_f32_16x16x32_bf16 v[24:27], v[136:139], v[186:189], v[24:27]
	v_mfma_f32_16x16x32_bf16 v[12:15], v[128:131], v[194:197], v[12:15]
	v_mfma_f32_16x16x32_bf16 v[8:11], v[136:139], v[194:197], v[8:11]
	v_mfma_f32_16x16x32_bf16 v[60:63], v[132:135], v[174:177], v[60:63]
	v_mfma_f32_16x16x32_bf16 v[56:59], v[160:163], v[174:177], v[56:59]
	v_mfma_f32_16x16x32_bf16 v[44:47], v[132:135], v[182:185], v[44:47]
	v_mfma_f32_16x16x32_bf16 v[40:43], v[160:163], v[182:185], v[40:43]
	v_mfma_f32_16x16x32_bf16 v[28:31], v[132:135], v[190:193], v[28:31]
	v_mfma_f32_16x16x32_bf16 v[24:27], v[160:163], v[190:193], v[24:27]
	v_mfma_f32_16x16x32_bf16 v[12:15], v[132:135], v[202:205], v[12:15]
	v_mfma_f32_16x16x32_bf16 v[8:11], v[160:163], v[202:205], v[8:11]
	s_setprio 0
	s_barrier
	s_add_u32 s26, s26, 0x40080
	s_addc_u32 s27, s27, 0
	s_add_i32 s28, s28, s34
	s_mov_b32 m0, s28
	s_nop 0
	global_load_lds_dwordx4 v146, s[26:27]
	s_add_i32 m0, s28, 0x2000
	s_nop 0
	global_load_lds_dwordx4 v142, s[26:27]
	s_waitcnt vmcnt(8)
	s_barrier
	s_setprio 1
	v_mfma_f32_16x16x32_bf16 v[52:55], v[206:209], v[170:173], v[52:55]
	v_mfma_f32_16x16x32_bf16 v[48:51], v[214:217], v[170:173], v[48:51]
	v_mfma_f32_16x16x32_bf16 v[36:39], v[206:209], v[178:181], v[36:39]
	v_mfma_f32_16x16x32_bf16 v[32:35], v[214:217], v[178:181], v[32:35]
	v_mfma_f32_16x16x32_bf16 v[20:23], v[206:209], v[186:189], v[20:23]
	v_mfma_f32_16x16x32_bf16 v[16:19], v[214:217], v[186:189], v[16:19]
	v_mfma_f32_16x16x32_bf16 v[4:7], v[206:209], v[194:197], v[4:7]
	v_mfma_f32_16x16x32_bf16 v[0:3], v[214:217], v[194:197], v[0:3]
	v_mfma_f32_16x16x32_bf16 v[52:55], v[210:213], v[174:177], v[52:55]
	v_mfma_f32_16x16x32_bf16 v[48:51], v[218:221], v[174:177], v[48:51]
	v_mfma_f32_16x16x32_bf16 v[36:39], v[210:213], v[182:185], v[36:39]
	v_mfma_f32_16x16x32_bf16 v[32:35], v[218:221], v[182:185], v[32:35]
	v_mfma_f32_16x16x32_bf16 v[20:23], v[210:213], v[190:193], v[20:23]
	v_mfma_f32_16x16x32_bf16 v[16:19], v[218:221], v[190:193], v[16:19]
	v_mfma_f32_16x16x32_bf16 v[4:7], v[210:213], v[202:205], v[4:7]
	v_mfma_f32_16x16x32_bf16 v[0:3], v[218:221], v[202:205], v[0:3]
	s_setprio 0
	s_add_i32 s56, s56, 2
	s_add_u32 s6, s6, 0x100
	s_addc_u32 s7, s7, 0
	s_add_u32 s54, s54, 0x100
	s_addc_u32 s55, s55, 0
	s_cmp_gt_u32 s56, 13
	s_barrier
.LBB0_578:
	ds_read_b128 v[128:131], v167
	ds_read_b128 v[132:135], v167 offset:1024
	ds_read_b128 v[136:139], v167 offset:2048
	ds_read_b128 v[160:163], v167 offset:3072
	s_add_u32 s26, s6, 0xfffc0080
	s_addc_u32 s27, s7, -1
	s_cmp_eq_u32 s56, 12
	s_cselect_b32 s29, s5, s27
	s_cselect_b32 s28, s21, s26
	s_cselect_b32 s27, s19, s55
	s_cselect_b32 s26, s53, s54
	s_add_i32 m0, s37, 0xc000
	ds_read_b128 v[170:173], v168
	ds_read_b128 v[174:177], v168 offset:1024
	ds_read_b128 v[178:181], v168 offset:2048
	ds_read_b128 v[182:185], v168 offset:3072
	ds_read_b128 v[186:189], v168 offset:4096
	ds_read_b128 v[190:193], v168 offset:5120
	ds_read_b128 v[194:197], v168 offset:6144
	ds_read_b128 v[202:205], v168 offset:7168
	global_load_lds_dwordx4 v152, s[6:7]
	s_add_i32 m0, s37, 0xe000
	s_nop 0
	global_load_lds_dwordx4 v154, s[6:7]
	s_waitcnt lgkmcnt(8)
	s_waitcnt vmcnt(8)
	s_barrier
	s_waitcnt lgkmcnt(0)
	s_setprio 1
	s_waitcnt lgkmcnt(0)
	v_mfma_f32_16x16x32_bf16 v[124:127], v[128:131], v[170:173], v[124:127]
	v_mfma_f32_16x16x32_bf16 v[120:123], v[136:139], v[170:173], v[120:123]
	v_mfma_f32_16x16x32_bf16 v[108:111], v[128:131], v[178:181], v[108:111]
	v_mfma_f32_16x16x32_bf16 v[104:107], v[136:139], v[178:181], v[104:107]
	v_mfma_f32_16x16x32_bf16 v[92:95], v[128:131], v[186:189], v[92:95]
	v_mfma_f32_16x16x32_bf16 v[88:91], v[136:139], v[186:189], v[88:91]
	v_mfma_f32_16x16x32_bf16 v[76:79], v[128:131], v[194:197], v[76:79]
	v_mfma_f32_16x16x32_bf16 v[72:75], v[136:139], v[194:197], v[72:75]
	v_mfma_f32_16x16x32_bf16 v[124:127], v[132:135], v[174:177], v[124:127]
	v_mfma_f32_16x16x32_bf16 v[120:123], v[160:163], v[174:177], v[120:123]
	v_mfma_f32_16x16x32_bf16 v[108:111], v[132:135], v[182:185], v[108:111]
	v_mfma_f32_16x16x32_bf16 v[104:107], v[160:163], v[182:185], v[104:107]
	v_mfma_f32_16x16x32_bf16 v[92:95], v[132:135], v[190:193], v[92:95]
	v_mfma_f32_16x16x32_bf16 v[88:91], v[160:163], v[190:193], v[88:91]
	v_mfma_f32_16x16x32_bf16 v[76:79], v[132:135], v[202:205], v[76:79]
	v_mfma_f32_16x16x32_bf16 v[72:75], v[160:163], v[202:205], v[72:75]
	s_setprio 0
	s_barrier
	s_add_i32 s57, s48, s34
	s_mov_b32 m0, s57
	ds_read_b128 v[206:209], v169
	ds_read_b128 v[210:213], v169 offset:1024
	ds_read_b128 v[214:217], v169 offset:2048
	ds_read_b128 v[218:221], v169 offset:3072
	global_load_lds_dwordx4 v146, s[26:27]
	s_add_i32 m0, s57, 0x2000
	s_nop 0
	global_load_lds_dwordx4 v142, s[26:27]
	s_waitcnt vmcnt(8)
	s_barrier
; #define PG8_STAGE(bufoff, gbase, voff) do { _Pragma("unroll") for (int _i = 0; _i < 2; ++_i) \
;         __builtin_amdgcn_global_load_lds((const unsigned*)((const char*)(gbase) + (voff)[_i]), (LAS unsigned*)(lds + (bufoff) + ldsw + _i * 8192), 16, 0, 0); } while (0)
; #define PG8_LDA(dst, b, h) do { _Pragma("unroll") for (int m = 0; m < 4; ++m) _Pragma("unroll") for (int k = 0; k < 2; ++k) dst[m][k] = *(const LAS bf16x8*)(lds + PG8_SA(b, h) + aoff + m * 2048 + k * 1024); } while (0)
; #define PG8_LDB(dst, b, h) do { _Pragma("unroll") for (int n = 0; n < 2; ++n) _Pragma("unroll") for (int k = 0; k < 2; ++k) dst[n][k] = *(const LAS bf16x8*)(lds + PG8_SB(b, h) + boff + n * 2048 + k * 1024); } while (0)
; #define PG8_MMA(ai, bj, At, Bt) do { __builtin_amdgcn_s_setprio(1); _Pragma("unroll") for (int m = 0; m < 4; ++m) _Pragma("unroll") for (int n = 0; n < 2; ++n) _Pragma("unroll") for (int k = 0; k < 2; ++k) \
;         acc[ai][bj][m][n] = __builtin_amdgcn_mfma_f32_16x16x32_bf16(Bt[n][k], At[m][k], acc[ai][bj][m][n], 0, 0, 0); __builtin_amdgcn_s_setprio(0); } while (0)
; #define PG8_WAIT_V(n) asm volatile("s_waitcnt vmcnt(" #n ")" ::: "memory")
; #define PG8_WAIT_L(n) asm volatile("s_waitcnt lgkmcnt(" #n ")" ::: "memory")
; #define PG8_BAR __builtin_amdgcn_s_barrier()
; #define PG8_SCHED __builtin_amdgcn_sched_barrier(0)
; template <class Epi, class Sched>
; __device__ __forceinline__ void gemm_phase(LAS unsigned char* lds, const Gemm g, const Sched& S, const Epi& E) {
;     ...
;             PG8_BAR; PG8_WAIT_L(0); PG8_MMA(1, 0, At, B0); PG8_BAR; PG8_SCHED;
;             PG8_STAGE(PG8_SB(0, 1), b2 + hstep, voffB);
;             PG8_WAIT_V(6); PG8_BAR; PG8_MMA(1, 1, At, B1); PG8_BAR;
;             PG8_LDB(B0, 1, 0); PG8_SCHED; PG8_LDA(At, 1, 0); PG8_STAGE(PG8_SA(0, 1), a2 + hstep, voffA);
;             PG8_WAIT_L(8); PG8_BAR; PG8_WAIT_L(0); PG8_MMA(0, 0, At, B0); PG8_BAR; PG8_SCHED;
	s_waitcnt lgkmcnt(0)
	s_setprio 1
	s_waitcnt lgkmcnt(0)
	v_mfma_f32_16x16x32_bf16 v[116:119], v[206:209], v[170:173], v[116:119]
	v_mfma_f32_16x16x32_bf16 v[112:115], v[214:217], v[170:173], v[112:115]
	v_mfma_f32_16x16x32_bf16 v[100:103], v[206:209], v[178:181], v[100:103]
	v_mfma_f32_16x16x32_bf16 v[96:99], v[214:217], v[178:181], v[96:99]
	v_mfma_f32_16x16x32_bf16 v[84:87], v[206:209], v[186:189], v[84:87]
	v_mfma_f32_16x16x32_bf16 v[80:83], v[214:217], v[186:189], v[80:83]
	v_mfma_f32_16x16x32_bf16 v[68:71], v[206:209], v[194:197], v[68:71]
	v_mfma_f32_16x16x32_bf16 v[64:67], v[214:217], v[194:197], v[64:67]
	v_mfma_f32_16x16x32_bf16 v[116:119], v[210:213], v[174:177], v[116:119]
	v_mfma_f32_16x16x32_bf16 v[112:115], v[218:221], v[174:177], v[112:115]
	v_mfma_f32_16x16x32_bf16 v[100:103], v[210:213], v[182:185], v[100:103]
	v_mfma_f32_16x16x32_bf16 v[96:99], v[218:221], v[182:185], v[96:99]
	v_mfma_f32_16x16x32_bf16 v[84:87], v[210:213], v[190:193], v[84:87]
	v_mfma_f32_16x16x32_bf16 v[80:83], v[218:221], v[190:193], v[80:83]
	v_mfma_f32_16x16x32_bf16 v[68:71], v[210:213], v[202:205], v[68:71]
	v_mfma_f32_16x16x32_bf16 v[64:67], v[218:221], v[202:205], v[64:67]
	s_setprio 0
	s_mov_b32 m0, s37
	v_lshl_add_u64 v[222:223], s[28:29], 0, v[148:149]
	s_barrier
	ds_read_b128 v[170:173], v168 offset:16384
	ds_read_b128 v[174:177], v168 offset:17408
	ds_read_b128 v[178:181], v168 offset:18432
	ds_read_b128 v[182:185], v168 offset:19456
	ds_read_b128 v[186:189], v168 offset:20480
	ds_read_b128 v[190:193], v168 offset:21504
	ds_read_b128 v[194:197], v168 offset:22528
	ds_read_b128 v[202:205], v168 offset:23552
	global_load_lds_dwordx4 v148, s[28:29]
	v_lshl_add_u64 v[224:225], s[28:29], 0, v[144:145]
	s_mov_b32 m0, s38
	s_nop 0
	global_load_lds_dwordx4 v144, s[28:29]
	s_barrier
	s_waitcnt lgkmcnt(0)
	s_setprio 1
	s_waitcnt lgkmcnt(0)
	v_mfma_f32_16x16x32_bf16 v[60:63], v[128:131], v[170:173], v[60:63]
	v_mfma_f32_16x16x32_bf16 v[56:59], v[136:139], v[170:173], v[56:59]
	v_mfma_f32_16x16x32_bf16 v[44:47], v[128:131], v[178:181], v[44:47]
	v_mfma_f32_16x16x32_bf16 v[40:43], v[136:139], v[178:181], v[40:43]
	v_mfma_f32_16x16x32_bf16 v[28:31], v[128:131], v[186:189], v[28:31]
	v_mfma_f32_16x16x32_bf16 v[24:27], v[136:139], v[186:189], v[24:27]
	v_mfma_f32_16x16x32_bf16 v[12:15], v[128:131], v[194:197], v[12:15]
	v_mfma_f32_16x16x32_bf16 v[8:11], v[136:139], v[194:197], v[8:11]
	v_mfma_f32_16x16x32_bf16 v[60:63], v[132:135], v[174:177], v[60:63]
	v_mfma_f32_16x16x32_bf16 v[56:59], v[160:163], v[174:177], v[56:59]
	v_mfma_f32_16x16x32_bf16 v[44:47], v[132:135], v[182:185], v[44:47]
	v_mfma_f32_16x16x32_bf16 v[40:43], v[160:163], v[182:185], v[40:43]
	v_mfma_f32_16x16x32_bf16 v[28:31], v[132:135], v[190:193], v[28:31]
	v_mfma_f32_16x16x32_bf16 v[24:27], v[160:163], v[190:193], v[24:27]
	v_mfma_f32_16x16x32_bf16 v[12:15], v[132:135], v[202:205], v[12:15]
	v_mfma_f32_16x16x32_bf16 v[8:11], v[160:163], v[202:205], v[8:11]
	s_setprio 0
	s_barrier
	s_add_u32 s58, s26, 0x40000
	s_addc_u32 s59, s27, 0
	s_add_i32 s57, s49, s34
	s_mov_b32 m0, s57
	s_nop 0
	global_load_lds_dwordx4 v146, s[58:59]
	s_add_i32 m0, s57, 0x2000
	s_nop 0
	global_load_lds_dwordx4 v142, s[58:59]
	s_add_u32 s28, s28, 0x40000
	s_addc_u32 s29, s29, 0
	s_mov_b32 m0, s39
	s_nop 0
	global_load_lds_dwordx4 v148, s[28:29]
	s_mov_b32 m0, s40
	s_nop 0
	global_load_lds_dwordx4 v144, s[28:29]
	s_waitcnt vmcnt(10)
	s_barrier
	s_setprio 1
	v_mfma_f32_16x16x32_bf16 v[52:55], v[206:209], v[170:173], v[52:55]
	v_mfma_f32_16x16x32_bf16 v[48:51], v[214:217], v[170:173], v[48:51]
	v_mfma_f32_16x16x32_bf16 v[36:39], v[206:209], v[178:181], v[36:39]
	v_mfma_f32_16x16x32_bf16 v[32:35], v[214:217], v[178:181], v[32:35]
	v_mfma_f32_16x16x32_bf16 v[20:23], v[206:209], v[186:189], v[20:23]
	v_mfma_f32_16x16x32_bf16 v[16:19], v[214:217], v[186:189], v[16:19]
	v_mfma_f32_16x16x32_bf16 v[4:7], v[206:209], v[194:197], v[4:7]
	v_mfma_f32_16x16x32_bf16 v[0:3], v[214:217], v[194:197], v[0:3]
	v_mfma_f32_16x16x32_bf16 v[52:55], v[210:213], v[174:177], v[52:55]
	v_mfma_f32_16x16x32_bf16 v[48:51], v[218:221], v[174:177], v[48:51]
	v_mfma_f32_16x16x32_bf16 v[36:39], v[210:213], v[182:185], v[36:39]
	v_mfma_f32_16x16x32_bf16 v[32:35], v[218:221], v[182:185], v[32:35]
	v_mfma_f32_16x16x32_bf16 v[20:23], v[210:213], v[190:193], v[20:23]
	v_mfma_f32_16x16x32_bf16 v[16:19], v[218:221], v[190:193], v[16:19]
	v_mfma_f32_16x16x32_bf16 v[4:7], v[210:213], v[202:205], v[4:7]
	v_mfma_f32_16x16x32_bf16 v[0:3], v[218:221], v[202:205], v[0:3]
	s_setprio 0
	s_add_i32 s57, 0, 0x18000
	v_add_u32_e32 v150, s57, v166
	s_barrier
	ds_read_b128 v[128:131], v150
	ds_read_b128 v[132:135], v150 offset:1024
	ds_read_b128 v[136:139], v150 offset:2048
	ds_read_b128 v[160:163], v150 offset:3072
	ds_read_b128 v[170:173], v168 offset:32768
	ds_read_b128 v[174:177], v168 offset:33792
	ds_read_b128 v[178:181], v168 offset:34816
	ds_read_b128 v[182:185], v168 offset:35840
	ds_read_b128 v[186:189], v168 offset:36864
	ds_read_b128 v[190:193], v168 offset:37888
	ds_read_b128 v[194:197], v168 offset:38912
	ds_read_b128 v[202:205], v168 offset:39936
	s_waitcnt lgkmcnt(8)
	s_waitcnt vmcnt(8)
	s_barrier
; #define PG8_STAGE(bufoff, gbase, voff) do { _Pragma("unroll") for (int _i = 0; _i < 2; ++_i) \
;         __builtin_amdgcn_global_load_lds((const unsigned*)((const char*)(gbase) + (voff)[_i]), (LAS unsigned*)(lds + (bufoff) + ldsw + _i * 8192), 16, 0, 0); } while (0)
; #define PG8_LDA(dst, b, h) do { _Pragma("unroll") for (int m = 0; m < 4; ++m) _Pragma("unroll") for (int k = 0; k < 2; ++k) dst[m][k] = *(const LAS bf16x8*)(lds + PG8_SA(b, h) + aoff + m * 2048 + k * 1024); } while (0)
; #define PG8_LDB(dst, b, h) do { _Pragma("unroll") for (int n = 0; n < 2; ++n) _Pragma("unroll") for (int k = 0; k < 2; ++k) dst[n][k] = *(const LAS bf16x8*)(lds + PG8_SB(b, h) + boff + n * 2048 + k * 1024); } while (0)
; #define PG8_MMA(ai, bj, At, Bt) do { __builtin_amdgcn_s_setprio(1); _Pragma("unroll") for (int m = 0; m < 4; ++m) _Pragma("unroll") for (int n = 0; n < 2; ++n) _Pragma("unroll") for (int k = 0; k < 2; ++k) \
;         acc[ai][bj][m][n] = __builtin_amdgcn_mfma_f32_16x16x32_bf16(Bt[n][k], At[m][k], acc[ai][bj][m][n], 0, 0, 0); __builtin_amdgcn_s_setprio(0); } while (0)
; #define PG8_WAIT_L(n) asm volatile("s_waitcnt lgkmcnt(" #n ")" ::: "memory")
; #define PG8_BAR __builtin_amdgcn_s_barrier()
; #define PG8_SCHED __builtin_amdgcn_sched_barrier(0)
; template <class Epi, class Sched>
; __device__ __forceinline__ void gemm_phase(LAS unsigned char* lds, const Gemm g, const Sched& S, const Epi& E) {
;     ...
;             PG8_WAIT_L(8); PG8_BAR; PG8_WAIT_L(0); PG8_MMA(0, 0, At, B0); PG8_BAR; PG8_SCHED;
;             PG8_LDB(B1, 1, 1); PG8_STAGE(PG8_SB(1, 0), b3, voffB);
;             PG8_BAR; PG8_WAIT_L(0); PG8_MMA(0, 1, At, B1); PG8_BAR;
;             PG8_LDA(At, 1, 1); PG8_STAGE(PG8_SA(1, 0), a3, voffA);
;             PG8_BAR; PG8_WAIT_L(0); PG8_MMA(1, 0, At, B0); PG8_BAR; PG8_SCHED;
	s_waitcnt lgkmcnt(0)
	s_setprio 1
	s_waitcnt lgkmcnt(0)
	v_mfma_f32_16x16x32_bf16 v[124:127], v[128:131], v[170:173], v[124:127]
	v_mfma_f32_16x16x32_bf16 v[120:123], v[136:139], v[170:173], v[120:123]
	v_mfma_f32_16x16x32_bf16 v[108:111], v[128:131], v[178:181], v[108:111]
	v_mfma_f32_16x16x32_bf16 v[104:107], v[136:139], v[178:181], v[104:107]
	v_mfma_f32_16x16x32_bf16 v[92:95], v[128:131], v[186:189], v[92:95]
	v_mfma_f32_16x16x32_bf16 v[88:91], v[136:139], v[186:189], v[88:91]
	v_mfma_f32_16x16x32_bf16 v[76:79], v[128:131], v[194:197], v[76:79]
	v_mfma_f32_16x16x32_bf16 v[72:75], v[136:139], v[194:197], v[72:75]
	v_mfma_f32_16x16x32_bf16 v[124:127], v[132:135], v[174:177], v[124:127]
	v_mfma_f32_16x16x32_bf16 v[120:123], v[160:163], v[174:177], v[120:123]
	v_mfma_f32_16x16x32_bf16 v[108:111], v[132:135], v[182:185], v[108:111]
	v_mfma_f32_16x16x32_bf16 v[104:107], v[160:163], v[182:185], v[104:107]
	v_mfma_f32_16x16x32_bf16 v[92:95], v[132:135], v[190:193], v[92:95]
	v_mfma_f32_16x16x32_bf16 v[88:91], v[160:163], v[190:193], v[88:91]
	v_mfma_f32_16x16x32_bf16 v[76:79], v[132:135], v[202:205], v[76:79]
	v_mfma_f32_16x16x32_bf16 v[72:75], v[160:163], v[202:205], v[72:75]
	s_setprio 0
	s_barrier
	s_add_i32 s28, 0, 0x1c000
	s_add_i32 s29, s57, s34
	v_add_u32_e32 v150, s28, v166
	s_add_u32 s0, s26, 0x80
	s_addc_u32 s1, s27, 0
	s_mov_b32 m0, s29
	ds_read_b128 v[206:209], v150
	ds_read_b128 v[210:213], v150 offset:1024
	ds_read_b128 v[214:217], v150 offset:2048
	ds_read_b128 v[218:221], v150 offset:3072
	global_load_lds_dwordx4 v146, s[0:1]
	s_add_i32 m0, s29, 0x2000
	s_nop 0
	global_load_lds_dwordx4 v142, s[0:1]
	s_waitcnt vmcnt(8)
	s_barrier
	s_waitcnt lgkmcnt(0)
	s_setprio 1
	s_waitcnt lgkmcnt(0)
	v_mfma_f32_16x16x32_bf16 v[116:119], v[206:209], v[170:173], v[116:119]
	v_mfma_f32_16x16x32_bf16 v[112:115], v[214:217], v[170:173], v[112:115]
	v_mfma_f32_16x16x32_bf16 v[100:103], v[206:209], v[178:181], v[100:103]
	v_mfma_f32_16x16x32_bf16 v[96:99], v[214:217], v[178:181], v[96:99]
	v_mfma_f32_16x16x32_bf16 v[84:87], v[206:209], v[186:189], v[84:87]
	v_mfma_f32_16x16x32_bf16 v[80:83], v[214:217], v[186:189], v[80:83]
	v_mfma_f32_16x16x32_bf16 v[68:71], v[206:209], v[194:197], v[68:71]
	v_mfma_f32_16x16x32_bf16 v[64:67], v[214:217], v[194:197], v[64:67]
	v_mfma_f32_16x16x32_bf16 v[116:119], v[210:213], v[174:177], v[116:119]
	v_mfma_f32_16x16x32_bf16 v[112:115], v[218:221], v[174:177], v[112:115]
	v_mfma_f32_16x16x32_bf16 v[100:103], v[210:213], v[182:185], v[100:103]
	v_mfma_f32_16x16x32_bf16 v[96:99], v[218:221], v[182:185], v[96:99]
	v_mfma_f32_16x16x32_bf16 v[84:87], v[210:213], v[190:193], v[84:87]
	v_mfma_f32_16x16x32_bf16 v[80:83], v[218:221], v[190:193], v[80:83]
	v_mfma_f32_16x16x32_bf16 v[68:71], v[210:213], v[202:205], v[68:71]
	v_mfma_f32_16x16x32_bf16 v[64:67], v[218:221], v[202:205], v[64:67]
	s_setprio 0
	s_mov_b32 m0, s44
	s_mov_b64 s[0:1], 0x80
	v_lshl_add_u64 v[140:141], v[222:223], 0, s[0:1]
	s_barrier
	ds_read_b128 v[170:173], v168 offset:49152
	ds_read_b128 v[174:177], v168 offset:50176
	ds_read_b128 v[178:181], v168 offset:51200
	ds_read_b128 v[182:185], v168 offset:52224
	ds_read_b128 v[186:189], v168 offset:53248
	ds_read_b128 v[190:193], v168 offset:54272
	ds_read_b128 v[194:197], v168 offset:55296
	ds_read_b128 v[202:205], v168 offset:56320
	global_load_lds_dwordx4 v[140:141], off
	v_lshl_add_u64 v[140:141], v[224:225], 0, s[0:1]
	s_mov_b32 m0, s45
	s_nop 0
	global_load_lds_dwordx4 v[140:141], off
	s_barrier
; #define PG8_STAGE(bufoff, gbase, voff) do { _Pragma("unroll") for (int _i = 0; _i < 2; ++_i) \
;         __builtin_amdgcn_global_load_lds((const unsigned*)((const char*)(gbase) + (voff)[_i]), (LAS unsigned*)(lds + (bufoff) + ldsw + _i * 8192), 16, 0, 0); } while (0)
; #define PG8_MMA(ai, bj, At, Bt) do { __builtin_amdgcn_s_setprio(1); _Pragma("unroll") for (int m = 0; m < 4; ++m) _Pragma("unroll") for (int n = 0; n < 2; ++n) _Pragma("unroll") for (int k = 0; k < 2; ++k) \
;         acc[ai][bj][m][n] = __builtin_amdgcn_mfma_f32_16x16x32_bf16(Bt[n][k], At[m][k], acc[ai][bj][m][n], 0, 0, 0); __builtin_amdgcn_s_setprio(0); } while (0)
; #define PG8_WAIT_V(n) asm volatile("s_waitcnt vmcnt(" #n ")" ::: "memory")
; #define PG8_WAIT_L(n) asm volatile("s_waitcnt lgkmcnt(" #n ")" ::: "memory")
; #define PG8_BAR __builtin_amdgcn_s_barrier()
; #define PG8_SCHED __builtin_amdgcn_sched_barrier(0)
; template <class Epi, class Sched>
; __device__ __forceinline__ void gemm_phase(LAS unsigned char* lds, const Gemm g, const Sched& S, const Epi& E) {
;     ...
;             PG8_BAR; PG8_WAIT_L(0); PG8_MMA(1, 0, At, B0); PG8_BAR; PG8_SCHED;
;             PG8_STAGE(PG8_SB(1, 1), b3 + hstep, voffB);
;             PG8_WAIT_V(6); PG8_BAR; PG8_MMA(1, 1, At, B1); PG8_BAR;
;     __device__ __forceinline__ void operator()(const AccT& acc, const Unit& u, int wr, int wc, int fr, int fq) const {
;     ...
;         const int row0 = u.pm * 256 + wr * 64 + fr, col0 = u.pn * 256 + wc * 32 + 8 * fq;
;         const bool rope = u.pn < 2;
;         const int i = 4 * (wc & 1) + fq;
; #pragma unroll
;         for (int ai = 0; ai < 2; ++ai)
; #pragma unroll
;             for (int m = 0; m < 4; ++m) {
;                 const int row = row0 + ai * 128 + m * 16;
;                 f32x4 cs = {1.f, 1.f, 1.f, 1.f}, sn = {0.f, 0.f, 0.f, 0.f};
;                 if (rope) { const int t = row & 2047; const int pos = (i < 4) ? (t >> 6) : (t & 63);
;                     cs = *(const f32x4*)(ropeA + pos * 16 + ((4 * i) & 15)); sn = *(const f32x4*)(ropeA + 1024 + pos * 16 + ((4 * i) & 15)); }
	s_waitcnt lgkmcnt(0)
	s_setprio 1
	s_waitcnt lgkmcnt(0)
	v_mfma_f32_16x16x32_bf16 v[60:63], v[128:131], v[170:173], v[60:63]
	v_mfma_f32_16x16x32_bf16 v[56:59], v[136:139], v[170:173], v[56:59]
	v_mfma_f32_16x16x32_bf16 v[44:47], v[128:131], v[178:181], v[44:47]
	v_mfma_f32_16x16x32_bf16 v[40:43], v[136:139], v[178:181], v[40:43]
	v_mfma_f32_16x16x32_bf16 v[28:31], v[128:131], v[186:189], v[28:31]
	v_mfma_f32_16x16x32_bf16 v[24:27], v[136:139], v[186:189], v[24:27]
	v_mfma_f32_16x16x32_bf16 v[12:15], v[128:131], v[194:197], v[12:15]
	v_mfma_f32_16x16x32_bf16 v[8:11], v[136:139], v[194:197], v[8:11]
	v_mfma_f32_16x16x32_bf16 v[60:63], v[132:135], v[174:177], v[60:63]
	v_mfma_f32_16x16x32_bf16 v[56:59], v[160:163], v[174:177], v[56:59]
	v_mfma_f32_16x16x32_bf16 v[44:47], v[132:135], v[182:185], v[44:47]
	v_mfma_f32_16x16x32_bf16 v[40:43], v[160:163], v[182:185], v[40:43]
	v_mfma_f32_16x16x32_bf16 v[28:31], v[132:135], v[190:193], v[28:31]
	v_mfma_f32_16x16x32_bf16 v[24:27], v[160:163], v[190:193], v[24:27]
	v_mfma_f32_16x16x32_bf16 v[12:15], v[132:135], v[202:205], v[12:15]
	v_mfma_f32_16x16x32_bf16 v[8:11], v[160:163], v[202:205], v[8:11]
	s_setprio 0
	s_barrier
	s_add_u32 s26, s26, 0x40080
	s_addc_u32 s27, s27, 0
	s_add_i32 s28, s28, s34
	s_mov_b32 m0, s28
	s_nop 0
	global_load_lds_dwordx4 v146, s[26:27]
	s_add_i32 m0, s28, 0x2000
	s_nop 0
	global_load_lds_dwordx4 v142, s[26:27]
	s_waitcnt vmcnt(8)
	s_barrier
	s_setprio 1
	v_mfma_f32_16x16x32_bf16 v[52:55], v[206:209], v[170:173], v[52:55]
	v_mfma_f32_16x16x32_bf16 v[48:51], v[214:217], v[170:173], v[48:51]
	v_mfma_f32_16x16x32_bf16 v[36:39], v[206:209], v[178:181], v[36:39]
	v_mfma_f32_16x16x32_bf16 v[32:35], v[214:217], v[178:181], v[32:35]
	v_mfma_f32_16x16x32_bf16 v[20:23], v[206:209], v[186:189], v[20:23]
	v_mfma_f32_16x16x32_bf16 v[16:19], v[214:217], v[186:189], v[16:19]
	v_mfma_f32_16x16x32_bf16 v[4:7], v[206:209], v[194:197], v[4:7]
	v_mfma_f32_16x16x32_bf16 v[0:3], v[214:217], v[194:197], v[0:3]
	v_mfma_f32_16x16x32_bf16 v[52:55], v[210:213], v[174:177], v[52:55]
	v_mfma_f32_16x16x32_bf16 v[48:51], v[218:221], v[174:177], v[48:51]
	v_mfma_f32_16x16x32_bf16 v[36:39], v[210:213], v[182:185], v[36:39]
	v_mfma_f32_16x16x32_bf16 v[32:35], v[218:221], v[182:185], v[32:35]
	v_mfma_f32_16x16x32_bf16 v[20:23], v[210:213], v[190:193], v[20:23]
	v_mfma_f32_16x16x32_bf16 v[16:19], v[218:221], v[190:193], v[16:19]
	v_mfma_f32_16x16x32_bf16 v[4:7], v[210:213], v[202:205], v[4:7]
	v_mfma_f32_16x16x32_bf16 v[0:3], v[218:221], v[202:205], v[0:3]
	s_setprio 0
	s_add_i32 s56, s56, 2
	s_add_u32 s6, s6, 0x100
	s_addc_u32 s7, s7, 0
	s_add_u32 s54, s54, 0x100
	s_addc_u32 s55, s55, 0
	s_cmp_gt_u32 s56, 13
	s_barrier
	s_cbranch_scc0 .LBB0_578
	v_mov_b32_e32 v129, v165
	v_mov_b32_e32 v173, v164
	s_lshl_b32 s4, s4, 8
	s_add_i32 s4, s4, s42
	v_add_u32_e32 v128, s46, v129
	v_add_u32_e32 v170, s4, v173
	v_cmp_gt_i32_e64 s[4:5], 4, v128
	v_lshlrev_b32_e32 v128, 2, v128
	s_cmp_lt_i32 s52, 2
	v_and_b32_e32 v130, 12, v128
	s_cselect_b64 s[26:27], -1, 0
	s_cmp_gt_i32 s52, 1
	v_and_b32_e32 v172, 63, v173
	v_mov_b32_e32 v128, 1.0
	v_mov_b32_e32 v132, 0
	v_lshlrev_b32_e32 v162, 2, v130
	v_mov_b32_e32 v134, 0
	v_mov_b32_e32 v135, 0
	v_mov_b32_e32 v136, 0
	v_mov_b32_e32 v137, 0
	v_mov_b32_e32 v138, 1.0
	v_mov_b32_e32 v139, 1.0
	v_mov_b32_e32 v140, 1.0
	v_mov_b32_e32 v141, 1.0
	s_cbranch_scc1 .LBB0_581
	v_bfe_u32 v130, v170, 6, 5
	v_cndmask_b32_e64 v130, v172, v130, s[4:5]
	v_lshlrev_b32_e32 v150, 6, v130
	v_lshl_add_u64 v[130:131], s[16:17], 0, v[150:151]
	v_mov_b32_e32 v163, v151
	v_lshl_add_u64 v[134:135], s[8:9], 0, v[150:151]
	v_lshl_add_u64 v[130:131], v[130:131], 0, v[162:163]
	v_lshl_add_u64 v[134:135], v[134:135], 0, v[162:163]
	global_load_dwordx4 v[138:141], v[130:131], off
	s_nop 0
	global_load_dwordx4 v[134:137], v[134:135], off
	s_waitcnt vmcnt(0)

; #define PG8_STAGE(bufoff, gbase, voff) do { _Pragma("unroll") for (int _i = 0; _i < 2; ++_i) \
;         __builtin_amdgcn_global_load_lds((const unsigned*)((const char*)(gbase) + (voff)[_i]), (LAS unsigned*)(lds + (bufoff) + ldsw + _i * 8192), 16, 0, 0); } while (0)
; #define PG8_LDA(dst, b, h) do { _Pragma("unroll") for (int m = 0; m < 4; ++m) _Pragma("unroll") for (int k = 0; k < 2; ++k) dst[m][k] = *(const LAS bf16x8*)(lds + PG8_SA(b, h) + aoff + m * 2048 + k * 1024); } while (0)
; #define PG8_LDB(dst, b, h) do { _Pragma("unroll") for (int n = 0; n < 2; ++n) _Pragma("unroll") for (int k = 0; k < 2; ++k) dst[n][k] = *(const LAS bf16x8*)(lds + PG8_SB(b, h) + boff + n * 2048 + k * 1024); } while (0)
; #define PG8_WAIT_V(n) asm volatile("s_waitcnt vmcnt(" #n ")" ::: "memory")
; #define PG8_WAIT_L(n) asm volatile("s_waitcnt lgkmcnt(" #n ")" ::: "memory")
; #define PG8_BAR __builtin_amdgcn_s_barrier()
; #define PG8_SCHED __builtin_amdgcn_sched_barrier(0)
; template <class Epi, class Sched>
; __device__ __forceinline__ void gemm_phase(LAS unsigned char* lds, const Gemm g, const Sched& S, const Epi& E) {
;     ...
;         const bool has_next = S.next(ui + 1, nxt);
;         const char* nA = has_next ? (const char*)g.A + (size_t)nxt.pm * tstep : cA; const char* nB = has_next ? (const char*)g.Bt + (size_t)nxt.pn * tstep : cB;
;         for (int t = 0; t < nt; t += 2) {
;             const bool last = (t == nt - 2);
;             const char* a1 = cA + (size_t)(t + 1) * kstep;
;             const char* a2 = last ? nA : cA + (size_t)(t + 2) * kstep; const char* b2 = last ? nB : cB + (size_t)(t + 2) * kstep;
;             const char* a3 = a2 + kstep; const char* b3 = b2 + kstep;
;             PG8_LDB(B0, 0, 0); PG8_SCHED; PG8_LDA(At, 0, 0); PG8_STAGE(PG8_SA(1, 1), a1 + hstep, voffA);
;             PG8_WAIT_L(8); PG8_BAR; PG8_WAIT_L(0); PG8_MMA(0, 0, At, B0); PG8_BAR; PG8_SCHED;
;             PG8_LDB(B1, 0, 1); PG8_STAGE(PG8_SB(0, 0), b2, voffB);
;             PG8_BAR; PG8_WAIT_L(0); PG8_MMA(0, 1, At, B1); PG8_BAR;
;             PG8_LDA(At, 0, 1); PG8_STAGE(PG8_SA(0, 0), a2, voffA);
;             PG8_BAR; PG8_WAIT_L(0); PG8_MMA(1, 0, At, B0); PG8_BAR; PG8_SCHED;
;             PG8_STAGE(PG8_SB(0, 1), b2 + hstep, voffB);
;             PG8_WAIT_V(6); PG8_BAR; PG8_MMA(1, 1, At, B1); PG8_BAR;
.LBB0_612:
	s_ashr_i32 s35, s34, 31
	v_cmp_lt_i64_e32 vcc, s[6:7], v[142:143]
	s_lshl_b64 s[6:7], s[34:35], 19
	s_add_u32 s36, s40, s6
	s_addc_u32 s37, s41, s7
	s_and_b64 s[6:7], vcc, exec
	s_cselect_b32 s8, s37, s1
	s_cselect_b32 s9, s36, s0
	s_ashr_i32 s31, s30, 31
	s_lshl_b64 s[6:7], s[30:31], 19
	s_add_u32 s38, s96, s6
	s_addc_u32 s39, s97, s7
	s_and_b64 s[6:7], vcc, exec
	s_cselect_b32 s31, s39, s5
	s_cselect_b32 s35, s38, s4
	s_add_u32 s0, s0, 0x40080
	s_addc_u32 s1, s1, 0
	s_add_u32 s65, s4, 0x100
	s_addc_u32 s66, s5, 0
	s_mov_b32 s67, -2
	s_waitcnt lgkmcnt(0)
	ds_read_b128 v[146:149], v171
	ds_read_b128 v[150:153], v171 offset:1024
	ds_read_b128 v[154:157], v171 offset:2048
	ds_read_b128 v[158:161], v171 offset:3072
	s_add_u32 s4, s0, 0xfffc0080
	s_addc_u32 s5, s1, -1
	s_cmp_eq_u32 s67, 12
	s_cselect_b32 s7, s8, s5
	s_cselect_b32 s6, s9, s4
	s_cselect_b32 s5, s31, s66
	s_cselect_b32 s4, s35, s65
	s_add_i32 m0, s45, 0xc000
	ds_read_b128 v[162:165], v172
	ds_read_b128 v[178:181], v172 offset:1024
	ds_read_b128 v[182:185], v172 offset:2048
	ds_read_b128 v[186:189], v172 offset:3072
	ds_read_b128 v[190:193], v172 offset:4096
	ds_read_b128 v[194:197], v172 offset:5120
	ds_read_b128 v[202:205], v172 offset:6144
	ds_read_b128 v[206:209], v172 offset:7168
	global_load_lds_dwordx4 v138, s[0:1]
	s_add_i32 m0, s45, 0xe000
	s_nop 0
	global_load_lds_dwordx4 v140, s[0:1]
	s_waitcnt lgkmcnt(8)
	s_waitcnt vmcnt(8)
	s_barrier
	s_waitcnt lgkmcnt(0)
	s_setprio 1
	s_waitcnt lgkmcnt(0)
	v_mfma_f32_16x16x32_bf16 v[124:127], v[146:149], v[162:165], 0
	v_mfma_f32_16x16x32_bf16 v[120:123], v[154:157], v[162:165], 0
	v_mfma_f32_16x16x32_bf16 v[108:111], v[146:149], v[182:185], 0
	v_mfma_f32_16x16x32_bf16 v[104:107], v[154:157], v[182:185], 0
	v_mfma_f32_16x16x32_bf16 v[92:95], v[146:149], v[190:193], 0
	v_mfma_f32_16x16x32_bf16 v[88:91], v[154:157], v[190:193], 0
	v_mfma_f32_16x16x32_bf16 v[76:79], v[146:149], v[202:205], 0
	v_mfma_f32_16x16x32_bf16 v[72:75], v[154:157], v[202:205], 0
	v_mfma_f32_16x16x32_bf16 v[124:127], v[150:153], v[178:181], v[124:127]
	v_mfma_f32_16x16x32_bf16 v[120:123], v[158:161], v[178:181], v[120:123]
	v_mfma_f32_16x16x32_bf16 v[108:111], v[150:153], v[186:189], v[108:111]
	v_mfma_f32_16x16x32_bf16 v[104:107], v[158:161], v[186:189], v[104:107]
	v_mfma_f32_16x16x32_bf16 v[92:95], v[150:153], v[194:197], v[92:95]
	v_mfma_f32_16x16x32_bf16 v[88:91], v[158:161], v[194:197], v[88:91]
	v_mfma_f32_16x16x32_bf16 v[76:79], v[150:153], v[206:209], v[76:79]
	v_mfma_f32_16x16x32_bf16 v[72:75], v[158:161], v[206:209], v[72:75]
	s_setprio 0
	s_barrier
	s_add_i32 s68, s57, s44
	s_mov_b32 m0, s68
	ds_read_b128 v[210:213], v173
	ds_read_b128 v[214:217], v173 offset:1024
	ds_read_b128 v[218:221], v173 offset:2048
	ds_read_b128 v[222:225], v173 offset:3072
	global_load_lds_dwordx4 v130, s[4:5]
	s_add_i32 m0, s68, 0x2000
	s_nop 0
	global_load_lds_dwordx4 v134, s[4:5]
	s_waitcnt vmcnt(8)
	s_barrier
	s_waitcnt lgkmcnt(0)
	s_setprio 1
	s_waitcnt lgkmcnt(0)
	v_mfma_f32_16x16x32_bf16 v[116:119], v[210:213], v[162:165], 0
	v_mfma_f32_16x16x32_bf16 v[112:115], v[218:221], v[162:165], 0
	v_mfma_f32_16x16x32_bf16 v[100:103], v[210:213], v[182:185], 0
	v_mfma_f32_16x16x32_bf16 v[96:99], v[218:221], v[182:185], 0
	v_mfma_f32_16x16x32_bf16 v[84:87], v[210:213], v[190:193], 0
	v_mfma_f32_16x16x32_bf16 v[80:83], v[218:221], v[190:193], 0
	v_mfma_f32_16x16x32_bf16 v[68:71], v[210:213], v[202:205], 0
	v_mfma_f32_16x16x32_bf16 v[64:67], v[218:221], v[202:205], 0
	v_mfma_f32_16x16x32_bf16 v[116:119], v[214:217], v[178:181], v[116:119]
	v_mfma_f32_16x16x32_bf16 v[112:115], v[222:225], v[178:181], v[112:115]
	v_mfma_f32_16x16x32_bf16 v[100:103], v[214:217], v[186:189], v[100:103]
	v_mfma_f32_16x16x32_bf16 v[96:99], v[222:225], v[186:189], v[96:99]
	v_mfma_f32_16x16x32_bf16 v[84:87], v[214:217], v[194:197], v[84:87]
	v_mfma_f32_16x16x32_bf16 v[80:83], v[222:225], v[194:197], v[80:83]
	v_mfma_f32_16x16x32_bf16 v[68:71], v[214:217], v[206:209], v[68:71]
	v_mfma_f32_16x16x32_bf16 v[64:67], v[222:225], v[206:209], v[64:67]
	s_setprio 0
	s_mov_b32 m0, s45
	v_lshl_add_u64 v[226:227], s[6:7], 0, v[128:129]
	s_barrier
	ds_read_b128 v[162:165], v172 offset:16384
	ds_read_b128 v[178:181], v172 offset:17408
	ds_read_b128 v[182:185], v172 offset:18432
	ds_read_b128 v[186:189], v172 offset:19456
	ds_read_b128 v[190:193], v172 offset:20480
	ds_read_b128 v[194:197], v172 offset:21504
	ds_read_b128 v[202:205], v172 offset:22528
	ds_read_b128 v[206:209], v172 offset:23552
	global_load_lds_dwordx4 v128, s[6:7]
	v_lshl_add_u64 v[228:229], s[6:7], 0, v[132:133]
	s_mov_b32 m0, s46
	s_nop 0
	global_load_lds_dwordx4 v132, s[6:7]
	s_barrier
	s_waitcnt lgkmcnt(0)
	s_setprio 1
	s_waitcnt lgkmcnt(0)
	v_mfma_f32_16x16x32_bf16 v[60:63], v[146:149], v[162:165], 0
	v_mfma_f32_16x16x32_bf16 v[56:59], v[154:157], v[162:165], 0
	v_mfma_f32_16x16x32_bf16 v[44:47], v[146:149], v[182:185], 0
	v_mfma_f32_16x16x32_bf16 v[40:43], v[154:157], v[182:185], 0
	v_mfma_f32_16x16x32_bf16 v[28:31], v[146:149], v[190:193], 0
	v_mfma_f32_16x16x32_bf16 v[24:27], v[154:157], v[190:193], 0
	v_mfma_f32_16x16x32_bf16 v[12:15], v[146:149], v[202:205], 0
	v_mfma_f32_16x16x32_bf16 v[8:11], v[154:157], v[202:205], 0
	v_mfma_f32_16x16x32_bf16 v[60:63], v[150:153], v[178:181], v[60:63]
	v_mfma_f32_16x16x32_bf16 v[56:59], v[158:161], v[178:181], v[56:59]
	v_mfma_f32_16x16x32_bf16 v[44:47], v[150:153], v[186:189], v[44:47]
	v_mfma_f32_16x16x32_bf16 v[40:43], v[158:161], v[186:189], v[40:43]
	v_mfma_f32_16x16x32_bf16 v[28:31], v[150:153], v[194:197], v[28:31]
	v_mfma_f32_16x16x32_bf16 v[24:27], v[158:161], v[194:197], v[24:27]
	v_mfma_f32_16x16x32_bf16 v[12:15], v[150:153], v[206:209], v[12:15]
	v_mfma_f32_16x16x32_bf16 v[8:11], v[158:161], v[206:209], v[8:11]
	s_setprio 0
	s_barrier
; #define PG8_STAGE(bufoff, gbase, voff) do { _Pragma("unroll") for (int _i = 0; _i < 2; ++_i) \
;         __builtin_amdgcn_global_load_lds((const unsigned*)((const char*)(gbase) + (voff)[_i]), (LAS unsigned*)(lds + (bufoff) + ldsw + _i * 8192), 16, 0, 0); } while (0)
; #define PG8_LDA(dst, b, h) do { _Pragma("unroll") for (int m = 0; m < 4; ++m) _Pragma("unroll") for (int k = 0; k < 2; ++k) dst[m][k] = *(const LAS bf16x8*)(lds + PG8_SA(b, h) + aoff + m * 2048 + k * 1024); } while (0)
; #define PG8_LDB(dst, b, h) do { _Pragma("unroll") for (int n = 0; n < 2; ++n) _Pragma("unroll") for (int k = 0; k < 2; ++k) dst[n][k] = *(const LAS bf16x8*)(lds + PG8_SB(b, h) + boff + n * 2048 + k * 1024); } while (0)
; #define PG8_MMA(ai, bj, At, Bt) do { __builtin_amdgcn_s_setprio(1); _Pragma("unroll") for (int m = 0; m < 4; ++m) _Pragma("unroll") for (int n = 0; n < 2; ++n) _Pragma("unroll") for (int k = 0; k < 2; ++k) \
;         acc[ai][bj][m][n] = __builtin_amdgcn_mfma_f32_16x16x32_bf16(Bt[n][k], At[m][k], acc[ai][bj][m][n], 0, 0, 0); __builtin_amdgcn_s_setprio(0); } while (0)
; #define PG8_WAIT_V(n) asm volatile("s_waitcnt vmcnt(" #n ")" ::: "memory")
; #define PG8_WAIT_L(n) asm volatile("s_waitcnt lgkmcnt(" #n ")" ::: "memory")
; #define PG8_BAR __builtin_amdgcn_s_barrier()
; #define PG8_SCHED __builtin_amdgcn_sched_barrier(0)
; template <class Epi, class Sched>
; __device__ __forceinline__ void gemm_phase(LAS unsigned char* lds, const Gemm g, const Sched& S, const Epi& E) {
;     ...
;             PG8_WAIT_V(6); PG8_BAR; PG8_MMA(1, 1, At, B1); PG8_BAR;
;             PG8_LDB(B0, 1, 0); PG8_SCHED; PG8_LDA(At, 1, 0); PG8_STAGE(PG8_SA(0, 1), a2 + hstep, voffA);
;             PG8_WAIT_L(8); PG8_BAR; PG8_WAIT_L(0); PG8_MMA(0, 0, At, B0); PG8_BAR; PG8_SCHED;
;             PG8_LDB(B1, 1, 1); PG8_STAGE(PG8_SB(1, 0), b3, voffB);
;             PG8_BAR; PG8_WAIT_L(0); PG8_MMA(0, 1, At, B1); PG8_BAR;
;             PG8_LDA(At, 1, 1); PG8_STAGE(PG8_SA(1, 0), a3, voffA);
;             PG8_BAR; PG8_WAIT_L(0); PG8_MMA(1, 0, At, B0); PG8_BAR; PG8_SCHED;
	s_add_u32 s68, s4, 0x40000
	s_addc_u32 s69, s5, 0
	s_add_i32 s70, s58, s44
	s_mov_b32 m0, s70
	s_nop 0
	global_load_lds_dwordx4 v130, s[68:69]
	s_add_i32 m0, s70, 0x2000
	s_nop 0
	global_load_lds_dwordx4 v134, s[68:69]
	s_add_u32 s6, s6, 0x40000
	s_addc_u32 s7, s7, 0
	s_mov_b32 m0, s47
	s_nop 0
	global_load_lds_dwordx4 v128, s[6:7]
	s_mov_b32 m0, s48
	s_nop 0
	global_load_lds_dwordx4 v132, s[6:7]
	s_waitcnt vmcnt(10)
	s_barrier
	s_setprio 1
	v_mfma_f32_16x16x32_bf16 v[52:55], v[210:213], v[162:165], 0
	v_mfma_f32_16x16x32_bf16 v[48:51], v[218:221], v[162:165], 0
	v_mfma_f32_16x16x32_bf16 v[36:39], v[210:213], v[182:185], 0
	v_mfma_f32_16x16x32_bf16 v[32:35], v[218:221], v[182:185], 0
	v_mfma_f32_16x16x32_bf16 v[20:23], v[210:213], v[190:193], 0
	v_mfma_f32_16x16x32_bf16 v[16:19], v[218:221], v[190:193], 0
	v_mfma_f32_16x16x32_bf16 v[4:7], v[210:213], v[202:205], 0
	v_mfma_f32_16x16x32_bf16 v[0:3], v[218:221], v[202:205], 0
	v_mfma_f32_16x16x32_bf16 v[52:55], v[214:217], v[178:181], v[52:55]
	v_mfma_f32_16x16x32_bf16 v[48:51], v[222:225], v[178:181], v[48:51]
	v_mfma_f32_16x16x32_bf16 v[36:39], v[214:217], v[186:189], v[36:39]
	v_mfma_f32_16x16x32_bf16 v[32:35], v[222:225], v[186:189], v[32:35]
	v_mfma_f32_16x16x32_bf16 v[20:23], v[214:217], v[194:197], v[20:23]
	v_mfma_f32_16x16x32_bf16 v[16:19], v[222:225], v[194:197], v[16:19]
	v_mfma_f32_16x16x32_bf16 v[4:7], v[214:217], v[206:209], v[4:7]
	v_mfma_f32_16x16x32_bf16 v[0:3], v[222:225], v[206:209], v[0:3]
	s_setprio 0
	s_add_i32 s68, 0, 0x18000
	v_add_u32_e32 v136, s68, v170
	s_barrier
	ds_read_b128 v[146:149], v136
	ds_read_b128 v[150:153], v136 offset:1024
	ds_read_b128 v[154:157], v136 offset:2048
	ds_read_b128 v[158:161], v136 offset:3072
	ds_read_b128 v[162:165], v172 offset:32768
	ds_read_b128 v[178:181], v172 offset:33792
	ds_read_b128 v[182:185], v172 offset:34816
	ds_read_b128 v[186:189], v172 offset:35840
	ds_read_b128 v[190:193], v172 offset:36864
	ds_read_b128 v[194:197], v172 offset:37888
	ds_read_b128 v[202:205], v172 offset:38912
	ds_read_b128 v[206:209], v172 offset:39936
	s_waitcnt lgkmcnt(8)
	s_waitcnt vmcnt(8)
	s_barrier
	s_waitcnt lgkmcnt(0)
	s_setprio 1
	s_waitcnt lgkmcnt(0)
	v_mfma_f32_16x16x32_bf16 v[124:127], v[146:149], v[162:165], v[124:127]
	v_mfma_f32_16x16x32_bf16 v[120:123], v[154:157], v[162:165], v[120:123]
	v_mfma_f32_16x16x32_bf16 v[108:111], v[146:149], v[182:185], v[108:111]
	v_mfma_f32_16x16x32_bf16 v[104:107], v[154:157], v[182:185], v[104:107]
	v_mfma_f32_16x16x32_bf16 v[92:95], v[146:149], v[190:193], v[92:95]
	v_mfma_f32_16x16x32_bf16 v[88:91], v[154:157], v[190:193], v[88:91]
	v_mfma_f32_16x16x32_bf16 v[76:79], v[146:149], v[202:205], v[76:79]
	v_mfma_f32_16x16x32_bf16 v[72:75], v[154:157], v[202:205], v[72:75]
	v_mfma_f32_16x16x32_bf16 v[124:127], v[150:153], v[178:181], v[124:127]
	v_mfma_f32_16x16x32_bf16 v[120:123], v[158:161], v[178:181], v[120:123]
	v_mfma_f32_16x16x32_bf16 v[108:111], v[150:153], v[186:189], v[108:111]
	v_mfma_f32_16x16x32_bf16 v[104:107], v[158:161], v[186:189], v[104:107]
	v_mfma_f32_16x16x32_bf16 v[92:95], v[150:153], v[194:197], v[92:95]
	v_mfma_f32_16x16x32_bf16 v[88:91], v[158:161], v[194:197], v[88:91]
	v_mfma_f32_16x16x32_bf16 v[76:79], v[150:153], v[206:209], v[76:79]
	v_mfma_f32_16x16x32_bf16 v[72:75], v[158:161], v[206:209], v[72:75]
	s_setprio 0
	s_barrier
	s_add_i32 s6, 0, 0x1c000
	s_add_i32 s7, s68, s44
	v_add_u32_e32 v136, s6, v170
	s_add_u32 s20, s4, 0x80
	s_addc_u32 s21, s5, 0
	s_mov_b32 m0, s7
	ds_read_b128 v[210:213], v136
	ds_read_b128 v[214:217], v136 offset:1024
	ds_read_b128 v[218:221], v136 offset:2048
	ds_read_b128 v[222:225], v136 offset:3072
	global_load_lds_dwordx4 v130, s[20:21]
	s_add_i32 m0, s7, 0x2000
	s_nop 0
	global_load_lds_dwordx4 v134, s[20:21]
	s_waitcnt vmcnt(8)
	s_barrier
	s_waitcnt lgkmcnt(0)
	s_setprio 1
	s_waitcnt lgkmcnt(0)
	v_mfma_f32_16x16x32_bf16 v[116:119], v[210:213], v[162:165], v[116:119]
	v_mfma_f32_16x16x32_bf16 v[112:115], v[218:221], v[162:165], v[112:115]
	v_mfma_f32_16x16x32_bf16 v[100:103], v[210:213], v[182:185], v[100:103]
	v_mfma_f32_16x16x32_bf16 v[96:99], v[218:221], v[182:185], v[96:99]
	v_mfma_f32_16x16x32_bf16 v[84:87], v[210:213], v[190:193], v[84:87]
	v_mfma_f32_16x16x32_bf16 v[80:83], v[218:221], v[190:193], v[80:83]
	v_mfma_f32_16x16x32_bf16 v[68:71], v[210:213], v[202:205], v[68:71]
	v_mfma_f32_16x16x32_bf16 v[64:67], v[218:221], v[202:205], v[64:67]
	v_mfma_f32_16x16x32_bf16 v[116:119], v[214:217], v[178:181], v[116:119]
	v_mfma_f32_16x16x32_bf16 v[112:115], v[222:225], v[178:181], v[112:115]
	v_mfma_f32_16x16x32_bf16 v[100:103], v[214:217], v[186:189], v[100:103]
	v_mfma_f32_16x16x32_bf16 v[96:99], v[222:225], v[186:189], v[96:99]
	v_mfma_f32_16x16x32_bf16 v[84:87], v[214:217], v[194:197], v[84:87]
	v_mfma_f32_16x16x32_bf16 v[80:83], v[222:225], v[194:197], v[80:83]
	v_mfma_f32_16x16x32_bf16 v[68:71], v[214:217], v[206:209], v[68:71]
	v_mfma_f32_16x16x32_bf16 v[64:67], v[222:225], v[206:209], v[64:67]
	s_setprio 0
	s_mov_b32 m0, s54
	s_mov_b64 s[20:21], 0x80
	v_lshl_add_u64 v[166:167], v[226:227], 0, s[20:21]
	s_barrier
	ds_read_b128 v[162:165], v172 offset:49152
	ds_read_b128 v[178:181], v172 offset:50176
	ds_read_b128 v[182:185], v172 offset:51200
	ds_read_b128 v[186:189], v172 offset:52224
	ds_read_b128 v[190:193], v172 offset:53248
	ds_read_b128 v[194:197], v172 offset:54272
	ds_read_b128 v[202:205], v172 offset:55296
	ds_read_b128 v[206:209], v172 offset:56320
	global_load_lds_dwordx4 v[166:167], off
	v_lshl_add_u64 v[166:167], v[228:229], 0, s[20:21]
	s_mov_b32 m0, s55
	s_nop 0
	global_load_lds_dwordx4 v[166:167], off
	s_barrier
; #define PG8_STAGE(bufoff, gbase, voff) do { _Pragma("unroll") for (int _i = 0; _i < 2; ++_i) \
;         __builtin_amdgcn_global_load_lds((const unsigned*)((const char*)(gbase) + (voff)[_i]), (LAS unsigned*)(lds + (bufoff) + ldsw + _i * 8192), 16, 0, 0); } while (0)
; #define PG8_LDA(dst, b, h) do { _Pragma("unroll") for (int m = 0; m < 4; ++m) _Pragma("unroll") for (int k = 0; k < 2; ++k) dst[m][k] = *(const LAS bf16x8*)(lds + PG8_SA(b, h) + aoff + m * 2048 + k * 1024); } while (0)
; #define PG8_LDB(dst, b, h) do { _Pragma("unroll") for (int n = 0; n < 2; ++n) _Pragma("unroll") for (int k = 0; k < 2; ++k) dst[n][k] = *(const LAS bf16x8*)(lds + PG8_SB(b, h) + boff + n * 2048 + k * 1024); } while (0)
; #define PG8_MMA(ai, bj, At, Bt) do { __builtin_amdgcn_s_setprio(1); _Pragma("unroll") for (int m = 0; m < 4; ++m) _Pragma("unroll") for (int n = 0; n < 2; ++n) _Pragma("unroll") for (int k = 0; k < 2; ++k) \
;         acc[ai][bj][m][n] = __builtin_amdgcn_mfma_f32_16x16x32_bf16(Bt[n][k], At[m][k], acc[ai][bj][m][n], 0, 0, 0); __builtin_amdgcn_s_setprio(0); } while (0)
; #define PG8_WAIT_V(n) asm volatile("s_waitcnt vmcnt(" #n ")" ::: "memory")
; #define PG8_WAIT_L(n) asm volatile("s_waitcnt lgkmcnt(" #n ")" ::: "memory")
; #define PG8_BAR __builtin_amdgcn_s_barrier()
; #define PG8_SCHED __builtin_amdgcn_sched_barrier(0)
; template <class Epi, class Sched>
; __device__ __forceinline__ void gemm_phase(LAS unsigned char* lds, const Gemm g, const Sched& S, const Epi& E) {
;     ...
;             PG8_LDB(B0, 0, 0); PG8_SCHED; PG8_LDA(At, 0, 0); PG8_STAGE(PG8_SA(1, 1), a1 + hstep, voffA);
;             PG8_WAIT_L(8); PG8_BAR; PG8_WAIT_L(0); PG8_MMA(0, 0, At, B0); PG8_BAR; PG8_SCHED;
;             PG8_LDB(B1, 0, 1); PG8_STAGE(PG8_SB(0, 0), b2, voffB);
;             PG8_BAR; PG8_WAIT_L(0); PG8_MMA(0, 1, At, B1); PG8_BAR;
;             PG8_LDA(At, 0, 1); PG8_STAGE(PG8_SA(0, 0), a2, voffA);
;     ...
;             PG8_BAR; PG8_WAIT_L(0); PG8_MMA(1, 0, At, B0); PG8_BAR; PG8_SCHED;
;             PG8_STAGE(PG8_SB(1, 1), b3 + hstep, voffB);
;             PG8_WAIT_V(6); PG8_BAR; PG8_MMA(1, 1, At, B1); PG8_BAR;
	s_waitcnt lgkmcnt(0)
	s_setprio 1
	s_waitcnt lgkmcnt(0)
	v_mfma_f32_16x16x32_bf16 v[60:63], v[146:149], v[162:165], v[60:63]
	v_mfma_f32_16x16x32_bf16 v[56:59], v[154:157], v[162:165], v[56:59]
	v_mfma_f32_16x16x32_bf16 v[44:47], v[146:149], v[182:185], v[44:47]
	v_mfma_f32_16x16x32_bf16 v[40:43], v[154:157], v[182:185], v[40:43]
	v_mfma_f32_16x16x32_bf16 v[28:31], v[146:149], v[190:193], v[28:31]
	v_mfma_f32_16x16x32_bf16 v[24:27], v[154:157], v[190:193], v[24:27]
	v_mfma_f32_16x16x32_bf16 v[12:15], v[146:149], v[202:205], v[12:15]
	v_mfma_f32_16x16x32_bf16 v[8:11], v[154:157], v[202:205], v[8:11]
	v_mfma_f32_16x16x32_bf16 v[60:63], v[150:153], v[178:181], v[60:63]
	v_mfma_f32_16x16x32_bf16 v[56:59], v[158:161], v[178:181], v[56:59]
	v_mfma_f32_16x16x32_bf16 v[44:47], v[150:153], v[186:189], v[44:47]
	v_mfma_f32_16x16x32_bf16 v[40:43], v[158:161], v[186:189], v[40:43]
	v_mfma_f32_16x16x32_bf16 v[28:31], v[150:153], v[194:197], v[28:31]
	v_mfma_f32_16x16x32_bf16 v[24:27], v[158:161], v[194:197], v[24:27]
	v_mfma_f32_16x16x32_bf16 v[12:15], v[150:153], v[206:209], v[12:15]
	v_mfma_f32_16x16x32_bf16 v[8:11], v[158:161], v[206:209], v[8:11]
	s_setprio 0
	s_barrier
	s_add_u32 s4, s4, 0x40080
	s_addc_u32 s5, s5, 0
	s_add_i32 s6, s6, s44
	s_mov_b32 m0, s6
	s_nop 0
	global_load_lds_dwordx4 v130, s[4:5]
	s_add_i32 m0, s6, 0x2000
	s_nop 0
	global_load_lds_dwordx4 v134, s[4:5]
	s_waitcnt vmcnt(8)
	s_barrier
	s_setprio 1
	v_mfma_f32_16x16x32_bf16 v[52:55], v[210:213], v[162:165], v[52:55]
	v_mfma_f32_16x16x32_bf16 v[48:51], v[218:221], v[162:165], v[48:51]
	v_mfma_f32_16x16x32_bf16 v[36:39], v[210:213], v[182:185], v[36:39]
	v_mfma_f32_16x16x32_bf16 v[32:35], v[218:221], v[182:185], v[32:35]
	v_mfma_f32_16x16x32_bf16 v[20:23], v[210:213], v[190:193], v[20:23]
	v_mfma_f32_16x16x32_bf16 v[16:19], v[218:221], v[190:193], v[16:19]
	v_mfma_f32_16x16x32_bf16 v[4:7], v[210:213], v[202:205], v[4:7]
	v_mfma_f32_16x16x32_bf16 v[0:3], v[218:221], v[202:205], v[0:3]
	v_mfma_f32_16x16x32_bf16 v[52:55], v[214:217], v[178:181], v[52:55]
	v_mfma_f32_16x16x32_bf16 v[48:51], v[222:225], v[178:181], v[48:51]
	v_mfma_f32_16x16x32_bf16 v[36:39], v[214:217], v[186:189], v[36:39]
	v_mfma_f32_16x16x32_bf16 v[32:35], v[222:225], v[186:189], v[32:35]
	v_mfma_f32_16x16x32_bf16 v[20:23], v[214:217], v[194:197], v[20:23]
	v_mfma_f32_16x16x32_bf16 v[16:19], v[222:225], v[194:197], v[16:19]
	v_mfma_f32_16x16x32_bf16 v[4:7], v[214:217], v[206:209], v[4:7]
	v_mfma_f32_16x16x32_bf16 v[0:3], v[222:225], v[206:209], v[0:3]
	s_setprio 0
	s_add_i32 s67, s67, 2
	s_add_u32 s0, s0, 0x100
	s_addc_u32 s1, s1, 0
	s_add_u32 s65, s65, 0x100
	s_addc_u32 s66, s66, 0
	s_cmp_gt_u32 s67, 13
	s_barrier
.LBB0_613:
	ds_read_b128 v[146:149], v171
	ds_read_b128 v[150:153], v171 offset:1024
	ds_read_b128 v[154:157], v171 offset:2048
	ds_read_b128 v[158:161], v171 offset:3072
	s_add_u32 s4, s0, 0xfffc0080
	s_addc_u32 s5, s1, -1
	s_cmp_eq_u32 s67, 12
	s_cselect_b32 s7, s8, s5
	s_cselect_b32 s6, s9, s4
	s_cselect_b32 s5, s31, s66
	s_cselect_b32 s4, s35, s65
	s_add_i32 m0, s45, 0xc000
	ds_read_b128 v[162:165], v172
	ds_read_b128 v[178:181], v172 offset:1024
	ds_read_b128 v[182:185], v172 offset:2048
	ds_read_b128 v[186:189], v172 offset:3072
	ds_read_b128 v[190:193], v172 offset:4096
	ds_read_b128 v[194:197], v172 offset:5120
	ds_read_b128 v[202:205], v172 offset:6144
	ds_read_b128 v[206:209], v172 offset:7168
	global_load_lds_dwordx4 v138, s[0:1]
	s_add_i32 m0, s45, 0xe000
	s_nop 0
	global_load_lds_dwordx4 v140, s[0:1]
	s_waitcnt lgkmcnt(8)
	s_waitcnt vmcnt(8)
	s_barrier
	s_waitcnt lgkmcnt(0)
	s_setprio 1
	s_waitcnt lgkmcnt(0)
	v_mfma_f32_16x16x32_bf16 v[124:127], v[146:149], v[162:165], v[124:127]
	v_mfma_f32_16x16x32_bf16 v[120:123], v[154:157], v[162:165], v[120:123]
	v_mfma_f32_16x16x32_bf16 v[108:111], v[146:149], v[182:185], v[108:111]
	v_mfma_f32_16x16x32_bf16 v[104:107], v[154:157], v[182:185], v[104:107]
	v_mfma_f32_16x16x32_bf16 v[92:95], v[146:149], v[190:193], v[92:95]
	v_mfma_f32_16x16x32_bf16 v[88:91], v[154:157], v[190:193], v[88:91]
	v_mfma_f32_16x16x32_bf16 v[76:79], v[146:149], v[202:205], v[76:79]
	v_mfma_f32_16x16x32_bf16 v[72:75], v[154:157], v[202:205], v[72:75]
	v_mfma_f32_16x16x32_bf16 v[124:127], v[150:153], v[178:181], v[124:127]
	v_mfma_f32_16x16x32_bf16 v[120:123], v[158:161], v[178:181], v[120:123]
	v_mfma_f32_16x16x32_bf16 v[108:111], v[150:153], v[186:189], v[108:111]
	v_mfma_f32_16x16x32_bf16 v[104:107], v[158:161], v[186:189], v[104:107]
	v_mfma_f32_16x16x32_bf16 v[92:95], v[150:153], v[194:197], v[92:95]
	v_mfma_f32_16x16x32_bf16 v[88:91], v[158:161], v[194:197], v[88:91]
	v_mfma_f32_16x16x32_bf16 v[76:79], v[150:153], v[206:209], v[76:79]
	v_mfma_f32_16x16x32_bf16 v[72:75], v[158:161], v[206:209], v[72:75]
	s_setprio 0
	s_barrier
	s_add_i32 s68, s57, s44
	s_mov_b32 m0, s68
	ds_read_b128 v[210:213], v173
	ds_read_b128 v[214:217], v173 offset:1024
	ds_read_b128 v[218:221], v173 offset:2048
	ds_read_b128 v[222:225], v173 offset:3072
	global_load_lds_dwordx4 v130, s[4:5]
	s_add_i32 m0, s68, 0x2000
	s_nop 0
	global_load_lds_dwordx4 v134, s[4:5]
	s_waitcnt vmcnt(8)
	s_barrier
; #define PG8_STAGE(bufoff, gbase, voff) do { _Pragma("unroll") for (int _i = 0; _i < 2; ++_i) \
;         __builtin_amdgcn_global_load_lds((const unsigned*)((const char*)(gbase) + (voff)[_i]), (LAS unsigned*)(lds + (bufoff) + ldsw + _i * 8192), 16, 0, 0); } while (0)
; #define PG8_LDA(dst, b, h) do { _Pragma("unroll") for (int m = 0; m < 4; ++m) _Pragma("unroll") for (int k = 0; k < 2; ++k) dst[m][k] = *(const LAS bf16x8*)(lds + PG8_SA(b, h) + aoff + m * 2048 + k * 1024); } while (0)
; #define PG8_LDB(dst, b, h) do { _Pragma("unroll") for (int n = 0; n < 2; ++n) _Pragma("unroll") for (int k = 0; k < 2; ++k) dst[n][k] = *(const LAS bf16x8*)(lds + PG8_SB(b, h) + boff + n * 2048 + k * 1024); } while (0)
; #define PG8_MMA(ai, bj, At, Bt) do { __builtin_amdgcn_s_setprio(1); _Pragma("unroll") for (int m = 0; m < 4; ++m) _Pragma("unroll") for (int n = 0; n < 2; ++n) _Pragma("unroll") for (int k = 0; k < 2; ++k) \
;         acc[ai][bj][m][n] = __builtin_amdgcn_mfma_f32_16x16x32_bf16(Bt[n][k], At[m][k], acc[ai][bj][m][n], 0, 0, 0); __builtin_amdgcn_s_setprio(0); } while (0)
; #define PG8_WAIT_V(n) asm volatile("s_waitcnt vmcnt(" #n ")" ::: "memory")
; #define PG8_WAIT_L(n) asm volatile("s_waitcnt lgkmcnt(" #n ")" ::: "memory")
; #define PG8_BAR __builtin_amdgcn_s_barrier()
; #define PG8_SCHED __builtin_amdgcn_sched_barrier(0)
; template <class Epi, class Sched>
; __device__ __forceinline__ void gemm_phase(LAS unsigned char* lds, const Gemm g, const Sched& S, const Epi& E) {
;     ...
;             PG8_BAR; PG8_WAIT_L(0); PG8_MMA(1, 0, At, B0); PG8_BAR; PG8_SCHED;
;             PG8_STAGE(PG8_SB(0, 1), b2 + hstep, voffB);
;             PG8_WAIT_V(6); PG8_BAR; PG8_MMA(1, 1, At, B1); PG8_BAR;
;             PG8_LDB(B0, 1, 0); PG8_SCHED; PG8_LDA(At, 1, 0); PG8_STAGE(PG8_SA(0, 1), a2 + hstep, voffA);
;             PG8_WAIT_L(8); PG8_BAR; PG8_WAIT_L(0); PG8_MMA(0, 0, At, B0); PG8_BAR; PG8_SCHED;
	s_waitcnt lgkmcnt(0)
	s_setprio 1
	s_waitcnt lgkmcnt(0)
	v_mfma_f32_16x16x32_bf16 v[116:119], v[210:213], v[162:165], v[116:119]
	v_mfma_f32_16x16x32_bf16 v[112:115], v[218:221], v[162:165], v[112:115]
	v_mfma_f32_16x16x32_bf16 v[100:103], v[210:213], v[182:185], v[100:103]
	v_mfma_f32_16x16x32_bf16 v[96:99], v[218:221], v[182:185], v[96:99]
	v_mfma_f32_16x16x32_bf16 v[84:87], v[210:213], v[190:193], v[84:87]
	v_mfma_f32_16x16x32_bf16 v[80:83], v[218:221], v[190:193], v[80:83]
	v_mfma_f32_16x16x32_bf16 v[68:71], v[210:213], v[202:205], v[68:71]
	v_mfma_f32_16x16x32_bf16 v[64:67], v[218:221], v[202:205], v[64:67]
	v_mfma_f32_16x16x32_bf16 v[116:119], v[214:217], v[178:181], v[116:119]
	v_mfma_f32_16x16x32_bf16 v[112:115], v[222:225], v[178:181], v[112:115]
	v_mfma_f32_16x16x32_bf16 v[100:103], v[214:217], v[186:189], v[100:103]
	v_mfma_f32_16x16x32_bf16 v[96:99], v[222:225], v[186:189], v[96:99]
	v_mfma_f32_16x16x32_bf16 v[84:87], v[214:217], v[194:197], v[84:87]
	v_mfma_f32_16x16x32_bf16 v[80:83], v[222:225], v[194:197], v[80:83]
	v_mfma_f32_16x16x32_bf16 v[68:71], v[214:217], v[206:209], v[68:71]
	v_mfma_f32_16x16x32_bf16 v[64:67], v[222:225], v[206:209], v[64:67]
	s_setprio 0
	s_mov_b32 m0, s45
	v_lshl_add_u64 v[226:227], s[6:7], 0, v[128:129]
	s_barrier
	ds_read_b128 v[162:165], v172 offset:16384
	ds_read_b128 v[178:181], v172 offset:17408
	ds_read_b128 v[182:185], v172 offset:18432
	ds_read_b128 v[186:189], v172 offset:19456
	ds_read_b128 v[190:193], v172 offset:20480
	ds_read_b128 v[194:197], v172 offset:21504
	ds_read_b128 v[202:205], v172 offset:22528
	ds_read_b128 v[206:209], v172 offset:23552
	global_load_lds_dwordx4 v128, s[6:7]
	v_lshl_add_u64 v[228:229], s[6:7], 0, v[132:133]
	s_mov_b32 m0, s46
	s_nop 0
	global_load_lds_dwordx4 v132, s[6:7]
	s_barrier
	s_waitcnt lgkmcnt(0)
	s_setprio 1
	s_waitcnt lgkmcnt(0)
	v_mfma_f32_16x16x32_bf16 v[60:63], v[146:149], v[162:165], v[60:63]
	v_mfma_f32_16x16x32_bf16 v[56:59], v[154:157], v[162:165], v[56:59]
	v_mfma_f32_16x16x32_bf16 v[44:47], v[146:149], v[182:185], v[44:47]
	v_mfma_f32_16x16x32_bf16 v[40:43], v[154:157], v[182:185], v[40:43]
	v_mfma_f32_16x16x32_bf16 v[28:31], v[146:149], v[190:193], v[28:31]
	v_mfma_f32_16x16x32_bf16 v[24:27], v[154:157], v[190:193], v[24:27]
	v_mfma_f32_16x16x32_bf16 v[12:15], v[146:149], v[202:205], v[12:15]
	v_mfma_f32_16x16x32_bf16 v[8:11], v[154:157], v[202:205], v[8:11]
	v_mfma_f32_16x16x32_bf16 v[60:63], v[150:153], v[178:181], v[60:63]
	v_mfma_f32_16x16x32_bf16 v[56:59], v[158:161], v[178:181], v[56:59]
	v_mfma_f32_16x16x32_bf16 v[44:47], v[150:153], v[186:189], v[44:47]
	v_mfma_f32_16x16x32_bf16 v[40:43], v[158:161], v[186:189], v[40:43]
	v_mfma_f32_16x16x32_bf16 v[28:31], v[150:153], v[194:197], v[28:31]
	v_mfma_f32_16x16x32_bf16 v[24:27], v[158:161], v[194:197], v[24:27]
	v_mfma_f32_16x16x32_bf16 v[12:15], v[150:153], v[206:209], v[12:15]
	v_mfma_f32_16x16x32_bf16 v[8:11], v[158:161], v[206:209], v[8:11]
	s_setprio 0
	s_barrier
	s_add_u32 s68, s4, 0x40000
	s_addc_u32 s69, s5, 0
	s_add_i32 s70, s58, s44
	s_mov_b32 m0, s70
	s_nop 0
	global_load_lds_dwordx4 v130, s[68:69]
	s_add_i32 m0, s70, 0x2000
	s_nop 0
	global_load_lds_dwordx4 v134, s[68:69]
	s_add_u32 s6, s6, 0x40000
	s_addc_u32 s7, s7, 0
	s_mov_b32 m0, s47
	s_nop 0
	global_load_lds_dwordx4 v128, s[6:7]
	s_mov_b32 m0, s48
	s_nop 0
	global_load_lds_dwordx4 v132, s[6:7]
	s_waitcnt vmcnt(10)
	s_barrier
	s_setprio 1
	v_mfma_f32_16x16x32_bf16 v[52:55], v[210:213], v[162:165], v[52:55]
	v_mfma_f32_16x16x32_bf16 v[48:51], v[218:221], v[162:165], v[48:51]
	v_mfma_f32_16x16x32_bf16 v[36:39], v[210:213], v[182:185], v[36:39]
	v_mfma_f32_16x16x32_bf16 v[32:35], v[218:221], v[182:185], v[32:35]
	v_mfma_f32_16x16x32_bf16 v[20:23], v[210:213], v[190:193], v[20:23]
	v_mfma_f32_16x16x32_bf16 v[16:19], v[218:221], v[190:193], v[16:19]
	v_mfma_f32_16x16x32_bf16 v[4:7], v[210:213], v[202:205], v[4:7]
	v_mfma_f32_16x16x32_bf16 v[0:3], v[218:221], v[202:205], v[0:3]
	v_mfma_f32_16x16x32_bf16 v[52:55], v[214:217], v[178:181], v[52:55]
	v_mfma_f32_16x16x32_bf16 v[48:51], v[222:225], v[178:181], v[48:51]
	v_mfma_f32_16x16x32_bf16 v[36:39], v[214:217], v[186:189], v[36:39]
	v_mfma_f32_16x16x32_bf16 v[32:35], v[222:225], v[186:189], v[32:35]
	v_mfma_f32_16x16x32_bf16 v[20:23], v[214:217], v[194:197], v[20:23]
	v_mfma_f32_16x16x32_bf16 v[16:19], v[222:225], v[194:197], v[16:19]
	v_mfma_f32_16x16x32_bf16 v[4:7], v[214:217], v[206:209], v[4:7]
	v_mfma_f32_16x16x32_bf16 v[0:3], v[222:225], v[206:209], v[0:3]
	s_setprio 0
	s_add_i32 s68, 0, 0x18000
	v_add_u32_e32 v136, s68, v170
	s_barrier
	ds_read_b128 v[146:149], v136
	ds_read_b128 v[150:153], v136 offset:1024
	ds_read_b128 v[154:157], v136 offset:2048
	ds_read_b128 v[158:161], v136 offset:3072
	ds_read_b128 v[162:165], v172 offset:32768
	ds_read_b128 v[178:181], v172 offset:33792
	ds_read_b128 v[182:185], v172 offset:34816
	ds_read_b128 v[186:189], v172 offset:35840
	ds_read_b128 v[190:193], v172 offset:36864
	ds_read_b128 v[194:197], v172 offset:37888
	ds_read_b128 v[202:205], v172 offset:38912
	ds_read_b128 v[206:209], v172 offset:39936
	s_waitcnt lgkmcnt(8)
	s_waitcnt vmcnt(8)
	s_barrier
; #define PG8_STAGE(bufoff, gbase, voff) do { _Pragma("unroll") for (int _i = 0; _i < 2; ++_i) \
;         __builtin_amdgcn_global_load_lds((const unsigned*)((const char*)(gbase) + (voff)[_i]), (LAS unsigned*)(lds + (bufoff) + ldsw + _i * 8192), 16, 0, 0); } while (0)
; #define PG8_LDA(dst, b, h) do { _Pragma("unroll") for (int m = 0; m < 4; ++m) _Pragma("unroll") for (int k = 0; k < 2; ++k) dst[m][k] = *(const LAS bf16x8*)(lds + PG8_SA(b, h) + aoff + m * 2048 + k * 1024); } while (0)
; #define PG8_LDB(dst, b, h) do { _Pragma("unroll") for (int n = 0; n < 2; ++n) _Pragma("unroll") for (int k = 0; k < 2; ++k) dst[n][k] = *(const LAS bf16x8*)(lds + PG8_SB(b, h) + boff + n * 2048 + k * 1024); } while (0)
; #define PG8_MMA(ai, bj, At, Bt) do { __builtin_amdgcn_s_setprio(1); _Pragma("unroll") for (int m = 0; m < 4; ++m) _Pragma("unroll") for (int n = 0; n < 2; ++n) _Pragma("unroll") for (int k = 0; k < 2; ++k) \
;         acc[ai][bj][m][n] = __builtin_amdgcn_mfma_f32_16x16x32_bf16(Bt[n][k], At[m][k], acc[ai][bj][m][n], 0, 0, 0); __builtin_amdgcn_s_setprio(0); } while (0)
; #define PG8_WAIT_V(n) asm volatile("s_waitcnt vmcnt(" #n ")" ::: "memory")
; #define PG8_WAIT_L(n) asm volatile("s_waitcnt lgkmcnt(" #n ")" ::: "memory")
; #define PG8_BAR __builtin_amdgcn_s_barrier()
; #define PG8_SCHED __builtin_amdgcn_sched_barrier(0)
; template <class Epi, class Sched>
; __device__ __forceinline__ void gemm_phase(LAS unsigned char* lds, const Gemm g, const Sched& S, const Epi& E) {
;     ...
;             PG8_WAIT_L(8); PG8_BAR; PG8_WAIT_L(0); PG8_MMA(0, 0, At, B0); PG8_BAR; PG8_SCHED;
;             PG8_LDB(B1, 1, 1); PG8_STAGE(PG8_SB(1, 0), b3, voffB);
;             PG8_BAR; PG8_WAIT_L(0); PG8_MMA(0, 1, At, B1); PG8_BAR;
;             PG8_LDA(At, 1, 1); PG8_STAGE(PG8_SA(1, 0), a3, voffA);
;             PG8_BAR; PG8_WAIT_L(0); PG8_MMA(1, 0, At, B0); PG8_BAR; PG8_SCHED;
;             PG8_STAGE(PG8_SB(1, 1), b3 + hstep, voffB);
;             PG8_WAIT_V(6); PG8_BAR; PG8_MMA(1, 1, At, B1); PG8_BAR;
	s_waitcnt lgkmcnt(0)
	s_setprio 1
	s_waitcnt lgkmcnt(0)
	v_mfma_f32_16x16x32_bf16 v[124:127], v[146:149], v[162:165], v[124:127]
	v_mfma_f32_16x16x32_bf16 v[120:123], v[154:157], v[162:165], v[120:123]
	v_mfma_f32_16x16x32_bf16 v[108:111], v[146:149], v[182:185], v[108:111]
	v_mfma_f32_16x16x32_bf16 v[104:107], v[154:157], v[182:185], v[104:107]
	v_mfma_f32_16x16x32_bf16 v[92:95], v[146:149], v[190:193], v[92:95]
	v_mfma_f32_16x16x32_bf16 v[88:91], v[154:157], v[190:193], v[88:91]
	v_mfma_f32_16x16x32_bf16 v[76:79], v[146:149], v[202:205], v[76:79]
	v_mfma_f32_16x16x32_bf16 v[72:75], v[154:157], v[202:205], v[72:75]
	v_mfma_f32_16x16x32_bf16 v[124:127], v[150:153], v[178:181], v[124:127]
	v_mfma_f32_16x16x32_bf16 v[120:123], v[158:161], v[178:181], v[120:123]
	v_mfma_f32_16x16x32_bf16 v[108:111], v[150:153], v[186:189], v[108:111]
	v_mfma_f32_16x16x32_bf16 v[104:107], v[158:161], v[186:189], v[104:107]
	v_mfma_f32_16x16x32_bf16 v[92:95], v[150:153], v[194:197], v[92:95]
	v_mfma_f32_16x16x32_bf16 v[88:91], v[158:161], v[194:197], v[88:91]
	v_mfma_f32_16x16x32_bf16 v[76:79], v[150:153], v[206:209], v[76:79]
	v_mfma_f32_16x16x32_bf16 v[72:75], v[158:161], v[206:209], v[72:75]
	s_setprio 0
	s_barrier
	s_add_i32 s6, 0, 0x1c000
	s_add_i32 s7, s68, s44
	v_add_u32_e32 v136, s6, v170
	s_add_u32 s20, s4, 0x80
	s_addc_u32 s21, s5, 0
	s_mov_b32 m0, s7
	ds_read_b128 v[210:213], v136
	ds_read_b128 v[214:217], v136 offset:1024
	ds_read_b128 v[218:221], v136 offset:2048
	ds_read_b128 v[222:225], v136 offset:3072
	global_load_lds_dwordx4 v130, s[20:21]
	s_add_i32 m0, s7, 0x2000
	s_nop 0
	global_load_lds_dwordx4 v134, s[20:21]
	s_waitcnt vmcnt(8)
	s_barrier
	s_waitcnt lgkmcnt(0)
	s_setprio 1
	s_waitcnt lgkmcnt(0)
	v_mfma_f32_16x16x32_bf16 v[116:119], v[210:213], v[162:165], v[116:119]
	v_mfma_f32_16x16x32_bf16 v[112:115], v[218:221], v[162:165], v[112:115]
	v_mfma_f32_16x16x32_bf16 v[100:103], v[210:213], v[182:185], v[100:103]
	v_mfma_f32_16x16x32_bf16 v[96:99], v[218:221], v[182:185], v[96:99]
	v_mfma_f32_16x16x32_bf16 v[84:87], v[210:213], v[190:193], v[84:87]
	v_mfma_f32_16x16x32_bf16 v[80:83], v[218:221], v[190:193], v[80:83]
	v_mfma_f32_16x16x32_bf16 v[68:71], v[210:213], v[202:205], v[68:71]
	v_mfma_f32_16x16x32_bf16 v[64:67], v[218:221], v[202:205], v[64:67]
	v_mfma_f32_16x16x32_bf16 v[116:119], v[214:217], v[178:181], v[116:119]
	v_mfma_f32_16x16x32_bf16 v[112:115], v[222:225], v[178:181], v[112:115]
	v_mfma_f32_16x16x32_bf16 v[100:103], v[214:217], v[186:189], v[100:103]
	v_mfma_f32_16x16x32_bf16 v[96:99], v[222:225], v[186:189], v[96:99]
	v_mfma_f32_16x16x32_bf16 v[84:87], v[214:217], v[194:197], v[84:87]
	v_mfma_f32_16x16x32_bf16 v[80:83], v[222:225], v[194:197], v[80:83]
	v_mfma_f32_16x16x32_bf16 v[68:71], v[214:217], v[206:209], v[68:71]
	v_mfma_f32_16x16x32_bf16 v[64:67], v[222:225], v[206:209], v[64:67]
	s_setprio 0
	s_mov_b32 m0, s54
	s_mov_b64 s[20:21], 0x80
	v_lshl_add_u64 v[166:167], v[226:227], 0, s[20:21]
	s_barrier
	ds_read_b128 v[162:165], v172 offset:49152
	ds_read_b128 v[178:181], v172 offset:50176
	ds_read_b128 v[182:185], v172 offset:51200
	ds_read_b128 v[186:189], v172 offset:52224
	ds_read_b128 v[190:193], v172 offset:53248
	ds_read_b128 v[194:197], v172 offset:54272
	ds_read_b128 v[202:205], v172 offset:55296
	ds_read_b128 v[206:209], v172 offset:56320
	global_load_lds_dwordx4 v[166:167], off
	v_lshl_add_u64 v[166:167], v[228:229], 0, s[20:21]
	s_mov_b32 m0, s55
	s_nop 0
	global_load_lds_dwordx4 v[166:167], off
	s_barrier
	s_waitcnt lgkmcnt(0)
	s_setprio 1
	s_waitcnt lgkmcnt(0)
	v_mfma_f32_16x16x32_bf16 v[60:63], v[146:149], v[162:165], v[60:63]
	v_mfma_f32_16x16x32_bf16 v[56:59], v[154:157], v[162:165], v[56:59]
	v_mfma_f32_16x16x32_bf16 v[44:47], v[146:149], v[182:185], v[44:47]
	v_mfma_f32_16x16x32_bf16 v[40:43], v[154:157], v[182:185], v[40:43]
	v_mfma_f32_16x16x32_bf16 v[28:31], v[146:149], v[190:193], v[28:31]
	v_mfma_f32_16x16x32_bf16 v[24:27], v[154:157], v[190:193], v[24:27]
	v_mfma_f32_16x16x32_bf16 v[12:15], v[146:149], v[202:205], v[12:15]
	v_mfma_f32_16x16x32_bf16 v[8:11], v[154:157], v[202:205], v[8:11]
	v_mfma_f32_16x16x32_bf16 v[60:63], v[150:153], v[178:181], v[60:63]
	v_mfma_f32_16x16x32_bf16 v[56:59], v[158:161], v[178:181], v[56:59]
	v_mfma_f32_16x16x32_bf16 v[44:47], v[150:153], v[186:189], v[44:47]
	v_mfma_f32_16x16x32_bf16 v[40:43], v[158:161], v[186:189], v[40:43]
	v_mfma_f32_16x16x32_bf16 v[28:31], v[150:153], v[194:197], v[28:31]
	v_mfma_f32_16x16x32_bf16 v[24:27], v[158:161], v[194:197], v[24:27]
	v_mfma_f32_16x16x32_bf16 v[12:15], v[150:153], v[206:209], v[12:15]
	v_mfma_f32_16x16x32_bf16 v[8:11], v[158:161], v[206:209], v[8:11]
	s_setprio 0
	s_barrier
	s_add_u32 s4, s4, 0x40080
	s_addc_u32 s5, s5, 0
	s_add_i32 s6, s6, s44
	s_mov_b32 m0, s6
	s_nop 0
	global_load_lds_dwordx4 v130, s[4:5]
	s_add_i32 m0, s6, 0x2000
	s_nop 0
	global_load_lds_dwordx4 v134, s[4:5]
	s_waitcnt vmcnt(8)
	s_barrier
	s_setprio 1
	v_mfma_f32_16x16x32_bf16 v[52:55], v[210:213], v[162:165], v[52:55]
	v_mfma_f32_16x16x32_bf16 v[48:51], v[218:221], v[162:165], v[48:51]
	v_mfma_f32_16x16x32_bf16 v[36:39], v[210:213], v[182:185], v[36:39]
	v_mfma_f32_16x16x32_bf16 v[32:35], v[218:221], v[182:185], v[32:35]
	v_mfma_f32_16x16x32_bf16 v[20:23], v[210:213], v[190:193], v[20:23]
	v_mfma_f32_16x16x32_bf16 v[16:19], v[218:221], v[190:193], v[16:19]
	v_mfma_f32_16x16x32_bf16 v[4:7], v[210:213], v[202:205], v[4:7]
	v_mfma_f32_16x16x32_bf16 v[0:3], v[218:221], v[202:205], v[0:3]
	v_mfma_f32_16x16x32_bf16 v[52:55], v[214:217], v[178:181], v[52:55]
	v_mfma_f32_16x16x32_bf16 v[48:51], v[222:225], v[178:181], v[48:51]
	v_mfma_f32_16x16x32_bf16 v[36:39], v[214:217], v[186:189], v[36:39]
	v_mfma_f32_16x16x32_bf16 v[32:35], v[222:225], v[186:189], v[32:35]
	v_mfma_f32_16x16x32_bf16 v[20:23], v[214:217], v[194:197], v[20:23]
	v_mfma_f32_16x16x32_bf16 v[16:19], v[222:225], v[194:197], v[16:19]
	v_mfma_f32_16x16x32_bf16 v[4:7], v[214:217], v[206:209], v[4:7]
	v_mfma_f32_16x16x32_bf16 v[0:3], v[222:225], v[206:209], v[0:3]
	s_setprio 0
	s_add_i32 s67, s67, 2
	s_add_u32 s0, s0, 0x100
	s_addc_u32 s1, s1, 0
	s_add_u32 s65, s65, 0x100
	s_addc_u32 s66, s66, 0
	s_cmp_gt_u32 s67, 13
	s_barrier
;     __device__ __forceinline__ void operator()(const AccT& acc, const Unit& u, int wr, int wc, int fr, int fq) const {
;     ...
;         const int rbase = wr * 64 + fr;
;         const int tb = u.pn * 256 + wc * 32 + 8 * fq;
;         const int o0 = wc * 32 + 8 * fq;
;         const int j = fr & 3; const float sgn = ((fr >> 2) & 1) ? 1.0f : -1.0f;
; #pragma unroll
;         for (int ai = 0; ai < 2; ++ai) {
;             const int hh = 2 * ai + wr;
;             const float l2f = lgd[hh] * 1.4426950408889634f, l2b = lgd[4 + hh] * 1.4426950408889634f;
;             const float zf0 = exp2f((float)(127 - o0) * l2f), zfs = exp2f(-l2f), zb0 = exp2f((float)o0 * l2b), zbs = exp2f(l2b);
; #pragma unroll
;             for (int m = 0; m < 4; ++m) {
;                 const int r = rbase + ai * 128 + m * 16;
;                 const int d = 4 * (2 * m + (fr >> 3)) + j;
; #pragma unroll
;                 for (int bj = 0; bj < 2; ++bj) {
;                     const int t0 = tb + bj * 128;
;                     float v[8];
; #pragma unroll
;                     for (int jj = 0; jj < 4; ++jj) { v[jj] = acc[ai][bj][m][0][jj]; v[4 + jj] = acc[ai][bj][m][1][jj]; }
;                     if constexpr (ROPE) {
;                         const int t = t0 & 2047;
; #pragma unroll
;                         for (int hf = 0; hf < 2; ++hf) {
;                             f32x4 cs, sn;
;                             if (m < 2) { const float c1 = ropeA[(t >> 6) * 16 + d], s1 = ropeA[1024 + (t >> 6) * 16 + d]; cs = (f32x4){c1, c1, c1, c1}; sn = (f32x4){s1, s1, s1, s1}; }
;                             else { const float* cb = ropeA + 2048 + (d - 16) * 64 + (t & 63) + 4 * hf; cs = *(const f32x4*)(cb); sn = *(const f32x4*)(cb + 1024); }
; #pragma unroll
;                             for (int jj = 0; jj < 4; ++jj) { const float pr = __shfl_xor(v[4 * hf + jj], 4); v[4 * hf + jj] = v[4 * hf + jj] * cs[jj] + sgn * pr * sn[jj]; }
;                             __builtin_amdgcn_sched_barrier(0);
;                         }
;                     }
;                     float zf[8], zb[8]; zf[0] = zf0; zb[0] = zb0;
; #pragma unroll
;                     for (int jj = 1; jj < 8; ++jj) { zf[jj] = zf[jj - 1] * zfs; zb[jj] = zb[jj - 1] * zbs; }
;                     u32x4 wf, wb;
	s_cbranch_scc0 .LBB0_613
	v_mov_b32_e32 v136, v169
	v_mov_b32_e32 v150, v168
	s_lshl_b32 s0, s33, 8
	global_load_dword v154, v137, s[22:23]
	global_load_dword v155, v137, s[22:23] offset:16
	s_or_b32 s0, s0, s53
	v_lshlrev_b32_e32 v151, 3, v136
	v_ashrrev_i32_e32 v136, 1, v150
	v_add_u32_e32 v162, s0, v151
	v_bfi_b32 v136, -4, v136, v150
	v_lshrrev_b32_e32 v146, 2, v162
	v_add_u32_e32 v192, 0x400, v136
	v_and_b32_e32 v187, 0x1f0, v146
	v_add_u32_e32 v146, v192, v187
	v_add_u32_e32 v148, v187, v136
	v_ashrrev_i32_e32 v147, 31, v146
	v_ashrrev_i32_e32 v149, 31, v148
	v_lshl_add_u64 v[146:147], v[146:147], 2, s[16:17]
	v_lshl_add_u64 v[148:149], v[148:149], 2, s[16:17]
	global_load_dword v153, v[146:147], off
	global_load_dword v166, v[148:149], off
	v_and_b32_e32 v157, 64, v174
	v_xor_b32_e32 v156, 4, v174
	v_add_u32_e32 v157, 64, v157
	v_cmp_lt_i32_e32 vcc, v156, v157
	v_mov_b32_e32 v152, v124
	v_add_u32_e32 v151, s53, v151
	v_cndmask_b32_e32 v156, v174, v156, vcc
	v_lshlrev_b32_e32 v177, 2, v156
	ds_bpermute_b32 v124, v177, v124
	v_sub_u32_e32 v156, 0x7f, v151
	v_add_u32_e32 v164, s52, v150
	v_and_b32_e32 v150, 4, v150
	v_cvt_f32_i32_e32 v179, v156
	v_cvt_f32_i32_e32 v178, v151
	v_cmp_eq_u32_e32 vcc, 0, v150
	ds_bpermute_b32 v157, v177, v125
	ds_bpermute_b32 v158, v177, v127
	s_waitcnt lgkmcnt(0)
	v_cndmask_b32_e64 v167, v124, -v124, vcc
	ds_bpermute_b32 v151, v177, v126
	v_ashrrev_i32_e32 v165, 31, v164
	v_and_b32_e32 v186, 56, v162
	s_waitcnt lgkmcnt(0)
	v_cndmask_b32_e64 v151, v151, -v151, vcc
	s_waitcnt vmcnt(0)
	v_mul_f32_e32 v124, 0x3fb8aa3b, v154
	v_mul_f32_e32 v150, 0x3fb8aa3b, v155
	v_cmp_lt_f32_e64 s[4:5], s60, v124
	v_mul_f32_e32 v156, v124, v179
	v_cmp_gt_f32_e64 s[6:7], s59, v150
	v_cndmask_b32_e64 v159, 0, v176, s[4:5]
	v_mul_f32_e32 v160, v150, v178
	v_cndmask_b32_e64 v161, 0, v176, s[6:7]
	v_cmp_gt_f32_e64 s[8:9], s59, v156
	v_fmac_f32_e32 v159, 0xbfb8aa3b, v154
	s_and_b64 s[0:1], s[4:5], exec
	v_cmp_gt_f32_e64 s[4:5], s59, v160
	v_fmac_f32_e32 v161, 0x3fb8aa3b, v155
	v_cndmask_b32_e64 v154, 0, v176, s[8:9]
	v_exp_f32_e32 v155, v159
	v_cndmask_b32_e64 v159, 0, v176, s[4:5]
	v_fmac_f32_e32 v154, v124, v179
	v_fmac_f32_e32 v159, v150, v178
	v_exp_f32_e32 v150, v154
	v_cndmask_b32_e64 v156, 0, v175, s[8:9]
	s_cselect_b32 s8, 0xffffffc0, 0
	v_exp_f32_e32 v161, v161
	v_exp_f32_e32 v159, v159
	v_ldexp_f32 v163, v155, s8
	v_pk_mul_f32 v[154:155], v[152:153], v[166:167]
	v_cndmask_b32_e64 v167, v157, -v157, vcc
	v_mov_b32_e32 v152, v125
	s_and_b64 s[0:1], s[6:7], exec
	v_add_f32_e32 v190, v154, v155
	v_pk_mul_f32 v[154:155], v[152:153], v[166:167]
	v_cndmask_b32_e64 v167, v158, -v158, vcc
	v_mov_b32_e32 v152, v127
	v_cndmask_b32_e64 v160, 0, v175, s[4:5]
	s_cselect_b32 s0, 0xffffffc0, 0
	v_ldexp_f32 v180, v150, v156
	v_add_f32_e32 v191, v154, v155
	v_pk_mul_f32 v[154:155], v[152:153], v[166:167]
	v_ldexp_f32 v124, v161, s0
	v_mul_f32_e32 v161, v126, v166
	v_ldexp_f32 v150, v159, v160
	v_mul_f32_e32 v181, v163, v180
	v_add_f32_e32 v193, v154, v155
	global_load_dword v188, v[148:149], off
	global_load_dword v157, v[146:147], off
	ds_bpermute_b32 v127, v177, v121
	v_mov_b32_e32 v156, v121
	ds_bpermute_b32 v121, v177, v123
	ds_bpermute_b32 v125, v177, v120
	ds_bpermute_b32 v152, v177, v122
	s_waitcnt lgkmcnt(3)
	v_cndmask_b32_e64 v189, v127, -v127, vcc
	s_waitcnt lgkmcnt(1)
	v_cndmask_b32_e64 v158, v125, -v125, vcc
	s_waitcnt lgkmcnt(0)
	v_cndmask_b32_e64 v127, v152, -v152, vcc
	s_waitcnt vmcnt(1)
	v_mul_f32_e32 v159, v120, v188
	s_waitcnt vmcnt(0)
	v_pk_mul_f32 v[154:155], v[156:157], v[188:189]
	v_cndmask_b32_e64 v189, v121, -v121, vcc
	v_mov_b32_e32 v156, v123
	v_add_f32_e32 v121, v154, v155
	v_pk_mul_f32 v[154:155], v[156:157], v[188:189]
	s_nop 0
	v_add_f32_e32 v123, v154, v155
	v_mov_b32_e32 v125, v153
	v_pk_mul_f32 v[152:153], v[124:125], v[150:151]
	v_mov_b32_e32 v125, v161
	v_pk_mul_f32 v[154:155], v[124:125], v[152:153]
	v_mov_b32_e32 v125, v157
	v_mov_b32_e32 v155, v158
	v_pk_mul_f32 v[156:157], v[124:125], v[154:155]
	v_mov_b32_e32 v158, v124
	v_pk_mul_f32 v[158:159], v[158:159], v[156:157]
	v_mul_f32_e32 v167, v163, v181
	v_mov_b32_e32 v159, v127
	v_mul_f32_e32 v183, v163, v167
	v_pk_mul_f32 v[160:161], v[124:125], v[158:159]
	v_mul_f32_e32 v182, v163, v183
	v_mul_f32_e32 v151, v124, v160
	v_mul_f32_e32 v185, v163, v182
	v_mul_f32_e32 v155, v124, v151
	v_mul_f32_e32 v124, v180, v190
	v_mul_f32_e32 v125, v181, v191
	v_fma_f32 v153, v126, v166, v153
	v_mul_f32_e32 v184, v163, v185
	v_cvt_pk_bf16_f32 v124, v124, v125
	v_mul_f32_e32 v125, v167, v153
	v_mul_f32_e32 v126, v183, v193
	v_fma_f32 v120, v120, v188, v157
	v_mul_f32_e32 v159, v163, v184
	v_cvt_pk_bf16_f32 v125, v125, v126
	v_mul_f32_e32 v126, v182, v120
	v_mul_f32_e32 v127, v185, v121
	v_fma_f32 v122, v122, v188, v161
	v_cvt_pk_bf16_f32 v126, v126, v127
	v_mul_f32_e32 v127, v184, v122
	v_mul_f32_e32 v157, v159, v123
	v_cvt_pk_bf16_f32 v127, v127, v157
	v_mul_f32_e32 v157, v150, v190
	v_mul_f32_e32 v120, v158, v120
	v_mul_f32_e32 v121, v160, v121
	v_mul_f32_e32 v161, v152, v191
	v_cvt_pk_bf16_f32 v188, v157, v161
	v_mul_f32_e32 v153, v154, v153
	v_mul_f32_e32 v157, v156, v193
	v_cvt_pk_bf16_f32 v189, v153, v157
	v_cvt_pk_bf16_f32 v190, v120, v121
	v_mul_f32_e32 v120, v151, v122
	v_mul_f32_e32 v121, v155, v123
	v_cvt_pk_bf16_f32 v191, v120, v121
	v_lshlrev_b64 v[120:121], 17, v[164:165]
	v_lshl_add_u64 v[120:121], s[80:81], 0, v[120:121]
	v_ashrrev_i32_e32 v163, 31, v162
	v_lshl_add_u64 v[120:121], v[162:163], 1, v[120:121]
	s_mov_b64 s[0:1], 0x2000000
	global_store_dwordx4 v[120:121], v[124:127], off
	s_nop 1
	v_lshl_add_u64 v[126:127], v[120:121], 0, s[0:1]
	s_brev_b32 s0, 64
	v_add_co_u32_e64 v122, s[4:5], s0, v120
	s_nop 1
	v_addc_co_u32_e64 v123, s[4:5], 0, v121, s[4:5]
	global_store_dwordx4 v[122:123], v[188:191], off
	v_add_u32_e32 v122, 0x80, v162
	v_lshrrev_b32_e32 v122, 2, v122
	v_and_b32_e32 v153, 0x1f0, v122
	v_add_u32_e32 v122, v153, v192
	v_add_u32_e32 v124, v153, v136
	v_ashrrev_i32_e32 v123, 31, v122
	v_ashrrev_i32_e32 v125, 31, v124
	v_lshl_add_u64 v[122:123], v[122:123], 2, s[16:17]
	v_lshl_add_u64 v[124:125], v[124:125], 2, s[16:17]
	global_load_dword v163, v[122:123], off
	global_load_dword v164, v[124:125], off
	ds_bpermute_b32 v157, v177, v116
	v_mov_b32_e32 v162, v116
	ds_bpermute_b32 v116, v177, v117
	ds_bpermute_b32 v161, v177, v118
	ds_bpermute_b32 v166, v177, v119
	s_waitcnt lgkmcnt(3)
;     __device__ __forceinline__ void operator()(const AccT& acc, const Unit& u, int wr, int wc, int fr, int fq) const {
;     ...
;                 const int r = rbase + ai * 128 + m * 16;
;                 const int d = 4 * (2 * m + (fr >> 3)) + j;
; #pragma unroll
;                 for (int bj = 0; bj < 2; ++bj) {
;                     const int t0 = tb + bj * 128;
;                     float v[8];
; #pragma unroll
;                     for (int jj = 0; jj < 4; ++jj) { v[jj] = acc[ai][bj][m][0][jj]; v[4 + jj] = acc[ai][bj][m][1][jj]; }
;                     if constexpr (ROPE) {
;                         const int t = t0 & 2047;
; #pragma unroll
;                         for (int hf = 0; hf < 2; ++hf) {
;                             f32x4 cs, sn;
;                             if (m < 2) { const float c1 = ropeA[(t >> 6) * 16 + d], s1 = ropeA[1024 + (t >> 6) * 16 + d]; cs = (f32x4){c1, c1, c1, c1}; sn = (f32x4){s1, s1, s1, s1}; }
;                             else { const float* cb = ropeA + 2048 + (d - 16) * 64 + (t & 63) + 4 * hf; cs = *(const f32x4*)(cb); sn = *(const f32x4*)(cb + 1024); }
; #pragma unroll
;                             for (int jj = 0; jj < 4; ++jj) { const float pr = __shfl_xor(v[4 * hf + jj], 4); v[4 * hf + jj] = v[4 * hf + jj] * cs[jj] + sgn * pr * sn[jj]; }
;                             __builtin_amdgcn_sched_barrier(0);
;                         }
;                     }
;                     float zf[8], zb[8]; zf[0] = zf0; zb[0] = zb0;
; #pragma unroll
;                     for (int jj = 1; jj < 8; ++jj) { zf[jj] = zf[jj - 1] * zfs; zb[jj] = zb[jj - 1] * zbs; }
;                     u32x4 wf, wb;
;                     wf.x = cvt_pk_bf16(v[0] * zf[0], v[1] * zf[1]); wf.y = cvt_pk_bf16(v[2] * zf[2], v[3] * zf[3]); wf.z = cvt_pk_bf16(v[4] * zf[4], v[5] * zf[5]); wf.w = cvt_pk_bf16(v[6] * zf[6], v[7] * zf[7]);
;                     wb.x = cvt_pk_bf16(v[0] * zb[0], v[1] * zb[1]); wb.y = cvt_pk_bf16(v[2] * zb[2], v[3] * zb[3]); wb.z = cvt_pk_bf16(v[4] * zb[4], v[5] * zb[5]); wb.w = cvt_pk_bf16(v[6] * zb[6], v[7] * zb[7]);
;                     *(u32x4*)(KTZ + (size_t)r * NT + t0) = wf;
;                     *(u32x4*)(KTZ + (size_t)(256 + r) * NT + t0) = wb;
;                     __builtin_amdgcn_sched_barrier(0);
	v_cndmask_b32_e64 v165, v157, -v157, vcc
	s_waitcnt vmcnt(0)
	v_pk_mul_f32 v[188:189], v[162:163], v[164:165]
	s_waitcnt lgkmcnt(2)
	v_cndmask_b32_e64 v165, v116, -v116, vcc
	v_mov_b32_e32 v162, v117
	v_pk_mul_f32 v[116:117], v[162:163], v[164:165]
	s_waitcnt lgkmcnt(1)
	v_cndmask_b32_e64 v165, v161, -v161, vcc
	v_mov_b32_e32 v162, v118
	v_add_f32_e32 v161, v116, v117
	v_pk_mul_f32 v[116:117], v[162:163], v[164:165]
	s_waitcnt lgkmcnt(0)
	v_cndmask_b32_e64 v165, v166, -v166, vcc
	v_mov_b32_e32 v162, v119
	v_add_f32_e32 v166, v116, v117
	v_pk_mul_f32 v[116:117], v[162:163], v[164:165]
	v_add_f32_e32 v157, v188, v189
	v_add_f32_e32 v164, v116, v117
	global_load_dword v117, v[122:123], off
	global_load_dword v118, v[124:125], off
	ds_bpermute_b32 v119, v177, v112
	v_mov_b32_e32 v116, v112
	ds_bpermute_b32 v112, v177, v113
	ds_bpermute_b32 v165, v177, v114
	ds_bpermute_b32 v188, v177, v115
	s_waitcnt lgkmcnt(3)
	v_cndmask_b32_e64 v119, v119, -v119, vcc
	s_waitcnt vmcnt(0)
	v_pk_mul_f32 v[162:163], v[116:117], v[118:119]
	s_waitcnt lgkmcnt(2)
	v_cndmask_b32_e64 v119, v112, -v112, vcc
	v_mov_b32_e32 v116, v113
	v_pk_mul_f32 v[112:113], v[116:117], v[118:119]
	s_waitcnt lgkmcnt(1)
	v_cndmask_b32_e64 v119, v165, -v165, vcc
	v_mov_b32_e32 v116, v114
	v_add_f32_e32 v162, v162, v163
	v_add_f32_e32 v163, v112, v113
	v_pk_mul_f32 v[112:113], v[116:117], v[118:119]
	s_waitcnt lgkmcnt(0)
	v_cndmask_b32_e64 v119, v188, -v188, vcc
	v_mov_b32_e32 v116, v115
	v_add_f32_e32 v165, v112, v113
	v_pk_mul_f32 v[112:113], v[116:117], v[118:119]
	s_nop 0
	v_add_f32_e32 v119, v112, v113
	v_mul_f32_e32 v112, v180, v157
	v_mul_f32_e32 v113, v181, v161
	v_cvt_pk_bf16_f32 v112, v112, v113
	v_mul_f32_e32 v113, v167, v166
	v_mul_f32_e32 v114, v183, v164
	v_cvt_pk_bf16_f32 v113, v113, v114
	v_mul_f32_e32 v114, v182, v162
	v_mul_f32_e32 v115, v185, v163
	v_cvt_pk_bf16_f32 v114, v114, v115
	v_mul_f32_e32 v115, v184, v165
	v_mul_f32_e32 v116, v159, v119
	v_cvt_pk_bf16_f32 v115, v115, v116
	v_mul_f32_e32 v116, v150, v157
	v_mul_f32_e32 v117, v152, v161
	v_cvt_pk_bf16_f32 v116, v116, v117
	v_mul_f32_e32 v117, v154, v166
	v_mul_f32_e32 v118, v156, v164
	v_cvt_pk_bf16_f32 v117, v117, v118
	v_mul_f32_e32 v118, v158, v162
	v_mul_f32_e32 v157, v160, v163
	v_mul_f32_e32 v119, v155, v119
	v_cvt_pk_bf16_f32 v118, v118, v157
	v_mul_f32_e32 v157, v151, v165
	v_cvt_pk_bf16_f32 v119, v157, v119
	global_store_dwordx4 v[120:121], v[112:115], off offset:256
	global_store_dwordx4 v[126:127], v[116:119], off offset:256
	v_add_u32_e32 v161, 0x408, v136
	v_add_u32_e32 v157, 8, v136
	v_add_u32_e32 v112, v161, v187
	v_add_u32_e32 v114, v187, v157
	v_ashrrev_i32_e32 v113, 31, v112
	v_ashrrev_i32_e32 v115, 31, v114
	v_lshl_add_u64 v[112:113], v[112:113], 2, s[16:17]
	v_lshl_add_u64 v[114:115], v[114:115], 2, s[16:17]
	global_load_dword v117, v[112:113], off
	global_load_dword v118, v[114:115], off
	ds_bpermute_b32 v119, v177, v108
	v_mov_b32_e32 v116, v108
	ds_bpermute_b32 v108, v177, v109
	ds_bpermute_b32 v162, v177, v110
	ds_bpermute_b32 v163, v177, v111
	s_waitcnt lgkmcnt(3)
	v_cndmask_b32_e64 v119, v119, -v119, vcc
	s_waitcnt vmcnt(0)
	v_pk_mul_f32 v[126:127], v[116:117], v[118:119]
	s_waitcnt lgkmcnt(2)
	v_cndmask_b32_e64 v119, v108, -v108, vcc
	v_mov_b32_e32 v116, v109
	v_pk_mul_f32 v[108:109], v[116:117], v[118:119]
	s_waitcnt lgkmcnt(1)
	v_cndmask_b32_e64 v119, v162, -v162, vcc
	v_mov_b32_e32 v116, v110
	v_add_f32_e32 v126, v126, v127
	v_add_f32_e32 v127, v108, v109
	v_pk_mul_f32 v[108:109], v[116:117], v[118:119]
	s_waitcnt lgkmcnt(0)
	v_cndmask_b32_e64 v119, v163, -v163, vcc
	v_mov_b32_e32 v116, v111
	v_add_f32_e32 v162, v108, v109
	v_pk_mul_f32 v[108:109], v[116:117], v[118:119]
	s_nop 0
	v_add_f32_e32 v118, v108, v109
	global_load_dword v109, v[112:113], off
	global_load_dword v110, v[114:115], off
	ds_bpermute_b32 v111, v177, v104
	v_mov_b32_e32 v108, v104
	ds_bpermute_b32 v104, v177, v105
	ds_bpermute_b32 v119, v177, v106
	ds_bpermute_b32 v163, v177, v107
	s_waitcnt lgkmcnt(3)
	v_cndmask_b32_e64 v111, v111, -v111, vcc
	s_waitcnt vmcnt(0)
	v_pk_mul_f32 v[116:117], v[108:109], v[110:111]
	s_waitcnt lgkmcnt(2)
	v_cndmask_b32_e64 v111, v104, -v104, vcc
	v_mov_b32_e32 v108, v105
	v_pk_mul_f32 v[104:105], v[108:109], v[110:111]
	s_waitcnt lgkmcnt(1)
	v_cndmask_b32_e64 v111, v119, -v119, vcc
	v_mov_b32_e32 v108, v106
	v_add_f32_e32 v119, v104, v105
	v_pk_mul_f32 v[104:105], v[108:109], v[110:111]
	s_waitcnt lgkmcnt(0)
	v_cndmask_b32_e64 v111, v163, -v163, vcc
	v_mov_b32_e32 v108, v107
	v_add_f32_e32 v163, v104, v105
	v_pk_mul_f32 v[104:105], v[108:109], v[110:111]
	v_add_f32_e32 v164, v116, v117
	v_add_f32_e32 v108, v104, v105
	v_mul_f32_e32 v104, v180, v126
	v_mul_f32_e32 v105, v181, v127
	v_cvt_pk_bf16_f32 v104, v104, v105
	v_mul_f32_e32 v105, v167, v162
	v_mul_f32_e32 v106, v183, v118
	v_cvt_pk_bf16_f32 v105, v105, v106
	v_mul_f32_e32 v106, v182, v164
	v_mul_f32_e32 v107, v185, v119
	v_cvt_pk_bf16_f32 v106, v106, v107
	v_mul_f32_e32 v107, v184, v163
	v_mul_f32_e32 v109, v159, v108
	v_cvt_pk_bf16_f32 v107, v107, v109
	v_mul_f32_e32 v109, v150, v126
	v_mul_f32_e32 v110, v152, v127
	v_cvt_pk_bf16_f32 v116, v109, v110
	v_mul_f32_e32 v109, v154, v162
	v_mul_f32_e32 v110, v156, v118
	v_cvt_pk_bf16_f32 v117, v109, v110
	v_mul_f32_e32 v109, v158, v164
	v_mul_f32_e32 v110, v160, v119
	v_cvt_pk_bf16_f32 v118, v109, v110
	v_mul_f32_e32 v109, v151, v163
	v_mul_f32_e32 v108, v155, v108
	s_mov_b64 s[0:1], 0x200000
	v_cvt_pk_bf16_f32 v119, v109, v108
	v_lshl_add_u64 v[108:109], v[120:121], 0, s[0:1]
	s_mov_b32 s0, 0x200000
	v_add_co_u32_e64 v110, s[4:5], s0, v120
	s_mov_b64 s[0:1], 0x2200000
	s_nop 0
	v_addc_co_u32_e64 v111, s[4:5], 0, v121, s[4:5]
	global_store_dwordx4 v[110:111], v[104:107], off
	v_lshl_add_u64 v[110:111], v[120:121], 0, s[0:1]
	s_mov_b32 s0, 0x2200000
	v_add_co_u32_e64 v104, s[4:5], s0, v120
	s_nop 1
	v_addc_co_u32_e64 v105, s[4:5], 0, v121, s[4:5]
	global_store_dwordx4 v[104:105], v[116:119], off
	v_add_u32_e32 v104, v153, v161
	v_add_u32_e32 v106, v153, v157
	v_ashrrev_i32_e32 v105, 31, v104
	v_ashrrev_i32_e32 v107, 31, v106
	v_lshl_add_u64 v[104:105], v[104:105], 2, s[16:17]
	v_lshl_add_u64 v[106:107], v[106:107], 2, s[16:17]
	global_load_dword v117, v[104:105], off
	global_load_dword v118, v[106:107], off
	ds_bpermute_b32 v119, v177, v100
	v_mov_b32_e32 v116, v100
	ds_bpermute_b32 v100, v177, v101
	ds_bpermute_b32 v153, v177, v102
	ds_bpermute_b32 v157, v177, v103
	s_waitcnt lgkmcnt(3)
; __device__ __forceinline__ unsigned cvt_pk_bf16(float lo, float hi) { unsigned r; asm volatile("v_cvt_pk_bf16_f32 %0, %1, %2" : "=v"(r) : "v"(lo), "v"(hi)); return r; }
;     __device__ __forceinline__ void operator()(const AccT& acc, const Unit& u, int wr, int wc, int fr, int fq) const {
;     ...
;                 for (int bj = 0; bj < 2; ++bj) {
;                     const int t0 = tb + bj * 128;
;                     float v[8];
; #pragma unroll
;                     for (int jj = 0; jj < 4; ++jj) { v[jj] = acc[ai][bj][m][0][jj]; v[4 + jj] = acc[ai][bj][m][1][jj]; }
;                     if constexpr (ROPE) {
;                         const int t = t0 & 2047;
; #pragma unroll
;                         for (int hf = 0; hf < 2; ++hf) {
;                             f32x4 cs, sn;
;                             if (m < 2) { const float c1 = ropeA[(t >> 6) * 16 + d], s1 = ropeA[1024 + (t >> 6) * 16 + d]; cs = (f32x4){c1, c1, c1, c1}; sn = (f32x4){s1, s1, s1, s1}; }
;                             else { const float* cb = ropeA + 2048 + (d - 16) * 64 + (t & 63) + 4 * hf; cs = *(const f32x4*)(cb); sn = *(const f32x4*)(cb + 1024); }
; #pragma unroll
;                             for (int jj = 0; jj < 4; ++jj) { const float pr = __shfl_xor(v[4 * hf + jj], 4); v[4 * hf + jj] = v[4 * hf + jj] * cs[jj] + sgn * pr * sn[jj]; }
;                             __builtin_amdgcn_sched_barrier(0);
;                         }
;                     }
;                     float zf[8], zb[8]; zf[0] = zf0; zb[0] = zb0;
; #pragma unroll
;                     for (int jj = 1; jj < 8; ++jj) { zf[jj] = zf[jj - 1] * zfs; zb[jj] = zb[jj - 1] * zbs; }
;                     u32x4 wf, wb;
;                     wf.x = cvt_pk_bf16(v[0] * zf[0], v[1] * zf[1]); wf.y = cvt_pk_bf16(v[2] * zf[2], v[3] * zf[3]); wf.z = cvt_pk_bf16(v[4] * zf[4], v[5] * zf[5]); wf.w = cvt_pk_bf16(v[6] * zf[6], v[7] * zf[7]);
;                     wb.x = cvt_pk_bf16(v[0] * zb[0], v[1] * zb[1]); wb.y = cvt_pk_bf16(v[2] * zb[2], v[3] * zb[3]); wb.z = cvt_pk_bf16(v[4] * zb[4], v[5] * zb[5]); wb.w = cvt_pk_bf16(v[6] * zb[6], v[7] * zb[7]);
;                     *(u32x4*)(KTZ + (size_t)r * NT + t0) = wf;
;                     *(u32x4*)(KTZ + (size_t)(256 + r) * NT + t0) = wb;
	v_cndmask_b32_e64 v119, v119, -v119, vcc
	s_waitcnt vmcnt(0)
	v_pk_mul_f32 v[126:127], v[116:117], v[118:119]
	s_waitcnt lgkmcnt(2)
	v_cndmask_b32_e64 v119, v100, -v100, vcc
	v_mov_b32_e32 v116, v101
	v_pk_mul_f32 v[100:101], v[116:117], v[118:119]
	s_waitcnt lgkmcnt(1)
	v_cndmask_b32_e64 v119, v153, -v153, vcc
	v_mov_b32_e32 v116, v102
	v_add_f32_e32 v126, v126, v127
	v_add_f32_e32 v127, v100, v101
	v_pk_mul_f32 v[100:101], v[116:117], v[118:119]
	s_waitcnt lgkmcnt(0)
	v_cndmask_b32_e64 v119, v157, -v157, vcc
	v_mov_b32_e32 v116, v103
	v_add_f32_e32 v153, v100, v101
	v_pk_mul_f32 v[100:101], v[116:117], v[118:119]
	s_nop 0
	v_add_f32_e32 v118, v100, v101
	global_load_dword v101, v[104:105], off
	global_load_dword v102, v[106:107], off
	ds_bpermute_b32 v103, v177, v96
	v_mov_b32_e32 v100, v96
	ds_bpermute_b32 v96, v177, v97
	ds_bpermute_b32 v119, v177, v98
	ds_bpermute_b32 v157, v177, v99
	s_waitcnt lgkmcnt(3)
	v_cndmask_b32_e64 v103, v103, -v103, vcc
	s_waitcnt vmcnt(0)
	v_pk_mul_f32 v[116:117], v[100:101], v[102:103]
	s_waitcnt lgkmcnt(2)
	v_cndmask_b32_e64 v103, v96, -v96, vcc
	v_mov_b32_e32 v100, v97
	v_pk_mul_f32 v[96:97], v[100:101], v[102:103]
	s_waitcnt lgkmcnt(1)
	v_cndmask_b32_e64 v103, v119, -v119, vcc
	v_mov_b32_e32 v100, v98
	v_add_f32_e32 v116, v116, v117
	v_add_f32_e32 v117, v96, v97
	v_pk_mul_f32 v[96:97], v[100:101], v[102:103]
	s_waitcnt lgkmcnt(0)
	v_cndmask_b32_e64 v103, v157, -v157, vcc
	v_mov_b32_e32 v100, v99
	v_add_f32_e32 v119, v96, v97
	v_pk_mul_f32 v[96:97], v[100:101], v[102:103]
	s_nop 0
	v_add_f32_e32 v103, v96, v97
	v_mul_f32_e32 v96, v180, v126
	v_mul_f32_e32 v97, v181, v127
	v_cvt_pk_bf16_f32 v96, v96, v97
	v_mul_f32_e32 v97, v167, v153
	v_mul_f32_e32 v98, v183, v118
	v_cvt_pk_bf16_f32 v97, v97, v98
	v_mul_f32_e32 v98, v182, v116
	v_mul_f32_e32 v99, v185, v117
	v_cvt_pk_bf16_f32 v98, v98, v99
	v_mul_f32_e32 v99, v184, v119
	v_mul_f32_e32 v100, v159, v103
	v_cvt_pk_bf16_f32 v99, v99, v100
	v_mul_f32_e32 v100, v150, v126
	v_mul_f32_e32 v101, v152, v127
	v_cvt_pk_bf16_f32 v100, v100, v101
	v_mul_f32_e32 v101, v154, v153
	v_mul_f32_e32 v102, v156, v118
	v_cvt_pk_bf16_f32 v101, v101, v102
	v_mul_f32_e32 v102, v158, v116
	v_mul_f32_e32 v116, v160, v117
	v_mul_f32_e32 v103, v155, v103
	v_cvt_pk_bf16_f32 v102, v102, v116
	v_mul_f32_e32 v116, v151, v119
	v_cvt_pk_bf16_f32 v103, v116, v103
	global_store_dwordx4 v[108:109], v[96:99], off offset:256
	global_store_dwordx4 v[110:111], v[100:103], off offset:256
	s_nop 1
	v_lshlrev_b32_e32 v100, 6, v136
	v_ashrrev_i32_e32 v101, 31, v100
	v_lshlrev_b64 v[102:103], 2, v[100:101]
	v_lshl_add_u64 v[96:97], s[24:25], 0, v[102:103]
	v_lshlrev_b32_e32 v136, 2, v186
	v_lshl_add_u64 v[96:97], v[96:97], 0, v[136:137]
	v_add_co_u32_e64 v98, s[4:5], s61, v96
	ds_bpermute_b32 v101, v177, v92
	s_nop 0
	v_addc_co_u32_e64 v99, s[4:5], 0, v97, s[4:5]
	global_load_dwordx4 v[108:111], v[98:99], off
	global_load_dwordx4 v[116:119], v[96:97], off
	ds_bpermute_b32 v127, v177, v93
	ds_bpermute_b32 v153, v177, v94
	ds_bpermute_b32 v157, v177, v95
	v_mov_b32_e32 v126, v92
	v_mov_b32_e32 v92, v94
	s_waitcnt lgkmcnt(3)
	v_cndmask_b32_e64 v163, v101, -v101, vcc
	s_waitcnt lgkmcnt(2)
	v_cndmask_b32_e64 v165, v127, -v127, vcc
	s_waitcnt lgkmcnt(1)
	v_cndmask_b32_e64 v187, v153, -v153, vcc
	s_waitcnt lgkmcnt(0)
	v_cndmask_b32_e64 v189, v157, -v157, vcc
	s_waitcnt vmcnt(1)
	v_mov_b32_e32 v127, v108
	s_waitcnt vmcnt(0)
	v_mov_b32_e32 v162, v116
	v_mov_b32_e32 v108, v93
	v_mov_b32_e32 v164, v117
	v_mov_b32_e32 v93, v110
	v_mov_b32_e32 v186, v118
	v_mov_b32_e32 v110, v95
	v_mov_b32_e32 v188, v119
	v_pk_mul_f32 v[94:95], v[126:127], v[162:163]
	v_pk_mul_f32 v[108:109], v[108:109], v[164:165]
	v_pk_mul_f32 v[92:93], v[92:93], v[186:187]
	v_pk_mul_f32 v[110:111], v[110:111], v[188:189]
	v_add_f32_e32 v101, v94, v95
	v_add_f32_e32 v153, v108, v109
	v_add_f32_e32 v157, v92, v93
	v_add_f32_e32 v161, v110, v111
	v_lshl_add_u64 v[92:93], s[16:17], 0, v[102:103]
	v_lshl_add_u64 v[94:95], v[92:93], 0, v[136:137]
	v_add_co_u32_e64 v92, s[4:5], s62, v94
	ds_bpermute_b32 v103, v177, v88
	s_nop 0
	v_addc_co_u32_e64 v93, s[4:5], 0, v95, s[4:5]
	v_add_co_u32_e64 v94, s[4:5], s49, v94
	ds_bpermute_b32 v126, v177, v89
	s_nop 0
	v_addc_co_u32_e64 v95, s[4:5], 0, v95, s[4:5]
	global_load_dwordx4 v[108:111], v[92:93], off offset:16
	global_load_dwordx4 v[116:119], v[94:95], off offset:16
	ds_bpermute_b32 v162, v177, v90
	ds_bpermute_b32 v164, v177, v91
	v_mov_b32_e32 v102, v88
	v_mov_b32_e32 v88, v90
	s_waitcnt lgkmcnt(3)
	v_cndmask_b32_e64 v127, v103, -v103, vcc
	s_waitcnt lgkmcnt(2)
	v_cndmask_b32_e64 v163, v126, -v126, vcc
	s_waitcnt lgkmcnt(1)
	v_cndmask_b32_e64 v165, v162, -v162, vcc
	s_waitcnt lgkmcnt(0)
	v_cndmask_b32_e64 v187, v164, -v164, vcc
	s_waitcnt vmcnt(1)
	v_mov_b32_e32 v103, v108
	s_waitcnt vmcnt(0)
; __device__ __forceinline__ unsigned cvt_pk_bf16(float lo, float hi) { unsigned r; asm volatile("v_cvt_pk_bf16_f32 %0, %1, %2" : "=v"(r) : "v"(lo), "v"(hi)); return r; }
;     __device__ __forceinline__ void operator()(const AccT& acc, const Unit& u, int wr, int wc, int fr, int fq) const {
;     ...
;                 for (int bj = 0; bj < 2; ++bj) {
;                     const int t0 = tb + bj * 128;
;                     float v[8];
; #pragma unroll
;                     for (int jj = 0; jj < 4; ++jj) { v[jj] = acc[ai][bj][m][0][jj]; v[4 + jj] = acc[ai][bj][m][1][jj]; }
;                     if constexpr (ROPE) {
;                         const int t = t0 & 2047;
; #pragma unroll
;                         for (int hf = 0; hf < 2; ++hf) {
;                             f32x4 cs, sn;
;                             if (m < 2) { const float c1 = ropeA[(t >> 6) * 16 + d], s1 = ropeA[1024 + (t >> 6) * 16 + d]; cs = (f32x4){c1, c1, c1, c1}; sn = (f32x4){s1, s1, s1, s1}; }
;                             else { const float* cb = ropeA + 2048 + (d - 16) * 64 + (t & 63) + 4 * hf; cs = *(const f32x4*)(cb); sn = *(const f32x4*)(cb + 1024); }
; #pragma unroll
;                             for (int jj = 0; jj < 4; ++jj) { const float pr = __shfl_xor(v[4 * hf + jj], 4); v[4 * hf + jj] = v[4 * hf + jj] * cs[jj] + sgn * pr * sn[jj]; }
;                             __builtin_amdgcn_sched_barrier(0);
;                         }
;                     }
;                     float zf[8], zb[8]; zf[0] = zf0; zb[0] = zb0;
; #pragma unroll
;                     for (int jj = 1; jj < 8; ++jj) { zf[jj] = zf[jj - 1] * zfs; zb[jj] = zb[jj - 1] * zbs; }
;                     u32x4 wf, wb;
;                     wf.x = cvt_pk_bf16(v[0] * zf[0], v[1] * zf[1]); wf.y = cvt_pk_bf16(v[2] * zf[2], v[3] * zf[3]); wf.z = cvt_pk_bf16(v[4] * zf[4], v[5] * zf[5]); wf.w = cvt_pk_bf16(v[6] * zf[6], v[7] * zf[7]);
;                     wb.x = cvt_pk_bf16(v[0] * zb[0], v[1] * zb[1]); wb.y = cvt_pk_bf16(v[2] * zb[2], v[3] * zb[3]); wb.z = cvt_pk_bf16(v[4] * zb[4], v[5] * zb[5]); wb.w = cvt_pk_bf16(v[6] * zb[6], v[7] * zb[7]);
;                     *(u32x4*)(KTZ + (size_t)r * NT + t0) = wf;
;                     *(u32x4*)(KTZ + (size_t)(256 + r) * NT + t0) = wb;
	v_mov_b32_e32 v126, v116
	v_mov_b32_e32 v108, v89
	v_mov_b32_e32 v162, v117
	v_mov_b32_e32 v89, v110
	v_mov_b32_e32 v164, v118
	v_mov_b32_e32 v110, v91
	v_mov_b32_e32 v186, v119
	v_pk_mul_f32 v[90:91], v[102:103], v[126:127]
	v_pk_mul_f32 v[102:103], v[108:109], v[162:163]
	v_pk_mul_f32 v[88:89], v[88:89], v[164:165]
	v_pk_mul_f32 v[108:109], v[110:111], v[186:187]
	v_add_f32_e32 v90, v90, v91
	v_add_f32_e32 v91, v102, v103
	v_add_f32_e32 v88, v88, v89
	v_add_f32_e32 v89, v108, v109
	v_mul_f32_e32 v102, v180, v101
	v_mul_f32_e32 v103, v181, v153
	v_cvt_pk_bf16_f32 v108, v102, v103
	v_mul_f32_e32 v102, v167, v157
	v_mul_f32_e32 v103, v183, v161
	v_cvt_pk_bf16_f32 v109, v102, v103
	v_mul_f32_e32 v102, v182, v90
	v_mul_f32_e32 v103, v185, v91
	v_cvt_pk_bf16_f32 v110, v102, v103
	v_mul_f32_e32 v102, v184, v88
	v_mul_f32_e32 v103, v159, v89
	v_cvt_pk_bf16_f32 v111, v102, v103
	v_mul_f32_e32 v101, v150, v101
	v_mul_f32_e32 v102, v152, v153
	v_mul_f32_e32 v88, v151, v88
	v_mul_f32_e32 v89, v155, v89
	s_mov_b64 s[0:1], 0x400000
	v_cvt_pk_bf16_f32 v116, v101, v102
	v_mul_f32_e32 v101, v154, v157
	v_mul_f32_e32 v102, v156, v161
	v_cvt_pk_bf16_f32 v117, v101, v102
	v_mul_f32_e32 v90, v158, v90
	v_mul_f32_e32 v91, v160, v91
	v_cvt_pk_bf16_f32 v118, v90, v91
	v_cvt_pk_bf16_f32 v119, v88, v89
	v_lshl_add_u64 v[88:89], v[120:121], 0, s[0:1]
	s_mov_b32 s0, 0x400000
	v_add_co_u32_e64 v90, s[4:5], s0, v120
	s_mov_b64 s[0:1], 0x2400000
	s_nop 0
	v_addc_co_u32_e64 v91, s[4:5], 0, v121, s[4:5]
	global_store_dwordx4 v[90:91], v[108:111], off
	v_lshl_add_u64 v[90:91], v[120:121], 0, s[0:1]
	s_mov_b32 s0, 0x2400000
	v_add_co_u32_e64 v102, s[4:5], s0, v120
	s_nop 1
	v_addc_co_u32_e64 v103, s[4:5], 0, v121, s[4:5]
	global_store_dwordx4 v[102:103], v[116:119], off
	global_load_dwordx4 v[108:111], v[98:99], off
	s_nop 0
	global_load_dwordx4 v[116:119], v[96:97], off
	ds_bpermute_b32 v101, v177, v84
	ds_bpermute_b32 v103, v177, v85
	ds_bpermute_b32 v126, v177, v86
	ds_bpermute_b32 v153, v177, v87
	v_mov_b32_e32 v102, v84
	v_mov_b32_e32 v84, v86
	s_waitcnt lgkmcnt(3)
	v_cndmask_b32_e64 v127, v101, -v101, vcc
	s_waitcnt lgkmcnt(2)
	v_cndmask_b32_e64 v163, v103, -v103, vcc
	s_waitcnt lgkmcnt(1)
	v_cndmask_b32_e64 v165, v126, -v126, vcc
	s_waitcnt lgkmcnt(0)
	v_cndmask_b32_e64 v187, v153, -v153, vcc
	s_waitcnt vmcnt(1)
	v_mov_b32_e32 v103, v108
	s_waitcnt vmcnt(0)
	v_mov_b32_e32 v126, v116
	v_mov_b32_e32 v108, v85
	v_mov_b32_e32 v162, v117
	v_mov_b32_e32 v85, v110
	v_mov_b32_e32 v164, v118
	v_mov_b32_e32 v110, v87
	v_mov_b32_e32 v186, v119
	v_pk_mul_f32 v[86:87], v[102:103], v[126:127]
	v_pk_mul_f32 v[102:103], v[108:109], v[162:163]
	v_pk_mul_f32 v[84:85], v[84:85], v[164:165]
	v_pk_mul_f32 v[108:109], v[110:111], v[186:187]
	v_add_f32_e32 v101, v86, v87
	v_add_f32_e32 v153, v102, v103
	v_add_f32_e32 v157, v84, v85
	v_add_f32_e32 v161, v108, v109
	global_load_dwordx4 v[84:87], v[92:93], off offset:16
	global_load_dwordx4 v[108:111], v[94:95], off offset:16
	ds_bpermute_b32 v103, v177, v80
	ds_bpermute_b32 v116, v177, v81
	ds_bpermute_b32 v118, v177, v82
	ds_bpermute_b32 v126, v177, v83
	v_mov_b32_e32 v102, v80
	v_mov_b32_e32 v80, v82
	s_waitcnt lgkmcnt(3)
	v_cndmask_b32_e64 v117, v103, -v103, vcc
	s_waitcnt lgkmcnt(2)
	v_cndmask_b32_e64 v119, v116, -v116, vcc
	s_waitcnt lgkmcnt(1)
	v_cndmask_b32_e64 v127, v118, -v118, vcc
	s_waitcnt lgkmcnt(0)
	v_cndmask_b32_e64 v163, v126, -v126, vcc
	s_waitcnt vmcnt(1)
	v_mov_b32_e32 v103, v84
	s_waitcnt vmcnt(0)
	v_mov_b32_e32 v116, v108
	v_mov_b32_e32 v84, v81
	v_mov_b32_e32 v118, v109
	v_mov_b32_e32 v81, v86
	v_mov_b32_e32 v126, v110
	v_mov_b32_e32 v86, v83
	v_mov_b32_e32 v162, v111
	v_pk_mul_f32 v[82:83], v[102:103], v[116:117]
	v_pk_mul_f32 v[84:85], v[84:85], v[118:119]
	v_pk_mul_f32 v[80:81], v[80:81], v[126:127]
	v_pk_mul_f32 v[86:87], v[86:87], v[162:163]
	v_add_f32_e32 v102, v82, v83
	v_add_f32_e32 v103, v84, v85
	v_add_f32_e32 v108, v80, v81
	v_add_f32_e32 v87, v86, v87
	v_mul_f32_e32 v80, v180, v101
	v_mul_f32_e32 v81, v181, v153
	v_cvt_pk_bf16_f32 v80, v80, v81
	v_mul_f32_e32 v81, v167, v157
	v_mul_f32_e32 v82, v183, v161
	v_cvt_pk_bf16_f32 v81, v81, v82
	v_mul_f32_e32 v82, v182, v102
	v_mul_f32_e32 v83, v185, v103
	v_cvt_pk_bf16_f32 v82, v82, v83
	v_mul_f32_e32 v83, v184, v108
	v_mul_f32_e32 v84, v159, v87
	v_cvt_pk_bf16_f32 v83, v83, v84
	v_mul_f32_e32 v84, v150, v101
	v_mul_f32_e32 v85, v152, v153
	v_cvt_pk_bf16_f32 v84, v84, v85
	v_mul_f32_e32 v85, v154, v157
	v_mul_f32_e32 v86, v156, v161
	v_cvt_pk_bf16_f32 v85, v85, v86
	v_mul_f32_e32 v86, v158, v102
	v_mul_f32_e32 v101, v160, v103
	v_mul_f32_e32 v87, v155, v87
	v_cvt_pk_bf16_f32 v86, v86, v101
	v_mul_f32_e32 v101, v151, v108
	v_cvt_pk_bf16_f32 v87, v101, v87
	global_store_dwordx4 v[88:89], v[80:83], off offset:256
	global_store_dwordx4 v[90:91], v[84:87], off offset:256
	s_nop 0
	v_add_u32_e32 v80, 0x200, v100
	v_ashrrev_i32_e32 v81, 31, v80
	v_lshl_add_u64 v[82:83], s[24:25], 0, v[136:137]
	v_lshlrev_b64 v[100:101], 2, v[80:81]
	v_lshl_add_u64 v[80:81], v[82:83], 0, v[100:101]
	v_add_co_u32_e64 v82, s[4:5], s61, v80
	ds_bpermute_b32 v103, v177, v76
	s_nop 0
	v_addc_co_u32_e64 v83, s[4:5], 0, v81, s[4:5]
	global_load_dwordx4 v[84:87], v[82:83], off
	global_load_dwordx4 v[88:91], v[80:81], off
	ds_bpermute_b32 v108, v177, v77
	ds_bpermute_b32 v110, v177, v78
	ds_bpermute_b32 v116, v177, v79
	v_mov_b32_e32 v102, v76
	v_mov_b32_e32 v76, v78
	s_waitcnt lgkmcnt(3)
	v_cndmask_b32_e64 v109, v103, -v103, vcc
	s_waitcnt lgkmcnt(2)
	v_cndmask_b32_e64 v111, v108, -v108, vcc
	s_waitcnt lgkmcnt(1)
	v_cndmask_b32_e64 v117, v110, -v110, vcc
	s_waitcnt lgkmcnt(0)
; __device__ __forceinline__ unsigned cvt_pk_bf16(float lo, float hi) { unsigned r; asm volatile("v_cvt_pk_bf16_f32 %0, %1, %2" : "=v"(r) : "v"(lo), "v"(hi)); return r; }
;     __device__ __forceinline__ void operator()(const AccT& acc, const Unit& u, int wr, int wc, int fr, int fq) const {
;     ...
;                 for (int bj = 0; bj < 2; ++bj) {
;                     const int t0 = tb + bj * 128;
;                     float v[8];
; #pragma unroll
;                     for (int jj = 0; jj < 4; ++jj) { v[jj] = acc[ai][bj][m][0][jj]; v[4 + jj] = acc[ai][bj][m][1][jj]; }
;                     if constexpr (ROPE) {
;                         const int t = t0 & 2047;
; #pragma unroll
;                         for (int hf = 0; hf < 2; ++hf) {
;                             f32x4 cs, sn;
;                             if (m < 2) { const float c1 = ropeA[(t >> 6) * 16 + d], s1 = ropeA[1024 + (t >> 6) * 16 + d]; cs = (f32x4){c1, c1, c1, c1}; sn = (f32x4){s1, s1, s1, s1}; }
;                             else { const float* cb = ropeA + 2048 + (d - 16) * 64 + (t & 63) + 4 * hf; cs = *(const f32x4*)(cb); sn = *(const f32x4*)(cb + 1024); }
; #pragma unroll
;                             for (int jj = 0; jj < 4; ++jj) { const float pr = __shfl_xor(v[4 * hf + jj], 4); v[4 * hf + jj] = v[4 * hf + jj] * cs[jj] + sgn * pr * sn[jj]; }
;                             __builtin_amdgcn_sched_barrier(0);
;                         }
;                     }
;                     float zf[8], zb[8]; zf[0] = zf0; zb[0] = zb0;
; #pragma unroll
;                     for (int jj = 1; jj < 8; ++jj) { zf[jj] = zf[jj - 1] * zfs; zb[jj] = zb[jj - 1] * zbs; }
;                     u32x4 wf, wb;
;                     wf.x = cvt_pk_bf16(v[0] * zf[0], v[1] * zf[1]); wf.y = cvt_pk_bf16(v[2] * zf[2], v[3] * zf[3]); wf.z = cvt_pk_bf16(v[4] * zf[4], v[5] * zf[5]); wf.w = cvt_pk_bf16(v[6] * zf[6], v[7] * zf[7]);
;                     wb.x = cvt_pk_bf16(v[0] * zb[0], v[1] * zb[1]); wb.y = cvt_pk_bf16(v[2] * zb[2], v[3] * zb[3]); wb.z = cvt_pk_bf16(v[4] * zb[4], v[5] * zb[5]); wb.w = cvt_pk_bf16(v[6] * zb[6], v[7] * zb[7]);
;                     *(u32x4*)(KTZ + (size_t)r * NT + t0) = wf;
;                     *(u32x4*)(KTZ + (size_t)(256 + r) * NT + t0) = wb;
	v_cndmask_b32_e64 v119, v116, -v116, vcc
	s_waitcnt vmcnt(1)
	v_mov_b32_e32 v103, v84
	s_waitcnt vmcnt(0)
	v_mov_b32_e32 v108, v88
	v_mov_b32_e32 v84, v77
	v_mov_b32_e32 v110, v89
	v_mov_b32_e32 v77, v86
	v_mov_b32_e32 v116, v90
	v_mov_b32_e32 v86, v79
	v_mov_b32_e32 v118, v91
	v_pk_mul_f32 v[78:79], v[102:103], v[108:109]
	v_pk_mul_f32 v[84:85], v[84:85], v[110:111]
	v_pk_mul_f32 v[76:77], v[76:77], v[116:117]
	v_pk_mul_f32 v[86:87], v[86:87], v[118:119]
	v_add_f32_e32 v118, v78, v79
	v_add_f32_e32 v119, v84, v85
	v_add_f32_e32 v126, v76, v77
	v_add_f32_e32 v127, v86, v87
	v_lshl_add_u64 v[76:77], s[16:17], 0, v[100:101]
	v_lshl_add_u64 v[78:79], v[76:77], 0, v[136:137]
	v_add_co_u32_e64 v76, s[4:5], s62, v78
	ds_bpermute_b32 v101, v177, v72
	s_nop 0
	v_addc_co_u32_e64 v77, s[4:5], 0, v79, s[4:5]
	v_add_co_u32_e64 v78, s[4:5], s49, v78
	ds_bpermute_b32 v102, v177, v73
	s_nop 0
	v_addc_co_u32_e64 v79, s[4:5], 0, v79, s[4:5]
	global_load_dwordx4 v[84:87], v[76:77], off offset:16
	global_load_dwordx4 v[88:91], v[78:79], off offset:16
	ds_bpermute_b32 v108, v177, v74
	ds_bpermute_b32 v110, v177, v75
	v_mov_b32_e32 v100, v72
	v_mov_b32_e32 v72, v74
	s_waitcnt lgkmcnt(3)
	v_cndmask_b32_e64 v103, v101, -v101, vcc
	s_waitcnt lgkmcnt(2)
	v_cndmask_b32_e64 v109, v102, -v102, vcc
	s_waitcnt lgkmcnt(1)
	v_cndmask_b32_e64 v111, v108, -v108, vcc
	s_waitcnt lgkmcnt(0)
	v_cndmask_b32_e64 v117, v110, -v110, vcc
	s_waitcnt vmcnt(1)
	v_mov_b32_e32 v101, v84
	s_waitcnt vmcnt(0)
	v_mov_b32_e32 v102, v88
	v_mov_b32_e32 v84, v73
	v_mov_b32_e32 v108, v89
	v_mov_b32_e32 v73, v86
	v_mov_b32_e32 v110, v90
	v_mov_b32_e32 v86, v75
	v_mov_b32_e32 v116, v91
	v_pk_mul_f32 v[74:75], v[100:101], v[102:103]
	v_pk_mul_f32 v[84:85], v[84:85], v[108:109]
	v_pk_mul_f32 v[72:73], v[72:73], v[110:111]
	v_pk_mul_f32 v[86:87], v[86:87], v[116:117]
	v_add_f32_e32 v74, v74, v75
	v_add_f32_e32 v75, v84, v85
	v_add_f32_e32 v72, v72, v73
	v_add_f32_e32 v73, v86, v87
	v_mul_f32_e32 v84, v180, v118
	v_mul_f32_e32 v85, v181, v119
	v_cvt_pk_bf16_f32 v84, v84, v85
	v_mul_f32_e32 v85, v167, v126
	v_mul_f32_e32 v86, v183, v127
	v_cvt_pk_bf16_f32 v85, v85, v86
	v_mul_f32_e32 v86, v182, v74
	v_mul_f32_e32 v87, v185, v75
	v_cvt_pk_bf16_f32 v86, v86, v87
	v_mul_f32_e32 v87, v184, v72
	v_mul_f32_e32 v88, v159, v73
	v_cvt_pk_bf16_f32 v87, v87, v88
	v_mul_f32_e32 v88, v150, v118
	v_mul_f32_e32 v89, v152, v119
	v_cvt_pk_bf16_f32 v88, v88, v89
	v_mul_f32_e32 v89, v154, v126
	v_mul_f32_e32 v90, v156, v127
	v_mul_f32_e32 v72, v151, v72
	v_mul_f32_e32 v73, v155, v73
	s_mov_b64 s[0:1], 0x600000
	v_cvt_pk_bf16_f32 v89, v89, v90
	v_mul_f32_e32 v74, v158, v74
	v_mul_f32_e32 v75, v160, v75
	v_cvt_pk_bf16_f32 v90, v74, v75
	v_cvt_pk_bf16_f32 v91, v72, v73
	v_lshl_add_u64 v[72:73], v[120:121], 0, s[0:1]
	s_mov_b32 s0, 0x600000
	v_add_co_u32_e64 v74, s[4:5], s0, v120
	s_mov_b64 s[0:1], 0x2600000
	s_nop 0
	v_addc_co_u32_e64 v75, s[4:5], 0, v121, s[4:5]
	global_store_dwordx4 v[74:75], v[84:87], off
	v_lshl_add_u64 v[74:75], v[120:121], 0, s[0:1]
	s_mov_b32 s0, 0x2600000
	v_add_co_u32_e64 v84, s[4:5], s0, v120
	s_nop 1
	v_addc_co_u32_e64 v85, s[4:5], 0, v121, s[4:5]
	global_store_dwordx4 v[84:85], v[88:91], off
	global_load_dwordx4 v[84:87], v[82:83], off
	s_nop 0
	global_load_dwordx4 v[88:91], v[80:81], off
	ds_bpermute_b32 v101, v177, v68
	ds_bpermute_b32 v102, v177, v69
	ds_bpermute_b32 v108, v177, v70
	ds_bpermute_b32 v110, v177, v71
	v_mov_b32_e32 v100, v68
	v_mov_b32_e32 v68, v70
	s_waitcnt lgkmcnt(3)
	v_cndmask_b32_e64 v103, v101, -v101, vcc
	s_waitcnt lgkmcnt(2)
	v_cndmask_b32_e64 v109, v102, -v102, vcc
	s_waitcnt lgkmcnt(1)
	v_cndmask_b32_e64 v111, v108, -v108, vcc
	s_waitcnt lgkmcnt(0)
	v_cndmask_b32_e64 v117, v110, -v110, vcc
	s_waitcnt vmcnt(1)
	v_mov_b32_e32 v101, v84
	s_waitcnt vmcnt(0)
	v_mov_b32_e32 v102, v88
	v_mov_b32_e32 v84, v69
	v_mov_b32_e32 v108, v89
	v_mov_b32_e32 v69, v86
	v_mov_b32_e32 v110, v90
	v_mov_b32_e32 v86, v71
	v_mov_b32_e32 v116, v91
	v_pk_mul_f32 v[70:71], v[100:101], v[102:103]
	v_pk_mul_f32 v[84:85], v[84:85], v[108:109]
	v_pk_mul_f32 v[68:69], v[68:69], v[110:111]
	v_pk_mul_f32 v[86:87], v[86:87], v[116:117]
	v_add_f32_e32 v110, v70, v71
	v_add_f32_e32 v111, v84, v85
	v_add_f32_e32 v116, v68, v69
	v_add_f32_e32 v117, v86, v87
	global_load_dwordx4 v[68:71], v[76:77], off offset:16
	global_load_dwordx4 v[84:87], v[78:79], off offset:16
	ds_bpermute_b32 v89, v177, v64
	ds_bpermute_b32 v90, v177, v65
	ds_bpermute_b32 v100, v177, v66
	ds_bpermute_b32 v102, v177, v67
	v_mov_b32_e32 v88, v64
	v_mov_b32_e32 v64, v66
	s_waitcnt lgkmcnt(3)
	v_cndmask_b32_e64 v91, v89, -v89, vcc
	s_waitcnt lgkmcnt(2)
	v_cndmask_b32_e64 v101, v90, -v90, vcc
	s_waitcnt lgkmcnt(1)
	v_cndmask_b32_e64 v103, v100, -v100, vcc
	s_waitcnt lgkmcnt(0)
	v_cndmask_b32_e64 v109, v102, -v102, vcc
	s_waitcnt vmcnt(1)
	v_mov_b32_e32 v89, v68
	s_waitcnt vmcnt(0)
;     __device__ __forceinline__ void operator()(const AccT& acc, const Unit& u, int wr, int wc, int fr, int fq) const {
;     ...
;         for (int ai = 0; ai < 2; ++ai) {
;             const int hh = 2 * ai + wr;
;             const float l2f = lgd[hh] * 1.4426950408889634f, l2b = lgd[4 + hh] * 1.4426950408889634f;
;             const float zf0 = exp2f((float)(127 - o0) * l2f), zfs = exp2f(-l2f), zb0 = exp2f((float)o0 * l2b), zbs = exp2f(l2b);
; #pragma unroll
;             for (int m = 0; m < 4; ++m) {
;                 const int r = rbase + ai * 128 + m * 16;
;                 const int d = 4 * (2 * m + (fr >> 3)) + j;
; #pragma unroll
;                 for (int bj = 0; bj < 2; ++bj) {
;                     const int t0 = tb + bj * 128;
;                     float v[8];
; #pragma unroll
;                     for (int jj = 0; jj < 4; ++jj) { v[jj] = acc[ai][bj][m][0][jj]; v[4 + jj] = acc[ai][bj][m][1][jj]; }
;                     if constexpr (ROPE) {
;                         const int t = t0 & 2047;
; #pragma unroll
;                         for (int hf = 0; hf < 2; ++hf) {
;                             f32x4 cs, sn;
;                             if (m < 2) { const float c1 = ropeA[(t >> 6) * 16 + d], s1 = ropeA[1024 + (t >> 6) * 16 + d]; cs = (f32x4){c1, c1, c1, c1}; sn = (f32x4){s1, s1, s1, s1}; }
;                             else { const float* cb = ropeA + 2048 + (d - 16) * 64 + (t & 63) + 4 * hf; cs = *(const f32x4*)(cb); sn = *(const f32x4*)(cb + 1024); }
; #pragma unroll
;                             for (int jj = 0; jj < 4; ++jj) { const float pr = __shfl_xor(v[4 * hf + jj], 4); v[4 * hf + jj] = v[4 * hf + jj] * cs[jj] + sgn * pr * sn[jj]; }
;                             __builtin_amdgcn_sched_barrier(0);
;                         }
;                     }
;                     float zf[8], zb[8]; zf[0] = zf0; zb[0] = zb0;
; #pragma unroll
;                     for (int jj = 1; jj < 8; ++jj) { zf[jj] = zf[jj - 1] * zfs; zb[jj] = zb[jj - 1] * zbs; }
;                     u32x4 wf, wb;
;                     wf.x = cvt_pk_bf16(v[0] * zf[0], v[1] * zf[1]); wf.y = cvt_pk_bf16(v[2] * zf[2], v[3] * zf[3]); wf.z = cvt_pk_bf16(v[4] * zf[4], v[5] * zf[5]); wf.w = cvt_pk_bf16(v[6] * zf[6], v[7] * zf[7]);
	v_mov_b32_e32 v90, v84
	v_mov_b32_e32 v68, v65
	v_mov_b32_e32 v100, v85
	v_mov_b32_e32 v65, v70
	v_mov_b32_e32 v102, v86
	v_mov_b32_e32 v70, v67
	v_mov_b32_e32 v108, v87
	v_pk_mul_f32 v[66:67], v[88:89], v[90:91]
	v_pk_mul_f32 v[68:69], v[68:69], v[100:101]
	v_pk_mul_f32 v[64:65], v[64:65], v[102:103]
	v_pk_mul_f32 v[70:71], v[70:71], v[108:109]
	v_add_f32_e32 v84, v66, v67
	v_add_f32_e32 v85, v68, v69
	v_add_f32_e32 v86, v64, v65
	v_add_f32_e32 v71, v70, v71
	v_mul_f32_e32 v64, v180, v110
	v_mul_f32_e32 v65, v181, v111
	v_cvt_pk_bf16_f32 v64, v64, v65
	v_mul_f32_e32 v65, v167, v116
	v_mul_f32_e32 v66, v183, v117
	v_cvt_pk_bf16_f32 v65, v65, v66
	v_mul_f32_e32 v66, v182, v84
	v_mul_f32_e32 v67, v185, v85
	v_cvt_pk_bf16_f32 v66, v66, v67
	v_mul_f32_e32 v67, v184, v86
	v_mul_f32_e32 v68, v159, v71
	v_cvt_pk_bf16_f32 v67, v67, v68
	v_mul_f32_e32 v68, v150, v110
	v_mul_f32_e32 v69, v152, v111
	v_cvt_pk_bf16_f32 v68, v68, v69
	v_mul_f32_e32 v69, v154, v116
	v_mul_f32_e32 v70, v156, v117
	v_cvt_pk_bf16_f32 v69, v69, v70
	v_mul_f32_e32 v70, v158, v84
	v_mul_f32_e32 v84, v160, v85
	v_mul_f32_e32 v71, v155, v71
	v_cvt_pk_bf16_f32 v70, v70, v84
	v_mul_f32_e32 v84, v151, v86
	v_cvt_pk_bf16_f32 v71, v84, v71
	global_store_dwordx4 v[72:73], v[64:67], off offset:256
	global_store_dwordx4 v[74:75], v[68:71], off offset:256
	global_load_dword v64, v137, s[22:23] offset:8
	s_nop 0
	global_load_dword v70, v137, s[22:23] offset:24
	global_load_dword v67, v[146:147], off
	global_load_dword v74, v[148:149], off
	ds_bpermute_b32 v65, v177, v60
	ds_bpermute_b32 v68, v177, v62
	v_mov_b32_e32 v66, v60
	ds_bpermute_b32 v60, v177, v61
	ds_bpermute_b32 v71, v177, v63
	s_waitcnt lgkmcnt(3)
	v_cndmask_b32_e64 v75, v65, -v65, vcc
	s_waitcnt lgkmcnt(2)
	v_cndmask_b32_e64 v65, v68, -v68, vcc
	s_waitcnt vmcnt(3)
	v_mul_f32_e32 v72, 0x3fb8aa3b, v64
	s_waitcnt vmcnt(2)
	v_mul_f32_e32 v73, 0x3fb8aa3b, v70
	v_mul_f32_e32 v84, v72, v179
	s_waitcnt vmcnt(0)
	v_pk_mul_f32 v[68:69], v[66:67], v[74:75]
	s_waitcnt lgkmcnt(1)
	v_cndmask_b32_e64 v75, v60, -v60, vcc
	v_mov_b32_e32 v66, v61
	v_cmp_lt_f32_e64 s[4:5], s60, v72
	v_mul_f32_e32 v87, v73, v178
	v_pk_mul_f32 v[60:61], v[66:67], v[74:75]
	s_waitcnt lgkmcnt(0)
	v_cndmask_b32_e64 v75, v71, -v71, vcc
	v_mov_b32_e32 v66, v63
	v_cmp_gt_f32_e64 s[8:9], s59, v84
	v_cndmask_b32_e64 v86, 0, v176, s[4:5]
	v_cmp_gt_f32_e64 s[6:7], s59, v73
	s_and_b64 s[0:1], s[4:5], exec
	v_cmp_gt_f32_e64 s[4:5], s59, v87
	v_add_f32_e32 v110, v60, v61
	v_pk_mul_f32 v[60:61], v[66:67], v[74:75]
	v_cndmask_b32_e64 v66, 0, v176, s[8:9]
	v_cndmask_b32_e64 v88, 0, v176, s[6:7]
	v_add_f32_e32 v89, v68, v69
	v_fmac_f32_e32 v86, 0xbfb8aa3b, v64
	v_cndmask_b32_e64 v69, 0, v176, s[4:5]
	v_fmac_f32_e32 v66, v72, v179
	v_fmac_f32_e32 v88, 0x3fb8aa3b, v70
	v_exp_f32_e32 v68, v86
	v_fmac_f32_e32 v69, v73, v178
	v_exp_f32_e32 v66, v66
	v_exp_f32_e32 v70, v88
	v_exp_f32_e32 v69, v69
	v_cndmask_b32_e64 v63, 0, v175, s[8:9]
	s_cselect_b32 s8, 0xffffffc0, 0
	s_and_b64 s[0:1], s[6:7], exec
	v_cndmask_b32_e64 v64, 0, v175, s[4:5]
	s_cselect_b32 s0, 0xffffffc0, 0
	v_ldexp_f32 v100, v68, s8
	v_ldexp_f32 v63, v66, v63
	v_mul_f32_e32 v85, v62, v74
	v_ldexp_f32 v90, v70, s0
	v_ldexp_f32 v64, v69, v64
	v_mul_f32_e32 v75, v100, v63
	v_add_f32_e32 v111, v60, v61
	global_load_dword v108, v[148:149], off
	global_load_dword v69, v[146:147], off
	ds_bpermute_b32 v61, v177, v57
	ds_bpermute_b32 v60, v177, v56
	v_mov_b32_e32 v68, v57
	ds_bpermute_b32 v57, v177, v59
	ds_bpermute_b32 v66, v177, v58
	s_waitcnt lgkmcnt(3)
	v_cndmask_b32_e64 v109, v61, -v61, vcc
	s_waitcnt lgkmcnt(2)
	v_cndmask_b32_e64 v70, v60, -v60, vcc
	s_waitcnt lgkmcnt(0)
	v_cndmask_b32_e64 v72, v66, -v66, vcc
	s_waitcnt vmcnt(1)
	v_mul_f32_e32 v71, v56, v108
	s_waitcnt vmcnt(0)
	v_pk_mul_f32 v[60:61], v[68:69], v[108:109]
	v_cndmask_b32_e64 v109, v57, -v57, vcc
	v_mov_b32_e32 v68, v59
	v_add_f32_e32 v57, v60, v61
	v_pk_mul_f32 v[60:61], v[68:69], v[108:109]
	s_nop 0
	v_add_f32_e32 v59, v60, v61
	v_mov_b32_e32 v91, v67
	v_pk_mul_f32 v[60:61], v[90:91], v[64:65]
	v_mov_b32_e32 v91, v85
	v_pk_mul_f32 v[66:67], v[90:91], v[60:61]
	v_mov_b32_e32 v91, v69
	v_mov_b32_e32 v67, v70
	v_mul_f32_e32 v84, v100, v75
	v_pk_mul_f32 v[68:69], v[90:91], v[66:67]
	v_mov_b32_e32 v70, v90
	v_mul_f32_e32 v86, v100, v84
	v_pk_mul_f32 v[70:71], v[70:71], v[68:69]
	v_mul_f32_e32 v85, v100, v86
	v_mov_b32_e32 v71, v72
	v_mul_f32_e32 v88, v100, v85
	v_pk_mul_f32 v[72:73], v[90:91], v[70:71]
	v_fma_f32 v61, v62, v74, v61
	v_mul_f32_e32 v87, v100, v88
	v_mul_f32_e32 v65, v90, v72
	v_mul_f32_e32 v62, v84, v61
	v_fma_f32 v56, v56, v108, v69
	v_mul_f32_e32 v71, v100, v87
	v_mul_f32_e32 v67, v90, v65
	v_mul_f32_e32 v90, v63, v89
	v_mul_f32_e32 v91, v75, v110
	v_cvt_pk_bf16_f32 v100, v90, v91
	v_mul_f32_e32 v74, v86, v111
	v_cvt_pk_bf16_f32 v101, v62, v74
	v_mul_f32_e32 v62, v85, v56
	v_fma_f32 v58, v58, v108, v73
	v_mul_f32_e32 v69, v88, v57
	v_cvt_pk_bf16_f32 v102, v62, v69
	v_mul_f32_e32 v62, v87, v58
	v_mul_f32_e32 v69, v71, v59
	v_cvt_pk_bf16_f32 v103, v62, v69
	v_mul_f32_e32 v62, v64, v89
	v_mul_f32_e32 v56, v70, v56
	v_mul_f32_e32 v57, v72, v57
	v_mul_f32_e32 v69, v60, v110
	v_cvt_pk_bf16_f32 v108, v62, v69
	v_mul_f32_e32 v61, v66, v61
	v_mul_f32_e32 v62, v68, v111
	v_cvt_pk_bf16_f32 v109, v61, v62
	v_cvt_pk_bf16_f32 v110, v56, v57
	v_mul_f32_e32 v56, v65, v58
	v_mul_f32_e32 v57, v67, v59
	s_mov_b64 s[0:1], 0x1000000
	v_cvt_pk_bf16_f32 v111, v56, v57
	v_lshl_add_u64 v[56:57], v[120:121], 0, s[0:1]
	s_mov_b32 s0, 0x1000000
	v_add_co_u32_e64 v58, s[4:5], s0, v120
	s_mov_b64 s[0:1], 0x3000000
	s_nop 0
	v_addc_co_u32_e64 v59, s[4:5], 0, v121, s[4:5]
	global_store_dwordx4 v[58:59], v[100:103], off
	v_lshl_add_u64 v[58:59], v[120:121], 0, s[0:1]
	s_mov_b32 s0, 0x3000000
	v_add_co_u32_e64 v90, s[4:5], s0, v120
	s_nop 1
	v_addc_co_u32_e64 v91, s[4:5], 0, v121, s[4:5]
	global_store_dwordx4 v[90:91], v[108:111], off
	global_load_dword v91, v[122:123], off
	s_nop 0
	global_load_dword v100, v[124:125], off
	ds_bpermute_b32 v61, v177, v52
	v_mov_b32_e32 v90, v52
	ds_bpermute_b32 v52, v177, v53
	ds_bpermute_b32 v62, v177, v54
	ds_bpermute_b32 v69, v177, v55
	s_waitcnt lgkmcnt(3)
; __device__ __forceinline__ unsigned cvt_pk_bf16(float lo, float hi) { unsigned r; asm volatile("v_cvt_pk_bf16_f32 %0, %1, %2" : "=v"(r) : "v"(lo), "v"(hi)); return r; }
;     __device__ __forceinline__ void operator()(const AccT& acc, const Unit& u, int wr, int wc, int fr, int fq) const {
;     ...
;                 for (int bj = 0; bj < 2; ++bj) {
;                     const int t0 = tb + bj * 128;
;                     float v[8];
; #pragma unroll
;                     for (int jj = 0; jj < 4; ++jj) { v[jj] = acc[ai][bj][m][0][jj]; v[4 + jj] = acc[ai][bj][m][1][jj]; }
;                     if constexpr (ROPE) {
;                         const int t = t0 & 2047;
; #pragma unroll
;                         for (int hf = 0; hf < 2; ++hf) {
;                             f32x4 cs, sn;
;                             if (m < 2) { const float c1 = ropeA[(t >> 6) * 16 + d], s1 = ropeA[1024 + (t >> 6) * 16 + d]; cs = (f32x4){c1, c1, c1, c1}; sn = (f32x4){s1, s1, s1, s1}; }
;                             else { const float* cb = ropeA + 2048 + (d - 16) * 64 + (t & 63) + 4 * hf; cs = *(const f32x4*)(cb); sn = *(const f32x4*)(cb + 1024); }
; #pragma unroll
;                             for (int jj = 0; jj < 4; ++jj) { const float pr = __shfl_xor(v[4 * hf + jj], 4); v[4 * hf + jj] = v[4 * hf + jj] * cs[jj] + sgn * pr * sn[jj]; }
;                             __builtin_amdgcn_sched_barrier(0);
;                         }
;                     }
;                     float zf[8], zb[8]; zf[0] = zf0; zb[0] = zb0;
; #pragma unroll
;                     for (int jj = 1; jj < 8; ++jj) { zf[jj] = zf[jj - 1] * zfs; zb[jj] = zb[jj - 1] * zbs; }
;                     u32x4 wf, wb;
;                     wf.x = cvt_pk_bf16(v[0] * zf[0], v[1] * zf[1]); wf.y = cvt_pk_bf16(v[2] * zf[2], v[3] * zf[3]); wf.z = cvt_pk_bf16(v[4] * zf[4], v[5] * zf[5]); wf.w = cvt_pk_bf16(v[6] * zf[6], v[7] * zf[7]);
;                     wb.x = cvt_pk_bf16(v[0] * zb[0], v[1] * zb[1]); wb.y = cvt_pk_bf16(v[2] * zb[2], v[3] * zb[3]); wb.z = cvt_pk_bf16(v[4] * zb[4], v[5] * zb[5]); wb.w = cvt_pk_bf16(v[6] * zb[6], v[7] * zb[7]);
;                     *(u32x4*)(KTZ + (size_t)r * NT + t0) = wf;
;                     *(u32x4*)(KTZ + (size_t)(256 + r) * NT + t0) = wb;
	v_cndmask_b32_e64 v101, v61, -v61, vcc
	s_waitcnt vmcnt(0)
	v_pk_mul_f32 v[102:103], v[90:91], v[100:101]
	s_waitcnt lgkmcnt(2)
	v_cndmask_b32_e64 v101, v52, -v52, vcc
	v_mov_b32_e32 v90, v53
	v_pk_mul_f32 v[52:53], v[90:91], v[100:101]
	s_waitcnt lgkmcnt(1)
	v_cndmask_b32_e64 v101, v62, -v62, vcc
	v_mov_b32_e32 v90, v54
	v_add_f32_e32 v62, v52, v53
	v_pk_mul_f32 v[52:53], v[90:91], v[100:101]
	s_waitcnt lgkmcnt(0)
	v_cndmask_b32_e64 v101, v69, -v69, vcc
	v_mov_b32_e32 v90, v55
	v_add_f32_e32 v69, v52, v53
	v_pk_mul_f32 v[52:53], v[90:91], v[100:101]
	v_add_f32_e32 v61, v102, v103
	v_add_f32_e32 v73, v52, v53
	global_load_dword v53, v[122:123], off
	global_load_dword v54, v[124:125], off
	ds_bpermute_b32 v55, v177, v48
	v_mov_b32_e32 v52, v48
	ds_bpermute_b32 v48, v177, v49
	ds_bpermute_b32 v74, v177, v50
	ds_bpermute_b32 v89, v177, v51
	s_waitcnt lgkmcnt(3)
	v_cndmask_b32_e64 v55, v55, -v55, vcc
	s_waitcnt vmcnt(0)
	v_pk_mul_f32 v[90:91], v[52:53], v[54:55]
	s_waitcnt lgkmcnt(2)
	v_cndmask_b32_e64 v55, v48, -v48, vcc
	v_mov_b32_e32 v52, v49
	v_pk_mul_f32 v[48:49], v[52:53], v[54:55]
	s_waitcnt lgkmcnt(1)
	v_cndmask_b32_e64 v55, v74, -v74, vcc
	v_mov_b32_e32 v52, v50
	v_add_f32_e32 v74, v48, v49
	v_pk_mul_f32 v[48:49], v[52:53], v[54:55]
	s_waitcnt lgkmcnt(0)
	v_cndmask_b32_e64 v55, v89, -v89, vcc
	v_mov_b32_e32 v52, v51
	v_add_f32_e32 v89, v48, v49
	v_pk_mul_f32 v[48:49], v[52:53], v[54:55]
	v_add_f32_e32 v90, v90, v91
	v_add_f32_e32 v55, v48, v49
	v_mul_f32_e32 v48, v63, v61
	v_mul_f32_e32 v49, v75, v62
	v_cvt_pk_bf16_f32 v48, v48, v49
	v_mul_f32_e32 v49, v84, v69
	v_mul_f32_e32 v50, v86, v73
	v_cvt_pk_bf16_f32 v49, v49, v50
	v_mul_f32_e32 v50, v85, v90
	v_mul_f32_e32 v51, v88, v74
	v_cvt_pk_bf16_f32 v50, v50, v51
	v_mul_f32_e32 v51, v87, v89
	v_mul_f32_e32 v52, v71, v55
	v_cvt_pk_bf16_f32 v51, v51, v52
	v_mul_f32_e32 v52, v64, v61
	v_mul_f32_e32 v53, v60, v62
	v_cvt_pk_bf16_f32 v52, v52, v53
	v_mul_f32_e32 v53, v66, v69
	v_mul_f32_e32 v54, v68, v73
	v_cvt_pk_bf16_f32 v53, v53, v54
	v_mul_f32_e32 v54, v70, v90
	v_mul_f32_e32 v61, v72, v74
	v_mul_f32_e32 v55, v67, v55
	v_cvt_pk_bf16_f32 v54, v54, v61
	v_mul_f32_e32 v61, v65, v89
	v_cvt_pk_bf16_f32 v55, v61, v55
	global_store_dwordx4 v[56:57], v[48:51], off offset:256
	global_store_dwordx4 v[58:59], v[52:55], off offset:256
	global_load_dword v49, v[112:113], off
	s_nop 0
	global_load_dword v50, v[114:115], off
	ds_bpermute_b32 v51, v177, v44
	v_mov_b32_e32 v48, v44
	ds_bpermute_b32 v44, v177, v45
	ds_bpermute_b32 v54, v177, v46
	ds_bpermute_b32 v55, v177, v47
	s_waitcnt lgkmcnt(3)
	v_cndmask_b32_e64 v51, v51, -v51, vcc
	s_waitcnt vmcnt(0)
	v_pk_mul_f32 v[52:53], v[48:49], v[50:51]
	s_waitcnt lgkmcnt(2)
	v_cndmask_b32_e64 v51, v44, -v44, vcc
	v_mov_b32_e32 v48, v45
	v_pk_mul_f32 v[44:45], v[48:49], v[50:51]
	s_waitcnt lgkmcnt(1)
	v_cndmask_b32_e64 v51, v54, -v54, vcc
	v_mov_b32_e32 v48, v46
	v_add_f32_e32 v52, v52, v53
	v_add_f32_e32 v53, v44, v45
	v_pk_mul_f32 v[44:45], v[48:49], v[50:51]
	s_waitcnt lgkmcnt(0)
	v_cndmask_b32_e64 v51, v55, -v55, vcc
	v_mov_b32_e32 v48, v47
	v_add_f32_e32 v54, v44, v45
	v_pk_mul_f32 v[44:45], v[48:49], v[50:51]
	s_nop 0
	v_add_f32_e32 v50, v44, v45
	global_load_dword v45, v[112:113], off
	global_load_dword v46, v[114:115], off
	ds_bpermute_b32 v47, v177, v40
	v_mov_b32_e32 v44, v40
	ds_bpermute_b32 v40, v177, v41
	ds_bpermute_b32 v51, v177, v42
	ds_bpermute_b32 v55, v177, v43
	s_waitcnt lgkmcnt(3)
	v_cndmask_b32_e64 v47, v47, -v47, vcc
	s_waitcnt vmcnt(0)
	v_pk_mul_f32 v[48:49], v[44:45], v[46:47]
	s_waitcnt lgkmcnt(2)
	v_cndmask_b32_e64 v47, v40, -v40, vcc
	v_mov_b32_e32 v44, v41
	v_pk_mul_f32 v[40:41], v[44:45], v[46:47]
	s_waitcnt lgkmcnt(1)
	v_cndmask_b32_e64 v47, v51, -v51, vcc
	v_mov_b32_e32 v44, v42
	v_add_f32_e32 v48, v48, v49
	v_add_f32_e32 v49, v40, v41
	v_pk_mul_f32 v[40:41], v[44:45], v[46:47]
	s_waitcnt lgkmcnt(0)
	v_cndmask_b32_e64 v47, v55, -v55, vcc
	v_mov_b32_e32 v44, v43
	v_add_f32_e32 v51, v40, v41
	v_pk_mul_f32 v[40:41], v[44:45], v[46:47]
	s_nop 0
	v_add_f32_e32 v40, v40, v41
	v_mul_f32_e32 v41, v63, v52
	v_mul_f32_e32 v42, v75, v53
	v_cvt_pk_bf16_f32 v42, v41, v42
	v_mul_f32_e32 v41, v84, v54
	v_mul_f32_e32 v43, v86, v50
	v_cvt_pk_bf16_f32 v43, v41, v43
	v_mul_f32_e32 v41, v85, v48
	v_mul_f32_e32 v44, v88, v49
	v_cvt_pk_bf16_f32 v44, v41, v44
	v_mul_f32_e32 v41, v87, v51
	v_mul_f32_e32 v45, v71, v40
	v_cvt_pk_bf16_f32 v45, v41, v45
	v_mul_f32_e32 v41, v64, v52
	v_mul_f32_e32 v46, v60, v53
	v_cvt_pk_bf16_f32 v46, v41, v46
	v_mul_f32_e32 v41, v66, v54
	v_mul_f32_e32 v47, v68, v50
	v_cvt_pk_bf16_f32 v47, v41, v47
	v_mul_f32_e32 v41, v70, v48
	v_mul_f32_e32 v48, v72, v49
	v_cvt_pk_bf16_f32 v48, v41, v48
	v_mul_f32_e32 v41, v65, v51
	v_mul_f32_e32 v40, v67, v40
	s_mov_b64 s[0:1], 0x1200000
	v_cvt_pk_bf16_f32 v49, v41, v40
	v_lshl_add_u64 v[40:41], v[120:121], 0, s[0:1]
	s_mov_b32 s0, 0x1200000
	v_add_co_u32_e64 v50, s[4:5], s0, v120
	s_mov_b64 s[0:1], 0x3200000
	s_nop 0
	v_addc_co_u32_e64 v51, s[4:5], 0, v121, s[4:5]
	global_store_dwordx4 v[50:51], v[42:45], off
	s_nop 1
	v_lshl_add_u64 v[42:43], v[120:121], 0, s[0:1]
	s_mov_b32 s0, 0x3200000
	v_add_co_u32_e64 v44, s[4:5], s0, v120
	s_nop 1
	v_addc_co_u32_e64 v45, s[4:5], 0, v121, s[4:5]
	global_store_dwordx4 v[44:45], v[46:49], off
	global_load_dword v45, v[104:105], off
	s_nop 0
	global_load_dword v46, v[106:107], off
	ds_bpermute_b32 v47, v177, v36
	v_mov_b32_e32 v44, v36
	ds_bpermute_b32 v36, v177, v37
	ds_bpermute_b32 v50, v177, v38
	ds_bpermute_b32 v51, v177, v39
	s_waitcnt lgkmcnt(3)
	v_cndmask_b32_e64 v47, v47, -v47, vcc
	s_waitcnt vmcnt(0)
	v_pk_mul_f32 v[48:49], v[44:45], v[46:47]
	s_waitcnt lgkmcnt(2)
; __device__ __forceinline__ unsigned cvt_pk_bf16(float lo, float hi) { unsigned r; asm volatile("v_cvt_pk_bf16_f32 %0, %1, %2" : "=v"(r) : "v"(lo), "v"(hi)); return r; }
;     __device__ __forceinline__ void operator()(const AccT& acc, const Unit& u, int wr, int wc, int fr, int fq) const {
;     ...
;                 for (int bj = 0; bj < 2; ++bj) {
;                     const int t0 = tb + bj * 128;
;                     float v[8];
; #pragma unroll
;                     for (int jj = 0; jj < 4; ++jj) { v[jj] = acc[ai][bj][m][0][jj]; v[4 + jj] = acc[ai][bj][m][1][jj]; }
;                     if constexpr (ROPE) {
;                         const int t = t0 & 2047;
; #pragma unroll
;                         for (int hf = 0; hf < 2; ++hf) {
;                             f32x4 cs, sn;
;                             if (m < 2) { const float c1 = ropeA[(t >> 6) * 16 + d], s1 = ropeA[1024 + (t >> 6) * 16 + d]; cs = (f32x4){c1, c1, c1, c1}; sn = (f32x4){s1, s1, s1, s1}; }
;                             else { const float* cb = ropeA + 2048 + (d - 16) * 64 + (t & 63) + 4 * hf; cs = *(const f32x4*)(cb); sn = *(const f32x4*)(cb + 1024); }
; #pragma unroll
;                             for (int jj = 0; jj < 4; ++jj) { const float pr = __shfl_xor(v[4 * hf + jj], 4); v[4 * hf + jj] = v[4 * hf + jj] * cs[jj] + sgn * pr * sn[jj]; }
;                             __builtin_amdgcn_sched_barrier(0);
;                         }
;                     }
;                     float zf[8], zb[8]; zf[0] = zf0; zb[0] = zb0;
; #pragma unroll
;                     for (int jj = 1; jj < 8; ++jj) { zf[jj] = zf[jj - 1] * zfs; zb[jj] = zb[jj - 1] * zbs; }
;                     u32x4 wf, wb;
;                     wf.x = cvt_pk_bf16(v[0] * zf[0], v[1] * zf[1]); wf.y = cvt_pk_bf16(v[2] * zf[2], v[3] * zf[3]); wf.z = cvt_pk_bf16(v[4] * zf[4], v[5] * zf[5]); wf.w = cvt_pk_bf16(v[6] * zf[6], v[7] * zf[7]);
;                     wb.x = cvt_pk_bf16(v[0] * zb[0], v[1] * zb[1]); wb.y = cvt_pk_bf16(v[2] * zb[2], v[3] * zb[3]); wb.z = cvt_pk_bf16(v[4] * zb[4], v[5] * zb[5]); wb.w = cvt_pk_bf16(v[6] * zb[6], v[7] * zb[7]);
;                     *(u32x4*)(KTZ + (size_t)r * NT + t0) = wf;
;                     *(u32x4*)(KTZ + (size_t)(256 + r) * NT + t0) = wb;
	v_cndmask_b32_e64 v47, v36, -v36, vcc
	v_mov_b32_e32 v44, v37
	v_pk_mul_f32 v[36:37], v[44:45], v[46:47]
	s_waitcnt lgkmcnt(1)
	v_cndmask_b32_e64 v47, v50, -v50, vcc
	v_mov_b32_e32 v44, v38
	v_add_f32_e32 v48, v48, v49
	v_add_f32_e32 v49, v36, v37
	v_pk_mul_f32 v[36:37], v[44:45], v[46:47]
	s_waitcnt lgkmcnt(0)
	v_cndmask_b32_e64 v47, v51, -v51, vcc
	v_mov_b32_e32 v44, v39
	v_add_f32_e32 v50, v36, v37
	v_pk_mul_f32 v[36:37], v[44:45], v[46:47]
	s_nop 0
	v_add_f32_e32 v46, v36, v37
	global_load_dword v37, v[104:105], off
	global_load_dword v38, v[106:107], off
	ds_bpermute_b32 v39, v177, v32
	v_mov_b32_e32 v36, v32
	ds_bpermute_b32 v32, v177, v33
	ds_bpermute_b32 v47, v177, v34
	ds_bpermute_b32 v51, v177, v35
	s_waitcnt lgkmcnt(3)
	v_cndmask_b32_e64 v39, v39, -v39, vcc
	s_waitcnt vmcnt(0)
	v_pk_mul_f32 v[44:45], v[36:37], v[38:39]
	s_waitcnt lgkmcnt(2)
	v_cndmask_b32_e64 v39, v32, -v32, vcc
	v_mov_b32_e32 v36, v33
	v_pk_mul_f32 v[32:33], v[36:37], v[38:39]
	s_waitcnt lgkmcnt(1)
	v_cndmask_b32_e64 v39, v47, -v47, vcc
	v_mov_b32_e32 v36, v34
	v_add_f32_e32 v44, v44, v45
	v_add_f32_e32 v45, v32, v33
	v_pk_mul_f32 v[32:33], v[36:37], v[38:39]
	s_waitcnt lgkmcnt(0)
	v_cndmask_b32_e64 v39, v51, -v51, vcc
	v_mov_b32_e32 v36, v35
	v_add_f32_e32 v47, v32, v33
	v_pk_mul_f32 v[32:33], v[36:37], v[38:39]
	s_nop 0
	v_add_f32_e32 v39, v32, v33
	v_mul_f32_e32 v32, v63, v48
	v_mul_f32_e32 v33, v75, v49
	v_cvt_pk_bf16_f32 v32, v32, v33
	v_mul_f32_e32 v33, v84, v50
	v_mul_f32_e32 v34, v86, v46
	v_cvt_pk_bf16_f32 v33, v33, v34
	v_mul_f32_e32 v34, v85, v44
	v_mul_f32_e32 v35, v88, v45
	v_cvt_pk_bf16_f32 v34, v34, v35
	v_mul_f32_e32 v35, v87, v47
	v_mul_f32_e32 v36, v71, v39
	v_cvt_pk_bf16_f32 v35, v35, v36
	v_mul_f32_e32 v36, v64, v48
	v_mul_f32_e32 v37, v60, v49
	v_cvt_pk_bf16_f32 v36, v36, v37
	v_mul_f32_e32 v37, v66, v50
	v_mul_f32_e32 v38, v68, v46
	v_cvt_pk_bf16_f32 v37, v37, v38
	v_mul_f32_e32 v38, v70, v44
	v_mul_f32_e32 v44, v72, v45
	v_mul_f32_e32 v39, v67, v39
	v_cvt_pk_bf16_f32 v38, v38, v44
	v_mul_f32_e32 v44, v65, v47
	v_cvt_pk_bf16_f32 v39, v44, v39
	global_store_dwordx4 v[40:41], v[32:35], off offset:256
	global_store_dwordx4 v[42:43], v[36:39], off offset:256
	global_load_dwordx4 v[32:35], v[98:99], off
	s_nop 0
	global_load_dwordx4 v[36:39], v[96:97], off
	ds_bpermute_b32 v41, v177, v28
	ds_bpermute_b32 v42, v177, v29
	ds_bpermute_b32 v44, v177, v30
	ds_bpermute_b32 v46, v177, v31
	v_mov_b32_e32 v40, v28
	v_mov_b32_e32 v28, v30
	s_waitcnt lgkmcnt(3)
	v_cndmask_b32_e64 v43, v41, -v41, vcc
	s_waitcnt lgkmcnt(2)
	v_cndmask_b32_e64 v45, v42, -v42, vcc
	s_waitcnt lgkmcnt(1)
	v_cndmask_b32_e64 v47, v44, -v44, vcc
	s_waitcnt lgkmcnt(0)
	v_cndmask_b32_e64 v49, v46, -v46, vcc
	s_waitcnt vmcnt(1)
	v_mov_b32_e32 v41, v32
	s_waitcnt vmcnt(0)
	v_mov_b32_e32 v42, v36
	v_mov_b32_e32 v32, v29
	v_mov_b32_e32 v44, v37
	v_mov_b32_e32 v29, v34
	v_mov_b32_e32 v46, v38
	v_mov_b32_e32 v34, v31
	v_mov_b32_e32 v48, v39
	v_pk_mul_f32 v[30:31], v[40:41], v[42:43]
	v_pk_mul_f32 v[32:33], v[32:33], v[44:45]
	v_pk_mul_f32 v[28:29], v[28:29], v[46:47]
	v_pk_mul_f32 v[34:35], v[34:35], v[48:49]
	v_add_f32_e32 v46, v30, v31
	v_add_f32_e32 v47, v32, v33
	v_add_f32_e32 v48, v28, v29
	v_add_f32_e32 v49, v34, v35
	global_load_dwordx4 v[28:31], v[92:93], off offset:16
	global_load_dwordx4 v[32:35], v[94:95], off offset:16
	ds_bpermute_b32 v37, v177, v24
	ds_bpermute_b32 v38, v177, v25
	ds_bpermute_b32 v40, v177, v26
	ds_bpermute_b32 v42, v177, v27
	v_mov_b32_e32 v36, v24
	v_mov_b32_e32 v24, v26
	s_waitcnt lgkmcnt(3)
	v_cndmask_b32_e64 v39, v37, -v37, vcc
	s_waitcnt lgkmcnt(2)
	v_cndmask_b32_e64 v41, v38, -v38, vcc
	s_waitcnt lgkmcnt(1)
	v_cndmask_b32_e64 v43, v40, -v40, vcc
	s_waitcnt lgkmcnt(0)
	v_cndmask_b32_e64 v45, v42, -v42, vcc
	s_waitcnt vmcnt(1)
	v_mov_b32_e32 v37, v28
	s_waitcnt vmcnt(0)
	v_mov_b32_e32 v38, v32
	v_mov_b32_e32 v28, v25
	v_mov_b32_e32 v40, v33
	v_mov_b32_e32 v25, v30
	v_mov_b32_e32 v42, v34
	v_mov_b32_e32 v30, v27
	v_mov_b32_e32 v44, v35
	v_pk_mul_f32 v[26:27], v[36:37], v[38:39]
	v_pk_mul_f32 v[28:29], v[28:29], v[40:41]
	v_pk_mul_f32 v[24:25], v[24:25], v[42:43]
	v_pk_mul_f32 v[30:31], v[30:31], v[44:45]
	v_add_f32_e32 v32, v26, v27
	v_add_f32_e32 v33, v28, v29
	v_add_f32_e32 v24, v24, v25
	v_add_f32_e32 v25, v30, v31
	v_mul_f32_e32 v26, v63, v46
	v_mul_f32_e32 v27, v75, v47
	v_cvt_pk_bf16_f32 v26, v26, v27
	v_mul_f32_e32 v27, v84, v48
	v_mul_f32_e32 v28, v86, v49
	v_cvt_pk_bf16_f32 v27, v27, v28
	v_mul_f32_e32 v28, v85, v32
	v_mul_f32_e32 v29, v88, v33
	v_cvt_pk_bf16_f32 v28, v28, v29
	v_mul_f32_e32 v29, v87, v24
	v_mul_f32_e32 v30, v71, v25
	v_cvt_pk_bf16_f32 v29, v29, v30
	v_mul_f32_e32 v30, v64, v46
	v_mul_f32_e32 v31, v60, v47
	v_cvt_pk_bf16_f32 v30, v30, v31
	v_mul_f32_e32 v31, v66, v48
	v_mul_f32_e32 v32, v70, v32
	v_mul_f32_e32 v33, v72, v33
	v_mul_f32_e32 v24, v65, v24
	v_mul_f32_e32 v25, v67, v25
	s_mov_b64 s[0:1], 0x1400000
	v_mul_f32_e32 v34, v68, v49
	v_cvt_pk_bf16_f32 v31, v31, v34
	v_cvt_pk_bf16_f32 v32, v32, v33
	v_cvt_pk_bf16_f32 v33, v24, v25
	v_lshl_add_u64 v[24:25], v[120:121], 0, s[0:1]
	s_mov_b32 s0, 0x1400000
	v_add_co_u32_e64 v34, s[4:5], s0, v120
	s_mov_b64 s[0:1], 0x3400000
	s_nop 0
	v_addc_co_u32_e64 v35, s[4:5], 0, v121, s[4:5]
	global_store_dwordx4 v[34:35], v[26:29], off
	s_nop 1
	v_lshl_add_u64 v[26:27], v[120:121], 0, s[0:1]
	s_mov_b32 s0, 0x3400000
	v_add_co_u32_e64 v28, s[4:5], s0, v120
	s_nop 1
	v_addc_co_u32_e64 v29, s[4:5], 0, v121, s[4:5]
	global_store_dwordx4 v[28:29], v[30:33], off
	global_load_dwordx4 v[28:31], v[98:99], off
	s_nop 0
	global_load_dwordx4 v[32:35], v[96:97], off
	ds_bpermute_b32 v37, v177, v20
	ds_bpermute_b32 v38, v177, v21
	ds_bpermute_b32 v40, v177, v22
	ds_bpermute_b32 v42, v177, v23
	v_mov_b32_e32 v36, v20
	v_mov_b32_e32 v20, v22
	s_waitcnt lgkmcnt(3)
; __device__ __forceinline__ unsigned cvt_pk_bf16(float lo, float hi) { unsigned r; asm volatile("v_cvt_pk_bf16_f32 %0, %1, %2" : "=v"(r) : "v"(lo), "v"(hi)); return r; }
;     __device__ __forceinline__ void operator()(const AccT& acc, const Unit& u, int wr, int wc, int fr, int fq) const {
;     ...
;                 for (int bj = 0; bj < 2; ++bj) {
;                     const int t0 = tb + bj * 128;
;                     float v[8];
; #pragma unroll
;                     for (int jj = 0; jj < 4; ++jj) { v[jj] = acc[ai][bj][m][0][jj]; v[4 + jj] = acc[ai][bj][m][1][jj]; }
;                     if constexpr (ROPE) {
;                         const int t = t0 & 2047;
; #pragma unroll
;                         for (int hf = 0; hf < 2; ++hf) {
;                             f32x4 cs, sn;
;                             if (m < 2) { const float c1 = ropeA[(t >> 6) * 16 + d], s1 = ropeA[1024 + (t >> 6) * 16 + d]; cs = (f32x4){c1, c1, c1, c1}; sn = (f32x4){s1, s1, s1, s1}; }
;                             else { const float* cb = ropeA + 2048 + (d - 16) * 64 + (t & 63) + 4 * hf; cs = *(const f32x4*)(cb); sn = *(const f32x4*)(cb + 1024); }
; #pragma unroll
;                             for (int jj = 0; jj < 4; ++jj) { const float pr = __shfl_xor(v[4 * hf + jj], 4); v[4 * hf + jj] = v[4 * hf + jj] * cs[jj] + sgn * pr * sn[jj]; }
;                             __builtin_amdgcn_sched_barrier(0);
;                         }
;                     }
;                     float zf[8], zb[8]; zf[0] = zf0; zb[0] = zb0;
; #pragma unroll
;                     for (int jj = 1; jj < 8; ++jj) { zf[jj] = zf[jj - 1] * zfs; zb[jj] = zb[jj - 1] * zbs; }
;                     u32x4 wf, wb;
;                     wf.x = cvt_pk_bf16(v[0] * zf[0], v[1] * zf[1]); wf.y = cvt_pk_bf16(v[2] * zf[2], v[3] * zf[3]); wf.z = cvt_pk_bf16(v[4] * zf[4], v[5] * zf[5]); wf.w = cvt_pk_bf16(v[6] * zf[6], v[7] * zf[7]);
;                     wb.x = cvt_pk_bf16(v[0] * zb[0], v[1] * zb[1]); wb.y = cvt_pk_bf16(v[2] * zb[2], v[3] * zb[3]); wb.z = cvt_pk_bf16(v[4] * zb[4], v[5] * zb[5]); wb.w = cvt_pk_bf16(v[6] * zb[6], v[7] * zb[7]);
;                     *(u32x4*)(KTZ + (size_t)r * NT + t0) = wf;
;                     *(u32x4*)(KTZ + (size_t)(256 + r) * NT + t0) = wb;
	v_cndmask_b32_e64 v39, v37, -v37, vcc
	s_waitcnt lgkmcnt(2)
	v_cndmask_b32_e64 v41, v38, -v38, vcc
	s_waitcnt lgkmcnt(1)
	v_cndmask_b32_e64 v43, v40, -v40, vcc
	s_waitcnt lgkmcnt(0)
	v_cndmask_b32_e64 v45, v42, -v42, vcc
	s_waitcnt vmcnt(1)
	v_mov_b32_e32 v37, v28
	s_waitcnt vmcnt(0)
	v_mov_b32_e32 v38, v32
	v_mov_b32_e32 v28, v21
	v_mov_b32_e32 v40, v33
	v_mov_b32_e32 v21, v30
	v_mov_b32_e32 v42, v34
	v_mov_b32_e32 v30, v23
	v_mov_b32_e32 v44, v35
	v_pk_mul_f32 v[22:23], v[36:37], v[38:39]
	v_pk_mul_f32 v[28:29], v[28:29], v[40:41]
	v_pk_mul_f32 v[20:21], v[20:21], v[42:43]
	v_pk_mul_f32 v[30:31], v[30:31], v[44:45]
	v_add_f32_e32 v42, v22, v23
	v_add_f32_e32 v43, v28, v29
	v_add_f32_e32 v44, v20, v21
	v_add_f32_e32 v45, v30, v31
	global_load_dwordx4 v[20:23], v[92:93], off offset:16
	global_load_dwordx4 v[28:31], v[94:95], off offset:16
	ds_bpermute_b32 v33, v177, v16
	ds_bpermute_b32 v34, v177, v17
	ds_bpermute_b32 v36, v177, v18
	ds_bpermute_b32 v38, v177, v19
	v_mov_b32_e32 v32, v16
	v_mov_b32_e32 v16, v18
	s_waitcnt lgkmcnt(3)
	v_cndmask_b32_e64 v35, v33, -v33, vcc
	s_waitcnt lgkmcnt(2)
	v_cndmask_b32_e64 v37, v34, -v34, vcc
	s_waitcnt lgkmcnt(1)
	v_cndmask_b32_e64 v39, v36, -v36, vcc
	s_waitcnt lgkmcnt(0)
	v_cndmask_b32_e64 v41, v38, -v38, vcc
	s_waitcnt vmcnt(1)
	v_mov_b32_e32 v33, v20
	s_waitcnt vmcnt(0)
	v_mov_b32_e32 v34, v28
	v_mov_b32_e32 v20, v17
	v_mov_b32_e32 v36, v29
	v_mov_b32_e32 v17, v22
	v_mov_b32_e32 v38, v30
	v_mov_b32_e32 v22, v19
	v_mov_b32_e32 v40, v31
	v_pk_mul_f32 v[18:19], v[32:33], v[34:35]
	v_pk_mul_f32 v[20:21], v[20:21], v[36:37]
	v_pk_mul_f32 v[16:17], v[16:17], v[38:39]
	v_pk_mul_f32 v[22:23], v[22:23], v[40:41]
	v_add_f32_e32 v28, v18, v19
	v_add_f32_e32 v29, v20, v21
	v_add_f32_e32 v30, v16, v17
	v_add_f32_e32 v23, v22, v23
	v_mul_f32_e32 v16, v63, v42
	v_mul_f32_e32 v17, v75, v43
	v_cvt_pk_bf16_f32 v16, v16, v17
	v_mul_f32_e32 v17, v84, v44
	v_mul_f32_e32 v18, v86, v45
	v_cvt_pk_bf16_f32 v17, v17, v18
	v_mul_f32_e32 v18, v85, v28
	v_mul_f32_e32 v19, v88, v29
	v_cvt_pk_bf16_f32 v18, v18, v19
	v_mul_f32_e32 v19, v87, v30
	v_mul_f32_e32 v20, v71, v23
	v_cvt_pk_bf16_f32 v19, v19, v20
	v_mul_f32_e32 v20, v64, v42
	v_mul_f32_e32 v21, v60, v43
	v_cvt_pk_bf16_f32 v20, v20, v21
	v_mul_f32_e32 v21, v66, v44
	v_mul_f32_e32 v22, v68, v45
	v_cvt_pk_bf16_f32 v21, v21, v22
	v_mul_f32_e32 v22, v70, v28
	v_mul_f32_e32 v28, v72, v29
	v_mul_f32_e32 v23, v67, v23
	v_cvt_pk_bf16_f32 v22, v22, v28
	v_mul_f32_e32 v28, v65, v30
	v_cvt_pk_bf16_f32 v23, v28, v23
	global_store_dwordx4 v[24:25], v[16:19], off offset:256
	global_store_dwordx4 v[26:27], v[20:23], off offset:256
	global_load_dwordx4 v[16:19], v[82:83], off
	s_nop 0
	global_load_dwordx4 v[20:23], v[80:81], off
	ds_bpermute_b32 v25, v177, v12
	ds_bpermute_b32 v26, v177, v13
	ds_bpermute_b32 v28, v177, v14
	ds_bpermute_b32 v30, v177, v15
	v_mov_b32_e32 v24, v12
	v_mov_b32_e32 v12, v14
	s_waitcnt lgkmcnt(3)
	v_cndmask_b32_e64 v27, v25, -v25, vcc
	s_waitcnt lgkmcnt(2)
	v_cndmask_b32_e64 v29, v26, -v26, vcc
	s_waitcnt lgkmcnt(1)
	v_cndmask_b32_e64 v31, v28, -v28, vcc
	s_waitcnt lgkmcnt(0)
	v_cndmask_b32_e64 v33, v30, -v30, vcc
	s_waitcnt vmcnt(1)
	v_mov_b32_e32 v25, v16
	s_waitcnt vmcnt(0)
	v_mov_b32_e32 v26, v20
	v_mov_b32_e32 v16, v13
	v_mov_b32_e32 v28, v21
	v_mov_b32_e32 v13, v18
	v_mov_b32_e32 v30, v22
	v_mov_b32_e32 v18, v15
	v_mov_b32_e32 v32, v23
	v_pk_mul_f32 v[14:15], v[24:25], v[26:27]
	v_pk_mul_f32 v[16:17], v[16:17], v[28:29]
	v_pk_mul_f32 v[12:13], v[12:13], v[30:31]
	v_pk_mul_f32 v[18:19], v[18:19], v[32:33]
	v_add_f32_e32 v30, v14, v15
	v_add_f32_e32 v31, v16, v17
	v_add_f32_e32 v32, v12, v13
	v_add_f32_e32 v33, v18, v19
	global_load_dwordx4 v[12:15], v[76:77], off offset:16
	global_load_dwordx4 v[16:19], v[78:79], off offset:16
	ds_bpermute_b32 v21, v177, v8
	ds_bpermute_b32 v22, v177, v9
	ds_bpermute_b32 v24, v177, v10
	ds_bpermute_b32 v26, v177, v11
	v_mov_b32_e32 v20, v8
	v_mov_b32_e32 v8, v10
	s_waitcnt lgkmcnt(3)
	v_cndmask_b32_e64 v23, v21, -v21, vcc
	s_waitcnt lgkmcnt(2)
	v_cndmask_b32_e64 v25, v22, -v22, vcc
	s_waitcnt lgkmcnt(1)
	v_cndmask_b32_e64 v27, v24, -v24, vcc
	s_waitcnt lgkmcnt(0)
	v_cndmask_b32_e64 v29, v26, -v26, vcc
	s_waitcnt vmcnt(1)
	v_mov_b32_e32 v21, v12
	s_waitcnt vmcnt(0)
; #define PG8_WAIT_V(n) asm volatile("s_waitcnt vmcnt(" #n ")" ::: "memory")
; #define PG8_BAR __builtin_amdgcn_s_barrier()
; template <class Epi, class Sched>
; __device__ __forceinline__ void gemm_phase(LAS unsigned char* lds, const Gemm g, const Sched& S, const Epi& E) {
;     ...
;     PG8_WAIT_V(0);
;     if (wr == 0) PG8_BAR;
;     __device__ __forceinline__ void operator()(const AccT& acc, const Unit& u, int wr, int wc, int fr, int fq) const {
;     ...
;                 for (int bj = 0; bj < 2; ++bj) {
;                     const int t0 = tb + bj * 128;
;                     float v[8];
; #pragma unroll
;                     for (int jj = 0; jj < 4; ++jj) { v[jj] = acc[ai][bj][m][0][jj]; v[4 + jj] = acc[ai][bj][m][1][jj]; }
;                     if constexpr (ROPE) {
;                         const int t = t0 & 2047;
; #pragma unroll
;                         for (int hf = 0; hf < 2; ++hf) {
;                             f32x4 cs, sn;
;                             if (m < 2) { const float c1 = ropeA[(t >> 6) * 16 + d], s1 = ropeA[1024 + (t >> 6) * 16 + d]; cs = (f32x4){c1, c1, c1, c1}; sn = (f32x4){s1, s1, s1, s1}; }
;                             else { const float* cb = ropeA + 2048 + (d - 16) * 64 + (t & 63) + 4 * hf; cs = *(const f32x4*)(cb); sn = *(const f32x4*)(cb + 1024); }
; #pragma unroll
;                             for (int jj = 0; jj < 4; ++jj) { const float pr = __shfl_xor(v[4 * hf + jj], 4); v[4 * hf + jj] = v[4 * hf + jj] * cs[jj] + sgn * pr * sn[jj]; }
;                             __builtin_amdgcn_sched_barrier(0);
;                         }
;                     }
;                     float zf[8], zb[8]; zf[0] = zf0; zb[0] = zb0;
; #pragma unroll
;                     for (int jj = 1; jj < 8; ++jj) { zf[jj] = zf[jj - 1] * zfs; zb[jj] = zb[jj - 1] * zbs; }
;                     u32x4 wf, wb;
;                     wf.x = cvt_pk_bf16(v[0] * zf[0], v[1] * zf[1]); wf.y = cvt_pk_bf16(v[2] * zf[2], v[3] * zf[3]); wf.z = cvt_pk_bf16(v[4] * zf[4], v[5] * zf[5]); wf.w = cvt_pk_bf16(v[6] * zf[6], v[7] * zf[7]);
;                     wb.x = cvt_pk_bf16(v[0] * zb[0], v[1] * zb[1]); wb.y = cvt_pk_bf16(v[2] * zb[2], v[3] * zb[3]); wb.z = cvt_pk_bf16(v[4] * zb[4], v[5] * zb[5]); wb.w = cvt_pk_bf16(v[6] * zb[6], v[7] * zb[7]);
;                     *(u32x4*)(KTZ + (size_t)r * NT + t0) = wf;
;                     *(u32x4*)(KTZ + (size_t)(256 + r) * NT + t0) = wb;
	v_mov_b32_e32 v22, v16
	v_mov_b32_e32 v12, v9
	v_mov_b32_e32 v24, v17
	v_mov_b32_e32 v9, v14
	v_mov_b32_e32 v26, v18
	v_mov_b32_e32 v14, v11
	v_mov_b32_e32 v28, v19
	v_pk_mul_f32 v[10:11], v[20:21], v[22:23]
	v_pk_mul_f32 v[12:13], v[12:13], v[24:25]
	v_pk_mul_f32 v[8:9], v[8:9], v[26:27]
	v_pk_mul_f32 v[14:15], v[14:15], v[28:29]
	v_add_f32_e32 v16, v10, v11
	v_add_f32_e32 v17, v12, v13
	v_add_f32_e32 v8, v8, v9
	v_add_f32_e32 v9, v14, v15
	v_mul_f32_e32 v10, v63, v30
	v_mul_f32_e32 v11, v75, v31
	v_cvt_pk_bf16_f32 v10, v10, v11
	v_mul_f32_e32 v11, v84, v32
	v_mul_f32_e32 v12, v86, v33
	v_cvt_pk_bf16_f32 v11, v11, v12
	v_mul_f32_e32 v12, v85, v16
	v_mul_f32_e32 v13, v88, v17
	v_cvt_pk_bf16_f32 v12, v12, v13
	v_mul_f32_e32 v13, v87, v8
	v_mul_f32_e32 v14, v71, v9
	v_cvt_pk_bf16_f32 v13, v13, v14
	v_mul_f32_e32 v14, v64, v30
	v_mul_f32_e32 v15, v60, v31
	v_cvt_pk_bf16_f32 v14, v14, v15
	v_mul_f32_e32 v15, v66, v32
	v_mul_f32_e32 v18, v68, v33
	v_cvt_pk_bf16_f32 v15, v15, v18
	v_add_co_u32_e64 v18, s[4:5], s63, v120
	v_mul_f32_e32 v16, v70, v16
	v_mul_f32_e32 v17, v72, v17
	v_addc_co_u32_e64 v19, s[4:5], 0, v121, s[4:5]
	v_cvt_pk_bf16_f32 v16, v16, v17
	v_mul_f32_e32 v8, v65, v8
	v_mul_f32_e32 v9, v67, v9
	v_cvt_pk_bf16_f32 v17, v8, v9
	global_store_dwordx4 v[18:19], v[10:13], off
	v_lshl_add_u64 v[8:9], v[120:121], 0, s[26:27]
	s_nop 0
	v_add_co_u32_e64 v12, s[4:5], s64, v120
	v_lshl_add_u64 v[10:11], v[120:121], 0, s[28:29]
	s_nop 0
	v_addc_co_u32_e64 v13, s[4:5], 0, v121, s[4:5]
	global_store_dwordx4 v[12:13], v[14:17], off
	global_load_dwordx4 v[12:15], v[82:83], off
	s_nop 0
	global_load_dwordx4 v[16:19], v[80:81], off
	ds_bpermute_b32 v34, v177, v4
	ds_bpermute_b32 v32, v177, v5
	ds_bpermute_b32 v33, v177, v6
	ds_bpermute_b32 v28, v177, v7
	global_load_dwordx4 v[20:23], v[76:77], off offset:16
	global_load_dwordx4 v[24:27], v[78:79], off offset:16
	s_waitcnt lgkmcnt(0)
	v_cndmask_b32_e64 v29, v28, -v28, vcc
	v_mov_b32_e32 v30, v7
	s_waitcnt vmcnt(3)
	v_mov_b32_e32 v31, v15
	s_waitcnt vmcnt(2)
	v_mov_b32_e32 v28, v19
	v_cndmask_b32_e64 v19, v33, -v33, vcc
	v_mov_b32_e32 v7, v14
	v_cndmask_b32_e64 v15, v32, -v32, vcc
	v_mov_b32_e32 v32, v5
	v_mov_b32_e32 v33, v13
	v_mov_b32_e32 v14, v17
	v_cndmask_b32_e64 v17, v34, -v34, vcc
	v_mov_b32_e32 v5, v12
	ds_bpermute_b32 v13, v177, v0
	v_mov_b32_e32 v12, v0
	ds_bpermute_b32 v34, v177, v1
	ds_bpermute_b32 v35, v177, v2
	v_mov_b32_e32 v0, v2
	ds_bpermute_b32 v2, v177, v3
	v_pk_mul_f32 v[28:29], v[30:31], v[28:29]
	v_pk_mul_f32 v[6:7], v[6:7], v[18:19]
	v_pk_mul_f32 v[14:15], v[32:33], v[14:15]
	v_pk_mul_f32 v[4:5], v[4:5], v[16:17]
	v_add_f32_e32 v18, v28, v29
	v_add_f32_e32 v19, v6, v7
	v_add_f32_e32 v28, v14, v15
	v_add_f32_e32 v29, v4, v5
	s_waitcnt lgkmcnt(3)
	v_cndmask_b32_e64 v5, v13, -v13, vcc
	s_waitcnt lgkmcnt(2)
	v_cndmask_b32_e64 v7, v34, -v34, vcc
	s_waitcnt lgkmcnt(1)
	v_cndmask_b32_e64 v15, v35, -v35, vcc
	s_waitcnt lgkmcnt(0)
	v_cndmask_b32_e64 v17, v2, -v2, vcc
	s_waitcnt vmcnt(1)
	v_mov_b32_e32 v13, v20
	s_waitcnt vmcnt(0)
	v_mov_b32_e32 v4, v24
	v_mov_b32_e32 v20, v1
	v_mov_b32_e32 v6, v25
	v_mov_b32_e32 v1, v22
	v_mov_b32_e32 v14, v26
	v_mov_b32_e32 v22, v3
	v_mov_b32_e32 v16, v27
	v_pk_mul_f32 v[2:3], v[12:13], v[4:5]
	v_pk_mul_f32 v[4:5], v[20:21], v[6:7]
	v_pk_mul_f32 v[0:1], v[0:1], v[14:15]
	v_pk_mul_f32 v[6:7], v[22:23], v[16:17]
	v_add_f32_e32 v12, v2, v3
	v_add_f32_e32 v13, v4, v5
	v_add_f32_e32 v14, v0, v1
	v_add_f32_e32 v7, v6, v7
	v_mul_f32_e32 v0, v63, v29
	v_mul_f32_e32 v1, v75, v28
	v_cvt_pk_bf16_f32 v0, v0, v1
	v_mul_f32_e32 v1, v84, v19
	v_mul_f32_e32 v2, v86, v18
	v_cvt_pk_bf16_f32 v1, v1, v2
	v_mul_f32_e32 v2, v85, v12
	v_mul_f32_e32 v3, v88, v13
	v_cvt_pk_bf16_f32 v2, v2, v3
	v_mul_f32_e32 v3, v87, v14
	v_mul_f32_e32 v4, v71, v7
	v_cvt_pk_bf16_f32 v3, v3, v4
	v_mul_f32_e32 v4, v64, v29
	v_mul_f32_e32 v5, v60, v28
	v_cvt_pk_bf16_f32 v4, v4, v5
	v_mul_f32_e32 v5, v66, v19
	v_mul_f32_e32 v6, v68, v18
	v_cvt_pk_bf16_f32 v5, v5, v6
	v_mul_f32_e32 v6, v70, v12
	v_mul_f32_e32 v12, v72, v13
	v_mul_f32_e32 v7, v67, v7
	v_cvt_pk_bf16_f32 v6, v6, v12
	v_mul_f32_e32 v12, v65, v14
	v_cvt_pk_bf16_f32 v7, v12, v7
	global_store_dwordx4 v[8:9], v[0:3], off offset:256
	global_store_dwordx4 v[10:11], v[4:7], off offset:256
	s_and_b64 vcc, exec, s[2:3]
	s_mov_b32 s33, s30
	s_mov_b64 s[4:5], s[38:39]
	s_mov_b64 s[0:1], s[36:37]
	s_cbranch_vccz .LBB0_606
	s_waitcnt vmcnt(0)
	s_cmpk_gt_u32 s42, 0xff
	s_cbranch_scc1 .LBB0_617
	s_barrier

; #define PG8_STAGE(bufoff, gbase, voff) do { _Pragma("unroll") for (int _i = 0; _i < 2; ++_i) \
;         __builtin_amdgcn_global_load_lds((const unsigned*)((const char*)(gbase) + (voff)[_i]), (LAS unsigned*)(lds + (bufoff) + ldsw + _i * 8192), 16, 0, 0); } while (0)
; #define PG8_LDA(dst, b, h) do { _Pragma("unroll") for (int m = 0; m < 4; ++m) _Pragma("unroll") for (int k = 0; k < 2; ++k) dst[m][k] = *(const LAS bf16x8*)(lds + PG8_SA(b, h) + aoff + m * 2048 + k * 1024); } while (0)
; #define PG8_LDB(dst, b, h) do { _Pragma("unroll") for (int n = 0; n < 2; ++n) _Pragma("unroll") for (int k = 0; k < 2; ++k) dst[n][k] = *(const LAS bf16x8*)(lds + PG8_SB(b, h) + boff + n * 2048 + k * 1024); } while (0)
; #define PG8_MMA(ai, bj, At, Bt) do { __builtin_amdgcn_s_setprio(1); _Pragma("unroll") for (int m = 0; m < 4; ++m) _Pragma("unroll") for (int n = 0; n < 2; ++n) _Pragma("unroll") for (int k = 0; k < 2; ++k) \
;         acc[ai][bj][m][n] = __builtin_amdgcn_mfma_f32_16x16x32_bf16(Bt[n][k], At[m][k], acc[ai][bj][m][n], 0, 0, 0); __builtin_amdgcn_s_setprio(0); } while (0)
; #define PG8_WAIT_L(n) asm volatile("s_waitcnt lgkmcnt(" #n ")" ::: "memory")
; template <class Epi, class Sched>
; __device__ __forceinline__ void gemm_phase(LAS unsigned char* lds, const Gemm g, const Sched& S, const Epi& E) {
;     ...
;         const bool has_next = S.next(ui + 1, nxt);
;         const char* nA = has_next ? (const char*)g.A + (size_t)nxt.pm * tstep : cA; const char* nB = has_next ? (const char*)g.Bt + (size_t)nxt.pn * tstep : cB;
;         for (int t = 0; t < nt; t += 2) {
;             const bool last = (t == nt - 2);
;             const char* a1 = cA + (size_t)(t + 1) * kstep;
;             const char* a2 = last ? nA : cA + (size_t)(t + 2) * kstep; const char* b2 = last ? nB : cB + (size_t)(t + 2) * kstep;
;             const char* a3 = a2 + kstep; const char* b3 = b2 + kstep;
;             PG8_LDB(B0, 0, 0); PG8_SCHED; PG8_LDA(At, 0, 0); PG8_STAGE(PG8_SA(1, 1), a1 + hstep, voffA);
;             PG8_WAIT_L(8); PG8_BAR; PG8_WAIT_L(0); PG8_MMA(0, 0, At, B0); PG8_BAR; PG8_SCHED;
;             PG8_LDB(B1, 0, 1); PG8_STAGE(PG8_SB(0, 0), b2, voffB);
;             PG8_BAR; PG8_WAIT_L(0); PG8_MMA(0, 1, At, B1); PG8_BAR;
;             PG8_LDA(At, 0, 1); PG8_STAGE(PG8_SA(0, 0), a2, voffA);
;             PG8_BAR; PG8_WAIT_L(0); PG8_MMA(1, 0, At, B0); PG8_BAR; PG8_SCHED;
.LBB0_632:
	s_ashr_i32 s23, s22, 31
	v_cmp_lt_i64_e32 vcc, s[24:25], v[140:141]
	s_lshl_b64 s[24:25], s[22:23], 19
	s_add_u32 s24, s38, s24
	s_addc_u32 s25, s39, s25
	s_and_b64 s[26:27], vcc, exec
	s_cselect_b32 s23, s25, s31
	s_cselect_b32 s61, s24, s30
	s_ashr_i32 s21, s20, 31
	s_lshl_b64 s[26:27], s[20:21], 19
	s_add_u32 s26, s96, s26
	s_addc_u32 s27, s97, s27
	s_and_b64 s[36:37], vcc, exec
	s_cselect_b32 s21, s27, s35
	s_cselect_b32 s62, s26, s34
	s_add_u32 s30, s30, 0x40080
	s_addc_u32 s31, s31, 0
	s_add_u32 s63, s34, 0x100
	s_addc_u32 s64, s35, 0
	s_mov_b32 s65, -2
	s_waitcnt lgkmcnt(0)
	ds_read_b128 v[150:153], v147
	ds_read_b128 v[154:157], v147 offset:1024
	ds_read_b128 v[158:161], v147 offset:2048
	ds_read_b128 v[162:165], v147 offset:3072
	s_add_u32 s34, s30, 0xfffc0080
	s_addc_u32 s35, s31, -1
	s_cmp_eq_u32 s65, 12
	s_cselect_b32 s37, s23, s35
	s_cselect_b32 s36, s61, s34
	s_cselect_b32 s35, s21, s64
	s_cselect_b32 s34, s62, s63
	s_add_i32 m0, s29, 0xc000
	ds_read_b128 v[166:169], v148
	ds_read_b128 v[170:173], v148 offset:1024
	ds_read_b128 v[174:177], v148 offset:2048
	ds_read_b128 v[178:181], v148 offset:3072
	ds_read_b128 v[182:185], v148 offset:4096
	ds_read_b128 v[186:189], v148 offset:5120
	ds_read_b128 v[190:193], v148 offset:6144
	ds_read_b128 v[194:197], v148 offset:7168
	global_load_lds_dwordx4 v136, s[30:31]
	s_add_i32 m0, s29, 0xe000
	s_nop 0
	global_load_lds_dwordx4 v138, s[30:31]
	s_waitcnt lgkmcnt(8)
	s_waitcnt vmcnt(8)
	s_barrier
	s_waitcnt lgkmcnt(0)
	s_setprio 1
	s_waitcnt lgkmcnt(0)
	v_mfma_f32_16x16x32_bf16 v[124:127], v[150:153], v[166:169], 0
	v_mfma_f32_16x16x32_bf16 v[120:123], v[158:161], v[166:169], 0
	v_mfma_f32_16x16x32_bf16 v[116:119], v[150:153], v[174:177], 0
	v_mfma_f32_16x16x32_bf16 v[108:111], v[158:161], v[174:177], 0
	v_mfma_f32_16x16x32_bf16 v[100:103], v[150:153], v[182:185], 0
	v_mfma_f32_16x16x32_bf16 v[92:95], v[158:161], v[182:185], 0
	v_mfma_f32_16x16x32_bf16 v[84:87], v[150:153], v[190:193], 0
	v_mfma_f32_16x16x32_bf16 v[76:79], v[158:161], v[190:193], 0
	v_mfma_f32_16x16x32_bf16 v[124:127], v[154:157], v[170:173], v[124:127]
	v_mfma_f32_16x16x32_bf16 v[120:123], v[162:165], v[170:173], v[120:123]
	v_mfma_f32_16x16x32_bf16 v[116:119], v[154:157], v[178:181], v[116:119]
	v_mfma_f32_16x16x32_bf16 v[108:111], v[162:165], v[178:181], v[108:111]
	v_mfma_f32_16x16x32_bf16 v[100:103], v[154:157], v[186:189], v[100:103]
	v_mfma_f32_16x16x32_bf16 v[92:95], v[162:165], v[186:189], v[92:95]
	v_mfma_f32_16x16x32_bf16 v[84:87], v[154:157], v[194:197], v[84:87]
	v_mfma_f32_16x16x32_bf16 v[76:79], v[162:165], v[194:197], v[76:79]
	s_setprio 0
	s_barrier
	s_add_i32 s66, s54, s43
	s_mov_b32 m0, s66
	ds_read_b128 v[202:205], v149
	ds_read_b128 v[206:209], v149 offset:1024
	ds_read_b128 v[210:213], v149 offset:2048
	ds_read_b128 v[214:217], v149 offset:3072
	global_load_lds_dwordx4 v130, s[34:35]
	s_add_i32 m0, s66, 0x2000
	s_nop 0
	global_load_lds_dwordx4 v134, s[34:35]
	s_waitcnt vmcnt(8)
	s_barrier
	s_waitcnt lgkmcnt(0)
	s_setprio 1
	s_waitcnt lgkmcnt(0)
	v_mfma_f32_16x16x32_bf16 v[112:115], v[202:205], v[166:169], 0
	v_mfma_f32_16x16x32_bf16 v[104:107], v[210:213], v[166:169], 0
	v_mfma_f32_16x16x32_bf16 v[96:99], v[202:205], v[174:177], 0
	v_mfma_f32_16x16x32_bf16 v[88:91], v[210:213], v[174:177], 0
	v_mfma_f32_16x16x32_bf16 v[80:83], v[202:205], v[182:185], 0
	v_mfma_f32_16x16x32_bf16 v[72:75], v[210:213], v[182:185], 0
	v_mfma_f32_16x16x32_bf16 v[68:71], v[202:205], v[190:193], 0
	v_mfma_f32_16x16x32_bf16 v[64:67], v[210:213], v[190:193], 0
	v_mfma_f32_16x16x32_bf16 v[112:115], v[206:209], v[170:173], v[112:115]
	v_mfma_f32_16x16x32_bf16 v[104:107], v[214:217], v[170:173], v[104:107]
	v_mfma_f32_16x16x32_bf16 v[96:99], v[206:209], v[178:181], v[96:99]
	v_mfma_f32_16x16x32_bf16 v[88:91], v[214:217], v[178:181], v[88:91]
	v_mfma_f32_16x16x32_bf16 v[80:83], v[206:209], v[186:189], v[80:83]
	v_mfma_f32_16x16x32_bf16 v[72:75], v[214:217], v[186:189], v[72:75]
	v_mfma_f32_16x16x32_bf16 v[68:71], v[206:209], v[194:197], v[68:71]
	v_mfma_f32_16x16x32_bf16 v[64:67], v[214:217], v[194:197], v[64:67]
	s_setprio 0
	s_mov_b32 m0, s29
	v_lshl_add_u64 v[220:221], s[36:37], 0, v[128:129]
	s_barrier
	ds_read_b128 v[166:169], v148 offset:16384
	ds_read_b128 v[170:173], v148 offset:17408
	ds_read_b128 v[174:177], v148 offset:18432
	ds_read_b128 v[178:181], v148 offset:19456
	ds_read_b128 v[182:185], v148 offset:20480
	ds_read_b128 v[186:189], v148 offset:21504
	ds_read_b128 v[190:193], v148 offset:22528
	ds_read_b128 v[194:197], v148 offset:23552
	global_load_lds_dwordx4 v128, s[36:37]
	v_lshl_add_u64 v[222:223], s[36:37], 0, v[132:133]
	s_mov_b32 m0, s44
	s_nop 0
	global_load_lds_dwordx4 v132, s[36:37]
	s_barrier
	s_waitcnt lgkmcnt(0)
	s_setprio 1
	s_waitcnt lgkmcnt(0)
	v_mfma_f32_16x16x32_bf16 v[60:63], v[150:153], v[166:169], 0
	v_mfma_f32_16x16x32_bf16 v[56:59], v[158:161], v[166:169], 0
	v_mfma_f32_16x16x32_bf16 v[52:55], v[150:153], v[174:177], 0
	v_mfma_f32_16x16x32_bf16 v[44:47], v[158:161], v[174:177], 0
	v_mfma_f32_16x16x32_bf16 v[36:39], v[150:153], v[182:185], 0
	v_mfma_f32_16x16x32_bf16 v[28:31], v[158:161], v[182:185], 0
	v_mfma_f32_16x16x32_bf16 v[20:23], v[150:153], v[190:193], 0
	v_mfma_f32_16x16x32_bf16 v[12:15], v[158:161], v[190:193], 0
	v_mfma_f32_16x16x32_bf16 v[60:63], v[154:157], v[170:173], v[60:63]
	v_mfma_f32_16x16x32_bf16 v[56:59], v[162:165], v[170:173], v[56:59]
	v_mfma_f32_16x16x32_bf16 v[52:55], v[154:157], v[178:181], v[52:55]
	v_mfma_f32_16x16x32_bf16 v[44:47], v[162:165], v[178:181], v[44:47]
	v_mfma_f32_16x16x32_bf16 v[36:39], v[154:157], v[186:189], v[36:39]
	v_mfma_f32_16x16x32_bf16 v[28:31], v[162:165], v[186:189], v[28:31]
	v_mfma_f32_16x16x32_bf16 v[20:23], v[154:157], v[194:197], v[20:23]
	v_mfma_f32_16x16x32_bf16 v[12:15], v[162:165], v[194:197], v[12:15]
	s_setprio 0
	s_barrier
; #define PG8_STAGE(bufoff, gbase, voff) do { _Pragma("unroll") for (int _i = 0; _i < 2; ++_i) \
;         __builtin_amdgcn_global_load_lds((const unsigned*)((const char*)(gbase) + (voff)[_i]), (LAS unsigned*)(lds + (bufoff) + ldsw + _i * 8192), 16, 0, 0); } while (0)
; #define PG8_LDA(dst, b, h) do { _Pragma("unroll") for (int m = 0; m < 4; ++m) _Pragma("unroll") for (int k = 0; k < 2; ++k) dst[m][k] = *(const LAS bf16x8*)(lds + PG8_SA(b, h) + aoff + m * 2048 + k * 1024); } while (0)
; #define PG8_LDB(dst, b, h) do { _Pragma("unroll") for (int n = 0; n < 2; ++n) _Pragma("unroll") for (int k = 0; k < 2; ++k) dst[n][k] = *(const LAS bf16x8*)(lds + PG8_SB(b, h) + boff + n * 2048 + k * 1024); } while (0)
; #define PG8_MMA(ai, bj, At, Bt) do { __builtin_amdgcn_s_setprio(1); _Pragma("unroll") for (int m = 0; m < 4; ++m) _Pragma("unroll") for (int n = 0; n < 2; ++n) _Pragma("unroll") for (int k = 0; k < 2; ++k) \
;         acc[ai][bj][m][n] = __builtin_amdgcn_mfma_f32_16x16x32_bf16(Bt[n][k], At[m][k], acc[ai][bj][m][n], 0, 0, 0); __builtin_amdgcn_s_setprio(0); } while (0)
; #define PG8_WAIT_V(n) asm volatile("s_waitcnt vmcnt(" #n ")" ::: "memory")
; #define PG8_WAIT_L(n) asm volatile("s_waitcnt lgkmcnt(" #n ")" ::: "memory")
; #define PG8_BAR __builtin_amdgcn_s_barrier()
; #define PG8_SCHED __builtin_amdgcn_sched_barrier(0)
; template <class Epi, class Sched>
; __device__ __forceinline__ void gemm_phase(LAS unsigned char* lds, const Gemm g, const Sched& S, const Epi& E) {
;     ...
;             PG8_STAGE(PG8_SB(0, 1), b2 + hstep, voffB);
;             PG8_WAIT_V(6); PG8_BAR; PG8_MMA(1, 1, At, B1); PG8_BAR;
;             PG8_LDB(B0, 1, 0); PG8_SCHED; PG8_LDA(At, 1, 0); PG8_STAGE(PG8_SA(0, 1), a2 + hstep, voffA);
;             PG8_WAIT_L(8); PG8_BAR; PG8_WAIT_L(0); PG8_MMA(0, 0, At, B0); PG8_BAR; PG8_SCHED;
;             PG8_LDB(B1, 1, 1); PG8_STAGE(PG8_SB(1, 0), b3, voffB);
;             PG8_BAR; PG8_WAIT_L(0); PG8_MMA(0, 1, At, B1); PG8_BAR;
;             PG8_LDA(At, 1, 1); PG8_STAGE(PG8_SA(1, 0), a3, voffA);
	s_add_u32 s66, s34, 0x40000
	s_addc_u32 s67, s35, 0
	s_add_i32 s68, s55, s43
	s_mov_b32 m0, s68
	s_nop 0
	global_load_lds_dwordx4 v130, s[66:67]
	s_add_i32 m0, s68, 0x2000
	s_nop 0
	global_load_lds_dwordx4 v134, s[66:67]
	s_add_u32 s36, s36, 0x40000
	s_addc_u32 s37, s37, 0
	s_mov_b32 m0, s45
	s_nop 0
	global_load_lds_dwordx4 v128, s[36:37]
	s_mov_b32 m0, s46
	s_nop 0
	global_load_lds_dwordx4 v132, s[36:37]
	s_waitcnt vmcnt(10)
	s_barrier
	s_setprio 1
	v_mfma_f32_16x16x32_bf16 v[48:51], v[202:205], v[166:169], 0
	v_mfma_f32_16x16x32_bf16 v[40:43], v[210:213], v[166:169], 0
	v_mfma_f32_16x16x32_bf16 v[32:35], v[202:205], v[174:177], 0
	v_mfma_f32_16x16x32_bf16 v[24:27], v[210:213], v[174:177], 0
	v_mfma_f32_16x16x32_bf16 v[16:19], v[202:205], v[182:185], 0
	v_mfma_f32_16x16x32_bf16 v[8:11], v[210:213], v[182:185], 0
	v_mfma_f32_16x16x32_bf16 v[4:7], v[202:205], v[190:193], 0
	v_mfma_f32_16x16x32_bf16 v[0:3], v[210:213], v[190:193], 0
	v_mfma_f32_16x16x32_bf16 v[48:51], v[206:209], v[170:173], v[48:51]
	v_mfma_f32_16x16x32_bf16 v[40:43], v[214:217], v[170:173], v[40:43]
	v_mfma_f32_16x16x32_bf16 v[32:35], v[206:209], v[178:181], v[32:35]
	v_mfma_f32_16x16x32_bf16 v[24:27], v[214:217], v[178:181], v[24:27]
	v_mfma_f32_16x16x32_bf16 v[16:19], v[206:209], v[186:189], v[16:19]
	v_mfma_f32_16x16x32_bf16 v[8:11], v[214:217], v[186:189], v[8:11]
	v_mfma_f32_16x16x32_bf16 v[4:7], v[206:209], v[194:197], v[4:7]
	v_mfma_f32_16x16x32_bf16 v[0:3], v[214:217], v[194:197], v[0:3]
	s_setprio 0
	s_add_i32 s66, 0, 0x18000
	v_add_u32_e32 v162, s66, v146
	s_barrier
	ds_read_b128 v[150:153], v162
	ds_read_b128 v[154:157], v162 offset:1024
	ds_read_b128 v[158:161], v162 offset:2048
	ds_read_b128 v[162:165], v162 offset:3072
	ds_read_b128 v[166:169], v148 offset:32768
	ds_read_b128 v[170:173], v148 offset:33792
	ds_read_b128 v[174:177], v148 offset:34816
	ds_read_b128 v[178:181], v148 offset:35840
	ds_read_b128 v[182:185], v148 offset:36864
	ds_read_b128 v[186:189], v148 offset:37888
	ds_read_b128 v[190:193], v148 offset:38912
	ds_read_b128 v[194:197], v148 offset:39936
	s_waitcnt lgkmcnt(8)
	s_waitcnt vmcnt(8)
	s_barrier
	s_waitcnt lgkmcnt(0)
	s_setprio 1
	s_waitcnt lgkmcnt(0)
	v_mfma_f32_16x16x32_bf16 v[124:127], v[150:153], v[166:169], v[124:127]
	v_mfma_f32_16x16x32_bf16 v[120:123], v[158:161], v[166:169], v[120:123]
	v_mfma_f32_16x16x32_bf16 v[116:119], v[150:153], v[174:177], v[116:119]
	v_mfma_f32_16x16x32_bf16 v[108:111], v[158:161], v[174:177], v[108:111]
	v_mfma_f32_16x16x32_bf16 v[100:103], v[150:153], v[182:185], v[100:103]
	v_mfma_f32_16x16x32_bf16 v[92:95], v[158:161], v[182:185], v[92:95]
	v_mfma_f32_16x16x32_bf16 v[84:87], v[150:153], v[190:193], v[84:87]
	v_mfma_f32_16x16x32_bf16 v[76:79], v[158:161], v[190:193], v[76:79]
	v_mfma_f32_16x16x32_bf16 v[124:127], v[154:157], v[170:173], v[124:127]
	v_mfma_f32_16x16x32_bf16 v[120:123], v[162:165], v[170:173], v[120:123]
	v_mfma_f32_16x16x32_bf16 v[116:119], v[154:157], v[178:181], v[116:119]
	v_mfma_f32_16x16x32_bf16 v[108:111], v[162:165], v[178:181], v[108:111]
	v_mfma_f32_16x16x32_bf16 v[100:103], v[154:157], v[186:189], v[100:103]
	v_mfma_f32_16x16x32_bf16 v[92:95], v[162:165], v[186:189], v[92:95]
	v_mfma_f32_16x16x32_bf16 v[84:87], v[154:157], v[194:197], v[84:87]
	v_mfma_f32_16x16x32_bf16 v[76:79], v[162:165], v[194:197], v[76:79]
	s_setprio 0
	s_barrier
	s_add_i32 s36, 0, 0x1c000
	s_add_i32 s37, s66, s43
	v_add_u32_e32 v214, s36, v146
	s_add_u32 s4, s34, 0x80
	s_addc_u32 s5, s35, 0
	s_mov_b32 m0, s37
	ds_read_b128 v[202:205], v214
	ds_read_b128 v[206:209], v214 offset:1024
	ds_read_b128 v[210:213], v214 offset:2048
	ds_read_b128 v[214:217], v214 offset:3072
	global_load_lds_dwordx4 v130, s[4:5]
	s_add_i32 m0, s37, 0x2000
	s_nop 0
	global_load_lds_dwordx4 v134, s[4:5]
	s_waitcnt vmcnt(8)
	s_barrier
	s_waitcnt lgkmcnt(0)
	s_setprio 1
	s_waitcnt lgkmcnt(0)
	v_mfma_f32_16x16x32_bf16 v[112:115], v[202:205], v[166:169], v[112:115]
	v_mfma_f32_16x16x32_bf16 v[104:107], v[210:213], v[166:169], v[104:107]
	v_mfma_f32_16x16x32_bf16 v[96:99], v[202:205], v[174:177], v[96:99]
	v_mfma_f32_16x16x32_bf16 v[88:91], v[210:213], v[174:177], v[88:91]
	v_mfma_f32_16x16x32_bf16 v[80:83], v[202:205], v[182:185], v[80:83]
	v_mfma_f32_16x16x32_bf16 v[72:75], v[210:213], v[182:185], v[72:75]
	v_mfma_f32_16x16x32_bf16 v[68:71], v[202:205], v[190:193], v[68:71]
	v_mfma_f32_16x16x32_bf16 v[64:67], v[210:213], v[190:193], v[64:67]
	v_mfma_f32_16x16x32_bf16 v[112:115], v[206:209], v[170:173], v[112:115]
	v_mfma_f32_16x16x32_bf16 v[104:107], v[214:217], v[170:173], v[104:107]
	v_mfma_f32_16x16x32_bf16 v[96:99], v[206:209], v[178:181], v[96:99]
	v_mfma_f32_16x16x32_bf16 v[88:91], v[214:217], v[178:181], v[88:91]
	v_mfma_f32_16x16x32_bf16 v[80:83], v[206:209], v[186:189], v[80:83]
	v_mfma_f32_16x16x32_bf16 v[72:75], v[214:217], v[186:189], v[72:75]
	v_mfma_f32_16x16x32_bf16 v[68:71], v[206:209], v[194:197], v[68:71]
	v_mfma_f32_16x16x32_bf16 v[64:67], v[214:217], v[194:197], v[64:67]
	s_setprio 0
	s_mov_b32 m0, s51
	s_mov_b64 s[4:5], 0x80
	v_lshl_add_u64 v[198:199], v[220:221], 0, s[4:5]
	s_barrier
	ds_read_b128 v[166:169], v148 offset:49152
	ds_read_b128 v[170:173], v148 offset:50176
	ds_read_b128 v[174:177], v148 offset:51200
	ds_read_b128 v[178:181], v148 offset:52224
	ds_read_b128 v[182:185], v148 offset:53248
	ds_read_b128 v[186:189], v148 offset:54272
	ds_read_b128 v[190:193], v148 offset:55296
	ds_read_b128 v[194:197], v148 offset:56320
	global_load_lds_dwordx4 v[198:199], off
	v_lshl_add_u64 v[198:199], v[222:223], 0, s[4:5]
	s_mov_b32 m0, s52
	s_nop 0
	global_load_lds_dwordx4 v[198:199], off
	s_barrier
; #define PG8_STAGE(bufoff, gbase, voff) do { _Pragma("unroll") for (int _i = 0; _i < 2; ++_i) \
;         __builtin_amdgcn_global_load_lds((const unsigned*)((const char*)(gbase) + (voff)[_i]), (LAS unsigned*)(lds + (bufoff) + ldsw + _i * 8192), 16, 0, 0); } while (0)
; #define PG8_LDA(dst, b, h) do { _Pragma("unroll") for (int m = 0; m < 4; ++m) _Pragma("unroll") for (int k = 0; k < 2; ++k) dst[m][k] = *(const LAS bf16x8*)(lds + PG8_SA(b, h) + aoff + m * 2048 + k * 1024); } while (0)
; #define PG8_WAIT_V(n) asm volatile("s_waitcnt vmcnt(" #n ")" ::: "memory")
; #define PG8_WAIT_L(n) asm volatile("s_waitcnt lgkmcnt(" #n ")" ::: "memory")
; template <class Epi, class Sched>
; __device__ __forceinline__ void gemm_phase(LAS unsigned char* lds, const Gemm g, const Sched& S, const Epi& E) {
;     ...
;         for (int t = 0; t < nt; t += 2) {
;             const bool last = (t == nt - 2);
;             const char* a1 = cA + (size_t)(t + 1) * kstep;
;             const char* a2 = last ? nA : cA + (size_t)(t + 2) * kstep; const char* b2 = last ? nB : cB + (size_t)(t + 2) * kstep;
;             const char* a3 = a2 + kstep; const char* b3 = b2 + kstep;
;             PG8_LDB(B0, 0, 0); PG8_SCHED; PG8_LDA(At, 0, 0); PG8_STAGE(PG8_SA(1, 1), a1 + hstep, voffA);
;             PG8_WAIT_L(8); PG8_BAR; PG8_WAIT_L(0); PG8_MMA(0, 0, At, B0); PG8_BAR; PG8_SCHED;
;             PG8_LDB(B1, 0, 1); PG8_STAGE(PG8_SB(0, 0), b2, voffB);
;             PG8_BAR; PG8_WAIT_L(0); PG8_MMA(0, 1, At, B1); PG8_BAR;
;             PG8_LDA(At, 0, 1); PG8_STAGE(PG8_SA(0, 0), a2, voffA);
;             PG8_BAR; PG8_WAIT_L(0); PG8_MMA(1, 0, At, B0); PG8_BAR; PG8_SCHED;
;             PG8_STAGE(PG8_SB(0, 1), b2 + hstep, voffB);
;             PG8_WAIT_V(6); PG8_BAR; PG8_MMA(1, 1, At, B1); PG8_BAR;
;             PG8_LDB(B0, 1, 0); PG8_SCHED; PG8_LDA(At, 1, 0); PG8_STAGE(PG8_SA(0, 1), a2 + hstep, voffA);
;             PG8_WAIT_L(8); PG8_BAR; PG8_WAIT_L(0); PG8_MMA(0, 0, At, B0); PG8_BAR; PG8_SCHED;
;             PG8_LDB(B1, 1, 1); PG8_STAGE(PG8_SB(1, 0), b3, voffB);
;             PG8_BAR; PG8_WAIT_L(0); PG8_MMA(0, 1, At, B1); PG8_BAR;
;             PG8_LDA(At, 1, 1); PG8_STAGE(PG8_SA(1, 0), a3, voffA);
;             PG8_BAR; PG8_WAIT_L(0); PG8_MMA(1, 0, At, B0); PG8_BAR; PG8_SCHED;
;             PG8_STAGE(PG8_SB(1, 1), b3 + hstep, voffB);
;             PG8_WAIT_V(6); PG8_BAR; PG8_MMA(1, 1, At, B1); PG8_BAR;
	s_waitcnt lgkmcnt(0)
	s_setprio 1
	s_waitcnt lgkmcnt(0)
	v_mfma_f32_16x16x32_bf16 v[60:63], v[150:153], v[166:169], v[60:63]
	v_mfma_f32_16x16x32_bf16 v[56:59], v[158:161], v[166:169], v[56:59]
	v_mfma_f32_16x16x32_bf16 v[52:55], v[150:153], v[174:177], v[52:55]
	v_mfma_f32_16x16x32_bf16 v[44:47], v[158:161], v[174:177], v[44:47]
	v_mfma_f32_16x16x32_bf16 v[36:39], v[150:153], v[182:185], v[36:39]
	v_mfma_f32_16x16x32_bf16 v[28:31], v[158:161], v[182:185], v[28:31]
	v_mfma_f32_16x16x32_bf16 v[20:23], v[150:153], v[190:193], v[20:23]
	v_mfma_f32_16x16x32_bf16 v[12:15], v[158:161], v[190:193], v[12:15]
	v_mfma_f32_16x16x32_bf16 v[60:63], v[154:157], v[170:173], v[60:63]
	v_mfma_f32_16x16x32_bf16 v[56:59], v[162:165], v[170:173], v[56:59]
	v_mfma_f32_16x16x32_bf16 v[52:55], v[154:157], v[178:181], v[52:55]
	v_mfma_f32_16x16x32_bf16 v[44:47], v[162:165], v[178:181], v[44:47]
	v_mfma_f32_16x16x32_bf16 v[36:39], v[154:157], v[186:189], v[36:39]
	v_mfma_f32_16x16x32_bf16 v[28:31], v[162:165], v[186:189], v[28:31]
	v_mfma_f32_16x16x32_bf16 v[20:23], v[154:157], v[194:197], v[20:23]
	v_mfma_f32_16x16x32_bf16 v[12:15], v[162:165], v[194:197], v[12:15]
	s_setprio 0
	s_barrier
	s_add_u32 s34, s34, 0x40080
	s_addc_u32 s35, s35, 0
	s_add_i32 s36, s36, s43
	s_mov_b32 m0, s36
	s_nop 0
	global_load_lds_dwordx4 v130, s[34:35]
	s_add_i32 m0, s36, 0x2000
	s_nop 0
	global_load_lds_dwordx4 v134, s[34:35]
	s_waitcnt vmcnt(8)
	s_barrier
	s_setprio 1
	v_mfma_f32_16x16x32_bf16 v[48:51], v[202:205], v[166:169], v[48:51]
	v_mfma_f32_16x16x32_bf16 v[40:43], v[210:213], v[166:169], v[40:43]
	v_mfma_f32_16x16x32_bf16 v[32:35], v[202:205], v[174:177], v[32:35]
	v_mfma_f32_16x16x32_bf16 v[24:27], v[210:213], v[174:177], v[24:27]
	v_mfma_f32_16x16x32_bf16 v[16:19], v[202:205], v[182:185], v[16:19]
	v_mfma_f32_16x16x32_bf16 v[8:11], v[210:213], v[182:185], v[8:11]
	v_mfma_f32_16x16x32_bf16 v[4:7], v[202:205], v[190:193], v[4:7]
	v_mfma_f32_16x16x32_bf16 v[0:3], v[210:213], v[190:193], v[0:3]
	v_mfma_f32_16x16x32_bf16 v[48:51], v[206:209], v[170:173], v[48:51]
	v_mfma_f32_16x16x32_bf16 v[40:43], v[214:217], v[170:173], v[40:43]
	v_mfma_f32_16x16x32_bf16 v[32:35], v[206:209], v[178:181], v[32:35]
	v_mfma_f32_16x16x32_bf16 v[24:27], v[214:217], v[178:181], v[24:27]
	v_mfma_f32_16x16x32_bf16 v[16:19], v[206:209], v[186:189], v[16:19]
	v_mfma_f32_16x16x32_bf16 v[8:11], v[214:217], v[186:189], v[8:11]
	v_mfma_f32_16x16x32_bf16 v[4:7], v[206:209], v[194:197], v[4:7]
	v_mfma_f32_16x16x32_bf16 v[0:3], v[214:217], v[194:197], v[0:3]
	s_setprio 0
	s_add_i32 s65, s65, 2
	s_add_u32 s30, s30, 0x100
	s_addc_u32 s31, s31, 0
	s_add_u32 s63, s63, 0x100
	s_addc_u32 s64, s64, 0
	s_cmp_gt_u32 s65, 13
	s_barrier
.LBB0_633:
	ds_read_b128 v[150:153], v147
	ds_read_b128 v[154:157], v147 offset:1024
	ds_read_b128 v[158:161], v147 offset:2048
	ds_read_b128 v[162:165], v147 offset:3072
	s_add_u32 s34, s30, 0xfffc0080
	s_addc_u32 s35, s31, -1
	s_cmp_eq_u32 s65, 12
	s_cselect_b32 s37, s23, s35
	s_cselect_b32 s36, s61, s34
	s_cselect_b32 s35, s21, s64
	s_cselect_b32 s34, s62, s63
	s_add_i32 m0, s29, 0xc000
	ds_read_b128 v[166:169], v148
	ds_read_b128 v[170:173], v148 offset:1024
	ds_read_b128 v[174:177], v148 offset:2048
	ds_read_b128 v[178:181], v148 offset:3072
	ds_read_b128 v[182:185], v148 offset:4096
	ds_read_b128 v[186:189], v148 offset:5120
	ds_read_b128 v[190:193], v148 offset:6144
	ds_read_b128 v[194:197], v148 offset:7168
	global_load_lds_dwordx4 v136, s[30:31]
	s_add_i32 m0, s29, 0xe000
	s_nop 0
	global_load_lds_dwordx4 v138, s[30:31]
	s_waitcnt lgkmcnt(8)
	s_waitcnt vmcnt(8)
	s_barrier
	s_waitcnt lgkmcnt(0)
	s_setprio 1
	s_waitcnt lgkmcnt(0)
	v_mfma_f32_16x16x32_bf16 v[124:127], v[150:153], v[166:169], v[124:127]
	v_mfma_f32_16x16x32_bf16 v[120:123], v[158:161], v[166:169], v[120:123]
	v_mfma_f32_16x16x32_bf16 v[116:119], v[150:153], v[174:177], v[116:119]
	v_mfma_f32_16x16x32_bf16 v[108:111], v[158:161], v[174:177], v[108:111]
	v_mfma_f32_16x16x32_bf16 v[100:103], v[150:153], v[182:185], v[100:103]
	v_mfma_f32_16x16x32_bf16 v[92:95], v[158:161], v[182:185], v[92:95]
	v_mfma_f32_16x16x32_bf16 v[84:87], v[150:153], v[190:193], v[84:87]
	v_mfma_f32_16x16x32_bf16 v[76:79], v[158:161], v[190:193], v[76:79]
	v_mfma_f32_16x16x32_bf16 v[124:127], v[154:157], v[170:173], v[124:127]
	v_mfma_f32_16x16x32_bf16 v[120:123], v[162:165], v[170:173], v[120:123]
	v_mfma_f32_16x16x32_bf16 v[116:119], v[154:157], v[178:181], v[116:119]
	v_mfma_f32_16x16x32_bf16 v[108:111], v[162:165], v[178:181], v[108:111]
	v_mfma_f32_16x16x32_bf16 v[100:103], v[154:157], v[186:189], v[100:103]
	v_mfma_f32_16x16x32_bf16 v[92:95], v[162:165], v[186:189], v[92:95]
	v_mfma_f32_16x16x32_bf16 v[84:87], v[154:157], v[194:197], v[84:87]
	v_mfma_f32_16x16x32_bf16 v[76:79], v[162:165], v[194:197], v[76:79]
	s_setprio 0
	s_barrier
	s_add_i32 s66, s54, s43
	s_mov_b32 m0, s66
	ds_read_b128 v[202:205], v149
	ds_read_b128 v[206:209], v149 offset:1024
	ds_read_b128 v[210:213], v149 offset:2048
	ds_read_b128 v[214:217], v149 offset:3072
	global_load_lds_dwordx4 v130, s[34:35]
	s_add_i32 m0, s66, 0x2000
	s_nop 0
	global_load_lds_dwordx4 v134, s[34:35]
	s_waitcnt vmcnt(8)
	s_barrier
; #define PG8_STAGE(bufoff, gbase, voff) do { _Pragma("unroll") for (int _i = 0; _i < 2; ++_i) \
;         __builtin_amdgcn_global_load_lds((const unsigned*)((const char*)(gbase) + (voff)[_i]), (LAS unsigned*)(lds + (bufoff) + ldsw + _i * 8192), 16, 0, 0); } while (0)
; #define PG8_LDA(dst, b, h) do { _Pragma("unroll") for (int m = 0; m < 4; ++m) _Pragma("unroll") for (int k = 0; k < 2; ++k) dst[m][k] = *(const LAS bf16x8*)(lds + PG8_SA(b, h) + aoff + m * 2048 + k * 1024); } while (0)
; #define PG8_LDB(dst, b, h) do { _Pragma("unroll") for (int n = 0; n < 2; ++n) _Pragma("unroll") for (int k = 0; k < 2; ++k) dst[n][k] = *(const LAS bf16x8*)(lds + PG8_SB(b, h) + boff + n * 2048 + k * 1024); } while (0)
; #define PG8_MMA(ai, bj, At, Bt) do { __builtin_amdgcn_s_setprio(1); _Pragma("unroll") for (int m = 0; m < 4; ++m) _Pragma("unroll") for (int n = 0; n < 2; ++n) _Pragma("unroll") for (int k = 0; k < 2; ++k) \
;         acc[ai][bj][m][n] = __builtin_amdgcn_mfma_f32_16x16x32_bf16(Bt[n][k], At[m][k], acc[ai][bj][m][n], 0, 0, 0); __builtin_amdgcn_s_setprio(0); } while (0)
; #define PG8_WAIT_V(n) asm volatile("s_waitcnt vmcnt(" #n ")" ::: "memory")
; #define PG8_WAIT_L(n) asm volatile("s_waitcnt lgkmcnt(" #n ")" ::: "memory")
; #define PG8_BAR __builtin_amdgcn_s_barrier()
; #define PG8_SCHED __builtin_amdgcn_sched_barrier(0)
; template <class Epi, class Sched>
; __device__ __forceinline__ void gemm_phase(LAS unsigned char* lds, const Gemm g, const Sched& S, const Epi& E) {
;     ...
;             PG8_BAR; PG8_WAIT_L(0); PG8_MMA(0, 1, At, B1); PG8_BAR;
;             PG8_LDA(At, 0, 1); PG8_STAGE(PG8_SA(0, 0), a2, voffA);
;             PG8_BAR; PG8_WAIT_L(0); PG8_MMA(1, 0, At, B0); PG8_BAR; PG8_SCHED;
;             PG8_STAGE(PG8_SB(0, 1), b2 + hstep, voffB);
;             PG8_WAIT_V(6); PG8_BAR; PG8_MMA(1, 1, At, B1); PG8_BAR;
;             PG8_LDB(B0, 1, 0); PG8_SCHED; PG8_LDA(At, 1, 0); PG8_STAGE(PG8_SA(0, 1), a2 + hstep, voffA);
;             PG8_WAIT_L(8); PG8_BAR; PG8_WAIT_L(0); PG8_MMA(0, 0, At, B0); PG8_BAR; PG8_SCHED;
	s_waitcnt lgkmcnt(0)
	s_setprio 1
	s_waitcnt lgkmcnt(0)
	v_mfma_f32_16x16x32_bf16 v[112:115], v[202:205], v[166:169], v[112:115]
	v_mfma_f32_16x16x32_bf16 v[104:107], v[210:213], v[166:169], v[104:107]
	v_mfma_f32_16x16x32_bf16 v[96:99], v[202:205], v[174:177], v[96:99]
	v_mfma_f32_16x16x32_bf16 v[88:91], v[210:213], v[174:177], v[88:91]
	v_mfma_f32_16x16x32_bf16 v[80:83], v[202:205], v[182:185], v[80:83]
	v_mfma_f32_16x16x32_bf16 v[72:75], v[210:213], v[182:185], v[72:75]
	v_mfma_f32_16x16x32_bf16 v[68:71], v[202:205], v[190:193], v[68:71]
	v_mfma_f32_16x16x32_bf16 v[64:67], v[210:213], v[190:193], v[64:67]
	v_mfma_f32_16x16x32_bf16 v[112:115], v[206:209], v[170:173], v[112:115]
	v_mfma_f32_16x16x32_bf16 v[104:107], v[214:217], v[170:173], v[104:107]
	v_mfma_f32_16x16x32_bf16 v[96:99], v[206:209], v[178:181], v[96:99]
	v_mfma_f32_16x16x32_bf16 v[88:91], v[214:217], v[178:181], v[88:91]
	v_mfma_f32_16x16x32_bf16 v[80:83], v[206:209], v[186:189], v[80:83]
	v_mfma_f32_16x16x32_bf16 v[72:75], v[214:217], v[186:189], v[72:75]
	v_mfma_f32_16x16x32_bf16 v[68:71], v[206:209], v[194:197], v[68:71]
	v_mfma_f32_16x16x32_bf16 v[64:67], v[214:217], v[194:197], v[64:67]
	s_setprio 0
	s_mov_b32 m0, s29
	v_lshl_add_u64 v[220:221], s[36:37], 0, v[128:129]
	s_barrier
	ds_read_b128 v[166:169], v148 offset:16384
	ds_read_b128 v[170:173], v148 offset:17408
	ds_read_b128 v[174:177], v148 offset:18432
	ds_read_b128 v[178:181], v148 offset:19456
	ds_read_b128 v[182:185], v148 offset:20480
	ds_read_b128 v[186:189], v148 offset:21504
	ds_read_b128 v[190:193], v148 offset:22528
	ds_read_b128 v[194:197], v148 offset:23552
	global_load_lds_dwordx4 v128, s[36:37]
	v_lshl_add_u64 v[222:223], s[36:37], 0, v[132:133]
	s_mov_b32 m0, s44
	s_nop 0
	global_load_lds_dwordx4 v132, s[36:37]
	s_barrier
	s_waitcnt lgkmcnt(0)
	s_setprio 1
	s_waitcnt lgkmcnt(0)
	v_mfma_f32_16x16x32_bf16 v[60:63], v[150:153], v[166:169], v[60:63]
	v_mfma_f32_16x16x32_bf16 v[56:59], v[158:161], v[166:169], v[56:59]
	v_mfma_f32_16x16x32_bf16 v[52:55], v[150:153], v[174:177], v[52:55]
	v_mfma_f32_16x16x32_bf16 v[44:47], v[158:161], v[174:177], v[44:47]
	v_mfma_f32_16x16x32_bf16 v[36:39], v[150:153], v[182:185], v[36:39]
	v_mfma_f32_16x16x32_bf16 v[28:31], v[158:161], v[182:185], v[28:31]
	v_mfma_f32_16x16x32_bf16 v[20:23], v[150:153], v[190:193], v[20:23]
	v_mfma_f32_16x16x32_bf16 v[12:15], v[158:161], v[190:193], v[12:15]
	v_mfma_f32_16x16x32_bf16 v[60:63], v[154:157], v[170:173], v[60:63]
	v_mfma_f32_16x16x32_bf16 v[56:59], v[162:165], v[170:173], v[56:59]
	v_mfma_f32_16x16x32_bf16 v[52:55], v[154:157], v[178:181], v[52:55]
	v_mfma_f32_16x16x32_bf16 v[44:47], v[162:165], v[178:181], v[44:47]
	v_mfma_f32_16x16x32_bf16 v[36:39], v[154:157], v[186:189], v[36:39]
	v_mfma_f32_16x16x32_bf16 v[28:31], v[162:165], v[186:189], v[28:31]
	v_mfma_f32_16x16x32_bf16 v[20:23], v[154:157], v[194:197], v[20:23]
	v_mfma_f32_16x16x32_bf16 v[12:15], v[162:165], v[194:197], v[12:15]
	s_setprio 0
	s_barrier
	s_add_u32 s66, s34, 0x40000
	s_addc_u32 s67, s35, 0
	s_add_i32 s68, s55, s43
	s_mov_b32 m0, s68
	s_nop 0
	global_load_lds_dwordx4 v130, s[66:67]
	s_add_i32 m0, s68, 0x2000
	s_nop 0
	global_load_lds_dwordx4 v134, s[66:67]
	s_add_u32 s36, s36, 0x40000
	s_addc_u32 s37, s37, 0
	s_mov_b32 m0, s45
	s_nop 0
	global_load_lds_dwordx4 v128, s[36:37]
	s_mov_b32 m0, s46
	s_nop 0
	global_load_lds_dwordx4 v132, s[36:37]
	s_waitcnt vmcnt(10)
	s_barrier
	s_setprio 1
	v_mfma_f32_16x16x32_bf16 v[48:51], v[202:205], v[166:169], v[48:51]
	v_mfma_f32_16x16x32_bf16 v[40:43], v[210:213], v[166:169], v[40:43]
	v_mfma_f32_16x16x32_bf16 v[32:35], v[202:205], v[174:177], v[32:35]
	v_mfma_f32_16x16x32_bf16 v[24:27], v[210:213], v[174:177], v[24:27]
	v_mfma_f32_16x16x32_bf16 v[16:19], v[202:205], v[182:185], v[16:19]
	v_mfma_f32_16x16x32_bf16 v[8:11], v[210:213], v[182:185], v[8:11]
	v_mfma_f32_16x16x32_bf16 v[4:7], v[202:205], v[190:193], v[4:7]
	v_mfma_f32_16x16x32_bf16 v[0:3], v[210:213], v[190:193], v[0:3]
	v_mfma_f32_16x16x32_bf16 v[48:51], v[206:209], v[170:173], v[48:51]
	v_mfma_f32_16x16x32_bf16 v[40:43], v[214:217], v[170:173], v[40:43]
	v_mfma_f32_16x16x32_bf16 v[32:35], v[206:209], v[178:181], v[32:35]
	v_mfma_f32_16x16x32_bf16 v[24:27], v[214:217], v[178:181], v[24:27]
	v_mfma_f32_16x16x32_bf16 v[16:19], v[206:209], v[186:189], v[16:19]
	v_mfma_f32_16x16x32_bf16 v[8:11], v[214:217], v[186:189], v[8:11]
	v_mfma_f32_16x16x32_bf16 v[4:7], v[206:209], v[194:197], v[4:7]
	v_mfma_f32_16x16x32_bf16 v[0:3], v[214:217], v[194:197], v[0:3]
	s_setprio 0
	s_add_i32 s66, 0, 0x18000
	v_add_u32_e32 v162, s66, v146
	s_barrier
	ds_read_b128 v[150:153], v162
	ds_read_b128 v[154:157], v162 offset:1024
	ds_read_b128 v[158:161], v162 offset:2048
	ds_read_b128 v[162:165], v162 offset:3072
	ds_read_b128 v[166:169], v148 offset:32768
	ds_read_b128 v[170:173], v148 offset:33792
	ds_read_b128 v[174:177], v148 offset:34816
	ds_read_b128 v[178:181], v148 offset:35840
	ds_read_b128 v[182:185], v148 offset:36864
	ds_read_b128 v[186:189], v148 offset:37888
	ds_read_b128 v[190:193], v148 offset:38912
	ds_read_b128 v[194:197], v148 offset:39936
	s_waitcnt lgkmcnt(8)
	s_waitcnt vmcnt(8)
	s_barrier
; #define PG8_STAGE(bufoff, gbase, voff) do { _Pragma("unroll") for (int _i = 0; _i < 2; ++_i) \
;         __builtin_amdgcn_global_load_lds((const unsigned*)((const char*)(gbase) + (voff)[_i]), (LAS unsigned*)(lds + (bufoff) + ldsw + _i * 8192), 16, 0, 0); } while (0)
; #define PG8_LDA(dst, b, h) do { _Pragma("unroll") for (int m = 0; m < 4; ++m) _Pragma("unroll") for (int k = 0; k < 2; ++k) dst[m][k] = *(const LAS bf16x8*)(lds + PG8_SA(b, h) + aoff + m * 2048 + k * 1024); } while (0)
; #define PG8_LDB(dst, b, h) do { _Pragma("unroll") for (int n = 0; n < 2; ++n) _Pragma("unroll") for (int k = 0; k < 2; ++k) dst[n][k] = *(const LAS bf16x8*)(lds + PG8_SB(b, h) + boff + n * 2048 + k * 1024); } while (0)
; #define PG8_MMA(ai, bj, At, Bt) do { __builtin_amdgcn_s_setprio(1); _Pragma("unroll") for (int m = 0; m < 4; ++m) _Pragma("unroll") for (int n = 0; n < 2; ++n) _Pragma("unroll") for (int k = 0; k < 2; ++k) \
;         acc[ai][bj][m][n] = __builtin_amdgcn_mfma_f32_16x16x32_bf16(Bt[n][k], At[m][k], acc[ai][bj][m][n], 0, 0, 0); __builtin_amdgcn_s_setprio(0); } while (0)
; #define PG8_WAIT_V(n) asm volatile("s_waitcnt vmcnt(" #n ")" ::: "memory")
; #define PG8_WAIT_L(n) asm volatile("s_waitcnt lgkmcnt(" #n ")" ::: "memory")
; #define PG8_BAR __builtin_amdgcn_s_barrier()
; #define PG8_SCHED __builtin_amdgcn_sched_barrier(0)
; template <class Epi, class Sched>
; __device__ __forceinline__ void gemm_phase(LAS unsigned char* lds, const Gemm g, const Sched& S, const Epi& E) {
;     ...
;             PG8_WAIT_L(8); PG8_BAR; PG8_WAIT_L(0); PG8_MMA(0, 0, At, B0); PG8_BAR; PG8_SCHED;
;             PG8_LDB(B1, 1, 1); PG8_STAGE(PG8_SB(1, 0), b3, voffB);
;             PG8_BAR; PG8_WAIT_L(0); PG8_MMA(0, 1, At, B1); PG8_BAR;
;             PG8_LDA(At, 1, 1); PG8_STAGE(PG8_SA(1, 0), a3, voffA);
;             PG8_BAR; PG8_WAIT_L(0); PG8_MMA(1, 0, At, B0); PG8_BAR; PG8_SCHED;
;             PG8_STAGE(PG8_SB(1, 1), b3 + hstep, voffB);
;             PG8_WAIT_V(6); PG8_BAR; PG8_MMA(1, 1, At, B1); PG8_BAR;
	s_waitcnt lgkmcnt(0)
	s_setprio 1
	s_waitcnt lgkmcnt(0)
	v_mfma_f32_16x16x32_bf16 v[124:127], v[150:153], v[166:169], v[124:127]
	v_mfma_f32_16x16x32_bf16 v[120:123], v[158:161], v[166:169], v[120:123]
	v_mfma_f32_16x16x32_bf16 v[116:119], v[150:153], v[174:177], v[116:119]
	v_mfma_f32_16x16x32_bf16 v[108:111], v[158:161], v[174:177], v[108:111]
	v_mfma_f32_16x16x32_bf16 v[100:103], v[150:153], v[182:185], v[100:103]
	v_mfma_f32_16x16x32_bf16 v[92:95], v[158:161], v[182:185], v[92:95]
	v_mfma_f32_16x16x32_bf16 v[84:87], v[150:153], v[190:193], v[84:87]
	v_mfma_f32_16x16x32_bf16 v[76:79], v[158:161], v[190:193], v[76:79]
	v_mfma_f32_16x16x32_bf16 v[124:127], v[154:157], v[170:173], v[124:127]
	v_mfma_f32_16x16x32_bf16 v[120:123], v[162:165], v[170:173], v[120:123]
	v_mfma_f32_16x16x32_bf16 v[116:119], v[154:157], v[178:181], v[116:119]
	v_mfma_f32_16x16x32_bf16 v[108:111], v[162:165], v[178:181], v[108:111]
	v_mfma_f32_16x16x32_bf16 v[100:103], v[154:157], v[186:189], v[100:103]
	v_mfma_f32_16x16x32_bf16 v[92:95], v[162:165], v[186:189], v[92:95]
	v_mfma_f32_16x16x32_bf16 v[84:87], v[154:157], v[194:197], v[84:87]
	v_mfma_f32_16x16x32_bf16 v[76:79], v[162:165], v[194:197], v[76:79]
	s_setprio 0
	s_barrier
	s_add_i32 s36, 0, 0x1c000
	s_add_i32 s37, s66, s43
	v_add_u32_e32 v214, s36, v146
	s_add_u32 s4, s34, 0x80
	s_addc_u32 s5, s35, 0
	s_mov_b32 m0, s37
	ds_read_b128 v[202:205], v214
	ds_read_b128 v[206:209], v214 offset:1024
	ds_read_b128 v[210:213], v214 offset:2048
	ds_read_b128 v[214:217], v214 offset:3072
	global_load_lds_dwordx4 v130, s[4:5]
	s_add_i32 m0, s37, 0x2000
	s_nop 0
	global_load_lds_dwordx4 v134, s[4:5]
	s_waitcnt vmcnt(8)
	s_barrier
	s_waitcnt lgkmcnt(0)
	s_setprio 1
	s_waitcnt lgkmcnt(0)
	v_mfma_f32_16x16x32_bf16 v[112:115], v[202:205], v[166:169], v[112:115]
	v_mfma_f32_16x16x32_bf16 v[104:107], v[210:213], v[166:169], v[104:107]
	v_mfma_f32_16x16x32_bf16 v[96:99], v[202:205], v[174:177], v[96:99]
	v_mfma_f32_16x16x32_bf16 v[88:91], v[210:213], v[174:177], v[88:91]
	v_mfma_f32_16x16x32_bf16 v[80:83], v[202:205], v[182:185], v[80:83]
	v_mfma_f32_16x16x32_bf16 v[72:75], v[210:213], v[182:185], v[72:75]
	v_mfma_f32_16x16x32_bf16 v[68:71], v[202:205], v[190:193], v[68:71]
	v_mfma_f32_16x16x32_bf16 v[64:67], v[210:213], v[190:193], v[64:67]
	v_mfma_f32_16x16x32_bf16 v[112:115], v[206:209], v[170:173], v[112:115]
	v_mfma_f32_16x16x32_bf16 v[104:107], v[214:217], v[170:173], v[104:107]
	v_mfma_f32_16x16x32_bf16 v[96:99], v[206:209], v[178:181], v[96:99]
	v_mfma_f32_16x16x32_bf16 v[88:91], v[214:217], v[178:181], v[88:91]
	v_mfma_f32_16x16x32_bf16 v[80:83], v[206:209], v[186:189], v[80:83]
	v_mfma_f32_16x16x32_bf16 v[72:75], v[214:217], v[186:189], v[72:75]
	v_mfma_f32_16x16x32_bf16 v[68:71], v[206:209], v[194:197], v[68:71]
	v_mfma_f32_16x16x32_bf16 v[64:67], v[214:217], v[194:197], v[64:67]
	s_setprio 0
	s_mov_b32 m0, s51
	s_mov_b64 s[4:5], 0x80
	v_lshl_add_u64 v[198:199], v[220:221], 0, s[4:5]
	s_barrier
	ds_read_b128 v[166:169], v148 offset:49152
	ds_read_b128 v[170:173], v148 offset:50176
	ds_read_b128 v[174:177], v148 offset:51200
	ds_read_b128 v[178:181], v148 offset:52224
	ds_read_b128 v[182:185], v148 offset:53248
	ds_read_b128 v[186:189], v148 offset:54272
	ds_read_b128 v[190:193], v148 offset:55296
	ds_read_b128 v[194:197], v148 offset:56320
	global_load_lds_dwordx4 v[198:199], off
	v_lshl_add_u64 v[198:199], v[222:223], 0, s[4:5]
	s_mov_b32 m0, s52
	s_nop 0
	global_load_lds_dwordx4 v[198:199], off
	s_barrier
	s_waitcnt lgkmcnt(0)
	s_setprio 1
	s_waitcnt lgkmcnt(0)
	v_mfma_f32_16x16x32_bf16 v[60:63], v[150:153], v[166:169], v[60:63]
	v_mfma_f32_16x16x32_bf16 v[56:59], v[158:161], v[166:169], v[56:59]
	v_mfma_f32_16x16x32_bf16 v[52:55], v[150:153], v[174:177], v[52:55]
	v_mfma_f32_16x16x32_bf16 v[44:47], v[158:161], v[174:177], v[44:47]
	v_mfma_f32_16x16x32_bf16 v[36:39], v[150:153], v[182:185], v[36:39]
	v_mfma_f32_16x16x32_bf16 v[28:31], v[158:161], v[182:185], v[28:31]
	v_mfma_f32_16x16x32_bf16 v[20:23], v[150:153], v[190:193], v[20:23]
	v_mfma_f32_16x16x32_bf16 v[12:15], v[158:161], v[190:193], v[12:15]
	v_mfma_f32_16x16x32_bf16 v[60:63], v[154:157], v[170:173], v[60:63]
	v_mfma_f32_16x16x32_bf16 v[56:59], v[162:165], v[170:173], v[56:59]
	v_mfma_f32_16x16x32_bf16 v[52:55], v[154:157], v[178:181], v[52:55]
	v_mfma_f32_16x16x32_bf16 v[44:47], v[162:165], v[178:181], v[44:47]
	v_mfma_f32_16x16x32_bf16 v[36:39], v[154:157], v[186:189], v[36:39]
	v_mfma_f32_16x16x32_bf16 v[28:31], v[162:165], v[186:189], v[28:31]
	v_mfma_f32_16x16x32_bf16 v[20:23], v[154:157], v[194:197], v[20:23]
	v_mfma_f32_16x16x32_bf16 v[12:15], v[162:165], v[194:197], v[12:15]
	s_setprio 0
	s_barrier
	s_add_u32 s34, s34, 0x40080
	s_addc_u32 s35, s35, 0
	s_add_i32 s36, s36, s43
	s_mov_b32 m0, s36
	s_nop 0
	global_load_lds_dwordx4 v130, s[34:35]
	s_add_i32 m0, s36, 0x2000
	s_nop 0
	global_load_lds_dwordx4 v134, s[34:35]
	s_waitcnt vmcnt(8)
	s_barrier
; __device__ __forceinline__ unsigned cvt_pk_bf16(float lo, float hi) { unsigned r; asm volatile("v_cvt_pk_bf16_f32 %0, %1, %2" : "=v"(r) : "v"(lo), "v"(hi)); return r; }
; template <class Epi, class Sched>
; __device__ __forceinline__ void gemm_phase(LAS unsigned char* lds, const Gemm g, const Sched& S, const Epi& E) {
;     ...
;         if (!has_next) break;
; #pragma unroll
;         for (int a = 0; a < 2; ++a)
; #pragma unroll
;             for (int b = 0; b < 2; ++b)
; #pragma unroll
;                 for (int m = 0; m < 4; ++m)
; #pragma unroll
;                     for (int n = 0; n < 2; ++n) acc[a][b][m][n] = (f32x4){0.f, 0.f, 0.f, 0.f};
;         cur = nxt; cA = nA; cB = nB; ++ui;
;     __device__ __forceinline__ void operator()(const AccT& acc, const Unit& u, int wr, int wc, int fr, int fq) const {
;     ...
; #pragma unroll
;         for (int ai = 0; ai < 2; ++ai)
; #pragma unroll
;             for (int m = 0; m < 4; ++m) {
;                 const int r = rbase + ai * 128 + m * 16;
; #pragma unroll
;                 for (int bj = 0; bj < 2; ++bj) {
;                     const int t0 = tb + bj * 128;
;                     const f32x4 v0 = acc[ai][bj][m][0], v1 = acc[ai][bj][m][1];
;                     u32x4 w; w.x = cvt_pk_bf16(v0[0], v0[1]); w.y = cvt_pk_bf16(v0[2], v0[3]); w.z = cvt_pk_bf16(v1[0], v1[1]); w.w = cvt_pk_bf16(v1[2], v1[3]);
;                     *(u32x4*)(VT + (size_t)r * NT + t0) = w;
;                 }
;             }
	s_setprio 1
	v_mfma_f32_16x16x32_bf16 v[48:51], v[202:205], v[166:169], v[48:51]
	v_mfma_f32_16x16x32_bf16 v[40:43], v[210:213], v[166:169], v[40:43]
	v_mfma_f32_16x16x32_bf16 v[32:35], v[202:205], v[174:177], v[32:35]
	v_mfma_f32_16x16x32_bf16 v[24:27], v[210:213], v[174:177], v[24:27]
	v_mfma_f32_16x16x32_bf16 v[16:19], v[202:205], v[182:185], v[16:19]
	v_mfma_f32_16x16x32_bf16 v[8:11], v[210:213], v[182:185], v[8:11]
	v_mfma_f32_16x16x32_bf16 v[4:7], v[202:205], v[190:193], v[4:7]
	v_mfma_f32_16x16x32_bf16 v[0:3], v[210:213], v[190:193], v[0:3]
	v_mfma_f32_16x16x32_bf16 v[48:51], v[206:209], v[170:173], v[48:51]
	v_mfma_f32_16x16x32_bf16 v[40:43], v[214:217], v[170:173], v[40:43]
	v_mfma_f32_16x16x32_bf16 v[32:35], v[206:209], v[178:181], v[32:35]
	v_mfma_f32_16x16x32_bf16 v[24:27], v[214:217], v[178:181], v[24:27]
	v_mfma_f32_16x16x32_bf16 v[16:19], v[206:209], v[186:189], v[16:19]
	v_mfma_f32_16x16x32_bf16 v[8:11], v[214:217], v[186:189], v[8:11]
	v_mfma_f32_16x16x32_bf16 v[4:7], v[206:209], v[194:197], v[4:7]
	v_mfma_f32_16x16x32_bf16 v[0:3], v[214:217], v[194:197], v[0:3]
	s_setprio 0
	s_add_i32 s65, s65, 2
	s_add_u32 s30, s30, 0x100
	s_addc_u32 s31, s31, 0
	s_add_u32 s63, s63, 0x100
	s_addc_u32 s64, s64, 0
	s_cmp_gt_u32 s65, 13
	s_barrier
	s_cbranch_scc0 .LBB0_633
	v_mov_b32_e32 v150, v144
	v_mov_b32_e32 v151, v145
	s_lshl_b32 s21, s28, 8
	s_add_i32 s21, s21, s48
	v_add_u32_e32 v150, s21, v150
	s_lshl_b32 s21, s60, 8
	s_or_b32 s21, s21, s49
	v_lshl_add_u32 v152, v151, 3, s21
	v_ashrrev_i32_e32 v151, 31, v150
	v_cvt_pk_bf16_f32 v124, v124, v125
	v_cvt_pk_bf16_f32 v125, v126, v127
	v_cvt_pk_bf16_f32 v126, v120, v121
	v_lshlrev_b64 v[120:121], 17, v[150:151]
	v_lshl_add_u64 v[120:121], s[0:1], 0, v[120:121]
	v_ashrrev_i32_e32 v153, 31, v152
	v_lshl_add_u64 v[120:121], v[152:153], 1, v[120:121]
	s_mov_b32 s21, 0x200000
	v_cvt_pk_bf16_f32 v127, v122, v123
	global_store_dwordx4 v[120:121], v[124:127], off
	v_cvt_pk_bf16_f32 v112, v112, v113
	v_cvt_pk_bf16_f32 v113, v114, v115
	v_cvt_pk_bf16_f32 v114, v104, v105
	v_cvt_pk_bf16_f32 v115, v106, v107
	global_store_dwordx4 v[120:121], v[112:115], off offset:256
	v_cvt_pk_bf16_f32 v104, v116, v117
	v_cvt_pk_bf16_f32 v105, v118, v119
	v_cvt_pk_bf16_f32 v106, v108, v109
	v_cvt_pk_bf16_f32 v107, v110, v111
	s_mov_b64 s[30:31], 0x200000
	v_add_co_u32_e32 v110, vcc, s21, v120
	v_lshl_add_u64 v[108:109], v[120:121], 0, s[30:31]
	s_nop 0
	v_addc_co_u32_e32 v111, vcc, 0, v121, vcc
	s_mov_b32 s21, 0x400000
	global_store_dwordx4 v[110:111], v[104:107], off
	v_cvt_pk_bf16_f32 v96, v96, v97
	v_cvt_pk_bf16_f32 v97, v98, v99
	v_cvt_pk_bf16_f32 v98, v88, v89
	v_cvt_pk_bf16_f32 v99, v90, v91
	global_store_dwordx4 v[108:109], v[96:99], off offset:256
	v_cvt_pk_bf16_f32 v88, v100, v101
	v_cvt_pk_bf16_f32 v89, v102, v103
	v_cvt_pk_bf16_f32 v90, v92, v93
	v_cvt_pk_bf16_f32 v91, v94, v95
	s_mov_b64 s[30:31], 0x400000
	v_add_co_u32_e32 v94, vcc, s21, v120
	v_lshl_add_u64 v[92:93], v[120:121], 0, s[30:31]
	s_nop 0
	v_addc_co_u32_e32 v95, vcc, 0, v121, vcc
	s_mov_b32 s21, 0x600000
	global_store_dwordx4 v[94:95], v[88:91], off
	v_cvt_pk_bf16_f32 v80, v80, v81
	v_cvt_pk_bf16_f32 v81, v82, v83
	v_cvt_pk_bf16_f32 v82, v72, v73
	v_cvt_pk_bf16_f32 v83, v74, v75
	global_store_dwordx4 v[92:93], v[80:83], off offset:256
	v_cvt_pk_bf16_f32 v72, v84, v85
	v_cvt_pk_bf16_f32 v73, v86, v87
	v_cvt_pk_bf16_f32 v74, v76, v77
	v_cvt_pk_bf16_f32 v75, v78, v79
	s_mov_b64 s[30:31], 0x600000
	v_add_co_u32_e32 v78, vcc, s21, v120
	v_lshl_add_u64 v[76:77], v[120:121], 0, s[30:31]
	s_nop 0
	v_addc_co_u32_e32 v79, vcc, 0, v121, vcc
	global_store_dwordx4 v[78:79], v[72:75], off
	v_cvt_pk_bf16_f32 v68, v68, v69
	v_cvt_pk_bf16_f32 v69, v70, v71
	v_cvt_pk_bf16_f32 v70, v64, v65
	v_cvt_pk_bf16_f32 v71, v66, v67
	global_store_dwordx4 v[76:77], v[68:71], off offset:256
	v_cvt_pk_bf16_f32 v60, v60, v61
	v_cvt_pk_bf16_f32 v61, v62, v63
	v_cvt_pk_bf16_f32 v62, v56, v57
	v_cvt_pk_bf16_f32 v63, v58, v59
	s_mov_b64 s[30:31], 0x1000000
	v_add_co_u32_e32 v58, vcc, s56, v120
	v_lshl_add_u64 v[56:57], v[120:121], 0, s[30:31]
	s_nop 0
	v_addc_co_u32_e32 v59, vcc, 0, v121, vcc
	global_store_dwordx4 v[58:59], v[60:63], off
	v_cvt_pk_bf16_f32 v48, v48, v49
	v_cvt_pk_bf16_f32 v49, v50, v51
	v_cvt_pk_bf16_f32 v50, v40, v41
	v_cvt_pk_bf16_f32 v51, v42, v43
	global_store_dwordx4 v[56:57], v[48:51], off offset:256
	v_cvt_pk_bf16_f32 v40, v52, v53
	v_cvt_pk_bf16_f32 v41, v54, v55
	v_cvt_pk_bf16_f32 v42, v44, v45
	v_cvt_pk_bf16_f32 v43, v46, v47
	v_add_co_u32_e32 v46, vcc, s57, v120
	v_lshl_add_u64 v[44:45], v[120:121], 0, s[6:7]
	s_nop 0
	v_addc_co_u32_e32 v47, vcc, 0, v121, vcc
	global_store_dwordx4 v[46:47], v[40:43], off
	v_cvt_pk_bf16_f32 v32, v32, v33
	v_cvt_pk_bf16_f32 v33, v34, v35
	v_cvt_pk_bf16_f32 v34, v24, v25
	v_cvt_pk_bf16_f32 v35, v26, v27
	global_store_dwordx4 v[44:45], v[32:35], off offset:256
	v_cvt_pk_bf16_f32 v24, v36, v37
	v_cvt_pk_bf16_f32 v25, v38, v39
	v_cvt_pk_bf16_f32 v26, v28, v29
	v_cvt_pk_bf16_f32 v27, v30, v31
	v_add_co_u32_e32 v30, vcc, s58, v120
	v_lshl_add_u64 v[28:29], v[120:121], 0, s[8:9]
	s_nop 0
	v_addc_co_u32_e32 v31, vcc, 0, v121, vcc
	global_store_dwordx4 v[30:31], v[24:27], off
	v_cvt_pk_bf16_f32 v16, v16, v17
	v_cvt_pk_bf16_f32 v17, v18, v19
	v_cvt_pk_bf16_f32 v18, v8, v9
	v_cvt_pk_bf16_f32 v19, v10, v11
	global_store_dwordx4 v[28:29], v[16:19], off offset:256
	v_cvt_pk_bf16_f32 v8, v20, v21
	v_cvt_pk_bf16_f32 v9, v22, v23
	v_cvt_pk_bf16_f32 v10, v12, v13
	v_cvt_pk_bf16_f32 v11, v14, v15
	v_add_co_u32_e32 v14, vcc, s59, v120
	v_lshl_add_u64 v[12:13], v[120:121], 0, s[16:17]
	s_nop 0
	v_addc_co_u32_e32 v15, vcc, 0, v121, vcc
	s_and_b64 vcc, exec, s[2:3]
	s_mov_b32 s60, s20
	s_mov_b32 s28, s22
	s_mov_b64 s[34:35], s[26:27]
	s_mov_b64 s[30:31], s[24:25]
	global_store_dwordx4 v[14:15], v[8:11], off
	v_cvt_pk_bf16_f32 v4, v4, v5
	v_cvt_pk_bf16_f32 v5, v6, v7
	v_cvt_pk_bf16_f32 v6, v0, v1
	v_cvt_pk_bf16_f32 v7, v2, v3
	global_store_dwordx4 v[12:13], v[4:7], off offset:256
	s_cbranch_vccz .LBB0_626
	s_waitcnt vmcnt(0)
	s_cmpk_gt_u32 s33, 0xff
	s_cbranch_scc1 .LBB0_637
	s_barrier

; #define PG8_STAGE(bufoff, gbase, voff) do { _Pragma("unroll") for (int _i = 0; _i < 2; ++_i) \
;         __builtin_amdgcn_global_load_lds((const unsigned*)((const char*)(gbase) + (voff)[_i]), (LAS unsigned*)(lds + (bufoff) + ldsw + _i * 8192), 16, 0, 0); } while (0)
; #define PG8_LDA(dst, b, h) do { _Pragma("unroll") for (int m = 0; m < 4; ++m) _Pragma("unroll") for (int k = 0; k < 2; ++k) dst[m][k] = *(const LAS bf16x8*)(lds + PG8_SA(b, h) + aoff + m * 2048 + k * 1024); } while (0)
; #define PG8_LDB(dst, b, h) do { _Pragma("unroll") for (int n = 0; n < 2; ++n) _Pragma("unroll") for (int k = 0; k < 2; ++k) dst[n][k] = *(const LAS bf16x8*)(lds + PG8_SB(b, h) + boff + n * 2048 + k * 1024); } while (0)
; #define PG8_MMA(ai, bj, At, Bt) do { __builtin_amdgcn_s_setprio(1); _Pragma("unroll") for (int m = 0; m < 4; ++m) _Pragma("unroll") for (int n = 0; n < 2; ++n) _Pragma("unroll") for (int k = 0; k < 2; ++k) \
;         acc[ai][bj][m][n] = __builtin_amdgcn_mfma_f32_16x16x32_bf16(Bt[n][k], At[m][k], acc[ai][bj][m][n], 0, 0, 0); __builtin_amdgcn_s_setprio(0); } while (0)
; #define PG8_WAIT_L(n) asm volatile("s_waitcnt lgkmcnt(" #n ")" ::: "memory")
; template <class Epi, class Sched>
; __device__ __forceinline__ void gemm_phase(LAS unsigned char* lds, const Gemm g, const Sched& S, const Epi& E) {
;     ...
;         const bool has_next = S.next(ui + 1, nxt);
;         const char* nA = has_next ? (const char*)g.A + (size_t)nxt.pm * tstep : cA; const char* nB = has_next ? (const char*)g.Bt + (size_t)nxt.pn * tstep : cB;
;         for (int t = 0; t < nt; t += 2) {
;             const bool last = (t == nt - 2);
;             const char* a1 = cA + (size_t)(t + 1) * kstep;
;             const char* a2 = last ? nA : cA + (size_t)(t + 2) * kstep; const char* b2 = last ? nB : cB + (size_t)(t + 2) * kstep;
;             const char* a3 = a2 + kstep; const char* b3 = b2 + kstep;
;             PG8_LDB(B0, 0, 0); PG8_SCHED; PG8_LDA(At, 0, 0); PG8_STAGE(PG8_SA(1, 1), a1 + hstep, voffA);
;             PG8_WAIT_L(8); PG8_BAR; PG8_WAIT_L(0); PG8_MMA(0, 0, At, B0); PG8_BAR; PG8_SCHED;
;             PG8_LDB(B1, 0, 1); PG8_STAGE(PG8_SB(0, 0), b2, voffB);
;             PG8_BAR; PG8_WAIT_L(0); PG8_MMA(0, 1, At, B1); PG8_BAR;
;             PG8_LDA(At, 0, 1); PG8_STAGE(PG8_SA(0, 0), a2, voffA);
;             PG8_BAR; PG8_WAIT_L(0); PG8_MMA(1, 0, At, B0); PG8_BAR; PG8_SCHED;
.LBB0_652:
	s_ashr_i32 s9, s8, 31
	v_cmp_lt_i64_e32 vcc, s[16:17], v[142:143]
	s_lshl_b64 s[16:17], s[8:9], 19
	s_add_u32 s16, s14, s16
	s_addc_u32 s17, s15, s17
	s_and_b64 s[18:19], vcc, exec
	s_cselect_b32 s9, s17, s23
	s_cselect_b32 s48, s16, s22
	s_ashr_i32 s7, s6, 31
	s_lshl_b64 s[18:19], s[6:7], 19
	s_add_u32 s18, s12, s18
	s_addc_u32 s19, s13, s19
	s_and_b64 s[26:27], vcc, exec
	s_cselect_b32 s7, s19, s25
	s_cselect_b32 s49, s18, s24
	s_add_u32 s22, s22, 0x40080
	s_addc_u32 s23, s23, 0
	s_add_u32 s51, s24, 0x100
	s_addc_u32 s52, s25, 0
	s_mov_b32 s53, -2
	s_waitcnt lgkmcnt(0)
	ds_read_b128 v[152:155], v149
	ds_read_b128 v[156:159], v149 offset:1024
	ds_read_b128 v[160:163], v149 offset:2048
	ds_read_b128 v[164:167], v149 offset:3072
	s_add_u32 s24, s22, 0xfffc0080
	s_addc_u32 s25, s23, -1
	s_cmp_eq_u32 s53, 12
	s_cselect_b32 s27, s9, s25
	s_cselect_b32 s26, s48, s24
	s_cselect_b32 s25, s7, s52
	s_cselect_b32 s24, s49, s51
	s_add_i32 m0, s21, 0xc000
	ds_read_b128 v[168:171], v150
	ds_read_b128 v[172:175], v150 offset:1024
	ds_read_b128 v[176:179], v150 offset:2048
	ds_read_b128 v[180:183], v150 offset:3072
	ds_read_b128 v[184:187], v150 offset:4096
	ds_read_b128 v[188:191], v150 offset:5120
	ds_read_b128 v[192:195], v150 offset:6144
	ds_read_b128 v[196:199], v150 offset:7168
	global_load_lds_dwordx4 v138, s[22:23]
	s_add_i32 m0, s21, 0xe000
	s_nop 0
	global_load_lds_dwordx4 v140, s[22:23]
	s_waitcnt lgkmcnt(8)
	s_waitcnt vmcnt(8)
	s_barrier
	s_waitcnt lgkmcnt(0)
	s_setprio 1
	s_waitcnt lgkmcnt(0)
	v_mfma_f32_16x16x32_bf16 v[124:127], v[152:155], v[168:171], 0
	v_mfma_f32_16x16x32_bf16 v[120:123], v[160:163], v[168:171], 0
	v_mfma_f32_16x16x32_bf16 v[112:115], v[152:155], v[176:179], 0
	v_mfma_f32_16x16x32_bf16 v[104:107], v[160:163], v[176:179], 0
	v_mfma_f32_16x16x32_bf16 v[96:99], v[152:155], v[184:187], 0
	v_mfma_f32_16x16x32_bf16 v[88:91], v[160:163], v[184:187], 0
	v_mfma_f32_16x16x32_bf16 v[80:83], v[152:155], v[192:195], 0
	v_mfma_f32_16x16x32_bf16 v[72:75], v[160:163], v[192:195], 0
	v_mfma_f32_16x16x32_bf16 v[124:127], v[156:159], v[172:175], v[124:127]
	v_mfma_f32_16x16x32_bf16 v[120:123], v[164:167], v[172:175], v[120:123]
	v_mfma_f32_16x16x32_bf16 v[112:115], v[156:159], v[180:183], v[112:115]
	v_mfma_f32_16x16x32_bf16 v[104:107], v[164:167], v[180:183], v[104:107]
	v_mfma_f32_16x16x32_bf16 v[96:99], v[156:159], v[188:191], v[96:99]
	v_mfma_f32_16x16x32_bf16 v[88:91], v[164:167], v[188:191], v[88:91]
	v_mfma_f32_16x16x32_bf16 v[80:83], v[156:159], v[196:199], v[80:83]
	v_mfma_f32_16x16x32_bf16 v[72:75], v[164:167], v[196:199], v[72:75]
	s_setprio 0
	s_barrier
	s_add_i32 s54, s45, s30
	s_mov_b32 m0, s54
	ds_read_b128 v[202:205], v151
	ds_read_b128 v[206:209], v151 offset:1024
	ds_read_b128 v[210:213], v151 offset:2048
	ds_read_b128 v[214:217], v151 offset:3072
	global_load_lds_dwordx4 v130, s[24:25]
	s_add_i32 m0, s54, 0x2000
	s_nop 0
	global_load_lds_dwordx4 v134, s[24:25]
	s_waitcnt vmcnt(8)
	s_barrier
	s_waitcnt lgkmcnt(0)
	s_setprio 1
	s_waitcnt lgkmcnt(0)
	v_mfma_f32_16x16x32_bf16 v[116:119], v[202:205], v[168:171], 0
	v_mfma_f32_16x16x32_bf16 v[108:111], v[210:213], v[168:171], 0
	v_mfma_f32_16x16x32_bf16 v[100:103], v[202:205], v[176:179], 0
	v_mfma_f32_16x16x32_bf16 v[92:95], v[210:213], v[176:179], 0
	v_mfma_f32_16x16x32_bf16 v[84:87], v[202:205], v[184:187], 0
	v_mfma_f32_16x16x32_bf16 v[76:79], v[210:213], v[184:187], 0
	v_mfma_f32_16x16x32_bf16 v[68:71], v[202:205], v[192:195], 0
	v_mfma_f32_16x16x32_bf16 v[64:67], v[210:213], v[192:195], 0
	v_mfma_f32_16x16x32_bf16 v[116:119], v[206:209], v[172:175], v[116:119]
	v_mfma_f32_16x16x32_bf16 v[108:111], v[214:217], v[172:175], v[108:111]
	v_mfma_f32_16x16x32_bf16 v[100:103], v[206:209], v[180:183], v[100:103]
	v_mfma_f32_16x16x32_bf16 v[92:95], v[214:217], v[180:183], v[92:95]
	v_mfma_f32_16x16x32_bf16 v[84:87], v[206:209], v[188:191], v[84:87]
	v_mfma_f32_16x16x32_bf16 v[76:79], v[214:217], v[188:191], v[76:79]
	v_mfma_f32_16x16x32_bf16 v[68:71], v[206:209], v[196:199], v[68:71]
	v_mfma_f32_16x16x32_bf16 v[64:67], v[214:217], v[196:199], v[64:67]
	s_setprio 0
	s_mov_b32 m0, s21
	v_lshl_add_u64 v[222:223], s[26:27], 0, v[128:129]
	s_barrier
	ds_read_b128 v[168:171], v150 offset:16384
	ds_read_b128 v[172:175], v150 offset:17408
	ds_read_b128 v[176:179], v150 offset:18432
	ds_read_b128 v[180:183], v150 offset:19456
	ds_read_b128 v[184:187], v150 offset:20480
	ds_read_b128 v[188:191], v150 offset:21504
	ds_read_b128 v[192:195], v150 offset:22528
	ds_read_b128 v[196:199], v150 offset:23552
	global_load_lds_dwordx4 v128, s[26:27]
	v_lshl_add_u64 v[224:225], s[26:27], 0, v[132:133]
	s_mov_b32 m0, s31
	s_nop 0
	global_load_lds_dwordx4 v132, s[26:27]
	s_barrier
	s_waitcnt lgkmcnt(0)
	s_setprio 1
	s_waitcnt lgkmcnt(0)
	v_mfma_f32_16x16x32_bf16 v[60:63], v[152:155], v[168:171], 0
	v_mfma_f32_16x16x32_bf16 v[56:59], v[160:163], v[168:171], 0
	v_mfma_f32_16x16x32_bf16 v[48:51], v[152:155], v[176:179], 0
	v_mfma_f32_16x16x32_bf16 v[40:43], v[160:163], v[176:179], 0
	v_mfma_f32_16x16x32_bf16 v[32:35], v[152:155], v[184:187], 0
	v_mfma_f32_16x16x32_bf16 v[24:27], v[160:163], v[184:187], 0
	v_mfma_f32_16x16x32_bf16 v[16:19], v[152:155], v[192:195], 0
	v_mfma_f32_16x16x32_bf16 v[8:11], v[160:163], v[192:195], 0
	v_mfma_f32_16x16x32_bf16 v[60:63], v[156:159], v[172:175], v[60:63]
	v_mfma_f32_16x16x32_bf16 v[56:59], v[164:167], v[172:175], v[56:59]
	v_mfma_f32_16x16x32_bf16 v[48:51], v[156:159], v[180:183], v[48:51]
	v_mfma_f32_16x16x32_bf16 v[40:43], v[164:167], v[180:183], v[40:43]
	v_mfma_f32_16x16x32_bf16 v[32:35], v[156:159], v[188:191], v[32:35]
	v_mfma_f32_16x16x32_bf16 v[24:27], v[164:167], v[188:191], v[24:27]
	v_mfma_f32_16x16x32_bf16 v[16:19], v[156:159], v[196:199], v[16:19]
	v_mfma_f32_16x16x32_bf16 v[8:11], v[164:167], v[196:199], v[8:11]
	s_setprio 0
	s_barrier
; #define PG8_STAGE(bufoff, gbase, voff) do { _Pragma("unroll") for (int _i = 0; _i < 2; ++_i) \
;         __builtin_amdgcn_global_load_lds((const unsigned*)((const char*)(gbase) + (voff)[_i]), (LAS unsigned*)(lds + (bufoff) + ldsw + _i * 8192), 16, 0, 0); } while (0)
; #define PG8_LDA(dst, b, h) do { _Pragma("unroll") for (int m = 0; m < 4; ++m) _Pragma("unroll") for (int k = 0; k < 2; ++k) dst[m][k] = *(const LAS bf16x8*)(lds + PG8_SA(b, h) + aoff + m * 2048 + k * 1024); } while (0)
; #define PG8_LDB(dst, b, h) do { _Pragma("unroll") for (int n = 0; n < 2; ++n) _Pragma("unroll") for (int k = 0; k < 2; ++k) dst[n][k] = *(const LAS bf16x8*)(lds + PG8_SB(b, h) + boff + n * 2048 + k * 1024); } while (0)
; #define PG8_MMA(ai, bj, At, Bt) do { __builtin_amdgcn_s_setprio(1); _Pragma("unroll") for (int m = 0; m < 4; ++m) _Pragma("unroll") for (int n = 0; n < 2; ++n) _Pragma("unroll") for (int k = 0; k < 2; ++k) \
;         acc[ai][bj][m][n] = __builtin_amdgcn_mfma_f32_16x16x32_bf16(Bt[n][k], At[m][k], acc[ai][bj][m][n], 0, 0, 0); __builtin_amdgcn_s_setprio(0); } while (0)
; #define PG8_WAIT_V(n) asm volatile("s_waitcnt vmcnt(" #n ")" ::: "memory")
; #define PG8_WAIT_L(n) asm volatile("s_waitcnt lgkmcnt(" #n ")" ::: "memory")
; #define PG8_BAR __builtin_amdgcn_s_barrier()
; #define PG8_SCHED __builtin_amdgcn_sched_barrier(0)
; template <class Epi, class Sched>
; __device__ __forceinline__ void gemm_phase(LAS unsigned char* lds, const Gemm g, const Sched& S, const Epi& E) {
;     ...
;             PG8_STAGE(PG8_SB(0, 1), b2 + hstep, voffB);
;             PG8_WAIT_V(6); PG8_BAR; PG8_MMA(1, 1, At, B1); PG8_BAR;
;             PG8_LDB(B0, 1, 0); PG8_SCHED; PG8_LDA(At, 1, 0); PG8_STAGE(PG8_SA(0, 1), a2 + hstep, voffA);
;             PG8_WAIT_L(8); PG8_BAR; PG8_WAIT_L(0); PG8_MMA(0, 0, At, B0); PG8_BAR; PG8_SCHED;
;             PG8_LDB(B1, 1, 1); PG8_STAGE(PG8_SB(1, 0), b3, voffB);
;             PG8_BAR; PG8_WAIT_L(0); PG8_MMA(0, 1, At, B1); PG8_BAR;
;             PG8_LDA(At, 1, 1); PG8_STAGE(PG8_SA(1, 0), a3, voffA);
	s_add_u32 s54, s24, 0x40000
	s_addc_u32 s55, s25, 0
	s_add_i32 s56, s46, s30
	s_mov_b32 m0, s56
	s_nop 0
	global_load_lds_dwordx4 v130, s[54:55]
	s_add_i32 m0, s56, 0x2000
	s_nop 0
	global_load_lds_dwordx4 v134, s[54:55]
	s_add_u32 s26, s26, 0x40000
	s_addc_u32 s27, s27, 0
	s_mov_b32 m0, s33
	s_nop 0
	global_load_lds_dwordx4 v128, s[26:27]
	s_mov_b32 m0, s34
	s_nop 0
	global_load_lds_dwordx4 v132, s[26:27]
	s_waitcnt vmcnt(10)
	s_barrier
	s_setprio 1
	v_mfma_f32_16x16x32_bf16 v[52:55], v[202:205], v[168:171], 0
	v_mfma_f32_16x16x32_bf16 v[44:47], v[210:213], v[168:171], 0
	v_mfma_f32_16x16x32_bf16 v[36:39], v[202:205], v[176:179], 0
	v_mfma_f32_16x16x32_bf16 v[28:31], v[210:213], v[176:179], 0
	v_mfma_f32_16x16x32_bf16 v[20:23], v[202:205], v[184:187], 0
	v_mfma_f32_16x16x32_bf16 v[12:15], v[210:213], v[184:187], 0
	v_mfma_f32_16x16x32_bf16 v[4:7], v[202:205], v[192:195], 0
	v_mfma_f32_16x16x32_bf16 v[0:3], v[210:213], v[192:195], 0
	v_mfma_f32_16x16x32_bf16 v[52:55], v[206:209], v[172:175], v[52:55]
	v_mfma_f32_16x16x32_bf16 v[44:47], v[214:217], v[172:175], v[44:47]
	v_mfma_f32_16x16x32_bf16 v[36:39], v[206:209], v[180:183], v[36:39]
	v_mfma_f32_16x16x32_bf16 v[28:31], v[214:217], v[180:183], v[28:31]
	v_mfma_f32_16x16x32_bf16 v[20:23], v[206:209], v[188:191], v[20:23]
	v_mfma_f32_16x16x32_bf16 v[12:15], v[214:217], v[188:191], v[12:15]
	v_mfma_f32_16x16x32_bf16 v[4:7], v[206:209], v[196:199], v[4:7]
	v_mfma_f32_16x16x32_bf16 v[0:3], v[214:217], v[196:199], v[0:3]
	s_setprio 0
	s_add_i32 s54, 0, 0x18000
	v_add_u32_e32 v136, s54, v148
	s_barrier
	ds_read_b128 v[152:155], v136
	ds_read_b128 v[156:159], v136 offset:1024
	ds_read_b128 v[160:163], v136 offset:2048
	ds_read_b128 v[164:167], v136 offset:3072
	ds_read_b128 v[168:171], v150 offset:32768
	ds_read_b128 v[172:175], v150 offset:33792
	ds_read_b128 v[176:179], v150 offset:34816
	ds_read_b128 v[180:183], v150 offset:35840
	ds_read_b128 v[184:187], v150 offset:36864
	ds_read_b128 v[188:191], v150 offset:37888
	ds_read_b128 v[192:195], v150 offset:38912
	ds_read_b128 v[196:199], v150 offset:39936
	s_waitcnt lgkmcnt(8)
	s_waitcnt vmcnt(8)
	s_barrier
	s_waitcnt lgkmcnt(0)
	s_setprio 1
	s_waitcnt lgkmcnt(0)
	v_mfma_f32_16x16x32_bf16 v[124:127], v[152:155], v[168:171], v[124:127]
	v_mfma_f32_16x16x32_bf16 v[120:123], v[160:163], v[168:171], v[120:123]
	v_mfma_f32_16x16x32_bf16 v[112:115], v[152:155], v[176:179], v[112:115]
	v_mfma_f32_16x16x32_bf16 v[104:107], v[160:163], v[176:179], v[104:107]
	v_mfma_f32_16x16x32_bf16 v[96:99], v[152:155], v[184:187], v[96:99]
	v_mfma_f32_16x16x32_bf16 v[88:91], v[160:163], v[184:187], v[88:91]
	v_mfma_f32_16x16x32_bf16 v[80:83], v[152:155], v[192:195], v[80:83]
	v_mfma_f32_16x16x32_bf16 v[72:75], v[160:163], v[192:195], v[72:75]
	v_mfma_f32_16x16x32_bf16 v[124:127], v[156:159], v[172:175], v[124:127]
	v_mfma_f32_16x16x32_bf16 v[120:123], v[164:167], v[172:175], v[120:123]
	v_mfma_f32_16x16x32_bf16 v[112:115], v[156:159], v[180:183], v[112:115]
	v_mfma_f32_16x16x32_bf16 v[104:107], v[164:167], v[180:183], v[104:107]
	v_mfma_f32_16x16x32_bf16 v[96:99], v[156:159], v[188:191], v[96:99]
	v_mfma_f32_16x16x32_bf16 v[88:91], v[164:167], v[188:191], v[88:91]
	v_mfma_f32_16x16x32_bf16 v[80:83], v[156:159], v[196:199], v[80:83]
	v_mfma_f32_16x16x32_bf16 v[72:75], v[164:167], v[196:199], v[72:75]
	s_setprio 0
	s_barrier
	s_add_i32 s26, 0, 0x1c000
	s_add_i32 s27, s54, s30
	v_add_u32_e32 v136, s26, v148
	s_add_u32 s0, s24, 0x80
	s_addc_u32 s1, s25, 0
	s_mov_b32 m0, s27
	ds_read_b128 v[202:205], v136
	ds_read_b128 v[206:209], v136 offset:1024
	ds_read_b128 v[210:213], v136 offset:2048
	ds_read_b128 v[214:217], v136 offset:3072
	global_load_lds_dwordx4 v130, s[0:1]
	s_add_i32 m0, s27, 0x2000
	s_nop 0
	global_load_lds_dwordx4 v134, s[0:1]
	s_waitcnt vmcnt(8)
	s_barrier
	s_waitcnt lgkmcnt(0)
	s_setprio 1
	s_waitcnt lgkmcnt(0)
	v_mfma_f32_16x16x32_bf16 v[116:119], v[202:205], v[168:171], v[116:119]
	v_mfma_f32_16x16x32_bf16 v[108:111], v[210:213], v[168:171], v[108:111]
	v_mfma_f32_16x16x32_bf16 v[100:103], v[202:205], v[176:179], v[100:103]
	v_mfma_f32_16x16x32_bf16 v[92:95], v[210:213], v[176:179], v[92:95]
	v_mfma_f32_16x16x32_bf16 v[84:87], v[202:205], v[184:187], v[84:87]
	v_mfma_f32_16x16x32_bf16 v[76:79], v[210:213], v[184:187], v[76:79]
	v_mfma_f32_16x16x32_bf16 v[68:71], v[202:205], v[192:195], v[68:71]
	v_mfma_f32_16x16x32_bf16 v[64:67], v[210:213], v[192:195], v[64:67]
	v_mfma_f32_16x16x32_bf16 v[116:119], v[206:209], v[172:175], v[116:119]
	v_mfma_f32_16x16x32_bf16 v[108:111], v[214:217], v[172:175], v[108:111]
	v_mfma_f32_16x16x32_bf16 v[100:103], v[206:209], v[180:183], v[100:103]
	v_mfma_f32_16x16x32_bf16 v[92:95], v[214:217], v[180:183], v[92:95]
	v_mfma_f32_16x16x32_bf16 v[84:87], v[206:209], v[188:191], v[84:87]
	v_mfma_f32_16x16x32_bf16 v[76:79], v[214:217], v[188:191], v[76:79]
	v_mfma_f32_16x16x32_bf16 v[68:71], v[206:209], v[196:199], v[68:71]
	v_mfma_f32_16x16x32_bf16 v[64:67], v[214:217], v[196:199], v[64:67]
	s_setprio 0
	s_mov_b32 m0, s42
	s_mov_b64 s[0:1], 0x80
	v_lshl_add_u64 v[218:219], v[222:223], 0, s[0:1]
	s_barrier
	ds_read_b128 v[168:171], v150 offset:49152
	ds_read_b128 v[172:175], v150 offset:50176
	ds_read_b128 v[176:179], v150 offset:51200
	ds_read_b128 v[180:183], v150 offset:52224
	ds_read_b128 v[184:187], v150 offset:53248
	ds_read_b128 v[188:191], v150 offset:54272
	ds_read_b128 v[192:195], v150 offset:55296
	ds_read_b128 v[196:199], v150 offset:56320
	global_load_lds_dwordx4 v[218:219], off
	v_lshl_add_u64 v[218:219], v[224:225], 0, s[0:1]
	s_mov_b32 m0, s43
	s_nop 0
	global_load_lds_dwordx4 v[218:219], off
	s_barrier
; #define PG8_STAGE(bufoff, gbase, voff) do { _Pragma("unroll") for (int _i = 0; _i < 2; ++_i) \
;         __builtin_amdgcn_global_load_lds((const unsigned*)((const char*)(gbase) + (voff)[_i]), (LAS unsigned*)(lds + (bufoff) + ldsw + _i * 8192), 16, 0, 0); } while (0)
; #define PG8_LDA(dst, b, h) do { _Pragma("unroll") for (int m = 0; m < 4; ++m) _Pragma("unroll") for (int k = 0; k < 2; ++k) dst[m][k] = *(const LAS bf16x8*)(lds + PG8_SA(b, h) + aoff + m * 2048 + k * 1024); } while (0)
; #define PG8_WAIT_V(n) asm volatile("s_waitcnt vmcnt(" #n ")" ::: "memory")
; #define PG8_WAIT_L(n) asm volatile("s_waitcnt lgkmcnt(" #n ")" ::: "memory")
; template <class Epi, class Sched>
; __device__ __forceinline__ void gemm_phase(LAS unsigned char* lds, const Gemm g, const Sched& S, const Epi& E) {
;     ...
;         for (int t = 0; t < nt; t += 2) {
;             const bool last = (t == nt - 2);
;             const char* a1 = cA + (size_t)(t + 1) * kstep;
;             const char* a2 = last ? nA : cA + (size_t)(t + 2) * kstep; const char* b2 = last ? nB : cB + (size_t)(t + 2) * kstep;
;             const char* a3 = a2 + kstep; const char* b3 = b2 + kstep;
;             PG8_LDB(B0, 0, 0); PG8_SCHED; PG8_LDA(At, 0, 0); PG8_STAGE(PG8_SA(1, 1), a1 + hstep, voffA);
;             PG8_WAIT_L(8); PG8_BAR; PG8_WAIT_L(0); PG8_MMA(0, 0, At, B0); PG8_BAR; PG8_SCHED;
;             PG8_LDB(B1, 0, 1); PG8_STAGE(PG8_SB(0, 0), b2, voffB);
;             PG8_BAR; PG8_WAIT_L(0); PG8_MMA(0, 1, At, B1); PG8_BAR;
;             PG8_LDA(At, 0, 1); PG8_STAGE(PG8_SA(0, 0), a2, voffA);
;             PG8_BAR; PG8_WAIT_L(0); PG8_MMA(1, 0, At, B0); PG8_BAR; PG8_SCHED;
;             PG8_STAGE(PG8_SB(0, 1), b2 + hstep, voffB);
;             PG8_WAIT_V(6); PG8_BAR; PG8_MMA(1, 1, At, B1); PG8_BAR;
;             PG8_LDB(B0, 1, 0); PG8_SCHED; PG8_LDA(At, 1, 0); PG8_STAGE(PG8_SA(0, 1), a2 + hstep, voffA);
;             PG8_WAIT_L(8); PG8_BAR; PG8_WAIT_L(0); PG8_MMA(0, 0, At, B0); PG8_BAR; PG8_SCHED;
;             PG8_LDB(B1, 1, 1); PG8_STAGE(PG8_SB(1, 0), b3, voffB);
;             PG8_BAR; PG8_WAIT_L(0); PG8_MMA(0, 1, At, B1); PG8_BAR;
;             PG8_LDA(At, 1, 1); PG8_STAGE(PG8_SA(1, 0), a3, voffA);
;             PG8_BAR; PG8_WAIT_L(0); PG8_MMA(1, 0, At, B0); PG8_BAR; PG8_SCHED;
;             PG8_STAGE(PG8_SB(1, 1), b3 + hstep, voffB);
;             PG8_WAIT_V(6); PG8_BAR; PG8_MMA(1, 1, At, B1); PG8_BAR;
	s_waitcnt lgkmcnt(0)
	s_setprio 1
	s_waitcnt lgkmcnt(0)
	v_mfma_f32_16x16x32_bf16 v[60:63], v[152:155], v[168:171], v[60:63]
	v_mfma_f32_16x16x32_bf16 v[56:59], v[160:163], v[168:171], v[56:59]
	v_mfma_f32_16x16x32_bf16 v[48:51], v[152:155], v[176:179], v[48:51]
	v_mfma_f32_16x16x32_bf16 v[40:43], v[160:163], v[176:179], v[40:43]
	v_mfma_f32_16x16x32_bf16 v[32:35], v[152:155], v[184:187], v[32:35]
	v_mfma_f32_16x16x32_bf16 v[24:27], v[160:163], v[184:187], v[24:27]
	v_mfma_f32_16x16x32_bf16 v[16:19], v[152:155], v[192:195], v[16:19]
	v_mfma_f32_16x16x32_bf16 v[8:11], v[160:163], v[192:195], v[8:11]
	v_mfma_f32_16x16x32_bf16 v[60:63], v[156:159], v[172:175], v[60:63]
	v_mfma_f32_16x16x32_bf16 v[56:59], v[164:167], v[172:175], v[56:59]
	v_mfma_f32_16x16x32_bf16 v[48:51], v[156:159], v[180:183], v[48:51]
	v_mfma_f32_16x16x32_bf16 v[40:43], v[164:167], v[180:183], v[40:43]
	v_mfma_f32_16x16x32_bf16 v[32:35], v[156:159], v[188:191], v[32:35]
	v_mfma_f32_16x16x32_bf16 v[24:27], v[164:167], v[188:191], v[24:27]
	v_mfma_f32_16x16x32_bf16 v[16:19], v[156:159], v[196:199], v[16:19]
	v_mfma_f32_16x16x32_bf16 v[8:11], v[164:167], v[196:199], v[8:11]
	s_setprio 0
	s_barrier
	s_add_u32 s24, s24, 0x40080
	s_addc_u32 s25, s25, 0
	s_add_i32 s26, s26, s30
	s_mov_b32 m0, s26
	s_nop 0
	global_load_lds_dwordx4 v130, s[24:25]
	s_add_i32 m0, s26, 0x2000
	s_nop 0
	global_load_lds_dwordx4 v134, s[24:25]
	s_waitcnt vmcnt(8)
	s_barrier
	s_setprio 1
	v_mfma_f32_16x16x32_bf16 v[52:55], v[202:205], v[168:171], v[52:55]
	v_mfma_f32_16x16x32_bf16 v[44:47], v[210:213], v[168:171], v[44:47]
	v_mfma_f32_16x16x32_bf16 v[36:39], v[202:205], v[176:179], v[36:39]
	v_mfma_f32_16x16x32_bf16 v[28:31], v[210:213], v[176:179], v[28:31]
	v_mfma_f32_16x16x32_bf16 v[20:23], v[202:205], v[184:187], v[20:23]
	v_mfma_f32_16x16x32_bf16 v[12:15], v[210:213], v[184:187], v[12:15]
	v_mfma_f32_16x16x32_bf16 v[4:7], v[202:205], v[192:195], v[4:7]
	v_mfma_f32_16x16x32_bf16 v[0:3], v[210:213], v[192:195], v[0:3]
	v_mfma_f32_16x16x32_bf16 v[52:55], v[206:209], v[172:175], v[52:55]
	v_mfma_f32_16x16x32_bf16 v[44:47], v[214:217], v[172:175], v[44:47]
	v_mfma_f32_16x16x32_bf16 v[36:39], v[206:209], v[180:183], v[36:39]
	v_mfma_f32_16x16x32_bf16 v[28:31], v[214:217], v[180:183], v[28:31]
	v_mfma_f32_16x16x32_bf16 v[20:23], v[206:209], v[188:191], v[20:23]
	v_mfma_f32_16x16x32_bf16 v[12:15], v[214:217], v[188:191], v[12:15]
	v_mfma_f32_16x16x32_bf16 v[4:7], v[206:209], v[196:199], v[4:7]
	v_mfma_f32_16x16x32_bf16 v[0:3], v[214:217], v[196:199], v[0:3]
	s_setprio 0
	s_add_i32 s53, s53, 2
	s_add_u32 s22, s22, 0x100
	s_addc_u32 s23, s23, 0
	s_add_u32 s51, s51, 0x100
	s_addc_u32 s52, s52, 0
	s_cmp_gt_u32 s53, 13
	s_barrier
.LBB0_653:
	ds_read_b128 v[152:155], v149
	ds_read_b128 v[156:159], v149 offset:1024
	ds_read_b128 v[160:163], v149 offset:2048
	ds_read_b128 v[164:167], v149 offset:3072
	s_add_u32 s24, s22, 0xfffc0080
	s_addc_u32 s25, s23, -1
	s_cmp_eq_u32 s53, 12
	s_cselect_b32 s27, s9, s25
	s_cselect_b32 s26, s48, s24
	s_cselect_b32 s25, s7, s52
	s_cselect_b32 s24, s49, s51
	s_add_i32 m0, s21, 0xc000
	ds_read_b128 v[168:171], v150
	ds_read_b128 v[172:175], v150 offset:1024
	ds_read_b128 v[176:179], v150 offset:2048
	ds_read_b128 v[180:183], v150 offset:3072
	ds_read_b128 v[184:187], v150 offset:4096
	ds_read_b128 v[188:191], v150 offset:5120
	ds_read_b128 v[192:195], v150 offset:6144
	ds_read_b128 v[196:199], v150 offset:7168
	global_load_lds_dwordx4 v138, s[22:23]
	s_add_i32 m0, s21, 0xe000
	s_nop 0
	global_load_lds_dwordx4 v140, s[22:23]
	s_waitcnt lgkmcnt(8)
	s_waitcnt vmcnt(8)
	s_barrier
	s_waitcnt lgkmcnt(0)
	s_setprio 1
	s_waitcnt lgkmcnt(0)
	v_mfma_f32_16x16x32_bf16 v[124:127], v[152:155], v[168:171], v[124:127]
	v_mfma_f32_16x16x32_bf16 v[120:123], v[160:163], v[168:171], v[120:123]
	v_mfma_f32_16x16x32_bf16 v[112:115], v[152:155], v[176:179], v[112:115]
	v_mfma_f32_16x16x32_bf16 v[104:107], v[160:163], v[176:179], v[104:107]
	v_mfma_f32_16x16x32_bf16 v[96:99], v[152:155], v[184:187], v[96:99]
	v_mfma_f32_16x16x32_bf16 v[88:91], v[160:163], v[184:187], v[88:91]
	v_mfma_f32_16x16x32_bf16 v[80:83], v[152:155], v[192:195], v[80:83]
	v_mfma_f32_16x16x32_bf16 v[72:75], v[160:163], v[192:195], v[72:75]
	v_mfma_f32_16x16x32_bf16 v[124:127], v[156:159], v[172:175], v[124:127]
	v_mfma_f32_16x16x32_bf16 v[120:123], v[164:167], v[172:175], v[120:123]
	v_mfma_f32_16x16x32_bf16 v[112:115], v[156:159], v[180:183], v[112:115]
	v_mfma_f32_16x16x32_bf16 v[104:107], v[164:167], v[180:183], v[104:107]
	v_mfma_f32_16x16x32_bf16 v[96:99], v[156:159], v[188:191], v[96:99]
	v_mfma_f32_16x16x32_bf16 v[88:91], v[164:167], v[188:191], v[88:91]
	v_mfma_f32_16x16x32_bf16 v[80:83], v[156:159], v[196:199], v[80:83]
	v_mfma_f32_16x16x32_bf16 v[72:75], v[164:167], v[196:199], v[72:75]
	s_setprio 0
	s_barrier
	s_add_i32 s54, s45, s30
	s_mov_b32 m0, s54
	ds_read_b128 v[202:205], v151
	ds_read_b128 v[206:209], v151 offset:1024
	ds_read_b128 v[210:213], v151 offset:2048
	ds_read_b128 v[214:217], v151 offset:3072
	global_load_lds_dwordx4 v130, s[24:25]
	s_add_i32 m0, s54, 0x2000
	s_nop 0
	global_load_lds_dwordx4 v134, s[24:25]
	s_waitcnt vmcnt(8)
	s_barrier
; #define PG8_STAGE(bufoff, gbase, voff) do { _Pragma("unroll") for (int _i = 0; _i < 2; ++_i) \
;         __builtin_amdgcn_global_load_lds((const unsigned*)((const char*)(gbase) + (voff)[_i]), (LAS unsigned*)(lds + (bufoff) + ldsw + _i * 8192), 16, 0, 0); } while (0)
; #define PG8_LDA(dst, b, h) do { _Pragma("unroll") for (int m = 0; m < 4; ++m) _Pragma("unroll") for (int k = 0; k < 2; ++k) dst[m][k] = *(const LAS bf16x8*)(lds + PG8_SA(b, h) + aoff + m * 2048 + k * 1024); } while (0)
; #define PG8_LDB(dst, b, h) do { _Pragma("unroll") for (int n = 0; n < 2; ++n) _Pragma("unroll") for (int k = 0; k < 2; ++k) dst[n][k] = *(const LAS bf16x8*)(lds + PG8_SB(b, h) + boff + n * 2048 + k * 1024); } while (0)
; #define PG8_MMA(ai, bj, At, Bt) do { __builtin_amdgcn_s_setprio(1); _Pragma("unroll") for (int m = 0; m < 4; ++m) _Pragma("unroll") for (int n = 0; n < 2; ++n) _Pragma("unroll") for (int k = 0; k < 2; ++k) \
;         acc[ai][bj][m][n] = __builtin_amdgcn_mfma_f32_16x16x32_bf16(Bt[n][k], At[m][k], acc[ai][bj][m][n], 0, 0, 0); __builtin_amdgcn_s_setprio(0); } while (0)
; #define PG8_WAIT_V(n) asm volatile("s_waitcnt vmcnt(" #n ")" ::: "memory")
; #define PG8_WAIT_L(n) asm volatile("s_waitcnt lgkmcnt(" #n ")" ::: "memory")
; #define PG8_BAR __builtin_amdgcn_s_barrier()
; #define PG8_SCHED __builtin_amdgcn_sched_barrier(0)
; template <class Epi, class Sched>
; __device__ __forceinline__ void gemm_phase(LAS unsigned char* lds, const Gemm g, const Sched& S, const Epi& E) {
;     ...
;             PG8_BAR; PG8_WAIT_L(0); PG8_MMA(0, 1, At, B1); PG8_BAR;
;             PG8_LDA(At, 0, 1); PG8_STAGE(PG8_SA(0, 0), a2, voffA);
;             PG8_BAR; PG8_WAIT_L(0); PG8_MMA(1, 0, At, B0); PG8_BAR; PG8_SCHED;
;             PG8_STAGE(PG8_SB(0, 1), b2 + hstep, voffB);
;             PG8_WAIT_V(6); PG8_BAR; PG8_MMA(1, 1, At, B1); PG8_BAR;
;             PG8_LDB(B0, 1, 0); PG8_SCHED; PG8_LDA(At, 1, 0); PG8_STAGE(PG8_SA(0, 1), a2 + hstep, voffA);
;             PG8_WAIT_L(8); PG8_BAR; PG8_WAIT_L(0); PG8_MMA(0, 0, At, B0); PG8_BAR; PG8_SCHED;
	s_waitcnt lgkmcnt(0)
	s_setprio 1
	s_waitcnt lgkmcnt(0)
	v_mfma_f32_16x16x32_bf16 v[116:119], v[202:205], v[168:171], v[116:119]
	v_mfma_f32_16x16x32_bf16 v[108:111], v[210:213], v[168:171], v[108:111]
	v_mfma_f32_16x16x32_bf16 v[100:103], v[202:205], v[176:179], v[100:103]
	v_mfma_f32_16x16x32_bf16 v[92:95], v[210:213], v[176:179], v[92:95]
	v_mfma_f32_16x16x32_bf16 v[84:87], v[202:205], v[184:187], v[84:87]
	v_mfma_f32_16x16x32_bf16 v[76:79], v[210:213], v[184:187], v[76:79]
	v_mfma_f32_16x16x32_bf16 v[68:71], v[202:205], v[192:195], v[68:71]
	v_mfma_f32_16x16x32_bf16 v[64:67], v[210:213], v[192:195], v[64:67]
	v_mfma_f32_16x16x32_bf16 v[116:119], v[206:209], v[172:175], v[116:119]
	v_mfma_f32_16x16x32_bf16 v[108:111], v[214:217], v[172:175], v[108:111]
	v_mfma_f32_16x16x32_bf16 v[100:103], v[206:209], v[180:183], v[100:103]
	v_mfma_f32_16x16x32_bf16 v[92:95], v[214:217], v[180:183], v[92:95]
	v_mfma_f32_16x16x32_bf16 v[84:87], v[206:209], v[188:191], v[84:87]
	v_mfma_f32_16x16x32_bf16 v[76:79], v[214:217], v[188:191], v[76:79]
	v_mfma_f32_16x16x32_bf16 v[68:71], v[206:209], v[196:199], v[68:71]
	v_mfma_f32_16x16x32_bf16 v[64:67], v[214:217], v[196:199], v[64:67]
	s_setprio 0
	s_mov_b32 m0, s21
	v_lshl_add_u64 v[222:223], s[26:27], 0, v[128:129]
	s_barrier
	ds_read_b128 v[168:171], v150 offset:16384
	ds_read_b128 v[172:175], v150 offset:17408
	ds_read_b128 v[176:179], v150 offset:18432
	ds_read_b128 v[180:183], v150 offset:19456
	ds_read_b128 v[184:187], v150 offset:20480
	ds_read_b128 v[188:191], v150 offset:21504
	ds_read_b128 v[192:195], v150 offset:22528
	ds_read_b128 v[196:199], v150 offset:23552
	global_load_lds_dwordx4 v128, s[26:27]
	v_lshl_add_u64 v[224:225], s[26:27], 0, v[132:133]
	s_mov_b32 m0, s31
	s_nop 0
	global_load_lds_dwordx4 v132, s[26:27]
	s_barrier
	s_waitcnt lgkmcnt(0)
	s_setprio 1
	s_waitcnt lgkmcnt(0)
	v_mfma_f32_16x16x32_bf16 v[60:63], v[152:155], v[168:171], v[60:63]
	v_mfma_f32_16x16x32_bf16 v[56:59], v[160:163], v[168:171], v[56:59]
	v_mfma_f32_16x16x32_bf16 v[48:51], v[152:155], v[176:179], v[48:51]
	v_mfma_f32_16x16x32_bf16 v[40:43], v[160:163], v[176:179], v[40:43]
	v_mfma_f32_16x16x32_bf16 v[32:35], v[152:155], v[184:187], v[32:35]
	v_mfma_f32_16x16x32_bf16 v[24:27], v[160:163], v[184:187], v[24:27]
	v_mfma_f32_16x16x32_bf16 v[16:19], v[152:155], v[192:195], v[16:19]
	v_mfma_f32_16x16x32_bf16 v[8:11], v[160:163], v[192:195], v[8:11]
	v_mfma_f32_16x16x32_bf16 v[60:63], v[156:159], v[172:175], v[60:63]
	v_mfma_f32_16x16x32_bf16 v[56:59], v[164:167], v[172:175], v[56:59]
	v_mfma_f32_16x16x32_bf16 v[48:51], v[156:159], v[180:183], v[48:51]
	v_mfma_f32_16x16x32_bf16 v[40:43], v[164:167], v[180:183], v[40:43]
	v_mfma_f32_16x16x32_bf16 v[32:35], v[156:159], v[188:191], v[32:35]
	v_mfma_f32_16x16x32_bf16 v[24:27], v[164:167], v[188:191], v[24:27]
	v_mfma_f32_16x16x32_bf16 v[16:19], v[156:159], v[196:199], v[16:19]
	v_mfma_f32_16x16x32_bf16 v[8:11], v[164:167], v[196:199], v[8:11]
	s_setprio 0
	s_barrier
	s_add_u32 s54, s24, 0x40000
	s_addc_u32 s55, s25, 0
	s_add_i32 s56, s46, s30
	s_mov_b32 m0, s56
	s_nop 0
	global_load_lds_dwordx4 v130, s[54:55]
	s_add_i32 m0, s56, 0x2000
	s_nop 0
	global_load_lds_dwordx4 v134, s[54:55]
	s_add_u32 s26, s26, 0x40000
	s_addc_u32 s27, s27, 0
	s_mov_b32 m0, s33
	s_nop 0
	global_load_lds_dwordx4 v128, s[26:27]
	s_mov_b32 m0, s34
	s_nop 0
	global_load_lds_dwordx4 v132, s[26:27]
	s_waitcnt vmcnt(10)
	s_barrier
	s_setprio 1
	v_mfma_f32_16x16x32_bf16 v[52:55], v[202:205], v[168:171], v[52:55]
	v_mfma_f32_16x16x32_bf16 v[44:47], v[210:213], v[168:171], v[44:47]
	v_mfma_f32_16x16x32_bf16 v[36:39], v[202:205], v[176:179], v[36:39]
	v_mfma_f32_16x16x32_bf16 v[28:31], v[210:213], v[176:179], v[28:31]
	v_mfma_f32_16x16x32_bf16 v[20:23], v[202:205], v[184:187], v[20:23]
	v_mfma_f32_16x16x32_bf16 v[12:15], v[210:213], v[184:187], v[12:15]
	v_mfma_f32_16x16x32_bf16 v[4:7], v[202:205], v[192:195], v[4:7]
	v_mfma_f32_16x16x32_bf16 v[0:3], v[210:213], v[192:195], v[0:3]
	v_mfma_f32_16x16x32_bf16 v[52:55], v[206:209], v[172:175], v[52:55]
	v_mfma_f32_16x16x32_bf16 v[44:47], v[214:217], v[172:175], v[44:47]
	v_mfma_f32_16x16x32_bf16 v[36:39], v[206:209], v[180:183], v[36:39]
	v_mfma_f32_16x16x32_bf16 v[28:31], v[214:217], v[180:183], v[28:31]
	v_mfma_f32_16x16x32_bf16 v[20:23], v[206:209], v[188:191], v[20:23]
	v_mfma_f32_16x16x32_bf16 v[12:15], v[214:217], v[188:191], v[12:15]
	v_mfma_f32_16x16x32_bf16 v[4:7], v[206:209], v[196:199], v[4:7]
	v_mfma_f32_16x16x32_bf16 v[0:3], v[214:217], v[196:199], v[0:3]
	s_setprio 0
	s_add_i32 s54, 0, 0x18000
	v_add_u32_e32 v136, s54, v148
	s_barrier
	ds_read_b128 v[152:155], v136
	ds_read_b128 v[156:159], v136 offset:1024
	ds_read_b128 v[160:163], v136 offset:2048
	ds_read_b128 v[164:167], v136 offset:3072
	ds_read_b128 v[168:171], v150 offset:32768
	ds_read_b128 v[172:175], v150 offset:33792
	ds_read_b128 v[176:179], v150 offset:34816
	ds_read_b128 v[180:183], v150 offset:35840
	ds_read_b128 v[184:187], v150 offset:36864
	ds_read_b128 v[188:191], v150 offset:37888
	ds_read_b128 v[192:195], v150 offset:38912
	ds_read_b128 v[196:199], v150 offset:39936
	s_waitcnt lgkmcnt(8)
	s_waitcnt vmcnt(8)
	s_barrier
; #define PG8_STAGE(bufoff, gbase, voff) do { _Pragma("unroll") for (int _i = 0; _i < 2; ++_i) \
;         __builtin_amdgcn_global_load_lds((const unsigned*)((const char*)(gbase) + (voff)[_i]), (LAS unsigned*)(lds + (bufoff) + ldsw + _i * 8192), 16, 0, 0); } while (0)
; #define PG8_LDA(dst, b, h) do { _Pragma("unroll") for (int m = 0; m < 4; ++m) _Pragma("unroll") for (int k = 0; k < 2; ++k) dst[m][k] = *(const LAS bf16x8*)(lds + PG8_SA(b, h) + aoff + m * 2048 + k * 1024); } while (0)
; #define PG8_LDB(dst, b, h) do { _Pragma("unroll") for (int n = 0; n < 2; ++n) _Pragma("unroll") for (int k = 0; k < 2; ++k) dst[n][k] = *(const LAS bf16x8*)(lds + PG8_SB(b, h) + boff + n * 2048 + k * 1024); } while (0)
; #define PG8_MMA(ai, bj, At, Bt) do { __builtin_amdgcn_s_setprio(1); _Pragma("unroll") for (int m = 0; m < 4; ++m) _Pragma("unroll") for (int n = 0; n < 2; ++n) _Pragma("unroll") for (int k = 0; k < 2; ++k) \
;         acc[ai][bj][m][n] = __builtin_amdgcn_mfma_f32_16x16x32_bf16(Bt[n][k], At[m][k], acc[ai][bj][m][n], 0, 0, 0); __builtin_amdgcn_s_setprio(0); } while (0)
; #define PG8_WAIT_V(n) asm volatile("s_waitcnt vmcnt(" #n ")" ::: "memory")
; #define PG8_WAIT_L(n) asm volatile("s_waitcnt lgkmcnt(" #n ")" ::: "memory")
; #define PG8_BAR __builtin_amdgcn_s_barrier()
; #define PG8_SCHED __builtin_amdgcn_sched_barrier(0)
; template <class Epi, class Sched>
; __device__ __forceinline__ void gemm_phase(LAS unsigned char* lds, const Gemm g, const Sched& S, const Epi& E) {
;     ...
;             PG8_WAIT_L(8); PG8_BAR; PG8_WAIT_L(0); PG8_MMA(0, 0, At, B0); PG8_BAR; PG8_SCHED;
;             PG8_LDB(B1, 1, 1); PG8_STAGE(PG8_SB(1, 0), b3, voffB);
;             PG8_BAR; PG8_WAIT_L(0); PG8_MMA(0, 1, At, B1); PG8_BAR;
;             PG8_LDA(At, 1, 1); PG8_STAGE(PG8_SA(1, 0), a3, voffA);
;             PG8_BAR; PG8_WAIT_L(0); PG8_MMA(1, 0, At, B0); PG8_BAR; PG8_SCHED;
;             PG8_STAGE(PG8_SB(1, 1), b3 + hstep, voffB);
;             PG8_WAIT_V(6); PG8_BAR; PG8_MMA(1, 1, At, B1); PG8_BAR;
	s_waitcnt lgkmcnt(0)
	s_setprio 1
	s_waitcnt lgkmcnt(0)
	v_mfma_f32_16x16x32_bf16 v[124:127], v[152:155], v[168:171], v[124:127]
	v_mfma_f32_16x16x32_bf16 v[120:123], v[160:163], v[168:171], v[120:123]
	v_mfma_f32_16x16x32_bf16 v[112:115], v[152:155], v[176:179], v[112:115]
	v_mfma_f32_16x16x32_bf16 v[104:107], v[160:163], v[176:179], v[104:107]
	v_mfma_f32_16x16x32_bf16 v[96:99], v[152:155], v[184:187], v[96:99]
	v_mfma_f32_16x16x32_bf16 v[88:91], v[160:163], v[184:187], v[88:91]
	v_mfma_f32_16x16x32_bf16 v[80:83], v[152:155], v[192:195], v[80:83]
	v_mfma_f32_16x16x32_bf16 v[72:75], v[160:163], v[192:195], v[72:75]
	v_mfma_f32_16x16x32_bf16 v[124:127], v[156:159], v[172:175], v[124:127]
	v_mfma_f32_16x16x32_bf16 v[120:123], v[164:167], v[172:175], v[120:123]
	v_mfma_f32_16x16x32_bf16 v[112:115], v[156:159], v[180:183], v[112:115]
	v_mfma_f32_16x16x32_bf16 v[104:107], v[164:167], v[180:183], v[104:107]
	v_mfma_f32_16x16x32_bf16 v[96:99], v[156:159], v[188:191], v[96:99]
	v_mfma_f32_16x16x32_bf16 v[88:91], v[164:167], v[188:191], v[88:91]
	v_mfma_f32_16x16x32_bf16 v[80:83], v[156:159], v[196:199], v[80:83]
	v_mfma_f32_16x16x32_bf16 v[72:75], v[164:167], v[196:199], v[72:75]
	s_setprio 0
	s_barrier
	s_add_i32 s26, 0, 0x1c000
	s_add_i32 s27, s54, s30
	v_add_u32_e32 v136, s26, v148
	s_add_u32 s0, s24, 0x80
	s_addc_u32 s1, s25, 0
	s_mov_b32 m0, s27
	ds_read_b128 v[202:205], v136
	ds_read_b128 v[206:209], v136 offset:1024
	ds_read_b128 v[210:213], v136 offset:2048
	ds_read_b128 v[214:217], v136 offset:3072
	global_load_lds_dwordx4 v130, s[0:1]
	s_add_i32 m0, s27, 0x2000
	s_nop 0
	global_load_lds_dwordx4 v134, s[0:1]
	s_waitcnt vmcnt(8)
	s_barrier
	s_waitcnt lgkmcnt(0)
	s_setprio 1
	s_waitcnt lgkmcnt(0)
	v_mfma_f32_16x16x32_bf16 v[116:119], v[202:205], v[168:171], v[116:119]
	v_mfma_f32_16x16x32_bf16 v[108:111], v[210:213], v[168:171], v[108:111]
	v_mfma_f32_16x16x32_bf16 v[100:103], v[202:205], v[176:179], v[100:103]
	v_mfma_f32_16x16x32_bf16 v[92:95], v[210:213], v[176:179], v[92:95]
	v_mfma_f32_16x16x32_bf16 v[84:87], v[202:205], v[184:187], v[84:87]
	v_mfma_f32_16x16x32_bf16 v[76:79], v[210:213], v[184:187], v[76:79]
	v_mfma_f32_16x16x32_bf16 v[68:71], v[202:205], v[192:195], v[68:71]
	v_mfma_f32_16x16x32_bf16 v[64:67], v[210:213], v[192:195], v[64:67]
	v_mfma_f32_16x16x32_bf16 v[116:119], v[206:209], v[172:175], v[116:119]
	v_mfma_f32_16x16x32_bf16 v[108:111], v[214:217], v[172:175], v[108:111]
	v_mfma_f32_16x16x32_bf16 v[100:103], v[206:209], v[180:183], v[100:103]
	v_mfma_f32_16x16x32_bf16 v[92:95], v[214:217], v[180:183], v[92:95]
	v_mfma_f32_16x16x32_bf16 v[84:87], v[206:209], v[188:191], v[84:87]
	v_mfma_f32_16x16x32_bf16 v[76:79], v[214:217], v[188:191], v[76:79]
	v_mfma_f32_16x16x32_bf16 v[68:71], v[206:209], v[196:199], v[68:71]
	v_mfma_f32_16x16x32_bf16 v[64:67], v[214:217], v[196:199], v[64:67]
	s_setprio 0
	s_mov_b32 m0, s42
	s_mov_b64 s[0:1], 0x80
	v_lshl_add_u64 v[218:219], v[222:223], 0, s[0:1]
	s_barrier
	ds_read_b128 v[168:171], v150 offset:49152
	ds_read_b128 v[172:175], v150 offset:50176
	ds_read_b128 v[176:179], v150 offset:51200
	ds_read_b128 v[180:183], v150 offset:52224
	ds_read_b128 v[184:187], v150 offset:53248
	ds_read_b128 v[188:191], v150 offset:54272
	ds_read_b128 v[192:195], v150 offset:55296
	ds_read_b128 v[196:199], v150 offset:56320
	global_load_lds_dwordx4 v[218:219], off
	v_lshl_add_u64 v[218:219], v[224:225], 0, s[0:1]
	s_mov_b32 m0, s43
	s_nop 0
	global_load_lds_dwordx4 v[218:219], off
	s_barrier
	s_waitcnt lgkmcnt(0)
	s_setprio 1
	s_waitcnt lgkmcnt(0)
	v_mfma_f32_16x16x32_bf16 v[60:63], v[152:155], v[168:171], v[60:63]
	v_mfma_f32_16x16x32_bf16 v[56:59], v[160:163], v[168:171], v[56:59]
	v_mfma_f32_16x16x32_bf16 v[48:51], v[152:155], v[176:179], v[48:51]
	v_mfma_f32_16x16x32_bf16 v[40:43], v[160:163], v[176:179], v[40:43]
	v_mfma_f32_16x16x32_bf16 v[32:35], v[152:155], v[184:187], v[32:35]
	v_mfma_f32_16x16x32_bf16 v[24:27], v[160:163], v[184:187], v[24:27]
	v_mfma_f32_16x16x32_bf16 v[16:19], v[152:155], v[192:195], v[16:19]
	v_mfma_f32_16x16x32_bf16 v[8:11], v[160:163], v[192:195], v[8:11]
	v_mfma_f32_16x16x32_bf16 v[60:63], v[156:159], v[172:175], v[60:63]
	v_mfma_f32_16x16x32_bf16 v[56:59], v[164:167], v[172:175], v[56:59]
	v_mfma_f32_16x16x32_bf16 v[48:51], v[156:159], v[180:183], v[48:51]
	v_mfma_f32_16x16x32_bf16 v[40:43], v[164:167], v[180:183], v[40:43]
	v_mfma_f32_16x16x32_bf16 v[32:35], v[156:159], v[188:191], v[32:35]
	v_mfma_f32_16x16x32_bf16 v[24:27], v[164:167], v[188:191], v[24:27]
	v_mfma_f32_16x16x32_bf16 v[16:19], v[156:159], v[196:199], v[16:19]
	v_mfma_f32_16x16x32_bf16 v[8:11], v[164:167], v[196:199], v[8:11]
	s_setprio 0
	s_barrier
	s_add_u32 s24, s24, 0x40080
	s_addc_u32 s25, s25, 0
	s_add_i32 s26, s26, s30
	s_mov_b32 m0, s26
	s_nop 0
	global_load_lds_dwordx4 v130, s[24:25]
	s_add_i32 m0, s26, 0x2000
	s_nop 0
	global_load_lds_dwordx4 v134, s[24:25]
	s_waitcnt vmcnt(8)
	s_barrier
	s_setprio 1
	v_mfma_f32_16x16x32_bf16 v[52:55], v[202:205], v[168:171], v[52:55]
	v_mfma_f32_16x16x32_bf16 v[44:47], v[210:213], v[168:171], v[44:47]
	v_mfma_f32_16x16x32_bf16 v[36:39], v[202:205], v[176:179], v[36:39]
	v_mfma_f32_16x16x32_bf16 v[28:31], v[210:213], v[176:179], v[28:31]
	v_mfma_f32_16x16x32_bf16 v[20:23], v[202:205], v[184:187], v[20:23]
	v_mfma_f32_16x16x32_bf16 v[12:15], v[210:213], v[184:187], v[12:15]
	v_mfma_f32_16x16x32_bf16 v[4:7], v[202:205], v[192:195], v[4:7]
	v_mfma_f32_16x16x32_bf16 v[0:3], v[210:213], v[192:195], v[0:3]
	v_mfma_f32_16x16x32_bf16 v[52:55], v[206:209], v[172:175], v[52:55]
	v_mfma_f32_16x16x32_bf16 v[44:47], v[214:217], v[172:175], v[44:47]
	v_mfma_f32_16x16x32_bf16 v[36:39], v[206:209], v[180:183], v[36:39]
	v_mfma_f32_16x16x32_bf16 v[28:31], v[214:217], v[180:183], v[28:31]
	v_mfma_f32_16x16x32_bf16 v[20:23], v[206:209], v[188:191], v[20:23]
	v_mfma_f32_16x16x32_bf16 v[12:15], v[214:217], v[188:191], v[12:15]
	v_mfma_f32_16x16x32_bf16 v[4:7], v[206:209], v[196:199], v[4:7]
	v_mfma_f32_16x16x32_bf16 v[0:3], v[214:217], v[196:199], v[0:3]
	s_setprio 0
	s_add_i32 s53, s53, 2
	s_add_u32 s22, s22, 0x100
	s_addc_u32 s23, s23, 0
	s_add_u32 s51, s51, 0x100
	s_addc_u32 s52, s52, 0
	s_cmp_gt_u32 s53, 13
	s_barrier
; __device__ __forceinline__ unsigned cvt_pk_bf16(float lo, float hi) { unsigned r; asm volatile("v_cvt_pk_bf16_f32 %0, %1, %2" : "=v"(r) : "v"(lo), "v"(hi)); return r; }
;     __device__ __forceinline__ void operator()(const AccT& acc, const Unit& u, int wr, int wc, int fr, int fq) const {
;     ...
; #pragma unroll
;         for (int ai = 0; ai < 2; ++ai)
; #pragma unroll
;             for (int m = 0; m < 4; ++m) {
;                 const int gm = rbase + ai * 128 + m * 16;
; #pragma unroll
;                 for (int bj = 0; bj < 2; ++bj) {
;                     const int t0 = tb + bj * 128;
;                     const f32x4 v0 = acc[ai][bj][m][0], v1 = acc[ai][bj][m][1];
;                     u32x4 w; w.x = cvt_pk_bf16(v0[0], v0[1]); w.y = cvt_pk_bf16(v0[2], v0[3]); w.z = cvt_pk_bf16(v1[0], v1[1]); w.w = cvt_pk_bf16(v1[2], v1[3]);
;                     *(u32x4*)(YT + ((size_t)((t0 >> 10) * 512 + gm)) * 2048 + part * 1024 + (t0 & 1023)) = w;
;                 }
	s_cbranch_scc0 .LBB0_653
	v_mov_b32_e32 v136, v147
	v_mov_b32_e32 v152, v146
	s_lshl_b32 s7, s20, 8
	s_add_i32 s7, s7, s36
	v_add_u32_e32 v152, s7, v152
	s_lshl_b32 s7, s47, 8
	s_or_b32 s7, s7, s37
	v_lshl_add_u32 v153, v136, 3, s7
	v_cvt_pk_bf16_f32 v124, v124, v125
	v_cvt_pk_bf16_f32 v125, v126, v127
	v_cvt_pk_bf16_f32 v126, v120, v121
	v_ashrrev_i32_e32 v120, 1, v153
	v_cvt_pk_bf16_f32 v127, v122, v123
	v_and_b32_e32 v122, 0xfffffe00, v120
	v_add_u32_e32 v120, v122, v152
	v_ashrrev_i32_e32 v121, 31, v120
	v_lshlrev_b64 v[120:121], 12, v[120:121]
	v_and_b32_e32 v123, 0x3f8, v153
	v_lshl_add_u64 v[120:121], s[68:69], 0, v[120:121]
	v_lshlrev_b32_e32 v136, 1, v123
	v_lshl_add_u64 v[120:121], v[120:121], 0, v[136:137]
	global_store_dwordx4 v[120:121], v[124:127], off
	v_add_u32_e32 v120, 0x80, v153
	v_cvt_pk_bf16_f32 v116, v116, v117
	v_cvt_pk_bf16_f32 v117, v118, v119
	v_cvt_pk_bf16_f32 v118, v108, v109
	v_ashrrev_i32_e32 v108, 1, v120
	v_and_b32_e32 v121, 0xfffffe00, v108
	v_add_u32_e32 v108, v121, v152
	v_ashrrev_i32_e32 v109, 31, v108
	v_lshlrev_b64 v[108:109], 12, v[108:109]
	v_cvt_pk_bf16_f32 v119, v110, v111
	v_lshl_add_u64 v[110:111], s[68:69], 0, v[108:109]
	v_and_b32_e32 v108, 0x3f8, v120
	v_lshlrev_b32_e32 v108, 1, v108
	v_mov_b32_e32 v109, v137
	v_lshl_add_u64 v[110:111], v[110:111], 0, v[108:109]
	global_store_dwordx4 v[110:111], v[116:119], off
	v_cvt_pk_bf16_f32 v110, v112, v113
	v_cvt_pk_bf16_f32 v111, v114, v115
	v_cvt_pk_bf16_f32 v112, v104, v105
	v_cvt_pk_bf16_f32 v113, v106, v107
	s_and_b64 vcc, exec, s[4:5]
	s_nop 0
	v_add_u32_e32 v116, 16, v152
	v_add_u32_e32 v104, v122, v116
	v_ashrrev_i32_e32 v105, 31, v104
	v_lshlrev_b64 v[104:105], 12, v[104:105]
	v_lshl_add_u64 v[104:105], s[68:69], 0, v[104:105]
	v_lshl_add_u64 v[104:105], v[104:105], 0, v[136:137]
	global_store_dwordx4 v[104:105], v[110:113], off
	v_cvt_pk_bf16_f32 v100, v100, v101
	v_cvt_pk_bf16_f32 v101, v102, v103
	v_cvt_pk_bf16_f32 v102, v92, v93
	v_add_u32_e32 v92, v121, v116
	v_ashrrev_i32_e32 v93, 31, v92
	v_lshlrev_b64 v[92:93], 12, v[92:93]
	v_lshl_add_u64 v[92:93], s[68:69], 0, v[92:93]
	v_lshl_add_u64 v[92:93], v[92:93], 0, v[108:109]
	v_cvt_pk_bf16_f32 v103, v94, v95
	global_store_dwordx4 v[92:93], v[100:103], off
	v_cvt_pk_bf16_f32 v92, v96, v97
	v_cvt_pk_bf16_f32 v93, v98, v99
	v_cvt_pk_bf16_f32 v94, v88, v89
	v_cvt_pk_bf16_f32 v95, v90, v91
	s_mov_b32 s47, s6
	s_nop 0
	v_add_u32_e32 v100, 32, v152
	v_add_u32_e32 v88, v122, v100
	v_ashrrev_i32_e32 v89, 31, v88
	v_lshlrev_b64 v[88:89], 12, v[88:89]
	v_lshl_add_u64 v[88:89], s[68:69], 0, v[88:89]
	v_lshl_add_u64 v[88:89], v[88:89], 0, v[136:137]
	global_store_dwordx4 v[88:89], v[92:95], off
	v_cvt_pk_bf16_f32 v84, v84, v85
	v_cvt_pk_bf16_f32 v85, v86, v87
	v_cvt_pk_bf16_f32 v86, v76, v77
	v_add_u32_e32 v76, v121, v100
	v_ashrrev_i32_e32 v77, 31, v76
	v_lshlrev_b64 v[76:77], 12, v[76:77]
	v_lshl_add_u64 v[76:77], s[68:69], 0, v[76:77]
	v_lshl_add_u64 v[76:77], v[76:77], 0, v[108:109]
	v_cvt_pk_bf16_f32 v87, v78, v79
	global_store_dwordx4 v[76:77], v[84:87], off
	v_cvt_pk_bf16_f32 v76, v80, v81
	v_cvt_pk_bf16_f32 v77, v82, v83
	v_cvt_pk_bf16_f32 v78, v72, v73
	v_cvt_pk_bf16_f32 v79, v74, v75
	s_mov_b32 s20, s8
	s_nop 0
	v_add_u32_e32 v84, 48, v152
	v_add_u32_e32 v72, v122, v84
	v_ashrrev_i32_e32 v73, 31, v72
	v_lshlrev_b64 v[72:73], 12, v[72:73]
	v_lshl_add_u64 v[72:73], s[68:69], 0, v[72:73]
	v_lshl_add_u64 v[72:73], v[72:73], 0, v[136:137]
	global_store_dwordx4 v[72:73], v[76:79], off
	v_cvt_pk_bf16_f32 v68, v68, v69
	v_cvt_pk_bf16_f32 v69, v70, v71
; __device__ __forceinline__ unsigned cvt_pk_bf16(float lo, float hi) { unsigned r; asm volatile("v_cvt_pk_bf16_f32 %0, %1, %2" : "=v"(r) : "v"(lo), "v"(hi)); return r; }
; #define PG8_WAIT_V(n) asm volatile("s_waitcnt vmcnt(" #n ")" ::: "memory")
; #define PG8_BAR __builtin_amdgcn_s_barrier()
; template <class Epi, class Sched>
; __device__ __forceinline__ void gemm_phase(LAS unsigned char* lds, const Gemm g, const Sched& S, const Epi& E) {
;     ...
;         if (!has_next) break;
; #pragma unroll
;         for (int a = 0; a < 2; ++a)
; #pragma unroll
;             for (int b = 0; b < 2; ++b)
; #pragma unroll
;                 for (int m = 0; m < 4; ++m)
; #pragma unroll
;                     for (int n = 0; n < 2; ++n) acc[a][b][m][n] = (f32x4){0.f, 0.f, 0.f, 0.f};
;         cur = nxt; cA = nA; cB = nB; ++ui;
;     }
;     PG8_WAIT_V(0);
;     if (wr == 0) PG8_BAR;
;     PG8_BAR;
;     __device__ __forceinline__ void operator()(const AccT& acc, const Unit& u, int wr, int wc, int fr, int fq) const {
;     ...
; #pragma unroll
;         for (int ai = 0; ai < 2; ++ai)
; #pragma unroll
;             for (int m = 0; m < 4; ++m) {
;                 const int gm = rbase + ai * 128 + m * 16;
; #pragma unroll
;                 for (int bj = 0; bj < 2; ++bj) {
;                     const int t0 = tb + bj * 128;
;                     const f32x4 v0 = acc[ai][bj][m][0], v1 = acc[ai][bj][m][1];
;                     u32x4 w; w.x = cvt_pk_bf16(v0[0], v0[1]); w.y = cvt_pk_bf16(v0[2], v0[3]); w.z = cvt_pk_bf16(v1[0], v1[1]); w.w = cvt_pk_bf16(v1[2], v1[3]);
;                     *(u32x4*)(YT + ((size_t)((t0 >> 10) * 512 + gm)) * 2048 + part * 1024 + (t0 & 1023)) = w;
;                 }
	v_cvt_pk_bf16_f32 v70, v64, v65
	v_add_u32_e32 v64, v121, v84
	v_ashrrev_i32_e32 v65, 31, v64
	v_lshlrev_b64 v[64:65], 12, v[64:65]
	v_lshl_add_u64 v[64:65], s[68:69], 0, v[64:65]
	v_lshl_add_u64 v[64:65], v[64:65], 0, v[108:109]
	v_cvt_pk_bf16_f32 v71, v66, v67
	global_store_dwordx4 v[64:65], v[68:71], off
	v_add_u32_e32 v64, 0x80, v152
	v_cvt_pk_bf16_f32 v60, v60, v61
	v_cvt_pk_bf16_f32 v61, v62, v63
	v_cvt_pk_bf16_f32 v62, v56, v57
	v_add_u32_e32 v56, v122, v64
	v_ashrrev_i32_e32 v57, 31, v56
	v_lshlrev_b64 v[56:57], 12, v[56:57]
	v_lshl_add_u64 v[56:57], s[68:69], 0, v[56:57]
	v_lshl_add_u64 v[56:57], v[56:57], 0, v[136:137]
	v_cvt_pk_bf16_f32 v63, v58, v59
	global_store_dwordx4 v[56:57], v[60:63], off
	v_cvt_pk_bf16_f32 v52, v52, v53
	v_cvt_pk_bf16_f32 v53, v54, v55
	v_cvt_pk_bf16_f32 v54, v44, v45
	v_add_u32_e32 v44, v121, v64
	v_ashrrev_i32_e32 v45, 31, v44
	v_lshlrev_b64 v[44:45], 12, v[44:45]
	v_lshl_add_u64 v[44:45], s[68:69], 0, v[44:45]
	v_lshl_add_u64 v[44:45], v[44:45], 0, v[108:109]
	v_cvt_pk_bf16_f32 v55, v46, v47
	global_store_dwordx4 v[44:45], v[52:55], off
	v_cvt_pk_bf16_f32 v44, v48, v49
	v_cvt_pk_bf16_f32 v45, v50, v51
	v_cvt_pk_bf16_f32 v46, v40, v41
	v_cvt_pk_bf16_f32 v47, v42, v43
	s_mov_b64 s[24:25], s[18:19]
	s_nop 0
	v_add_u32_e32 v52, 0x90, v152
	v_add_u32_e32 v40, v122, v52
	v_ashrrev_i32_e32 v41, 31, v40
	v_lshlrev_b64 v[40:41], 12, v[40:41]
	v_lshl_add_u64 v[40:41], s[68:69], 0, v[40:41]
	v_lshl_add_u64 v[40:41], v[40:41], 0, v[136:137]
	global_store_dwordx4 v[40:41], v[44:47], off
	v_cvt_pk_bf16_f32 v36, v36, v37
	v_cvt_pk_bf16_f32 v37, v38, v39
	v_cvt_pk_bf16_f32 v38, v28, v29
	v_add_u32_e32 v28, v121, v52
	v_ashrrev_i32_e32 v29, 31, v28
	v_lshlrev_b64 v[28:29], 12, v[28:29]
	v_lshl_add_u64 v[28:29], s[68:69], 0, v[28:29]
	v_lshl_add_u64 v[28:29], v[28:29], 0, v[108:109]
	v_cvt_pk_bf16_f32 v39, v30, v31
	global_store_dwordx4 v[28:29], v[36:39], off
	v_cvt_pk_bf16_f32 v28, v32, v33
	v_cvt_pk_bf16_f32 v29, v34, v35
	v_cvt_pk_bf16_f32 v30, v24, v25
	v_cvt_pk_bf16_f32 v31, v26, v27
	s_mov_b64 s[22:23], s[16:17]
	s_nop 0
	v_add_u32_e32 v36, 0xa0, v152
	v_add_u32_e32 v24, v122, v36
	v_ashrrev_i32_e32 v25, 31, v24
	v_lshlrev_b64 v[24:25], 12, v[24:25]
	v_lshl_add_u64 v[24:25], s[68:69], 0, v[24:25]
	v_lshl_add_u64 v[24:25], v[24:25], 0, v[136:137]
	global_store_dwordx4 v[24:25], v[28:31], off
	v_cvt_pk_bf16_f32 v20, v20, v21
	v_cvt_pk_bf16_f32 v21, v22, v23
	v_cvt_pk_bf16_f32 v22, v12, v13
	v_add_u32_e32 v12, v121, v36
	v_ashrrev_i32_e32 v13, 31, v12
	v_lshlrev_b64 v[12:13], 12, v[12:13]
	v_lshl_add_u64 v[12:13], s[68:69], 0, v[12:13]
	v_lshl_add_u64 v[12:13], v[12:13], 0, v[108:109]
	v_cvt_pk_bf16_f32 v23, v14, v15
	global_store_dwordx4 v[12:13], v[20:23], off
	v_cvt_pk_bf16_f32 v12, v16, v17
	v_cvt_pk_bf16_f32 v13, v18, v19
	v_cvt_pk_bf16_f32 v14, v8, v9
	v_cvt_pk_bf16_f32 v15, v10, v11
	s_nop 1
	v_add_u32_e32 v20, 0xb0, v152
	v_add_u32_e32 v8, v122, v20
	v_ashrrev_i32_e32 v9, 31, v8
	v_lshlrev_b64 v[8:9], 12, v[8:9]
	v_lshl_add_u64 v[8:9], s[68:69], 0, v[8:9]
	v_lshl_add_u64 v[8:9], v[8:9], 0, v[136:137]
	global_store_dwordx4 v[8:9], v[12:15], off
	v_cvt_pk_bf16_f32 v4, v4, v5
	v_cvt_pk_bf16_f32 v5, v6, v7
	v_cvt_pk_bf16_f32 v6, v0, v1
	v_add_u32_e32 v0, v121, v20
	v_ashrrev_i32_e32 v1, 31, v0
	v_lshlrev_b64 v[0:1], 12, v[0:1]
	v_lshl_add_u64 v[0:1], s[68:69], 0, v[0:1]
	v_lshl_add_u64 v[0:1], v[0:1], 0, v[108:109]
	v_cvt_pk_bf16_f32 v7, v2, v3
	global_store_dwordx4 v[0:1], v[4:7], off
	s_cbranch_vccz .LBB0_646
	s_waitcnt vmcnt(0)
	s_cmpk_gt_u32 s28, 0xff
	s_cbranch_scc1 .LBB0_657
	s_barrier

; #define PG8_STAGE(bufoff, gbase, voff) do { _Pragma("unroll") for (int _i = 0; _i < 2; ++_i) \
;         __builtin_amdgcn_global_load_lds((const unsigned*)((const char*)(gbase) + (voff)[_i]), (LAS unsigned*)(lds + (bufoff) + ldsw + _i * 8192), 16, 0, 0); } while (0)
; #define PG8_LDA(dst, b, h) do { _Pragma("unroll") for (int m = 0; m < 4; ++m) _Pragma("unroll") for (int k = 0; k < 2; ++k) dst[m][k] = *(const LAS bf16x8*)(lds + PG8_SA(b, h) + aoff + m * 2048 + k * 1024); } while (0)
; #define PG8_LDB(dst, b, h) do { _Pragma("unroll") for (int n = 0; n < 2; ++n) _Pragma("unroll") for (int k = 0; k < 2; ++k) dst[n][k] = *(const LAS bf16x8*)(lds + PG8_SB(b, h) + boff + n * 2048 + k * 1024); } while (0)
; #define PG8_MMA(ai, bj, At, Bt) do { __builtin_amdgcn_s_setprio(1); _Pragma("unroll") for (int m = 0; m < 4; ++m) _Pragma("unroll") for (int n = 0; n < 2; ++n) _Pragma("unroll") for (int k = 0; k < 2; ++k) \
;         acc[ai][bj][m][n] = __builtin_amdgcn_mfma_f32_16x16x32_bf16(Bt[n][k], At[m][k], acc[ai][bj][m][n], 0, 0, 0); __builtin_amdgcn_s_setprio(0); } while (0)
; #define PG8_WAIT_L(n) asm volatile("s_waitcnt lgkmcnt(" #n ")" ::: "memory")
; template <class Epi, class Sched>
; __device__ __forceinline__ void gemm_phase(LAS unsigned char* lds, const Gemm g, const Sched& S, const Epi& E) {
;     ...
;         const bool has_next = S.next(ui + 1, nxt);
;         const char* nA = has_next ? (const char*)g.A + (size_t)nxt.pm * tstep : cA; const char* nB = has_next ? (const char*)g.Bt + (size_t)nxt.pn * tstep : cB;
;         for (int t = 0; t < nt; t += 2) {
;             const bool last = (t == nt - 2);
;             const char* a1 = cA + (size_t)(t + 1) * kstep;
;             const char* a2 = last ? nA : cA + (size_t)(t + 2) * kstep; const char* b2 = last ? nB : cB + (size_t)(t + 2) * kstep;
;             const char* a3 = a2 + kstep; const char* b3 = b2 + kstep;
;             PG8_LDB(B0, 0, 0); PG8_SCHED; PG8_LDA(At, 0, 0); PG8_STAGE(PG8_SA(1, 1), a1 + hstep, voffA);
;             PG8_WAIT_L(8); PG8_BAR; PG8_WAIT_L(0); PG8_MMA(0, 0, At, B0); PG8_BAR; PG8_SCHED;
;             PG8_LDB(B1, 0, 1); PG8_STAGE(PG8_SB(0, 0), b2, voffB);
;             PG8_BAR; PG8_WAIT_L(0); PG8_MMA(0, 1, At, B1); PG8_BAR;
;             PG8_LDA(At, 0, 1); PG8_STAGE(PG8_SA(0, 0), a2, voffA);
;             PG8_BAR; PG8_WAIT_L(0); PG8_MMA(1, 0, At, B0); PG8_BAR; PG8_SCHED;
.LBB0_672:
	s_ashr_i32 s9, s8, 31
	v_cmp_lt_i64_e32 vcc, s[12:13], v[142:143]
	s_lshl_b64 s[12:13], s[8:9], 19
	s_add_u32 s12, s26, s12
	s_addc_u32 s13, s27, s13
	s_and_b64 s[14:15], vcc, exec
	s_cselect_b32 s9, s13, s19
	s_cselect_b32 s46, s12, s18
	s_ashr_i32 s7, s6, 31
	s_lshl_b64 s[14:15], s[6:7], 19
	s_add_u32 s14, s10, s14
	s_addc_u32 s15, s11, s15
	s_and_b64 s[22:23], vcc, exec
	s_cselect_b32 s7, s15, s21
	s_cselect_b32 s47, s14, s20
	s_add_u32 s18, s18, 0x40080
	s_addc_u32 s19, s19, 0
	s_add_u32 s48, s20, 0x100
	s_addc_u32 s49, s21, 0
	s_mov_b32 s51, -2
	s_waitcnt lgkmcnt(0)
	ds_read_b128 v[152:155], v149
	ds_read_b128 v[156:159], v149 offset:1024
	ds_read_b128 v[160:163], v149 offset:2048
	ds_read_b128 v[164:167], v149 offset:3072
	s_add_u32 s20, s18, 0xfffc0080
	s_addc_u32 s21, s19, -1
	s_cmp_eq_u32 s51, 12
	s_cselect_b32 s23, s9, s21
	s_cselect_b32 s22, s46, s20
	s_cselect_b32 s21, s7, s49
	s_cselect_b32 s20, s47, s48
	s_add_i32 m0, s17, 0xc000
	ds_read_b128 v[168:171], v150
	ds_read_b128 v[172:175], v150 offset:1024
	ds_read_b128 v[176:179], v150 offset:2048
	ds_read_b128 v[180:183], v150 offset:3072
	ds_read_b128 v[184:187], v150 offset:4096
	ds_read_b128 v[188:191], v150 offset:5120
	ds_read_b128 v[192:195], v150 offset:6144
	ds_read_b128 v[196:199], v150 offset:7168
	global_load_lds_dwordx4 v138, s[18:19]
	s_add_i32 m0, s17, 0xe000
	s_nop 0
	global_load_lds_dwordx4 v140, s[18:19]
	s_waitcnt lgkmcnt(8)
	s_waitcnt vmcnt(8)
	s_barrier
	s_waitcnt lgkmcnt(0)
	s_setprio 1
	s_waitcnt lgkmcnt(0)
	v_mfma_f32_16x16x32_bf16 v[124:127], v[152:155], v[168:171], 0
	v_mfma_f32_16x16x32_bf16 v[120:123], v[160:163], v[168:171], 0
	v_mfma_f32_16x16x32_bf16 v[112:115], v[152:155], v[176:179], 0
	v_mfma_f32_16x16x32_bf16 v[104:107], v[160:163], v[176:179], 0
	v_mfma_f32_16x16x32_bf16 v[96:99], v[152:155], v[184:187], 0
	v_mfma_f32_16x16x32_bf16 v[88:91], v[160:163], v[184:187], 0
	v_mfma_f32_16x16x32_bf16 v[80:83], v[152:155], v[192:195], 0
	v_mfma_f32_16x16x32_bf16 v[72:75], v[160:163], v[192:195], 0
	v_mfma_f32_16x16x32_bf16 v[124:127], v[156:159], v[172:175], v[124:127]
	v_mfma_f32_16x16x32_bf16 v[120:123], v[164:167], v[172:175], v[120:123]
	v_mfma_f32_16x16x32_bf16 v[112:115], v[156:159], v[180:183], v[112:115]
	v_mfma_f32_16x16x32_bf16 v[104:107], v[164:167], v[180:183], v[104:107]
	v_mfma_f32_16x16x32_bf16 v[96:99], v[156:159], v[188:191], v[96:99]
	v_mfma_f32_16x16x32_bf16 v[88:91], v[164:167], v[188:191], v[88:91]
	v_mfma_f32_16x16x32_bf16 v[80:83], v[156:159], v[196:199], v[80:83]
	v_mfma_f32_16x16x32_bf16 v[72:75], v[164:167], v[196:199], v[72:75]
	s_setprio 0
	s_barrier
	s_add_i32 s52, s43, s28
	s_mov_b32 m0, s52
	ds_read_b128 v[202:205], v151
	ds_read_b128 v[206:209], v151 offset:1024
	ds_read_b128 v[210:213], v151 offset:2048
	ds_read_b128 v[214:217], v151 offset:3072
	global_load_lds_dwordx4 v130, s[20:21]
	s_add_i32 m0, s52, 0x2000
	s_nop 0
	global_load_lds_dwordx4 v134, s[20:21]
	s_waitcnt vmcnt(8)
	s_barrier
	s_waitcnt lgkmcnt(0)
	s_setprio 1
	s_waitcnt lgkmcnt(0)
	v_mfma_f32_16x16x32_bf16 v[116:119], v[202:205], v[168:171], 0
	v_mfma_f32_16x16x32_bf16 v[108:111], v[210:213], v[168:171], 0
	v_mfma_f32_16x16x32_bf16 v[100:103], v[202:205], v[176:179], 0
	v_mfma_f32_16x16x32_bf16 v[92:95], v[210:213], v[176:179], 0
	v_mfma_f32_16x16x32_bf16 v[84:87], v[202:205], v[184:187], 0
	v_mfma_f32_16x16x32_bf16 v[76:79], v[210:213], v[184:187], 0
	v_mfma_f32_16x16x32_bf16 v[68:71], v[202:205], v[192:195], 0
	v_mfma_f32_16x16x32_bf16 v[64:67], v[210:213], v[192:195], 0
	v_mfma_f32_16x16x32_bf16 v[116:119], v[206:209], v[172:175], v[116:119]
	v_mfma_f32_16x16x32_bf16 v[108:111], v[214:217], v[172:175], v[108:111]
	v_mfma_f32_16x16x32_bf16 v[100:103], v[206:209], v[180:183], v[100:103]
	v_mfma_f32_16x16x32_bf16 v[92:95], v[214:217], v[180:183], v[92:95]
	v_mfma_f32_16x16x32_bf16 v[84:87], v[206:209], v[188:191], v[84:87]
	v_mfma_f32_16x16x32_bf16 v[76:79], v[214:217], v[188:191], v[76:79]
	v_mfma_f32_16x16x32_bf16 v[68:71], v[206:209], v[196:199], v[68:71]
	v_mfma_f32_16x16x32_bf16 v[64:67], v[214:217], v[196:199], v[64:67]
	s_setprio 0
	s_mov_b32 m0, s17
	v_lshl_add_u64 v[222:223], s[22:23], 0, v[128:129]
	s_barrier
	ds_read_b128 v[168:171], v150 offset:16384
	ds_read_b128 v[172:175], v150 offset:17408
	ds_read_b128 v[176:179], v150 offset:18432
	ds_read_b128 v[180:183], v150 offset:19456
	ds_read_b128 v[184:187], v150 offset:20480
	ds_read_b128 v[188:191], v150 offset:21504
	ds_read_b128 v[192:195], v150 offset:22528
	ds_read_b128 v[196:199], v150 offset:23552
	global_load_lds_dwordx4 v128, s[22:23]
	v_lshl_add_u64 v[224:225], s[22:23], 0, v[132:133]
	s_mov_b32 m0, s29
	s_nop 0
	global_load_lds_dwordx4 v132, s[22:23]
	s_barrier
	s_waitcnt lgkmcnt(0)
	s_setprio 1
	s_waitcnt lgkmcnt(0)
	v_mfma_f32_16x16x32_bf16 v[60:63], v[152:155], v[168:171], 0
	v_mfma_f32_16x16x32_bf16 v[56:59], v[160:163], v[168:171], 0
	v_mfma_f32_16x16x32_bf16 v[48:51], v[152:155], v[176:179], 0
	v_mfma_f32_16x16x32_bf16 v[40:43], v[160:163], v[176:179], 0
	v_mfma_f32_16x16x32_bf16 v[32:35], v[152:155], v[184:187], 0
	v_mfma_f32_16x16x32_bf16 v[24:27], v[160:163], v[184:187], 0
	v_mfma_f32_16x16x32_bf16 v[16:19], v[152:155], v[192:195], 0
	v_mfma_f32_16x16x32_bf16 v[8:11], v[160:163], v[192:195], 0
	v_mfma_f32_16x16x32_bf16 v[60:63], v[156:159], v[172:175], v[60:63]
	v_mfma_f32_16x16x32_bf16 v[56:59], v[164:167], v[172:175], v[56:59]
	v_mfma_f32_16x16x32_bf16 v[48:51], v[156:159], v[180:183], v[48:51]
	v_mfma_f32_16x16x32_bf16 v[40:43], v[164:167], v[180:183], v[40:43]
	v_mfma_f32_16x16x32_bf16 v[32:35], v[156:159], v[188:191], v[32:35]
	v_mfma_f32_16x16x32_bf16 v[24:27], v[164:167], v[188:191], v[24:27]
	v_mfma_f32_16x16x32_bf16 v[16:19], v[156:159], v[196:199], v[16:19]
	v_mfma_f32_16x16x32_bf16 v[8:11], v[164:167], v[196:199], v[8:11]
	s_setprio 0
	s_barrier
; #define PG8_STAGE(bufoff, gbase, voff) do { _Pragma("unroll") for (int _i = 0; _i < 2; ++_i) \
;         __builtin_amdgcn_global_load_lds((const unsigned*)((const char*)(gbase) + (voff)[_i]), (LAS unsigned*)(lds + (bufoff) + ldsw + _i * 8192), 16, 0, 0); } while (0)
; #define PG8_LDA(dst, b, h) do { _Pragma("unroll") for (int m = 0; m < 4; ++m) _Pragma("unroll") for (int k = 0; k < 2; ++k) dst[m][k] = *(const LAS bf16x8*)(lds + PG8_SA(b, h) + aoff + m * 2048 + k * 1024); } while (0)
; #define PG8_LDB(dst, b, h) do { _Pragma("unroll") for (int n = 0; n < 2; ++n) _Pragma("unroll") for (int k = 0; k < 2; ++k) dst[n][k] = *(const LAS bf16x8*)(lds + PG8_SB(b, h) + boff + n * 2048 + k * 1024); } while (0)
; #define PG8_MMA(ai, bj, At, Bt) do { __builtin_amdgcn_s_setprio(1); _Pragma("unroll") for (int m = 0; m < 4; ++m) _Pragma("unroll") for (int n = 0; n < 2; ++n) _Pragma("unroll") for (int k = 0; k < 2; ++k) \
;         acc[ai][bj][m][n] = __builtin_amdgcn_mfma_f32_16x16x32_bf16(Bt[n][k], At[m][k], acc[ai][bj][m][n], 0, 0, 0); __builtin_amdgcn_s_setprio(0); } while (0)
; #define PG8_WAIT_V(n) asm volatile("s_waitcnt vmcnt(" #n ")" ::: "memory")
; #define PG8_WAIT_L(n) asm volatile("s_waitcnt lgkmcnt(" #n ")" ::: "memory")
; #define PG8_BAR __builtin_amdgcn_s_barrier()
; #define PG8_SCHED __builtin_amdgcn_sched_barrier(0)
; template <class Epi, class Sched>
; __device__ __forceinline__ void gemm_phase(LAS unsigned char* lds, const Gemm g, const Sched& S, const Epi& E) {
;     ...
;             PG8_STAGE(PG8_SB(0, 1), b2 + hstep, voffB);
;             PG8_WAIT_V(6); PG8_BAR; PG8_MMA(1, 1, At, B1); PG8_BAR;
;             PG8_LDB(B0, 1, 0); PG8_SCHED; PG8_LDA(At, 1, 0); PG8_STAGE(PG8_SA(0, 1), a2 + hstep, voffA);
;             PG8_WAIT_L(8); PG8_BAR; PG8_WAIT_L(0); PG8_MMA(0, 0, At, B0); PG8_BAR; PG8_SCHED;
;             PG8_LDB(B1, 1, 1); PG8_STAGE(PG8_SB(1, 0), b3, voffB);
;             PG8_BAR; PG8_WAIT_L(0); PG8_MMA(0, 1, At, B1); PG8_BAR;
;             PG8_LDA(At, 1, 1); PG8_STAGE(PG8_SA(1, 0), a3, voffA);
	s_add_u32 s52, s20, 0x40000
	s_addc_u32 s53, s21, 0
	s_add_i32 s54, s44, s28
	s_mov_b32 m0, s54
	s_nop 0
	global_load_lds_dwordx4 v130, s[52:53]
	s_add_i32 m0, s54, 0x2000
	s_nop 0
	global_load_lds_dwordx4 v134, s[52:53]
	s_add_u32 s22, s22, 0x40000
	s_addc_u32 s23, s23, 0
	s_mov_b32 m0, s30
	s_nop 0
	global_load_lds_dwordx4 v128, s[22:23]
	s_mov_b32 m0, s31
	s_nop 0
	global_load_lds_dwordx4 v132, s[22:23]
	s_waitcnt vmcnt(10)
	s_barrier
	s_setprio 1
	v_mfma_f32_16x16x32_bf16 v[52:55], v[202:205], v[168:171], 0
	v_mfma_f32_16x16x32_bf16 v[44:47], v[210:213], v[168:171], 0
	v_mfma_f32_16x16x32_bf16 v[36:39], v[202:205], v[176:179], 0
	v_mfma_f32_16x16x32_bf16 v[28:31], v[210:213], v[176:179], 0
	v_mfma_f32_16x16x32_bf16 v[20:23], v[202:205], v[184:187], 0
	v_mfma_f32_16x16x32_bf16 v[12:15], v[210:213], v[184:187], 0
	v_mfma_f32_16x16x32_bf16 v[4:7], v[202:205], v[192:195], 0
	v_mfma_f32_16x16x32_bf16 v[0:3], v[210:213], v[192:195], 0
	v_mfma_f32_16x16x32_bf16 v[52:55], v[206:209], v[172:175], v[52:55]
	v_mfma_f32_16x16x32_bf16 v[44:47], v[214:217], v[172:175], v[44:47]
	v_mfma_f32_16x16x32_bf16 v[36:39], v[206:209], v[180:183], v[36:39]
	v_mfma_f32_16x16x32_bf16 v[28:31], v[214:217], v[180:183], v[28:31]
	v_mfma_f32_16x16x32_bf16 v[20:23], v[206:209], v[188:191], v[20:23]
	v_mfma_f32_16x16x32_bf16 v[12:15], v[214:217], v[188:191], v[12:15]
	v_mfma_f32_16x16x32_bf16 v[4:7], v[206:209], v[196:199], v[4:7]
	v_mfma_f32_16x16x32_bf16 v[0:3], v[214:217], v[196:199], v[0:3]
	s_setprio 0
	s_add_i32 s52, 0, 0x18000
	v_add_u32_e32 v136, s52, v148
	s_barrier
	ds_read_b128 v[152:155], v136
	ds_read_b128 v[156:159], v136 offset:1024
	ds_read_b128 v[160:163], v136 offset:2048
	ds_read_b128 v[164:167], v136 offset:3072
	ds_read_b128 v[168:171], v150 offset:32768
	ds_read_b128 v[172:175], v150 offset:33792
	ds_read_b128 v[176:179], v150 offset:34816
	ds_read_b128 v[180:183], v150 offset:35840
	ds_read_b128 v[184:187], v150 offset:36864
	ds_read_b128 v[188:191], v150 offset:37888
	ds_read_b128 v[192:195], v150 offset:38912
	ds_read_b128 v[196:199], v150 offset:39936
	s_waitcnt lgkmcnt(8)
	s_waitcnt vmcnt(8)
	s_barrier
	s_waitcnt lgkmcnt(0)
	s_setprio 1
	s_waitcnt lgkmcnt(0)
	v_mfma_f32_16x16x32_bf16 v[124:127], v[152:155], v[168:171], v[124:127]
	v_mfma_f32_16x16x32_bf16 v[120:123], v[160:163], v[168:171], v[120:123]
	v_mfma_f32_16x16x32_bf16 v[112:115], v[152:155], v[176:179], v[112:115]
	v_mfma_f32_16x16x32_bf16 v[104:107], v[160:163], v[176:179], v[104:107]
	v_mfma_f32_16x16x32_bf16 v[96:99], v[152:155], v[184:187], v[96:99]
	v_mfma_f32_16x16x32_bf16 v[88:91], v[160:163], v[184:187], v[88:91]
	v_mfma_f32_16x16x32_bf16 v[80:83], v[152:155], v[192:195], v[80:83]
	v_mfma_f32_16x16x32_bf16 v[72:75], v[160:163], v[192:195], v[72:75]
	v_mfma_f32_16x16x32_bf16 v[124:127], v[156:159], v[172:175], v[124:127]
	v_mfma_f32_16x16x32_bf16 v[120:123], v[164:167], v[172:175], v[120:123]
	v_mfma_f32_16x16x32_bf16 v[112:115], v[156:159], v[180:183], v[112:115]
	v_mfma_f32_16x16x32_bf16 v[104:107], v[164:167], v[180:183], v[104:107]
	v_mfma_f32_16x16x32_bf16 v[96:99], v[156:159], v[188:191], v[96:99]
	v_mfma_f32_16x16x32_bf16 v[88:91], v[164:167], v[188:191], v[88:91]
	v_mfma_f32_16x16x32_bf16 v[80:83], v[156:159], v[196:199], v[80:83]
	v_mfma_f32_16x16x32_bf16 v[72:75], v[164:167], v[196:199], v[72:75]
	s_setprio 0
	s_barrier
	s_add_i32 s22, 0, 0x1c000
	s_add_i32 s23, s52, s28
	v_add_u32_e32 v136, s22, v148
	s_add_u32 s0, s20, 0x80
	s_addc_u32 s1, s21, 0
	s_mov_b32 m0, s23
	ds_read_b128 v[202:205], v136
	ds_read_b128 v[206:209], v136 offset:1024
	ds_read_b128 v[210:213], v136 offset:2048
	ds_read_b128 v[214:217], v136 offset:3072
	global_load_lds_dwordx4 v130, s[0:1]
	s_add_i32 m0, s23, 0x2000
	s_nop 0
	global_load_lds_dwordx4 v134, s[0:1]
	s_waitcnt vmcnt(8)
	s_barrier
	s_waitcnt lgkmcnt(0)
	s_setprio 1
	s_waitcnt lgkmcnt(0)
	v_mfma_f32_16x16x32_bf16 v[116:119], v[202:205], v[168:171], v[116:119]
	v_mfma_f32_16x16x32_bf16 v[108:111], v[210:213], v[168:171], v[108:111]
	v_mfma_f32_16x16x32_bf16 v[100:103], v[202:205], v[176:179], v[100:103]
	v_mfma_f32_16x16x32_bf16 v[92:95], v[210:213], v[176:179], v[92:95]
	v_mfma_f32_16x16x32_bf16 v[84:87], v[202:205], v[184:187], v[84:87]
	v_mfma_f32_16x16x32_bf16 v[76:79], v[210:213], v[184:187], v[76:79]
	v_mfma_f32_16x16x32_bf16 v[68:71], v[202:205], v[192:195], v[68:71]
	v_mfma_f32_16x16x32_bf16 v[64:67], v[210:213], v[192:195], v[64:67]
	v_mfma_f32_16x16x32_bf16 v[116:119], v[206:209], v[172:175], v[116:119]
	v_mfma_f32_16x16x32_bf16 v[108:111], v[214:217], v[172:175], v[108:111]
	v_mfma_f32_16x16x32_bf16 v[100:103], v[206:209], v[180:183], v[100:103]
	v_mfma_f32_16x16x32_bf16 v[92:95], v[214:217], v[180:183], v[92:95]
	v_mfma_f32_16x16x32_bf16 v[84:87], v[206:209], v[188:191], v[84:87]
	v_mfma_f32_16x16x32_bf16 v[76:79], v[214:217], v[188:191], v[76:79]
	v_mfma_f32_16x16x32_bf16 v[68:71], v[206:209], v[196:199], v[68:71]
	v_mfma_f32_16x16x32_bf16 v[64:67], v[214:217], v[196:199], v[64:67]
	s_setprio 0
	s_mov_b32 m0, s36
	s_mov_b64 s[0:1], 0x80
	v_lshl_add_u64 v[218:219], v[222:223], 0, s[0:1]
	s_barrier
	ds_read_b128 v[168:171], v150 offset:49152
	ds_read_b128 v[172:175], v150 offset:50176
	ds_read_b128 v[176:179], v150 offset:51200
	ds_read_b128 v[180:183], v150 offset:52224
	ds_read_b128 v[184:187], v150 offset:53248
	ds_read_b128 v[188:191], v150 offset:54272
	ds_read_b128 v[192:195], v150 offset:55296
	ds_read_b128 v[196:199], v150 offset:56320
	global_load_lds_dwordx4 v[218:219], off
	v_lshl_add_u64 v[218:219], v[224:225], 0, s[0:1]
	s_mov_b32 m0, s37
	s_nop 0
	global_load_lds_dwordx4 v[218:219], off
	s_barrier
; #define PG8_STAGE(bufoff, gbase, voff) do { _Pragma("unroll") for (int _i = 0; _i < 2; ++_i) \
;         __builtin_amdgcn_global_load_lds((const unsigned*)((const char*)(gbase) + (voff)[_i]), (LAS unsigned*)(lds + (bufoff) + ldsw + _i * 8192), 16, 0, 0); } while (0)
; #define PG8_LDA(dst, b, h) do { _Pragma("unroll") for (int m = 0; m < 4; ++m) _Pragma("unroll") for (int k = 0; k < 2; ++k) dst[m][k] = *(const LAS bf16x8*)(lds + PG8_SA(b, h) + aoff + m * 2048 + k * 1024); } while (0)
; #define PG8_LDB(dst, b, h) do { _Pragma("unroll") for (int n = 0; n < 2; ++n) _Pragma("unroll") for (int k = 0; k < 2; ++k) dst[n][k] = *(const LAS bf16x8*)(lds + PG8_SB(b, h) + boff + n * 2048 + k * 1024); } while (0)
; #define PG8_WAIT_V(n) asm volatile("s_waitcnt vmcnt(" #n ")" ::: "memory")
; #define PG8_WAIT_L(n) asm volatile("s_waitcnt lgkmcnt(" #n ")" ::: "memory")
; #define PG8_BAR __builtin_amdgcn_s_barrier()
; #define PG8_SCHED __builtin_amdgcn_sched_barrier(0)
; template <class Epi, class Sched>
; __device__ __forceinline__ void gemm_phase(LAS unsigned char* lds, const Gemm g, const Sched& S, const Epi& E) {
;     ...
;             PG8_LDB(B0, 0, 0); PG8_SCHED; PG8_LDA(At, 0, 0); PG8_STAGE(PG8_SA(1, 1), a1 + hstep, voffA);
;             PG8_WAIT_L(8); PG8_BAR; PG8_WAIT_L(0); PG8_MMA(0, 0, At, B0); PG8_BAR; PG8_SCHED;
;             PG8_LDB(B1, 0, 1); PG8_STAGE(PG8_SB(0, 0), b2, voffB);
;             PG8_BAR; PG8_WAIT_L(0); PG8_MMA(0, 1, At, B1); PG8_BAR;
;             PG8_LDA(At, 0, 1); PG8_STAGE(PG8_SA(0, 0), a2, voffA);
;             PG8_BAR; PG8_WAIT_L(0); PG8_MMA(1, 0, At, B0); PG8_BAR; PG8_SCHED;
;             PG8_STAGE(PG8_SB(0, 1), b2 + hstep, voffB);
;             PG8_WAIT_V(6); PG8_BAR; PG8_MMA(1, 1, At, B1); PG8_BAR;
;             PG8_LDB(B0, 1, 0); PG8_SCHED; PG8_LDA(At, 1, 0); PG8_STAGE(PG8_SA(0, 1), a2 + hstep, voffA);
;             PG8_WAIT_L(8); PG8_BAR; PG8_WAIT_L(0); PG8_MMA(0, 0, At, B0); PG8_BAR; PG8_SCHED;
;             PG8_LDB(B1, 1, 1); PG8_STAGE(PG8_SB(1, 0), b3, voffB);
;             PG8_BAR; PG8_WAIT_L(0); PG8_MMA(0, 1, At, B1); PG8_BAR;
;             PG8_LDA(At, 1, 1); PG8_STAGE(PG8_SA(1, 0), a3, voffA);
;             PG8_BAR; PG8_WAIT_L(0); PG8_MMA(1, 0, At, B0); PG8_BAR; PG8_SCHED;
;             PG8_STAGE(PG8_SB(1, 1), b3 + hstep, voffB);
;             PG8_WAIT_V(6); PG8_BAR; PG8_MMA(1, 1, At, B1); PG8_BAR;
	s_waitcnt lgkmcnt(0)
	s_setprio 1
	s_waitcnt lgkmcnt(0)
	v_mfma_f32_16x16x32_bf16 v[60:63], v[152:155], v[168:171], v[60:63]
	v_mfma_f32_16x16x32_bf16 v[56:59], v[160:163], v[168:171], v[56:59]
	v_mfma_f32_16x16x32_bf16 v[48:51], v[152:155], v[176:179], v[48:51]
	v_mfma_f32_16x16x32_bf16 v[40:43], v[160:163], v[176:179], v[40:43]
	v_mfma_f32_16x16x32_bf16 v[32:35], v[152:155], v[184:187], v[32:35]
	v_mfma_f32_16x16x32_bf16 v[24:27], v[160:163], v[184:187], v[24:27]
	v_mfma_f32_16x16x32_bf16 v[16:19], v[152:155], v[192:195], v[16:19]
	v_mfma_f32_16x16x32_bf16 v[8:11], v[160:163], v[192:195], v[8:11]
	v_mfma_f32_16x16x32_bf16 v[60:63], v[156:159], v[172:175], v[60:63]
	v_mfma_f32_16x16x32_bf16 v[56:59], v[164:167], v[172:175], v[56:59]
	v_mfma_f32_16x16x32_bf16 v[48:51], v[156:159], v[180:183], v[48:51]
	v_mfma_f32_16x16x32_bf16 v[40:43], v[164:167], v[180:183], v[40:43]
	v_mfma_f32_16x16x32_bf16 v[32:35], v[156:159], v[188:191], v[32:35]
	v_mfma_f32_16x16x32_bf16 v[24:27], v[164:167], v[188:191], v[24:27]
	v_mfma_f32_16x16x32_bf16 v[16:19], v[156:159], v[196:199], v[16:19]
	v_mfma_f32_16x16x32_bf16 v[8:11], v[164:167], v[196:199], v[8:11]
	s_setprio 0
	s_barrier
	s_add_u32 s20, s20, 0x40080
	s_addc_u32 s21, s21, 0
	s_add_i32 s22, s22, s28
	s_mov_b32 m0, s22
	s_nop 0
	global_load_lds_dwordx4 v130, s[20:21]
	s_add_i32 m0, s22, 0x2000
	s_nop 0
	global_load_lds_dwordx4 v134, s[20:21]
	s_waitcnt vmcnt(8)
	s_barrier
	s_setprio 1
	v_mfma_f32_16x16x32_bf16 v[52:55], v[202:205], v[168:171], v[52:55]
	v_mfma_f32_16x16x32_bf16 v[44:47], v[210:213], v[168:171], v[44:47]
	v_mfma_f32_16x16x32_bf16 v[36:39], v[202:205], v[176:179], v[36:39]
	v_mfma_f32_16x16x32_bf16 v[28:31], v[210:213], v[176:179], v[28:31]
	v_mfma_f32_16x16x32_bf16 v[20:23], v[202:205], v[184:187], v[20:23]
	v_mfma_f32_16x16x32_bf16 v[12:15], v[210:213], v[184:187], v[12:15]
	v_mfma_f32_16x16x32_bf16 v[4:7], v[202:205], v[192:195], v[4:7]
	v_mfma_f32_16x16x32_bf16 v[0:3], v[210:213], v[192:195], v[0:3]
	v_mfma_f32_16x16x32_bf16 v[52:55], v[206:209], v[172:175], v[52:55]
	v_mfma_f32_16x16x32_bf16 v[44:47], v[214:217], v[172:175], v[44:47]
	v_mfma_f32_16x16x32_bf16 v[36:39], v[206:209], v[180:183], v[36:39]
	v_mfma_f32_16x16x32_bf16 v[28:31], v[214:217], v[180:183], v[28:31]
	v_mfma_f32_16x16x32_bf16 v[20:23], v[206:209], v[188:191], v[20:23]
	v_mfma_f32_16x16x32_bf16 v[12:15], v[214:217], v[188:191], v[12:15]
	v_mfma_f32_16x16x32_bf16 v[4:7], v[206:209], v[196:199], v[4:7]
	v_mfma_f32_16x16x32_bf16 v[0:3], v[214:217], v[196:199], v[0:3]
	s_setprio 0
	s_add_i32 s51, s51, 2
	s_add_u32 s18, s18, 0x100
	s_addc_u32 s19, s19, 0
	s_add_u32 s48, s48, 0x100
	s_addc_u32 s49, s49, 0
	s_cmp_gt_u32 s51, 13
	s_barrier
.LBB0_673:
	ds_read_b128 v[152:155], v149
	ds_read_b128 v[156:159], v149 offset:1024
	ds_read_b128 v[160:163], v149 offset:2048
	ds_read_b128 v[164:167], v149 offset:3072
	s_add_u32 s20, s18, 0xfffc0080
	s_addc_u32 s21, s19, -1
	s_cmp_eq_u32 s51, 12
	s_cselect_b32 s23, s9, s21
	s_cselect_b32 s22, s46, s20
	s_cselect_b32 s21, s7, s49
	s_cselect_b32 s20, s47, s48
	s_add_i32 m0, s17, 0xc000
	ds_read_b128 v[168:171], v150
	ds_read_b128 v[172:175], v150 offset:1024
	ds_read_b128 v[176:179], v150 offset:2048
	ds_read_b128 v[180:183], v150 offset:3072
	ds_read_b128 v[184:187], v150 offset:4096
	ds_read_b128 v[188:191], v150 offset:5120
	ds_read_b128 v[192:195], v150 offset:6144
	ds_read_b128 v[196:199], v150 offset:7168
	global_load_lds_dwordx4 v138, s[18:19]
	s_add_i32 m0, s17, 0xe000
	s_nop 0
	global_load_lds_dwordx4 v140, s[18:19]
	s_waitcnt lgkmcnt(8)
	s_waitcnt vmcnt(8)
	s_barrier
	s_waitcnt lgkmcnt(0)
	s_setprio 1
	s_waitcnt lgkmcnt(0)
	v_mfma_f32_16x16x32_bf16 v[124:127], v[152:155], v[168:171], v[124:127]
	v_mfma_f32_16x16x32_bf16 v[120:123], v[160:163], v[168:171], v[120:123]
	v_mfma_f32_16x16x32_bf16 v[112:115], v[152:155], v[176:179], v[112:115]
	v_mfma_f32_16x16x32_bf16 v[104:107], v[160:163], v[176:179], v[104:107]
	v_mfma_f32_16x16x32_bf16 v[96:99], v[152:155], v[184:187], v[96:99]
	v_mfma_f32_16x16x32_bf16 v[88:91], v[160:163], v[184:187], v[88:91]
	v_mfma_f32_16x16x32_bf16 v[80:83], v[152:155], v[192:195], v[80:83]
	v_mfma_f32_16x16x32_bf16 v[72:75], v[160:163], v[192:195], v[72:75]
	v_mfma_f32_16x16x32_bf16 v[124:127], v[156:159], v[172:175], v[124:127]
	v_mfma_f32_16x16x32_bf16 v[120:123], v[164:167], v[172:175], v[120:123]
	v_mfma_f32_16x16x32_bf16 v[112:115], v[156:159], v[180:183], v[112:115]
	v_mfma_f32_16x16x32_bf16 v[104:107], v[164:167], v[180:183], v[104:107]
	v_mfma_f32_16x16x32_bf16 v[96:99], v[156:159], v[188:191], v[96:99]
	v_mfma_f32_16x16x32_bf16 v[88:91], v[164:167], v[188:191], v[88:91]
	v_mfma_f32_16x16x32_bf16 v[80:83], v[156:159], v[196:199], v[80:83]
	v_mfma_f32_16x16x32_bf16 v[72:75], v[164:167], v[196:199], v[72:75]
	s_setprio 0
	s_barrier
	s_add_i32 s52, s43, s28
	s_mov_b32 m0, s52
	ds_read_b128 v[202:205], v151
	ds_read_b128 v[206:209], v151 offset:1024
	ds_read_b128 v[210:213], v151 offset:2048
	ds_read_b128 v[214:217], v151 offset:3072
	global_load_lds_dwordx4 v130, s[20:21]
	s_add_i32 m0, s52, 0x2000
	s_nop 0
	global_load_lds_dwordx4 v134, s[20:21]
	s_waitcnt vmcnt(8)
	s_barrier
; #define PG8_STAGE(bufoff, gbase, voff) do { _Pragma("unroll") for (int _i = 0; _i < 2; ++_i) \
;         __builtin_amdgcn_global_load_lds((const unsigned*)((const char*)(gbase) + (voff)[_i]), (LAS unsigned*)(lds + (bufoff) + ldsw + _i * 8192), 16, 0, 0); } while (0)
; #define PG8_LDA(dst, b, h) do { _Pragma("unroll") for (int m = 0; m < 4; ++m) _Pragma("unroll") for (int k = 0; k < 2; ++k) dst[m][k] = *(const LAS bf16x8*)(lds + PG8_SA(b, h) + aoff + m * 2048 + k * 1024); } while (0)
; #define PG8_LDB(dst, b, h) do { _Pragma("unroll") for (int n = 0; n < 2; ++n) _Pragma("unroll") for (int k = 0; k < 2; ++k) dst[n][k] = *(const LAS bf16x8*)(lds + PG8_SB(b, h) + boff + n * 2048 + k * 1024); } while (0)
; #define PG8_MMA(ai, bj, At, Bt) do { __builtin_amdgcn_s_setprio(1); _Pragma("unroll") for (int m = 0; m < 4; ++m) _Pragma("unroll") for (int n = 0; n < 2; ++n) _Pragma("unroll") for (int k = 0; k < 2; ++k) \
;         acc[ai][bj][m][n] = __builtin_amdgcn_mfma_f32_16x16x32_bf16(Bt[n][k], At[m][k], acc[ai][bj][m][n], 0, 0, 0); __builtin_amdgcn_s_setprio(0); } while (0)
; #define PG8_WAIT_V(n) asm volatile("s_waitcnt vmcnt(" #n ")" ::: "memory")
; #define PG8_BAR __builtin_amdgcn_s_barrier()
; template <class Epi, class Sched>
; __device__ __forceinline__ void gemm_phase(LAS unsigned char* lds, const Gemm g, const Sched& S, const Epi& E) {
;     ...
;             PG8_LDB(B1, 0, 1); PG8_STAGE(PG8_SB(0, 0), b2, voffB);
;             PG8_BAR; PG8_WAIT_L(0); PG8_MMA(0, 1, At, B1); PG8_BAR;
;             PG8_LDA(At, 0, 1); PG8_STAGE(PG8_SA(0, 0), a2, voffA);
;             PG8_BAR; PG8_WAIT_L(0); PG8_MMA(1, 0, At, B0); PG8_BAR; PG8_SCHED;
;             PG8_STAGE(PG8_SB(0, 1), b2 + hstep, voffB);
;             PG8_WAIT_V(6); PG8_BAR; PG8_MMA(1, 1, At, B1); PG8_BAR;
;             PG8_LDB(B0, 1, 0); PG8_SCHED; PG8_LDA(At, 1, 0); PG8_STAGE(PG8_SA(0, 1), a2 + hstep, voffA);
;             PG8_WAIT_L(8); PG8_BAR; PG8_WAIT_L(0); PG8_MMA(0, 0, At, B0); PG8_BAR; PG8_SCHED;
;             PG8_LDB(B1, 1, 1); PG8_STAGE(PG8_SB(1, 0), b3, voffB);
;             PG8_BAR; PG8_WAIT_L(0); PG8_MMA(0, 1, At, B1); PG8_BAR;
;             PG8_LDA(At, 1, 1); PG8_STAGE(PG8_SA(1, 0), a3, voffA);
;             PG8_BAR; PG8_WAIT_L(0); PG8_MMA(1, 0, At, B0); PG8_BAR; PG8_SCHED;
;             PG8_STAGE(PG8_SB(1, 1), b3 + hstep, voffB);
;             PG8_WAIT_V(6); PG8_BAR; PG8_MMA(1, 1, At, B1); PG8_BAR;
	s_waitcnt lgkmcnt(0)
	s_setprio 1
	s_waitcnt lgkmcnt(0)
	v_mfma_f32_16x16x32_bf16 v[116:119], v[202:205], v[168:171], v[116:119]
	v_mfma_f32_16x16x32_bf16 v[108:111], v[210:213], v[168:171], v[108:111]
	v_mfma_f32_16x16x32_bf16 v[100:103], v[202:205], v[176:179], v[100:103]
	v_mfma_f32_16x16x32_bf16 v[92:95], v[210:213], v[176:179], v[92:95]
	v_mfma_f32_16x16x32_bf16 v[84:87], v[202:205], v[184:187], v[84:87]
	v_mfma_f32_16x16x32_bf16 v[76:79], v[210:213], v[184:187], v[76:79]
	v_mfma_f32_16x16x32_bf16 v[68:71], v[202:205], v[192:195], v[68:71]
	v_mfma_f32_16x16x32_bf16 v[64:67], v[210:213], v[192:195], v[64:67]
	v_mfma_f32_16x16x32_bf16 v[116:119], v[206:209], v[172:175], v[116:119]
	v_mfma_f32_16x16x32_bf16 v[108:111], v[214:217], v[172:175], v[108:111]
	v_mfma_f32_16x16x32_bf16 v[100:103], v[206:209], v[180:183], v[100:103]
	v_mfma_f32_16x16x32_bf16 v[92:95], v[214:217], v[180:183], v[92:95]
	v_mfma_f32_16x16x32_bf16 v[84:87], v[206:209], v[188:191], v[84:87]
	v_mfma_f32_16x16x32_bf16 v[76:79], v[214:217], v[188:191], v[76:79]
	v_mfma_f32_16x16x32_bf16 v[68:71], v[206:209], v[196:199], v[68:71]
	v_mfma_f32_16x16x32_bf16 v[64:67], v[214:217], v[196:199], v[64:67]
	s_setprio 0
	s_mov_b32 m0, s17
	v_lshl_add_u64 v[222:223], s[22:23], 0, v[128:129]
	s_barrier
	ds_read_b128 v[168:171], v150 offset:16384
	ds_read_b128 v[172:175], v150 offset:17408
	ds_read_b128 v[176:179], v150 offset:18432
	ds_read_b128 v[180:183], v150 offset:19456
	ds_read_b128 v[184:187], v150 offset:20480
	ds_read_b128 v[188:191], v150 offset:21504
	ds_read_b128 v[192:195], v150 offset:22528
	ds_read_b128 v[196:199], v150 offset:23552
	global_load_lds_dwordx4 v128, s[22:23]
	v_lshl_add_u64 v[224:225], s[22:23], 0, v[132:133]
	s_mov_b32 m0, s29
	s_nop 0
	global_load_lds_dwordx4 v132, s[22:23]
	s_barrier
	s_waitcnt lgkmcnt(0)
	s_setprio 1
	s_waitcnt lgkmcnt(0)
	v_mfma_f32_16x16x32_bf16 v[60:63], v[152:155], v[168:171], v[60:63]
	v_mfma_f32_16x16x32_bf16 v[56:59], v[160:163], v[168:171], v[56:59]
	v_mfma_f32_16x16x32_bf16 v[48:51], v[152:155], v[176:179], v[48:51]
	v_mfma_f32_16x16x32_bf16 v[40:43], v[160:163], v[176:179], v[40:43]
	v_mfma_f32_16x16x32_bf16 v[32:35], v[152:155], v[184:187], v[32:35]
	v_mfma_f32_16x16x32_bf16 v[24:27], v[160:163], v[184:187], v[24:27]
	v_mfma_f32_16x16x32_bf16 v[16:19], v[152:155], v[192:195], v[16:19]
	v_mfma_f32_16x16x32_bf16 v[8:11], v[160:163], v[192:195], v[8:11]
	v_mfma_f32_16x16x32_bf16 v[60:63], v[156:159], v[172:175], v[60:63]
	v_mfma_f32_16x16x32_bf16 v[56:59], v[164:167], v[172:175], v[56:59]
	v_mfma_f32_16x16x32_bf16 v[48:51], v[156:159], v[180:183], v[48:51]
	v_mfma_f32_16x16x32_bf16 v[40:43], v[164:167], v[180:183], v[40:43]
	v_mfma_f32_16x16x32_bf16 v[32:35], v[156:159], v[188:191], v[32:35]
	v_mfma_f32_16x16x32_bf16 v[24:27], v[164:167], v[188:191], v[24:27]
	v_mfma_f32_16x16x32_bf16 v[16:19], v[156:159], v[196:199], v[16:19]
	v_mfma_f32_16x16x32_bf16 v[8:11], v[164:167], v[196:199], v[8:11]
	s_setprio 0
	s_barrier
	s_add_u32 s52, s20, 0x40000
	s_addc_u32 s53, s21, 0
	s_add_i32 s54, s44, s28
	s_mov_b32 m0, s54
	s_nop 0
	global_load_lds_dwordx4 v130, s[52:53]
	s_add_i32 m0, s54, 0x2000
	s_nop 0
	global_load_lds_dwordx4 v134, s[52:53]
	s_add_u32 s22, s22, 0x40000
	s_addc_u32 s23, s23, 0
	s_mov_b32 m0, s30
	s_nop 0
	global_load_lds_dwordx4 v128, s[22:23]
	s_mov_b32 m0, s31
	s_nop 0
	global_load_lds_dwordx4 v132, s[22:23]
	s_waitcnt vmcnt(10)
	s_barrier
	s_setprio 1
	v_mfma_f32_16x16x32_bf16 v[52:55], v[202:205], v[168:171], v[52:55]
	v_mfma_f32_16x16x32_bf16 v[44:47], v[210:213], v[168:171], v[44:47]
	v_mfma_f32_16x16x32_bf16 v[36:39], v[202:205], v[176:179], v[36:39]
	v_mfma_f32_16x16x32_bf16 v[28:31], v[210:213], v[176:179], v[28:31]
	v_mfma_f32_16x16x32_bf16 v[20:23], v[202:205], v[184:187], v[20:23]
	v_mfma_f32_16x16x32_bf16 v[12:15], v[210:213], v[184:187], v[12:15]
	v_mfma_f32_16x16x32_bf16 v[4:7], v[202:205], v[192:195], v[4:7]
	v_mfma_f32_16x16x32_bf16 v[0:3], v[210:213], v[192:195], v[0:3]
	v_mfma_f32_16x16x32_bf16 v[52:55], v[206:209], v[172:175], v[52:55]
	v_mfma_f32_16x16x32_bf16 v[44:47], v[214:217], v[172:175], v[44:47]
	v_mfma_f32_16x16x32_bf16 v[36:39], v[206:209], v[180:183], v[36:39]
	v_mfma_f32_16x16x32_bf16 v[28:31], v[214:217], v[180:183], v[28:31]
	v_mfma_f32_16x16x32_bf16 v[20:23], v[206:209], v[188:191], v[20:23]
	v_mfma_f32_16x16x32_bf16 v[12:15], v[214:217], v[188:191], v[12:15]
	v_mfma_f32_16x16x32_bf16 v[4:7], v[206:209], v[196:199], v[4:7]
	v_mfma_f32_16x16x32_bf16 v[0:3], v[214:217], v[196:199], v[0:3]
	s_setprio 0
	s_add_i32 s52, 0, 0x18000
	v_add_u32_e32 v136, s52, v148
	s_barrier
	ds_read_b128 v[152:155], v136
	ds_read_b128 v[156:159], v136 offset:1024
	ds_read_b128 v[160:163], v136 offset:2048
	ds_read_b128 v[164:167], v136 offset:3072
	ds_read_b128 v[168:171], v150 offset:32768
	ds_read_b128 v[172:175], v150 offset:33792
	ds_read_b128 v[176:179], v150 offset:34816
	ds_read_b128 v[180:183], v150 offset:35840
	ds_read_b128 v[184:187], v150 offset:36864
	ds_read_b128 v[188:191], v150 offset:37888
	ds_read_b128 v[192:195], v150 offset:38912
	ds_read_b128 v[196:199], v150 offset:39936
	s_waitcnt lgkmcnt(8)
	s_waitcnt vmcnt(8)
	s_barrier
; #define PG8_STAGE(bufoff, gbase, voff) do { _Pragma("unroll") for (int _i = 0; _i < 2; ++_i) \
;         __builtin_amdgcn_global_load_lds((const unsigned*)((const char*)(gbase) + (voff)[_i]), (LAS unsigned*)(lds + (bufoff) + ldsw + _i * 8192), 16, 0, 0); } while (0)
; #define PG8_LDA(dst, b, h) do { _Pragma("unroll") for (int m = 0; m < 4; ++m) _Pragma("unroll") for (int k = 0; k < 2; ++k) dst[m][k] = *(const LAS bf16x8*)(lds + PG8_SA(b, h) + aoff + m * 2048 + k * 1024); } while (0)
; #define PG8_LDB(dst, b, h) do { _Pragma("unroll") for (int n = 0; n < 2; ++n) _Pragma("unroll") for (int k = 0; k < 2; ++k) dst[n][k] = *(const LAS bf16x8*)(lds + PG8_SB(b, h) + boff + n * 2048 + k * 1024); } while (0)
; #define PG8_MMA(ai, bj, At, Bt) do { __builtin_amdgcn_s_setprio(1); _Pragma("unroll") for (int m = 0; m < 4; ++m) _Pragma("unroll") for (int n = 0; n < 2; ++n) _Pragma("unroll") for (int k = 0; k < 2; ++k) \
;         acc[ai][bj][m][n] = __builtin_amdgcn_mfma_f32_16x16x32_bf16(Bt[n][k], At[m][k], acc[ai][bj][m][n], 0, 0, 0); __builtin_amdgcn_s_setprio(0); } while (0)
; #define PG8_WAIT_V(n) asm volatile("s_waitcnt vmcnt(" #n ")" ::: "memory")
; #define PG8_WAIT_L(n) asm volatile("s_waitcnt lgkmcnt(" #n ")" ::: "memory")
; #define PG8_BAR __builtin_amdgcn_s_barrier()
; #define PG8_SCHED __builtin_amdgcn_sched_barrier(0)
; template <class Epi, class Sched>
; __device__ __forceinline__ void gemm_phase(LAS unsigned char* lds, const Gemm g, const Sched& S, const Epi& E) {
;     ...
;             PG8_LDB(B0, 1, 0); PG8_SCHED; PG8_LDA(At, 1, 0); PG8_STAGE(PG8_SA(0, 1), a2 + hstep, voffA);
;             PG8_WAIT_L(8); PG8_BAR; PG8_WAIT_L(0); PG8_MMA(0, 0, At, B0); PG8_BAR; PG8_SCHED;
;             PG8_LDB(B1, 1, 1); PG8_STAGE(PG8_SB(1, 0), b3, voffB);
;             PG8_BAR; PG8_WAIT_L(0); PG8_MMA(0, 1, At, B1); PG8_BAR;
;             PG8_LDA(At, 1, 1); PG8_STAGE(PG8_SA(1, 0), a3, voffA);
;             PG8_BAR; PG8_WAIT_L(0); PG8_MMA(1, 0, At, B0); PG8_BAR; PG8_SCHED;
;             PG8_STAGE(PG8_SB(1, 1), b3 + hstep, voffB);
;             PG8_WAIT_V(6); PG8_BAR; PG8_MMA(1, 1, At, B1); PG8_BAR;
	s_waitcnt lgkmcnt(0)
	s_setprio 1
	s_waitcnt lgkmcnt(0)
	v_mfma_f32_16x16x32_bf16 v[124:127], v[152:155], v[168:171], v[124:127]
	v_mfma_f32_16x16x32_bf16 v[120:123], v[160:163], v[168:171], v[120:123]
	v_mfma_f32_16x16x32_bf16 v[112:115], v[152:155], v[176:179], v[112:115]
	v_mfma_f32_16x16x32_bf16 v[104:107], v[160:163], v[176:179], v[104:107]
	v_mfma_f32_16x16x32_bf16 v[96:99], v[152:155], v[184:187], v[96:99]
	v_mfma_f32_16x16x32_bf16 v[88:91], v[160:163], v[184:187], v[88:91]
	v_mfma_f32_16x16x32_bf16 v[80:83], v[152:155], v[192:195], v[80:83]
	v_mfma_f32_16x16x32_bf16 v[72:75], v[160:163], v[192:195], v[72:75]
	v_mfma_f32_16x16x32_bf16 v[124:127], v[156:159], v[172:175], v[124:127]
	v_mfma_f32_16x16x32_bf16 v[120:123], v[164:167], v[172:175], v[120:123]
	v_mfma_f32_16x16x32_bf16 v[112:115], v[156:159], v[180:183], v[112:115]
	v_mfma_f32_16x16x32_bf16 v[104:107], v[164:167], v[180:183], v[104:107]
	v_mfma_f32_16x16x32_bf16 v[96:99], v[156:159], v[188:191], v[96:99]
	v_mfma_f32_16x16x32_bf16 v[88:91], v[164:167], v[188:191], v[88:91]
	v_mfma_f32_16x16x32_bf16 v[80:83], v[156:159], v[196:199], v[80:83]
	v_mfma_f32_16x16x32_bf16 v[72:75], v[164:167], v[196:199], v[72:75]
	s_setprio 0
	s_barrier
	s_add_i32 s22, 0, 0x1c000
	s_add_i32 s23, s52, s28
	v_add_u32_e32 v136, s22, v148
	s_add_u32 s0, s20, 0x80
	s_addc_u32 s1, s21, 0
	s_mov_b32 m0, s23
	ds_read_b128 v[202:205], v136
	ds_read_b128 v[206:209], v136 offset:1024
	ds_read_b128 v[210:213], v136 offset:2048
	ds_read_b128 v[214:217], v136 offset:3072
	global_load_lds_dwordx4 v130, s[0:1]
	s_add_i32 m0, s23, 0x2000
	s_nop 0
	global_load_lds_dwordx4 v134, s[0:1]
	s_waitcnt vmcnt(8)
	s_barrier
	s_waitcnt lgkmcnt(0)
	s_setprio 1
	s_waitcnt lgkmcnt(0)
	v_mfma_f32_16x16x32_bf16 v[116:119], v[202:205], v[168:171], v[116:119]
	v_mfma_f32_16x16x32_bf16 v[108:111], v[210:213], v[168:171], v[108:111]
	v_mfma_f32_16x16x32_bf16 v[100:103], v[202:205], v[176:179], v[100:103]
	v_mfma_f32_16x16x32_bf16 v[92:95], v[210:213], v[176:179], v[92:95]
	v_mfma_f32_16x16x32_bf16 v[84:87], v[202:205], v[184:187], v[84:87]
	v_mfma_f32_16x16x32_bf16 v[76:79], v[210:213], v[184:187], v[76:79]
	v_mfma_f32_16x16x32_bf16 v[68:71], v[202:205], v[192:195], v[68:71]
	v_mfma_f32_16x16x32_bf16 v[64:67], v[210:213], v[192:195], v[64:67]
	v_mfma_f32_16x16x32_bf16 v[116:119], v[206:209], v[172:175], v[116:119]
	v_mfma_f32_16x16x32_bf16 v[108:111], v[214:217], v[172:175], v[108:111]
	v_mfma_f32_16x16x32_bf16 v[100:103], v[206:209], v[180:183], v[100:103]
	v_mfma_f32_16x16x32_bf16 v[92:95], v[214:217], v[180:183], v[92:95]
	v_mfma_f32_16x16x32_bf16 v[84:87], v[206:209], v[188:191], v[84:87]
	v_mfma_f32_16x16x32_bf16 v[76:79], v[214:217], v[188:191], v[76:79]
	v_mfma_f32_16x16x32_bf16 v[68:71], v[206:209], v[196:199], v[68:71]
	v_mfma_f32_16x16x32_bf16 v[64:67], v[214:217], v[196:199], v[64:67]
	s_setprio 0
	s_mov_b32 m0, s36
	s_mov_b64 s[0:1], 0x80
	v_lshl_add_u64 v[218:219], v[222:223], 0, s[0:1]
	s_barrier
	ds_read_b128 v[168:171], v150 offset:49152
	ds_read_b128 v[172:175], v150 offset:50176
	ds_read_b128 v[176:179], v150 offset:51200
	ds_read_b128 v[180:183], v150 offset:52224
	ds_read_b128 v[184:187], v150 offset:53248
	ds_read_b128 v[188:191], v150 offset:54272
	ds_read_b128 v[192:195], v150 offset:55296
	ds_read_b128 v[196:199], v150 offset:56320
	global_load_lds_dwordx4 v[218:219], off
	v_lshl_add_u64 v[218:219], v[224:225], 0, s[0:1]
	s_mov_b32 m0, s37
	s_nop 0
	global_load_lds_dwordx4 v[218:219], off
	s_barrier
	s_waitcnt lgkmcnt(0)
	s_setprio 1
	s_waitcnt lgkmcnt(0)
	v_mfma_f32_16x16x32_bf16 v[60:63], v[152:155], v[168:171], v[60:63]
	v_mfma_f32_16x16x32_bf16 v[56:59], v[160:163], v[168:171], v[56:59]
	v_mfma_f32_16x16x32_bf16 v[48:51], v[152:155], v[176:179], v[48:51]
	v_mfma_f32_16x16x32_bf16 v[40:43], v[160:163], v[176:179], v[40:43]
	v_mfma_f32_16x16x32_bf16 v[32:35], v[152:155], v[184:187], v[32:35]
	v_mfma_f32_16x16x32_bf16 v[24:27], v[160:163], v[184:187], v[24:27]
	v_mfma_f32_16x16x32_bf16 v[16:19], v[152:155], v[192:195], v[16:19]
	v_mfma_f32_16x16x32_bf16 v[8:11], v[160:163], v[192:195], v[8:11]
	v_mfma_f32_16x16x32_bf16 v[60:63], v[156:159], v[172:175], v[60:63]
	v_mfma_f32_16x16x32_bf16 v[56:59], v[164:167], v[172:175], v[56:59]
	v_mfma_f32_16x16x32_bf16 v[48:51], v[156:159], v[180:183], v[48:51]
	v_mfma_f32_16x16x32_bf16 v[40:43], v[164:167], v[180:183], v[40:43]
	v_mfma_f32_16x16x32_bf16 v[32:35], v[156:159], v[188:191], v[32:35]
	v_mfma_f32_16x16x32_bf16 v[24:27], v[164:167], v[188:191], v[24:27]
	v_mfma_f32_16x16x32_bf16 v[16:19], v[156:159], v[196:199], v[16:19]
	v_mfma_f32_16x16x32_bf16 v[8:11], v[164:167], v[196:199], v[8:11]
	s_setprio 0
	s_barrier
	s_add_u32 s20, s20, 0x40080
	s_addc_u32 s21, s21, 0
	s_add_i32 s22, s22, s28
	s_mov_b32 m0, s22
	s_nop 0
	global_load_lds_dwordx4 v130, s[20:21]
	s_add_i32 m0, s22, 0x2000
	s_nop 0
	global_load_lds_dwordx4 v134, s[20:21]
	s_waitcnt vmcnt(8)
	s_barrier
	s_setprio 1
	v_mfma_f32_16x16x32_bf16 v[52:55], v[202:205], v[168:171], v[52:55]
	v_mfma_f32_16x16x32_bf16 v[44:47], v[210:213], v[168:171], v[44:47]
	v_mfma_f32_16x16x32_bf16 v[36:39], v[202:205], v[176:179], v[36:39]
	v_mfma_f32_16x16x32_bf16 v[28:31], v[210:213], v[176:179], v[28:31]
	v_mfma_f32_16x16x32_bf16 v[20:23], v[202:205], v[184:187], v[20:23]
	v_mfma_f32_16x16x32_bf16 v[12:15], v[210:213], v[184:187], v[12:15]
	v_mfma_f32_16x16x32_bf16 v[4:7], v[202:205], v[192:195], v[4:7]
	v_mfma_f32_16x16x32_bf16 v[0:3], v[210:213], v[192:195], v[0:3]
	v_mfma_f32_16x16x32_bf16 v[52:55], v[206:209], v[172:175], v[52:55]
	v_mfma_f32_16x16x32_bf16 v[44:47], v[214:217], v[172:175], v[44:47]
	v_mfma_f32_16x16x32_bf16 v[36:39], v[206:209], v[180:183], v[36:39]
	v_mfma_f32_16x16x32_bf16 v[28:31], v[214:217], v[180:183], v[28:31]
	v_mfma_f32_16x16x32_bf16 v[20:23], v[206:209], v[188:191], v[20:23]
	v_mfma_f32_16x16x32_bf16 v[12:15], v[214:217], v[188:191], v[12:15]
	v_mfma_f32_16x16x32_bf16 v[4:7], v[206:209], v[196:199], v[4:7]
	v_mfma_f32_16x16x32_bf16 v[0:3], v[214:217], v[196:199], v[0:3]
	s_setprio 0
	s_add_i32 s51, s51, 2
	s_add_u32 s18, s18, 0x100
	s_addc_u32 s19, s19, 0
	s_add_u32 s48, s48, 0x100
	s_addc_u32 s49, s49, 0
	s_cmp_gt_u32 s51, 13
	s_barrier
; __device__ __forceinline__ unsigned cvt_pk_bf16(float lo, float hi) { unsigned r; asm volatile("v_cvt_pk_bf16_f32 %0, %1, %2" : "=v"(r) : "v"(lo), "v"(hi)); return r; }
;     __device__ __forceinline__ void operator()(const AccT& acc, const Unit& u, int wr, int wc, int fr, int fq) const {
;     ...
;         const int rbase = u.pm * 256 + wr * 64 + fr;
;         const int tb = u.pn * 256 + wc * 32 + 8 * fq;
; #pragma unroll
;         for (int ai = 0; ai < 2; ++ai)
; #pragma unroll
;             for (int m = 0; m < 4; ++m) {
;                 const int gm = rbase + ai * 128 + m * 16;
; #pragma unroll
;                 for (int bj = 0; bj < 2; ++bj) {
;                     const int t0 = tb + bj * 128;
;                     const f32x4 v0 = acc[ai][bj][m][0], v1 = acc[ai][bj][m][1];
;                     u32x4 w; w.x = cvt_pk_bf16(v0[0], v0[1]); w.y = cvt_pk_bf16(v0[2], v0[3]); w.z = cvt_pk_bf16(v1[0], v1[1]); w.w = cvt_pk_bf16(v1[2], v1[3]);
;                     *(u32x4*)(YT + ((size_t)((t0 >> 10) * 512 + gm)) * 2048 + part * 1024 + (t0 & 1023)) = w;
;                 }
;             }
	s_cbranch_scc0 .LBB0_673
	v_mov_b32_e32 v136, v147
	v_mov_b32_e32 v152, v146
	s_lshl_b32 s7, s16, 8
	s_add_i32 s7, s7, s34
	v_add_u32_e32 v152, s7, v152
	s_lshl_b32 s7, s45, 8
	s_or_b32 s7, s7, s35
	v_lshl_add_u32 v153, v136, 3, s7
	v_cvt_pk_bf16_f32 v124, v124, v125
	v_cvt_pk_bf16_f32 v125, v126, v127
	v_cvt_pk_bf16_f32 v126, v120, v121
	v_ashrrev_i32_e32 v120, 1, v153
	v_cvt_pk_bf16_f32 v127, v122, v123
	v_and_b32_e32 v122, 0xfffffe00, v120
	v_add_u32_e32 v120, v122, v152
	v_ashrrev_i32_e32 v121, 31, v120
	v_lshlrev_b64 v[120:121], 12, v[120:121]
	v_and_b32_e32 v123, 0x3f8, v153
	v_lshl_add_u64 v[120:121], s[4:5], 0, v[120:121]
	v_lshlrev_b32_e32 v136, 1, v123
	v_lshl_add_u64 v[120:121], v[120:121], 0, v[136:137]
	global_store_dwordx4 v[120:121], v[124:127], off
	v_add_u32_e32 v120, 0x80, v153
	v_cvt_pk_bf16_f32 v116, v116, v117
	v_cvt_pk_bf16_f32 v117, v118, v119
	v_cvt_pk_bf16_f32 v118, v108, v109
	v_ashrrev_i32_e32 v108, 1, v120
	v_and_b32_e32 v121, 0xfffffe00, v108
	v_add_u32_e32 v108, v121, v152
	v_ashrrev_i32_e32 v109, 31, v108
	v_lshlrev_b64 v[108:109], 12, v[108:109]
	v_cvt_pk_bf16_f32 v119, v110, v111
	v_lshl_add_u64 v[110:111], s[4:5], 0, v[108:109]
	v_and_b32_e32 v108, 0x3f8, v120
	v_lshlrev_b32_e32 v108, 1, v108
	v_mov_b32_e32 v109, v137
	v_lshl_add_u64 v[110:111], v[110:111], 0, v[108:109]
	global_store_dwordx4 v[110:111], v[116:119], off
	v_cvt_pk_bf16_f32 v110, v112, v113
	v_cvt_pk_bf16_f32 v111, v114, v115
	v_cvt_pk_bf16_f32 v112, v104, v105
	v_cvt_pk_bf16_f32 v113, v106, v107
	s_and_b64 vcc, exec, s[2:3]
	s_nop 0
	v_add_u32_e32 v116, 16, v152
	v_add_u32_e32 v104, v122, v116
	v_ashrrev_i32_e32 v105, 31, v104
	v_lshlrev_b64 v[104:105], 12, v[104:105]
	v_lshl_add_u64 v[104:105], s[4:5], 0, v[104:105]
	v_lshl_add_u64 v[104:105], v[104:105], 0, v[136:137]
	global_store_dwordx4 v[104:105], v[110:113], off
	v_cvt_pk_bf16_f32 v100, v100, v101
	v_cvt_pk_bf16_f32 v101, v102, v103
	v_cvt_pk_bf16_f32 v102, v92, v93
	v_add_u32_e32 v92, v121, v116
	v_ashrrev_i32_e32 v93, 31, v92
	v_lshlrev_b64 v[92:93], 12, v[92:93]
	v_lshl_add_u64 v[92:93], s[4:5], 0, v[92:93]
	v_lshl_add_u64 v[92:93], v[92:93], 0, v[108:109]
	v_cvt_pk_bf16_f32 v103, v94, v95
	global_store_dwordx4 v[92:93], v[100:103], off
	v_cvt_pk_bf16_f32 v92, v96, v97
	v_cvt_pk_bf16_f32 v93, v98, v99
	v_cvt_pk_bf16_f32 v94, v88, v89
	v_cvt_pk_bf16_f32 v95, v90, v91
	s_mov_b32 s45, s6
	s_nop 0
	v_add_u32_e32 v100, 32, v152
	v_add_u32_e32 v88, v122, v100
	v_ashrrev_i32_e32 v89, 31, v88
	v_lshlrev_b64 v[88:89], 12, v[88:89]
	v_lshl_add_u64 v[88:89], s[4:5], 0, v[88:89]
	v_lshl_add_u64 v[88:89], v[88:89], 0, v[136:137]
	global_store_dwordx4 v[88:89], v[92:95], off
	v_cvt_pk_bf16_f32 v84, v84, v85
	v_cvt_pk_bf16_f32 v85, v86, v87
	v_cvt_pk_bf16_f32 v86, v76, v77
	v_add_u32_e32 v76, v121, v100
	v_ashrrev_i32_e32 v77, 31, v76
	v_lshlrev_b64 v[76:77], 12, v[76:77]
	v_lshl_add_u64 v[76:77], s[4:5], 0, v[76:77]
	v_lshl_add_u64 v[76:77], v[76:77], 0, v[108:109]
	v_cvt_pk_bf16_f32 v87, v78, v79
	global_store_dwordx4 v[76:77], v[84:87], off
	v_cvt_pk_bf16_f32 v76, v80, v81
	v_cvt_pk_bf16_f32 v77, v82, v83
	v_cvt_pk_bf16_f32 v78, v72, v73
	v_cvt_pk_bf16_f32 v79, v74, v75
	s_mov_b32 s16, s8
	s_nop 0
	v_add_u32_e32 v84, 48, v152
	v_add_u32_e32 v72, v122, v84
	v_ashrrev_i32_e32 v73, 31, v72
	v_lshlrev_b64 v[72:73], 12, v[72:73]
	v_lshl_add_u64 v[72:73], s[4:5], 0, v[72:73]
	v_lshl_add_u64 v[72:73], v[72:73], 0, v[136:137]
	global_store_dwordx4 v[72:73], v[76:79], off
	v_cvt_pk_bf16_f32 v68, v68, v69
	v_cvt_pk_bf16_f32 v69, v70, v71
	v_cvt_pk_bf16_f32 v70, v64, v65
	v_add_u32_e32 v64, v121, v84
	v_ashrrev_i32_e32 v65, 31, v64
	v_lshlrev_b64 v[64:65], 12, v[64:65]
	v_lshl_add_u64 v[64:65], s[4:5], 0, v[64:65]
	v_lshl_add_u64 v[64:65], v[64:65], 0, v[108:109]
	v_cvt_pk_bf16_f32 v71, v66, v67
	global_store_dwordx4 v[64:65], v[68:71], off
	v_add_u32_e32 v64, 0x80, v152
	v_cvt_pk_bf16_f32 v60, v60, v61
	v_cvt_pk_bf16_f32 v61, v62, v63
	v_cvt_pk_bf16_f32 v62, v56, v57
	v_add_u32_e32 v56, v122, v64
	v_ashrrev_i32_e32 v57, 31, v56
	v_lshlrev_b64 v[56:57], 12, v[56:57]
	v_lshl_add_u64 v[56:57], s[4:5], 0, v[56:57]
	v_lshl_add_u64 v[56:57], v[56:57], 0, v[136:137]
	v_cvt_pk_bf16_f32 v63, v58, v59
	global_store_dwordx4 v[56:57], v[60:63], off
	v_cvt_pk_bf16_f32 v52, v52, v53
	v_cvt_pk_bf16_f32 v53, v54, v55
	v_cvt_pk_bf16_f32 v54, v44, v45
	v_add_u32_e32 v44, v121, v64
	v_ashrrev_i32_e32 v45, 31, v44
	v_lshlrev_b64 v[44:45], 12, v[44:45]
	v_lshl_add_u64 v[44:45], s[4:5], 0, v[44:45]
	v_lshl_add_u64 v[44:45], v[44:45], 0, v[108:109]
	v_cvt_pk_bf16_f32 v55, v46, v47
	global_store_dwordx4 v[44:45], v[52:55], off
	v_cvt_pk_bf16_f32 v44, v48, v49
	v_cvt_pk_bf16_f32 v45, v50, v51
	v_cvt_pk_bf16_f32 v46, v40, v41
	v_cvt_pk_bf16_f32 v47, v42, v43
	s_mov_b64 s[20:21], s[14:15]
	s_nop 0
	v_add_u32_e32 v52, 0x90, v152
	v_add_u32_e32 v40, v122, v52
	v_ashrrev_i32_e32 v41, 31, v40
	v_lshlrev_b64 v[40:41], 12, v[40:41]
	v_lshl_add_u64 v[40:41], s[4:5], 0, v[40:41]
	v_lshl_add_u64 v[40:41], v[40:41], 0, v[136:137]
	global_store_dwordx4 v[40:41], v[44:47], off
	v_cvt_pk_bf16_f32 v36, v36, v37
	v_cvt_pk_bf16_f32 v37, v38, v39
	v_cvt_pk_bf16_f32 v38, v28, v29
	v_add_u32_e32 v28, v121, v52
	v_ashrrev_i32_e32 v29, 31, v28
	v_lshlrev_b64 v[28:29], 12, v[28:29]
	v_lshl_add_u64 v[28:29], s[4:5], 0, v[28:29]
	v_lshl_add_u64 v[28:29], v[28:29], 0, v[108:109]
	v_cvt_pk_bf16_f32 v39, v30, v31
	global_store_dwordx4 v[28:29], v[36:39], off
	v_cvt_pk_bf16_f32 v28, v32, v33
	v_cvt_pk_bf16_f32 v29, v34, v35
	v_cvt_pk_bf16_f32 v30, v24, v25
	v_cvt_pk_bf16_f32 v31, v26, v27
	s_mov_b64 s[18:19], s[12:13]
	s_nop 0
	v_add_u32_e32 v36, 0xa0, v152
	v_add_u32_e32 v24, v122, v36
	v_ashrrev_i32_e32 v25, 31, v24
	v_lshlrev_b64 v[24:25], 12, v[24:25]
	v_lshl_add_u64 v[24:25], s[4:5], 0, v[24:25]
	v_lshl_add_u64 v[24:25], v[24:25], 0, v[136:137]
	global_store_dwordx4 v[24:25], v[28:31], off
	v_cvt_pk_bf16_f32 v20, v20, v21
	v_cvt_pk_bf16_f32 v21, v22, v23
	v_cvt_pk_bf16_f32 v22, v12, v13
	v_add_u32_e32 v12, v121, v36
	v_ashrrev_i32_e32 v13, 31, v12
	v_lshlrev_b64 v[12:13], 12, v[12:13]
	v_lshl_add_u64 v[12:13], s[4:5], 0, v[12:13]
	v_lshl_add_u64 v[12:13], v[12:13], 0, v[108:109]
	v_cvt_pk_bf16_f32 v23, v14, v15
	global_store_dwordx4 v[12:13], v[20:23], off
	v_cvt_pk_bf16_f32 v12, v16, v17
	v_cvt_pk_bf16_f32 v13, v18, v19
	v_cvt_pk_bf16_f32 v14, v8, v9
	v_cvt_pk_bf16_f32 v15, v10, v11
	s_nop 1
	v_add_u32_e32 v20, 0xb0, v152
	v_add_u32_e32 v8, v122, v20
	v_ashrrev_i32_e32 v9, 31, v8
	v_lshlrev_b64 v[8:9], 12, v[8:9]
	v_lshl_add_u64 v[8:9], s[4:5], 0, v[8:9]
	v_lshl_add_u64 v[8:9], v[8:9], 0, v[136:137]
	global_store_dwordx4 v[8:9], v[12:15], off
	v_cvt_pk_bf16_f32 v4, v4, v5
	v_cvt_pk_bf16_f32 v5, v6, v7
	v_cvt_pk_bf16_f32 v6, v0, v1
	v_add_u32_e32 v0, v121, v20
	v_ashrrev_i32_e32 v1, 31, v0
	v_lshlrev_b64 v[0:1], 12, v[0:1]
	v_lshl_add_u64 v[0:1], s[4:5], 0, v[0:1]
	v_lshl_add_u64 v[0:1], v[0:1], 0, v[108:109]
	v_cvt_pk_bf16_f32 v7, v2, v3
	global_store_dwordx4 v[0:1], v[4:7], off
	s_cbranch_vccz .LBB0_666
; #define PG8_WAIT_V(n) asm volatile("s_waitcnt vmcnt(" #n ")" ::: "memory")
; #define PG8_BAR __builtin_amdgcn_s_barrier()
; template <class Epi, class Sched>
; __device__ __forceinline__ void gemm_phase(LAS unsigned char* lds, const Gemm g, const Sched& S, const Epi& E) {
;     ...
;     PG8_WAIT_V(0);
;     if (wr == 0) PG8_BAR;
;     PG8_BAR;
	s_waitcnt vmcnt(0)
	s_cmpk_gt_u32 s24, 0xff
	s_cbranch_scc1 .LBB0_677
	s_barrier

; #define PG8_STAGE(bufoff, gbase, voff) do { _Pragma("unroll") for (int _i = 0; _i < 2; ++_i) \
;         __builtin_amdgcn_global_load_lds((const unsigned*)((const char*)(gbase) + (voff)[_i]), (LAS unsigned*)(lds + (bufoff) + ldsw + _i * 8192), 16, 0, 0); } while (0)
; #define PG8_LDA(dst, b, h) do { _Pragma("unroll") for (int m = 0; m < 4; ++m) _Pragma("unroll") for (int k = 0; k < 2; ++k) dst[m][k] = *(const LAS bf16x8*)(lds + PG8_SA(b, h) + aoff + m * 2048 + k * 1024); } while (0)
; #define PG8_LDB(dst, b, h) do { _Pragma("unroll") for (int n = 0; n < 2; ++n) _Pragma("unroll") for (int k = 0; k < 2; ++k) dst[n][k] = *(const LAS bf16x8*)(lds + PG8_SB(b, h) + boff + n * 2048 + k * 1024); } while (0)
; #define PG8_WAIT_V(n) asm volatile("s_waitcnt vmcnt(" #n ")" ::: "memory")
; #define PG8_WAIT_L(n) asm volatile("s_waitcnt lgkmcnt(" #n ")" ::: "memory")
; #define PG8_BAR __builtin_amdgcn_s_barrier()
; #define PG8_SCHED __builtin_amdgcn_sched_barrier(0)
; template <class Epi, class Sched>
; __device__ __forceinline__ void gemm_phase(LAS unsigned char* lds, const Gemm g, const Sched& S, const Epi& E) {
;     ...
;         const bool has_next = S.next(ui + 1, nxt);
;         const char* nA = has_next ? (const char*)g.A + (size_t)nxt.pm * tstep : cA; const char* nB = has_next ? (const char*)g.Bt + (size_t)nxt.pn * tstep : cB;
;         for (int t = 0; t < nt; t += 2) {
;             const bool last = (t == nt - 2);
;             const char* a1 = cA + (size_t)(t + 1) * kstep;
;             const char* a2 = last ? nA : cA + (size_t)(t + 2) * kstep; const char* b2 = last ? nB : cB + (size_t)(t + 2) * kstep;
;             const char* a3 = a2 + kstep; const char* b3 = b2 + kstep;
;             PG8_LDB(B0, 0, 0); PG8_SCHED; PG8_LDA(At, 0, 0); PG8_STAGE(PG8_SA(1, 1), a1 + hstep, voffA);
;             PG8_WAIT_L(8); PG8_BAR; PG8_WAIT_L(0); PG8_MMA(0, 0, At, B0); PG8_BAR; PG8_SCHED;
;             PG8_LDB(B1, 0, 1); PG8_STAGE(PG8_SB(0, 0), b2, voffB);
;             PG8_BAR; PG8_WAIT_L(0); PG8_MMA(0, 1, At, B1); PG8_BAR;
;             PG8_LDA(At, 0, 1); PG8_STAGE(PG8_SA(0, 0), a2, voffA);
;             PG8_BAR; PG8_WAIT_L(0); PG8_MMA(1, 0, At, B0); PG8_BAR; PG8_SCHED;
;             PG8_STAGE(PG8_SB(0, 1), b2 + hstep, voffB);
;             PG8_WAIT_V(6); PG8_BAR; PG8_MMA(1, 1, At, B1); PG8_BAR;
.LBB0_692:
	s_ashr_i32 s19, s18, 31
	v_cmp_lt_i64_e64 s[24:25], s[20:21], 32
	s_lshl_b64 s[20:21], s[18:19], 19
	s_add_u32 s20, s40, s20
	s_addc_u32 s21, s41, s21
	s_and_b64 s[22:23], s[24:25], exec
	s_cselect_b32 s19, s21, s3
	s_cselect_b32 s57, s20, s2
	s_ashr_i32 s17, s16, 31
	s_lshl_b64 s[22:23], s[16:17], 19
	s_add_u32 s22, s28, s22
	s_addc_u32 s23, s29, s23
	s_and_b64 s[24:25], s[24:25], exec
	s_cselect_b32 s17, s23, s5
	s_cselect_b32 s58, s22, s4
	s_add_u32 s2, s2, 0x40080
	s_addc_u32 s3, s3, 0
	s_add_u32 s59, s4, 0x100
	s_addc_u32 s60, s5, 0
	s_mov_b32 s61, -2
	s_waitcnt lgkmcnt(0)
	ds_read_b128 v[140:143], v149
	ds_read_b128 v[154:157], v149 offset:1024
	ds_read_b128 v[158:161], v149 offset:2048
	ds_read_b128 v[162:165], v149 offset:3072
	s_add_u32 s4, s2, 0xfffc0080
	s_addc_u32 s5, s3, -1
	s_cmp_eq_u32 s61, 12
	s_cselect_b32 s25, s19, s5
	s_cselect_b32 s24, s57, s4
	s_cselect_b32 s5, s17, s60
	s_cselect_b32 s4, s58, s59
	s_add_i32 m0, s33, 0xc000
	ds_read_b128 v[166:169], v150
	ds_read_b128 v[170:173], v150 offset:1024
	ds_read_b128 v[174:177], v150 offset:2048
	ds_read_b128 v[178:181], v150 offset:3072
	ds_read_b128 v[182:185], v150 offset:4096
	ds_read_b128 v[186:189], v150 offset:5120
	ds_read_b128 v[190:193], v150 offset:6144
	ds_read_b128 v[194:197], v150 offset:7168
	global_load_lds_dwordx4 v136, s[2:3]
	s_add_i32 m0, s33, 0xe000
	s_nop 0
	global_load_lds_dwordx4 v138, s[2:3]
	s_waitcnt lgkmcnt(8)
	s_waitcnt vmcnt(8)
	s_barrier
	s_waitcnt lgkmcnt(0)
	s_setprio 1
	s_waitcnt lgkmcnt(0)
	v_mfma_f32_16x16x32_bf16 v[124:127], v[140:143], v[166:169], 0
	v_mfma_f32_16x16x32_bf16 v[120:123], v[158:161], v[166:169], 0
	v_mfma_f32_16x16x32_bf16 v[108:111], v[140:143], v[174:177], 0
	v_mfma_f32_16x16x32_bf16 v[104:107], v[158:161], v[174:177], 0
	v_mfma_f32_16x16x32_bf16 v[92:95], v[140:143], v[182:185], 0
	v_mfma_f32_16x16x32_bf16 v[88:91], v[158:161], v[182:185], 0
	v_mfma_f32_16x16x32_bf16 v[76:79], v[140:143], v[190:193], 0
	v_mfma_f32_16x16x32_bf16 v[72:75], v[158:161], v[190:193], 0
	v_mfma_f32_16x16x32_bf16 v[124:127], v[154:157], v[170:173], v[124:127]
	v_mfma_f32_16x16x32_bf16 v[120:123], v[162:165], v[170:173], v[120:123]
	v_mfma_f32_16x16x32_bf16 v[108:111], v[154:157], v[178:181], v[108:111]
	v_mfma_f32_16x16x32_bf16 v[104:107], v[162:165], v[178:181], v[104:107]
	v_mfma_f32_16x16x32_bf16 v[92:95], v[154:157], v[186:189], v[92:95]
	v_mfma_f32_16x16x32_bf16 v[88:91], v[162:165], v[186:189], v[88:91]
	v_mfma_f32_16x16x32_bf16 v[76:79], v[154:157], v[194:197], v[76:79]
	v_mfma_f32_16x16x32_bf16 v[72:75], v[162:165], v[194:197], v[72:75]
	s_setprio 0
	s_barrier
	s_add_i32 s62, s47, s31
	s_mov_b32 m0, s62
	ds_read_b128 v[202:205], v151
	ds_read_b128 v[206:209], v151 offset:1024
	ds_read_b128 v[210:213], v151 offset:2048
	ds_read_b128 v[214:217], v151 offset:3072
	global_load_lds_dwordx4 v130, s[4:5]
	s_add_i32 m0, s62, 0x2000
	s_nop 0
	global_load_lds_dwordx4 v134, s[4:5]
	s_waitcnt vmcnt(8)
	s_barrier
	s_waitcnt lgkmcnt(0)
	s_setprio 1
	s_waitcnt lgkmcnt(0)
	v_mfma_f32_16x16x32_bf16 v[116:119], v[202:205], v[166:169], 0
	v_mfma_f32_16x16x32_bf16 v[112:115], v[210:213], v[166:169], 0
	v_mfma_f32_16x16x32_bf16 v[100:103], v[202:205], v[174:177], 0
	v_mfma_f32_16x16x32_bf16 v[96:99], v[210:213], v[174:177], 0
	v_mfma_f32_16x16x32_bf16 v[84:87], v[202:205], v[182:185], 0
	v_mfma_f32_16x16x32_bf16 v[80:83], v[210:213], v[182:185], 0
	v_mfma_f32_16x16x32_bf16 v[68:71], v[202:205], v[190:193], 0
	v_mfma_f32_16x16x32_bf16 v[64:67], v[210:213], v[190:193], 0
	v_mfma_f32_16x16x32_bf16 v[116:119], v[206:209], v[170:173], v[116:119]
	v_mfma_f32_16x16x32_bf16 v[112:115], v[214:217], v[170:173], v[112:115]
	v_mfma_f32_16x16x32_bf16 v[100:103], v[206:209], v[178:181], v[100:103]
	v_mfma_f32_16x16x32_bf16 v[96:99], v[214:217], v[178:181], v[96:99]
	v_mfma_f32_16x16x32_bf16 v[84:87], v[206:209], v[186:189], v[84:87]
	v_mfma_f32_16x16x32_bf16 v[80:83], v[214:217], v[186:189], v[80:83]
	v_mfma_f32_16x16x32_bf16 v[68:71], v[206:209], v[194:197], v[68:71]
	v_mfma_f32_16x16x32_bf16 v[64:67], v[214:217], v[194:197], v[64:67]
	s_setprio 0
	s_mov_b32 m0, s33
	v_lshl_add_u64 v[218:219], s[24:25], 0, v[128:129]
	s_barrier
	ds_read_b128 v[166:169], v150 offset:16384
	ds_read_b128 v[170:173], v150 offset:17408
	ds_read_b128 v[174:177], v150 offset:18432
	ds_read_b128 v[178:181], v150 offset:19456
	ds_read_b128 v[182:185], v150 offset:20480
	ds_read_b128 v[186:189], v150 offset:21504
	ds_read_b128 v[190:193], v150 offset:22528
	ds_read_b128 v[194:197], v150 offset:23552
	global_load_lds_dwordx4 v128, s[24:25]
	v_lshl_add_u64 v[220:221], s[24:25], 0, v[132:133]
	s_mov_b32 m0, s34
	s_nop 0
	global_load_lds_dwordx4 v132, s[24:25]
	s_barrier
	s_waitcnt lgkmcnt(0)
	s_setprio 1
	s_waitcnt lgkmcnt(0)
	v_mfma_f32_16x16x32_bf16 v[60:63], v[140:143], v[166:169], 0
	v_mfma_f32_16x16x32_bf16 v[56:59], v[158:161], v[166:169], 0
	v_mfma_f32_16x16x32_bf16 v[44:47], v[140:143], v[174:177], 0
	v_mfma_f32_16x16x32_bf16 v[40:43], v[158:161], v[174:177], 0
	v_mfma_f32_16x16x32_bf16 v[28:31], v[140:143], v[182:185], 0
	v_mfma_f32_16x16x32_bf16 v[24:27], v[158:161], v[182:185], 0
	v_mfma_f32_16x16x32_bf16 v[12:15], v[140:143], v[190:193], 0
	v_mfma_f32_16x16x32_bf16 v[8:11], v[158:161], v[190:193], 0
	v_mfma_f32_16x16x32_bf16 v[60:63], v[154:157], v[170:173], v[60:63]
	v_mfma_f32_16x16x32_bf16 v[56:59], v[162:165], v[170:173], v[56:59]
	v_mfma_f32_16x16x32_bf16 v[44:47], v[154:157], v[178:181], v[44:47]
	v_mfma_f32_16x16x32_bf16 v[40:43], v[162:165], v[178:181], v[40:43]
	v_mfma_f32_16x16x32_bf16 v[28:31], v[154:157], v[186:189], v[28:31]
	v_mfma_f32_16x16x32_bf16 v[24:27], v[162:165], v[186:189], v[24:27]
	v_mfma_f32_16x16x32_bf16 v[12:15], v[154:157], v[194:197], v[12:15]
	v_mfma_f32_16x16x32_bf16 v[8:11], v[162:165], v[194:197], v[8:11]
	s_setprio 0
	s_barrier
; #define PG8_STAGE(bufoff, gbase, voff) do { _Pragma("unroll") for (int _i = 0; _i < 2; ++_i) \
;         __builtin_amdgcn_global_load_lds((const unsigned*)((const char*)(gbase) + (voff)[_i]), (LAS unsigned*)(lds + (bufoff) + ldsw + _i * 8192), 16, 0, 0); } while (0)
; #define PG8_LDA(dst, b, h) do { _Pragma("unroll") for (int m = 0; m < 4; ++m) _Pragma("unroll") for (int k = 0; k < 2; ++k) dst[m][k] = *(const LAS bf16x8*)(lds + PG8_SA(b, h) + aoff + m * 2048 + k * 1024); } while (0)
; #define PG8_LDB(dst, b, h) do { _Pragma("unroll") for (int n = 0; n < 2; ++n) _Pragma("unroll") for (int k = 0; k < 2; ++k) dst[n][k] = *(const LAS bf16x8*)(lds + PG8_SB(b, h) + boff + n * 2048 + k * 1024); } while (0)
; #define PG8_MMA(ai, bj, At, Bt) do { __builtin_amdgcn_s_setprio(1); _Pragma("unroll") for (int m = 0; m < 4; ++m) _Pragma("unroll") for (int n = 0; n < 2; ++n) _Pragma("unroll") for (int k = 0; k < 2; ++k) \
;         acc[ai][bj][m][n] = __builtin_amdgcn_mfma_f32_16x16x32_bf16(Bt[n][k], At[m][k], acc[ai][bj][m][n], 0, 0, 0); __builtin_amdgcn_s_setprio(0); } while (0)
; #define PG8_WAIT_V(n) asm volatile("s_waitcnt vmcnt(" #n ")" ::: "memory")
; #define PG8_WAIT_L(n) asm volatile("s_waitcnt lgkmcnt(" #n ")" ::: "memory")
; #define PG8_BAR __builtin_amdgcn_s_barrier()
; #define PG8_SCHED __builtin_amdgcn_sched_barrier(0)
; template <class Epi, class Sched>
; __device__ __forceinline__ void gemm_phase(LAS unsigned char* lds, const Gemm g, const Sched& S, const Epi& E) {
;     ...
;             PG8_LDB(B1, 0, 1); PG8_STAGE(PG8_SB(0, 0), b2, voffB);
;             PG8_BAR; PG8_WAIT_L(0); PG8_MMA(0, 1, At, B1); PG8_BAR;
;             PG8_LDA(At, 0, 1); PG8_STAGE(PG8_SA(0, 0), a2, voffA);
;             PG8_BAR; PG8_WAIT_L(0); PG8_MMA(1, 0, At, B0); PG8_BAR; PG8_SCHED;
;             PG8_STAGE(PG8_SB(0, 1), b2 + hstep, voffB);
;             PG8_WAIT_V(6); PG8_BAR; PG8_MMA(1, 1, At, B1); PG8_BAR;
;             PG8_LDB(B0, 1, 0); PG8_SCHED; PG8_LDA(At, 1, 0); PG8_STAGE(PG8_SA(0, 1), a2 + hstep, voffA);
;             PG8_WAIT_L(8); PG8_BAR; PG8_WAIT_L(0); PG8_MMA(0, 0, At, B0); PG8_BAR; PG8_SCHED;
	s_add_u32 s62, s4, 0x40000
	s_addc_u32 s63, s5, 0
	s_add_i32 s64, s48, s31
	s_mov_b32 m0, s64
	s_nop 0
	global_load_lds_dwordx4 v130, s[62:63]
	s_add_i32 m0, s64, 0x2000
	s_nop 0
	global_load_lds_dwordx4 v134, s[62:63]
	s_add_u32 s24, s24, 0x40000
	s_addc_u32 s25, s25, 0
	s_mov_b32 m0, s35
	s_nop 0
	global_load_lds_dwordx4 v128, s[24:25]
	s_mov_b32 m0, s36
	s_nop 0
	global_load_lds_dwordx4 v132, s[24:25]
	s_waitcnt vmcnt(10)
	s_barrier
	s_setprio 1
	v_mfma_f32_16x16x32_bf16 v[52:55], v[202:205], v[166:169], 0
	v_mfma_f32_16x16x32_bf16 v[48:51], v[210:213], v[166:169], 0
	v_mfma_f32_16x16x32_bf16 v[36:39], v[202:205], v[174:177], 0
	v_mfma_f32_16x16x32_bf16 v[32:35], v[210:213], v[174:177], 0
	v_mfma_f32_16x16x32_bf16 v[20:23], v[202:205], v[182:185], 0
	v_mfma_f32_16x16x32_bf16 v[16:19], v[210:213], v[182:185], 0
	v_mfma_f32_16x16x32_bf16 v[4:7], v[202:205], v[190:193], 0
	v_mfma_f32_16x16x32_bf16 v[0:3], v[210:213], v[190:193], 0
	v_mfma_f32_16x16x32_bf16 v[52:55], v[206:209], v[170:173], v[52:55]
	v_mfma_f32_16x16x32_bf16 v[48:51], v[214:217], v[170:173], v[48:51]
	v_mfma_f32_16x16x32_bf16 v[36:39], v[206:209], v[178:181], v[36:39]
	v_mfma_f32_16x16x32_bf16 v[32:35], v[214:217], v[178:181], v[32:35]
	v_mfma_f32_16x16x32_bf16 v[20:23], v[206:209], v[186:189], v[20:23]
	v_mfma_f32_16x16x32_bf16 v[16:19], v[214:217], v[186:189], v[16:19]
	v_mfma_f32_16x16x32_bf16 v[4:7], v[206:209], v[194:197], v[4:7]
	v_mfma_f32_16x16x32_bf16 v[0:3], v[214:217], v[194:197], v[0:3]
	s_setprio 0
	s_add_i32 s62, 0, 0x18000
	v_add_u32_e32 v162, s62, v148
	s_barrier
	ds_read_b128 v[140:143], v162
	ds_read_b128 v[154:157], v162 offset:1024
	ds_read_b128 v[158:161], v162 offset:2048
	ds_read_b128 v[162:165], v162 offset:3072
	ds_read_b128 v[166:169], v150 offset:32768
	ds_read_b128 v[170:173], v150 offset:33792
	ds_read_b128 v[174:177], v150 offset:34816
	ds_read_b128 v[178:181], v150 offset:35840
	ds_read_b128 v[182:185], v150 offset:36864
	ds_read_b128 v[186:189], v150 offset:37888
	ds_read_b128 v[190:193], v150 offset:38912
	ds_read_b128 v[194:197], v150 offset:39936
	s_waitcnt lgkmcnt(8)
	s_waitcnt vmcnt(8)
	s_barrier
	s_waitcnt lgkmcnt(0)
	s_setprio 1
	s_waitcnt lgkmcnt(0)
	v_mfma_f32_16x16x32_bf16 v[124:127], v[140:143], v[166:169], v[124:127]
	v_mfma_f32_16x16x32_bf16 v[120:123], v[158:161], v[166:169], v[120:123]
	v_mfma_f32_16x16x32_bf16 v[108:111], v[140:143], v[174:177], v[108:111]
	v_mfma_f32_16x16x32_bf16 v[104:107], v[158:161], v[174:177], v[104:107]
	v_mfma_f32_16x16x32_bf16 v[92:95], v[140:143], v[182:185], v[92:95]
	v_mfma_f32_16x16x32_bf16 v[88:91], v[158:161], v[182:185], v[88:91]
	v_mfma_f32_16x16x32_bf16 v[76:79], v[140:143], v[190:193], v[76:79]
	v_mfma_f32_16x16x32_bf16 v[72:75], v[158:161], v[190:193], v[72:75]
	v_mfma_f32_16x16x32_bf16 v[124:127], v[154:157], v[170:173], v[124:127]
	v_mfma_f32_16x16x32_bf16 v[120:123], v[162:165], v[170:173], v[120:123]
	v_mfma_f32_16x16x32_bf16 v[108:111], v[154:157], v[178:181], v[108:111]
	v_mfma_f32_16x16x32_bf16 v[104:107], v[162:165], v[178:181], v[104:107]
	v_mfma_f32_16x16x32_bf16 v[92:95], v[154:157], v[186:189], v[92:95]
	v_mfma_f32_16x16x32_bf16 v[88:91], v[162:165], v[186:189], v[88:91]
	v_mfma_f32_16x16x32_bf16 v[76:79], v[154:157], v[194:197], v[76:79]
	v_mfma_f32_16x16x32_bf16 v[72:75], v[162:165], v[194:197], v[72:75]
	s_setprio 0
	s_barrier
	s_add_i32 s24, 0, 0x1c000
	s_add_i32 s25, s62, s31
	v_add_u32_e32 v214, s24, v148
	s_add_u32 s0, s4, 0x80
	s_addc_u32 s1, s5, 0
	s_mov_b32 m0, s25
	ds_read_b128 v[202:205], v214
	ds_read_b128 v[206:209], v214 offset:1024
	ds_read_b128 v[210:213], v214 offset:2048
	ds_read_b128 v[214:217], v214 offset:3072
	global_load_lds_dwordx4 v130, s[0:1]
	s_add_i32 m0, s25, 0x2000
	s_nop 0
	global_load_lds_dwordx4 v134, s[0:1]
	s_waitcnt vmcnt(8)
	s_barrier
	s_waitcnt lgkmcnt(0)
	s_setprio 1
	s_waitcnt lgkmcnt(0)
	v_mfma_f32_16x16x32_bf16 v[116:119], v[202:205], v[166:169], v[116:119]
	v_mfma_f32_16x16x32_bf16 v[112:115], v[210:213], v[166:169], v[112:115]
	v_mfma_f32_16x16x32_bf16 v[100:103], v[202:205], v[174:177], v[100:103]
	v_mfma_f32_16x16x32_bf16 v[96:99], v[210:213], v[174:177], v[96:99]
	v_mfma_f32_16x16x32_bf16 v[84:87], v[202:205], v[182:185], v[84:87]
	v_mfma_f32_16x16x32_bf16 v[80:83], v[210:213], v[182:185], v[80:83]
	v_mfma_f32_16x16x32_bf16 v[68:71], v[202:205], v[190:193], v[68:71]
	v_mfma_f32_16x16x32_bf16 v[64:67], v[210:213], v[190:193], v[64:67]
	v_mfma_f32_16x16x32_bf16 v[116:119], v[206:209], v[170:173], v[116:119]
	v_mfma_f32_16x16x32_bf16 v[112:115], v[214:217], v[170:173], v[112:115]
	v_mfma_f32_16x16x32_bf16 v[100:103], v[206:209], v[178:181], v[100:103]
	v_mfma_f32_16x16x32_bf16 v[96:99], v[214:217], v[178:181], v[96:99]
	v_mfma_f32_16x16x32_bf16 v[84:87], v[206:209], v[186:189], v[84:87]
	v_mfma_f32_16x16x32_bf16 v[80:83], v[214:217], v[186:189], v[80:83]
	v_mfma_f32_16x16x32_bf16 v[68:71], v[206:209], v[194:197], v[68:71]
	v_mfma_f32_16x16x32_bf16 v[64:67], v[214:217], v[194:197], v[64:67]
	s_setprio 0
	s_mov_b32 m0, s44
	s_mov_b64 s[0:1], 0x80
	v_lshl_add_u64 v[144:145], v[218:219], 0, s[0:1]
	s_barrier
	ds_read_b128 v[166:169], v150 offset:49152
	ds_read_b128 v[170:173], v150 offset:50176
	ds_read_b128 v[174:177], v150 offset:51200
	ds_read_b128 v[178:181], v150 offset:52224
	ds_read_b128 v[182:185], v150 offset:53248
	ds_read_b128 v[186:189], v150 offset:54272
	ds_read_b128 v[190:193], v150 offset:55296
	ds_read_b128 v[194:197], v150 offset:56320
	global_load_lds_dwordx4 v[144:145], off
	v_lshl_add_u64 v[144:145], v[220:221], 0, s[0:1]
	s_mov_b32 m0, s45
	s_nop 0
	global_load_lds_dwordx4 v[144:145], off
	s_barrier
; #define PG8_STAGE(bufoff, gbase, voff) do { _Pragma("unroll") for (int _i = 0; _i < 2; ++_i) \
;         __builtin_amdgcn_global_load_lds((const unsigned*)((const char*)(gbase) + (voff)[_i]), (LAS unsigned*)(lds + (bufoff) + ldsw + _i * 8192), 16, 0, 0); } while (0)
; #define PG8_LDA(dst, b, h) do { _Pragma("unroll") for (int m = 0; m < 4; ++m) _Pragma("unroll") for (int k = 0; k < 2; ++k) dst[m][k] = *(const LAS bf16x8*)(lds + PG8_SA(b, h) + aoff + m * 2048 + k * 1024); } while (0)
; #define PG8_WAIT_V(n) asm volatile("s_waitcnt vmcnt(" #n ")" ::: "memory")
; #define PG8_WAIT_L(n) asm volatile("s_waitcnt lgkmcnt(" #n ")" ::: "memory")
; template <class Epi, class Sched>
; __device__ __forceinline__ void gemm_phase(LAS unsigned char* lds, const Gemm g, const Sched& S, const Epi& E) {
;     ...
;         for (int t = 0; t < nt; t += 2) {
;             const bool last = (t == nt - 2);
;             const char* a1 = cA + (size_t)(t + 1) * kstep;
;             const char* a2 = last ? nA : cA + (size_t)(t + 2) * kstep; const char* b2 = last ? nB : cB + (size_t)(t + 2) * kstep;
;             const char* a3 = a2 + kstep; const char* b3 = b2 + kstep;
;             PG8_LDB(B0, 0, 0); PG8_SCHED; PG8_LDA(At, 0, 0); PG8_STAGE(PG8_SA(1, 1), a1 + hstep, voffA);
;             PG8_WAIT_L(8); PG8_BAR; PG8_WAIT_L(0); PG8_MMA(0, 0, At, B0); PG8_BAR; PG8_SCHED;
;             PG8_LDB(B1, 0, 1); PG8_STAGE(PG8_SB(0, 0), b2, voffB);
;             PG8_BAR; PG8_WAIT_L(0); PG8_MMA(0, 1, At, B1); PG8_BAR;
;             PG8_LDA(At, 0, 1); PG8_STAGE(PG8_SA(0, 0), a2, voffA);
;             PG8_BAR; PG8_WAIT_L(0); PG8_MMA(1, 0, At, B0); PG8_BAR; PG8_SCHED;
;             PG8_STAGE(PG8_SB(0, 1), b2 + hstep, voffB);
;             PG8_WAIT_V(6); PG8_BAR; PG8_MMA(1, 1, At, B1); PG8_BAR;
;             PG8_LDB(B0, 1, 0); PG8_SCHED; PG8_LDA(At, 1, 0); PG8_STAGE(PG8_SA(0, 1), a2 + hstep, voffA);
;             PG8_WAIT_L(8); PG8_BAR; PG8_WAIT_L(0); PG8_MMA(0, 0, At, B0); PG8_BAR; PG8_SCHED;
;             PG8_LDB(B1, 1, 1); PG8_STAGE(PG8_SB(1, 0), b3, voffB);
;             PG8_BAR; PG8_WAIT_L(0); PG8_MMA(0, 1, At, B1); PG8_BAR;
;             PG8_LDA(At, 1, 1); PG8_STAGE(PG8_SA(1, 0), a3, voffA);
;             PG8_BAR; PG8_WAIT_L(0); PG8_MMA(1, 0, At, B0); PG8_BAR; PG8_SCHED;
;             PG8_STAGE(PG8_SB(1, 1), b3 + hstep, voffB);
;             PG8_WAIT_V(6); PG8_BAR; PG8_MMA(1, 1, At, B1); PG8_BAR;
	s_waitcnt lgkmcnt(0)
	s_setprio 1
	s_waitcnt lgkmcnt(0)
	v_mfma_f32_16x16x32_bf16 v[60:63], v[140:143], v[166:169], v[60:63]
	v_mfma_f32_16x16x32_bf16 v[56:59], v[158:161], v[166:169], v[56:59]
	v_mfma_f32_16x16x32_bf16 v[44:47], v[140:143], v[174:177], v[44:47]
	v_mfma_f32_16x16x32_bf16 v[40:43], v[158:161], v[174:177], v[40:43]
	v_mfma_f32_16x16x32_bf16 v[28:31], v[140:143], v[182:185], v[28:31]
	v_mfma_f32_16x16x32_bf16 v[24:27], v[158:161], v[182:185], v[24:27]
	v_mfma_f32_16x16x32_bf16 v[12:15], v[140:143], v[190:193], v[12:15]
	v_mfma_f32_16x16x32_bf16 v[8:11], v[158:161], v[190:193], v[8:11]
	v_mfma_f32_16x16x32_bf16 v[60:63], v[154:157], v[170:173], v[60:63]
	v_mfma_f32_16x16x32_bf16 v[56:59], v[162:165], v[170:173], v[56:59]
	v_mfma_f32_16x16x32_bf16 v[44:47], v[154:157], v[178:181], v[44:47]
	v_mfma_f32_16x16x32_bf16 v[40:43], v[162:165], v[178:181], v[40:43]
	v_mfma_f32_16x16x32_bf16 v[28:31], v[154:157], v[186:189], v[28:31]
	v_mfma_f32_16x16x32_bf16 v[24:27], v[162:165], v[186:189], v[24:27]
	v_mfma_f32_16x16x32_bf16 v[12:15], v[154:157], v[194:197], v[12:15]
	v_mfma_f32_16x16x32_bf16 v[8:11], v[162:165], v[194:197], v[8:11]
	s_setprio 0
	s_barrier
	s_add_u32 s4, s4, 0x40080
	s_addc_u32 s5, s5, 0
	s_add_i32 s24, s24, s31
	s_mov_b32 m0, s24
	s_nop 0
	global_load_lds_dwordx4 v130, s[4:5]
	s_add_i32 m0, s24, 0x2000
	s_nop 0
	global_load_lds_dwordx4 v134, s[4:5]
	s_waitcnt vmcnt(8)
	s_barrier
	s_setprio 1
	v_mfma_f32_16x16x32_bf16 v[52:55], v[202:205], v[166:169], v[52:55]
	v_mfma_f32_16x16x32_bf16 v[48:51], v[210:213], v[166:169], v[48:51]
	v_mfma_f32_16x16x32_bf16 v[36:39], v[202:205], v[174:177], v[36:39]
	v_mfma_f32_16x16x32_bf16 v[32:35], v[210:213], v[174:177], v[32:35]
	v_mfma_f32_16x16x32_bf16 v[20:23], v[202:205], v[182:185], v[20:23]
	v_mfma_f32_16x16x32_bf16 v[16:19], v[210:213], v[182:185], v[16:19]
	v_mfma_f32_16x16x32_bf16 v[4:7], v[202:205], v[190:193], v[4:7]
	v_mfma_f32_16x16x32_bf16 v[0:3], v[210:213], v[190:193], v[0:3]
	v_mfma_f32_16x16x32_bf16 v[52:55], v[206:209], v[170:173], v[52:55]
	v_mfma_f32_16x16x32_bf16 v[48:51], v[214:217], v[170:173], v[48:51]
	v_mfma_f32_16x16x32_bf16 v[36:39], v[206:209], v[178:181], v[36:39]
	v_mfma_f32_16x16x32_bf16 v[32:35], v[214:217], v[178:181], v[32:35]
	v_mfma_f32_16x16x32_bf16 v[20:23], v[206:209], v[186:189], v[20:23]
	v_mfma_f32_16x16x32_bf16 v[16:19], v[214:217], v[186:189], v[16:19]
	v_mfma_f32_16x16x32_bf16 v[4:7], v[206:209], v[194:197], v[4:7]
	v_mfma_f32_16x16x32_bf16 v[0:3], v[214:217], v[194:197], v[0:3]
	s_setprio 0
	s_add_i32 s61, s61, 2
	s_add_u32 s2, s2, 0x100
	s_addc_u32 s3, s3, 0
	s_add_u32 s59, s59, 0x100
	s_addc_u32 s60, s60, 0
	s_cmp_gt_u32 s61, 13
	s_barrier
.LBB0_693:
	ds_read_b128 v[140:143], v149
	ds_read_b128 v[154:157], v149 offset:1024
	ds_read_b128 v[158:161], v149 offset:2048
	ds_read_b128 v[162:165], v149 offset:3072
	s_add_u32 s4, s2, 0xfffc0080
	s_addc_u32 s5, s3, -1
	s_cmp_eq_u32 s61, 12
	s_cselect_b32 s25, s19, s5
	s_cselect_b32 s24, s57, s4
	s_cselect_b32 s5, s17, s60
	s_cselect_b32 s4, s58, s59
	s_add_i32 m0, s33, 0xc000
	ds_read_b128 v[166:169], v150
	ds_read_b128 v[170:173], v150 offset:1024
	ds_read_b128 v[174:177], v150 offset:2048
	ds_read_b128 v[178:181], v150 offset:3072
	ds_read_b128 v[182:185], v150 offset:4096
	ds_read_b128 v[186:189], v150 offset:5120
	ds_read_b128 v[190:193], v150 offset:6144
	ds_read_b128 v[194:197], v150 offset:7168
	global_load_lds_dwordx4 v136, s[2:3]
	s_add_i32 m0, s33, 0xe000
	s_nop 0
	global_load_lds_dwordx4 v138, s[2:3]
	s_waitcnt lgkmcnt(8)
	s_waitcnt vmcnt(8)
	s_barrier
	s_waitcnt lgkmcnt(0)
	s_setprio 1
	s_waitcnt lgkmcnt(0)
	v_mfma_f32_16x16x32_bf16 v[124:127], v[140:143], v[166:169], v[124:127]
	v_mfma_f32_16x16x32_bf16 v[120:123], v[158:161], v[166:169], v[120:123]
	v_mfma_f32_16x16x32_bf16 v[108:111], v[140:143], v[174:177], v[108:111]
	v_mfma_f32_16x16x32_bf16 v[104:107], v[158:161], v[174:177], v[104:107]
	v_mfma_f32_16x16x32_bf16 v[92:95], v[140:143], v[182:185], v[92:95]
	v_mfma_f32_16x16x32_bf16 v[88:91], v[158:161], v[182:185], v[88:91]
	v_mfma_f32_16x16x32_bf16 v[76:79], v[140:143], v[190:193], v[76:79]
	v_mfma_f32_16x16x32_bf16 v[72:75], v[158:161], v[190:193], v[72:75]
	v_mfma_f32_16x16x32_bf16 v[124:127], v[154:157], v[170:173], v[124:127]
	v_mfma_f32_16x16x32_bf16 v[120:123], v[162:165], v[170:173], v[120:123]
	v_mfma_f32_16x16x32_bf16 v[108:111], v[154:157], v[178:181], v[108:111]
	v_mfma_f32_16x16x32_bf16 v[104:107], v[162:165], v[178:181], v[104:107]
	v_mfma_f32_16x16x32_bf16 v[92:95], v[154:157], v[186:189], v[92:95]
	v_mfma_f32_16x16x32_bf16 v[88:91], v[162:165], v[186:189], v[88:91]
	v_mfma_f32_16x16x32_bf16 v[76:79], v[154:157], v[194:197], v[76:79]
	v_mfma_f32_16x16x32_bf16 v[72:75], v[162:165], v[194:197], v[72:75]
	s_setprio 0
	s_barrier
	s_add_i32 s62, s47, s31
	s_mov_b32 m0, s62
	ds_read_b128 v[202:205], v151
	ds_read_b128 v[206:209], v151 offset:1024
	ds_read_b128 v[210:213], v151 offset:2048
	ds_read_b128 v[214:217], v151 offset:3072
	global_load_lds_dwordx4 v130, s[4:5]
	s_add_i32 m0, s62, 0x2000
	s_nop 0
	global_load_lds_dwordx4 v134, s[4:5]
	s_waitcnt vmcnt(8)
	s_barrier
; #define PG8_STAGE(bufoff, gbase, voff) do { _Pragma("unroll") for (int _i = 0; _i < 2; ++_i) \
;         __builtin_amdgcn_global_load_lds((const unsigned*)((const char*)(gbase) + (voff)[_i]), (LAS unsigned*)(lds + (bufoff) + ldsw + _i * 8192), 16, 0, 0); } while (0)
; #define PG8_LDA(dst, b, h) do { _Pragma("unroll") for (int m = 0; m < 4; ++m) _Pragma("unroll") for (int k = 0; k < 2; ++k) dst[m][k] = *(const LAS bf16x8*)(lds + PG8_SA(b, h) + aoff + m * 2048 + k * 1024); } while (0)
; #define PG8_LDB(dst, b, h) do { _Pragma("unroll") for (int n = 0; n < 2; ++n) _Pragma("unroll") for (int k = 0; k < 2; ++k) dst[n][k] = *(const LAS bf16x8*)(lds + PG8_SB(b, h) + boff + n * 2048 + k * 1024); } while (0)
; #define PG8_MMA(ai, bj, At, Bt) do { __builtin_amdgcn_s_setprio(1); _Pragma("unroll") for (int m = 0; m < 4; ++m) _Pragma("unroll") for (int n = 0; n < 2; ++n) _Pragma("unroll") for (int k = 0; k < 2; ++k) \
;         acc[ai][bj][m][n] = __builtin_amdgcn_mfma_f32_16x16x32_bf16(Bt[n][k], At[m][k], acc[ai][bj][m][n], 0, 0, 0); __builtin_amdgcn_s_setprio(0); } while (0)
; #define PG8_WAIT_V(n) asm volatile("s_waitcnt vmcnt(" #n ")" ::: "memory")
; #define PG8_WAIT_L(n) asm volatile("s_waitcnt lgkmcnt(" #n ")" ::: "memory")
; #define PG8_BAR __builtin_amdgcn_s_barrier()
; #define PG8_SCHED __builtin_amdgcn_sched_barrier(0)
; template <class Epi, class Sched>
; __device__ __forceinline__ void gemm_phase(LAS unsigned char* lds, const Gemm g, const Sched& S, const Epi& E) {
;     ...
;             PG8_LDB(B1, 0, 1); PG8_STAGE(PG8_SB(0, 0), b2, voffB);
;             PG8_BAR; PG8_WAIT_L(0); PG8_MMA(0, 1, At, B1); PG8_BAR;
;             PG8_LDA(At, 0, 1); PG8_STAGE(PG8_SA(0, 0), a2, voffA);
;             PG8_BAR; PG8_WAIT_L(0); PG8_MMA(1, 0, At, B0); PG8_BAR; PG8_SCHED;
;             PG8_STAGE(PG8_SB(0, 1), b2 + hstep, voffB);
;             PG8_WAIT_V(6); PG8_BAR; PG8_MMA(1, 1, At, B1); PG8_BAR;
;             PG8_LDB(B0, 1, 0); PG8_SCHED; PG8_LDA(At, 1, 0); PG8_STAGE(PG8_SA(0, 1), a2 + hstep, voffA);
;             PG8_WAIT_L(8); PG8_BAR; PG8_WAIT_L(0); PG8_MMA(0, 0, At, B0); PG8_BAR; PG8_SCHED;
	s_waitcnt lgkmcnt(0)
	s_setprio 1
	s_waitcnt lgkmcnt(0)
	v_mfma_f32_16x16x32_bf16 v[116:119], v[202:205], v[166:169], v[116:119]
	v_mfma_f32_16x16x32_bf16 v[112:115], v[210:213], v[166:169], v[112:115]
	v_mfma_f32_16x16x32_bf16 v[100:103], v[202:205], v[174:177], v[100:103]
	v_mfma_f32_16x16x32_bf16 v[96:99], v[210:213], v[174:177], v[96:99]
	v_mfma_f32_16x16x32_bf16 v[84:87], v[202:205], v[182:185], v[84:87]
	v_mfma_f32_16x16x32_bf16 v[80:83], v[210:213], v[182:185], v[80:83]
	v_mfma_f32_16x16x32_bf16 v[68:71], v[202:205], v[190:193], v[68:71]
	v_mfma_f32_16x16x32_bf16 v[64:67], v[210:213], v[190:193], v[64:67]
	v_mfma_f32_16x16x32_bf16 v[116:119], v[206:209], v[170:173], v[116:119]
	v_mfma_f32_16x16x32_bf16 v[112:115], v[214:217], v[170:173], v[112:115]
	v_mfma_f32_16x16x32_bf16 v[100:103], v[206:209], v[178:181], v[100:103]
	v_mfma_f32_16x16x32_bf16 v[96:99], v[214:217], v[178:181], v[96:99]
	v_mfma_f32_16x16x32_bf16 v[84:87], v[206:209], v[186:189], v[84:87]
	v_mfma_f32_16x16x32_bf16 v[80:83], v[214:217], v[186:189], v[80:83]
	v_mfma_f32_16x16x32_bf16 v[68:71], v[206:209], v[194:197], v[68:71]
	v_mfma_f32_16x16x32_bf16 v[64:67], v[214:217], v[194:197], v[64:67]
	s_setprio 0
	s_mov_b32 m0, s33
	v_lshl_add_u64 v[218:219], s[24:25], 0, v[128:129]
	s_barrier
	ds_read_b128 v[166:169], v150 offset:16384
	ds_read_b128 v[170:173], v150 offset:17408
	ds_read_b128 v[174:177], v150 offset:18432
	ds_read_b128 v[178:181], v150 offset:19456
	ds_read_b128 v[182:185], v150 offset:20480
	ds_read_b128 v[186:189], v150 offset:21504
	ds_read_b128 v[190:193], v150 offset:22528
	ds_read_b128 v[194:197], v150 offset:23552
	global_load_lds_dwordx4 v128, s[24:25]
	v_lshl_add_u64 v[220:221], s[24:25], 0, v[132:133]
	s_mov_b32 m0, s34
	s_nop 0
	global_load_lds_dwordx4 v132, s[24:25]
	s_barrier
	s_waitcnt lgkmcnt(0)
	s_setprio 1
	s_waitcnt lgkmcnt(0)
	v_mfma_f32_16x16x32_bf16 v[60:63], v[140:143], v[166:169], v[60:63]
	v_mfma_f32_16x16x32_bf16 v[56:59], v[158:161], v[166:169], v[56:59]
	v_mfma_f32_16x16x32_bf16 v[44:47], v[140:143], v[174:177], v[44:47]
	v_mfma_f32_16x16x32_bf16 v[40:43], v[158:161], v[174:177], v[40:43]
	v_mfma_f32_16x16x32_bf16 v[28:31], v[140:143], v[182:185], v[28:31]
	v_mfma_f32_16x16x32_bf16 v[24:27], v[158:161], v[182:185], v[24:27]
	v_mfma_f32_16x16x32_bf16 v[12:15], v[140:143], v[190:193], v[12:15]
	v_mfma_f32_16x16x32_bf16 v[8:11], v[158:161], v[190:193], v[8:11]
	v_mfma_f32_16x16x32_bf16 v[60:63], v[154:157], v[170:173], v[60:63]
	v_mfma_f32_16x16x32_bf16 v[56:59], v[162:165], v[170:173], v[56:59]
	v_mfma_f32_16x16x32_bf16 v[44:47], v[154:157], v[178:181], v[44:47]
	v_mfma_f32_16x16x32_bf16 v[40:43], v[162:165], v[178:181], v[40:43]
	v_mfma_f32_16x16x32_bf16 v[28:31], v[154:157], v[186:189], v[28:31]
	v_mfma_f32_16x16x32_bf16 v[24:27], v[162:165], v[186:189], v[24:27]
	v_mfma_f32_16x16x32_bf16 v[12:15], v[154:157], v[194:197], v[12:15]
	v_mfma_f32_16x16x32_bf16 v[8:11], v[162:165], v[194:197], v[8:11]
	s_setprio 0
	s_barrier
	s_add_u32 s62, s4, 0x40000
	s_addc_u32 s63, s5, 0
	s_add_i32 s64, s48, s31
	s_mov_b32 m0, s64
	s_nop 0
	global_load_lds_dwordx4 v130, s[62:63]
	s_add_i32 m0, s64, 0x2000
	s_nop 0
	global_load_lds_dwordx4 v134, s[62:63]
	s_add_u32 s24, s24, 0x40000
	s_addc_u32 s25, s25, 0
	s_mov_b32 m0, s35
	s_nop 0
	global_load_lds_dwordx4 v128, s[24:25]
	s_mov_b32 m0, s36
	s_nop 0
	global_load_lds_dwordx4 v132, s[24:25]
	s_waitcnt vmcnt(10)
	s_barrier
	s_setprio 1
	v_mfma_f32_16x16x32_bf16 v[52:55], v[202:205], v[166:169], v[52:55]
	v_mfma_f32_16x16x32_bf16 v[48:51], v[210:213], v[166:169], v[48:51]
	v_mfma_f32_16x16x32_bf16 v[36:39], v[202:205], v[174:177], v[36:39]
	v_mfma_f32_16x16x32_bf16 v[32:35], v[210:213], v[174:177], v[32:35]
	v_mfma_f32_16x16x32_bf16 v[20:23], v[202:205], v[182:185], v[20:23]
	v_mfma_f32_16x16x32_bf16 v[16:19], v[210:213], v[182:185], v[16:19]
	v_mfma_f32_16x16x32_bf16 v[4:7], v[202:205], v[190:193], v[4:7]
	v_mfma_f32_16x16x32_bf16 v[0:3], v[210:213], v[190:193], v[0:3]
	v_mfma_f32_16x16x32_bf16 v[52:55], v[206:209], v[170:173], v[52:55]
	v_mfma_f32_16x16x32_bf16 v[48:51], v[214:217], v[170:173], v[48:51]
	v_mfma_f32_16x16x32_bf16 v[36:39], v[206:209], v[178:181], v[36:39]
	v_mfma_f32_16x16x32_bf16 v[32:35], v[214:217], v[178:181], v[32:35]
	v_mfma_f32_16x16x32_bf16 v[20:23], v[206:209], v[186:189], v[20:23]
	v_mfma_f32_16x16x32_bf16 v[16:19], v[214:217], v[186:189], v[16:19]
	v_mfma_f32_16x16x32_bf16 v[4:7], v[206:209], v[194:197], v[4:7]
	v_mfma_f32_16x16x32_bf16 v[0:3], v[214:217], v[194:197], v[0:3]
	s_setprio 0
	s_add_i32 s62, 0, 0x18000
	v_add_u32_e32 v162, s62, v148
	s_barrier
	ds_read_b128 v[140:143], v162
	ds_read_b128 v[154:157], v162 offset:1024
	ds_read_b128 v[158:161], v162 offset:2048
	ds_read_b128 v[162:165], v162 offset:3072
	ds_read_b128 v[166:169], v150 offset:32768
	ds_read_b128 v[170:173], v150 offset:33792
	ds_read_b128 v[174:177], v150 offset:34816
	ds_read_b128 v[178:181], v150 offset:35840
	ds_read_b128 v[182:185], v150 offset:36864
	ds_read_b128 v[186:189], v150 offset:37888
	ds_read_b128 v[190:193], v150 offset:38912
	ds_read_b128 v[194:197], v150 offset:39936
	s_waitcnt lgkmcnt(8)
	s_waitcnt vmcnt(8)
	s_barrier
; #define PG8_STAGE(bufoff, gbase, voff) do { _Pragma("unroll") for (int _i = 0; _i < 2; ++_i) \
;         __builtin_amdgcn_global_load_lds((const unsigned*)((const char*)(gbase) + (voff)[_i]), (LAS unsigned*)(lds + (bufoff) + ldsw + _i * 8192), 16, 0, 0); } while (0)
; #define PG8_LDA(dst, b, h) do { _Pragma("unroll") for (int m = 0; m < 4; ++m) _Pragma("unroll") for (int k = 0; k < 2; ++k) dst[m][k] = *(const LAS bf16x8*)(lds + PG8_SA(b, h) + aoff + m * 2048 + k * 1024); } while (0)
; #define PG8_LDB(dst, b, h) do { _Pragma("unroll") for (int n = 0; n < 2; ++n) _Pragma("unroll") for (int k = 0; k < 2; ++k) dst[n][k] = *(const LAS bf16x8*)(lds + PG8_SB(b, h) + boff + n * 2048 + k * 1024); } while (0)
; #define PG8_MMA(ai, bj, At, Bt) do { __builtin_amdgcn_s_setprio(1); _Pragma("unroll") for (int m = 0; m < 4; ++m) _Pragma("unroll") for (int n = 0; n < 2; ++n) _Pragma("unroll") for (int k = 0; k < 2; ++k) \
;         acc[ai][bj][m][n] = __builtin_amdgcn_mfma_f32_16x16x32_bf16(Bt[n][k], At[m][k], acc[ai][bj][m][n], 0, 0, 0); __builtin_amdgcn_s_setprio(0); } while (0)
; #define PG8_WAIT_V(n) asm volatile("s_waitcnt vmcnt(" #n ")" ::: "memory")
; #define PG8_WAIT_L(n) asm volatile("s_waitcnt lgkmcnt(" #n ")" ::: "memory")
; #define PG8_BAR __builtin_amdgcn_s_barrier()
; #define PG8_SCHED __builtin_amdgcn_sched_barrier(0)
; template <class Epi, class Sched>
; __device__ __forceinline__ void gemm_phase(LAS unsigned char* lds, const Gemm g, const Sched& S, const Epi& E) {
;     ...
;             PG8_LDB(B0, 1, 0); PG8_SCHED; PG8_LDA(At, 1, 0); PG8_STAGE(PG8_SA(0, 1), a2 + hstep, voffA);
;             PG8_WAIT_L(8); PG8_BAR; PG8_WAIT_L(0); PG8_MMA(0, 0, At, B0); PG8_BAR; PG8_SCHED;
;             PG8_LDB(B1, 1, 1); PG8_STAGE(PG8_SB(1, 0), b3, voffB);
;             PG8_BAR; PG8_WAIT_L(0); PG8_MMA(0, 1, At, B1); PG8_BAR;
;             PG8_LDA(At, 1, 1); PG8_STAGE(PG8_SA(1, 0), a3, voffA);
;             PG8_BAR; PG8_WAIT_L(0); PG8_MMA(1, 0, At, B0); PG8_BAR; PG8_SCHED;
;             PG8_STAGE(PG8_SB(1, 1), b3 + hstep, voffB);
;             PG8_WAIT_V(6); PG8_BAR; PG8_MMA(1, 1, At, B1); PG8_BAR;
	s_waitcnt lgkmcnt(0)
	s_setprio 1
	s_waitcnt lgkmcnt(0)
	v_mfma_f32_16x16x32_bf16 v[124:127], v[140:143], v[166:169], v[124:127]
	v_mfma_f32_16x16x32_bf16 v[120:123], v[158:161], v[166:169], v[120:123]
	v_mfma_f32_16x16x32_bf16 v[108:111], v[140:143], v[174:177], v[108:111]
	v_mfma_f32_16x16x32_bf16 v[104:107], v[158:161], v[174:177], v[104:107]
	v_mfma_f32_16x16x32_bf16 v[92:95], v[140:143], v[182:185], v[92:95]
	v_mfma_f32_16x16x32_bf16 v[88:91], v[158:161], v[182:185], v[88:91]
	v_mfma_f32_16x16x32_bf16 v[76:79], v[140:143], v[190:193], v[76:79]
	v_mfma_f32_16x16x32_bf16 v[72:75], v[158:161], v[190:193], v[72:75]
	v_mfma_f32_16x16x32_bf16 v[124:127], v[154:157], v[170:173], v[124:127]
	v_mfma_f32_16x16x32_bf16 v[120:123], v[162:165], v[170:173], v[120:123]
	v_mfma_f32_16x16x32_bf16 v[108:111], v[154:157], v[178:181], v[108:111]
	v_mfma_f32_16x16x32_bf16 v[104:107], v[162:165], v[178:181], v[104:107]
	v_mfma_f32_16x16x32_bf16 v[92:95], v[154:157], v[186:189], v[92:95]
	v_mfma_f32_16x16x32_bf16 v[88:91], v[162:165], v[186:189], v[88:91]
	v_mfma_f32_16x16x32_bf16 v[76:79], v[154:157], v[194:197], v[76:79]
	v_mfma_f32_16x16x32_bf16 v[72:75], v[162:165], v[194:197], v[72:75]
	s_setprio 0
	s_barrier
	s_add_i32 s24, 0, 0x1c000
	s_add_i32 s25, s62, s31
	v_add_u32_e32 v214, s24, v148
	s_add_u32 s0, s4, 0x80
	s_addc_u32 s1, s5, 0
	s_mov_b32 m0, s25
	ds_read_b128 v[202:205], v214
	ds_read_b128 v[206:209], v214 offset:1024
	ds_read_b128 v[210:213], v214 offset:2048
	ds_read_b128 v[214:217], v214 offset:3072
	global_load_lds_dwordx4 v130, s[0:1]
	s_add_i32 m0, s25, 0x2000
	s_nop 0
	global_load_lds_dwordx4 v134, s[0:1]
	s_waitcnt vmcnt(8)
	s_barrier
	s_waitcnt lgkmcnt(0)
	s_setprio 1
	s_waitcnt lgkmcnt(0)
	v_mfma_f32_16x16x32_bf16 v[116:119], v[202:205], v[166:169], v[116:119]
	v_mfma_f32_16x16x32_bf16 v[112:115], v[210:213], v[166:169], v[112:115]
	v_mfma_f32_16x16x32_bf16 v[100:103], v[202:205], v[174:177], v[100:103]
	v_mfma_f32_16x16x32_bf16 v[96:99], v[210:213], v[174:177], v[96:99]
	v_mfma_f32_16x16x32_bf16 v[84:87], v[202:205], v[182:185], v[84:87]
	v_mfma_f32_16x16x32_bf16 v[80:83], v[210:213], v[182:185], v[80:83]
	v_mfma_f32_16x16x32_bf16 v[68:71], v[202:205], v[190:193], v[68:71]
	v_mfma_f32_16x16x32_bf16 v[64:67], v[210:213], v[190:193], v[64:67]
	v_mfma_f32_16x16x32_bf16 v[116:119], v[206:209], v[170:173], v[116:119]
	v_mfma_f32_16x16x32_bf16 v[112:115], v[214:217], v[170:173], v[112:115]
	v_mfma_f32_16x16x32_bf16 v[100:103], v[206:209], v[178:181], v[100:103]
	v_mfma_f32_16x16x32_bf16 v[96:99], v[214:217], v[178:181], v[96:99]
	v_mfma_f32_16x16x32_bf16 v[84:87], v[206:209], v[186:189], v[84:87]
	v_mfma_f32_16x16x32_bf16 v[80:83], v[214:217], v[186:189], v[80:83]
	v_mfma_f32_16x16x32_bf16 v[68:71], v[206:209], v[194:197], v[68:71]
	v_mfma_f32_16x16x32_bf16 v[64:67], v[214:217], v[194:197], v[64:67]
	s_setprio 0
	s_mov_b32 m0, s44
	s_mov_b64 s[0:1], 0x80
	v_lshl_add_u64 v[144:145], v[218:219], 0, s[0:1]
	s_barrier
	ds_read_b128 v[166:169], v150 offset:49152
	ds_read_b128 v[170:173], v150 offset:50176
	ds_read_b128 v[174:177], v150 offset:51200
	ds_read_b128 v[178:181], v150 offset:52224
	ds_read_b128 v[182:185], v150 offset:53248
	ds_read_b128 v[186:189], v150 offset:54272
	ds_read_b128 v[190:193], v150 offset:55296
	ds_read_b128 v[194:197], v150 offset:56320
	global_load_lds_dwordx4 v[144:145], off
	v_lshl_add_u64 v[144:145], v[220:221], 0, s[0:1]
	s_mov_b32 m0, s45
	s_nop 0
	global_load_lds_dwordx4 v[144:145], off
	s_barrier
	s_waitcnt lgkmcnt(0)
	s_setprio 1
	s_waitcnt lgkmcnt(0)
	v_mfma_f32_16x16x32_bf16 v[60:63], v[140:143], v[166:169], v[60:63]
	v_mfma_f32_16x16x32_bf16 v[56:59], v[158:161], v[166:169], v[56:59]
	v_mfma_f32_16x16x32_bf16 v[44:47], v[140:143], v[174:177], v[44:47]
	v_mfma_f32_16x16x32_bf16 v[40:43], v[158:161], v[174:177], v[40:43]
	v_mfma_f32_16x16x32_bf16 v[28:31], v[140:143], v[182:185], v[28:31]
	v_mfma_f32_16x16x32_bf16 v[24:27], v[158:161], v[182:185], v[24:27]
	v_mfma_f32_16x16x32_bf16 v[12:15], v[140:143], v[190:193], v[12:15]
	v_mfma_f32_16x16x32_bf16 v[8:11], v[158:161], v[190:193], v[8:11]
	v_mfma_f32_16x16x32_bf16 v[60:63], v[154:157], v[170:173], v[60:63]
	v_mfma_f32_16x16x32_bf16 v[56:59], v[162:165], v[170:173], v[56:59]
	v_mfma_f32_16x16x32_bf16 v[44:47], v[154:157], v[178:181], v[44:47]
	v_mfma_f32_16x16x32_bf16 v[40:43], v[162:165], v[178:181], v[40:43]
	v_mfma_f32_16x16x32_bf16 v[28:31], v[154:157], v[186:189], v[28:31]
	v_mfma_f32_16x16x32_bf16 v[24:27], v[162:165], v[186:189], v[24:27]
	v_mfma_f32_16x16x32_bf16 v[12:15], v[154:157], v[194:197], v[12:15]
	v_mfma_f32_16x16x32_bf16 v[8:11], v[162:165], v[194:197], v[8:11]
	s_setprio 0
	s_barrier
	s_add_u32 s4, s4, 0x40080
	s_addc_u32 s5, s5, 0
	s_add_i32 s24, s24, s31
	s_mov_b32 m0, s24
	s_nop 0
	global_load_lds_dwordx4 v130, s[4:5]
	s_add_i32 m0, s24, 0x2000
	s_nop 0
	global_load_lds_dwordx4 v134, s[4:5]
	s_waitcnt vmcnt(8)
	s_barrier
	s_setprio 1
	v_mfma_f32_16x16x32_bf16 v[52:55], v[202:205], v[166:169], v[52:55]
	v_mfma_f32_16x16x32_bf16 v[48:51], v[210:213], v[166:169], v[48:51]
	v_mfma_f32_16x16x32_bf16 v[36:39], v[202:205], v[174:177], v[36:39]
	v_mfma_f32_16x16x32_bf16 v[32:35], v[210:213], v[174:177], v[32:35]
	v_mfma_f32_16x16x32_bf16 v[20:23], v[202:205], v[182:185], v[20:23]
	v_mfma_f32_16x16x32_bf16 v[16:19], v[210:213], v[182:185], v[16:19]
	v_mfma_f32_16x16x32_bf16 v[4:7], v[202:205], v[190:193], v[4:7]
	v_mfma_f32_16x16x32_bf16 v[0:3], v[210:213], v[190:193], v[0:3]
	v_mfma_f32_16x16x32_bf16 v[52:55], v[206:209], v[170:173], v[52:55]
	v_mfma_f32_16x16x32_bf16 v[48:51], v[214:217], v[170:173], v[48:51]
	v_mfma_f32_16x16x32_bf16 v[36:39], v[206:209], v[178:181], v[36:39]
	v_mfma_f32_16x16x32_bf16 v[32:35], v[214:217], v[178:181], v[32:35]
	v_mfma_f32_16x16x32_bf16 v[20:23], v[206:209], v[186:189], v[20:23]
	v_mfma_f32_16x16x32_bf16 v[16:19], v[214:217], v[186:189], v[16:19]
	v_mfma_f32_16x16x32_bf16 v[4:7], v[206:209], v[194:197], v[4:7]
	v_mfma_f32_16x16x32_bf16 v[0:3], v[214:217], v[194:197], v[0:3]
	s_setprio 0
	s_add_i32 s61, s61, 2
	s_add_u32 s2, s2, 0x100
	s_addc_u32 s3, s3, 0
	s_add_u32 s59, s59, 0x100
	s_addc_u32 s60, s60, 0
	s_cmp_gt_u32 s61, 13
	s_barrier
;     __device__ __forceinline__ void operator()(const AccT& acc, const Unit& u, int wr, int wc, int fr, int fq) const {
;         asm volatile("" : "+v"(fr), "+v"(fq));
;         const int rbase = wr * 64 + fr;
;         const int tb = u.pn * 256 + wc * 32 + 8 * fq;
;         const int o0 = wc * 32 + 8 * fq;
;         const int j = fr & 3; const float sgn = ((fr >> 2) & 1) ? 1.0f : -1.0f;
; #pragma unroll
;         for (int ai = 0; ai < 2; ++ai) {
;             const int hh = 2 * ai + wr;
;             const float l2f = lgd[hh] * 1.4426950408889634f, l2b = lgd[4 + hh] * 1.4426950408889634f;
;             const float zf0 = exp2f((float)(127 - o0) * l2f), zfs = exp2f(-l2f), zb0 = exp2f((float)o0 * l2b), zbs = exp2f(l2b);
; #pragma unroll
;             for (int m = 0; m < 4; ++m) {
;                 const int r = rbase + ai * 128 + m * 16;
;                 const int d = 4 * (2 * m + (fr >> 3)) + j;
; #pragma unroll
;                 for (int bj = 0; bj < 2; ++bj) {
;                     const int t0 = tb + bj * 128;
;                     float v[8];
; #pragma unroll
;                     for (int jj = 0; jj < 4; ++jj) { v[jj] = acc[ai][bj][m][0][jj]; v[4 + jj] = acc[ai][bj][m][1][jj]; }
;                     if constexpr (ROPE) {
;                         const int t = t0 & 2047;
; #pragma unroll
;                         for (int hf = 0; hf < 2; ++hf) {
;                             f32x4 cs, sn;
;                             if (m < 2) { const float c1 = ropeA[(t >> 6) * 16 + d], s1 = ropeA[1024 + (t >> 6) * 16 + d]; cs = (f32x4){c1, c1, c1, c1}; sn = (f32x4){s1, s1, s1, s1}; }
;                             else { const float* cb = ropeA + 2048 + (d - 16) * 64 + (t & 63) + 4 * hf; cs = *(const f32x4*)(cb); sn = *(const f32x4*)(cb + 1024); }
; #pragma unroll
;                             for (int jj = 0; jj < 4; ++jj) { const float pr = __shfl_xor(v[4 * hf + jj], 4); v[4 * hf + jj] = v[4 * hf + jj] * cs[jj] + sgn * pr * sn[jj]; }
;                             __builtin_amdgcn_sched_barrier(0);
;                         }
;                     }
;                     float zf[8], zb[8]; zf[0] = zf0; zb[0] = zb0;
; #pragma unroll
;                     for (int jj = 1; jj < 8; ++jj) { zf[jj] = zf[jj - 1] * zfs; zb[jj] = zb[jj - 1] * zbs; }
;                     u32x4 wf, wb;
	s_cbranch_scc0 .LBB0_693
	v_mov_b32_e32 v141, v147
	v_mov_b32_e32 v140, v146
	global_load_dword v156, v131, s[6:7]
	global_load_dword v157, v131, s[6:7] offset:16
	s_lshl_b32 s2, s56, 8
	s_or_b32 s2, s2, s43
	v_add_u32_e32 v140, s42, v140
	v_lshlrev_b32_e32 v141, 3, v141
	v_add_u32_e32 v142, s2, v141
	v_add_u32_e32 v143, s43, v141
	v_ashrrev_i32_e32 v141, 31, v140
	v_sub_u32_e32 v144, 0x7f, v143
	v_lshlrev_b64 v[140:141], 14, v[140:141]
	v_cvt_f32_i32_e32 v154, v143
	v_ashrrev_i32_e32 v143, 31, v142
	v_cvt_f32_i32_e32 v155, v144
	v_lshl_add_u64 v[140:141], s[70:71], 0, v[140:141]
	s_mov_b32 s3, 0x400000
	v_lshl_add_u64 v[140:141], v[142:143], 1, v[140:141]
	v_add_co_u32_e32 v144, vcc, s3, v140
	s_mov_b64 s[4:5], 0x400000
	s_nop 0
	v_addc_co_u32_e32 v145, vcc, 0, v141, vcc
	v_lshl_add_u64 v[142:143], v[140:141], 0, s[4:5]
	s_waitcnt vmcnt(0)
	v_mul_f32_e32 v158, 0x3fb8aa3b, v156
	v_mul_f32_e32 v159, 0x3fb8aa3b, v157
	v_mul_f32_e32 v160, v158, v155
	v_cmp_lt_f32_e32 vcc, s51, v158
	v_mul_f32_e32 v162, v159, v154
	v_cmp_gt_f32_e64 s[2:3], s49, v159
	v_cndmask_b32_e32 v161, 0, v153, vcc
	v_cmp_gt_f32_e64 s[4:5], s49, v160
	v_cndmask_b32_e64 v163, 0, v153, s[2:3]
	s_and_b64 s[24:25], vcc, exec
	v_cmp_gt_f32_e32 vcc, s49, v162
	v_fmac_f32_e32 v163, 0x3fb8aa3b, v157
	v_cndmask_b32_e64 v157, 0, v153, s[4:5]
	v_cndmask_b32_e32 v162, 0, v153, vcc
	v_fmac_f32_e32 v161, 0xbfb8aa3b, v156
	v_fmac_f32_e32 v157, v158, v155
	v_fmac_f32_e32 v162, v159, v154
	v_exp_f32_e32 v161, v161
	v_exp_f32_e32 v163, v163
	v_exp_f32_e32 v157, v157
	v_exp_f32_e32 v158, v162
	v_cndmask_b32_e64 v160, 0, v152, s[4:5]
	s_cselect_b32 s4, 0xffffffc0, 0
	s_and_b64 s[2:3], s[2:3], exec
	v_cndmask_b32_e32 v156, 0, v152, vcc
	s_cselect_b32 s2, 0xffffffc0, 0
	v_ldexp_f32 v161, v161, s4
	v_ldexp_f32 v162, v163, s2
	v_ldexp_f32 v163, v157, v160
	v_ldexp_f32 v156, v158, v156
	v_mul_f32_e32 v164, v161, v163
	v_mul_f32_e32 v157, v162, v156
	v_mul_f32_e32 v158, v124, v163
	v_mul_f32_e32 v165, v124, v156
	v_mul_f32_e32 v166, v161, v164
	v_mul_f32_e32 v124, v162, v157
	v_mul_f32_e32 v159, v125, v164
	v_mul_f32_e32 v167, v125, v157
	v_mul_f32_e32 v168, v161, v166
	v_mul_f32_e32 v125, v162, v124
	v_cvt_pk_bf16_f32 v158, v158, v159
	v_mul_f32_e32 v159, v126, v166
	v_mul_f32_e32 v169, v126, v124
	v_mul_f32_e32 v170, v161, v168
	v_mul_f32_e32 v126, v162, v125
	v_mul_f32_e32 v171, v161, v170
	v_mul_f32_e32 v172, v162, v126
	v_mul_f32_e32 v160, v127, v168
	v_mul_f32_e32 v174, v161, v171
	v_mul_f32_e32 v175, v162, v172
	v_cvt_pk_bf16_f32 v159, v159, v160
	v_mul_f32_e32 v160, v120, v170
	v_mul_f32_e32 v173, v120, v126
	v_mul_f32_e32 v120, v121, v171
	v_mul_f32_e32 v177, v161, v174
	v_mul_f32_e32 v162, v162, v175
	v_mul_f32_e32 v176, v121, v172
	v_cvt_pk_bf16_f32 v160, v160, v120
	v_mul_f32_e32 v120, v122, v174
	v_mul_f32_e32 v121, v123, v177
	v_mul_f32_e32 v123, v123, v162
	v_cvt_pk_bf16_f32 v161, v120, v121
	v_mul_f32_e32 v127, v127, v125
	v_mul_f32_e32 v178, v122, v175
	v_cvt_pk_bf16_f32 v120, v165, v167
	v_cvt_pk_bf16_f32 v121, v169, v127
	v_cvt_pk_bf16_f32 v122, v173, v176
	v_cvt_pk_bf16_f32 v123, v178, v123
	global_store_dwordx4 v[140:141], v[158:161], off
	global_store_dwordx4 v[144:145], v[120:123], off
	s_nop 1
	v_mul_f32_e32 v120, v116, v163
	v_mul_f32_e32 v121, v117, v164
	v_cvt_pk_bf16_f32 v120, v120, v121
	v_mul_f32_e32 v121, v118, v166
	v_mul_f32_e32 v122, v119, v168
	v_cvt_pk_bf16_f32 v121, v121, v122
	v_mul_f32_e32 v122, v112, v170
	v_mul_f32_e32 v123, v113, v171
	v_cvt_pk_bf16_f32 v122, v122, v123
	v_mul_f32_e32 v123, v114, v174
	v_mul_f32_e32 v116, v116, v156
	v_mul_f32_e32 v117, v117, v157
	v_mul_f32_e32 v127, v115, v177
	v_cvt_pk_bf16_f32 v123, v123, v127
	v_cvt_pk_bf16_f32 v116, v116, v117
	v_mul_f32_e32 v117, v118, v124
	v_mul_f32_e32 v118, v119, v125
	v_mul_f32_e32 v112, v112, v126
	v_mul_f32_e32 v113, v113, v172
	v_cvt_pk_bf16_f32 v117, v117, v118
	v_cvt_pk_bf16_f32 v118, v112, v113
	v_mul_f32_e32 v112, v114, v175
	v_mul_f32_e32 v113, v115, v162
	v_cvt_pk_bf16_f32 v119, v112, v113
	global_store_dwordx4 v[140:141], v[120:123], off offset:256
	global_store_dwordx4 v[142:143], v[116:119], off offset:256
	v_mul_f32_e32 v112, v108, v163
	v_mul_f32_e32 v113, v109, v164
	v_cvt_pk_bf16_f32 v112, v112, v113
	v_mul_f32_e32 v113, v110, v166
	v_mul_f32_e32 v114, v111, v168
	v_cvt_pk_bf16_f32 v113, v113, v114
	v_mul_f32_e32 v114, v104, v170
	v_mul_f32_e32 v115, v105, v171
	v_cvt_pk_bf16_f32 v114, v114, v115
	v_mul_f32_e32 v115, v106, v174
	v_mul_f32_e32 v108, v108, v156
	v_mul_f32_e32 v109, v109, v157
	v_mul_f32_e32 v116, v107, v177
	v_cvt_pk_bf16_f32 v115, v115, v116
	v_cvt_pk_bf16_f32 v108, v108, v109
	v_mul_f32_e32 v109, v110, v124
	v_mul_f32_e32 v110, v111, v125
	v_mul_f32_e32 v104, v104, v126
	s_mov_b64 s[2:3], 0x40000
	v_cvt_pk_bf16_f32 v109, v109, v110
	v_mul_f32_e32 v105, v105, v172
	v_cvt_pk_bf16_f32 v110, v104, v105
	v_mul_f32_e32 v104, v106, v175
	v_lshl_add_u64 v[116:117], v[140:141], 0, s[2:3]
	s_mov_b32 s2, 0x40000
	v_mul_f32_e32 v105, v107, v162
	v_cvt_pk_bf16_f32 v111, v104, v105
	v_add_co_u32_e32 v104, vcc, s2, v140
	s_mov_b64 s[2:3], 0x440000
	s_nop 0
	v_addc_co_u32_e32 v105, vcc, 0, v141, vcc
	global_store_dwordx4 v[104:105], v[112:115], off
	s_nop 1
	v_lshl_add_u64 v[112:113], v[140:141], 0, s[2:3]
	s_mov_b32 s2, 0x440000
	v_add_co_u32_e32 v104, vcc, s2, v140
	s_nop 1
	v_addc_co_u32_e32 v105, vcc, 0, v141, vcc
	global_store_dwordx4 v[104:105], v[108:111], off
	v_mul_f32_e32 v104, v100, v163
	v_mul_f32_e32 v105, v101, v164
	v_cvt_pk_bf16_f32 v104, v104, v105
	v_mul_f32_e32 v105, v102, v166
	v_mul_f32_e32 v106, v103, v168
	v_cvt_pk_bf16_f32 v105, v105, v106
; __device__ __forceinline__ unsigned cvt_pk_bf16(float lo, float hi) { unsigned r; asm volatile("v_cvt_pk_bf16_f32 %0, %1, %2" : "=v"(r) : "v"(lo), "v"(hi)); return r; }
;     __device__ __forceinline__ void operator()(const AccT& acc, const Unit& u, int wr, int wc, int fr, int fq) const {
;     ...
;                 for (int bj = 0; bj < 2; ++bj) {
;                     const int t0 = tb + bj * 128;
;                     float v[8];
; #pragma unroll
;                     for (int jj = 0; jj < 4; ++jj) { v[jj] = acc[ai][bj][m][0][jj]; v[4 + jj] = acc[ai][bj][m][1][jj]; }
;                     if constexpr (ROPE) {
;                         const int t = t0 & 2047;
; #pragma unroll
;                         for (int hf = 0; hf < 2; ++hf) {
;                             f32x4 cs, sn;
;                             if (m < 2) { const float c1 = ropeA[(t >> 6) * 16 + d], s1 = ropeA[1024 + (t >> 6) * 16 + d]; cs = (f32x4){c1, c1, c1, c1}; sn = (f32x4){s1, s1, s1, s1}; }
;                             else { const float* cb = ropeA + 2048 + (d - 16) * 64 + (t & 63) + 4 * hf; cs = *(const f32x4*)(cb); sn = *(const f32x4*)(cb + 1024); }
; #pragma unroll
;                             for (int jj = 0; jj < 4; ++jj) { const float pr = __shfl_xor(v[4 * hf + jj], 4); v[4 * hf + jj] = v[4 * hf + jj] * cs[jj] + sgn * pr * sn[jj]; }
;                             __builtin_amdgcn_sched_barrier(0);
;                         }
;                     }
;                     float zf[8], zb[8]; zf[0] = zf0; zb[0] = zb0;
; #pragma unroll
;                     for (int jj = 1; jj < 8; ++jj) { zf[jj] = zf[jj - 1] * zfs; zb[jj] = zb[jj - 1] * zbs; }
;                     u32x4 wf, wb;
;                     wf.x = cvt_pk_bf16(v[0] * zf[0], v[1] * zf[1]); wf.y = cvt_pk_bf16(v[2] * zf[2], v[3] * zf[3]); wf.z = cvt_pk_bf16(v[4] * zf[4], v[5] * zf[5]); wf.w = cvt_pk_bf16(v[6] * zf[6], v[7] * zf[7]);
;                     wb.x = cvt_pk_bf16(v[0] * zb[0], v[1] * zb[1]); wb.y = cvt_pk_bf16(v[2] * zb[2], v[3] * zb[3]); wb.z = cvt_pk_bf16(v[4] * zb[4], v[5] * zb[5]); wb.w = cvt_pk_bf16(v[6] * zb[6], v[7] * zb[7]);
;                     *(u32x4*)(KTZ + (size_t)r * NT + t0) = wf;
;                     *(u32x4*)(KTZ + (size_t)(256 + r) * NT + t0) = wb;
	v_mul_f32_e32 v106, v96, v170
	v_mul_f32_e32 v107, v97, v171
	v_cvt_pk_bf16_f32 v106, v106, v107
	v_mul_f32_e32 v107, v98, v174
	v_mul_f32_e32 v100, v100, v156
	v_mul_f32_e32 v101, v101, v157
	v_mul_f32_e32 v108, v99, v177
	v_cvt_pk_bf16_f32 v107, v107, v108
	v_cvt_pk_bf16_f32 v100, v100, v101
	v_mul_f32_e32 v101, v102, v124
	v_mul_f32_e32 v102, v103, v125
	v_mul_f32_e32 v96, v96, v126
	v_mul_f32_e32 v97, v97, v172
	v_cvt_pk_bf16_f32 v101, v101, v102
	v_cvt_pk_bf16_f32 v102, v96, v97
	v_mul_f32_e32 v96, v98, v175
	v_mul_f32_e32 v97, v99, v162
	v_cvt_pk_bf16_f32 v103, v96, v97
	global_store_dwordx4 v[116:117], v[104:107], off offset:256
	global_store_dwordx4 v[112:113], v[100:103], off offset:256
	v_mul_f32_e32 v96, v92, v163
	v_mul_f32_e32 v97, v93, v164
	v_cvt_pk_bf16_f32 v96, v96, v97
	v_mul_f32_e32 v97, v94, v166
	v_mul_f32_e32 v98, v95, v168
	v_cvt_pk_bf16_f32 v97, v97, v98
	v_mul_f32_e32 v98, v88, v170
	v_mul_f32_e32 v99, v89, v171
	v_cvt_pk_bf16_f32 v98, v98, v99
	v_mul_f32_e32 v99, v90, v174
	v_mul_f32_e32 v92, v92, v156
	v_mul_f32_e32 v93, v93, v157
	v_mul_f32_e32 v100, v91, v177
	v_cvt_pk_bf16_f32 v99, v99, v100
	v_cvt_pk_bf16_f32 v92, v92, v93
	v_mul_f32_e32 v93, v94, v124
	v_mul_f32_e32 v94, v95, v125
	v_mul_f32_e32 v88, v88, v126
	s_mov_b64 s[2:3], 0x80000
	v_cvt_pk_bf16_f32 v93, v93, v94
	v_mul_f32_e32 v89, v89, v172
	v_cvt_pk_bf16_f32 v94, v88, v89
	v_mul_f32_e32 v88, v90, v175
	v_lshl_add_u64 v[100:101], v[140:141], 0, s[2:3]
	s_mov_b32 s2, 0x80000
	v_mul_f32_e32 v89, v91, v162
	v_cvt_pk_bf16_f32 v95, v88, v89
	v_add_co_u32_e32 v88, vcc, s2, v140
	s_mov_b64 s[2:3], 0x480000
	s_nop 0
	v_addc_co_u32_e32 v89, vcc, 0, v141, vcc
	global_store_dwordx4 v[88:89], v[96:99], off
	s_nop 1
	v_lshl_add_u64 v[96:97], v[140:141], 0, s[2:3]
	s_mov_b32 s2, 0x480000
	v_add_co_u32_e32 v88, vcc, s2, v140
	s_nop 1
	v_addc_co_u32_e32 v89, vcc, 0, v141, vcc
	global_store_dwordx4 v[88:89], v[92:95], off
	v_mul_f32_e32 v88, v84, v163
	v_mul_f32_e32 v89, v85, v164
	v_cvt_pk_bf16_f32 v88, v88, v89
	v_mul_f32_e32 v89, v86, v166
	v_mul_f32_e32 v90, v87, v168
	v_cvt_pk_bf16_f32 v89, v89, v90
	v_mul_f32_e32 v90, v80, v170
	v_mul_f32_e32 v91, v81, v171
	v_cvt_pk_bf16_f32 v90, v90, v91
	v_mul_f32_e32 v91, v82, v174
	v_mul_f32_e32 v84, v84, v156
	v_mul_f32_e32 v85, v85, v157
	v_mul_f32_e32 v92, v83, v177
	v_cvt_pk_bf16_f32 v91, v91, v92
	v_cvt_pk_bf16_f32 v84, v84, v85
	v_mul_f32_e32 v85, v86, v124
	v_mul_f32_e32 v86, v87, v125
	v_mul_f32_e32 v80, v80, v126
	v_mul_f32_e32 v81, v81, v172
	v_cvt_pk_bf16_f32 v85, v85, v86
	v_cvt_pk_bf16_f32 v86, v80, v81
	v_mul_f32_e32 v80, v82, v175
	v_mul_f32_e32 v81, v83, v162
	v_cvt_pk_bf16_f32 v87, v80, v81
	global_store_dwordx4 v[100:101], v[88:91], off offset:256
	global_store_dwordx4 v[96:97], v[84:87], off offset:256
	v_mul_f32_e32 v80, v76, v163
	v_mul_f32_e32 v81, v77, v164
	v_cvt_pk_bf16_f32 v80, v80, v81
	v_mul_f32_e32 v81, v78, v166
	v_mul_f32_e32 v82, v79, v168
	v_cvt_pk_bf16_f32 v81, v81, v82
	v_mul_f32_e32 v82, v72, v170
	v_mul_f32_e32 v83, v73, v171
	v_cvt_pk_bf16_f32 v82, v82, v83
	v_mul_f32_e32 v83, v74, v174
	v_mul_f32_e32 v76, v76, v156
	v_mul_f32_e32 v77, v77, v157
	v_mul_f32_e32 v84, v75, v177
	v_cvt_pk_bf16_f32 v83, v83, v84
	v_cvt_pk_bf16_f32 v76, v76, v77
	v_mul_f32_e32 v77, v78, v124
	v_mul_f32_e32 v78, v79, v125
	v_mul_f32_e32 v72, v72, v126
	s_mov_b64 s[2:3], 0xc0000
	v_cvt_pk_bf16_f32 v77, v77, v78
	v_mul_f32_e32 v73, v73, v172
	v_cvt_pk_bf16_f32 v78, v72, v73
	v_mul_f32_e32 v72, v74, v175
	v_lshl_add_u64 v[84:85], v[140:141], 0, s[2:3]
	s_mov_b32 s2, 0xc0000
	v_mul_f32_e32 v73, v75, v162
	v_cvt_pk_bf16_f32 v79, v72, v73
	v_add_co_u32_e32 v72, vcc, s2, v140
	s_mov_b64 s[2:3], 0x4c0000
	s_nop 0
	v_addc_co_u32_e32 v73, vcc, 0, v141, vcc
	global_store_dwordx4 v[72:73], v[80:83], off
	s_nop 1
	v_lshl_add_u64 v[80:81], v[140:141], 0, s[2:3]
	s_mov_b32 s2, 0x4c0000
	v_add_co_u32_e32 v72, vcc, s2, v140
	s_nop 1
	v_addc_co_u32_e32 v73, vcc, 0, v141, vcc
	global_store_dwordx4 v[72:73], v[76:79], off
	v_mul_f32_e32 v72, v68, v163
	v_mul_f32_e32 v73, v69, v164
	v_cvt_pk_bf16_f32 v72, v72, v73
	v_mul_f32_e32 v73, v70, v166
	v_mul_f32_e32 v74, v71, v168
	v_cvt_pk_bf16_f32 v73, v73, v74
	v_mul_f32_e32 v74, v64, v170
	v_mul_f32_e32 v75, v65, v171
	v_cvt_pk_bf16_f32 v74, v74, v75
	v_mul_f32_e32 v75, v66, v174
	v_mul_f32_e32 v68, v68, v156
	v_mul_f32_e32 v69, v69, v157
	v_mul_f32_e32 v76, v67, v177
	v_cvt_pk_bf16_f32 v75, v75, v76
	v_cvt_pk_bf16_f32 v68, v68, v69
	v_mul_f32_e32 v69, v70, v124
	v_mul_f32_e32 v70, v71, v125
	v_mul_f32_e32 v64, v64, v126
	v_mul_f32_e32 v65, v65, v172
	v_cvt_pk_bf16_f32 v69, v69, v70
	v_cvt_pk_bf16_f32 v70, v64, v65
	v_mul_f32_e32 v64, v66, v175
	v_mul_f32_e32 v65, v67, v162
	v_cvt_pk_bf16_f32 v71, v64, v65
	global_store_dwordx4 v[84:85], v[72:75], off offset:256
	global_store_dwordx4 v[80:81], v[68:71], off offset:256
	global_load_dword v70, v131, s[6:7] offset:8
	s_nop 0
	global_load_dword v71, v131, s[6:7] offset:24
	s_mov_b32 s17, 0x200000
	v_add_co_u32_e32 v76, vcc, s17, v140
	s_mov_b32 s19, 0x600000
	s_nop 0
	v_addc_co_u32_e32 v77, vcc, 0, v141, vcc
	v_add_co_u32_e32 v68, vcc, s19, v140
	s_mov_b64 s[2:3], 0x200000
	s_nop 0
	v_addc_co_u32_e32 v69, vcc, 0, v141, vcc
	s_mov_b64 s[4:5], 0x600000
	v_lshl_add_u64 v[64:65], v[140:141], 0, s[2:3]
	v_lshl_add_u64 v[66:67], v[140:141], 0, s[4:5]
	s_waitcnt vmcnt(0)
; __device__ __forceinline__ unsigned cvt_pk_bf16(float lo, float hi) { unsigned r; asm volatile("v_cvt_pk_bf16_f32 %0, %1, %2" : "=v"(r) : "v"(lo), "v"(hi)); return r; }
;     __device__ __forceinline__ void operator()(const AccT& acc, const Unit& u, int wr, int wc, int fr, int fq) const {
;     ...
;             const int hh = 2 * ai + wr;
;             const float l2f = lgd[hh] * 1.4426950408889634f, l2b = lgd[4 + hh] * 1.4426950408889634f;
;             const float zf0 = exp2f((float)(127 - o0) * l2f), zfs = exp2f(-l2f), zb0 = exp2f((float)o0 * l2b), zbs = exp2f(l2b);
; #pragma unroll
;             for (int m = 0; m < 4; ++m) {
;                 const int r = rbase + ai * 128 + m * 16;
;                 const int d = 4 * (2 * m + (fr >> 3)) + j;
; #pragma unroll
;                 for (int bj = 0; bj < 2; ++bj) {
;                     const int t0 = tb + bj * 128;
;                     float v[8];
; #pragma unroll
;                     for (int jj = 0; jj < 4; ++jj) { v[jj] = acc[ai][bj][m][0][jj]; v[4 + jj] = acc[ai][bj][m][1][jj]; }
;                     if constexpr (ROPE) {
;                         const int t = t0 & 2047;
; #pragma unroll
;                         for (int hf = 0; hf < 2; ++hf) {
;                             f32x4 cs, sn;
;                             if (m < 2) { const float c1 = ropeA[(t >> 6) * 16 + d], s1 = ropeA[1024 + (t >> 6) * 16 + d]; cs = (f32x4){c1, c1, c1, c1}; sn = (f32x4){s1, s1, s1, s1}; }
;                             else { const float* cb = ropeA + 2048 + (d - 16) * 64 + (t & 63) + 4 * hf; cs = *(const f32x4*)(cb); sn = *(const f32x4*)(cb + 1024); }
; #pragma unroll
;                             for (int jj = 0; jj < 4; ++jj) { const float pr = __shfl_xor(v[4 * hf + jj], 4); v[4 * hf + jj] = v[4 * hf + jj] * cs[jj] + sgn * pr * sn[jj]; }
;                             __builtin_amdgcn_sched_barrier(0);
;                         }
;                     }
;                     float zf[8], zb[8]; zf[0] = zf0; zb[0] = zb0;
; #pragma unroll
;                     for (int jj = 1; jj < 8; ++jj) { zf[jj] = zf[jj - 1] * zfs; zb[jj] = zb[jj - 1] * zbs; }
;                     u32x4 wf, wb;
;                     wf.x = cvt_pk_bf16(v[0] * zf[0], v[1] * zf[1]); wf.y = cvt_pk_bf16(v[2] * zf[2], v[3] * zf[3]); wf.z = cvt_pk_bf16(v[4] * zf[4], v[5] * zf[5]); wf.w = cvt_pk_bf16(v[6] * zf[6], v[7] * zf[7]);
	v_mul_f32_e32 v72, 0x3fb8aa3b, v70
	v_mul_f32_e32 v73, 0x3fb8aa3b, v71
	v_mul_f32_e32 v74, v72, v155
	v_cmp_lt_f32_e32 vcc, s51, v72
	v_mul_f32_e32 v78, v73, v154
	v_cmp_gt_f32_e64 s[2:3], s49, v73
	v_cndmask_b32_e32 v75, 0, v153, vcc
	v_cmp_gt_f32_e64 s[4:5], s49, v74
	v_cndmask_b32_e64 v79, 0, v153, s[2:3]
	s_and_b64 s[24:25], vcc, exec
	v_cmp_gt_f32_e32 vcc, s49, v78
	v_fmac_f32_e32 v79, 0x3fb8aa3b, v71
	v_cndmask_b32_e64 v71, 0, v153, s[4:5]
	v_cndmask_b32_e32 v78, 0, v153, vcc
	v_fmac_f32_e32 v75, 0xbfb8aa3b, v70
	v_fmac_f32_e32 v71, v72, v155
	v_fmac_f32_e32 v78, v73, v154
	v_exp_f32_e32 v75, v75
	v_exp_f32_e32 v79, v79
	v_exp_f32_e32 v71, v71
	v_exp_f32_e32 v72, v78
	v_cndmask_b32_e64 v74, 0, v152, s[4:5]
	s_cselect_b32 s4, 0xffffffc0, 0
	s_and_b64 s[2:3], s[2:3], exec
	v_cndmask_b32_e32 v70, 0, v152, vcc
	s_cselect_b32 s2, 0xffffffc0, 0
	v_ldexp_f32 v75, v75, s4
	v_ldexp_f32 v78, v79, s2
	v_ldexp_f32 v79, v71, v74
	v_ldexp_f32 v70, v72, v70
	v_mul_f32_e32 v80, v75, v79
	v_mul_f32_e32 v71, v78, v70
	v_mul_f32_e32 v72, v60, v79
	v_mul_f32_e32 v81, v60, v70
	v_mul_f32_e32 v82, v75, v80
	v_mul_f32_e32 v60, v78, v71
	v_mul_f32_e32 v83, v75, v82
	v_mul_f32_e32 v84, v78, v60
	v_mul_f32_e32 v85, v75, v83
	v_mul_f32_e32 v86, v78, v84
	v_mul_f32_e32 v73, v61, v80
	v_mul_f32_e32 v87, v75, v85
	v_mul_f32_e32 v88, v78, v86
	v_cvt_pk_bf16_f32 v72, v72, v73
	v_mul_f32_e32 v73, v62, v82
	v_mul_f32_e32 v74, v63, v83
	v_mul_f32_e32 v90, v75, v87
	v_mul_f32_e32 v91, v78, v88
	v_cvt_pk_bf16_f32 v73, v73, v74
	v_mul_f32_e32 v74, v56, v85
	v_mul_f32_e32 v89, v56, v86
	v_mul_f32_e32 v56, v57, v87
	v_mul_f32_e32 v93, v75, v90
	v_mul_f32_e32 v78, v78, v91
	v_mul_f32_e32 v92, v57, v88
	v_cvt_pk_bf16_f32 v74, v74, v56
	v_mul_f32_e32 v56, v58, v90
	v_mul_f32_e32 v57, v59, v93
	v_mul_f32_e32 v59, v59, v78
	v_cvt_pk_bf16_f32 v75, v56, v57
	v_mul_f32_e32 v61, v61, v71
	v_mul_f32_e32 v62, v62, v60
	v_mul_f32_e32 v63, v63, v84
	v_mul_f32_e32 v94, v58, v91
	v_cvt_pk_bf16_f32 v56, v81, v61
	v_cvt_pk_bf16_f32 v57, v62, v63
	v_cvt_pk_bf16_f32 v58, v89, v92
	v_cvt_pk_bf16_f32 v59, v94, v59
	global_store_dwordx4 v[76:77], v[72:75], off
	global_store_dwordx4 v[68:69], v[56:59], off
	s_nop 1
	v_mul_f32_e32 v56, v52, v79
	v_mul_f32_e32 v57, v53, v80
	v_cvt_pk_bf16_f32 v56, v56, v57
	v_mul_f32_e32 v57, v54, v82
	v_mul_f32_e32 v58, v55, v83
	v_cvt_pk_bf16_f32 v57, v57, v58
	v_mul_f32_e32 v58, v48, v85
	v_mul_f32_e32 v59, v49, v87
	v_cvt_pk_bf16_f32 v58, v58, v59
	v_mul_f32_e32 v59, v50, v90
	v_mul_f32_e32 v52, v52, v70
	v_mul_f32_e32 v53, v53, v71
	v_mul_f32_e32 v61, v51, v93
	v_cvt_pk_bf16_f32 v59, v59, v61
	v_cvt_pk_bf16_f32 v52, v52, v53
	v_mul_f32_e32 v53, v54, v60
	v_mul_f32_e32 v54, v55, v84
	v_mul_f32_e32 v48, v48, v86
	v_mul_f32_e32 v49, v49, v88
	v_cvt_pk_bf16_f32 v53, v53, v54
	v_cvt_pk_bf16_f32 v54, v48, v49
	v_mul_f32_e32 v48, v50, v91
	v_mul_f32_e32 v49, v51, v78
	v_cvt_pk_bf16_f32 v55, v48, v49
	global_store_dwordx4 v[64:65], v[56:59], off offset:256
	global_store_dwordx4 v[66:67], v[52:55], off offset:256
	v_mul_f32_e32 v48, v44, v79
	v_mul_f32_e32 v49, v45, v80
	v_cvt_pk_bf16_f32 v48, v48, v49
	v_mul_f32_e32 v49, v46, v82
	v_mul_f32_e32 v50, v47, v83
	v_cvt_pk_bf16_f32 v49, v49, v50
	v_mul_f32_e32 v50, v40, v85
	v_mul_f32_e32 v51, v41, v87
	v_cvt_pk_bf16_f32 v50, v50, v51
	v_mul_f32_e32 v51, v42, v90
	v_mul_f32_e32 v44, v44, v70
	v_mul_f32_e32 v45, v45, v71
	v_mul_f32_e32 v52, v43, v93
	v_cvt_pk_bf16_f32 v51, v51, v52
	v_cvt_pk_bf16_f32 v44, v44, v45
	v_mul_f32_e32 v45, v46, v60
	v_mul_f32_e32 v46, v47, v84
	v_mul_f32_e32 v40, v40, v86
	s_mov_b64 s[2:3], 0x240000
	v_cvt_pk_bf16_f32 v45, v45, v46
	v_mul_f32_e32 v41, v41, v88
	v_cvt_pk_bf16_f32 v46, v40, v41
	v_mul_f32_e32 v40, v42, v91
	v_lshl_add_u64 v[52:53], v[140:141], 0, s[2:3]
	s_mov_b32 s2, 0x240000
	v_mul_f32_e32 v41, v43, v78
	v_cvt_pk_bf16_f32 v47, v40, v41
	v_add_co_u32_e32 v40, vcc, s2, v140
	s_mov_b64 s[2:3], 0x640000
	s_nop 0
	v_addc_co_u32_e32 v41, vcc, 0, v141, vcc
	global_store_dwordx4 v[40:41], v[48:51], off
	s_nop 1
	v_lshl_add_u64 v[48:49], v[140:141], 0, s[2:3]
	s_mov_b32 s2, 0x640000
	v_add_co_u32_e32 v40, vcc, s2, v140
	s_nop 1
	v_addc_co_u32_e32 v41, vcc, 0, v141, vcc
	global_store_dwordx4 v[40:41], v[44:47], off
	v_mul_f32_e32 v40, v36, v79
	v_mul_f32_e32 v41, v37, v80
	v_cvt_pk_bf16_f32 v40, v40, v41
	v_mul_f32_e32 v41, v38, v82
	v_mul_f32_e32 v42, v39, v83
	v_cvt_pk_bf16_f32 v41, v41, v42
	v_mul_f32_e32 v42, v32, v85
	v_mul_f32_e32 v43, v33, v87
	v_cvt_pk_bf16_f32 v42, v42, v43
	v_mul_f32_e32 v43, v34, v90
	v_mul_f32_e32 v36, v36, v70
; #define PG8_WAIT_V(n) asm volatile("s_waitcnt vmcnt(" #n ")" ::: "memory")
; template <class Epi, class Sched>
; __device__ __forceinline__ void gemm_phase(LAS unsigned char* lds, const Gemm g, const Sched& S, const Epi& E) {
;     ...
;     PG8_WAIT_V(0);
;     if (wr == 0) PG8_BAR;
;     PG8_BAR;
;     __device__ __forceinline__ void operator()(const AccT& acc, const Unit& u, int wr, int wc, int fr, int fq) const {
;     ...
;                 for (int bj = 0; bj < 2; ++bj) {
;                     const int t0 = tb + bj * 128;
;                     float v[8];
; #pragma unroll
;                     for (int jj = 0; jj < 4; ++jj) { v[jj] = acc[ai][bj][m][0][jj]; v[4 + jj] = acc[ai][bj][m][1][jj]; }
;                     if constexpr (ROPE) {
;                         const int t = t0 & 2047;
; #pragma unroll
;                         for (int hf = 0; hf < 2; ++hf) {
;                             f32x4 cs, sn;
;                             if (m < 2) { const float c1 = ropeA[(t >> 6) * 16 + d], s1 = ropeA[1024 + (t >> 6) * 16 + d]; cs = (f32x4){c1, c1, c1, c1}; sn = (f32x4){s1, s1, s1, s1}; }
;                             else { const float* cb = ropeA + 2048 + (d - 16) * 64 + (t & 63) + 4 * hf; cs = *(const f32x4*)(cb); sn = *(const f32x4*)(cb + 1024); }
; #pragma unroll
;                             for (int jj = 0; jj < 4; ++jj) { const float pr = __shfl_xor(v[4 * hf + jj], 4); v[4 * hf + jj] = v[4 * hf + jj] * cs[jj] + sgn * pr * sn[jj]; }
;                             __builtin_amdgcn_sched_barrier(0);
;                         }
;                     }
;                     float zf[8], zb[8]; zf[0] = zf0; zb[0] = zb0;
; #pragma unroll
;                     for (int jj = 1; jj < 8; ++jj) { zf[jj] = zf[jj - 1] * zfs; zb[jj] = zb[jj - 1] * zbs; }
;                     u32x4 wf, wb;
;                     wf.x = cvt_pk_bf16(v[0] * zf[0], v[1] * zf[1]); wf.y = cvt_pk_bf16(v[2] * zf[2], v[3] * zf[3]); wf.z = cvt_pk_bf16(v[4] * zf[4], v[5] * zf[5]); wf.w = cvt_pk_bf16(v[6] * zf[6], v[7] * zf[7]);
;                     wb.x = cvt_pk_bf16(v[0] * zb[0], v[1] * zb[1]); wb.y = cvt_pk_bf16(v[2] * zb[2], v[3] * zb[3]); wb.z = cvt_pk_bf16(v[4] * zb[4], v[5] * zb[5]); wb.w = cvt_pk_bf16(v[6] * zb[6], v[7] * zb[7]);
;                     *(u32x4*)(KTZ + (size_t)r * NT + t0) = wf;
;                     *(u32x4*)(KTZ + (size_t)(256 + r) * NT + t0) = wb;
	v_mul_f32_e32 v37, v37, v71
	v_mul_f32_e32 v44, v35, v93
	v_cvt_pk_bf16_f32 v43, v43, v44
	v_cvt_pk_bf16_f32 v36, v36, v37
	v_mul_f32_e32 v37, v38, v60
	v_mul_f32_e32 v38, v39, v84
	v_mul_f32_e32 v32, v32, v86
	v_mul_f32_e32 v33, v33, v88
	v_cvt_pk_bf16_f32 v37, v37, v38
	v_cvt_pk_bf16_f32 v38, v32, v33
	v_mul_f32_e32 v32, v34, v91
	v_mul_f32_e32 v33, v35, v78
	v_cvt_pk_bf16_f32 v39, v32, v33
	global_store_dwordx4 v[52:53], v[40:43], off offset:256
	global_store_dwordx4 v[48:49], v[36:39], off offset:256
	v_mul_f32_e32 v32, v28, v79
	v_mul_f32_e32 v33, v29, v80
	v_cvt_pk_bf16_f32 v32, v32, v33
	v_mul_f32_e32 v33, v30, v82
	v_mul_f32_e32 v34, v31, v83
	v_cvt_pk_bf16_f32 v33, v33, v34
	v_mul_f32_e32 v34, v24, v85
	v_mul_f32_e32 v35, v25, v87
	v_cvt_pk_bf16_f32 v34, v34, v35
	v_mul_f32_e32 v35, v26, v90
	v_mul_f32_e32 v28, v28, v70
	v_mul_f32_e32 v29, v29, v71
	v_mul_f32_e32 v36, v27, v93
	v_cvt_pk_bf16_f32 v35, v35, v36
	v_cvt_pk_bf16_f32 v28, v28, v29
	v_mul_f32_e32 v29, v30, v60
	v_mul_f32_e32 v30, v31, v84
	v_mul_f32_e32 v24, v24, v86
	v_cvt_pk_bf16_f32 v29, v29, v30
	v_mul_f32_e32 v25, v25, v88
	v_cvt_pk_bf16_f32 v30, v24, v25
	v_mul_f32_e32 v24, v26, v91
	v_mul_f32_e32 v25, v27, v78
	v_cvt_pk_bf16_f32 v31, v24, v25
	v_add_co_u32_e32 v24, vcc, s52, v140
	s_mov_b64 s[2:3], 0x280000
	s_nop 0
	v_addc_co_u32_e32 v25, vcc, 0, v141, vcc
	global_store_dwordx4 v[24:25], v[32:35], off
	v_add_co_u32_e32 v24, vcc, s53, v140
	v_lshl_add_u64 v[36:37], v[140:141], 0, s[2:3]
	s_nop 0
	v_addc_co_u32_e32 v25, vcc, 0, v141, vcc
	v_lshl_add_u64 v[32:33], v[140:141], 0, s[8:9]
	global_store_dwordx4 v[24:25], v[28:31], off
	v_mul_f32_e32 v24, v20, v79
	v_mul_f32_e32 v25, v21, v80
	v_cvt_pk_bf16_f32 v24, v24, v25
	v_mul_f32_e32 v25, v22, v82
	v_mul_f32_e32 v26, v23, v83
	v_cvt_pk_bf16_f32 v25, v25, v26
	v_mul_f32_e32 v26, v16, v85
	v_mul_f32_e32 v27, v17, v87
	v_cvt_pk_bf16_f32 v26, v26, v27
	v_mul_f32_e32 v27, v18, v90
	v_mul_f32_e32 v20, v20, v70
	v_mul_f32_e32 v21, v21, v71
	v_mul_f32_e32 v28, v19, v93
	v_cvt_pk_bf16_f32 v27, v27, v28
	v_cvt_pk_bf16_f32 v20, v20, v21
	v_mul_f32_e32 v21, v22, v60
	v_mul_f32_e32 v22, v23, v84
	v_mul_f32_e32 v16, v16, v86
	v_mul_f32_e32 v17, v17, v88
	v_cvt_pk_bf16_f32 v21, v21, v22
	v_cvt_pk_bf16_f32 v22, v16, v17
	v_mul_f32_e32 v16, v18, v91
	v_mul_f32_e32 v17, v19, v78
	v_cvt_pk_bf16_f32 v23, v16, v17
	global_store_dwordx4 v[36:37], v[24:27], off offset:256
	global_store_dwordx4 v[32:33], v[20:23], off offset:256
	v_mul_f32_e32 v16, v12, v79
	v_mul_f32_e32 v17, v13, v80
	v_cvt_pk_bf16_f32 v16, v16, v17
	v_mul_f32_e32 v17, v14, v82
	v_mul_f32_e32 v18, v15, v83
	v_cvt_pk_bf16_f32 v17, v17, v18
	v_mul_f32_e32 v18, v8, v85
	v_mul_f32_e32 v19, v9, v87
	v_cvt_pk_bf16_f32 v18, v18, v19
	v_mul_f32_e32 v19, v10, v90
	v_mul_f32_e32 v12, v12, v70
	v_mul_f32_e32 v13, v13, v71
	v_mul_f32_e32 v20, v11, v93
	v_cvt_pk_bf16_f32 v19, v19, v20
	v_cvt_pk_bf16_f32 v12, v12, v13
	v_mul_f32_e32 v13, v14, v60
	v_mul_f32_e32 v14, v15, v84
	v_mul_f32_e32 v8, v8, v86
	v_cvt_pk_bf16_f32 v13, v13, v14
	v_mul_f32_e32 v9, v9, v88
	v_cvt_pk_bf16_f32 v14, v8, v9
	v_mul_f32_e32 v8, v10, v91
	v_mul_f32_e32 v9, v11, v78
	v_cvt_pk_bf16_f32 v15, v8, v9
	v_add_co_u32_e32 v8, vcc, s54, v140
	v_lshl_add_u64 v[20:21], v[140:141], 0, s[10:11]
	s_nop 0
	v_addc_co_u32_e32 v9, vcc, 0, v141, vcc
	global_store_dwordx4 v[8:9], v[16:19], off
	v_add_co_u32_e32 v8, vcc, s55, v140
	s_nop 0
	v_lshl_add_u64 v[16:17], v[140:141], 0, s[12:13]
	v_addc_co_u32_e32 v9, vcc, 0, v141, vcc
	global_store_dwordx4 v[8:9], v[12:15], off
	v_mul_f32_e32 v8, v4, v79
	v_mul_f32_e32 v9, v5, v80
	v_cvt_pk_bf16_f32 v8, v8, v9
	v_mul_f32_e32 v9, v6, v82
	v_mul_f32_e32 v10, v7, v83
	v_cvt_pk_bf16_f32 v9, v9, v10
	v_mul_f32_e32 v10, v0, v85
	v_mul_f32_e32 v11, v1, v87
	v_cvt_pk_bf16_f32 v10, v10, v11
	v_mul_f32_e32 v11, v2, v90
	v_mul_f32_e32 v4, v4, v70
	v_mul_f32_e32 v5, v5, v71
	v_mul_f32_e32 v12, v3, v93
	v_cvt_pk_bf16_f32 v11, v11, v12
	v_cvt_pk_bf16_f32 v4, v4, v5
	v_mul_f32_e32 v5, v6, v60
	v_mul_f32_e32 v6, v7, v84
	v_mul_f32_e32 v0, v0, v86
	v_mul_f32_e32 v1, v1, v88
	v_cvt_pk_bf16_f32 v5, v5, v6
	v_cvt_pk_bf16_f32 v6, v0, v1
	v_mul_f32_e32 v0, v2, v91
	v_mul_f32_e32 v1, v3, v78
	v_cvt_pk_bf16_f32 v7, v0, v1
	global_store_dwordx4 v[20:21], v[8:11], off offset:256
	global_store_dwordx4 v[16:17], v[4:7], off offset:256
	s_and_b64 vcc, exec, s[14:15]
	s_mov_b32 s56, s16
	s_mov_b64 s[4:5], s[22:23]
	s_mov_b64 s[2:3], s[20:21]
	s_cbranch_vccz .LBB0_686
	s_waitcnt vmcnt(0)
	s_cmpk_gt_u32 s27, 0xff
	s_cbranch_scc1 .LBB0_697
	s_barrier

; #define PG8_STAGE(bufoff, gbase, voff) do { _Pragma("unroll") for (int _i = 0; _i < 2; ++_i) \
;         __builtin_amdgcn_global_load_lds((const unsigned*)((const char*)(gbase) + (voff)[_i]), (LAS unsigned*)(lds + (bufoff) + ldsw + _i * 8192), 16, 0, 0); } while (0)
; #define PG8_LDA(dst, b, h) do { _Pragma("unroll") for (int m = 0; m < 4; ++m) _Pragma("unroll") for (int k = 0; k < 2; ++k) dst[m][k] = *(const LAS bf16x8*)(lds + PG8_SA(b, h) + aoff + m * 2048 + k * 1024); } while (0)
; #define PG8_LDB(dst, b, h) do { _Pragma("unroll") for (int n = 0; n < 2; ++n) _Pragma("unroll") for (int k = 0; k < 2; ++k) dst[n][k] = *(const LAS bf16x8*)(lds + PG8_SB(b, h) + boff + n * 2048 + k * 1024); } while (0)
; #define PG8_WAIT_V(n) asm volatile("s_waitcnt vmcnt(" #n ")" ::: "memory")
; #define PG8_WAIT_L(n) asm volatile("s_waitcnt lgkmcnt(" #n ")" ::: "memory")
; #define PG8_BAR __builtin_amdgcn_s_barrier()
; #define PG8_SCHED __builtin_amdgcn_sched_barrier(0)
; template <class Epi, class Sched>
; __device__ __forceinline__ void gemm_phase(LAS unsigned char* lds, const Gemm g, const Sched& S, const Epi& E) {
;     ...
;         const bool has_next = S.next(ui + 1, nxt);
;         const char* nA = has_next ? (const char*)g.A + (size_t)nxt.pm * tstep : cA; const char* nB = has_next ? (const char*)g.Bt + (size_t)nxt.pn * tstep : cB;
;         for (int t = 0; t < nt; t += 2) {
;             const bool last = (t == nt - 2);
;             const char* a1 = cA + (size_t)(t + 1) * kstep;
;             const char* a2 = last ? nA : cA + (size_t)(t + 2) * kstep; const char* b2 = last ? nB : cB + (size_t)(t + 2) * kstep;
;             const char* a3 = a2 + kstep; const char* b3 = b2 + kstep;
;             PG8_LDB(B0, 0, 0); PG8_SCHED; PG8_LDA(At, 0, 0); PG8_STAGE(PG8_SA(1, 1), a1 + hstep, voffA);
;             PG8_WAIT_L(8); PG8_BAR; PG8_WAIT_L(0); PG8_MMA(0, 0, At, B0); PG8_BAR; PG8_SCHED;
;             PG8_LDB(B1, 0, 1); PG8_STAGE(PG8_SB(0, 0), b2, voffB);
;             PG8_BAR; PG8_WAIT_L(0); PG8_MMA(0, 1, At, B1); PG8_BAR;
;             PG8_LDA(At, 0, 1); PG8_STAGE(PG8_SA(0, 0), a2, voffA);
;             PG8_BAR; PG8_WAIT_L(0); PG8_MMA(1, 0, At, B0); PG8_BAR; PG8_SCHED;
;             PG8_STAGE(PG8_SB(0, 1), b2 + hstep, voffB);
;             PG8_WAIT_V(6); PG8_BAR; PG8_MMA(1, 1, At, B1); PG8_BAR;
.LBB0_712:
	s_ashr_i32 s15, s14, 31
	v_cmp_lt_i64_e64 s[26:27], s[16:17], 64
	s_lshl_b64 s[16:17], s[14:15], 19
	s_add_u32 s16, s38, s16
	s_addc_u32 s17, s39, s17
	s_and_b64 s[18:19], s[26:27], exec
	s_cselect_b32 s15, s17, s23
	s_cselect_b32 s54, s16, s22
	s_ashr_i32 s13, s12, 31
	s_lshl_b64 s[18:19], s[12:13], 19
	s_add_u32 s18, s28, s18
	s_addc_u32 s19, s29, s19
	s_and_b64 s[26:27], s[26:27], exec
	s_cselect_b32 s13, s19, s25
	s_cselect_b32 s55, s18, s24
	s_add_u32 s22, s22, 0x40080
	s_addc_u32 s23, s23, 0
	s_add_u32 s56, s24, 0x100
	s_addc_u32 s57, s25, 0
	s_mov_b32 s58, -2
	s_waitcnt lgkmcnt(0)
	ds_read_b128 v[146:149], v143
	ds_read_b128 v[150:153], v143 offset:1024
	ds_read_b128 v[154:157], v143 offset:2048
	ds_read_b128 v[158:161], v143 offset:3072
	s_add_u32 s24, s22, 0xfffc0080
	s_addc_u32 s25, s23, -1
	s_cmp_eq_u32 s58, 12
	s_cselect_b32 s27, s15, s25
	s_cselect_b32 s26, s54, s24
	s_cselect_b32 s25, s13, s57
	s_cselect_b32 s24, s55, s56
	s_add_i32 m0, s21, 0xc000
	ds_read_b128 v[162:165], v144
	ds_read_b128 v[166:169], v144 offset:1024
	ds_read_b128 v[170:173], v144 offset:2048
	ds_read_b128 v[174:177], v144 offset:3072
	ds_read_b128 v[178:181], v144 offset:4096
	ds_read_b128 v[182:185], v144 offset:5120
	ds_read_b128 v[186:189], v144 offset:6144
	ds_read_b128 v[190:193], v144 offset:7168
	global_load_lds_dwordx4 v136, s[22:23]
	s_add_i32 m0, s21, 0xe000
	s_nop 0
	global_load_lds_dwordx4 v138, s[22:23]
	s_waitcnt lgkmcnt(8)
	s_waitcnt vmcnt(8)
	s_barrier
	s_waitcnt lgkmcnt(0)
	s_setprio 1
	s_waitcnt lgkmcnt(0)
	v_mfma_f32_16x16x32_bf16 v[124:127], v[146:149], v[162:165], 0
	v_mfma_f32_16x16x32_bf16 v[120:123], v[154:157], v[162:165], 0
	v_mfma_f32_16x16x32_bf16 v[116:119], v[146:149], v[170:173], 0
	v_mfma_f32_16x16x32_bf16 v[108:111], v[154:157], v[170:173], 0
	v_mfma_f32_16x16x32_bf16 v[100:103], v[146:149], v[178:181], 0
	v_mfma_f32_16x16x32_bf16 v[92:95], v[154:157], v[178:181], 0
	v_mfma_f32_16x16x32_bf16 v[84:87], v[146:149], v[186:189], 0
	v_mfma_f32_16x16x32_bf16 v[76:79], v[154:157], v[186:189], 0
	v_mfma_f32_16x16x32_bf16 v[124:127], v[150:153], v[166:169], v[124:127]
	v_mfma_f32_16x16x32_bf16 v[120:123], v[158:161], v[166:169], v[120:123]
	v_mfma_f32_16x16x32_bf16 v[116:119], v[150:153], v[174:177], v[116:119]
	v_mfma_f32_16x16x32_bf16 v[108:111], v[158:161], v[174:177], v[108:111]
	v_mfma_f32_16x16x32_bf16 v[100:103], v[150:153], v[182:185], v[100:103]
	v_mfma_f32_16x16x32_bf16 v[92:95], v[158:161], v[182:185], v[92:95]
	v_mfma_f32_16x16x32_bf16 v[84:87], v[150:153], v[190:193], v[84:87]
	v_mfma_f32_16x16x32_bf16 v[76:79], v[158:161], v[190:193], v[76:79]
	s_setprio 0
	s_barrier
	s_add_i32 s59, s46, s34
	s_mov_b32 m0, s59
	ds_read_b128 v[194:197], v145
	ds_read_b128 v[202:205], v145 offset:1024
	ds_read_b128 v[206:209], v145 offset:2048
	ds_read_b128 v[210:213], v145 offset:3072
	global_load_lds_dwordx4 v130, s[24:25]
	s_add_i32 m0, s59, 0x2000
	s_nop 0
	global_load_lds_dwordx4 v134, s[24:25]
	s_waitcnt vmcnt(8)
	s_barrier
	s_waitcnt lgkmcnt(0)
	s_setprio 1
	s_waitcnt lgkmcnt(0)
	v_mfma_f32_16x16x32_bf16 v[112:115], v[194:197], v[162:165], 0
	v_mfma_f32_16x16x32_bf16 v[104:107], v[206:209], v[162:165], 0
	v_mfma_f32_16x16x32_bf16 v[96:99], v[194:197], v[170:173], 0
	v_mfma_f32_16x16x32_bf16 v[88:91], v[206:209], v[170:173], 0
	v_mfma_f32_16x16x32_bf16 v[80:83], v[194:197], v[178:181], 0
	v_mfma_f32_16x16x32_bf16 v[72:75], v[206:209], v[178:181], 0
	v_mfma_f32_16x16x32_bf16 v[68:71], v[194:197], v[186:189], 0
	v_mfma_f32_16x16x32_bf16 v[64:67], v[206:209], v[186:189], 0
	v_mfma_f32_16x16x32_bf16 v[112:115], v[202:205], v[166:169], v[112:115]
	v_mfma_f32_16x16x32_bf16 v[104:107], v[210:213], v[166:169], v[104:107]
	v_mfma_f32_16x16x32_bf16 v[96:99], v[202:205], v[174:177], v[96:99]
	v_mfma_f32_16x16x32_bf16 v[88:91], v[210:213], v[174:177], v[88:91]
	v_mfma_f32_16x16x32_bf16 v[80:83], v[202:205], v[182:185], v[80:83]
	v_mfma_f32_16x16x32_bf16 v[72:75], v[210:213], v[182:185], v[72:75]
	v_mfma_f32_16x16x32_bf16 v[68:71], v[202:205], v[190:193], v[68:71]
	v_mfma_f32_16x16x32_bf16 v[64:67], v[210:213], v[190:193], v[64:67]
	s_setprio 0
	s_mov_b32 m0, s21
	v_lshl_add_u64 v[216:217], s[26:27], 0, v[128:129]
	s_barrier
	ds_read_b128 v[162:165], v144 offset:16384
	ds_read_b128 v[166:169], v144 offset:17408
	ds_read_b128 v[170:173], v144 offset:18432
	ds_read_b128 v[174:177], v144 offset:19456
	ds_read_b128 v[178:181], v144 offset:20480
	ds_read_b128 v[182:185], v144 offset:21504
	ds_read_b128 v[186:189], v144 offset:22528
	ds_read_b128 v[190:193], v144 offset:23552
	global_load_lds_dwordx4 v128, s[26:27]
	v_lshl_add_u64 v[218:219], s[26:27], 0, v[132:133]
	s_mov_b32 m0, s35
	s_nop 0
	global_load_lds_dwordx4 v132, s[26:27]
	s_barrier
	s_waitcnt lgkmcnt(0)
	s_setprio 1
	s_waitcnt lgkmcnt(0)
	v_mfma_f32_16x16x32_bf16 v[60:63], v[146:149], v[162:165], 0
	v_mfma_f32_16x16x32_bf16 v[56:59], v[154:157], v[162:165], 0
	v_mfma_f32_16x16x32_bf16 v[52:55], v[146:149], v[170:173], 0
	v_mfma_f32_16x16x32_bf16 v[44:47], v[154:157], v[170:173], 0
	v_mfma_f32_16x16x32_bf16 v[36:39], v[146:149], v[178:181], 0
	v_mfma_f32_16x16x32_bf16 v[28:31], v[154:157], v[178:181], 0
	v_mfma_f32_16x16x32_bf16 v[20:23], v[146:149], v[186:189], 0
	v_mfma_f32_16x16x32_bf16 v[12:15], v[154:157], v[186:189], 0
	v_mfma_f32_16x16x32_bf16 v[60:63], v[150:153], v[166:169], v[60:63]
	v_mfma_f32_16x16x32_bf16 v[56:59], v[158:161], v[166:169], v[56:59]
	v_mfma_f32_16x16x32_bf16 v[52:55], v[150:153], v[174:177], v[52:55]
	v_mfma_f32_16x16x32_bf16 v[44:47], v[158:161], v[174:177], v[44:47]
	v_mfma_f32_16x16x32_bf16 v[36:39], v[150:153], v[182:185], v[36:39]
	v_mfma_f32_16x16x32_bf16 v[28:31], v[158:161], v[182:185], v[28:31]
	v_mfma_f32_16x16x32_bf16 v[20:23], v[150:153], v[190:193], v[20:23]
	v_mfma_f32_16x16x32_bf16 v[12:15], v[158:161], v[190:193], v[12:15]
	s_setprio 0
	s_barrier
; #define PG8_STAGE(bufoff, gbase, voff) do { _Pragma("unroll") for (int _i = 0; _i < 2; ++_i) \
;         __builtin_amdgcn_global_load_lds((const unsigned*)((const char*)(gbase) + (voff)[_i]), (LAS unsigned*)(lds + (bufoff) + ldsw + _i * 8192), 16, 0, 0); } while (0)
; #define PG8_LDA(dst, b, h) do { _Pragma("unroll") for (int m = 0; m < 4; ++m) _Pragma("unroll") for (int k = 0; k < 2; ++k) dst[m][k] = *(const LAS bf16x8*)(lds + PG8_SA(b, h) + aoff + m * 2048 + k * 1024); } while (0)
; #define PG8_LDB(dst, b, h) do { _Pragma("unroll") for (int n = 0; n < 2; ++n) _Pragma("unroll") for (int k = 0; k < 2; ++k) dst[n][k] = *(const LAS bf16x8*)(lds + PG8_SB(b, h) + boff + n * 2048 + k * 1024); } while (0)
; #define PG8_MMA(ai, bj, At, Bt) do { __builtin_amdgcn_s_setprio(1); _Pragma("unroll") for (int m = 0; m < 4; ++m) _Pragma("unroll") for (int n = 0; n < 2; ++n) _Pragma("unroll") for (int k = 0; k < 2; ++k) \
;         acc[ai][bj][m][n] = __builtin_amdgcn_mfma_f32_16x16x32_bf16(Bt[n][k], At[m][k], acc[ai][bj][m][n], 0, 0, 0); __builtin_amdgcn_s_setprio(0); } while (0)
; #define PG8_WAIT_V(n) asm volatile("s_waitcnt vmcnt(" #n ")" ::: "memory")
; #define PG8_WAIT_L(n) asm volatile("s_waitcnt lgkmcnt(" #n ")" ::: "memory")
; #define PG8_BAR __builtin_amdgcn_s_barrier()
; #define PG8_SCHED __builtin_amdgcn_sched_barrier(0)
; template <class Epi, class Sched>
; __device__ __forceinline__ void gemm_phase(LAS unsigned char* lds, const Gemm g, const Sched& S, const Epi& E) {
;     ...
;             PG8_LDB(B1, 0, 1); PG8_STAGE(PG8_SB(0, 0), b2, voffB);
;             PG8_BAR; PG8_WAIT_L(0); PG8_MMA(0, 1, At, B1); PG8_BAR;
;             PG8_LDA(At, 0, 1); PG8_STAGE(PG8_SA(0, 0), a2, voffA);
;             PG8_BAR; PG8_WAIT_L(0); PG8_MMA(1, 0, At, B0); PG8_BAR; PG8_SCHED;
;             PG8_STAGE(PG8_SB(0, 1), b2 + hstep, voffB);
;             PG8_WAIT_V(6); PG8_BAR; PG8_MMA(1, 1, At, B1); PG8_BAR;
;             PG8_LDB(B0, 1, 0); PG8_SCHED; PG8_LDA(At, 1, 0); PG8_STAGE(PG8_SA(0, 1), a2 + hstep, voffA);
;             PG8_WAIT_L(8); PG8_BAR; PG8_WAIT_L(0); PG8_MMA(0, 0, At, B0); PG8_BAR; PG8_SCHED;
	s_add_u32 s60, s24, 0x40000
	s_addc_u32 s61, s25, 0
	s_add_i32 s59, s47, s34
	s_mov_b32 m0, s59
	s_nop 0
	global_load_lds_dwordx4 v130, s[60:61]
	s_add_i32 m0, s59, 0x2000
	s_nop 0
	global_load_lds_dwordx4 v134, s[60:61]
	s_add_u32 s26, s26, 0x40000
	s_addc_u32 s27, s27, 0
	s_mov_b32 m0, s36
	s_nop 0
	global_load_lds_dwordx4 v128, s[26:27]
	s_mov_b32 m0, s37
	s_nop 0
	global_load_lds_dwordx4 v132, s[26:27]
	s_waitcnt vmcnt(10)
	s_barrier
	s_setprio 1
	v_mfma_f32_16x16x32_bf16 v[48:51], v[194:197], v[162:165], 0
	v_mfma_f32_16x16x32_bf16 v[40:43], v[206:209], v[162:165], 0
	v_mfma_f32_16x16x32_bf16 v[32:35], v[194:197], v[170:173], 0
	v_mfma_f32_16x16x32_bf16 v[24:27], v[206:209], v[170:173], 0
	v_mfma_f32_16x16x32_bf16 v[16:19], v[194:197], v[178:181], 0
	v_mfma_f32_16x16x32_bf16 v[8:11], v[206:209], v[178:181], 0
	v_mfma_f32_16x16x32_bf16 v[4:7], v[194:197], v[186:189], 0
	v_mfma_f32_16x16x32_bf16 v[0:3], v[206:209], v[186:189], 0
	v_mfma_f32_16x16x32_bf16 v[48:51], v[202:205], v[166:169], v[48:51]
	v_mfma_f32_16x16x32_bf16 v[40:43], v[210:213], v[166:169], v[40:43]
	v_mfma_f32_16x16x32_bf16 v[32:35], v[202:205], v[174:177], v[32:35]
	v_mfma_f32_16x16x32_bf16 v[24:27], v[210:213], v[174:177], v[24:27]
	v_mfma_f32_16x16x32_bf16 v[16:19], v[202:205], v[182:185], v[16:19]
	v_mfma_f32_16x16x32_bf16 v[8:11], v[210:213], v[182:185], v[8:11]
	v_mfma_f32_16x16x32_bf16 v[4:7], v[202:205], v[190:193], v[4:7]
	v_mfma_f32_16x16x32_bf16 v[0:3], v[210:213], v[190:193], v[0:3]
	s_setprio 0
	s_add_i32 s59, 0, 0x18000
	v_add_u32_e32 v158, s59, v142
	s_barrier
	ds_read_b128 v[146:149], v158
	ds_read_b128 v[150:153], v158 offset:1024
	ds_read_b128 v[154:157], v158 offset:2048
	ds_read_b128 v[158:161], v158 offset:3072
	ds_read_b128 v[162:165], v144 offset:32768
	ds_read_b128 v[166:169], v144 offset:33792
	ds_read_b128 v[170:173], v144 offset:34816
	ds_read_b128 v[174:177], v144 offset:35840
	ds_read_b128 v[178:181], v144 offset:36864
	ds_read_b128 v[182:185], v144 offset:37888
	ds_read_b128 v[186:189], v144 offset:38912
	ds_read_b128 v[190:193], v144 offset:39936
	s_waitcnt lgkmcnt(8)
	s_waitcnt vmcnt(8)
	s_barrier
	s_waitcnt lgkmcnt(0)
	s_setprio 1
	s_waitcnt lgkmcnt(0)
	v_mfma_f32_16x16x32_bf16 v[124:127], v[146:149], v[162:165], v[124:127]
	v_mfma_f32_16x16x32_bf16 v[120:123], v[154:157], v[162:165], v[120:123]
	v_mfma_f32_16x16x32_bf16 v[116:119], v[146:149], v[170:173], v[116:119]
	v_mfma_f32_16x16x32_bf16 v[108:111], v[154:157], v[170:173], v[108:111]
	v_mfma_f32_16x16x32_bf16 v[100:103], v[146:149], v[178:181], v[100:103]
	v_mfma_f32_16x16x32_bf16 v[92:95], v[154:157], v[178:181], v[92:95]
	v_mfma_f32_16x16x32_bf16 v[84:87], v[146:149], v[186:189], v[84:87]
	v_mfma_f32_16x16x32_bf16 v[76:79], v[154:157], v[186:189], v[76:79]
	v_mfma_f32_16x16x32_bf16 v[124:127], v[150:153], v[166:169], v[124:127]
	v_mfma_f32_16x16x32_bf16 v[120:123], v[158:161], v[166:169], v[120:123]
	v_mfma_f32_16x16x32_bf16 v[116:119], v[150:153], v[174:177], v[116:119]
	v_mfma_f32_16x16x32_bf16 v[108:111], v[158:161], v[174:177], v[108:111]
	v_mfma_f32_16x16x32_bf16 v[100:103], v[150:153], v[182:185], v[100:103]
	v_mfma_f32_16x16x32_bf16 v[92:95], v[158:161], v[182:185], v[92:95]
	v_mfma_f32_16x16x32_bf16 v[84:87], v[150:153], v[190:193], v[84:87]
	v_mfma_f32_16x16x32_bf16 v[76:79], v[158:161], v[190:193], v[76:79]
	s_setprio 0
	s_barrier
	s_add_i32 s26, 0, 0x1c000
	s_add_i32 s27, s59, s34
	v_add_u32_e32 v210, s26, v142
	s_add_u32 s0, s24, 0x80
	s_addc_u32 s1, s25, 0
	s_mov_b32 m0, s27
	ds_read_b128 v[194:197], v210
	ds_read_b128 v[202:205], v210 offset:1024
	ds_read_b128 v[206:209], v210 offset:2048
	ds_read_b128 v[210:213], v210 offset:3072
	global_load_lds_dwordx4 v130, s[0:1]
	s_add_i32 m0, s27, 0x2000
	s_nop 0
	global_load_lds_dwordx4 v134, s[0:1]
	s_waitcnt vmcnt(8)
	s_barrier
	s_waitcnt lgkmcnt(0)
	s_setprio 1
	s_waitcnt lgkmcnt(0)
	v_mfma_f32_16x16x32_bf16 v[112:115], v[194:197], v[162:165], v[112:115]
	v_mfma_f32_16x16x32_bf16 v[104:107], v[206:209], v[162:165], v[104:107]
	v_mfma_f32_16x16x32_bf16 v[96:99], v[194:197], v[170:173], v[96:99]
	v_mfma_f32_16x16x32_bf16 v[88:91], v[206:209], v[170:173], v[88:91]
	v_mfma_f32_16x16x32_bf16 v[80:83], v[194:197], v[178:181], v[80:83]
	v_mfma_f32_16x16x32_bf16 v[72:75], v[206:209], v[178:181], v[72:75]
	v_mfma_f32_16x16x32_bf16 v[68:71], v[194:197], v[186:189], v[68:71]
	v_mfma_f32_16x16x32_bf16 v[64:67], v[206:209], v[186:189], v[64:67]
	v_mfma_f32_16x16x32_bf16 v[112:115], v[202:205], v[166:169], v[112:115]
	v_mfma_f32_16x16x32_bf16 v[104:107], v[210:213], v[166:169], v[104:107]
	v_mfma_f32_16x16x32_bf16 v[96:99], v[202:205], v[174:177], v[96:99]
	v_mfma_f32_16x16x32_bf16 v[88:91], v[210:213], v[174:177], v[88:91]
	v_mfma_f32_16x16x32_bf16 v[80:83], v[202:205], v[182:185], v[80:83]
	v_mfma_f32_16x16x32_bf16 v[72:75], v[210:213], v[182:185], v[72:75]
	v_mfma_f32_16x16x32_bf16 v[68:71], v[202:205], v[190:193], v[68:71]
	v_mfma_f32_16x16x32_bf16 v[64:67], v[210:213], v[190:193], v[64:67]
	s_setprio 0
	s_mov_b32 m0, s43
	s_mov_b64 s[0:1], 0x80
	v_lshl_add_u64 v[198:199], v[216:217], 0, s[0:1]
	s_barrier
	ds_read_b128 v[162:165], v144 offset:49152
	ds_read_b128 v[166:169], v144 offset:50176
	ds_read_b128 v[170:173], v144 offset:51200
	ds_read_b128 v[174:177], v144 offset:52224
	ds_read_b128 v[178:181], v144 offset:53248
	ds_read_b128 v[182:185], v144 offset:54272
	ds_read_b128 v[186:189], v144 offset:55296
	ds_read_b128 v[190:193], v144 offset:56320
	global_load_lds_dwordx4 v[198:199], off
	v_lshl_add_u64 v[198:199], v[218:219], 0, s[0:1]
	s_mov_b32 m0, s44
	s_nop 0
	global_load_lds_dwordx4 v[198:199], off
	s_barrier
; #define PG8_STAGE(bufoff, gbase, voff) do { _Pragma("unroll") for (int _i = 0; _i < 2; ++_i) \
;         __builtin_amdgcn_global_load_lds((const unsigned*)((const char*)(gbase) + (voff)[_i]), (LAS unsigned*)(lds + (bufoff) + ldsw + _i * 8192), 16, 0, 0); } while (0)
; #define PG8_LDA(dst, b, h) do { _Pragma("unroll") for (int m = 0; m < 4; ++m) _Pragma("unroll") for (int k = 0; k < 2; ++k) dst[m][k] = *(const LAS bf16x8*)(lds + PG8_SA(b, h) + aoff + m * 2048 + k * 1024); } while (0)
; #define PG8_WAIT_V(n) asm volatile("s_waitcnt vmcnt(" #n ")" ::: "memory")
; #define PG8_WAIT_L(n) asm volatile("s_waitcnt lgkmcnt(" #n ")" ::: "memory")
; template <class Epi, class Sched>
; __device__ __forceinline__ void gemm_phase(LAS unsigned char* lds, const Gemm g, const Sched& S, const Epi& E) {
;     ...
;         for (int t = 0; t < nt; t += 2) {
;             const bool last = (t == nt - 2);
;             const char* a1 = cA + (size_t)(t + 1) * kstep;
;             const char* a2 = last ? nA : cA + (size_t)(t + 2) * kstep; const char* b2 = last ? nB : cB + (size_t)(t + 2) * kstep;
;             const char* a3 = a2 + kstep; const char* b3 = b2 + kstep;
;             PG8_LDB(B0, 0, 0); PG8_SCHED; PG8_LDA(At, 0, 0); PG8_STAGE(PG8_SA(1, 1), a1 + hstep, voffA);
;             PG8_WAIT_L(8); PG8_BAR; PG8_WAIT_L(0); PG8_MMA(0, 0, At, B0); PG8_BAR; PG8_SCHED;
;             PG8_LDB(B1, 0, 1); PG8_STAGE(PG8_SB(0, 0), b2, voffB);
;             PG8_BAR; PG8_WAIT_L(0); PG8_MMA(0, 1, At, B1); PG8_BAR;
;             PG8_LDA(At, 0, 1); PG8_STAGE(PG8_SA(0, 0), a2, voffA);
;             PG8_BAR; PG8_WAIT_L(0); PG8_MMA(1, 0, At, B0); PG8_BAR; PG8_SCHED;
;             PG8_STAGE(PG8_SB(0, 1), b2 + hstep, voffB);
;             PG8_WAIT_V(6); PG8_BAR; PG8_MMA(1, 1, At, B1); PG8_BAR;
;             PG8_LDB(B0, 1, 0); PG8_SCHED; PG8_LDA(At, 1, 0); PG8_STAGE(PG8_SA(0, 1), a2 + hstep, voffA);
;             PG8_WAIT_L(8); PG8_BAR; PG8_WAIT_L(0); PG8_MMA(0, 0, At, B0); PG8_BAR; PG8_SCHED;
;             PG8_LDB(B1, 1, 1); PG8_STAGE(PG8_SB(1, 0), b3, voffB);
;             PG8_BAR; PG8_WAIT_L(0); PG8_MMA(0, 1, At, B1); PG8_BAR;
;             PG8_LDA(At, 1, 1); PG8_STAGE(PG8_SA(1, 0), a3, voffA);
;             PG8_BAR; PG8_WAIT_L(0); PG8_MMA(1, 0, At, B0); PG8_BAR; PG8_SCHED;
;             PG8_STAGE(PG8_SB(1, 1), b3 + hstep, voffB);
;             PG8_WAIT_V(6); PG8_BAR; PG8_MMA(1, 1, At, B1); PG8_BAR;
	s_waitcnt lgkmcnt(0)
	s_setprio 1
	s_waitcnt lgkmcnt(0)
	v_mfma_f32_16x16x32_bf16 v[60:63], v[146:149], v[162:165], v[60:63]
	v_mfma_f32_16x16x32_bf16 v[56:59], v[154:157], v[162:165], v[56:59]
	v_mfma_f32_16x16x32_bf16 v[52:55], v[146:149], v[170:173], v[52:55]
	v_mfma_f32_16x16x32_bf16 v[44:47], v[154:157], v[170:173], v[44:47]
	v_mfma_f32_16x16x32_bf16 v[36:39], v[146:149], v[178:181], v[36:39]
	v_mfma_f32_16x16x32_bf16 v[28:31], v[154:157], v[178:181], v[28:31]
	v_mfma_f32_16x16x32_bf16 v[20:23], v[146:149], v[186:189], v[20:23]
	v_mfma_f32_16x16x32_bf16 v[12:15], v[154:157], v[186:189], v[12:15]
	v_mfma_f32_16x16x32_bf16 v[60:63], v[150:153], v[166:169], v[60:63]
	v_mfma_f32_16x16x32_bf16 v[56:59], v[158:161], v[166:169], v[56:59]
	v_mfma_f32_16x16x32_bf16 v[52:55], v[150:153], v[174:177], v[52:55]
	v_mfma_f32_16x16x32_bf16 v[44:47], v[158:161], v[174:177], v[44:47]
	v_mfma_f32_16x16x32_bf16 v[36:39], v[150:153], v[182:185], v[36:39]
	v_mfma_f32_16x16x32_bf16 v[28:31], v[158:161], v[182:185], v[28:31]
	v_mfma_f32_16x16x32_bf16 v[20:23], v[150:153], v[190:193], v[20:23]
	v_mfma_f32_16x16x32_bf16 v[12:15], v[158:161], v[190:193], v[12:15]
	s_setprio 0
	s_barrier
	s_add_u32 s24, s24, 0x40080
	s_addc_u32 s25, s25, 0
	s_add_i32 s26, s26, s34
	s_mov_b32 m0, s26
	s_nop 0
	global_load_lds_dwordx4 v130, s[24:25]
	s_add_i32 m0, s26, 0x2000
	s_nop 0
	global_load_lds_dwordx4 v134, s[24:25]
	s_waitcnt vmcnt(8)
	s_barrier
	s_setprio 1
	v_mfma_f32_16x16x32_bf16 v[48:51], v[194:197], v[162:165], v[48:51]
	v_mfma_f32_16x16x32_bf16 v[40:43], v[206:209], v[162:165], v[40:43]
	v_mfma_f32_16x16x32_bf16 v[32:35], v[194:197], v[170:173], v[32:35]
	v_mfma_f32_16x16x32_bf16 v[24:27], v[206:209], v[170:173], v[24:27]
	v_mfma_f32_16x16x32_bf16 v[16:19], v[194:197], v[178:181], v[16:19]
	v_mfma_f32_16x16x32_bf16 v[8:11], v[206:209], v[178:181], v[8:11]
	v_mfma_f32_16x16x32_bf16 v[4:7], v[194:197], v[186:189], v[4:7]
	v_mfma_f32_16x16x32_bf16 v[0:3], v[206:209], v[186:189], v[0:3]
	v_mfma_f32_16x16x32_bf16 v[48:51], v[202:205], v[166:169], v[48:51]
	v_mfma_f32_16x16x32_bf16 v[40:43], v[210:213], v[166:169], v[40:43]
	v_mfma_f32_16x16x32_bf16 v[32:35], v[202:205], v[174:177], v[32:35]
	v_mfma_f32_16x16x32_bf16 v[24:27], v[210:213], v[174:177], v[24:27]
	v_mfma_f32_16x16x32_bf16 v[16:19], v[202:205], v[182:185], v[16:19]
	v_mfma_f32_16x16x32_bf16 v[8:11], v[210:213], v[182:185], v[8:11]
	v_mfma_f32_16x16x32_bf16 v[4:7], v[202:205], v[190:193], v[4:7]
	v_mfma_f32_16x16x32_bf16 v[0:3], v[210:213], v[190:193], v[0:3]
	s_setprio 0
	s_add_i32 s58, s58, 2
	s_add_u32 s22, s22, 0x100
	s_addc_u32 s23, s23, 0
	s_add_u32 s56, s56, 0x100
	s_addc_u32 s57, s57, 0
	s_cmp_gt_u32 s58, 13
	s_barrier
.LBB0_713:
	ds_read_b128 v[146:149], v143
	ds_read_b128 v[150:153], v143 offset:1024
	ds_read_b128 v[154:157], v143 offset:2048
	ds_read_b128 v[158:161], v143 offset:3072
	s_add_u32 s24, s22, 0xfffc0080
	s_addc_u32 s25, s23, -1
	s_cmp_eq_u32 s58, 12
	s_cselect_b32 s27, s15, s25
	s_cselect_b32 s26, s54, s24
	s_cselect_b32 s25, s13, s57
	s_cselect_b32 s24, s55, s56
	s_add_i32 m0, s21, 0xc000
	ds_read_b128 v[162:165], v144
	ds_read_b128 v[166:169], v144 offset:1024
	ds_read_b128 v[170:173], v144 offset:2048
	ds_read_b128 v[174:177], v144 offset:3072
	ds_read_b128 v[178:181], v144 offset:4096
	ds_read_b128 v[182:185], v144 offset:5120
	ds_read_b128 v[186:189], v144 offset:6144
	ds_read_b128 v[190:193], v144 offset:7168
	global_load_lds_dwordx4 v136, s[22:23]
	s_add_i32 m0, s21, 0xe000
	s_nop 0
	global_load_lds_dwordx4 v138, s[22:23]
	s_waitcnt lgkmcnt(8)
	s_waitcnt vmcnt(8)
	s_barrier
	s_waitcnt lgkmcnt(0)
	s_setprio 1
	s_waitcnt lgkmcnt(0)
	v_mfma_f32_16x16x32_bf16 v[124:127], v[146:149], v[162:165], v[124:127]
	v_mfma_f32_16x16x32_bf16 v[120:123], v[154:157], v[162:165], v[120:123]
	v_mfma_f32_16x16x32_bf16 v[116:119], v[146:149], v[170:173], v[116:119]
	v_mfma_f32_16x16x32_bf16 v[108:111], v[154:157], v[170:173], v[108:111]
	v_mfma_f32_16x16x32_bf16 v[100:103], v[146:149], v[178:181], v[100:103]
	v_mfma_f32_16x16x32_bf16 v[92:95], v[154:157], v[178:181], v[92:95]
	v_mfma_f32_16x16x32_bf16 v[84:87], v[146:149], v[186:189], v[84:87]
	v_mfma_f32_16x16x32_bf16 v[76:79], v[154:157], v[186:189], v[76:79]
	v_mfma_f32_16x16x32_bf16 v[124:127], v[150:153], v[166:169], v[124:127]
	v_mfma_f32_16x16x32_bf16 v[120:123], v[158:161], v[166:169], v[120:123]
	v_mfma_f32_16x16x32_bf16 v[116:119], v[150:153], v[174:177], v[116:119]
	v_mfma_f32_16x16x32_bf16 v[108:111], v[158:161], v[174:177], v[108:111]
	v_mfma_f32_16x16x32_bf16 v[100:103], v[150:153], v[182:185], v[100:103]
	v_mfma_f32_16x16x32_bf16 v[92:95], v[158:161], v[182:185], v[92:95]
	v_mfma_f32_16x16x32_bf16 v[84:87], v[150:153], v[190:193], v[84:87]
	v_mfma_f32_16x16x32_bf16 v[76:79], v[158:161], v[190:193], v[76:79]
	s_setprio 0
	s_barrier
	s_add_i32 s59, s46, s34
	s_mov_b32 m0, s59
	ds_read_b128 v[194:197], v145
	ds_read_b128 v[202:205], v145 offset:1024
	ds_read_b128 v[206:209], v145 offset:2048
	ds_read_b128 v[210:213], v145 offset:3072
	global_load_lds_dwordx4 v130, s[24:25]
	s_add_i32 m0, s59, 0x2000
	s_nop 0
	global_load_lds_dwordx4 v134, s[24:25]
	s_waitcnt vmcnt(8)
	s_barrier
; #define PG8_STAGE(bufoff, gbase, voff) do { _Pragma("unroll") for (int _i = 0; _i < 2; ++_i) \
;         __builtin_amdgcn_global_load_lds((const unsigned*)((const char*)(gbase) + (voff)[_i]), (LAS unsigned*)(lds + (bufoff) + ldsw + _i * 8192), 16, 0, 0); } while (0)
; #define PG8_LDA(dst, b, h) do { _Pragma("unroll") for (int m = 0; m < 4; ++m) _Pragma("unroll") for (int k = 0; k < 2; ++k) dst[m][k] = *(const LAS bf16x8*)(lds + PG8_SA(b, h) + aoff + m * 2048 + k * 1024); } while (0)
; #define PG8_LDB(dst, b, h) do { _Pragma("unroll") for (int n = 0; n < 2; ++n) _Pragma("unroll") for (int k = 0; k < 2; ++k) dst[n][k] = *(const LAS bf16x8*)(lds + PG8_SB(b, h) + boff + n * 2048 + k * 1024); } while (0)
; #define PG8_MMA(ai, bj, At, Bt) do { __builtin_amdgcn_s_setprio(1); _Pragma("unroll") for (int m = 0; m < 4; ++m) _Pragma("unroll") for (int n = 0; n < 2; ++n) _Pragma("unroll") for (int k = 0; k < 2; ++k) \
;         acc[ai][bj][m][n] = __builtin_amdgcn_mfma_f32_16x16x32_bf16(Bt[n][k], At[m][k], acc[ai][bj][m][n], 0, 0, 0); __builtin_amdgcn_s_setprio(0); } while (0)
; #define PG8_WAIT_V(n) asm volatile("s_waitcnt vmcnt(" #n ")" ::: "memory")
; #define PG8_WAIT_L(n) asm volatile("s_waitcnt lgkmcnt(" #n ")" ::: "memory")
; #define PG8_BAR __builtin_amdgcn_s_barrier()
; #define PG8_SCHED __builtin_amdgcn_sched_barrier(0)
; template <class Epi, class Sched>
; __device__ __forceinline__ void gemm_phase(LAS unsigned char* lds, const Gemm g, const Sched& S, const Epi& E) {
;     ...
;             PG8_LDB(B1, 0, 1); PG8_STAGE(PG8_SB(0, 0), b2, voffB);
;             PG8_BAR; PG8_WAIT_L(0); PG8_MMA(0, 1, At, B1); PG8_BAR;
;             PG8_LDA(At, 0, 1); PG8_STAGE(PG8_SA(0, 0), a2, voffA);
;             PG8_BAR; PG8_WAIT_L(0); PG8_MMA(1, 0, At, B0); PG8_BAR; PG8_SCHED;
;             PG8_STAGE(PG8_SB(0, 1), b2 + hstep, voffB);
;             PG8_WAIT_V(6); PG8_BAR; PG8_MMA(1, 1, At, B1); PG8_BAR;
;             PG8_LDB(B0, 1, 0); PG8_SCHED; PG8_LDA(At, 1, 0); PG8_STAGE(PG8_SA(0, 1), a2 + hstep, voffA);
;             PG8_WAIT_L(8); PG8_BAR; PG8_WAIT_L(0); PG8_MMA(0, 0, At, B0); PG8_BAR; PG8_SCHED;
	s_waitcnt lgkmcnt(0)
	s_setprio 1
	s_waitcnt lgkmcnt(0)
	v_mfma_f32_16x16x32_bf16 v[112:115], v[194:197], v[162:165], v[112:115]
	v_mfma_f32_16x16x32_bf16 v[104:107], v[206:209], v[162:165], v[104:107]
	v_mfma_f32_16x16x32_bf16 v[96:99], v[194:197], v[170:173], v[96:99]
	v_mfma_f32_16x16x32_bf16 v[88:91], v[206:209], v[170:173], v[88:91]
	v_mfma_f32_16x16x32_bf16 v[80:83], v[194:197], v[178:181], v[80:83]
	v_mfma_f32_16x16x32_bf16 v[72:75], v[206:209], v[178:181], v[72:75]
	v_mfma_f32_16x16x32_bf16 v[68:71], v[194:197], v[186:189], v[68:71]
	v_mfma_f32_16x16x32_bf16 v[64:67], v[206:209], v[186:189], v[64:67]
	v_mfma_f32_16x16x32_bf16 v[112:115], v[202:205], v[166:169], v[112:115]
	v_mfma_f32_16x16x32_bf16 v[104:107], v[210:213], v[166:169], v[104:107]
	v_mfma_f32_16x16x32_bf16 v[96:99], v[202:205], v[174:177], v[96:99]
	v_mfma_f32_16x16x32_bf16 v[88:91], v[210:213], v[174:177], v[88:91]
	v_mfma_f32_16x16x32_bf16 v[80:83], v[202:205], v[182:185], v[80:83]
	v_mfma_f32_16x16x32_bf16 v[72:75], v[210:213], v[182:185], v[72:75]
	v_mfma_f32_16x16x32_bf16 v[68:71], v[202:205], v[190:193], v[68:71]
	v_mfma_f32_16x16x32_bf16 v[64:67], v[210:213], v[190:193], v[64:67]
	s_setprio 0
	s_mov_b32 m0, s21
	v_lshl_add_u64 v[216:217], s[26:27], 0, v[128:129]
	s_barrier
	ds_read_b128 v[162:165], v144 offset:16384
	ds_read_b128 v[166:169], v144 offset:17408
	ds_read_b128 v[170:173], v144 offset:18432
	ds_read_b128 v[174:177], v144 offset:19456
	ds_read_b128 v[178:181], v144 offset:20480
	ds_read_b128 v[182:185], v144 offset:21504
	ds_read_b128 v[186:189], v144 offset:22528
	ds_read_b128 v[190:193], v144 offset:23552
	global_load_lds_dwordx4 v128, s[26:27]
	v_lshl_add_u64 v[218:219], s[26:27], 0, v[132:133]
	s_mov_b32 m0, s35
	s_nop 0
	global_load_lds_dwordx4 v132, s[26:27]
	s_barrier
	s_waitcnt lgkmcnt(0)
	s_setprio 1
	s_waitcnt lgkmcnt(0)
	v_mfma_f32_16x16x32_bf16 v[60:63], v[146:149], v[162:165], v[60:63]
	v_mfma_f32_16x16x32_bf16 v[56:59], v[154:157], v[162:165], v[56:59]
	v_mfma_f32_16x16x32_bf16 v[52:55], v[146:149], v[170:173], v[52:55]
	v_mfma_f32_16x16x32_bf16 v[44:47], v[154:157], v[170:173], v[44:47]
	v_mfma_f32_16x16x32_bf16 v[36:39], v[146:149], v[178:181], v[36:39]
	v_mfma_f32_16x16x32_bf16 v[28:31], v[154:157], v[178:181], v[28:31]
	v_mfma_f32_16x16x32_bf16 v[20:23], v[146:149], v[186:189], v[20:23]
	v_mfma_f32_16x16x32_bf16 v[12:15], v[154:157], v[186:189], v[12:15]
	v_mfma_f32_16x16x32_bf16 v[60:63], v[150:153], v[166:169], v[60:63]
	v_mfma_f32_16x16x32_bf16 v[56:59], v[158:161], v[166:169], v[56:59]
	v_mfma_f32_16x16x32_bf16 v[52:55], v[150:153], v[174:177], v[52:55]
	v_mfma_f32_16x16x32_bf16 v[44:47], v[158:161], v[174:177], v[44:47]
	v_mfma_f32_16x16x32_bf16 v[36:39], v[150:153], v[182:185], v[36:39]
	v_mfma_f32_16x16x32_bf16 v[28:31], v[158:161], v[182:185], v[28:31]
	v_mfma_f32_16x16x32_bf16 v[20:23], v[150:153], v[190:193], v[20:23]
	v_mfma_f32_16x16x32_bf16 v[12:15], v[158:161], v[190:193], v[12:15]
	s_setprio 0
	s_barrier
	s_add_u32 s60, s24, 0x40000
	s_addc_u32 s61, s25, 0
	s_add_i32 s59, s47, s34
	s_mov_b32 m0, s59
	s_nop 0
	global_load_lds_dwordx4 v130, s[60:61]
	s_add_i32 m0, s59, 0x2000
	s_nop 0
	global_load_lds_dwordx4 v134, s[60:61]
	s_add_u32 s26, s26, 0x40000
	s_addc_u32 s27, s27, 0
	s_mov_b32 m0, s36
	s_nop 0
	global_load_lds_dwordx4 v128, s[26:27]
	s_mov_b32 m0, s37
	s_nop 0
	global_load_lds_dwordx4 v132, s[26:27]
	s_waitcnt vmcnt(10)
	s_barrier
	s_setprio 1
	v_mfma_f32_16x16x32_bf16 v[48:51], v[194:197], v[162:165], v[48:51]
	v_mfma_f32_16x16x32_bf16 v[40:43], v[206:209], v[162:165], v[40:43]
	v_mfma_f32_16x16x32_bf16 v[32:35], v[194:197], v[170:173], v[32:35]
	v_mfma_f32_16x16x32_bf16 v[24:27], v[206:209], v[170:173], v[24:27]
	v_mfma_f32_16x16x32_bf16 v[16:19], v[194:197], v[178:181], v[16:19]
	v_mfma_f32_16x16x32_bf16 v[8:11], v[206:209], v[178:181], v[8:11]
	v_mfma_f32_16x16x32_bf16 v[4:7], v[194:197], v[186:189], v[4:7]
	v_mfma_f32_16x16x32_bf16 v[0:3], v[206:209], v[186:189], v[0:3]
	v_mfma_f32_16x16x32_bf16 v[48:51], v[202:205], v[166:169], v[48:51]
	v_mfma_f32_16x16x32_bf16 v[40:43], v[210:213], v[166:169], v[40:43]
	v_mfma_f32_16x16x32_bf16 v[32:35], v[202:205], v[174:177], v[32:35]
	v_mfma_f32_16x16x32_bf16 v[24:27], v[210:213], v[174:177], v[24:27]
	v_mfma_f32_16x16x32_bf16 v[16:19], v[202:205], v[182:185], v[16:19]
	v_mfma_f32_16x16x32_bf16 v[8:11], v[210:213], v[182:185], v[8:11]
	v_mfma_f32_16x16x32_bf16 v[4:7], v[202:205], v[190:193], v[4:7]
	v_mfma_f32_16x16x32_bf16 v[0:3], v[210:213], v[190:193], v[0:3]
	s_setprio 0
	s_add_i32 s59, 0, 0x18000
	v_add_u32_e32 v158, s59, v142
	s_barrier
	ds_read_b128 v[146:149], v158
	ds_read_b128 v[150:153], v158 offset:1024
	ds_read_b128 v[154:157], v158 offset:2048
	ds_read_b128 v[158:161], v158 offset:3072
	ds_read_b128 v[162:165], v144 offset:32768
	ds_read_b128 v[166:169], v144 offset:33792
	ds_read_b128 v[170:173], v144 offset:34816
	ds_read_b128 v[174:177], v144 offset:35840
	ds_read_b128 v[178:181], v144 offset:36864
	ds_read_b128 v[182:185], v144 offset:37888
	ds_read_b128 v[186:189], v144 offset:38912
	ds_read_b128 v[190:193], v144 offset:39936
	s_waitcnt lgkmcnt(8)
	s_waitcnt vmcnt(8)
	s_barrier
; #define PG8_STAGE(bufoff, gbase, voff) do { _Pragma("unroll") for (int _i = 0; _i < 2; ++_i) \
;         __builtin_amdgcn_global_load_lds((const unsigned*)((const char*)(gbase) + (voff)[_i]), (LAS unsigned*)(lds + (bufoff) + ldsw + _i * 8192), 16, 0, 0); } while (0)
; #define PG8_LDA(dst, b, h) do { _Pragma("unroll") for (int m = 0; m < 4; ++m) _Pragma("unroll") for (int k = 0; k < 2; ++k) dst[m][k] = *(const LAS bf16x8*)(lds + PG8_SA(b, h) + aoff + m * 2048 + k * 1024); } while (0)
; #define PG8_LDB(dst, b, h) do { _Pragma("unroll") for (int n = 0; n < 2; ++n) _Pragma("unroll") for (int k = 0; k < 2; ++k) dst[n][k] = *(const LAS bf16x8*)(lds + PG8_SB(b, h) + boff + n * 2048 + k * 1024); } while (0)
; #define PG8_MMA(ai, bj, At, Bt) do { __builtin_amdgcn_s_setprio(1); _Pragma("unroll") for (int m = 0; m < 4; ++m) _Pragma("unroll") for (int n = 0; n < 2; ++n) _Pragma("unroll") for (int k = 0; k < 2; ++k) \
;         acc[ai][bj][m][n] = __builtin_amdgcn_mfma_f32_16x16x32_bf16(Bt[n][k], At[m][k], acc[ai][bj][m][n], 0, 0, 0); __builtin_amdgcn_s_setprio(0); } while (0)
; #define PG8_WAIT_V(n) asm volatile("s_waitcnt vmcnt(" #n ")" ::: "memory")
; #define PG8_WAIT_L(n) asm volatile("s_waitcnt lgkmcnt(" #n ")" ::: "memory")
; #define PG8_BAR __builtin_amdgcn_s_barrier()
; #define PG8_SCHED __builtin_amdgcn_sched_barrier(0)
; template <class Epi, class Sched>
; __device__ __forceinline__ void gemm_phase(LAS unsigned char* lds, const Gemm g, const Sched& S, const Epi& E) {
;     ...
;             PG8_LDB(B0, 1, 0); PG8_SCHED; PG8_LDA(At, 1, 0); PG8_STAGE(PG8_SA(0, 1), a2 + hstep, voffA);
;             PG8_WAIT_L(8); PG8_BAR; PG8_WAIT_L(0); PG8_MMA(0, 0, At, B0); PG8_BAR; PG8_SCHED;
;             PG8_LDB(B1, 1, 1); PG8_STAGE(PG8_SB(1, 0), b3, voffB);
;             PG8_BAR; PG8_WAIT_L(0); PG8_MMA(0, 1, At, B1); PG8_BAR;
;             PG8_LDA(At, 1, 1); PG8_STAGE(PG8_SA(1, 0), a3, voffA);
;             PG8_BAR; PG8_WAIT_L(0); PG8_MMA(1, 0, At, B0); PG8_BAR; PG8_SCHED;
;             PG8_STAGE(PG8_SB(1, 1), b3 + hstep, voffB);
;             PG8_WAIT_V(6); PG8_BAR; PG8_MMA(1, 1, At, B1); PG8_BAR;
	s_waitcnt lgkmcnt(0)
	s_setprio 1
	s_waitcnt lgkmcnt(0)
	v_mfma_f32_16x16x32_bf16 v[124:127], v[146:149], v[162:165], v[124:127]
	v_mfma_f32_16x16x32_bf16 v[120:123], v[154:157], v[162:165], v[120:123]
	v_mfma_f32_16x16x32_bf16 v[116:119], v[146:149], v[170:173], v[116:119]
	v_mfma_f32_16x16x32_bf16 v[108:111], v[154:157], v[170:173], v[108:111]
	v_mfma_f32_16x16x32_bf16 v[100:103], v[146:149], v[178:181], v[100:103]
	v_mfma_f32_16x16x32_bf16 v[92:95], v[154:157], v[178:181], v[92:95]
	v_mfma_f32_16x16x32_bf16 v[84:87], v[146:149], v[186:189], v[84:87]
	v_mfma_f32_16x16x32_bf16 v[76:79], v[154:157], v[186:189], v[76:79]
	v_mfma_f32_16x16x32_bf16 v[124:127], v[150:153], v[166:169], v[124:127]
	v_mfma_f32_16x16x32_bf16 v[120:123], v[158:161], v[166:169], v[120:123]
	v_mfma_f32_16x16x32_bf16 v[116:119], v[150:153], v[174:177], v[116:119]
	v_mfma_f32_16x16x32_bf16 v[108:111], v[158:161], v[174:177], v[108:111]
	v_mfma_f32_16x16x32_bf16 v[100:103], v[150:153], v[182:185], v[100:103]
	v_mfma_f32_16x16x32_bf16 v[92:95], v[158:161], v[182:185], v[92:95]
	v_mfma_f32_16x16x32_bf16 v[84:87], v[150:153], v[190:193], v[84:87]
	v_mfma_f32_16x16x32_bf16 v[76:79], v[158:161], v[190:193], v[76:79]
	s_setprio 0
	s_barrier
	s_add_i32 s26, 0, 0x1c000
	s_add_i32 s27, s59, s34
	v_add_u32_e32 v210, s26, v142
	s_add_u32 s0, s24, 0x80
	s_addc_u32 s1, s25, 0
	s_mov_b32 m0, s27
	ds_read_b128 v[194:197], v210
	ds_read_b128 v[202:205], v210 offset:1024
	ds_read_b128 v[206:209], v210 offset:2048
	ds_read_b128 v[210:213], v210 offset:3072
	global_load_lds_dwordx4 v130, s[0:1]
	s_add_i32 m0, s27, 0x2000
	s_nop 0
	global_load_lds_dwordx4 v134, s[0:1]
	s_waitcnt vmcnt(8)
	s_barrier
	s_waitcnt lgkmcnt(0)
	s_setprio 1
	s_waitcnt lgkmcnt(0)
	v_mfma_f32_16x16x32_bf16 v[112:115], v[194:197], v[162:165], v[112:115]
	v_mfma_f32_16x16x32_bf16 v[104:107], v[206:209], v[162:165], v[104:107]
	v_mfma_f32_16x16x32_bf16 v[96:99], v[194:197], v[170:173], v[96:99]
	v_mfma_f32_16x16x32_bf16 v[88:91], v[206:209], v[170:173], v[88:91]
	v_mfma_f32_16x16x32_bf16 v[80:83], v[194:197], v[178:181], v[80:83]
	v_mfma_f32_16x16x32_bf16 v[72:75], v[206:209], v[178:181], v[72:75]
	v_mfma_f32_16x16x32_bf16 v[68:71], v[194:197], v[186:189], v[68:71]
	v_mfma_f32_16x16x32_bf16 v[64:67], v[206:209], v[186:189], v[64:67]
	v_mfma_f32_16x16x32_bf16 v[112:115], v[202:205], v[166:169], v[112:115]
	v_mfma_f32_16x16x32_bf16 v[104:107], v[210:213], v[166:169], v[104:107]
	v_mfma_f32_16x16x32_bf16 v[96:99], v[202:205], v[174:177], v[96:99]
	v_mfma_f32_16x16x32_bf16 v[88:91], v[210:213], v[174:177], v[88:91]
	v_mfma_f32_16x16x32_bf16 v[80:83], v[202:205], v[182:185], v[80:83]
	v_mfma_f32_16x16x32_bf16 v[72:75], v[210:213], v[182:185], v[72:75]
	v_mfma_f32_16x16x32_bf16 v[68:71], v[202:205], v[190:193], v[68:71]
	v_mfma_f32_16x16x32_bf16 v[64:67], v[210:213], v[190:193], v[64:67]
	s_setprio 0
	s_mov_b32 m0, s43
	s_mov_b64 s[0:1], 0x80
	v_lshl_add_u64 v[198:199], v[216:217], 0, s[0:1]
	s_barrier
	ds_read_b128 v[162:165], v144 offset:49152
	ds_read_b128 v[166:169], v144 offset:50176
	ds_read_b128 v[170:173], v144 offset:51200
	ds_read_b128 v[174:177], v144 offset:52224
	ds_read_b128 v[178:181], v144 offset:53248
	ds_read_b128 v[182:185], v144 offset:54272
	ds_read_b128 v[186:189], v144 offset:55296
	ds_read_b128 v[190:193], v144 offset:56320
	global_load_lds_dwordx4 v[198:199], off
	v_lshl_add_u64 v[198:199], v[218:219], 0, s[0:1]
	s_mov_b32 m0, s44
	s_nop 0
	global_load_lds_dwordx4 v[198:199], off
	s_barrier
	s_waitcnt lgkmcnt(0)
	s_setprio 1
	s_waitcnt lgkmcnt(0)
	v_mfma_f32_16x16x32_bf16 v[60:63], v[146:149], v[162:165], v[60:63]
	v_mfma_f32_16x16x32_bf16 v[56:59], v[154:157], v[162:165], v[56:59]
	v_mfma_f32_16x16x32_bf16 v[52:55], v[146:149], v[170:173], v[52:55]
	v_mfma_f32_16x16x32_bf16 v[44:47], v[154:157], v[170:173], v[44:47]
	v_mfma_f32_16x16x32_bf16 v[36:39], v[146:149], v[178:181], v[36:39]
	v_mfma_f32_16x16x32_bf16 v[28:31], v[154:157], v[178:181], v[28:31]
	v_mfma_f32_16x16x32_bf16 v[20:23], v[146:149], v[186:189], v[20:23]
	v_mfma_f32_16x16x32_bf16 v[12:15], v[154:157], v[186:189], v[12:15]
	v_mfma_f32_16x16x32_bf16 v[60:63], v[150:153], v[166:169], v[60:63]
	v_mfma_f32_16x16x32_bf16 v[56:59], v[158:161], v[166:169], v[56:59]
	v_mfma_f32_16x16x32_bf16 v[52:55], v[150:153], v[174:177], v[52:55]
	v_mfma_f32_16x16x32_bf16 v[44:47], v[158:161], v[174:177], v[44:47]
	v_mfma_f32_16x16x32_bf16 v[36:39], v[150:153], v[182:185], v[36:39]
	v_mfma_f32_16x16x32_bf16 v[28:31], v[158:161], v[182:185], v[28:31]
	v_mfma_f32_16x16x32_bf16 v[20:23], v[150:153], v[190:193], v[20:23]
	v_mfma_f32_16x16x32_bf16 v[12:15], v[158:161], v[190:193], v[12:15]
	s_setprio 0
	s_barrier
	s_add_u32 s24, s24, 0x40080
	s_addc_u32 s25, s25, 0
	s_add_i32 s26, s26, s34
	s_mov_b32 m0, s26
	s_nop 0
	global_load_lds_dwordx4 v130, s[24:25]
	s_add_i32 m0, s26, 0x2000
	s_nop 0
	global_load_lds_dwordx4 v134, s[24:25]
	s_waitcnt vmcnt(8)
	s_barrier
; __device__ __forceinline__ unsigned cvt_pk_bf16(float lo, float hi) { unsigned r; asm volatile("v_cvt_pk_bf16_f32 %0, %1, %2" : "=v"(r) : "v"(lo), "v"(hi)); return r; }
;     __device__ __forceinline__ void operator()(const AccT& acc, const Unit& u, int wr, int wc, int fr, int fq) const {
;     ...
;         const int rbase = u.pm * 256 + wr * 64 + fr;
;         const int tb = u.pn * 256 + wc * 32 + 8 * fq;
; #pragma unroll
;         for (int ai = 0; ai < 2; ++ai)
; #pragma unroll
;             for (int m = 0; m < 4; ++m) {
;                 const int r = rbase + ai * 128 + m * 16;
; #pragma unroll
;                 for (int bj = 0; bj < 2; ++bj) {
;                     const int t0 = tb + bj * 128;
;                     const f32x4 v0 = acc[ai][bj][m][0], v1 = acc[ai][bj][m][1];
;                     u32x4 w; w.x = cvt_pk_bf16(v0[0], v0[1]); w.y = cvt_pk_bf16(v0[2], v0[3]); w.z = cvt_pk_bf16(v1[0], v1[1]); w.w = cvt_pk_bf16(v1[2], v1[3]);
;                     *(u32x4*)(VT + (size_t)r * NT + t0) = w;
;                 }
	s_setprio 1
	v_mfma_f32_16x16x32_bf16 v[48:51], v[194:197], v[162:165], v[48:51]
	v_mfma_f32_16x16x32_bf16 v[40:43], v[206:209], v[162:165], v[40:43]
	v_mfma_f32_16x16x32_bf16 v[32:35], v[194:197], v[170:173], v[32:35]
	v_mfma_f32_16x16x32_bf16 v[24:27], v[206:209], v[170:173], v[24:27]
	v_mfma_f32_16x16x32_bf16 v[16:19], v[194:197], v[178:181], v[16:19]
	v_mfma_f32_16x16x32_bf16 v[8:11], v[206:209], v[178:181], v[8:11]
	v_mfma_f32_16x16x32_bf16 v[4:7], v[194:197], v[186:189], v[4:7]
	v_mfma_f32_16x16x32_bf16 v[0:3], v[206:209], v[186:189], v[0:3]
	v_mfma_f32_16x16x32_bf16 v[48:51], v[202:205], v[166:169], v[48:51]
	v_mfma_f32_16x16x32_bf16 v[40:43], v[210:213], v[166:169], v[40:43]
	v_mfma_f32_16x16x32_bf16 v[32:35], v[202:205], v[174:177], v[32:35]
	v_mfma_f32_16x16x32_bf16 v[24:27], v[210:213], v[174:177], v[24:27]
	v_mfma_f32_16x16x32_bf16 v[16:19], v[202:205], v[182:185], v[16:19]
	v_mfma_f32_16x16x32_bf16 v[8:11], v[210:213], v[182:185], v[8:11]
	v_mfma_f32_16x16x32_bf16 v[4:7], v[202:205], v[190:193], v[4:7]
	v_mfma_f32_16x16x32_bf16 v[0:3], v[210:213], v[190:193], v[0:3]
	s_setprio 0
	s_add_i32 s58, s58, 2
	s_add_u32 s22, s22, 0x100
	s_addc_u32 s23, s23, 0
	s_add_u32 s56, s56, 0x100
	s_addc_u32 s57, s57, 0
	s_cmp_gt_u32 s58, 13
	s_barrier
	s_cbranch_scc0 .LBB0_713
	v_mov_b32_e32 v146, v140
	v_mov_b32_e32 v147, v141
	s_lshl_b32 s13, s20, 8
	s_add_i32 s13, s13, s41
	v_add_u32_e32 v146, s13, v146
	s_lshl_b32 s13, s53, 8
	s_or_b32 s13, s13, s42
	v_lshl_add_u32 v148, v147, 3, s13
	v_ashrrev_i32_e32 v147, 31, v146
	v_cvt_pk_bf16_f32 v124, v124, v125
	v_cvt_pk_bf16_f32 v125, v126, v127
	v_cvt_pk_bf16_f32 v126, v120, v121
	v_lshlrev_b64 v[120:121], 14, v[146:147]
	v_lshl_add_u64 v[120:121], s[62:63], 0, v[120:121]
	v_ashrrev_i32_e32 v149, 31, v148
	v_lshl_add_u64 v[120:121], v[148:149], 1, v[120:121]
	s_mov_b32 s13, 0x40000
	v_cvt_pk_bf16_f32 v127, v122, v123
	global_store_dwordx4 v[120:121], v[124:127], off
	v_cvt_pk_bf16_f32 v112, v112, v113
	v_cvt_pk_bf16_f32 v113, v114, v115
	v_cvt_pk_bf16_f32 v114, v104, v105
	v_cvt_pk_bf16_f32 v115, v106, v107
	global_store_dwordx4 v[120:121], v[112:115], off offset:256
	v_cvt_pk_bf16_f32 v104, v116, v117
	v_cvt_pk_bf16_f32 v105, v118, v119
	v_cvt_pk_bf16_f32 v106, v108, v109
	v_cvt_pk_bf16_f32 v107, v110, v111
	s_mov_b64 s[22:23], 0x40000
	v_add_co_u32_e32 v110, vcc, s13, v120
	v_lshl_add_u64 v[108:109], v[120:121], 0, s[22:23]
	s_nop 0
	v_addc_co_u32_e32 v111, vcc, 0, v121, vcc
	s_mov_b32 s13, 0x80000
	global_store_dwordx4 v[110:111], v[104:107], off
	v_cvt_pk_bf16_f32 v96, v96, v97
	v_cvt_pk_bf16_f32 v97, v98, v99
	v_cvt_pk_bf16_f32 v98, v88, v89
	v_cvt_pk_bf16_f32 v99, v90, v91
	global_store_dwordx4 v[108:109], v[96:99], off offset:256
	v_cvt_pk_bf16_f32 v88, v100, v101
	v_cvt_pk_bf16_f32 v89, v102, v103
	v_cvt_pk_bf16_f32 v90, v92, v93
	v_cvt_pk_bf16_f32 v91, v94, v95
	s_mov_b64 s[22:23], 0x80000
	v_add_co_u32_e32 v94, vcc, s13, v120
	v_lshl_add_u64 v[92:93], v[120:121], 0, s[22:23]
	s_nop 0
	v_addc_co_u32_e32 v95, vcc, 0, v121, vcc
	global_store_dwordx4 v[94:95], v[88:91], off
	v_cvt_pk_bf16_f32 v80, v80, v81
	v_cvt_pk_bf16_f32 v81, v82, v83
	v_cvt_pk_bf16_f32 v82, v72, v73
	v_cvt_pk_bf16_f32 v83, v74, v75
	global_store_dwordx4 v[92:93], v[80:83], off offset:256
	v_cvt_pk_bf16_f32 v72, v84, v85
	v_cvt_pk_bf16_f32 v73, v86, v87
	v_cvt_pk_bf16_f32 v74, v76, v77
	v_cvt_pk_bf16_f32 v75, v78, v79
	s_mov_b64 s[22:23], 0xc0000
	v_add_co_u32_e32 v78, vcc, s48, v120
	v_lshl_add_u64 v[76:77], v[120:121], 0, s[22:23]
	s_nop 0
	v_addc_co_u32_e32 v79, vcc, 0, v121, vcc
	global_store_dwordx4 v[78:79], v[72:75], off
	v_cvt_pk_bf16_f32 v68, v68, v69
	v_cvt_pk_bf16_f32 v69, v70, v71
	v_cvt_pk_bf16_f32 v70, v64, v65
	v_cvt_pk_bf16_f32 v71, v66, v67
	global_store_dwordx4 v[76:77], v[68:71], off offset:256
	v_cvt_pk_bf16_f32 v60, v60, v61
	v_cvt_pk_bf16_f32 v61, v62, v63
	v_cvt_pk_bf16_f32 v62, v56, v57
	v_cvt_pk_bf16_f32 v63, v58, v59
	v_add_co_u32_e32 v58, vcc, s49, v120
	v_lshl_add_u64 v[56:57], v[120:121], 0, s[2:3]
	s_nop 0
	v_addc_co_u32_e32 v59, vcc, 0, v121, vcc
	global_store_dwordx4 v[58:59], v[60:63], off
	v_cvt_pk_bf16_f32 v48, v48, v49
	v_cvt_pk_bf16_f32 v49, v50, v51
	v_cvt_pk_bf16_f32 v50, v40, v41
	v_cvt_pk_bf16_f32 v51, v42, v43
	global_store_dwordx4 v[56:57], v[48:51], off offset:256
	v_cvt_pk_bf16_f32 v40, v52, v53
	v_cvt_pk_bf16_f32 v41, v54, v55
	v_cvt_pk_bf16_f32 v42, v44, v45
	v_cvt_pk_bf16_f32 v43, v46, v47
	v_add_co_u32_e32 v46, vcc, s50, v120
	v_lshl_add_u64 v[44:45], v[120:121], 0, s[4:5]
	s_nop 0
	v_addc_co_u32_e32 v47, vcc, 0, v121, vcc
	global_store_dwordx4 v[46:47], v[40:43], off
	v_cvt_pk_bf16_f32 v32, v32, v33
	v_cvt_pk_bf16_f32 v33, v34, v35
	v_cvt_pk_bf16_f32 v34, v24, v25
	v_cvt_pk_bf16_f32 v35, v26, v27
	global_store_dwordx4 v[44:45], v[32:35], off offset:256
	v_cvt_pk_bf16_f32 v24, v36, v37
	v_cvt_pk_bf16_f32 v25, v38, v39
	v_cvt_pk_bf16_f32 v26, v28, v29
	v_cvt_pk_bf16_f32 v27, v30, v31
	v_add_co_u32_e32 v30, vcc, s51, v120
	v_lshl_add_u64 v[28:29], v[120:121], 0, s[6:7]
	s_nop 0
	v_addc_co_u32_e32 v31, vcc, 0, v121, vcc
	global_store_dwordx4 v[30:31], v[24:27], off
	v_cvt_pk_bf16_f32 v16, v16, v17
	v_cvt_pk_bf16_f32 v17, v18, v19
	v_cvt_pk_bf16_f32 v18, v8, v9
	v_cvt_pk_bf16_f32 v19, v10, v11
	global_store_dwordx4 v[28:29], v[16:19], off offset:256
	v_cvt_pk_bf16_f32 v8, v20, v21
	v_cvt_pk_bf16_f32 v9, v22, v23
	v_cvt_pk_bf16_f32 v10, v12, v13
	v_cvt_pk_bf16_f32 v11, v14, v15
	v_add_co_u32_e32 v14, vcc, s52, v120
	v_lshl_add_u64 v[12:13], v[120:121], 0, s[8:9]
	s_nop 0
	v_addc_co_u32_e32 v15, vcc, 0, v121, vcc
	s_and_b64 vcc, exec, s[10:11]
	s_mov_b32 s53, s12
	s_mov_b32 s20, s14
	s_mov_b64 s[24:25], s[18:19]
	s_mov_b64 s[22:23], s[16:17]
	global_store_dwordx4 v[14:15], v[8:11], off
	v_cvt_pk_bf16_f32 v4, v4, v5
	v_cvt_pk_bf16_f32 v5, v6, v7
	v_cvt_pk_bf16_f32 v6, v0, v1
	v_cvt_pk_bf16_f32 v7, v2, v3
	global_store_dwordx4 v[12:13], v[4:7], off offset:256
	s_cbranch_vccz .LBB0_706
	s_waitcnt vmcnt(0)
	s_cmpk_gt_u32 s31, 0xff
	s_cbranch_scc1 .LBB0_717
	s_barrier

; #define PG8_STAGE(bufoff, gbase, voff) do { _Pragma("unroll") for (int _i = 0; _i < 2; ++_i) \
;         __builtin_amdgcn_global_load_lds((const unsigned*)((const char*)(gbase) + (voff)[_i]), (LAS unsigned*)(lds + (bufoff) + ldsw + _i * 8192), 16, 0, 0); } while (0)
; #define PG8_LDA(dst, b, h) do { _Pragma("unroll") for (int m = 0; m < 4; ++m) _Pragma("unroll") for (int k = 0; k < 2; ++k) dst[m][k] = *(const LAS bf16x8*)(lds + PG8_SA(b, h) + aoff + m * 2048 + k * 1024); } while (0)
; #define PG8_LDB(dst, b, h) do { _Pragma("unroll") for (int n = 0; n < 2; ++n) _Pragma("unroll") for (int k = 0; k < 2; ++k) dst[n][k] = *(const LAS bf16x8*)(lds + PG8_SB(b, h) + boff + n * 2048 + k * 1024); } while (0)
; #define PG8_WAIT_V(n) asm volatile("s_waitcnt vmcnt(" #n ")" ::: "memory")
; #define PG8_WAIT_L(n) asm volatile("s_waitcnt lgkmcnt(" #n ")" ::: "memory")
; #define PG8_BAR __builtin_amdgcn_s_barrier()
; #define PG8_SCHED __builtin_amdgcn_sched_barrier(0)
; template <class Epi, class Sched>
; __device__ __forceinline__ void gemm_phase(LAS unsigned char* lds, const Gemm g, const Sched& S, const Epi& E) {
;     ...
;         const bool has_next = S.next(ui + 1, nxt);
;         const char* nA = has_next ? (const char*)g.A + (size_t)nxt.pm * tstep : cA; const char* nB = has_next ? (const char*)g.Bt + (size_t)nxt.pn * tstep : cB;
;         for (int t = 0; t < nt; t += 2) {
;             const bool last = (t == nt - 2);
;             const char* a1 = cA + (size_t)(t + 1) * kstep;
;             const char* a2 = last ? nA : cA + (size_t)(t + 2) * kstep; const char* b2 = last ? nB : cB + (size_t)(t + 2) * kstep;
;             const char* a3 = a2 + kstep; const char* b3 = b2 + kstep;
;             PG8_LDB(B0, 0, 0); PG8_SCHED; PG8_LDA(At, 0, 0); PG8_STAGE(PG8_SA(1, 1), a1 + hstep, voffA);
;             PG8_WAIT_L(8); PG8_BAR; PG8_WAIT_L(0); PG8_MMA(0, 0, At, B0); PG8_BAR; PG8_SCHED;
;             PG8_LDB(B1, 0, 1); PG8_STAGE(PG8_SB(0, 0), b2, voffB);
;             PG8_BAR; PG8_WAIT_L(0); PG8_MMA(0, 1, At, B1); PG8_BAR;
;             PG8_LDA(At, 0, 1); PG8_STAGE(PG8_SA(0, 0), a2, voffA);
;             PG8_BAR; PG8_WAIT_L(0); PG8_MMA(1, 0, At, B0); PG8_BAR; PG8_SCHED;
;             PG8_STAGE(PG8_SB(0, 1), b2 + hstep, voffB);
;             PG8_WAIT_V(6); PG8_BAR; PG8_MMA(1, 1, At, B1); PG8_BAR;
.LBB0_825:
	s_ashr_i32 s7, s6, 31
	v_cmp_lt_i64_e32 vcc, s[8:9], v[156:157]
	s_lshl_b64 s[8:9], s[6:7], 20
	s_add_u32 s8, s22, s8
	s_addc_u32 s9, s23, s9
	s_and_b64 s[10:11], vcc, exec
	s_cselect_b32 s7, s9, s15
	s_cselect_b32 s39, s8, s14
	s_ashr_i32 s5, s4, 31
	s_lshl_b64 s[10:11], s[4:5], 20
	s_add_u32 s10, s50, s10
	s_addc_u32 s11, s51, s11
	s_and_b64 s[18:19], vcc, exec
	s_cselect_b32 s5, s11, s17
	s_cselect_b32 s40, s10, s16
	s_add_u32 s14, s14, 0x80080
	s_addc_u32 s15, s15, 0
	s_add_u32 s41, s16, 0x100
	s_addc_u32 s42, s17, 0
	s_mov_b32 s43, -2
	ds_read_b128 v[128:131], v168
	ds_read_b128 v[132:135], v168 offset:1024
	ds_read_b128 v[136:139], v168 offset:2048
	ds_read_b128 v[140:143], v168 offset:3072
	s_add_u32 s16, s14, 0xfff80080
	s_addc_u32 s17, s15, -1
	s_cmp_eq_u32 s43, 28
	s_cselect_b32 s19, s7, s17
	s_cselect_b32 s18, s39, s16
	s_cselect_b32 s17, s5, s42
	s_cselect_b32 s16, s40, s41
	s_add_i32 m0, s13, 0xc000
	ds_read_b128 v[162:165], v169
	ds_read_b128 v[172:175], v169 offset:1024
	ds_read_b128 v[176:179], v169 offset:2048
	ds_read_b128 v[180:183], v169 offset:3072
	ds_read_b128 v[184:187], v169 offset:4096
	ds_read_b128 v[188:191], v169 offset:5120
	ds_read_b128 v[192:195], v169 offset:6144
	ds_read_b128 v[196:199], v169 offset:7168
	global_load_lds_dwordx4 v152, s[14:15]
	s_add_i32 m0, s13, 0xe000
	s_nop 0
	global_load_lds_dwordx4 v154, s[14:15]
	s_waitcnt lgkmcnt(8)
	s_waitcnt vmcnt(8)
	s_barrier
	s_waitcnt lgkmcnt(0)
	s_setprio 1
	s_waitcnt lgkmcnt(0)
	v_mfma_f32_16x16x32_bf16 v[124:127], v[128:131], v[162:165], 0
	v_mfma_f32_16x16x32_bf16 v[120:123], v[136:139], v[162:165], 0
	v_mfma_f32_16x16x32_bf16 v[116:119], v[128:131], v[176:179], 0
	v_mfma_f32_16x16x32_bf16 v[112:115], v[136:139], v[176:179], 0
	v_mfma_f32_16x16x32_bf16 v[108:111], v[128:131], v[184:187], 0
	v_mfma_f32_16x16x32_bf16 v[100:103], v[136:139], v[184:187], 0
	v_mfma_f32_16x16x32_bf16 v[76:79], v[128:131], v[192:195], 0
	v_mfma_f32_16x16x32_bf16 v[72:75], v[136:139], v[192:195], 0
	v_mfma_f32_16x16x32_bf16 v[124:127], v[132:135], v[172:175], v[124:127]
	v_mfma_f32_16x16x32_bf16 v[120:123], v[140:143], v[172:175], v[120:123]
	v_mfma_f32_16x16x32_bf16 v[116:119], v[132:135], v[180:183], v[116:119]
	v_mfma_f32_16x16x32_bf16 v[112:115], v[140:143], v[180:183], v[112:115]
	v_mfma_f32_16x16x32_bf16 v[108:111], v[132:135], v[188:191], v[108:111]
	v_mfma_f32_16x16x32_bf16 v[100:103], v[140:143], v[188:191], v[100:103]
	v_mfma_f32_16x16x32_bf16 v[76:79], v[132:135], v[196:199], v[76:79]
	v_mfma_f32_16x16x32_bf16 v[72:75], v[140:143], v[196:199], v[72:75]
	s_setprio 0
	s_barrier
	s_add_i32 s44, s35, s24
	s_mov_b32 m0, s44
	ds_read_b128 v[202:205], v170
	ds_read_b128 v[206:209], v170 offset:1024
	ds_read_b128 v[210:213], v170 offset:2048
	ds_read_b128 v[214:217], v170 offset:3072
	global_load_lds_dwordx4 v146, s[16:17]
	s_add_i32 m0, s44, 0x2000
	s_nop 0
	global_load_lds_dwordx4 v150, s[16:17]
	s_waitcnt vmcnt(8)
	s_barrier
	s_waitcnt lgkmcnt(0)
	s_setprio 1
	s_waitcnt lgkmcnt(0)
	v_mfma_f32_16x16x32_bf16 v[104:107], v[202:205], v[162:165], 0
	v_mfma_f32_16x16x32_bf16 v[96:99], v[210:213], v[162:165], 0
	v_mfma_f32_16x16x32_bf16 v[92:95], v[202:205], v[176:179], 0
	v_mfma_f32_16x16x32_bf16 v[88:91], v[210:213], v[176:179], 0
	v_mfma_f32_16x16x32_bf16 v[84:87], v[202:205], v[184:187], 0
	v_mfma_f32_16x16x32_bf16 v[80:83], v[210:213], v[184:187], 0
	v_mfma_f32_16x16x32_bf16 v[68:71], v[202:205], v[192:195], 0
	v_mfma_f32_16x16x32_bf16 v[64:67], v[210:213], v[192:195], 0
	v_mfma_f32_16x16x32_bf16 v[104:107], v[206:209], v[172:175], v[104:107]
	v_mfma_f32_16x16x32_bf16 v[96:99], v[214:217], v[172:175], v[96:99]
	v_mfma_f32_16x16x32_bf16 v[92:95], v[206:209], v[180:183], v[92:95]
	v_mfma_f32_16x16x32_bf16 v[88:91], v[214:217], v[180:183], v[88:91]
	v_mfma_f32_16x16x32_bf16 v[84:87], v[206:209], v[188:191], v[84:87]
	v_mfma_f32_16x16x32_bf16 v[80:83], v[214:217], v[188:191], v[80:83]
	v_mfma_f32_16x16x32_bf16 v[68:71], v[206:209], v[196:199], v[68:71]
	v_mfma_f32_16x16x32_bf16 v[64:67], v[214:217], v[196:199], v[64:67]
	s_setprio 0
	s_mov_b32 m0, s13
	v_lshl_add_u64 v[222:223], s[18:19], 0, v[144:145]
	s_barrier
	ds_read_b128 v[162:165], v169 offset:16384
	ds_read_b128 v[172:175], v169 offset:17408
	ds_read_b128 v[176:179], v169 offset:18432
	ds_read_b128 v[180:183], v169 offset:19456
	ds_read_b128 v[184:187], v169 offset:20480
	ds_read_b128 v[188:191], v169 offset:21504
	ds_read_b128 v[192:195], v169 offset:22528
	ds_read_b128 v[196:199], v169 offset:23552
	global_load_lds_dwordx4 v144, s[18:19]
	v_lshl_add_u64 v[224:225], s[18:19], 0, v[148:149]
	s_mov_b32 m0, s25
	s_nop 0
	global_load_lds_dwordx4 v148, s[18:19]
	s_barrier
	s_waitcnt lgkmcnt(0)
	s_setprio 1
	s_waitcnt lgkmcnt(0)
	v_mfma_f32_16x16x32_bf16 v[60:63], v[128:131], v[162:165], 0
	v_mfma_f32_16x16x32_bf16 v[56:59], v[136:139], v[162:165], 0
	v_mfma_f32_16x16x32_bf16 v[48:51], v[128:131], v[176:179], 0
	v_mfma_f32_16x16x32_bf16 v[40:43], v[136:139], v[176:179], 0
	v_mfma_f32_16x16x32_bf16 v[32:35], v[128:131], v[184:187], 0
	v_mfma_f32_16x16x32_bf16 v[24:27], v[136:139], v[184:187], 0
	v_mfma_f32_16x16x32_bf16 v[16:19], v[128:131], v[192:195], 0
	v_mfma_f32_16x16x32_bf16 v[8:11], v[136:139], v[192:195], 0
	v_mfma_f32_16x16x32_bf16 v[60:63], v[132:135], v[172:175], v[60:63]
	v_mfma_f32_16x16x32_bf16 v[56:59], v[140:143], v[172:175], v[56:59]
	v_mfma_f32_16x16x32_bf16 v[48:51], v[132:135], v[180:183], v[48:51]
	v_mfma_f32_16x16x32_bf16 v[40:43], v[140:143], v[180:183], v[40:43]
	v_mfma_f32_16x16x32_bf16 v[32:35], v[132:135], v[188:191], v[32:35]
	v_mfma_f32_16x16x32_bf16 v[24:27], v[140:143], v[188:191], v[24:27]
	v_mfma_f32_16x16x32_bf16 v[16:19], v[132:135], v[196:199], v[16:19]
	v_mfma_f32_16x16x32_bf16 v[8:11], v[140:143], v[196:199], v[8:11]
	s_setprio 0
	s_barrier
; #define PG8_STAGE(bufoff, gbase, voff) do { _Pragma("unroll") for (int _i = 0; _i < 2; ++_i) \
;         __builtin_amdgcn_global_load_lds((const unsigned*)((const char*)(gbase) + (voff)[_i]), (LAS unsigned*)(lds + (bufoff) + ldsw + _i * 8192), 16, 0, 0); } while (0)
; #define PG8_LDA(dst, b, h) do { _Pragma("unroll") for (int m = 0; m < 4; ++m) _Pragma("unroll") for (int k = 0; k < 2; ++k) dst[m][k] = *(const LAS bf16x8*)(lds + PG8_SA(b, h) + aoff + m * 2048 + k * 1024); } while (0)
; #define PG8_LDB(dst, b, h) do { _Pragma("unroll") for (int n = 0; n < 2; ++n) _Pragma("unroll") for (int k = 0; k < 2; ++k) dst[n][k] = *(const LAS bf16x8*)(lds + PG8_SB(b, h) + boff + n * 2048 + k * 1024); } while (0)
; #define PG8_MMA(ai, bj, At, Bt) do { __builtin_amdgcn_s_setprio(1); _Pragma("unroll") for (int m = 0; m < 4; ++m) _Pragma("unroll") for (int n = 0; n < 2; ++n) _Pragma("unroll") for (int k = 0; k < 2; ++k) \
;         acc[ai][bj][m][n] = __builtin_amdgcn_mfma_f32_16x16x32_bf16(Bt[n][k], At[m][k], acc[ai][bj][m][n], 0, 0, 0); __builtin_amdgcn_s_setprio(0); } while (0)
; #define PG8_WAIT_V(n) asm volatile("s_waitcnt vmcnt(" #n ")" ::: "memory")
; #define PG8_WAIT_L(n) asm volatile("s_waitcnt lgkmcnt(" #n ")" ::: "memory")
; #define PG8_BAR __builtin_amdgcn_s_barrier()
; #define PG8_SCHED __builtin_amdgcn_sched_barrier(0)
; template <class Epi, class Sched>
; __device__ __forceinline__ void gemm_phase(LAS unsigned char* lds, const Gemm g, const Sched& S, const Epi& E) {
;     ...
;             PG8_LDB(B1, 0, 1); PG8_STAGE(PG8_SB(0, 0), b2, voffB);
;             PG8_BAR; PG8_WAIT_L(0); PG8_MMA(0, 1, At, B1); PG8_BAR;
;             PG8_LDA(At, 0, 1); PG8_STAGE(PG8_SA(0, 0), a2, voffA);
;             PG8_BAR; PG8_WAIT_L(0); PG8_MMA(1, 0, At, B0); PG8_BAR; PG8_SCHED;
;             PG8_STAGE(PG8_SB(0, 1), b2 + hstep, voffB);
;             PG8_WAIT_V(6); PG8_BAR; PG8_MMA(1, 1, At, B1); PG8_BAR;
;             PG8_LDB(B0, 1, 0); PG8_SCHED; PG8_LDA(At, 1, 0); PG8_STAGE(PG8_SA(0, 1), a2 + hstep, voffA);
;             PG8_WAIT_L(8); PG8_BAR; PG8_WAIT_L(0); PG8_MMA(0, 0, At, B0); PG8_BAR; PG8_SCHED;
	s_add_u32 s44, s16, 0x80000
	s_addc_u32 s45, s17, 0
	s_add_i32 s46, s36, s24
	s_mov_b32 m0, s46
	s_nop 0
	global_load_lds_dwordx4 v146, s[44:45]
	s_add_i32 m0, s46, 0x2000
	s_nop 0
	global_load_lds_dwordx4 v150, s[44:45]
	s_add_u32 s18, s18, 0x80000
	s_addc_u32 s19, s19, 0
	s_mov_b32 m0, s26
	s_nop 0
	global_load_lds_dwordx4 v144, s[18:19]
	s_mov_b32 m0, s27
	s_nop 0
	global_load_lds_dwordx4 v148, s[18:19]
	s_waitcnt vmcnt(10)
	s_barrier
	s_setprio 1
	v_mfma_f32_16x16x32_bf16 v[52:55], v[202:205], v[162:165], 0
	v_mfma_f32_16x16x32_bf16 v[44:47], v[210:213], v[162:165], 0
	v_mfma_f32_16x16x32_bf16 v[36:39], v[202:205], v[176:179], 0
	v_mfma_f32_16x16x32_bf16 v[28:31], v[210:213], v[176:179], 0
	v_mfma_f32_16x16x32_bf16 v[20:23], v[202:205], v[184:187], 0
	v_mfma_f32_16x16x32_bf16 v[12:15], v[210:213], v[184:187], 0
	v_mfma_f32_16x16x32_bf16 v[4:7], v[202:205], v[192:195], 0
	v_mfma_f32_16x16x32_bf16 v[0:3], v[210:213], v[192:195], 0
	v_mfma_f32_16x16x32_bf16 v[52:55], v[206:209], v[172:175], v[52:55]
	v_mfma_f32_16x16x32_bf16 v[44:47], v[214:217], v[172:175], v[44:47]
	v_mfma_f32_16x16x32_bf16 v[36:39], v[206:209], v[180:183], v[36:39]
	v_mfma_f32_16x16x32_bf16 v[28:31], v[214:217], v[180:183], v[28:31]
	v_mfma_f32_16x16x32_bf16 v[20:23], v[206:209], v[188:191], v[20:23]
	v_mfma_f32_16x16x32_bf16 v[12:15], v[214:217], v[188:191], v[12:15]
	v_mfma_f32_16x16x32_bf16 v[4:7], v[206:209], v[196:199], v[4:7]
	v_mfma_f32_16x16x32_bf16 v[0:3], v[214:217], v[196:199], v[0:3]
	s_setprio 0
	s_add_i32 s44, 0, 0x18000
	v_add_u32_e32 v140, s44, v167
	s_barrier
	ds_read_b128 v[128:131], v140
	ds_read_b128 v[132:135], v140 offset:1024
	ds_read_b128 v[136:139], v140 offset:2048
	ds_read_b128 v[140:143], v140 offset:3072
	ds_read_b128 v[162:165], v169 offset:32768
	ds_read_b128 v[172:175], v169 offset:33792
	ds_read_b128 v[176:179], v169 offset:34816
	ds_read_b128 v[180:183], v169 offset:35840
	ds_read_b128 v[184:187], v169 offset:36864
	ds_read_b128 v[188:191], v169 offset:37888
	ds_read_b128 v[192:195], v169 offset:38912
	ds_read_b128 v[196:199], v169 offset:39936
	s_waitcnt lgkmcnt(8)
	s_waitcnt vmcnt(8)
	s_barrier
	s_waitcnt lgkmcnt(0)
	s_setprio 1
	s_waitcnt lgkmcnt(0)
	v_mfma_f32_16x16x32_bf16 v[124:127], v[128:131], v[162:165], v[124:127]
	v_mfma_f32_16x16x32_bf16 v[120:123], v[136:139], v[162:165], v[120:123]
	v_mfma_f32_16x16x32_bf16 v[116:119], v[128:131], v[176:179], v[116:119]
	v_mfma_f32_16x16x32_bf16 v[112:115], v[136:139], v[176:179], v[112:115]
	v_mfma_f32_16x16x32_bf16 v[108:111], v[128:131], v[184:187], v[108:111]
	v_mfma_f32_16x16x32_bf16 v[100:103], v[136:139], v[184:187], v[100:103]
	v_mfma_f32_16x16x32_bf16 v[76:79], v[128:131], v[192:195], v[76:79]
	v_mfma_f32_16x16x32_bf16 v[72:75], v[136:139], v[192:195], v[72:75]
	v_mfma_f32_16x16x32_bf16 v[124:127], v[132:135], v[172:175], v[124:127]
	v_mfma_f32_16x16x32_bf16 v[120:123], v[140:143], v[172:175], v[120:123]
	v_mfma_f32_16x16x32_bf16 v[116:119], v[132:135], v[180:183], v[116:119]
	v_mfma_f32_16x16x32_bf16 v[112:115], v[140:143], v[180:183], v[112:115]
	v_mfma_f32_16x16x32_bf16 v[108:111], v[132:135], v[188:191], v[108:111]
	v_mfma_f32_16x16x32_bf16 v[100:103], v[140:143], v[188:191], v[100:103]
	v_mfma_f32_16x16x32_bf16 v[76:79], v[132:135], v[196:199], v[76:79]
	v_mfma_f32_16x16x32_bf16 v[72:75], v[140:143], v[196:199], v[72:75]
	s_setprio 0
	s_barrier
	s_add_i32 s18, 0, 0x1c000
	s_add_i32 s19, s44, s24
	v_add_u32_e32 v160, s18, v167
	s_add_u32 s0, s16, 0x80
	s_addc_u32 s1, s17, 0
	s_mov_b32 m0, s19
	ds_read_b128 v[202:205], v160
	ds_read_b128 v[206:209], v160 offset:1024
	ds_read_b128 v[210:213], v160 offset:2048
	ds_read_b128 v[214:217], v160 offset:3072
	global_load_lds_dwordx4 v146, s[0:1]
	s_add_i32 m0, s19, 0x2000
	s_nop 0
	global_load_lds_dwordx4 v150, s[0:1]
	s_waitcnt vmcnt(8)
	s_barrier
	s_waitcnt lgkmcnt(0)
	s_setprio 1
	s_waitcnt lgkmcnt(0)
	v_mfma_f32_16x16x32_bf16 v[104:107], v[202:205], v[162:165], v[104:107]
	v_mfma_f32_16x16x32_bf16 v[96:99], v[210:213], v[162:165], v[96:99]
	v_mfma_f32_16x16x32_bf16 v[92:95], v[202:205], v[176:179], v[92:95]
	v_mfma_f32_16x16x32_bf16 v[88:91], v[210:213], v[176:179], v[88:91]
	v_mfma_f32_16x16x32_bf16 v[84:87], v[202:205], v[184:187], v[84:87]
	v_mfma_f32_16x16x32_bf16 v[80:83], v[210:213], v[184:187], v[80:83]
	v_mfma_f32_16x16x32_bf16 v[68:71], v[202:205], v[192:195], v[68:71]
	v_mfma_f32_16x16x32_bf16 v[64:67], v[210:213], v[192:195], v[64:67]
	v_mfma_f32_16x16x32_bf16 v[104:107], v[206:209], v[172:175], v[104:107]
	v_mfma_f32_16x16x32_bf16 v[96:99], v[214:217], v[172:175], v[96:99]
	v_mfma_f32_16x16x32_bf16 v[92:95], v[206:209], v[180:183], v[92:95]
	v_mfma_f32_16x16x32_bf16 v[88:91], v[214:217], v[180:183], v[88:91]
	v_mfma_f32_16x16x32_bf16 v[84:87], v[206:209], v[188:191], v[84:87]
	v_mfma_f32_16x16x32_bf16 v[80:83], v[214:217], v[188:191], v[80:83]
	v_mfma_f32_16x16x32_bf16 v[68:71], v[206:209], v[196:199], v[68:71]
	v_mfma_f32_16x16x32_bf16 v[64:67], v[214:217], v[196:199], v[64:67]
	s_setprio 0
	s_mov_b32 m0, s31
	s_mov_b64 s[0:1], 0x80
	v_lshl_add_u64 v[218:219], v[222:223], 0, s[0:1]
	s_barrier
	ds_read_b128 v[162:165], v169 offset:49152
	ds_read_b128 v[172:175], v169 offset:50176
	ds_read_b128 v[176:179], v169 offset:51200
	ds_read_b128 v[180:183], v169 offset:52224
	ds_read_b128 v[184:187], v169 offset:53248
	ds_read_b128 v[188:191], v169 offset:54272
	ds_read_b128 v[192:195], v169 offset:55296
	ds_read_b128 v[196:199], v169 offset:56320
	global_load_lds_dwordx4 v[218:219], off
	v_lshl_add_u64 v[218:219], v[224:225], 0, s[0:1]
	s_mov_b32 m0, s33
	s_nop 0
	global_load_lds_dwordx4 v[218:219], off
	s_barrier
; #define PG8_STAGE(bufoff, gbase, voff) do { _Pragma("unroll") for (int _i = 0; _i < 2; ++_i) \
;         __builtin_amdgcn_global_load_lds((const unsigned*)((const char*)(gbase) + (voff)[_i]), (LAS unsigned*)(lds + (bufoff) + ldsw + _i * 8192), 16, 0, 0); } while (0)
; #define PG8_LDA(dst, b, h) do { _Pragma("unroll") for (int m = 0; m < 4; ++m) _Pragma("unroll") for (int k = 0; k < 2; ++k) dst[m][k] = *(const LAS bf16x8*)(lds + PG8_SA(b, h) + aoff + m * 2048 + k * 1024); } while (0)
; #define PG8_LDB(dst, b, h) do { _Pragma("unroll") for (int n = 0; n < 2; ++n) _Pragma("unroll") for (int k = 0; k < 2; ++k) dst[n][k] = *(const LAS bf16x8*)(lds + PG8_SB(b, h) + boff + n * 2048 + k * 1024); } while (0)
; #define PG8_WAIT_V(n) asm volatile("s_waitcnt vmcnt(" #n ")" ::: "memory")
; #define PG8_WAIT_L(n) asm volatile("s_waitcnt lgkmcnt(" #n ")" ::: "memory")
; #define PG8_BAR __builtin_amdgcn_s_barrier()
; #define PG8_SCHED __builtin_amdgcn_sched_barrier(0)
; template <class Epi, class Sched>
; __device__ __forceinline__ void gemm_phase(LAS unsigned char* lds, const Gemm g, const Sched& S, const Epi& E) {
;     ...
;             PG8_LDB(B0, 0, 0); PG8_SCHED; PG8_LDA(At, 0, 0); PG8_STAGE(PG8_SA(1, 1), a1 + hstep, voffA);
;             PG8_WAIT_L(8); PG8_BAR; PG8_WAIT_L(0); PG8_MMA(0, 0, At, B0); PG8_BAR; PG8_SCHED;
;             PG8_LDB(B1, 0, 1); PG8_STAGE(PG8_SB(0, 0), b2, voffB);
;             PG8_BAR; PG8_WAIT_L(0); PG8_MMA(0, 1, At, B1); PG8_BAR;
;             PG8_LDA(At, 0, 1); PG8_STAGE(PG8_SA(0, 0), a2, voffA);
;             PG8_BAR; PG8_WAIT_L(0); PG8_MMA(1, 0, At, B0); PG8_BAR; PG8_SCHED;
;             PG8_STAGE(PG8_SB(0, 1), b2 + hstep, voffB);
;             PG8_WAIT_V(6); PG8_BAR; PG8_MMA(1, 1, At, B1); PG8_BAR;
;             PG8_LDB(B0, 1, 0); PG8_SCHED; PG8_LDA(At, 1, 0); PG8_STAGE(PG8_SA(0, 1), a2 + hstep, voffA);
;             PG8_WAIT_L(8); PG8_BAR; PG8_WAIT_L(0); PG8_MMA(0, 0, At, B0); PG8_BAR; PG8_SCHED;
;             PG8_LDB(B1, 1, 1); PG8_STAGE(PG8_SB(1, 0), b3, voffB);
;             PG8_BAR; PG8_WAIT_L(0); PG8_MMA(0, 1, At, B1); PG8_BAR;
;             PG8_LDA(At, 1, 1); PG8_STAGE(PG8_SA(1, 0), a3, voffA);
;             PG8_BAR; PG8_WAIT_L(0); PG8_MMA(1, 0, At, B0); PG8_BAR; PG8_SCHED;
;             PG8_STAGE(PG8_SB(1, 1), b3 + hstep, voffB);
;             PG8_WAIT_V(6); PG8_BAR; PG8_MMA(1, 1, At, B1); PG8_BAR;
	s_waitcnt lgkmcnt(0)
	s_setprio 1
	s_waitcnt lgkmcnt(0)
	v_mfma_f32_16x16x32_bf16 v[60:63], v[128:131], v[162:165], v[60:63]
	v_mfma_f32_16x16x32_bf16 v[56:59], v[136:139], v[162:165], v[56:59]
	v_mfma_f32_16x16x32_bf16 v[48:51], v[128:131], v[176:179], v[48:51]
	v_mfma_f32_16x16x32_bf16 v[40:43], v[136:139], v[176:179], v[40:43]
	v_mfma_f32_16x16x32_bf16 v[32:35], v[128:131], v[184:187], v[32:35]
	v_mfma_f32_16x16x32_bf16 v[24:27], v[136:139], v[184:187], v[24:27]
	v_mfma_f32_16x16x32_bf16 v[16:19], v[128:131], v[192:195], v[16:19]
	v_mfma_f32_16x16x32_bf16 v[8:11], v[136:139], v[192:195], v[8:11]
	v_mfma_f32_16x16x32_bf16 v[60:63], v[132:135], v[172:175], v[60:63]
	v_mfma_f32_16x16x32_bf16 v[56:59], v[140:143], v[172:175], v[56:59]
	v_mfma_f32_16x16x32_bf16 v[48:51], v[132:135], v[180:183], v[48:51]
	v_mfma_f32_16x16x32_bf16 v[40:43], v[140:143], v[180:183], v[40:43]
	v_mfma_f32_16x16x32_bf16 v[32:35], v[132:135], v[188:191], v[32:35]
	v_mfma_f32_16x16x32_bf16 v[24:27], v[140:143], v[188:191], v[24:27]
	v_mfma_f32_16x16x32_bf16 v[16:19], v[132:135], v[196:199], v[16:19]
	v_mfma_f32_16x16x32_bf16 v[8:11], v[140:143], v[196:199], v[8:11]
	s_setprio 0
	s_barrier
	s_add_u32 s16, s16, 0x80080
	s_addc_u32 s17, s17, 0
	s_add_i32 s18, s18, s24
	s_mov_b32 m0, s18
	s_nop 0
	global_load_lds_dwordx4 v146, s[16:17]
	s_add_i32 m0, s18, 0x2000
	s_nop 0
	global_load_lds_dwordx4 v150, s[16:17]
	s_waitcnt vmcnt(8)
	s_barrier
	s_setprio 1
	v_mfma_f32_16x16x32_bf16 v[52:55], v[202:205], v[162:165], v[52:55]
	v_mfma_f32_16x16x32_bf16 v[44:47], v[210:213], v[162:165], v[44:47]
	v_mfma_f32_16x16x32_bf16 v[36:39], v[202:205], v[176:179], v[36:39]
	v_mfma_f32_16x16x32_bf16 v[28:31], v[210:213], v[176:179], v[28:31]
	v_mfma_f32_16x16x32_bf16 v[20:23], v[202:205], v[184:187], v[20:23]
	v_mfma_f32_16x16x32_bf16 v[12:15], v[210:213], v[184:187], v[12:15]
	v_mfma_f32_16x16x32_bf16 v[4:7], v[202:205], v[192:195], v[4:7]
	v_mfma_f32_16x16x32_bf16 v[0:3], v[210:213], v[192:195], v[0:3]
	v_mfma_f32_16x16x32_bf16 v[52:55], v[206:209], v[172:175], v[52:55]
	v_mfma_f32_16x16x32_bf16 v[44:47], v[214:217], v[172:175], v[44:47]
	v_mfma_f32_16x16x32_bf16 v[36:39], v[206:209], v[180:183], v[36:39]
	v_mfma_f32_16x16x32_bf16 v[28:31], v[214:217], v[180:183], v[28:31]
	v_mfma_f32_16x16x32_bf16 v[20:23], v[206:209], v[188:191], v[20:23]
	v_mfma_f32_16x16x32_bf16 v[12:15], v[214:217], v[188:191], v[12:15]
	v_mfma_f32_16x16x32_bf16 v[4:7], v[206:209], v[196:199], v[4:7]
	v_mfma_f32_16x16x32_bf16 v[0:3], v[214:217], v[196:199], v[0:3]
	s_setprio 0
	s_add_i32 s43, s43, 2
	s_add_u32 s14, s14, 0x100
	s_addc_u32 s15, s15, 0
	s_add_u32 s41, s41, 0x100
	s_addc_u32 s42, s42, 0
	s_cmp_gt_u32 s43, 29
	s_barrier
.LBB0_826:
	ds_read_b128 v[128:131], v168
	ds_read_b128 v[132:135], v168 offset:1024
	ds_read_b128 v[136:139], v168 offset:2048
	ds_read_b128 v[140:143], v168 offset:3072
	s_add_u32 s16, s14, 0xfff80080
	s_addc_u32 s17, s15, -1
	s_cmp_eq_u32 s43, 28
	s_cselect_b32 s19, s7, s17
	s_cselect_b32 s18, s39, s16
	s_cselect_b32 s17, s5, s42
	s_cselect_b32 s16, s40, s41
	s_add_i32 m0, s13, 0xc000
	ds_read_b128 v[162:165], v169
	ds_read_b128 v[172:175], v169 offset:1024
	ds_read_b128 v[176:179], v169 offset:2048
	ds_read_b128 v[180:183], v169 offset:3072
	ds_read_b128 v[184:187], v169 offset:4096
	ds_read_b128 v[188:191], v169 offset:5120
	ds_read_b128 v[192:195], v169 offset:6144
	ds_read_b128 v[196:199], v169 offset:7168
	global_load_lds_dwordx4 v152, s[14:15]
	s_add_i32 m0, s13, 0xe000
	s_nop 0
	global_load_lds_dwordx4 v154, s[14:15]
	s_waitcnt lgkmcnt(8)
	s_waitcnt vmcnt(8)
	s_barrier
	s_waitcnt lgkmcnt(0)
	s_setprio 1
	s_waitcnt lgkmcnt(0)
	v_mfma_f32_16x16x32_bf16 v[124:127], v[128:131], v[162:165], v[124:127]
	v_mfma_f32_16x16x32_bf16 v[120:123], v[136:139], v[162:165], v[120:123]
	v_mfma_f32_16x16x32_bf16 v[116:119], v[128:131], v[176:179], v[116:119]
	v_mfma_f32_16x16x32_bf16 v[112:115], v[136:139], v[176:179], v[112:115]
	v_mfma_f32_16x16x32_bf16 v[108:111], v[128:131], v[184:187], v[108:111]
	v_mfma_f32_16x16x32_bf16 v[100:103], v[136:139], v[184:187], v[100:103]
	v_mfma_f32_16x16x32_bf16 v[76:79], v[128:131], v[192:195], v[76:79]
	v_mfma_f32_16x16x32_bf16 v[72:75], v[136:139], v[192:195], v[72:75]
	v_mfma_f32_16x16x32_bf16 v[124:127], v[132:135], v[172:175], v[124:127]
	v_mfma_f32_16x16x32_bf16 v[120:123], v[140:143], v[172:175], v[120:123]
	v_mfma_f32_16x16x32_bf16 v[116:119], v[132:135], v[180:183], v[116:119]
	v_mfma_f32_16x16x32_bf16 v[112:115], v[140:143], v[180:183], v[112:115]
	v_mfma_f32_16x16x32_bf16 v[108:111], v[132:135], v[188:191], v[108:111]
	v_mfma_f32_16x16x32_bf16 v[100:103], v[140:143], v[188:191], v[100:103]
	v_mfma_f32_16x16x32_bf16 v[76:79], v[132:135], v[196:199], v[76:79]
	v_mfma_f32_16x16x32_bf16 v[72:75], v[140:143], v[196:199], v[72:75]
	s_setprio 0
	s_barrier
	s_add_i32 s44, s35, s24
	s_mov_b32 m0, s44
	ds_read_b128 v[202:205], v170
	ds_read_b128 v[206:209], v170 offset:1024
	ds_read_b128 v[210:213], v170 offset:2048
	ds_read_b128 v[214:217], v170 offset:3072
	global_load_lds_dwordx4 v146, s[16:17]
	s_add_i32 m0, s44, 0x2000
	s_nop 0
	global_load_lds_dwordx4 v150, s[16:17]
	s_waitcnt vmcnt(8)
	s_barrier
; #define PG8_STAGE(bufoff, gbase, voff) do { _Pragma("unroll") for (int _i = 0; _i < 2; ++_i) \
;         __builtin_amdgcn_global_load_lds((const unsigned*)((const char*)(gbase) + (voff)[_i]), (LAS unsigned*)(lds + (bufoff) + ldsw + _i * 8192), 16, 0, 0); } while (0)
; #define PG8_LDA(dst, b, h) do { _Pragma("unroll") for (int m = 0; m < 4; ++m) _Pragma("unroll") for (int k = 0; k < 2; ++k) dst[m][k] = *(const LAS bf16x8*)(lds + PG8_SA(b, h) + aoff + m * 2048 + k * 1024); } while (0)
; #define PG8_LDB(dst, b, h) do { _Pragma("unroll") for (int n = 0; n < 2; ++n) _Pragma("unroll") for (int k = 0; k < 2; ++k) dst[n][k] = *(const LAS bf16x8*)(lds + PG8_SB(b, h) + boff + n * 2048 + k * 1024); } while (0)
; #define PG8_WAIT_V(n) asm volatile("s_waitcnt vmcnt(" #n ")" ::: "memory")
; #define PG8_WAIT_L(n) asm volatile("s_waitcnt lgkmcnt(" #n ")" ::: "memory")
; #define PG8_BAR __builtin_amdgcn_s_barrier()
; #define PG8_SCHED __builtin_amdgcn_sched_barrier(0)
; template <class Epi, class Sched>
; __device__ __forceinline__ void gemm_phase(LAS unsigned char* lds, const Gemm g, const Sched& S, const Epi& E) {
;     ...
;             PG8_LDB(B0, 0, 0); PG8_SCHED; PG8_LDA(At, 0, 0); PG8_STAGE(PG8_SA(1, 1), a1 + hstep, voffA);
;             PG8_WAIT_L(8); PG8_BAR; PG8_WAIT_L(0); PG8_MMA(0, 0, At, B0); PG8_BAR; PG8_SCHED;
;             PG8_LDB(B1, 0, 1); PG8_STAGE(PG8_SB(0, 0), b2, voffB);
;             PG8_BAR; PG8_WAIT_L(0); PG8_MMA(0, 1, At, B1); PG8_BAR;
;             PG8_LDA(At, 0, 1); PG8_STAGE(PG8_SA(0, 0), a2, voffA);
;             PG8_BAR; PG8_WAIT_L(0); PG8_MMA(1, 0, At, B0); PG8_BAR; PG8_SCHED;
;             PG8_STAGE(PG8_SB(0, 1), b2 + hstep, voffB);
;             PG8_WAIT_V(6); PG8_BAR; PG8_MMA(1, 1, At, B1); PG8_BAR;
;             PG8_LDB(B0, 1, 0); PG8_SCHED; PG8_LDA(At, 1, 0); PG8_STAGE(PG8_SA(0, 1), a2 + hstep, voffA);
;             PG8_WAIT_L(8); PG8_BAR; PG8_WAIT_L(0); PG8_MMA(0, 0, At, B0); PG8_BAR; PG8_SCHED;
;             PG8_LDB(B1, 1, 1); PG8_STAGE(PG8_SB(1, 0), b3, voffB);
;             PG8_BAR; PG8_WAIT_L(0); PG8_MMA(0, 1, At, B1); PG8_BAR;
;             PG8_LDA(At, 1, 1); PG8_STAGE(PG8_SA(1, 0), a3, voffA);
;             PG8_BAR; PG8_WAIT_L(0); PG8_MMA(1, 0, At, B0); PG8_BAR; PG8_SCHED;
;             PG8_STAGE(PG8_SB(1, 1), b3 + hstep, voffB);
;             PG8_WAIT_V(6); PG8_BAR; PG8_MMA(1, 1, At, B1); PG8_BAR;
	s_waitcnt lgkmcnt(0)
	s_setprio 1
	s_waitcnt lgkmcnt(0)
	v_mfma_f32_16x16x32_bf16 v[104:107], v[202:205], v[162:165], v[104:107]
	v_mfma_f32_16x16x32_bf16 v[96:99], v[210:213], v[162:165], v[96:99]
	v_mfma_f32_16x16x32_bf16 v[92:95], v[202:205], v[176:179], v[92:95]
	v_mfma_f32_16x16x32_bf16 v[88:91], v[210:213], v[176:179], v[88:91]
	v_mfma_f32_16x16x32_bf16 v[84:87], v[202:205], v[184:187], v[84:87]
	v_mfma_f32_16x16x32_bf16 v[80:83], v[210:213], v[184:187], v[80:83]
	v_mfma_f32_16x16x32_bf16 v[68:71], v[202:205], v[192:195], v[68:71]
	v_mfma_f32_16x16x32_bf16 v[64:67], v[210:213], v[192:195], v[64:67]
	v_mfma_f32_16x16x32_bf16 v[104:107], v[206:209], v[172:175], v[104:107]
	v_mfma_f32_16x16x32_bf16 v[96:99], v[214:217], v[172:175], v[96:99]
	v_mfma_f32_16x16x32_bf16 v[92:95], v[206:209], v[180:183], v[92:95]
	v_mfma_f32_16x16x32_bf16 v[88:91], v[214:217], v[180:183], v[88:91]
	v_mfma_f32_16x16x32_bf16 v[84:87], v[206:209], v[188:191], v[84:87]
	v_mfma_f32_16x16x32_bf16 v[80:83], v[214:217], v[188:191], v[80:83]
	v_mfma_f32_16x16x32_bf16 v[68:71], v[206:209], v[196:199], v[68:71]
	v_mfma_f32_16x16x32_bf16 v[64:67], v[214:217], v[196:199], v[64:67]
	s_setprio 0
	s_mov_b32 m0, s13
	v_lshl_add_u64 v[222:223], s[18:19], 0, v[144:145]
	s_barrier
	ds_read_b128 v[162:165], v169 offset:16384
	ds_read_b128 v[172:175], v169 offset:17408
	ds_read_b128 v[176:179], v169 offset:18432
	ds_read_b128 v[180:183], v169 offset:19456
	ds_read_b128 v[184:187], v169 offset:20480
	ds_read_b128 v[188:191], v169 offset:21504
	ds_read_b128 v[192:195], v169 offset:22528
	ds_read_b128 v[196:199], v169 offset:23552
	global_load_lds_dwordx4 v144, s[18:19]
	v_lshl_add_u64 v[224:225], s[18:19], 0, v[148:149]
	s_mov_b32 m0, s25
	s_nop 0
	global_load_lds_dwordx4 v148, s[18:19]
	s_barrier
	s_waitcnt lgkmcnt(0)
	s_setprio 1
	s_waitcnt lgkmcnt(0)
	v_mfma_f32_16x16x32_bf16 v[60:63], v[128:131], v[162:165], v[60:63]
	v_mfma_f32_16x16x32_bf16 v[56:59], v[136:139], v[162:165], v[56:59]
	v_mfma_f32_16x16x32_bf16 v[48:51], v[128:131], v[176:179], v[48:51]
	v_mfma_f32_16x16x32_bf16 v[40:43], v[136:139], v[176:179], v[40:43]
	v_mfma_f32_16x16x32_bf16 v[32:35], v[128:131], v[184:187], v[32:35]
	v_mfma_f32_16x16x32_bf16 v[24:27], v[136:139], v[184:187], v[24:27]
	v_mfma_f32_16x16x32_bf16 v[16:19], v[128:131], v[192:195], v[16:19]
	v_mfma_f32_16x16x32_bf16 v[8:11], v[136:139], v[192:195], v[8:11]
	v_mfma_f32_16x16x32_bf16 v[60:63], v[132:135], v[172:175], v[60:63]
	v_mfma_f32_16x16x32_bf16 v[56:59], v[140:143], v[172:175], v[56:59]
	v_mfma_f32_16x16x32_bf16 v[48:51], v[132:135], v[180:183], v[48:51]
	v_mfma_f32_16x16x32_bf16 v[40:43], v[140:143], v[180:183], v[40:43]
	v_mfma_f32_16x16x32_bf16 v[32:35], v[132:135], v[188:191], v[32:35]
	v_mfma_f32_16x16x32_bf16 v[24:27], v[140:143], v[188:191], v[24:27]
	v_mfma_f32_16x16x32_bf16 v[16:19], v[132:135], v[196:199], v[16:19]
	v_mfma_f32_16x16x32_bf16 v[8:11], v[140:143], v[196:199], v[8:11]
	s_setprio 0
	s_barrier
	s_add_u32 s44, s16, 0x80000
	s_addc_u32 s45, s17, 0
	s_add_i32 s46, s36, s24
	s_mov_b32 m0, s46
	s_nop 0
	global_load_lds_dwordx4 v146, s[44:45]
	s_add_i32 m0, s46, 0x2000
	s_nop 0
	global_load_lds_dwordx4 v150, s[44:45]
	s_add_u32 s18, s18, 0x80000
	s_addc_u32 s19, s19, 0
	s_mov_b32 m0, s26
	s_nop 0
	global_load_lds_dwordx4 v144, s[18:19]
	s_mov_b32 m0, s27
	s_nop 0
	global_load_lds_dwordx4 v148, s[18:19]
	s_waitcnt vmcnt(10)
	s_barrier
	s_setprio 1
	v_mfma_f32_16x16x32_bf16 v[52:55], v[202:205], v[162:165], v[52:55]
	v_mfma_f32_16x16x32_bf16 v[44:47], v[210:213], v[162:165], v[44:47]
	v_mfma_f32_16x16x32_bf16 v[36:39], v[202:205], v[176:179], v[36:39]
	v_mfma_f32_16x16x32_bf16 v[28:31], v[210:213], v[176:179], v[28:31]
	v_mfma_f32_16x16x32_bf16 v[20:23], v[202:205], v[184:187], v[20:23]
	v_mfma_f32_16x16x32_bf16 v[12:15], v[210:213], v[184:187], v[12:15]
	v_mfma_f32_16x16x32_bf16 v[4:7], v[202:205], v[192:195], v[4:7]
	v_mfma_f32_16x16x32_bf16 v[0:3], v[210:213], v[192:195], v[0:3]
	v_mfma_f32_16x16x32_bf16 v[52:55], v[206:209], v[172:175], v[52:55]
	v_mfma_f32_16x16x32_bf16 v[44:47], v[214:217], v[172:175], v[44:47]
	v_mfma_f32_16x16x32_bf16 v[36:39], v[206:209], v[180:183], v[36:39]
	v_mfma_f32_16x16x32_bf16 v[28:31], v[214:217], v[180:183], v[28:31]
	v_mfma_f32_16x16x32_bf16 v[20:23], v[206:209], v[188:191], v[20:23]
	v_mfma_f32_16x16x32_bf16 v[12:15], v[214:217], v[188:191], v[12:15]
	v_mfma_f32_16x16x32_bf16 v[4:7], v[206:209], v[196:199], v[4:7]
	v_mfma_f32_16x16x32_bf16 v[0:3], v[214:217], v[196:199], v[0:3]
	s_setprio 0
	s_add_i32 s44, 0, 0x18000
	v_add_u32_e32 v140, s44, v167
	s_barrier
	ds_read_b128 v[128:131], v140
	ds_read_b128 v[132:135], v140 offset:1024
	ds_read_b128 v[136:139], v140 offset:2048
	ds_read_b128 v[140:143], v140 offset:3072
	ds_read_b128 v[162:165], v169 offset:32768
	ds_read_b128 v[172:175], v169 offset:33792
	ds_read_b128 v[176:179], v169 offset:34816
	ds_read_b128 v[180:183], v169 offset:35840
	ds_read_b128 v[184:187], v169 offset:36864
	ds_read_b128 v[188:191], v169 offset:37888
	ds_read_b128 v[192:195], v169 offset:38912
	ds_read_b128 v[196:199], v169 offset:39936
	s_waitcnt lgkmcnt(8)
	s_waitcnt vmcnt(8)
	s_barrier
; #define PG8_STAGE(bufoff, gbase, voff) do { _Pragma("unroll") for (int _i = 0; _i < 2; ++_i) \
;         __builtin_amdgcn_global_load_lds((const unsigned*)((const char*)(gbase) + (voff)[_i]), (LAS unsigned*)(lds + (bufoff) + ldsw + _i * 8192), 16, 0, 0); } while (0)
; #define PG8_LDA(dst, b, h) do { _Pragma("unroll") for (int m = 0; m < 4; ++m) _Pragma("unroll") for (int k = 0; k < 2; ++k) dst[m][k] = *(const LAS bf16x8*)(lds + PG8_SA(b, h) + aoff + m * 2048 + k * 1024); } while (0)
; #define PG8_LDB(dst, b, h) do { _Pragma("unroll") for (int n = 0; n < 2; ++n) _Pragma("unroll") for (int k = 0; k < 2; ++k) dst[n][k] = *(const LAS bf16x8*)(lds + PG8_SB(b, h) + boff + n * 2048 + k * 1024); } while (0)
; #define PG8_MMA(ai, bj, At, Bt) do { __builtin_amdgcn_s_setprio(1); _Pragma("unroll") for (int m = 0; m < 4; ++m) _Pragma("unroll") for (int n = 0; n < 2; ++n) _Pragma("unroll") for (int k = 0; k < 2; ++k) \
;         acc[ai][bj][m][n] = __builtin_amdgcn_mfma_f32_16x16x32_bf16(Bt[n][k], At[m][k], acc[ai][bj][m][n], 0, 0, 0); __builtin_amdgcn_s_setprio(0); } while (0)
; #define PG8_WAIT_V(n) asm volatile("s_waitcnt vmcnt(" #n ")" ::: "memory")
; #define PG8_WAIT_L(n) asm volatile("s_waitcnt lgkmcnt(" #n ")" ::: "memory")
; #define PG8_BAR __builtin_amdgcn_s_barrier()
; #define PG8_SCHED __builtin_amdgcn_sched_barrier(0)
; template <class Epi, class Sched>
; __device__ __forceinline__ void gemm_phase(LAS unsigned char* lds, const Gemm g, const Sched& S, const Epi& E) {
;     ...
;             PG8_LDB(B0, 1, 0); PG8_SCHED; PG8_LDA(At, 1, 0); PG8_STAGE(PG8_SA(0, 1), a2 + hstep, voffA);
;             PG8_WAIT_L(8); PG8_BAR; PG8_WAIT_L(0); PG8_MMA(0, 0, At, B0); PG8_BAR; PG8_SCHED;
;             PG8_LDB(B1, 1, 1); PG8_STAGE(PG8_SB(1, 0), b3, voffB);
;             PG8_BAR; PG8_WAIT_L(0); PG8_MMA(0, 1, At, B1); PG8_BAR;
;             PG8_LDA(At, 1, 1); PG8_STAGE(PG8_SA(1, 0), a3, voffA);
;             PG8_BAR; PG8_WAIT_L(0); PG8_MMA(1, 0, At, B0); PG8_BAR; PG8_SCHED;
;             PG8_STAGE(PG8_SB(1, 1), b3 + hstep, voffB);
;             PG8_WAIT_V(6); PG8_BAR; PG8_MMA(1, 1, At, B1); PG8_BAR;
;         }
	s_waitcnt lgkmcnt(0)
	s_setprio 1
	s_waitcnt lgkmcnt(0)
	v_mfma_f32_16x16x32_bf16 v[124:127], v[128:131], v[162:165], v[124:127]
	v_mfma_f32_16x16x32_bf16 v[120:123], v[136:139], v[162:165], v[120:123]
	v_mfma_f32_16x16x32_bf16 v[116:119], v[128:131], v[176:179], v[116:119]
	v_mfma_f32_16x16x32_bf16 v[112:115], v[136:139], v[176:179], v[112:115]
	v_mfma_f32_16x16x32_bf16 v[108:111], v[128:131], v[184:187], v[108:111]
	v_mfma_f32_16x16x32_bf16 v[100:103], v[136:139], v[184:187], v[100:103]
	v_mfma_f32_16x16x32_bf16 v[76:79], v[128:131], v[192:195], v[76:79]
	v_mfma_f32_16x16x32_bf16 v[72:75], v[136:139], v[192:195], v[72:75]
	v_mfma_f32_16x16x32_bf16 v[124:127], v[132:135], v[172:175], v[124:127]
	v_mfma_f32_16x16x32_bf16 v[120:123], v[140:143], v[172:175], v[120:123]
	v_mfma_f32_16x16x32_bf16 v[116:119], v[132:135], v[180:183], v[116:119]
	v_mfma_f32_16x16x32_bf16 v[112:115], v[140:143], v[180:183], v[112:115]
	v_mfma_f32_16x16x32_bf16 v[108:111], v[132:135], v[188:191], v[108:111]
	v_mfma_f32_16x16x32_bf16 v[100:103], v[140:143], v[188:191], v[100:103]
	v_mfma_f32_16x16x32_bf16 v[76:79], v[132:135], v[196:199], v[76:79]
	v_mfma_f32_16x16x32_bf16 v[72:75], v[140:143], v[196:199], v[72:75]
	s_setprio 0
	s_barrier
	s_add_i32 s18, 0, 0x1c000
	s_add_i32 s19, s44, s24
	v_add_u32_e32 v160, s18, v167
	s_add_u32 s0, s16, 0x80
	s_addc_u32 s1, s17, 0
	s_mov_b32 m0, s19
	ds_read_b128 v[202:205], v160
	ds_read_b128 v[206:209], v160 offset:1024
	ds_read_b128 v[210:213], v160 offset:2048
	ds_read_b128 v[214:217], v160 offset:3072
	global_load_lds_dwordx4 v146, s[0:1]
	s_add_i32 m0, s19, 0x2000
	s_nop 0
	global_load_lds_dwordx4 v150, s[0:1]
	s_waitcnt vmcnt(8)
	s_barrier
	s_waitcnt lgkmcnt(0)
	s_setprio 1
	s_waitcnt lgkmcnt(0)
	v_mfma_f32_16x16x32_bf16 v[104:107], v[202:205], v[162:165], v[104:107]
	v_mfma_f32_16x16x32_bf16 v[96:99], v[210:213], v[162:165], v[96:99]
	v_mfma_f32_16x16x32_bf16 v[92:95], v[202:205], v[176:179], v[92:95]
	v_mfma_f32_16x16x32_bf16 v[88:91], v[210:213], v[176:179], v[88:91]
	v_mfma_f32_16x16x32_bf16 v[84:87], v[202:205], v[184:187], v[84:87]
	v_mfma_f32_16x16x32_bf16 v[80:83], v[210:213], v[184:187], v[80:83]
	v_mfma_f32_16x16x32_bf16 v[68:71], v[202:205], v[192:195], v[68:71]
	v_mfma_f32_16x16x32_bf16 v[64:67], v[210:213], v[192:195], v[64:67]
	v_mfma_f32_16x16x32_bf16 v[104:107], v[206:209], v[172:175], v[104:107]
	v_mfma_f32_16x16x32_bf16 v[96:99], v[214:217], v[172:175], v[96:99]
	v_mfma_f32_16x16x32_bf16 v[92:95], v[206:209], v[180:183], v[92:95]
	v_mfma_f32_16x16x32_bf16 v[88:91], v[214:217], v[180:183], v[88:91]
	v_mfma_f32_16x16x32_bf16 v[84:87], v[206:209], v[188:191], v[84:87]
	v_mfma_f32_16x16x32_bf16 v[80:83], v[214:217], v[188:191], v[80:83]
	v_mfma_f32_16x16x32_bf16 v[68:71], v[206:209], v[196:199], v[68:71]
	v_mfma_f32_16x16x32_bf16 v[64:67], v[214:217], v[196:199], v[64:67]
	s_setprio 0
	s_mov_b32 m0, s31
	s_mov_b64 s[0:1], 0x80
	v_lshl_add_u64 v[218:219], v[222:223], 0, s[0:1]
	s_barrier
	ds_read_b128 v[162:165], v169 offset:49152
	ds_read_b128 v[172:175], v169 offset:50176
	ds_read_b128 v[176:179], v169 offset:51200
	ds_read_b128 v[180:183], v169 offset:52224
	ds_read_b128 v[184:187], v169 offset:53248
	ds_read_b128 v[188:191], v169 offset:54272
	ds_read_b128 v[192:195], v169 offset:55296
	ds_read_b128 v[196:199], v169 offset:56320
	global_load_lds_dwordx4 v[218:219], off
	v_lshl_add_u64 v[218:219], v[224:225], 0, s[0:1]
	s_mov_b32 m0, s33
	s_nop 0
	global_load_lds_dwordx4 v[218:219], off
	s_barrier
	s_waitcnt lgkmcnt(0)
	s_setprio 1
	s_waitcnt lgkmcnt(0)
	v_mfma_f32_16x16x32_bf16 v[60:63], v[128:131], v[162:165], v[60:63]
	v_mfma_f32_16x16x32_bf16 v[56:59], v[136:139], v[162:165], v[56:59]
	v_mfma_f32_16x16x32_bf16 v[48:51], v[128:131], v[176:179], v[48:51]
	v_mfma_f32_16x16x32_bf16 v[40:43], v[136:139], v[176:179], v[40:43]
	v_mfma_f32_16x16x32_bf16 v[32:35], v[128:131], v[184:187], v[32:35]
	v_mfma_f32_16x16x32_bf16 v[24:27], v[136:139], v[184:187], v[24:27]
	v_mfma_f32_16x16x32_bf16 v[16:19], v[128:131], v[192:195], v[16:19]
	v_mfma_f32_16x16x32_bf16 v[8:11], v[136:139], v[192:195], v[8:11]
	v_mfma_f32_16x16x32_bf16 v[60:63], v[132:135], v[172:175], v[60:63]
	v_mfma_f32_16x16x32_bf16 v[56:59], v[140:143], v[172:175], v[56:59]
	v_mfma_f32_16x16x32_bf16 v[48:51], v[132:135], v[180:183], v[48:51]
	v_mfma_f32_16x16x32_bf16 v[40:43], v[140:143], v[180:183], v[40:43]
	v_mfma_f32_16x16x32_bf16 v[32:35], v[132:135], v[188:191], v[32:35]
	v_mfma_f32_16x16x32_bf16 v[24:27], v[140:143], v[188:191], v[24:27]
	v_mfma_f32_16x16x32_bf16 v[16:19], v[132:135], v[196:199], v[16:19]
	v_mfma_f32_16x16x32_bf16 v[8:11], v[140:143], v[196:199], v[8:11]
	s_setprio 0
	s_barrier
	s_add_u32 s16, s16, 0x80080
	s_addc_u32 s17, s17, 0
	s_add_i32 s18, s18, s24
	s_mov_b32 m0, s18
	s_nop 0
	global_load_lds_dwordx4 v146, s[16:17]
	s_add_i32 m0, s18, 0x2000
	s_nop 0
	global_load_lds_dwordx4 v150, s[16:17]
	s_waitcnt vmcnt(8)
	s_barrier
	s_setprio 1
	v_mfma_f32_16x16x32_bf16 v[52:55], v[202:205], v[162:165], v[52:55]
	v_mfma_f32_16x16x32_bf16 v[44:47], v[210:213], v[162:165], v[44:47]
	v_mfma_f32_16x16x32_bf16 v[36:39], v[202:205], v[176:179], v[36:39]
	v_mfma_f32_16x16x32_bf16 v[28:31], v[210:213], v[176:179], v[28:31]
	v_mfma_f32_16x16x32_bf16 v[20:23], v[202:205], v[184:187], v[20:23]
	v_mfma_f32_16x16x32_bf16 v[12:15], v[210:213], v[184:187], v[12:15]
	v_mfma_f32_16x16x32_bf16 v[4:7], v[202:205], v[192:195], v[4:7]
	v_mfma_f32_16x16x32_bf16 v[0:3], v[210:213], v[192:195], v[0:3]
	v_mfma_f32_16x16x32_bf16 v[52:55], v[206:209], v[172:175], v[52:55]
	v_mfma_f32_16x16x32_bf16 v[44:47], v[214:217], v[172:175], v[44:47]
	v_mfma_f32_16x16x32_bf16 v[36:39], v[206:209], v[180:183], v[36:39]
	v_mfma_f32_16x16x32_bf16 v[28:31], v[214:217], v[180:183], v[28:31]
	v_mfma_f32_16x16x32_bf16 v[20:23], v[206:209], v[188:191], v[20:23]
	v_mfma_f32_16x16x32_bf16 v[12:15], v[214:217], v[188:191], v[12:15]
	v_mfma_f32_16x16x32_bf16 v[4:7], v[206:209], v[196:199], v[4:7]
	v_mfma_f32_16x16x32_bf16 v[0:3], v[214:217], v[196:199], v[0:3]
	s_setprio 0
	s_add_i32 s43, s43, 2
	s_add_u32 s14, s14, 0x100
	s_addc_u32 s15, s15, 0
	s_add_u32 s41, s41, 0x100
	s_addc_u32 s42, s42, 0
	s_cmp_gt_u32 s43, 29
	s_barrier
; __device__ __forceinline__ unsigned cvt_pk_bf16(float lo, float hi) { unsigned r; asm volatile("v_cvt_pk_bf16_f32 %0, %1, %2" : "=v"(r) : "v"(lo), "v"(hi)); return r; }
;     __device__ __forceinline__ void operator()(const AccT& acc, const Unit& u, int wr, int wc, int fr, int fq) const {
;     ...
;         const int row0 = u.pm * 256 + wr * 64 + fr; const int b = u.pn >> 1, ch0 = (u.pn & 1) * 256 + wc * 32 + 8 * fq;
;         const float sg = (fr & 1) ? -1.0f : 1.0f;
;         f32x4 yh[2][2];
; #pragma unroll
;         for (int bj = 0; bj < 2; ++bj)
; #pragma unroll
;             for (int n = 0; n < 2; ++n) yh[bj][n] = *(const f32x4*)(YCH + b * 512 + ch0 + bj * 128 + 4 * n) * sg;
; #pragma unroll
;         for (int ai = 0; ai < 2; ++ai)
; #pragma unroll
;             for (int m = 0; m < 4; ++m) {
;                 const int k = row0 + ai * 128 + m * 16;
; #pragma unroll
;                 for (int bj = 0; bj < 2; ++bj) {
;                     const f32x4 v0 = acc[ai][bj][m][0] + yh[bj][0], v1 = acc[ai][bj][m][1] + yh[bj][1];
;                     u32x4 w; w.x = cvt_pk_bf16(v0[0], v0[1]); w.y = cvt_pk_bf16(v0[2], v0[3]); w.z = cvt_pk_bf16(v1[0], v1[1]); w.w = cvt_pk_bf16(v1[2], v1[3]);
;                     *(u32x4*)(CAT + (size_t)(b * 2048 + k) * CATW + 1024 + ch0 + bj * 128) = w;
;                 }
	s_cbranch_scc0 .LBB0_826
	s_ashr_i32 s5, s38, 1
	s_lshl_b32 s7, s38, 8
	s_lshl_b32 s14, s5, 9
	s_and_b32 s7, s7, 0x100
	s_ashr_i32 s15, s14, 31
	v_mov_b32_e32 v171, v161
	v_mov_b32_e32 v128, v166
	s_or_b32 s7, s7, s30
	s_lshl_b64 s[14:15], s[14:15], 2
	s_add_u32 s14, s48, s14
	v_lshl_add_u32 v164, v128, 3, s7
	s_addc_u32 s15, s49, s15
	v_ashrrev_i32_e32 v165, 31, v164
	v_lshl_add_u64 v[128:129], v[164:165], 2, s[14:15]
	global_load_dwordx4 v[140:143], v[128:129], off
	global_load_dwordx4 v[136:139], v[128:129], off offset:16
	global_load_dwordx4 v[132:135], v[128:129], off offset:512
	s_nop 0
	global_load_dwordx4 v[128:131], v[128:129], off offset:528
	s_lshl_b32 s7, s12, 8
	s_lshl_b32 s5, s5, 11
	s_add_i32 s7, s7, s29
	v_and_b32_e32 v160, 1, v171
	s_add_i32 s7, s7, s5
	v_mov_b64_e32 v[162:163], s[96:97]
	v_cmp_eq_u32_e32 vcc, 0, v160
	v_add_u32_e32 v171, s7, v171
	v_lshlrev_b64 v[164:165], 1, v[164:165]
	v_cndmask_b32_e64 v160, -1.0, 1.0, vcc
	v_mad_i64_i32 v[172:173], s[14:15], v171, s37, v[162:163]
	v_add_u32_e32 v174, 16, v171
	v_lshl_add_u64 v[172:173], v[172:173], 0, v[164:165]
	v_mad_i64_i32 v[174:175], s[14:15], v174, s37, v[162:163]
	v_add_u32_e32 v176, 32, v171
	v_lshl_add_u64 v[174:175], v[174:175], 0, v[164:165]
	v_mad_i64_i32 v[176:177], s[14:15], v176, s37, v[162:163]
	v_lshl_add_u64 v[176:177], v[176:177], 0, v[164:165]
	v_add_u32_e32 v182, 48, v171
	s_and_b64 vcc, exec, s[2:3]
	s_mov_b32 s38, s4
	s_mov_b32 s12, s6
	s_mov_b64 s[16:17], s[10:11]
	s_waitcnt vmcnt(0)
	v_pk_fma_f32 v[126:127], v[142:143], v[160:161], v[126:127] op_sel_hi:[1,0,1]
	v_pk_fma_f32 v[124:125], v[140:141], v[160:161], v[124:125] op_sel_hi:[1,0,1]
	v_pk_fma_f32 v[122:123], v[138:139], v[160:161], v[122:123] op_sel_hi:[1,0,1]
	v_pk_fma_f32 v[180:181], v[128:129], v[160:161], v[80:81] op_sel_hi:[1,0,1]
	v_cvt_pk_bf16_f32 v80, v124, v125
	v_cvt_pk_bf16_f32 v81, v126, v127
	v_pk_fma_f32 v[120:121], v[136:137], v[160:161], v[120:121] op_sel_hi:[1,0,1]
	v_pk_fma_f32 v[106:107], v[134:135], v[160:161], v[106:107] op_sel_hi:[1,0,1]
	v_pk_fma_f32 v[104:105], v[132:133], v[160:161], v[104:105] op_sel_hi:[1,0,1]
	v_pk_fma_f32 v[178:179], v[130:131], v[160:161], v[82:83] op_sel_hi:[1,0,1]
	v_cvt_pk_bf16_f32 v82, v120, v121
	v_cvt_pk_bf16_f32 v83, v122, v123
	global_store_dwordx4 v[172:173], v[80:83], off offset:2048
	v_pk_fma_f32 v[98:99], v[130:131], v[160:161], v[98:99] op_sel_hi:[1,0,1]
	v_pk_fma_f32 v[96:97], v[128:129], v[160:161], v[96:97] op_sel_hi:[1,0,1]
	v_cvt_pk_bf16_f32 v80, v104, v105
	v_cvt_pk_bf16_f32 v81, v106, v107
	v_pk_fma_f32 v[118:119], v[142:143], v[160:161], v[118:119] op_sel_hi:[1,0,1]
	v_pk_fma_f32 v[116:117], v[140:141], v[160:161], v[116:117] op_sel_hi:[1,0,1]
	v_cvt_pk_bf16_f32 v82, v96, v97
	v_cvt_pk_bf16_f32 v83, v98, v99
	global_store_dwordx4 v[172:173], v[80:83], off offset:2304
	v_pk_fma_f32 v[114:115], v[138:139], v[160:161], v[114:115] op_sel_hi:[1,0,1]
	v_pk_fma_f32 v[112:113], v[136:137], v[160:161], v[112:113] op_sel_hi:[1,0,1]
	v_cvt_pk_bf16_f32 v80, v116, v117
	v_cvt_pk_bf16_f32 v81, v118, v119
	v_pk_fma_f32 v[94:95], v[134:135], v[160:161], v[94:95] op_sel_hi:[1,0,1]
	v_pk_fma_f32 v[92:93], v[132:133], v[160:161], v[92:93] op_sel_hi:[1,0,1]
	v_cvt_pk_bf16_f32 v82, v112, v113
	v_cvt_pk_bf16_f32 v83, v114, v115
	global_store_dwordx4 v[174:175], v[80:83], off offset:2048
	v_pk_fma_f32 v[90:91], v[130:131], v[160:161], v[90:91] op_sel_hi:[1,0,1]
	v_pk_fma_f32 v[88:89], v[128:129], v[160:161], v[88:89] op_sel_hi:[1,0,1]
	v_cvt_pk_bf16_f32 v80, v92, v93
	v_cvt_pk_bf16_f32 v81, v94, v95
	v_pk_fma_f32 v[110:111], v[142:143], v[160:161], v[110:111] op_sel_hi:[1,0,1]
	v_pk_fma_f32 v[108:109], v[140:141], v[160:161], v[108:109] op_sel_hi:[1,0,1]
	v_cvt_pk_bf16_f32 v82, v88, v89
	v_cvt_pk_bf16_f32 v83, v90, v91
	global_store_dwordx4 v[174:175], v[80:83], off offset:2304
	v_pk_fma_f32 v[102:103], v[138:139], v[160:161], v[102:103] op_sel_hi:[1,0,1]
	v_pk_fma_f32 v[100:101], v[136:137], v[160:161], v[100:101] op_sel_hi:[1,0,1]
	v_cvt_pk_bf16_f32 v80, v108, v109
	v_cvt_pk_bf16_f32 v81, v110, v111
	v_pk_fma_f32 v[86:87], v[134:135], v[160:161], v[86:87] op_sel_hi:[1,0,1]
	v_pk_fma_f32 v[84:85], v[132:133], v[160:161], v[84:85] op_sel_hi:[1,0,1]
	v_cvt_pk_bf16_f32 v82, v100, v101
	v_cvt_pk_bf16_f32 v83, v102, v103
	global_store_dwordx4 v[176:177], v[80:83], off offset:2048
	v_pk_fma_f32 v[76:77], v[140:141], v[160:161], v[76:77] op_sel_hi:[1,0,1]
	v_pk_fma_f32 v[78:79], v[142:143], v[160:161], v[78:79] op_sel_hi:[1,0,1]
	v_cvt_pk_bf16_f32 v80, v84, v85
	v_cvt_pk_bf16_f32 v81, v86, v87
	v_cvt_pk_bf16_f32 v82, v180, v181
	v_cvt_pk_bf16_f32 v83, v178, v179
	global_store_dwordx4 v[176:177], v[80:83], off offset:2304
	v_pk_fma_f32 v[70:71], v[134:135], v[160:161], v[70:71] op_sel_hi:[1,0,1]
	v_pk_fma_f32 v[68:69], v[132:133], v[160:161], v[68:69] op_sel_hi:[1,0,1]
	v_pk_fma_f32 v[80:81], v[138:139], v[160:161], v[74:75] op_sel_hi:[1,0,1]
	v_pk_fma_f32 v[74:75], v[136:137], v[160:161], v[72:73] op_sel_hi:[1,0,1]
	v_cvt_pk_bf16_f32 v72, v76, v77
	v_mad_i64_i32 v[76:77], s[14:15], v182, s37, v[162:163]
	v_cvt_pk_bf16_f32 v73, v78, v79
; __device__ __forceinline__ unsigned cvt_pk_bf16(float lo, float hi) { unsigned r; asm volatile("v_cvt_pk_bf16_f32 %0, %1, %2" : "=v"(r) : "v"(lo), "v"(hi)); return r; }
; #define PG8_WAIT_V(n) asm volatile("s_waitcnt vmcnt(" #n ")" ::: "memory")
; #define PG8_BAR __builtin_amdgcn_s_barrier()
; template <class Epi, class Sched>
; __device__ __forceinline__ void gemm_phase(LAS unsigned char* lds, const Gemm g, const Sched& S, const Epi& E) {
;     ...
;         if (!has_next) break;
; #pragma unroll
;         for (int a = 0; a < 2; ++a)
; #pragma unroll
;             for (int b = 0; b < 2; ++b)
; #pragma unroll
;                 for (int m = 0; m < 4; ++m)
; #pragma unroll
;                     for (int n = 0; n < 2; ++n) acc[a][b][m][n] = (f32x4){0.f, 0.f, 0.f, 0.f};
;         cur = nxt; cA = nA; cB = nB; ++ui;
;     }
;     PG8_WAIT_V(0);
;     if (wr == 0) PG8_BAR;
;     PG8_BAR;
;     __device__ __forceinline__ void operator()(const AccT& acc, const Unit& u, int wr, int wc, int fr, int fq) const {
;     ...
;         for (int ai = 0; ai < 2; ++ai)
; #pragma unroll
;             for (int m = 0; m < 4; ++m) {
;                 const int k = row0 + ai * 128 + m * 16;
; #pragma unroll
;                 for (int bj = 0; bj < 2; ++bj) {
;                     const f32x4 v0 = acc[ai][bj][m][0] + yh[bj][0], v1 = acc[ai][bj][m][1] + yh[bj][1];
;                     u32x4 w; w.x = cvt_pk_bf16(v0[0], v0[1]); w.y = cvt_pk_bf16(v0[2], v0[3]); w.z = cvt_pk_bf16(v1[0], v1[1]); w.w = cvt_pk_bf16(v1[2], v1[3]);
;                     *(u32x4*)(CAT + (size_t)(b * 2048 + k) * CATW + 1024 + ch0 + bj * 128) = w;
;                 }
	v_lshl_add_u64 v[76:77], v[76:77], 0, v[164:165]
	v_cvt_pk_bf16_f32 v74, v74, v75
	v_cvt_pk_bf16_f32 v75, v80, v81
	global_store_dwordx4 v[76:77], v[72:75], off offset:2048
	v_pk_fma_f32 v[60:61], v[140:141], v[160:161], v[60:61] op_sel_hi:[1,0,1]
	v_pk_fma_f32 v[62:63], v[142:143], v[160:161], v[62:63] op_sel_hi:[1,0,1]
	v_pk_fma_f32 v[72:73], v[130:131], v[160:161], v[66:67] op_sel_hi:[1,0,1]
	v_pk_fma_f32 v[66:67], v[128:129], v[160:161], v[64:65] op_sel_hi:[1,0,1]
	v_cvt_pk_bf16_f32 v64, v68, v69
	v_cvt_pk_bf16_f32 v65, v70, v71
	v_pk_fma_f32 v[54:55], v[134:135], v[160:161], v[54:55] op_sel_hi:[1,0,1]
	v_cvt_pk_bf16_f32 v66, v66, v67
	v_cvt_pk_bf16_f32 v67, v72, v73
	global_store_dwordx4 v[76:77], v[64:67], off offset:2304
	v_pk_fma_f32 v[52:53], v[132:133], v[160:161], v[52:53] op_sel_hi:[1,0,1]
	v_pk_fma_f32 v[38:39], v[134:135], v[160:161], v[38:39] op_sel_hi:[1,0,1]
	v_add_u32_e32 v66, 0x80, v171
	v_pk_fma_f32 v[64:65], v[138:139], v[160:161], v[58:59] op_sel_hi:[1,0,1]
	v_pk_fma_f32 v[58:59], v[136:137], v[160:161], v[56:57] op_sel_hi:[1,0,1]
	v_cvt_pk_bf16_f32 v56, v60, v61
	v_mad_i64_i32 v[60:61], s[14:15], v66, s37, v[162:163]
	v_cvt_pk_bf16_f32 v57, v62, v63
	v_lshl_add_u64 v[60:61], v[60:61], 0, v[164:165]
	v_cvt_pk_bf16_f32 v58, v58, v59
	v_cvt_pk_bf16_f32 v59, v64, v65
	global_store_dwordx4 v[60:61], v[56:59], off offset:2048
	v_pk_fma_f32 v[36:37], v[132:133], v[160:161], v[36:37] op_sel_hi:[1,0,1]
	v_pk_fma_f32 v[22:23], v[134:135], v[160:161], v[22:23] op_sel_hi:[1,0,1]
	v_pk_fma_f32 v[56:57], v[130:131], v[160:161], v[46:47] op_sel_hi:[1,0,1]
	v_pk_fma_f32 v[46:47], v[128:129], v[160:161], v[44:45] op_sel_hi:[1,0,1]
	v_cvt_pk_bf16_f32 v44, v52, v53
	v_cvt_pk_bf16_f32 v45, v54, v55
	v_add_u32_e32 v52, 0x90, v171
	v_cvt_pk_bf16_f32 v46, v46, v47
	v_cvt_pk_bf16_f32 v47, v56, v57
	global_store_dwordx4 v[60:61], v[44:47], off offset:2304
	v_pk_fma_f32 v[20:21], v[132:133], v[160:161], v[20:21] op_sel_hi:[1,0,1]
	v_pk_fma_f32 v[6:7], v[134:135], v[160:161], v[6:7] op_sel_hi:[1,0,1]
	v_pk_fma_f32 v[44:45], v[142:143], v[160:161], v[50:51] op_sel_hi:[1,0,1]
	v_pk_fma_f32 v[46:47], v[140:141], v[160:161], v[48:49] op_sel_hi:[1,0,1]
	v_pk_fma_f32 v[48:49], v[138:139], v[160:161], v[42:43] op_sel_hi:[1,0,1]
	v_pk_fma_f32 v[42:43], v[136:137], v[160:161], v[40:41] op_sel_hi:[1,0,1]
	v_cvt_pk_bf16_f32 v40, v46, v47
	v_cvt_pk_bf16_f32 v41, v44, v45
	v_mad_i64_i32 v[44:45], s[14:15], v52, s37, v[162:163]
	v_lshl_add_u64 v[44:45], v[44:45], 0, v[164:165]
	v_cvt_pk_bf16_f32 v42, v42, v43
	v_cvt_pk_bf16_f32 v43, v48, v49
	global_store_dwordx4 v[44:45], v[40:43], off offset:2048
	v_pk_fma_f32 v[4:5], v[132:133], v[160:161], v[4:5] op_sel_hi:[1,0,1]
	s_nop 0
	v_pk_fma_f32 v[40:41], v[130:131], v[160:161], v[30:31] op_sel_hi:[1,0,1]
	v_pk_fma_f32 v[30:31], v[128:129], v[160:161], v[28:29] op_sel_hi:[1,0,1]
	v_cvt_pk_bf16_f32 v28, v36, v37
	v_cvt_pk_bf16_f32 v29, v38, v39
	v_add_u32_e32 v36, 0xa0, v171
	v_cvt_pk_bf16_f32 v30, v30, v31
	v_cvt_pk_bf16_f32 v31, v40, v41
	global_store_dwordx4 v[44:45], v[28:31], off offset:2304
	s_nop 1
	v_pk_fma_f32 v[28:29], v[142:143], v[160:161], v[34:35] op_sel_hi:[1,0,1]
	v_pk_fma_f32 v[30:31], v[140:141], v[160:161], v[32:33] op_sel_hi:[1,0,1]
	v_pk_fma_f32 v[32:33], v[138:139], v[160:161], v[26:27] op_sel_hi:[1,0,1]
	v_pk_fma_f32 v[26:27], v[136:137], v[160:161], v[24:25] op_sel_hi:[1,0,1]
	v_cvt_pk_bf16_f32 v24, v30, v31
	v_cvt_pk_bf16_f32 v25, v28, v29
	v_mad_i64_i32 v[28:29], s[14:15], v36, s37, v[162:163]
	v_lshl_add_u64 v[28:29], v[28:29], 0, v[164:165]
	v_cvt_pk_bf16_f32 v26, v26, v27
	v_cvt_pk_bf16_f32 v27, v32, v33
	global_store_dwordx4 v[28:29], v[24:27], off offset:2048
	s_nop 1
	v_pk_fma_f32 v[24:25], v[130:131], v[160:161], v[14:15] op_sel_hi:[1,0,1]
	v_pk_fma_f32 v[14:15], v[128:129], v[160:161], v[12:13] op_sel_hi:[1,0,1]
	v_cvt_pk_bf16_f32 v12, v20, v21
	v_cvt_pk_bf16_f32 v13, v22, v23
	v_add_u32_e32 v20, 0xb0, v171
	v_cvt_pk_bf16_f32 v14, v14, v15
	v_cvt_pk_bf16_f32 v15, v24, v25
	global_store_dwordx4 v[28:29], v[12:15], off offset:2304
	s_nop 1
	v_pk_fma_f32 v[12:13], v[142:143], v[160:161], v[18:19] op_sel_hi:[1,0,1]
	v_pk_fma_f32 v[14:15], v[140:141], v[160:161], v[16:17] op_sel_hi:[1,0,1]
	v_pk_fma_f32 v[16:17], v[138:139], v[160:161], v[10:11] op_sel_hi:[1,0,1]
	v_pk_fma_f32 v[10:11], v[136:137], v[160:161], v[8:9] op_sel_hi:[1,0,1]
	v_cvt_pk_bf16_f32 v8, v14, v15
	v_cvt_pk_bf16_f32 v9, v12, v13
	v_mad_i64_i32 v[12:13], s[14:15], v20, s37, v[162:163]
	v_lshl_add_u64 v[12:13], v[12:13], 0, v[164:165]
	v_cvt_pk_bf16_f32 v10, v10, v11
	v_cvt_pk_bf16_f32 v11, v16, v17
	global_store_dwordx4 v[12:13], v[8:11], off offset:2048
	s_mov_b64 s[14:15], s[8:9]
	s_nop 0
	v_pk_fma_f32 v[8:9], v[130:131], v[160:161], v[2:3] op_sel_hi:[1,0,1]
	v_pk_fma_f32 v[2:3], v[128:129], v[160:161], v[0:1] op_sel_hi:[1,0,1]
	v_cvt_pk_bf16_f32 v0, v4, v5
	v_cvt_pk_bf16_f32 v1, v6, v7
	s_nop 0
	v_cvt_pk_bf16_f32 v2, v2, v3
	v_cvt_pk_bf16_f32 v3, v8, v9
	global_store_dwordx4 v[12:13], v[0:3], off offset:2304
	s_cbranch_vccz .LBB0_819
	s_waitcnt vmcnt(0)
	s_cmpk_gt_u32 s20, 0xff
	s_cbranch_scc1 .LBB0_830
	s_barrier

; #define PG8_STAGE(bufoff, gbase, voff) do { _Pragma("unroll") for (int _i = 0; _i < 2; ++_i) \
;         __builtin_amdgcn_global_load_lds((const unsigned*)((const char*)(gbase) + (voff)[_i]), (LAS unsigned*)(lds + (bufoff) + ldsw + _i * 8192), 16, 0, 0); } while (0)
; #define PG8_LDA(dst, b, h) do { _Pragma("unroll") for (int m = 0; m < 4; ++m) _Pragma("unroll") for (int k = 0; k < 2; ++k) dst[m][k] = *(const LAS bf16x8*)(lds + PG8_SA(b, h) + aoff + m * 2048 + k * 1024); } while (0)
; #define PG8_LDB(dst, b, h) do { _Pragma("unroll") for (int n = 0; n < 2; ++n) _Pragma("unroll") for (int k = 0; k < 2; ++k) dst[n][k] = *(const LAS bf16x8*)(lds + PG8_SB(b, h) + boff + n * 2048 + k * 1024); } while (0)
; #define PG8_WAIT_V(n) asm volatile("s_waitcnt vmcnt(" #n ")" ::: "memory")
; #define PG8_WAIT_L(n) asm volatile("s_waitcnt lgkmcnt(" #n ")" ::: "memory")
; #define PG8_BAR __builtin_amdgcn_s_barrier()
; #define PG8_SCHED __builtin_amdgcn_sched_barrier(0)
; template <class Epi, class Sched>
; __device__ __forceinline__ void gemm_phase(LAS unsigned char* lds, const Gemm g, const Sched& S, const Epi& E) {
;     ...
;         const bool has_next = S.next(ui + 1, nxt);
;         const char* nA = has_next ? (const char*)g.A + (size_t)nxt.pm * tstep : cA; const char* nB = has_next ? (const char*)g.Bt + (size_t)nxt.pn * tstep : cB;
;         for (int t = 0; t < nt; t += 2) {
;             const bool last = (t == nt - 2);
;             const char* a1 = cA + (size_t)(t + 1) * kstep;
;             const char* a2 = last ? nA : cA + (size_t)(t + 2) * kstep; const char* b2 = last ? nB : cB + (size_t)(t + 2) * kstep;
;             const char* a3 = a2 + kstep; const char* b3 = b2 + kstep;
;             PG8_LDB(B0, 0, 0); PG8_SCHED; PG8_LDA(At, 0, 0); PG8_STAGE(PG8_SA(1, 1), a1 + hstep, voffA);
;             PG8_WAIT_L(8); PG8_BAR; PG8_WAIT_L(0); PG8_MMA(0, 0, At, B0); PG8_BAR; PG8_SCHED;
;             PG8_LDB(B1, 0, 1); PG8_STAGE(PG8_SB(0, 0), b2, voffB);
;             PG8_BAR; PG8_WAIT_L(0); PG8_MMA(0, 1, At, B1); PG8_BAR;
;             PG8_LDA(At, 0, 1); PG8_STAGE(PG8_SA(0, 0), a2, voffA);
;             PG8_BAR; PG8_WAIT_L(0); PG8_MMA(1, 0, At, B0); PG8_BAR; PG8_SCHED;
;             PG8_STAGE(PG8_SB(0, 1), b2 + hstep, voffB);
;             PG8_WAIT_V(6); PG8_BAR; PG8_MMA(1, 1, At, B1); PG8_BAR;
.LBB0_901:
	s_add_u32 s56, s26, 0x100
	s_addc_u32 s57, s27, 0
	s_mov_b32 s58, -2
	s_waitcnt vmcnt(0)
	ds_read_b128 v[128:131], v237
	ds_read_b128 v[132:135], v237 offset:1024
	ds_read_b128 v[136:139], v237 offset:2048
	ds_read_b128 v[140:143], v237 offset:3072
	s_add_u32 s26, s24, 0x100
	s_addc_u32 s27, s25, 0
	s_cmp_eq_u32 s58, 20
	s_cselect_b32 s31, s5, s27
	s_cselect_b32 s30, s4, s26
	s_cselect_b32 s29, s7, s57
	s_cselect_b32 s28, s6, s56
	v_lshl_add_u64 v[176:177], s[24:25], 0, v[210:211]
	s_add_i32 m0, s38, 0xc000
	ds_read_b128 v[144:147], v238
	ds_read_b128 v[148:151], v238 offset:1024
	ds_read_b128 v[152:155], v238 offset:2048
	ds_read_b128 v[156:159], v238 offset:3072
	ds_read_b128 v[160:163], v238 offset:4096
	ds_read_b128 v[164:167], v238 offset:5120
	ds_read_b128 v[168:171], v238 offset:6144
	ds_read_b128 v[172:175], v238 offset:7168
	global_load_lds_dwordx4 v[176:177], off
	v_lshl_add_u64 v[176:177], s[24:25], 0, v[212:213]
	s_add_i32 m0, s38, 0xe000
	s_nop 0
	global_load_lds_dwordx4 v[176:177], off
	s_waitcnt lgkmcnt(8)
	s_waitcnt vmcnt(8)
	s_barrier
	s_waitcnt lgkmcnt(0)
	s_setprio 1
	s_waitcnt lgkmcnt(0)
	v_mfma_f32_16x16x32_bf16 v[124:127], v[128:131], v[144:147], 0
	v_mfma_f32_16x16x32_bf16 v[120:123], v[136:139], v[144:147], 0
	v_mfma_f32_16x16x32_bf16 v[108:111], v[128:131], v[152:155], 0
	v_mfma_f32_16x16x32_bf16 v[104:107], v[136:139], v[152:155], 0
	v_mfma_f32_16x16x32_bf16 v[92:95], v[128:131], v[160:163], 0
	v_mfma_f32_16x16x32_bf16 v[88:91], v[136:139], v[160:163], 0
	v_mfma_f32_16x16x32_bf16 v[76:79], v[128:131], v[168:171], 0
	v_mfma_f32_16x16x32_bf16 v[72:75], v[136:139], v[168:171], 0
	v_mfma_f32_16x16x32_bf16 v[124:127], v[132:135], v[148:151], v[124:127]
	v_mfma_f32_16x16x32_bf16 v[120:123], v[140:143], v[148:151], v[120:123]
	v_mfma_f32_16x16x32_bf16 v[108:111], v[132:135], v[156:159], v[108:111]
	v_mfma_f32_16x16x32_bf16 v[104:107], v[140:143], v[156:159], v[104:107]
	v_mfma_f32_16x16x32_bf16 v[92:95], v[132:135], v[164:167], v[92:95]
	v_mfma_f32_16x16x32_bf16 v[88:91], v[140:143], v[164:167], v[88:91]
	v_mfma_f32_16x16x32_bf16 v[76:79], v[132:135], v[172:175], v[76:79]
	v_mfma_f32_16x16x32_bf16 v[72:75], v[140:143], v[172:175], v[72:75]
	s_setprio 0
	s_barrier
	s_add_i32 s24, s50, s37
	s_mov_b32 m0, s24
	ds_read_b128 v[176:179], v239
	ds_read_b128 v[180:183], v239 offset:1024
	ds_read_b128 v[184:187], v239 offset:2048
	ds_read_b128 v[188:191], v239 offset:3072
	global_load_lds_dwordx4 v204, s[28:29]
	s_add_i32 m0, s24, 0x2000
	s_nop 0
	global_load_lds_dwordx4 v208, s[28:29]
	s_waitcnt vmcnt(8)
	s_barrier
	s_waitcnt lgkmcnt(0)
	s_setprio 1
	s_waitcnt lgkmcnt(0)
	v_mfma_f32_16x16x32_bf16 v[116:119], v[176:179], v[144:147], 0
	v_mfma_f32_16x16x32_bf16 v[112:115], v[184:187], v[144:147], 0
	v_mfma_f32_16x16x32_bf16 v[100:103], v[176:179], v[152:155], 0
	v_mfma_f32_16x16x32_bf16 v[96:99], v[184:187], v[152:155], 0
	v_mfma_f32_16x16x32_bf16 v[84:87], v[176:179], v[160:163], 0
	v_mfma_f32_16x16x32_bf16 v[80:83], v[184:187], v[160:163], 0
	v_mfma_f32_16x16x32_bf16 v[68:71], v[176:179], v[168:171], 0
	v_mfma_f32_16x16x32_bf16 v[64:67], v[184:187], v[168:171], 0
	v_mfma_f32_16x16x32_bf16 v[116:119], v[180:183], v[148:151], v[116:119]
	v_mfma_f32_16x16x32_bf16 v[112:115], v[188:191], v[148:151], v[112:115]
	v_mfma_f32_16x16x32_bf16 v[100:103], v[180:183], v[156:159], v[100:103]
	v_mfma_f32_16x16x32_bf16 v[96:99], v[188:191], v[156:159], v[96:99]
	v_mfma_f32_16x16x32_bf16 v[84:87], v[180:183], v[164:167], v[84:87]
	v_mfma_f32_16x16x32_bf16 v[80:83], v[188:191], v[164:167], v[80:83]
	v_mfma_f32_16x16x32_bf16 v[68:71], v[180:183], v[172:175], v[68:71]
	v_mfma_f32_16x16x32_bf16 v[64:67], v[188:191], v[172:175], v[64:67]
	s_setprio 0
	s_mov_b32 m0, s38
	v_lshl_add_u64 v[196:197], s[30:31], 0, v[202:203]
	s_barrier
	ds_read_b128 v[144:147], v238 offset:16384
	ds_read_b128 v[148:151], v238 offset:17408
	ds_read_b128 v[152:155], v238 offset:18432
	ds_read_b128 v[156:159], v238 offset:19456
	ds_read_b128 v[160:163], v238 offset:20480
	ds_read_b128 v[164:167], v238 offset:21504
	ds_read_b128 v[168:171], v238 offset:22528
	ds_read_b128 v[172:175], v238 offset:23552
	global_load_lds_dwordx4 v202, s[30:31]
	v_lshl_add_u64 v[198:199], s[30:31], 0, v[206:207]
	s_mov_b32 m0, s39
	s_nop 0
	global_load_lds_dwordx4 v206, s[30:31]
	s_barrier
	s_waitcnt lgkmcnt(0)
	s_setprio 1
	s_waitcnt lgkmcnt(0)
	v_mfma_f32_16x16x32_bf16 v[60:63], v[128:131], v[144:147], 0
	v_mfma_f32_16x16x32_bf16 v[56:59], v[136:139], v[144:147], 0
	v_mfma_f32_16x16x32_bf16 v[44:47], v[128:131], v[152:155], 0
	v_mfma_f32_16x16x32_bf16 v[40:43], v[136:139], v[152:155], 0
	v_mfma_f32_16x16x32_bf16 v[28:31], v[128:131], v[160:163], 0
	v_mfma_f32_16x16x32_bf16 v[24:27], v[136:139], v[160:163], 0
	v_mfma_f32_16x16x32_bf16 v[12:15], v[128:131], v[168:171], 0
	v_mfma_f32_16x16x32_bf16 v[8:11], v[136:139], v[168:171], 0
	v_mfma_f32_16x16x32_bf16 v[60:63], v[132:135], v[148:151], v[60:63]
	v_mfma_f32_16x16x32_bf16 v[56:59], v[140:143], v[148:151], v[56:59]
	v_mfma_f32_16x16x32_bf16 v[44:47], v[132:135], v[156:159], v[44:47]
	v_mfma_f32_16x16x32_bf16 v[40:43], v[140:143], v[156:159], v[40:43]
	v_mfma_f32_16x16x32_bf16 v[28:31], v[132:135], v[164:167], v[28:31]
	v_mfma_f32_16x16x32_bf16 v[24:27], v[140:143], v[164:167], v[24:27]
	v_mfma_f32_16x16x32_bf16 v[12:15], v[132:135], v[172:175], v[12:15]
	v_mfma_f32_16x16x32_bf16 v[8:11], v[140:143], v[172:175], v[8:11]
	s_setprio 0
	s_barrier
; #define PG8_STAGE(bufoff, gbase, voff) do { _Pragma("unroll") for (int _i = 0; _i < 2; ++_i) \
;         __builtin_amdgcn_global_load_lds((const unsigned*)((const char*)(gbase) + (voff)[_i]), (LAS unsigned*)(lds + (bufoff) + ldsw + _i * 8192), 16, 0, 0); } while (0)
; #define PG8_LDA(dst, b, h) do { _Pragma("unroll") for (int m = 0; m < 4; ++m) _Pragma("unroll") for (int k = 0; k < 2; ++k) dst[m][k] = *(const LAS bf16x8*)(lds + PG8_SA(b, h) + aoff + m * 2048 + k * 1024); } while (0)
; #define PG8_LDB(dst, b, h) do { _Pragma("unroll") for (int n = 0; n < 2; ++n) _Pragma("unroll") for (int k = 0; k < 2; ++k) dst[n][k] = *(const LAS bf16x8*)(lds + PG8_SB(b, h) + boff + n * 2048 + k * 1024); } while (0)
; #define PG8_MMA(ai, bj, At, Bt) do { __builtin_amdgcn_s_setprio(1); _Pragma("unroll") for (int m = 0; m < 4; ++m) _Pragma("unroll") for (int n = 0; n < 2; ++n) _Pragma("unroll") for (int k = 0; k < 2; ++k) \
;         acc[ai][bj][m][n] = __builtin_amdgcn_mfma_f32_16x16x32_bf16(Bt[n][k], At[m][k], acc[ai][bj][m][n], 0, 0, 0); __builtin_amdgcn_s_setprio(0); } while (0)
; #define PG8_WAIT_V(n) asm volatile("s_waitcnt vmcnt(" #n ")" ::: "memory")
; #define PG8_WAIT_L(n) asm volatile("s_waitcnt lgkmcnt(" #n ")" ::: "memory")
; #define PG8_BAR __builtin_amdgcn_s_barrier()
; #define PG8_SCHED __builtin_amdgcn_sched_barrier(0)
; template <class Epi, class Sched>
; __device__ __forceinline__ void gemm_phase(LAS unsigned char* lds, const Gemm g, const Sched& S, const Epi& E) {
;     ...
;             PG8_LDB(B1, 0, 1); PG8_STAGE(PG8_SB(0, 0), b2, voffB);
;             PG8_BAR; PG8_WAIT_L(0); PG8_MMA(0, 1, At, B1); PG8_BAR;
;             PG8_LDA(At, 0, 1); PG8_STAGE(PG8_SA(0, 0), a2, voffA);
;             PG8_BAR; PG8_WAIT_L(0); PG8_MMA(1, 0, At, B0); PG8_BAR; PG8_SCHED;
;             PG8_STAGE(PG8_SB(0, 1), b2 + hstep, voffB);
;             PG8_WAIT_V(6); PG8_BAR; PG8_MMA(1, 1, At, B1); PG8_BAR;
;             PG8_LDB(B0, 1, 0); PG8_SCHED; PG8_LDA(At, 1, 0); PG8_STAGE(PG8_SA(0, 1), a2 + hstep, voffA);
;             PG8_WAIT_L(8); PG8_BAR; PG8_WAIT_L(0); PG8_MMA(0, 0, At, B0); PG8_BAR; PG8_SCHED;
;             PG8_LDB(B1, 1, 1); PG8_STAGE(PG8_SB(1, 0), b3, voffB);
;             PG8_BAR; PG8_WAIT_L(0); PG8_MMA(0, 1, At, B1); PG8_BAR;
;             PG8_LDA(At, 1, 1); PG8_STAGE(PG8_SA(1, 0), a3, voffA);
	s_add_u32 s24, s28, 0x60000
	s_addc_u32 s25, s29, 0
	s_add_i32 s59, s51, s37
	s_mov_b32 m0, s59
	s_nop 0
	global_load_lds_dwordx4 v204, s[24:25]
	s_add_i32 m0, s59, 0x2000
	s_nop 0
	global_load_lds_dwordx4 v208, s[24:25]
	s_add_u32 s24, s30, 0x60000
	s_addc_u32 s25, s31, 0
	s_mov_b32 m0, s40
	s_nop 0
	global_load_lds_dwordx4 v202, s[24:25]
	s_mov_b32 m0, s41
	s_nop 0
	global_load_lds_dwordx4 v206, s[24:25]
	s_waitcnt vmcnt(10)
	s_barrier
	s_setprio 1
	v_mfma_f32_16x16x32_bf16 v[52:55], v[176:179], v[144:147], 0
	v_mfma_f32_16x16x32_bf16 v[48:51], v[184:187], v[144:147], 0
	v_mfma_f32_16x16x32_bf16 v[36:39], v[176:179], v[152:155], 0
	v_mfma_f32_16x16x32_bf16 v[32:35], v[184:187], v[152:155], 0
	v_mfma_f32_16x16x32_bf16 v[20:23], v[176:179], v[160:163], 0
	v_mfma_f32_16x16x32_bf16 v[16:19], v[184:187], v[160:163], 0
	v_mfma_f32_16x16x32_bf16 v[4:7], v[176:179], v[168:171], 0
	v_mfma_f32_16x16x32_bf16 v[0:3], v[184:187], v[168:171], 0
	v_mfma_f32_16x16x32_bf16 v[52:55], v[180:183], v[148:151], v[52:55]
	v_mfma_f32_16x16x32_bf16 v[48:51], v[188:191], v[148:151], v[48:51]
	v_mfma_f32_16x16x32_bf16 v[36:39], v[180:183], v[156:159], v[36:39]
	v_mfma_f32_16x16x32_bf16 v[32:35], v[188:191], v[156:159], v[32:35]
	v_mfma_f32_16x16x32_bf16 v[20:23], v[180:183], v[164:167], v[20:23]
	v_mfma_f32_16x16x32_bf16 v[16:19], v[188:191], v[164:167], v[16:19]
	v_mfma_f32_16x16x32_bf16 v[4:7], v[180:183], v[172:175], v[4:7]
	v_mfma_f32_16x16x32_bf16 v[0:3], v[188:191], v[172:175], v[0:3]
	s_setprio 0
	s_add_i32 s59, 0, 0x18000
	v_add_u32_e32 v140, s59, v236
	s_barrier
	ds_read_b128 v[128:131], v140
	ds_read_b128 v[132:135], v140 offset:1024
	ds_read_b128 v[136:139], v140 offset:2048
	ds_read_b128 v[140:143], v140 offset:3072
	ds_read_b128 v[144:147], v238 offset:32768
	ds_read_b128 v[148:151], v238 offset:33792
	ds_read_b128 v[152:155], v238 offset:34816
	ds_read_b128 v[156:159], v238 offset:35840
	ds_read_b128 v[160:163], v238 offset:36864
	ds_read_b128 v[164:167], v238 offset:37888
	ds_read_b128 v[168:171], v238 offset:38912
	ds_read_b128 v[172:175], v238 offset:39936
	s_waitcnt lgkmcnt(8)
	s_waitcnt vmcnt(8)
	s_barrier
	s_waitcnt lgkmcnt(0)
	s_setprio 1
	s_waitcnt lgkmcnt(0)
	v_mfma_f32_16x16x32_bf16 v[124:127], v[128:131], v[144:147], v[124:127]
	v_mfma_f32_16x16x32_bf16 v[120:123], v[136:139], v[144:147], v[120:123]
	v_mfma_f32_16x16x32_bf16 v[108:111], v[128:131], v[152:155], v[108:111]
	v_mfma_f32_16x16x32_bf16 v[104:107], v[136:139], v[152:155], v[104:107]
	v_mfma_f32_16x16x32_bf16 v[92:95], v[128:131], v[160:163], v[92:95]
	v_mfma_f32_16x16x32_bf16 v[88:91], v[136:139], v[160:163], v[88:91]
	v_mfma_f32_16x16x32_bf16 v[76:79], v[128:131], v[168:171], v[76:79]
	v_mfma_f32_16x16x32_bf16 v[72:75], v[136:139], v[168:171], v[72:75]
	v_mfma_f32_16x16x32_bf16 v[124:127], v[132:135], v[148:151], v[124:127]
	v_mfma_f32_16x16x32_bf16 v[120:123], v[140:143], v[148:151], v[120:123]
	v_mfma_f32_16x16x32_bf16 v[108:111], v[132:135], v[156:159], v[108:111]
	v_mfma_f32_16x16x32_bf16 v[104:107], v[140:143], v[156:159], v[104:107]
	v_mfma_f32_16x16x32_bf16 v[92:95], v[132:135], v[164:167], v[92:95]
	v_mfma_f32_16x16x32_bf16 v[88:91], v[140:143], v[164:167], v[88:91]
	v_mfma_f32_16x16x32_bf16 v[76:79], v[132:135], v[172:175], v[76:79]
	v_mfma_f32_16x16x32_bf16 v[72:75], v[140:143], v[172:175], v[72:75]
	s_setprio 0
	s_barrier
	s_add_i32 s30, 0, 0x1c000
	s_add_i32 s24, s59, s37
	v_add_u32_e32 v188, s30, v236
	s_add_u32 s0, s28, 0x80
	s_addc_u32 s1, s29, 0
	s_mov_b32 m0, s24
	ds_read_b128 v[176:179], v188
	ds_read_b128 v[180:183], v188 offset:1024
	ds_read_b128 v[184:187], v188 offset:2048
	ds_read_b128 v[188:191], v188 offset:3072
	global_load_lds_dwordx4 v204, s[0:1]
	s_add_i32 m0, s24, 0x2000
	s_nop 0
	global_load_lds_dwordx4 v208, s[0:1]
	s_waitcnt vmcnt(8)
	s_barrier
	s_waitcnt lgkmcnt(0)
	s_setprio 1
	s_waitcnt lgkmcnt(0)
	v_mfma_f32_16x16x32_bf16 v[116:119], v[176:179], v[144:147], v[116:119]
	v_mfma_f32_16x16x32_bf16 v[112:115], v[184:187], v[144:147], v[112:115]
	v_mfma_f32_16x16x32_bf16 v[100:103], v[176:179], v[152:155], v[100:103]
	v_mfma_f32_16x16x32_bf16 v[96:99], v[184:187], v[152:155], v[96:99]
	v_mfma_f32_16x16x32_bf16 v[84:87], v[176:179], v[160:163], v[84:87]
	v_mfma_f32_16x16x32_bf16 v[80:83], v[184:187], v[160:163], v[80:83]
	v_mfma_f32_16x16x32_bf16 v[68:71], v[176:179], v[168:171], v[68:71]
	v_mfma_f32_16x16x32_bf16 v[64:67], v[184:187], v[168:171], v[64:67]
	v_mfma_f32_16x16x32_bf16 v[116:119], v[180:183], v[148:151], v[116:119]
	v_mfma_f32_16x16x32_bf16 v[112:115], v[188:191], v[148:151], v[112:115]
	v_mfma_f32_16x16x32_bf16 v[100:103], v[180:183], v[156:159], v[100:103]
	v_mfma_f32_16x16x32_bf16 v[96:99], v[188:191], v[156:159], v[96:99]
	v_mfma_f32_16x16x32_bf16 v[84:87], v[180:183], v[164:167], v[84:87]
	v_mfma_f32_16x16x32_bf16 v[80:83], v[188:191], v[164:167], v[80:83]
	v_mfma_f32_16x16x32_bf16 v[68:71], v[180:183], v[172:175], v[68:71]
	v_mfma_f32_16x16x32_bf16 v[64:67], v[188:191], v[172:175], v[64:67]
	s_setprio 0
	s_mov_b32 m0, s47
	s_mov_b64 s[0:1], 0x80
	v_lshl_add_u64 v[192:193], v[196:197], 0, s[0:1]
	s_barrier
	ds_read_b128 v[144:147], v238 offset:49152
	ds_read_b128 v[148:151], v238 offset:50176
	ds_read_b128 v[152:155], v238 offset:51200
	ds_read_b128 v[156:159], v238 offset:52224
	ds_read_b128 v[160:163], v238 offset:53248
	ds_read_b128 v[164:167], v238 offset:54272
	ds_read_b128 v[168:171], v238 offset:55296
	ds_read_b128 v[172:175], v238 offset:56320
	global_load_lds_dwordx4 v[192:193], off
	v_lshl_add_u64 v[192:193], v[198:199], 0, s[0:1]
	s_mov_b32 m0, s48
	s_nop 0
	global_load_lds_dwordx4 v[192:193], off
	s_barrier
; #define PG8_STAGE(bufoff, gbase, voff) do { _Pragma("unroll") for (int _i = 0; _i < 2; ++_i) \
;         __builtin_amdgcn_global_load_lds((const unsigned*)((const char*)(gbase) + (voff)[_i]), (LAS unsigned*)(lds + (bufoff) + ldsw + _i * 8192), 16, 0, 0); } while (0)
; #define PG8_LDA(dst, b, h) do { _Pragma("unroll") for (int m = 0; m < 4; ++m) _Pragma("unroll") for (int k = 0; k < 2; ++k) dst[m][k] = *(const LAS bf16x8*)(lds + PG8_SA(b, h) + aoff + m * 2048 + k * 1024); } while (0)
; #define PG8_LDB(dst, b, h) do { _Pragma("unroll") for (int n = 0; n < 2; ++n) _Pragma("unroll") for (int k = 0; k < 2; ++k) dst[n][k] = *(const LAS bf16x8*)(lds + PG8_SB(b, h) + boff + n * 2048 + k * 1024); } while (0)
; #define PG8_WAIT_V(n) asm volatile("s_waitcnt vmcnt(" #n ")" ::: "memory")
; #define PG8_WAIT_L(n) asm volatile("s_waitcnt lgkmcnt(" #n ")" ::: "memory")
; #define PG8_BAR __builtin_amdgcn_s_barrier()
; #define PG8_SCHED __builtin_amdgcn_sched_barrier(0)
; template <class Epi, class Sched>
; __device__ __forceinline__ void gemm_phase(LAS unsigned char* lds, const Gemm g, const Sched& S, const Epi& E) {
;     ...
;             PG8_LDB(B0, 0, 0); PG8_SCHED; PG8_LDA(At, 0, 0); PG8_STAGE(PG8_SA(1, 1), a1 + hstep, voffA);
;             PG8_WAIT_L(8); PG8_BAR; PG8_WAIT_L(0); PG8_MMA(0, 0, At, B0); PG8_BAR; PG8_SCHED;
;             PG8_LDB(B1, 0, 1); PG8_STAGE(PG8_SB(0, 0), b2, voffB);
;             PG8_BAR; PG8_WAIT_L(0); PG8_MMA(0, 1, At, B1); PG8_BAR;
;             PG8_LDA(At, 0, 1); PG8_STAGE(PG8_SA(0, 0), a2, voffA);
;             PG8_BAR; PG8_WAIT_L(0); PG8_MMA(1, 0, At, B0); PG8_BAR; PG8_SCHED;
;             PG8_STAGE(PG8_SB(0, 1), b2 + hstep, voffB);
;             PG8_WAIT_V(6); PG8_BAR; PG8_MMA(1, 1, At, B1); PG8_BAR;
;             PG8_LDB(B0, 1, 0); PG8_SCHED; PG8_LDA(At, 1, 0); PG8_STAGE(PG8_SA(0, 1), a2 + hstep, voffA);
;             PG8_WAIT_L(8); PG8_BAR; PG8_WAIT_L(0); PG8_MMA(0, 0, At, B0); PG8_BAR; PG8_SCHED;
;             PG8_LDB(B1, 1, 1); PG8_STAGE(PG8_SB(1, 0), b3, voffB);
;             PG8_BAR; PG8_WAIT_L(0); PG8_MMA(0, 1, At, B1); PG8_BAR;
;             PG8_LDA(At, 1, 1); PG8_STAGE(PG8_SA(1, 0), a3, voffA);
;             PG8_BAR; PG8_WAIT_L(0); PG8_MMA(1, 0, At, B0); PG8_BAR; PG8_SCHED;
;             PG8_STAGE(PG8_SB(1, 1), b3 + hstep, voffB);
;             PG8_WAIT_V(6); PG8_BAR; PG8_MMA(1, 1, At, B1); PG8_BAR;
	s_waitcnt lgkmcnt(0)
	s_setprio 1
	s_waitcnt lgkmcnt(0)
	v_mfma_f32_16x16x32_bf16 v[60:63], v[128:131], v[144:147], v[60:63]
	v_mfma_f32_16x16x32_bf16 v[56:59], v[136:139], v[144:147], v[56:59]
	v_mfma_f32_16x16x32_bf16 v[44:47], v[128:131], v[152:155], v[44:47]
	v_mfma_f32_16x16x32_bf16 v[40:43], v[136:139], v[152:155], v[40:43]
	v_mfma_f32_16x16x32_bf16 v[28:31], v[128:131], v[160:163], v[28:31]
	v_mfma_f32_16x16x32_bf16 v[24:27], v[136:139], v[160:163], v[24:27]
	v_mfma_f32_16x16x32_bf16 v[12:15], v[128:131], v[168:171], v[12:15]
	v_mfma_f32_16x16x32_bf16 v[8:11], v[136:139], v[168:171], v[8:11]
	v_mfma_f32_16x16x32_bf16 v[60:63], v[132:135], v[148:151], v[60:63]
	v_mfma_f32_16x16x32_bf16 v[56:59], v[140:143], v[148:151], v[56:59]
	v_mfma_f32_16x16x32_bf16 v[44:47], v[132:135], v[156:159], v[44:47]
	v_mfma_f32_16x16x32_bf16 v[40:43], v[140:143], v[156:159], v[40:43]
	v_mfma_f32_16x16x32_bf16 v[28:31], v[132:135], v[164:167], v[28:31]
	v_mfma_f32_16x16x32_bf16 v[24:27], v[140:143], v[164:167], v[24:27]
	v_mfma_f32_16x16x32_bf16 v[12:15], v[132:135], v[172:175], v[12:15]
	v_mfma_f32_16x16x32_bf16 v[8:11], v[140:143], v[172:175], v[8:11]
	s_setprio 0
	s_barrier
	s_add_u32 s24, s28, 0x60080
	s_addc_u32 s25, s29, 0
	s_add_i32 s28, s30, s37
	s_mov_b32 m0, s28
	s_nop 0
	global_load_lds_dwordx4 v204, s[24:25]
	s_add_i32 m0, s28, 0x2000
	s_nop 0
	global_load_lds_dwordx4 v208, s[24:25]
	s_waitcnt vmcnt(8)
	s_barrier
	s_setprio 1
	v_mfma_f32_16x16x32_bf16 v[52:55], v[176:179], v[144:147], v[52:55]
	v_mfma_f32_16x16x32_bf16 v[48:51], v[184:187], v[144:147], v[48:51]
	v_mfma_f32_16x16x32_bf16 v[36:39], v[176:179], v[152:155], v[36:39]
	v_mfma_f32_16x16x32_bf16 v[32:35], v[184:187], v[152:155], v[32:35]
	v_mfma_f32_16x16x32_bf16 v[20:23], v[176:179], v[160:163], v[20:23]
	v_mfma_f32_16x16x32_bf16 v[16:19], v[184:187], v[160:163], v[16:19]
	v_mfma_f32_16x16x32_bf16 v[4:7], v[176:179], v[168:171], v[4:7]
	v_mfma_f32_16x16x32_bf16 v[0:3], v[184:187], v[168:171], v[0:3]
	v_mfma_f32_16x16x32_bf16 v[52:55], v[180:183], v[148:151], v[52:55]
	v_mfma_f32_16x16x32_bf16 v[48:51], v[188:191], v[148:151], v[48:51]
	v_mfma_f32_16x16x32_bf16 v[36:39], v[180:183], v[156:159], v[36:39]
	v_mfma_f32_16x16x32_bf16 v[32:35], v[188:191], v[156:159], v[32:35]
	v_mfma_f32_16x16x32_bf16 v[20:23], v[180:183], v[164:167], v[20:23]
	v_mfma_f32_16x16x32_bf16 v[16:19], v[188:191], v[164:167], v[16:19]
	v_mfma_f32_16x16x32_bf16 v[4:7], v[180:183], v[172:175], v[4:7]
	v_mfma_f32_16x16x32_bf16 v[0:3], v[188:191], v[172:175], v[0:3]
	s_setprio 0
	s_add_i32 s58, s58, 2
	s_add_u32 s56, s56, 0x100
	s_addc_u32 s57, s57, 0
	s_cmp_gt_u32 s58, 21
	s_mov_b64 s[24:25], s[26:27]
	s_barrier
.LBB0_902:
	ds_read_b128 v[128:131], v237
	ds_read_b128 v[132:135], v237 offset:1024
	ds_read_b128 v[136:139], v237 offset:2048
	ds_read_b128 v[140:143], v237 offset:3072
	s_add_u32 s26, s24, 0x100
	s_addc_u32 s27, s25, 0
	s_cmp_eq_u32 s58, 20
	s_cselect_b32 s31, s5, s27
	s_cselect_b32 s30, s4, s26
	s_cselect_b32 s29, s7, s57
	s_cselect_b32 s28, s6, s56
	v_lshl_add_u64 v[176:177], s[24:25], 0, v[210:211]
	s_add_i32 m0, s38, 0xc000
	ds_read_b128 v[144:147], v238
	ds_read_b128 v[148:151], v238 offset:1024
	ds_read_b128 v[152:155], v238 offset:2048
	ds_read_b128 v[156:159], v238 offset:3072
	ds_read_b128 v[160:163], v238 offset:4096
	ds_read_b128 v[164:167], v238 offset:5120
	ds_read_b128 v[168:171], v238 offset:6144
	ds_read_b128 v[172:175], v238 offset:7168
	global_load_lds_dwordx4 v[176:177], off
	v_lshl_add_u64 v[176:177], s[24:25], 0, v[212:213]
	s_add_i32 m0, s38, 0xe000
	s_nop 0
	global_load_lds_dwordx4 v[176:177], off
	s_waitcnt lgkmcnt(8)
	s_waitcnt vmcnt(8)
	s_barrier
	s_waitcnt lgkmcnt(0)
	s_setprio 1
	s_waitcnt lgkmcnt(0)
	v_mfma_f32_16x16x32_bf16 v[124:127], v[128:131], v[144:147], v[124:127]
	v_mfma_f32_16x16x32_bf16 v[120:123], v[136:139], v[144:147], v[120:123]
	v_mfma_f32_16x16x32_bf16 v[108:111], v[128:131], v[152:155], v[108:111]
	v_mfma_f32_16x16x32_bf16 v[104:107], v[136:139], v[152:155], v[104:107]
	v_mfma_f32_16x16x32_bf16 v[92:95], v[128:131], v[160:163], v[92:95]
	v_mfma_f32_16x16x32_bf16 v[88:91], v[136:139], v[160:163], v[88:91]
	v_mfma_f32_16x16x32_bf16 v[76:79], v[128:131], v[168:171], v[76:79]
	v_mfma_f32_16x16x32_bf16 v[72:75], v[136:139], v[168:171], v[72:75]
	v_mfma_f32_16x16x32_bf16 v[124:127], v[132:135], v[148:151], v[124:127]
	v_mfma_f32_16x16x32_bf16 v[120:123], v[140:143], v[148:151], v[120:123]
	v_mfma_f32_16x16x32_bf16 v[108:111], v[132:135], v[156:159], v[108:111]
	v_mfma_f32_16x16x32_bf16 v[104:107], v[140:143], v[156:159], v[104:107]
	v_mfma_f32_16x16x32_bf16 v[92:95], v[132:135], v[164:167], v[92:95]
	v_mfma_f32_16x16x32_bf16 v[88:91], v[140:143], v[164:167], v[88:91]
	v_mfma_f32_16x16x32_bf16 v[76:79], v[132:135], v[172:175], v[76:79]
	v_mfma_f32_16x16x32_bf16 v[72:75], v[140:143], v[172:175], v[72:75]
	s_setprio 0
	s_barrier
	s_add_i32 s24, s50, s37
	s_mov_b32 m0, s24
	ds_read_b128 v[176:179], v239
	ds_read_b128 v[180:183], v239 offset:1024
	ds_read_b128 v[184:187], v239 offset:2048
	ds_read_b128 v[188:191], v239 offset:3072
	global_load_lds_dwordx4 v204, s[28:29]
	s_add_i32 m0, s24, 0x2000
	s_nop 0
	global_load_lds_dwordx4 v208, s[28:29]
	s_waitcnt vmcnt(8)
	s_barrier
; #define PG8_STAGE(bufoff, gbase, voff) do { _Pragma("unroll") for (int _i = 0; _i < 2; ++_i) \
;         __builtin_amdgcn_global_load_lds((const unsigned*)((const char*)(gbase) + (voff)[_i]), (LAS unsigned*)(lds + (bufoff) + ldsw + _i * 8192), 16, 0, 0); } while (0)
; #define PG8_LDA(dst, b, h) do { _Pragma("unroll") for (int m = 0; m < 4; ++m) _Pragma("unroll") for (int k = 0; k < 2; ++k) dst[m][k] = *(const LAS bf16x8*)(lds + PG8_SA(b, h) + aoff + m * 2048 + k * 1024); } while (0)
; #define PG8_LDB(dst, b, h) do { _Pragma("unroll") for (int n = 0; n < 2; ++n) _Pragma("unroll") for (int k = 0; k < 2; ++k) dst[n][k] = *(const LAS bf16x8*)(lds + PG8_SB(b, h) + boff + n * 2048 + k * 1024); } while (0)
; #define PG8_MMA(ai, bj, At, Bt) do { __builtin_amdgcn_s_setprio(1); _Pragma("unroll") for (int m = 0; m < 4; ++m) _Pragma("unroll") for (int n = 0; n < 2; ++n) _Pragma("unroll") for (int k = 0; k < 2; ++k) \
;         acc[ai][bj][m][n] = __builtin_amdgcn_mfma_f32_16x16x32_bf16(Bt[n][k], At[m][k], acc[ai][bj][m][n], 0, 0, 0); __builtin_amdgcn_s_setprio(0); } while (0)
; #define PG8_WAIT_V(n) asm volatile("s_waitcnt vmcnt(" #n ")" ::: "memory")
; #define PG8_WAIT_L(n) asm volatile("s_waitcnt lgkmcnt(" #n ")" ::: "memory")
; #define PG8_BAR __builtin_amdgcn_s_barrier()
; #define PG8_SCHED __builtin_amdgcn_sched_barrier(0)
; template <class Epi, class Sched>
; __device__ __forceinline__ void gemm_phase(LAS unsigned char* lds, const Gemm g, const Sched& S, const Epi& E) {
;     ...
;             PG8_BAR; PG8_WAIT_L(0); PG8_MMA(0, 1, At, B1); PG8_BAR;
;             PG8_LDA(At, 0, 1); PG8_STAGE(PG8_SA(0, 0), a2, voffA);
;             PG8_BAR; PG8_WAIT_L(0); PG8_MMA(1, 0, At, B0); PG8_BAR; PG8_SCHED;
;             PG8_STAGE(PG8_SB(0, 1), b2 + hstep, voffB);
;             PG8_WAIT_V(6); PG8_BAR; PG8_MMA(1, 1, At, B1); PG8_BAR;
;             PG8_LDB(B0, 1, 0); PG8_SCHED; PG8_LDA(At, 1, 0); PG8_STAGE(PG8_SA(0, 1), a2 + hstep, voffA);
;             PG8_WAIT_L(8); PG8_BAR; PG8_WAIT_L(0); PG8_MMA(0, 0, At, B0); PG8_BAR; PG8_SCHED;
;             PG8_LDB(B1, 1, 1); PG8_STAGE(PG8_SB(1, 0), b3, voffB);
;             PG8_BAR; PG8_WAIT_L(0); PG8_MMA(0, 1, At, B1); PG8_BAR;
;             PG8_LDA(At, 1, 1); PG8_STAGE(PG8_SA(1, 0), a3, voffA);
	s_waitcnt lgkmcnt(0)
	s_setprio 1
	s_waitcnt lgkmcnt(0)
	v_mfma_f32_16x16x32_bf16 v[116:119], v[176:179], v[144:147], v[116:119]
	v_mfma_f32_16x16x32_bf16 v[112:115], v[184:187], v[144:147], v[112:115]
	v_mfma_f32_16x16x32_bf16 v[100:103], v[176:179], v[152:155], v[100:103]
	v_mfma_f32_16x16x32_bf16 v[96:99], v[184:187], v[152:155], v[96:99]
	v_mfma_f32_16x16x32_bf16 v[84:87], v[176:179], v[160:163], v[84:87]
	v_mfma_f32_16x16x32_bf16 v[80:83], v[184:187], v[160:163], v[80:83]
	v_mfma_f32_16x16x32_bf16 v[68:71], v[176:179], v[168:171], v[68:71]
	v_mfma_f32_16x16x32_bf16 v[64:67], v[184:187], v[168:171], v[64:67]
	v_mfma_f32_16x16x32_bf16 v[116:119], v[180:183], v[148:151], v[116:119]
	v_mfma_f32_16x16x32_bf16 v[112:115], v[188:191], v[148:151], v[112:115]
	v_mfma_f32_16x16x32_bf16 v[100:103], v[180:183], v[156:159], v[100:103]
	v_mfma_f32_16x16x32_bf16 v[96:99], v[188:191], v[156:159], v[96:99]
	v_mfma_f32_16x16x32_bf16 v[84:87], v[180:183], v[164:167], v[84:87]
	v_mfma_f32_16x16x32_bf16 v[80:83], v[188:191], v[164:167], v[80:83]
	v_mfma_f32_16x16x32_bf16 v[68:71], v[180:183], v[172:175], v[68:71]
	v_mfma_f32_16x16x32_bf16 v[64:67], v[188:191], v[172:175], v[64:67]
	s_setprio 0
	s_mov_b32 m0, s38
	v_lshl_add_u64 v[196:197], s[30:31], 0, v[202:203]
	s_barrier
	ds_read_b128 v[144:147], v238 offset:16384
	ds_read_b128 v[148:151], v238 offset:17408
	ds_read_b128 v[152:155], v238 offset:18432
	ds_read_b128 v[156:159], v238 offset:19456
	ds_read_b128 v[160:163], v238 offset:20480
	ds_read_b128 v[164:167], v238 offset:21504
	ds_read_b128 v[168:171], v238 offset:22528
	ds_read_b128 v[172:175], v238 offset:23552
	global_load_lds_dwordx4 v202, s[30:31]
	v_lshl_add_u64 v[198:199], s[30:31], 0, v[206:207]
	s_mov_b32 m0, s39
	s_nop 0
	global_load_lds_dwordx4 v206, s[30:31]
	s_barrier
	s_waitcnt lgkmcnt(0)
	s_setprio 1
	s_waitcnt lgkmcnt(0)
	v_mfma_f32_16x16x32_bf16 v[60:63], v[128:131], v[144:147], v[60:63]
	v_mfma_f32_16x16x32_bf16 v[56:59], v[136:139], v[144:147], v[56:59]
	v_mfma_f32_16x16x32_bf16 v[44:47], v[128:131], v[152:155], v[44:47]
	v_mfma_f32_16x16x32_bf16 v[40:43], v[136:139], v[152:155], v[40:43]
	v_mfma_f32_16x16x32_bf16 v[28:31], v[128:131], v[160:163], v[28:31]
	v_mfma_f32_16x16x32_bf16 v[24:27], v[136:139], v[160:163], v[24:27]
	v_mfma_f32_16x16x32_bf16 v[12:15], v[128:131], v[168:171], v[12:15]
	v_mfma_f32_16x16x32_bf16 v[8:11], v[136:139], v[168:171], v[8:11]
	v_mfma_f32_16x16x32_bf16 v[60:63], v[132:135], v[148:151], v[60:63]
	v_mfma_f32_16x16x32_bf16 v[56:59], v[140:143], v[148:151], v[56:59]
	v_mfma_f32_16x16x32_bf16 v[44:47], v[132:135], v[156:159], v[44:47]
	v_mfma_f32_16x16x32_bf16 v[40:43], v[140:143], v[156:159], v[40:43]
	v_mfma_f32_16x16x32_bf16 v[28:31], v[132:135], v[164:167], v[28:31]
	v_mfma_f32_16x16x32_bf16 v[24:27], v[140:143], v[164:167], v[24:27]
	v_mfma_f32_16x16x32_bf16 v[12:15], v[132:135], v[172:175], v[12:15]
	v_mfma_f32_16x16x32_bf16 v[8:11], v[140:143], v[172:175], v[8:11]
	s_setprio 0
	s_barrier
	s_add_u32 s24, s28, 0x60000
	s_addc_u32 s25, s29, 0
	s_add_i32 s59, s51, s37
	s_mov_b32 m0, s59
	s_nop 0
	global_load_lds_dwordx4 v204, s[24:25]
	s_add_i32 m0, s59, 0x2000
	s_nop 0
	global_load_lds_dwordx4 v208, s[24:25]
	s_add_u32 s24, s30, 0x60000
	s_addc_u32 s25, s31, 0
	s_mov_b32 m0, s40
	s_nop 0
	global_load_lds_dwordx4 v202, s[24:25]
	s_mov_b32 m0, s41
	s_nop 0
	global_load_lds_dwordx4 v206, s[24:25]
	s_waitcnt vmcnt(10)
	s_barrier
	s_setprio 1
	v_mfma_f32_16x16x32_bf16 v[52:55], v[176:179], v[144:147], v[52:55]
	v_mfma_f32_16x16x32_bf16 v[48:51], v[184:187], v[144:147], v[48:51]
	v_mfma_f32_16x16x32_bf16 v[36:39], v[176:179], v[152:155], v[36:39]
	v_mfma_f32_16x16x32_bf16 v[32:35], v[184:187], v[152:155], v[32:35]
	v_mfma_f32_16x16x32_bf16 v[20:23], v[176:179], v[160:163], v[20:23]
	v_mfma_f32_16x16x32_bf16 v[16:19], v[184:187], v[160:163], v[16:19]
	v_mfma_f32_16x16x32_bf16 v[4:7], v[176:179], v[168:171], v[4:7]
	v_mfma_f32_16x16x32_bf16 v[0:3], v[184:187], v[168:171], v[0:3]
	v_mfma_f32_16x16x32_bf16 v[52:55], v[180:183], v[148:151], v[52:55]
	v_mfma_f32_16x16x32_bf16 v[48:51], v[188:191], v[148:151], v[48:51]
	v_mfma_f32_16x16x32_bf16 v[36:39], v[180:183], v[156:159], v[36:39]
	v_mfma_f32_16x16x32_bf16 v[32:35], v[188:191], v[156:159], v[32:35]
	v_mfma_f32_16x16x32_bf16 v[20:23], v[180:183], v[164:167], v[20:23]
	v_mfma_f32_16x16x32_bf16 v[16:19], v[188:191], v[164:167], v[16:19]
	v_mfma_f32_16x16x32_bf16 v[4:7], v[180:183], v[172:175], v[4:7]
	v_mfma_f32_16x16x32_bf16 v[0:3], v[188:191], v[172:175], v[0:3]
	s_setprio 0
	s_add_i32 s59, 0, 0x18000
	v_add_u32_e32 v140, s59, v236
	s_barrier
	ds_read_b128 v[128:131], v140
	ds_read_b128 v[132:135], v140 offset:1024
	ds_read_b128 v[136:139], v140 offset:2048
	ds_read_b128 v[140:143], v140 offset:3072
	ds_read_b128 v[144:147], v238 offset:32768
	ds_read_b128 v[148:151], v238 offset:33792
	ds_read_b128 v[152:155], v238 offset:34816
	ds_read_b128 v[156:159], v238 offset:35840
	ds_read_b128 v[160:163], v238 offset:36864
	ds_read_b128 v[164:167], v238 offset:37888
	ds_read_b128 v[168:171], v238 offset:38912
	ds_read_b128 v[172:175], v238 offset:39936
	s_waitcnt lgkmcnt(8)
	s_waitcnt vmcnt(8)
	s_barrier
; #define PG8_STAGE(bufoff, gbase, voff) do { _Pragma("unroll") for (int _i = 0; _i < 2; ++_i) \
;         __builtin_amdgcn_global_load_lds((const unsigned*)((const char*)(gbase) + (voff)[_i]), (LAS unsigned*)(lds + (bufoff) + ldsw + _i * 8192), 16, 0, 0); } while (0)
; #define PG8_LDA(dst, b, h) do { _Pragma("unroll") for (int m = 0; m < 4; ++m) _Pragma("unroll") for (int k = 0; k < 2; ++k) dst[m][k] = *(const LAS bf16x8*)(lds + PG8_SA(b, h) + aoff + m * 2048 + k * 1024); } while (0)
; #define PG8_LDB(dst, b, h) do { _Pragma("unroll") for (int n = 0; n < 2; ++n) _Pragma("unroll") for (int k = 0; k < 2; ++k) dst[n][k] = *(const LAS bf16x8*)(lds + PG8_SB(b, h) + boff + n * 2048 + k * 1024); } while (0)
; #define PG8_MMA(ai, bj, At, Bt) do { __builtin_amdgcn_s_setprio(1); _Pragma("unroll") for (int m = 0; m < 4; ++m) _Pragma("unroll") for (int n = 0; n < 2; ++n) _Pragma("unroll") for (int k = 0; k < 2; ++k) \
;         acc[ai][bj][m][n] = __builtin_amdgcn_mfma_f32_16x16x32_bf16(Bt[n][k], At[m][k], acc[ai][bj][m][n], 0, 0, 0); __builtin_amdgcn_s_setprio(0); } while (0)
; #define PG8_WAIT_V(n) asm volatile("s_waitcnt vmcnt(" #n ")" ::: "memory")
; #define PG8_WAIT_L(n) asm volatile("s_waitcnt lgkmcnt(" #n ")" ::: "memory")
; #define PG8_BAR __builtin_amdgcn_s_barrier()
; template <class Epi, class Sched>
; __device__ __forceinline__ void gemm_phase(LAS unsigned char* lds, const Gemm g, const Sched& S, const Epi& E) {
;     ...
;             PG8_LDA(At, 0, 1); PG8_STAGE(PG8_SA(0, 0), a2, voffA);
;             PG8_BAR; PG8_WAIT_L(0); PG8_MMA(1, 0, At, B0); PG8_BAR; PG8_SCHED;
;             PG8_STAGE(PG8_SB(0, 1), b2 + hstep, voffB);
;             PG8_WAIT_V(6); PG8_BAR; PG8_MMA(1, 1, At, B1); PG8_BAR;
;             PG8_LDB(B0, 1, 0); PG8_SCHED; PG8_LDA(At, 1, 0); PG8_STAGE(PG8_SA(0, 1), a2 + hstep, voffA);
;             PG8_WAIT_L(8); PG8_BAR; PG8_WAIT_L(0); PG8_MMA(0, 0, At, B0); PG8_BAR; PG8_SCHED;
;             PG8_LDB(B1, 1, 1); PG8_STAGE(PG8_SB(1, 0), b3, voffB);
;             PG8_BAR; PG8_WAIT_L(0); PG8_MMA(0, 1, At, B1); PG8_BAR;
;             PG8_LDA(At, 1, 1); PG8_STAGE(PG8_SA(1, 0), a3, voffA);
;             PG8_BAR; PG8_WAIT_L(0); PG8_MMA(1, 0, At, B0); PG8_BAR; PG8_SCHED;
;             PG8_STAGE(PG8_SB(1, 1), b3 + hstep, voffB);
;             PG8_WAIT_V(6); PG8_BAR; PG8_MMA(1, 1, At, B1); PG8_BAR;
;         }
	s_waitcnt lgkmcnt(0)
	s_setprio 1
	s_waitcnt lgkmcnt(0)
	v_mfma_f32_16x16x32_bf16 v[124:127], v[128:131], v[144:147], v[124:127]
	v_mfma_f32_16x16x32_bf16 v[120:123], v[136:139], v[144:147], v[120:123]
	v_mfma_f32_16x16x32_bf16 v[108:111], v[128:131], v[152:155], v[108:111]
	v_mfma_f32_16x16x32_bf16 v[104:107], v[136:139], v[152:155], v[104:107]
	v_mfma_f32_16x16x32_bf16 v[92:95], v[128:131], v[160:163], v[92:95]
	v_mfma_f32_16x16x32_bf16 v[88:91], v[136:139], v[160:163], v[88:91]
	v_mfma_f32_16x16x32_bf16 v[76:79], v[128:131], v[168:171], v[76:79]
	v_mfma_f32_16x16x32_bf16 v[72:75], v[136:139], v[168:171], v[72:75]
	v_mfma_f32_16x16x32_bf16 v[124:127], v[132:135], v[148:151], v[124:127]
	v_mfma_f32_16x16x32_bf16 v[120:123], v[140:143], v[148:151], v[120:123]
	v_mfma_f32_16x16x32_bf16 v[108:111], v[132:135], v[156:159], v[108:111]
	v_mfma_f32_16x16x32_bf16 v[104:107], v[140:143], v[156:159], v[104:107]
	v_mfma_f32_16x16x32_bf16 v[92:95], v[132:135], v[164:167], v[92:95]
	v_mfma_f32_16x16x32_bf16 v[88:91], v[140:143], v[164:167], v[88:91]
	v_mfma_f32_16x16x32_bf16 v[76:79], v[132:135], v[172:175], v[76:79]
	v_mfma_f32_16x16x32_bf16 v[72:75], v[140:143], v[172:175], v[72:75]
	s_setprio 0
	s_barrier
	s_add_i32 s30, 0, 0x1c000
	s_add_i32 s24, s59, s37
	v_add_u32_e32 v188, s30, v236
	s_add_u32 s0, s28, 0x80
	s_addc_u32 s1, s29, 0
	s_mov_b32 m0, s24
	ds_read_b128 v[176:179], v188
	ds_read_b128 v[180:183], v188 offset:1024
	ds_read_b128 v[184:187], v188 offset:2048
	ds_read_b128 v[188:191], v188 offset:3072
	global_load_lds_dwordx4 v204, s[0:1]
	s_add_i32 m0, s24, 0x2000
	s_nop 0
	global_load_lds_dwordx4 v208, s[0:1]
	s_waitcnt vmcnt(8)
	s_barrier
	s_waitcnt lgkmcnt(0)
	s_setprio 1
	s_waitcnt lgkmcnt(0)
	v_mfma_f32_16x16x32_bf16 v[116:119], v[176:179], v[144:147], v[116:119]
	v_mfma_f32_16x16x32_bf16 v[112:115], v[184:187], v[144:147], v[112:115]
	v_mfma_f32_16x16x32_bf16 v[100:103], v[176:179], v[152:155], v[100:103]
	v_mfma_f32_16x16x32_bf16 v[96:99], v[184:187], v[152:155], v[96:99]
	v_mfma_f32_16x16x32_bf16 v[84:87], v[176:179], v[160:163], v[84:87]
	v_mfma_f32_16x16x32_bf16 v[80:83], v[184:187], v[160:163], v[80:83]
	v_mfma_f32_16x16x32_bf16 v[68:71], v[176:179], v[168:171], v[68:71]
	v_mfma_f32_16x16x32_bf16 v[64:67], v[184:187], v[168:171], v[64:67]
	v_mfma_f32_16x16x32_bf16 v[116:119], v[180:183], v[148:151], v[116:119]
	v_mfma_f32_16x16x32_bf16 v[112:115], v[188:191], v[148:151], v[112:115]
	v_mfma_f32_16x16x32_bf16 v[100:103], v[180:183], v[156:159], v[100:103]
	v_mfma_f32_16x16x32_bf16 v[96:99], v[188:191], v[156:159], v[96:99]
	v_mfma_f32_16x16x32_bf16 v[84:87], v[180:183], v[164:167], v[84:87]
	v_mfma_f32_16x16x32_bf16 v[80:83], v[188:191], v[164:167], v[80:83]
	v_mfma_f32_16x16x32_bf16 v[68:71], v[180:183], v[172:175], v[68:71]
	v_mfma_f32_16x16x32_bf16 v[64:67], v[188:191], v[172:175], v[64:67]
	s_setprio 0
	s_mov_b32 m0, s47
	s_mov_b64 s[0:1], 0x80
	v_lshl_add_u64 v[192:193], v[196:197], 0, s[0:1]
	s_barrier
	ds_read_b128 v[144:147], v238 offset:49152
	ds_read_b128 v[148:151], v238 offset:50176
	ds_read_b128 v[152:155], v238 offset:51200
	ds_read_b128 v[156:159], v238 offset:52224
	ds_read_b128 v[160:163], v238 offset:53248
	ds_read_b128 v[164:167], v238 offset:54272
	ds_read_b128 v[168:171], v238 offset:55296
	ds_read_b128 v[172:175], v238 offset:56320
	global_load_lds_dwordx4 v[192:193], off
	v_lshl_add_u64 v[192:193], v[198:199], 0, s[0:1]
	s_mov_b32 m0, s48
	s_nop 0
	global_load_lds_dwordx4 v[192:193], off
	s_barrier
	s_waitcnt lgkmcnt(0)
	s_setprio 1
	s_waitcnt lgkmcnt(0)
	v_mfma_f32_16x16x32_bf16 v[60:63], v[128:131], v[144:147], v[60:63]
	v_mfma_f32_16x16x32_bf16 v[56:59], v[136:139], v[144:147], v[56:59]
	v_mfma_f32_16x16x32_bf16 v[44:47], v[128:131], v[152:155], v[44:47]
	v_mfma_f32_16x16x32_bf16 v[40:43], v[136:139], v[152:155], v[40:43]
	v_mfma_f32_16x16x32_bf16 v[28:31], v[128:131], v[160:163], v[28:31]
	v_mfma_f32_16x16x32_bf16 v[24:27], v[136:139], v[160:163], v[24:27]
	v_mfma_f32_16x16x32_bf16 v[12:15], v[128:131], v[168:171], v[12:15]
	v_mfma_f32_16x16x32_bf16 v[8:11], v[136:139], v[168:171], v[8:11]
	v_mfma_f32_16x16x32_bf16 v[60:63], v[132:135], v[148:151], v[60:63]
	v_mfma_f32_16x16x32_bf16 v[56:59], v[140:143], v[148:151], v[56:59]
	v_mfma_f32_16x16x32_bf16 v[44:47], v[132:135], v[156:159], v[44:47]
	v_mfma_f32_16x16x32_bf16 v[40:43], v[140:143], v[156:159], v[40:43]
	v_mfma_f32_16x16x32_bf16 v[28:31], v[132:135], v[164:167], v[28:31]
	v_mfma_f32_16x16x32_bf16 v[24:27], v[140:143], v[164:167], v[24:27]
	v_mfma_f32_16x16x32_bf16 v[12:15], v[132:135], v[172:175], v[12:15]
	v_mfma_f32_16x16x32_bf16 v[8:11], v[140:143], v[172:175], v[8:11]
	s_setprio 0
	s_barrier
	s_add_u32 s24, s28, 0x60080
	s_addc_u32 s25, s29, 0
	s_add_i32 s28, s30, s37
	s_mov_b32 m0, s28
	s_nop 0
	global_load_lds_dwordx4 v204, s[24:25]
	s_add_i32 m0, s28, 0x2000
	s_nop 0
	global_load_lds_dwordx4 v208, s[24:25]
	s_waitcnt vmcnt(8)
	s_barrier
	s_setprio 1
	v_mfma_f32_16x16x32_bf16 v[52:55], v[176:179], v[144:147], v[52:55]
	v_mfma_f32_16x16x32_bf16 v[48:51], v[184:187], v[144:147], v[48:51]
	v_mfma_f32_16x16x32_bf16 v[36:39], v[176:179], v[152:155], v[36:39]
	v_mfma_f32_16x16x32_bf16 v[32:35], v[184:187], v[152:155], v[32:35]
	v_mfma_f32_16x16x32_bf16 v[20:23], v[176:179], v[160:163], v[20:23]
	v_mfma_f32_16x16x32_bf16 v[16:19], v[184:187], v[160:163], v[16:19]
	v_mfma_f32_16x16x32_bf16 v[4:7], v[176:179], v[168:171], v[4:7]
	v_mfma_f32_16x16x32_bf16 v[0:3], v[184:187], v[168:171], v[0:3]
	v_mfma_f32_16x16x32_bf16 v[52:55], v[180:183], v[148:151], v[52:55]
	v_mfma_f32_16x16x32_bf16 v[48:51], v[188:191], v[148:151], v[48:51]
	v_mfma_f32_16x16x32_bf16 v[36:39], v[180:183], v[156:159], v[36:39]
	v_mfma_f32_16x16x32_bf16 v[32:35], v[188:191], v[156:159], v[32:35]
	v_mfma_f32_16x16x32_bf16 v[20:23], v[180:183], v[164:167], v[20:23]
	v_mfma_f32_16x16x32_bf16 v[16:19], v[188:191], v[164:167], v[16:19]
	v_mfma_f32_16x16x32_bf16 v[4:7], v[180:183], v[172:175], v[4:7]
	v_mfma_f32_16x16x32_bf16 v[0:3], v[188:191], v[172:175], v[0:3]
	s_setprio 0
	s_add_i32 s58, s58, 2
	s_add_u32 s56, s56, 0x100
	s_addc_u32 s57, s57, 0
	s_cmp_gt_u32 s58, 21
	s_mov_b64 s[24:25], s[26:27]
	s_barrier
; __device__ __forceinline__ unsigned cvt_pk_bf16(float lo, float hi) { unsigned r; asm volatile("v_cvt_pk_bf16_f32 %0, %1, %2" : "=v"(r) : "v"(lo), "v"(hi)); return r; }
; __device__ __forceinline__ float bf_lo(unsigned u) { return __uint_as_float(u << 16); }
; __device__ __forceinline__ float bf_hi(unsigned u) { return __uint_as_float(u & 0xffff0000u); }
;     __device__ __forceinline__ void operator()(const AccT& acc, const Unit& u, int wr, int wc, int fr, int fq) const {
;     ...
;         const int rowt = u.pm * 256; const int b = rowt >> 11;
;         const bf16_t* res = res_b + (size_t)rowt * DM; bf16_t* out = hb + (size_t)rowt * DM;
;         const int col0 = u.pn * 256 + wc * 32 + 8 * fq;
;         f32x4 gv[2][2];
; #pragma unroll
;         for (int bj = 0; bj < 2; ++bj)
; #pragma unroll
;             for (int n = 0; n < 2; ++n) gv[bj][n] = *(const f32x4*)(gate + (size_t)b * NMOD + col0 + bj * 128 + n * 4) * gs;
;         u32x4 r[2][4][2];
; #pragma unroll
;         for (int ai = 0; ai < 2; ++ai)
; #pragma unroll
;             for (int m = 0; m < 4; ++m)
; #pragma unroll
;                 for (int bj = 0; bj < 2; ++bj) r[ai][m][bj] = *(const u32x4*)(res + (size_t)(wr * 64 + fr + ai * 128 + m * 16) * DM + col0 + bj * 128);
; #pragma unroll
;         for (int ai = 0; ai < 2; ++ai)
; #pragma unroll
;             for (int m = 0; m < 4; ++m)
; #pragma unroll
;                 for (int bj = 0; bj < 2; ++bj) {
;                     const u32x4 q = r[ai][m][bj];
;                     const f32x4 r0 = {bf_lo(q.x), bf_hi(q.x), bf_lo(q.y), bf_hi(q.y)}, r1 = {bf_lo(q.z), bf_hi(q.z), bf_lo(q.w), bf_hi(q.w)};
;                     const f32x4 h0 = r0 + gv[bj][0] * acc[ai][bj][m][0], h1 = r1 + gv[bj][1] * acc[ai][bj][m][1];
;                     u32x4 w; w.x = cvt_pk_bf16(h0[0], h0[1]); w.y = cvt_pk_bf16(h0[2], h0[3]); w.z = cvt_pk_bf16(h1[0], h1[1]); w.w = cvt_pk_bf16(h1[2], h1[3]);
;                     *(u32x4*)(out + (size_t)(wr * 64 + fr + ai * 128 + m * 16) * DM + col0 + bj * 128) = w;
	s_cbranch_scc0 .LBB0_902
	s_lshl_b32 s27, s55, 8
	v_mov_b32_e32 v146, v235
	v_mov_b32_e32 v128, v234
	s_lshl_b32 s24, s54, 8
	s_ashr_i32 s26, s54, 3
	s_or_b32 s27, s27, s46
	s_ashr_i32 s25, s24, 31
	v_lshl_add_u32 v144, v128, 3, s27
	s_mul_hi_i32 s27, s26, 0x9000
	s_mul_i32 s26, s26, 0x9000
	s_add_u32 s26, s43, s26
	s_addc_u32 s27, s44, s27
	v_ashrrev_i32_e32 v145, 31, v144
	s_lshl_b64 s[24:25], s[24:25], 11
	v_lshl_add_u64 v[132:133], v[144:145], 2, s[26:27]
	s_add_u32 s26, s62, s24
	v_add_u32_e32 v146, s45, v146
	s_addc_u32 s27, s63, s25
	v_lshlrev_b64 v[222:223], 1, v[144:145]
	v_ashrrev_i32_e32 v147, 31, v146
	v_lshl_add_u64 v[144:145], s[26:27], 0, v[222:223]
	v_lshlrev_b64 v[248:249], 11, v[146:147]
	v_lshl_add_u64 v[146:147], v[144:145], 0, v[248:249]
	global_load_dwordx4 v[136:139], v[132:133], off offset:16
	global_load_dwordx4 v[140:143], v[132:133], off
	global_load_dwordx4 v[128:131], v[132:133], off offset:528
	s_nop 0
	global_load_dwordx4 v[132:135], v[132:133], off offset:512
	s_nop 0
	global_load_dwordx4 v[240:243], v[146:147], off
	global_load_dwordx4 v[244:247], v[146:147], off offset:256
	v_lshl_add_u64 v[232:233], v[248:249], 0, s[10:11]
	v_lshl_add_u64 v[146:147], v[144:145], 0, v[232:233]
	global_load_dwordx4 v[196:199], v[146:147], off
	global_load_dwordx4 v[192:195], v[146:147], off offset:256
	v_lshl_add_u64 v[230:231], v[248:249], 0, s[12:13]
	v_lshl_add_u64 v[146:147], v[144:145], 0, v[230:231]
	global_load_dwordx4 v[188:191], v[146:147], off
	global_load_dwordx4 v[184:187], v[146:147], off offset:256
	v_lshl_add_u64 v[228:229], v[248:249], 0, s[14:15]
	v_lshl_add_u64 v[146:147], v[144:145], 0, v[228:229]
	global_load_dwordx4 v[180:183], v[146:147], off
	global_load_dwordx4 v[176:179], v[146:147], off offset:256
	v_lshl_add_u64 v[226:227], v[248:249], 0, s[16:17]
	v_lshl_add_u64 v[146:147], v[144:145], 0, v[226:227]
	global_load_dwordx4 v[172:175], v[146:147], off
	global_load_dwordx4 v[168:171], v[146:147], off offset:256
	v_lshl_add_u64 v[224:225], v[248:249], 0, s[18:19]
	v_lshl_add_u64 v[146:147], v[144:145], 0, v[224:225]
	global_load_dwordx4 v[164:167], v[146:147], off
	global_load_dwordx4 v[160:163], v[146:147], off offset:256
	v_lshl_add_u64 v[220:221], v[248:249], 0, s[20:21]
	v_lshl_add_u64 v[146:147], v[144:145], 0, v[220:221]
	global_load_dwordx4 v[156:159], v[146:147], off
	global_load_dwordx4 v[152:155], v[146:147], off offset:256
	v_lshl_add_u64 v[218:219], v[248:249], 0, s[22:23]
	v_lshl_add_u64 v[144:145], v[144:145], 0, v[218:219]
	global_load_dwordx4 v[148:151], v[144:145], off
	s_nop 0
	global_load_dwordx4 v[144:147], v[144:145], off offset:256
	s_add_u32 s24, s80, s24
	s_addc_u32 s25, s81, s25
	v_lshl_add_u64 v[222:223], s[24:25], 0, v[222:223]
	v_lshl_add_u64 v[248:249], v[222:223], 0, v[248:249]
	s_and_b64 vcc, exec, s[2:3]
	s_mov_b32 s55, s52
	s_mov_b32 s54, s53
	s_mov_b64 s[26:27], s[6:7]
	s_mov_b64 s[24:25], s[4:5]
	s_waitcnt vmcnt(0)
	v_lshlrev_b32_e32 v250, 16, v240
	v_and_b32_e32 v251, 0xffff0000, v240
	v_lshlrev_b32_e32 v240, 16, v241
	v_and_b32_e32 v241, 0xffff0000, v241
	v_lshlrev_b32_e32 v252, 16, v242
	v_and_b32_e32 v253, 0xffff0000, v242
	v_lshlrev_b32_e32 v242, 16, v243
	v_and_b32_e32 v243, 0xffff0000, v243
	v_pk_fma_f32 v[126:127], v[126:127], v[142:143], v[240:241]
	v_pk_fma_f32 v[124:125], v[124:125], v[140:141], v[250:251]
	v_pk_fma_f32 v[240:241], v[122:123], v[138:139], v[242:243]
	v_pk_fma_f32 v[122:123], v[120:121], v[136:137], v[252:253]
	v_cvt_pk_bf16_f32 v120, v124, v125
	v_cvt_pk_bf16_f32 v121, v126, v127
	v_lshlrev_b32_e32 v124, 16, v246
	v_cvt_pk_bf16_f32 v122, v122, v123
	v_cvt_pk_bf16_f32 v123, v240, v241
	global_store_dwordx4 v[248:249], v[120:123], off
	v_and_b32_e32 v125, 0xffff0000, v246
	v_lshlrev_b32_e32 v126, 16, v247
	v_lshlrev_b32_e32 v120, 16, v244
	v_and_b32_e32 v121, 0xffff0000, v244
	v_and_b32_e32 v127, 0xffff0000, v247
	v_lshlrev_b32_e32 v122, 16, v245
	v_and_b32_e32 v123, 0xffff0000, v245
	v_pk_fma_f32 v[116:117], v[116:117], v[132:133], v[120:121]
	v_pk_fma_f32 v[120:121], v[114:115], v[130:131], v[126:127]
	v_pk_fma_f32 v[114:115], v[112:113], v[128:129], v[124:125]
	v_pk_fma_f32 v[118:119], v[118:119], v[134:135], v[122:123]
	v_cvt_pk_bf16_f32 v112, v116, v117
	v_lshlrev_b32_e32 v116, 16, v197
	v_cvt_pk_bf16_f32 v113, v118, v119
	v_cvt_pk_bf16_f32 v114, v114, v115
	v_cvt_pk_bf16_f32 v115, v120, v121
	global_store_dwordx4 v[248:249], v[112:115], off offset:256
	v_and_b32_e32 v117, 0xffff0000, v197
	v_lshlrev_b32_e32 v118, 16, v198
	v_lshlrev_b32_e32 v114, 16, v196
	v_and_b32_e32 v115, 0xffff0000, v196
	v_and_b32_e32 v119, 0xffff0000, v198
	v_lshlrev_b32_e32 v120, 16, v199
	v_and_b32_e32 v121, 0xffff0000, v199
	v_lshl_add_u64 v[112:113], v[222:223], 0, v[232:233]
	v_pk_fma_f32 v[110:111], v[110:111], v[142:143], v[116:117]
	v_pk_fma_f32 v[108:109], v[108:109], v[140:141], v[114:115]
	v_pk_fma_f32 v[114:115], v[106:107], v[138:139], v[120:121]
	v_pk_fma_f32 v[106:107], v[104:105], v[136:137], v[118:119]
	v_cvt_pk_bf16_f32 v104, v108, v109
	v_cvt_pk_bf16_f32 v105, v110, v111
	v_lshlrev_b32_e32 v108, 16, v194
	v_cvt_pk_bf16_f32 v106, v106, v107
	v_cvt_pk_bf16_f32 v107, v114, v115
	global_store_dwordx4 v[112:113], v[104:107], off
	v_and_b32_e32 v109, 0xffff0000, v194
	v_lshlrev_b32_e32 v110, 16, v195
	v_lshlrev_b32_e32 v104, 16, v192
	v_and_b32_e32 v105, 0xffff0000, v192
	v_and_b32_e32 v111, 0xffff0000, v195
	v_lshlrev_b32_e32 v106, 16, v193
	v_and_b32_e32 v107, 0xffff0000, v193
	v_pk_fma_f32 v[100:101], v[100:101], v[132:133], v[104:105]
	v_pk_fma_f32 v[104:105], v[98:99], v[130:131], v[110:111]
	v_pk_fma_f32 v[98:99], v[96:97], v[128:129], v[108:109]
; __device__ __forceinline__ unsigned cvt_pk_bf16(float lo, float hi) { unsigned r; asm volatile("v_cvt_pk_bf16_f32 %0, %1, %2" : "=v"(r) : "v"(lo), "v"(hi)); return r; }
; __device__ __forceinline__ float bf_lo(unsigned u) { return __uint_as_float(u << 16); }
; __device__ __forceinline__ float bf_hi(unsigned u) { return __uint_as_float(u & 0xffff0000u); }
;     __device__ __forceinline__ void operator()(const AccT& acc, const Unit& u, int wr, int wc, int fr, int fq) const {
;     ...
;         for (int ai = 0; ai < 2; ++ai)
; #pragma unroll
;             for (int m = 0; m < 4; ++m)
; #pragma unroll
;                 for (int bj = 0; bj < 2; ++bj) {
;                     const u32x4 q = r[ai][m][bj];
;                     const f32x4 r0 = {bf_lo(q.x), bf_hi(q.x), bf_lo(q.y), bf_hi(q.y)}, r1 = {bf_lo(q.z), bf_hi(q.z), bf_lo(q.w), bf_hi(q.w)};
;                     const f32x4 h0 = r0 + gv[bj][0] * acc[ai][bj][m][0], h1 = r1 + gv[bj][1] * acc[ai][bj][m][1];
;                     u32x4 w; w.x = cvt_pk_bf16(h0[0], h0[1]); w.y = cvt_pk_bf16(h0[2], h0[3]); w.z = cvt_pk_bf16(h1[0], h1[1]); w.w = cvt_pk_bf16(h1[2], h1[3]);
;                     *(u32x4*)(out + (size_t)(wr * 64 + fr + ai * 128 + m * 16) * DM + col0 + bj * 128) = w;
	v_pk_fma_f32 v[102:103], v[102:103], v[134:135], v[106:107]
	v_cvt_pk_bf16_f32 v96, v100, v101
	v_lshlrev_b32_e32 v100, 16, v189
	v_cvt_pk_bf16_f32 v97, v102, v103
	v_cvt_pk_bf16_f32 v98, v98, v99
	v_cvt_pk_bf16_f32 v99, v104, v105
	global_store_dwordx4 v[112:113], v[96:99], off offset:256
	v_and_b32_e32 v101, 0xffff0000, v189
	v_lshlrev_b32_e32 v102, 16, v190
	v_lshlrev_b32_e32 v98, 16, v188
	v_and_b32_e32 v99, 0xffff0000, v188
	v_and_b32_e32 v103, 0xffff0000, v190
	v_lshlrev_b32_e32 v104, 16, v191
	v_and_b32_e32 v105, 0xffff0000, v191
	v_lshl_add_u64 v[96:97], v[222:223], 0, v[230:231]
	v_pk_fma_f32 v[94:95], v[94:95], v[142:143], v[100:101]
	v_pk_fma_f32 v[92:93], v[92:93], v[140:141], v[98:99]
	v_pk_fma_f32 v[98:99], v[90:91], v[138:139], v[104:105]
	v_pk_fma_f32 v[90:91], v[88:89], v[136:137], v[102:103]
	v_cvt_pk_bf16_f32 v88, v92, v93
	v_cvt_pk_bf16_f32 v89, v94, v95
	v_lshlrev_b32_e32 v92, 16, v186
	v_cvt_pk_bf16_f32 v90, v90, v91
	v_cvt_pk_bf16_f32 v91, v98, v99
	global_store_dwordx4 v[96:97], v[88:91], off
	v_and_b32_e32 v93, 0xffff0000, v186
	v_lshlrev_b32_e32 v94, 16, v187
	v_lshlrev_b32_e32 v88, 16, v184
	v_and_b32_e32 v89, 0xffff0000, v184
	v_and_b32_e32 v95, 0xffff0000, v187
	v_lshlrev_b32_e32 v90, 16, v185
	v_and_b32_e32 v91, 0xffff0000, v185
	v_pk_fma_f32 v[84:85], v[84:85], v[132:133], v[88:89]
	v_pk_fma_f32 v[88:89], v[82:83], v[130:131], v[94:95]
	v_pk_fma_f32 v[82:83], v[80:81], v[128:129], v[92:93]
	v_pk_fma_f32 v[86:87], v[86:87], v[134:135], v[90:91]
	v_cvt_pk_bf16_f32 v80, v84, v85
	v_lshlrev_b32_e32 v84, 16, v181
	v_cvt_pk_bf16_f32 v81, v86, v87
	v_cvt_pk_bf16_f32 v82, v82, v83
	v_cvt_pk_bf16_f32 v83, v88, v89
	global_store_dwordx4 v[96:97], v[80:83], off offset:256
	v_and_b32_e32 v85, 0xffff0000, v181
	v_lshlrev_b32_e32 v86, 16, v182
	v_lshlrev_b32_e32 v82, 16, v180
	v_and_b32_e32 v83, 0xffff0000, v180
	v_and_b32_e32 v87, 0xffff0000, v182
	v_lshlrev_b32_e32 v88, 16, v183
	v_and_b32_e32 v89, 0xffff0000, v183
	v_lshl_add_u64 v[80:81], v[222:223], 0, v[228:229]
	v_pk_fma_f32 v[78:79], v[78:79], v[142:143], v[84:85]
	v_pk_fma_f32 v[76:77], v[76:77], v[140:141], v[82:83]
	v_pk_fma_f32 v[82:83], v[74:75], v[138:139], v[88:89]
	v_pk_fma_f32 v[74:75], v[72:73], v[136:137], v[86:87]
	v_cvt_pk_bf16_f32 v72, v76, v77
	v_cvt_pk_bf16_f32 v73, v78, v79
	v_lshlrev_b32_e32 v76, 16, v178
	v_cvt_pk_bf16_f32 v74, v74, v75
	v_cvt_pk_bf16_f32 v75, v82, v83
	global_store_dwordx4 v[80:81], v[72:75], off
	v_and_b32_e32 v77, 0xffff0000, v178
	v_lshlrev_b32_e32 v78, 16, v179
	v_lshlrev_b32_e32 v72, 16, v176
	v_and_b32_e32 v73, 0xffff0000, v176
	v_and_b32_e32 v79, 0xffff0000, v179
	v_lshlrev_b32_e32 v74, 16, v177
	v_and_b32_e32 v75, 0xffff0000, v177
	v_pk_fma_f32 v[68:69], v[68:69], v[132:133], v[72:73]
	v_pk_fma_f32 v[72:73], v[66:67], v[130:131], v[78:79]
	v_pk_fma_f32 v[66:67], v[64:65], v[128:129], v[76:77]
	v_pk_fma_f32 v[70:71], v[70:71], v[134:135], v[74:75]
	v_cvt_pk_bf16_f32 v64, v68, v69
	v_lshlrev_b32_e32 v68, 16, v173
	v_cvt_pk_bf16_f32 v65, v70, v71
	v_cvt_pk_bf16_f32 v66, v66, v67
	v_cvt_pk_bf16_f32 v67, v72, v73
	global_store_dwordx4 v[80:81], v[64:67], off offset:256
	v_and_b32_e32 v69, 0xffff0000, v173
	v_lshlrev_b32_e32 v70, 16, v174
	v_lshlrev_b32_e32 v66, 16, v172
	v_and_b32_e32 v67, 0xffff0000, v172
	v_and_b32_e32 v71, 0xffff0000, v174
	v_lshlrev_b32_e32 v72, 16, v175
	v_and_b32_e32 v73, 0xffff0000, v175
	v_lshl_add_u64 v[64:65], v[222:223], 0, v[226:227]
	v_pk_fma_f32 v[62:63], v[62:63], v[142:143], v[68:69]
	v_pk_fma_f32 v[60:61], v[60:61], v[140:141], v[66:67]
	v_pk_fma_f32 v[66:67], v[58:59], v[138:139], v[72:73]
	v_pk_fma_f32 v[58:59], v[56:57], v[136:137], v[70:71]
	v_cvt_pk_bf16_f32 v56, v60, v61
	v_cvt_pk_bf16_f32 v57, v62, v63
	v_lshlrev_b32_e32 v60, 16, v170
	v_cvt_pk_bf16_f32 v58, v58, v59
	v_cvt_pk_bf16_f32 v59, v66, v67
	global_store_dwordx4 v[64:65], v[56:59], off
	v_and_b32_e32 v61, 0xffff0000, v170
	v_lshlrev_b32_e32 v62, 16, v171
	v_lshlrev_b32_e32 v56, 16, v168
	v_and_b32_e32 v57, 0xffff0000, v168
	v_and_b32_e32 v63, 0xffff0000, v171
	v_lshlrev_b32_e32 v58, 16, v169
	v_and_b32_e32 v59, 0xffff0000, v169
	v_pk_fma_f32 v[52:53], v[52:53], v[132:133], v[56:57]
	v_pk_fma_f32 v[56:57], v[50:51], v[130:131], v[62:63]
	v_pk_fma_f32 v[50:51], v[48:49], v[128:129], v[60:61]
	v_pk_fma_f32 v[54:55], v[54:55], v[134:135], v[58:59]
	v_cvt_pk_bf16_f32 v48, v52, v53
	v_lshlrev_b32_e32 v52, 16, v165
	v_cvt_pk_bf16_f32 v49, v54, v55
; __device__ __forceinline__ unsigned cvt_pk_bf16(float lo, float hi) { unsigned r; asm volatile("v_cvt_pk_bf16_f32 %0, %1, %2" : "=v"(r) : "v"(lo), "v"(hi)); return r; }
; __device__ __forceinline__ float bf_lo(unsigned u) { return __uint_as_float(u << 16); }
; __device__ __forceinline__ float bf_hi(unsigned u) { return __uint_as_float(u & 0xffff0000u); }
; #define PG8_WAIT_V(n) asm volatile("s_waitcnt vmcnt(" #n ")" ::: "memory")
; #define PG8_BAR __builtin_amdgcn_s_barrier()
; template <class Epi, class Sched>
; __device__ __forceinline__ void gemm_phase(LAS unsigned char* lds, const Gemm g, const Sched& S, const Epi& E) {
;     ...
;         if (!has_next) break;
; #pragma unroll
;         for (int a = 0; a < 2; ++a)
; #pragma unroll
;             for (int b = 0; b < 2; ++b)
; #pragma unroll
;                 for (int m = 0; m < 4; ++m)
; #pragma unroll
;                     for (int n = 0; n < 2; ++n) acc[a][b][m][n] = (f32x4){0.f, 0.f, 0.f, 0.f};
;         cur = nxt; cA = nA; cB = nB; ++ui;
;     }
;     PG8_WAIT_V(0);
;     if (wr == 0) PG8_BAR;
;     PG8_BAR;
;     __device__ __forceinline__ void operator()(const AccT& acc, const Unit& u, int wr, int wc, int fr, int fq) const {
;     ...
;         for (int ai = 0; ai < 2; ++ai)
; #pragma unroll
;             for (int m = 0; m < 4; ++m)
; #pragma unroll
;                 for (int bj = 0; bj < 2; ++bj) {
;                     const u32x4 q = r[ai][m][bj];
;                     const f32x4 r0 = {bf_lo(q.x), bf_hi(q.x), bf_lo(q.y), bf_hi(q.y)}, r1 = {bf_lo(q.z), bf_hi(q.z), bf_lo(q.w), bf_hi(q.w)};
;                     const f32x4 h0 = r0 + gv[bj][0] * acc[ai][bj][m][0], h1 = r1 + gv[bj][1] * acc[ai][bj][m][1];
;                     u32x4 w; w.x = cvt_pk_bf16(h0[0], h0[1]); w.y = cvt_pk_bf16(h0[2], h0[3]); w.z = cvt_pk_bf16(h1[0], h1[1]); w.w = cvt_pk_bf16(h1[2], h1[3]);
;                     *(u32x4*)(out + (size_t)(wr * 64 + fr + ai * 128 + m * 16) * DM + col0 + bj * 128) = w;
	v_cvt_pk_bf16_f32 v50, v50, v51
	v_cvt_pk_bf16_f32 v51, v56, v57
	global_store_dwordx4 v[64:65], v[48:51], off offset:256
	v_and_b32_e32 v53, 0xffff0000, v165
	v_lshlrev_b32_e32 v54, 16, v166
	v_lshlrev_b32_e32 v50, 16, v164
	v_and_b32_e32 v51, 0xffff0000, v164
	v_and_b32_e32 v55, 0xffff0000, v166
	v_lshlrev_b32_e32 v56, 16, v167
	v_and_b32_e32 v57, 0xffff0000, v167
	v_lshl_add_u64 v[48:49], v[222:223], 0, v[224:225]
	v_pk_fma_f32 v[46:47], v[46:47], v[142:143], v[52:53]
	v_pk_fma_f32 v[44:45], v[44:45], v[140:141], v[50:51]
	v_pk_fma_f32 v[50:51], v[42:43], v[138:139], v[56:57]
	v_pk_fma_f32 v[42:43], v[40:41], v[136:137], v[54:55]
	v_cvt_pk_bf16_f32 v40, v44, v45
	v_cvt_pk_bf16_f32 v41, v46, v47
	v_lshlrev_b32_e32 v44, 16, v162
	v_cvt_pk_bf16_f32 v42, v42, v43
	v_cvt_pk_bf16_f32 v43, v50, v51
	global_store_dwordx4 v[48:49], v[40:43], off
	v_and_b32_e32 v45, 0xffff0000, v162
	v_lshlrev_b32_e32 v46, 16, v163
	v_lshlrev_b32_e32 v40, 16, v160
	v_and_b32_e32 v41, 0xffff0000, v160
	v_and_b32_e32 v47, 0xffff0000, v163
	v_lshlrev_b32_e32 v42, 16, v161
	v_and_b32_e32 v43, 0xffff0000, v161
	v_pk_fma_f32 v[36:37], v[36:37], v[132:133], v[40:41]
	v_pk_fma_f32 v[40:41], v[34:35], v[130:131], v[46:47]
	v_pk_fma_f32 v[34:35], v[32:33], v[128:129], v[44:45]
	v_pk_fma_f32 v[38:39], v[38:39], v[134:135], v[42:43]
	v_cvt_pk_bf16_f32 v32, v36, v37
	v_lshlrev_b32_e32 v36, 16, v157
	v_cvt_pk_bf16_f32 v33, v38, v39
	v_cvt_pk_bf16_f32 v34, v34, v35
	v_cvt_pk_bf16_f32 v35, v40, v41
	global_store_dwordx4 v[48:49], v[32:35], off offset:256
	v_and_b32_e32 v37, 0xffff0000, v157
	v_lshlrev_b32_e32 v38, 16, v158
	v_lshlrev_b32_e32 v34, 16, v156
	v_and_b32_e32 v35, 0xffff0000, v156
	v_and_b32_e32 v39, 0xffff0000, v158
	v_lshlrev_b32_e32 v40, 16, v159
	v_and_b32_e32 v41, 0xffff0000, v159
	v_lshl_add_u64 v[32:33], v[222:223], 0, v[220:221]
	v_pk_fma_f32 v[30:31], v[30:31], v[142:143], v[36:37]
	v_pk_fma_f32 v[28:29], v[28:29], v[140:141], v[34:35]
	v_pk_fma_f32 v[34:35], v[26:27], v[138:139], v[40:41]
	v_pk_fma_f32 v[26:27], v[24:25], v[136:137], v[38:39]
	v_cvt_pk_bf16_f32 v24, v28, v29
	v_cvt_pk_bf16_f32 v25, v30, v31
	v_lshlrev_b32_e32 v28, 16, v154
	v_cvt_pk_bf16_f32 v26, v26, v27
	v_cvt_pk_bf16_f32 v27, v34, v35
	global_store_dwordx4 v[32:33], v[24:27], off
	v_and_b32_e32 v29, 0xffff0000, v154
	v_lshlrev_b32_e32 v30, 16, v155
	v_lshlrev_b32_e32 v24, 16, v152
	v_and_b32_e32 v25, 0xffff0000, v152
	v_and_b32_e32 v31, 0xffff0000, v155
	v_lshlrev_b32_e32 v26, 16, v153
	v_and_b32_e32 v27, 0xffff0000, v153
	v_pk_fma_f32 v[20:21], v[20:21], v[132:133], v[24:25]
	v_pk_fma_f32 v[24:25], v[18:19], v[130:131], v[30:31]
	v_pk_fma_f32 v[18:19], v[16:17], v[128:129], v[28:29]
	v_pk_fma_f32 v[22:23], v[22:23], v[134:135], v[26:27]
	v_cvt_pk_bf16_f32 v16, v20, v21
	v_lshlrev_b32_e32 v20, 16, v149
	v_cvt_pk_bf16_f32 v17, v22, v23
	v_cvt_pk_bf16_f32 v18, v18, v19
	v_cvt_pk_bf16_f32 v19, v24, v25
	global_store_dwordx4 v[32:33], v[16:19], off offset:256
	v_and_b32_e32 v21, 0xffff0000, v149
	v_lshlrev_b32_e32 v22, 16, v150
	v_lshlrev_b32_e32 v18, 16, v148
	v_and_b32_e32 v19, 0xffff0000, v148
	v_and_b32_e32 v23, 0xffff0000, v150
	v_lshlrev_b32_e32 v24, 16, v151
	v_and_b32_e32 v25, 0xffff0000, v151
	v_lshl_add_u64 v[16:17], v[222:223], 0, v[218:219]
	v_pk_fma_f32 v[14:15], v[14:15], v[142:143], v[20:21]
	v_pk_fma_f32 v[12:13], v[12:13], v[140:141], v[18:19]
	v_pk_fma_f32 v[18:19], v[10:11], v[138:139], v[24:25]
	v_pk_fma_f32 v[10:11], v[8:9], v[136:137], v[22:23]
	v_cvt_pk_bf16_f32 v8, v12, v13
	v_cvt_pk_bf16_f32 v9, v14, v15
	v_lshlrev_b32_e32 v12, 16, v146
	v_cvt_pk_bf16_f32 v10, v10, v11
	v_cvt_pk_bf16_f32 v11, v18, v19
	global_store_dwordx4 v[16:17], v[8:11], off
	v_and_b32_e32 v13, 0xffff0000, v146
	v_lshlrev_b32_e32 v14, 16, v147
	v_lshlrev_b32_e32 v8, 16, v144
	v_and_b32_e32 v9, 0xffff0000, v144
	v_and_b32_e32 v15, 0xffff0000, v147
	v_lshlrev_b32_e32 v10, 16, v145
	v_and_b32_e32 v11, 0xffff0000, v145
	v_pk_fma_f32 v[4:5], v[4:5], v[132:133], v[8:9]
	v_pk_fma_f32 v[8:9], v[2:3], v[130:131], v[14:15]
	v_pk_fma_f32 v[2:3], v[0:1], v[128:129], v[12:13]
	v_pk_fma_f32 v[6:7], v[6:7], v[134:135], v[10:11]
	v_cvt_pk_bf16_f32 v0, v4, v5
	s_nop 0
	v_cvt_pk_bf16_f32 v1, v6, v7
	v_cvt_pk_bf16_f32 v2, v2, v3
	v_cvt_pk_bf16_f32 v3, v8, v9
	global_store_dwordx4 v[16:17], v[0:3], off offset:256
	s_cbranch_vccz .LBB0_891
	s_waitcnt vmcnt(0)
	s_cmpk_gt_u32 s33, 0xff
	s_cbranch_scc1 .LBB0_906
	s_barrier

; #define PG8_STAGE(bufoff, gbase, voff) do { _Pragma("unroll") for (int _i = 0; _i < 2; ++_i) \
;         __builtin_amdgcn_global_load_lds((const unsigned*)((const char*)(gbase) + (voff)[_i]), (LAS unsigned*)(lds + (bufoff) + ldsw + _i * 8192), 16, 0, 0); } while (0)
; #define PG8_LDA(dst, b, h) do { _Pragma("unroll") for (int m = 0; m < 4; ++m) _Pragma("unroll") for (int k = 0; k < 2; ++k) dst[m][k] = *(const LAS bf16x8*)(lds + PG8_SA(b, h) + aoff + m * 2048 + k * 1024); } while (0)
; #define PG8_LDB(dst, b, h) do { _Pragma("unroll") for (int n = 0; n < 2; ++n) _Pragma("unroll") for (int k = 0; k < 2; ++k) dst[n][k] = *(const LAS bf16x8*)(lds + PG8_SB(b, h) + boff + n * 2048 + k * 1024); } while (0)
; #define PG8_WAIT_V(n) asm volatile("s_waitcnt vmcnt(" #n ")" ::: "memory")
; #define PG8_WAIT_L(n) asm volatile("s_waitcnt lgkmcnt(" #n ")" ::: "memory")
; #define PG8_BAR __builtin_amdgcn_s_barrier()
; #define PG8_SCHED __builtin_amdgcn_sched_barrier(0)
; template <class Epi, class Sched>
; __device__ __forceinline__ void gemm_phase(LAS unsigned char* lds, const Gemm g, const Sched& S, const Epi& E) {
;     ...
;         const bool has_next = S.next(ui + 1, nxt);
;         const char* nA = has_next ? (const char*)g.A + (size_t)nxt.pm * tstep : cA; const char* nB = has_next ? (const char*)g.Bt + (size_t)nxt.pn * tstep : cB;
;         for (int t = 0; t < nt; t += 2) {
;             const bool last = (t == nt - 2);
;             const char* a1 = cA + (size_t)(t + 1) * kstep;
;             const char* a2 = last ? nA : cA + (size_t)(t + 2) * kstep; const char* b2 = last ? nB : cB + (size_t)(t + 2) * kstep;
;             const char* a3 = a2 + kstep; const char* b3 = b2 + kstep;
;             PG8_LDB(B0, 0, 0); PG8_SCHED; PG8_LDA(At, 0, 0); PG8_STAGE(PG8_SA(1, 1), a1 + hstep, voffA);
;             PG8_WAIT_L(8); PG8_BAR; PG8_WAIT_L(0); PG8_MMA(0, 0, At, B0); PG8_BAR; PG8_SCHED;
;             PG8_LDB(B1, 0, 1); PG8_STAGE(PG8_SB(0, 0), b2, voffB);
;             PG8_BAR; PG8_WAIT_L(0); PG8_MMA(0, 1, At, B1); PG8_BAR;
;             PG8_LDA(At, 0, 1); PG8_STAGE(PG8_SA(0, 0), a2, voffA);
;             PG8_BAR; PG8_WAIT_L(0); PG8_MMA(1, 0, At, B0); PG8_BAR; PG8_SCHED;
;             PG8_STAGE(PG8_SB(0, 1), b2 + hstep, voffB);
;             PG8_WAIT_V(6); PG8_BAR; PG8_MMA(1, 1, At, B1); PG8_BAR;
.LBB0_1020:
	s_ashr_i32 s7, s6, 31
	v_cmp_lt_i64_e32 vcc, s[10:11], v[140:141]
	s_lshl_b64 s[10:11], s[6:7], 19
	s_add_u32 s10, s96, s10
	s_addc_u32 s11, s97, s11
	s_and_b64 s[12:13], vcc, exec
	s_cselect_b32 s7, s11, s17
	s_cselect_b32 s42, s10, s16
	s_ashr_i32 s5, s4, 31
	s_lshl_b64 s[12:13], s[4:5], 19
	s_add_u32 s12, s23, s12
	s_addc_u32 s13, s24, s13
	s_and_b64 s[20:21], vcc, exec
	s_cselect_b32 s5, s13, s19
	s_cselect_b32 s43, s12, s18
	s_add_u32 s16, s16, 0x40080
	s_addc_u32 s17, s17, 0
	s_add_u32 s44, s18, 0x100
	s_addc_u32 s45, s19, 0
	s_mov_b32 s46, -2
	ds_read_b128 v[150:153], v147
	ds_read_b128 v[154:157], v147 offset:1024
	ds_read_b128 v[158:161], v147 offset:2048
	ds_read_b128 v[162:165], v147 offset:3072
	s_add_u32 s18, s16, 0xfffc0080
	s_addc_u32 s19, s17, -1
	s_cmp_eq_u32 s46, 12
	s_cselect_b32 s21, s7, s19
	s_cselect_b32 s20, s42, s18
	s_cselect_b32 s19, s5, s45
	s_cselect_b32 s18, s43, s44
	s_add_i32 m0, s15, 0xc000
	ds_read_b128 v[166:169], v148
	ds_read_b128 v[170:173], v148 offset:1024
	ds_read_b128 v[174:177], v148 offset:2048
	ds_read_b128 v[178:181], v148 offset:3072
	ds_read_b128 v[182:185], v148 offset:4096
	ds_read_b128 v[186:189], v148 offset:5120
	ds_read_b128 v[190:193], v148 offset:6144
	ds_read_b128 v[194:197], v148 offset:7168
	global_load_lds_dwordx4 v136, s[16:17]
	s_add_i32 m0, s15, 0xe000
	s_nop 0
	global_load_lds_dwordx4 v138, s[16:17]
	s_waitcnt lgkmcnt(8)
	s_waitcnt vmcnt(8)
	s_barrier
	s_waitcnt lgkmcnt(0)
	s_setprio 1
	s_waitcnt lgkmcnt(0)
	v_mfma_f32_16x16x32_bf16 v[124:127], v[150:153], v[166:169], 0
	v_mfma_f32_16x16x32_bf16 v[116:119], v[158:161], v[166:169], 0
	v_mfma_f32_16x16x32_bf16 v[108:111], v[150:153], v[174:177], 0
	v_mfma_f32_16x16x32_bf16 v[100:103], v[158:161], v[174:177], 0
	v_mfma_f32_16x16x32_bf16 v[92:95], v[150:153], v[182:185], 0
	v_mfma_f32_16x16x32_bf16 v[84:87], v[158:161], v[182:185], 0
	v_mfma_f32_16x16x32_bf16 v[76:79], v[150:153], v[190:193], 0
	v_mfma_f32_16x16x32_bf16 v[68:71], v[158:161], v[190:193], 0
	v_mfma_f32_16x16x32_bf16 v[124:127], v[154:157], v[170:173], v[124:127]
	v_mfma_f32_16x16x32_bf16 v[116:119], v[162:165], v[170:173], v[116:119]
	v_mfma_f32_16x16x32_bf16 v[108:111], v[154:157], v[178:181], v[108:111]
	v_mfma_f32_16x16x32_bf16 v[100:103], v[162:165], v[178:181], v[100:103]
	v_mfma_f32_16x16x32_bf16 v[92:95], v[154:157], v[186:189], v[92:95]
	v_mfma_f32_16x16x32_bf16 v[84:87], v[162:165], v[186:189], v[84:87]
	v_mfma_f32_16x16x32_bf16 v[76:79], v[154:157], v[194:197], v[76:79]
	v_mfma_f32_16x16x32_bf16 v[68:71], v[162:165], v[194:197], v[68:71]
	s_setprio 0
	s_barrier
	s_add_i32 s47, s38, s25
	s_mov_b32 m0, s47
	ds_read_b128 v[202:205], v149
	ds_read_b128 v[206:209], v149 offset:1024
	ds_read_b128 v[210:213], v149 offset:2048
	ds_read_b128 v[214:217], v149 offset:3072
	global_load_lds_dwordx4 v132, s[18:19]
	s_add_i32 m0, s47, 0x2000
	s_nop 0
	global_load_lds_dwordx4 v128, s[18:19]
	s_waitcnt vmcnt(8)
	s_barrier
	s_waitcnt lgkmcnt(0)
	s_setprio 1
	s_waitcnt lgkmcnt(0)
	v_mfma_f32_16x16x32_bf16 v[120:123], v[202:205], v[166:169], 0
	v_mfma_f32_16x16x32_bf16 v[112:115], v[210:213], v[166:169], 0
	v_mfma_f32_16x16x32_bf16 v[104:107], v[202:205], v[174:177], 0
	v_mfma_f32_16x16x32_bf16 v[96:99], v[210:213], v[174:177], 0
	v_mfma_f32_16x16x32_bf16 v[88:91], v[202:205], v[182:185], 0
	v_mfma_f32_16x16x32_bf16 v[80:83], v[210:213], v[182:185], 0
	v_mfma_f32_16x16x32_bf16 v[72:75], v[202:205], v[190:193], 0
	v_mfma_f32_16x16x32_bf16 v[64:67], v[210:213], v[190:193], 0
	v_mfma_f32_16x16x32_bf16 v[120:123], v[206:209], v[170:173], v[120:123]
	v_mfma_f32_16x16x32_bf16 v[112:115], v[214:217], v[170:173], v[112:115]
	v_mfma_f32_16x16x32_bf16 v[104:107], v[206:209], v[178:181], v[104:107]
	v_mfma_f32_16x16x32_bf16 v[96:99], v[214:217], v[178:181], v[96:99]
	v_mfma_f32_16x16x32_bf16 v[88:91], v[206:209], v[186:189], v[88:91]
	v_mfma_f32_16x16x32_bf16 v[80:83], v[214:217], v[186:189], v[80:83]
	v_mfma_f32_16x16x32_bf16 v[72:75], v[206:209], v[194:197], v[72:75]
	v_mfma_f32_16x16x32_bf16 v[64:67], v[214:217], v[194:197], v[64:67]
	s_setprio 0
	s_mov_b32 m0, s15
	v_lshl_add_u64 v[220:221], s[20:21], 0, v[134:135]
	s_barrier
	ds_read_b128 v[166:169], v148 offset:16384
	ds_read_b128 v[170:173], v148 offset:17408
	ds_read_b128 v[174:177], v148 offset:18432
	ds_read_b128 v[178:181], v148 offset:19456
	ds_read_b128 v[182:185], v148 offset:20480
	ds_read_b128 v[186:189], v148 offset:21504
	ds_read_b128 v[190:193], v148 offset:22528
	ds_read_b128 v[194:197], v148 offset:23552
	global_load_lds_dwordx4 v134, s[20:21]
	v_lshl_add_u64 v[222:223], s[20:21], 0, v[130:131]
	s_mov_b32 m0, s28
	s_nop 0
	global_load_lds_dwordx4 v130, s[20:21]
	s_barrier
	s_waitcnt lgkmcnt(0)
	s_setprio 1
	s_waitcnt lgkmcnt(0)
	v_mfma_f32_16x16x32_bf16 v[60:63], v[150:153], v[166:169], 0
	v_mfma_f32_16x16x32_bf16 v[56:59], v[158:161], v[166:169], 0
	v_mfma_f32_16x16x32_bf16 v[44:47], v[150:153], v[174:177], 0
	v_mfma_f32_16x16x32_bf16 v[40:43], v[158:161], v[174:177], 0
	v_mfma_f32_16x16x32_bf16 v[28:31], v[150:153], v[182:185], 0
	v_mfma_f32_16x16x32_bf16 v[24:27], v[158:161], v[182:185], 0
	v_mfma_f32_16x16x32_bf16 v[12:15], v[150:153], v[190:193], 0
	v_mfma_f32_16x16x32_bf16 v[8:11], v[158:161], v[190:193], 0
	v_mfma_f32_16x16x32_bf16 v[60:63], v[154:157], v[170:173], v[60:63]
	v_mfma_f32_16x16x32_bf16 v[56:59], v[162:165], v[170:173], v[56:59]
	v_mfma_f32_16x16x32_bf16 v[44:47], v[154:157], v[178:181], v[44:47]
	v_mfma_f32_16x16x32_bf16 v[40:43], v[162:165], v[178:181], v[40:43]
	v_mfma_f32_16x16x32_bf16 v[28:31], v[154:157], v[186:189], v[28:31]
	v_mfma_f32_16x16x32_bf16 v[24:27], v[162:165], v[186:189], v[24:27]
	v_mfma_f32_16x16x32_bf16 v[12:15], v[154:157], v[194:197], v[12:15]
	v_mfma_f32_16x16x32_bf16 v[8:11], v[162:165], v[194:197], v[8:11]
	s_setprio 0
	s_barrier
; #define PG8_STAGE(bufoff, gbase, voff) do { _Pragma("unroll") for (int _i = 0; _i < 2; ++_i) \
;         __builtin_amdgcn_global_load_lds((const unsigned*)((const char*)(gbase) + (voff)[_i]), (LAS unsigned*)(lds + (bufoff) + ldsw + _i * 8192), 16, 0, 0); } while (0)
; #define PG8_LDA(dst, b, h) do { _Pragma("unroll") for (int m = 0; m < 4; ++m) _Pragma("unroll") for (int k = 0; k < 2; ++k) dst[m][k] = *(const LAS bf16x8*)(lds + PG8_SA(b, h) + aoff + m * 2048 + k * 1024); } while (0)
; #define PG8_LDB(dst, b, h) do { _Pragma("unroll") for (int n = 0; n < 2; ++n) _Pragma("unroll") for (int k = 0; k < 2; ++k) dst[n][k] = *(const LAS bf16x8*)(lds + PG8_SB(b, h) + boff + n * 2048 + k * 1024); } while (0)
; #define PG8_MMA(ai, bj, At, Bt) do { __builtin_amdgcn_s_setprio(1); _Pragma("unroll") for (int m = 0; m < 4; ++m) _Pragma("unroll") for (int n = 0; n < 2; ++n) _Pragma("unroll") for (int k = 0; k < 2; ++k) \
;         acc[ai][bj][m][n] = __builtin_amdgcn_mfma_f32_16x16x32_bf16(Bt[n][k], At[m][k], acc[ai][bj][m][n], 0, 0, 0); __builtin_amdgcn_s_setprio(0); } while (0)
; #define PG8_WAIT_V(n) asm volatile("s_waitcnt vmcnt(" #n ")" ::: "memory")
; #define PG8_WAIT_L(n) asm volatile("s_waitcnt lgkmcnt(" #n ")" ::: "memory")
; #define PG8_BAR __builtin_amdgcn_s_barrier()
; #define PG8_SCHED __builtin_amdgcn_sched_barrier(0)
; template <class Epi, class Sched>
; __device__ __forceinline__ void gemm_phase(LAS unsigned char* lds, const Gemm g, const Sched& S, const Epi& E) {
;     ...
;             PG8_LDB(B1, 0, 1); PG8_STAGE(PG8_SB(0, 0), b2, voffB);
;             PG8_BAR; PG8_WAIT_L(0); PG8_MMA(0, 1, At, B1); PG8_BAR;
;             PG8_LDA(At, 0, 1); PG8_STAGE(PG8_SA(0, 0), a2, voffA);
;             PG8_BAR; PG8_WAIT_L(0); PG8_MMA(1, 0, At, B0); PG8_BAR; PG8_SCHED;
;             PG8_STAGE(PG8_SB(0, 1), b2 + hstep, voffB);
;             PG8_WAIT_V(6); PG8_BAR; PG8_MMA(1, 1, At, B1); PG8_BAR;
;             PG8_LDB(B0, 1, 0); PG8_SCHED; PG8_LDA(At, 1, 0); PG8_STAGE(PG8_SA(0, 1), a2 + hstep, voffA);
;             PG8_WAIT_L(8); PG8_BAR; PG8_WAIT_L(0); PG8_MMA(0, 0, At, B0); PG8_BAR; PG8_SCHED;
;             PG8_LDB(B1, 1, 1); PG8_STAGE(PG8_SB(1, 0), b3, voffB);
;             PG8_BAR; PG8_WAIT_L(0); PG8_MMA(0, 1, At, B1); PG8_BAR;
;             PG8_LDA(At, 1, 1); PG8_STAGE(PG8_SA(1, 0), a3, voffA);
	s_add_u32 s48, s18, 0x40000
	s_addc_u32 s49, s19, 0
	s_add_i32 s47, s39, s25
	s_mov_b32 m0, s47
	s_nop 0
	global_load_lds_dwordx4 v132, s[48:49]
	s_add_i32 m0, s47, 0x2000
	s_nop 0
	global_load_lds_dwordx4 v128, s[48:49]
	s_add_u32 s20, s20, 0x40000
	s_addc_u32 s21, s21, 0
	s_mov_b32 m0, s29
	s_nop 0
	global_load_lds_dwordx4 v134, s[20:21]
	s_mov_b32 m0, s30
	s_nop 0
	global_load_lds_dwordx4 v130, s[20:21]
	s_waitcnt vmcnt(10)
	s_barrier
	s_setprio 1
	v_mfma_f32_16x16x32_bf16 v[52:55], v[202:205], v[166:169], 0
	v_mfma_f32_16x16x32_bf16 v[48:51], v[210:213], v[166:169], 0
	v_mfma_f32_16x16x32_bf16 v[36:39], v[202:205], v[174:177], 0
	v_mfma_f32_16x16x32_bf16 v[32:35], v[210:213], v[174:177], 0
	v_mfma_f32_16x16x32_bf16 v[20:23], v[202:205], v[182:185], 0
	v_mfma_f32_16x16x32_bf16 v[16:19], v[210:213], v[182:185], 0
	v_mfma_f32_16x16x32_bf16 v[4:7], v[202:205], v[190:193], 0
	v_mfma_f32_16x16x32_bf16 v[0:3], v[210:213], v[190:193], 0
	v_mfma_f32_16x16x32_bf16 v[52:55], v[206:209], v[170:173], v[52:55]
	v_mfma_f32_16x16x32_bf16 v[48:51], v[214:217], v[170:173], v[48:51]
	v_mfma_f32_16x16x32_bf16 v[36:39], v[206:209], v[178:181], v[36:39]
	v_mfma_f32_16x16x32_bf16 v[32:35], v[214:217], v[178:181], v[32:35]
	v_mfma_f32_16x16x32_bf16 v[20:23], v[206:209], v[186:189], v[20:23]
	v_mfma_f32_16x16x32_bf16 v[16:19], v[214:217], v[186:189], v[16:19]
	v_mfma_f32_16x16x32_bf16 v[4:7], v[206:209], v[194:197], v[4:7]
	v_mfma_f32_16x16x32_bf16 v[0:3], v[214:217], v[194:197], v[0:3]
	s_setprio 0
	s_add_i32 s47, 0, 0x18000
	v_add_u32_e32 v162, s47, v146
	s_barrier
	ds_read_b128 v[150:153], v162
	ds_read_b128 v[154:157], v162 offset:1024
	ds_read_b128 v[158:161], v162 offset:2048
	ds_read_b128 v[162:165], v162 offset:3072
	ds_read_b128 v[166:169], v148 offset:32768
	ds_read_b128 v[170:173], v148 offset:33792
	ds_read_b128 v[174:177], v148 offset:34816
	ds_read_b128 v[178:181], v148 offset:35840
	ds_read_b128 v[182:185], v148 offset:36864
	ds_read_b128 v[186:189], v148 offset:37888
	ds_read_b128 v[190:193], v148 offset:38912
	ds_read_b128 v[194:197], v148 offset:39936
	s_waitcnt lgkmcnt(8)
	s_waitcnt vmcnt(8)
	s_barrier
	s_waitcnt lgkmcnt(0)
	s_setprio 1
	s_waitcnt lgkmcnt(0)
	v_mfma_f32_16x16x32_bf16 v[124:127], v[150:153], v[166:169], v[124:127]
	v_mfma_f32_16x16x32_bf16 v[116:119], v[158:161], v[166:169], v[116:119]
	v_mfma_f32_16x16x32_bf16 v[108:111], v[150:153], v[174:177], v[108:111]
	v_mfma_f32_16x16x32_bf16 v[100:103], v[158:161], v[174:177], v[100:103]
	v_mfma_f32_16x16x32_bf16 v[92:95], v[150:153], v[182:185], v[92:95]
	v_mfma_f32_16x16x32_bf16 v[84:87], v[158:161], v[182:185], v[84:87]
	v_mfma_f32_16x16x32_bf16 v[76:79], v[150:153], v[190:193], v[76:79]
	v_mfma_f32_16x16x32_bf16 v[68:71], v[158:161], v[190:193], v[68:71]
	v_mfma_f32_16x16x32_bf16 v[124:127], v[154:157], v[170:173], v[124:127]
	v_mfma_f32_16x16x32_bf16 v[116:119], v[162:165], v[170:173], v[116:119]
	v_mfma_f32_16x16x32_bf16 v[108:111], v[154:157], v[178:181], v[108:111]
	v_mfma_f32_16x16x32_bf16 v[100:103], v[162:165], v[178:181], v[100:103]
	v_mfma_f32_16x16x32_bf16 v[92:95], v[154:157], v[186:189], v[92:95]
	v_mfma_f32_16x16x32_bf16 v[84:87], v[162:165], v[186:189], v[84:87]
	v_mfma_f32_16x16x32_bf16 v[76:79], v[154:157], v[194:197], v[76:79]
	v_mfma_f32_16x16x32_bf16 v[68:71], v[162:165], v[194:197], v[68:71]
	s_setprio 0
	s_barrier
	s_add_i32 s20, 0, 0x1c000
	s_add_i32 s21, s47, s25
	v_add_u32_e32 v214, s20, v146
	s_add_u32 s0, s18, 0x80
	s_addc_u32 s1, s19, 0
	s_mov_b32 m0, s21
	ds_read_b128 v[202:205], v214
	ds_read_b128 v[206:209], v214 offset:1024
	ds_read_b128 v[210:213], v214 offset:2048
	ds_read_b128 v[214:217], v214 offset:3072
	global_load_lds_dwordx4 v132, s[0:1]
	s_add_i32 m0, s21, 0x2000
	s_nop 0
	global_load_lds_dwordx4 v128, s[0:1]
	s_waitcnt vmcnt(8)
	s_barrier
	s_waitcnt lgkmcnt(0)
	s_setprio 1
	s_waitcnt lgkmcnt(0)
	v_mfma_f32_16x16x32_bf16 v[120:123], v[202:205], v[166:169], v[120:123]
	v_mfma_f32_16x16x32_bf16 v[112:115], v[210:213], v[166:169], v[112:115]
	v_mfma_f32_16x16x32_bf16 v[104:107], v[202:205], v[174:177], v[104:107]
	v_mfma_f32_16x16x32_bf16 v[96:99], v[210:213], v[174:177], v[96:99]
	v_mfma_f32_16x16x32_bf16 v[88:91], v[202:205], v[182:185], v[88:91]
	v_mfma_f32_16x16x32_bf16 v[80:83], v[210:213], v[182:185], v[80:83]
	v_mfma_f32_16x16x32_bf16 v[72:75], v[202:205], v[190:193], v[72:75]
	v_mfma_f32_16x16x32_bf16 v[64:67], v[210:213], v[190:193], v[64:67]
	v_mfma_f32_16x16x32_bf16 v[120:123], v[206:209], v[170:173], v[120:123]
	v_mfma_f32_16x16x32_bf16 v[112:115], v[214:217], v[170:173], v[112:115]
	v_mfma_f32_16x16x32_bf16 v[104:107], v[206:209], v[178:181], v[104:107]
	v_mfma_f32_16x16x32_bf16 v[96:99], v[214:217], v[178:181], v[96:99]
	v_mfma_f32_16x16x32_bf16 v[88:91], v[206:209], v[186:189], v[88:91]
	v_mfma_f32_16x16x32_bf16 v[80:83], v[214:217], v[186:189], v[80:83]
	v_mfma_f32_16x16x32_bf16 v[72:75], v[206:209], v[194:197], v[72:75]
	v_mfma_f32_16x16x32_bf16 v[64:67], v[214:217], v[194:197], v[64:67]
	s_setprio 0
	s_mov_b32 m0, s35
	s_mov_b64 s[0:1], 0x80
	v_lshl_add_u64 v[198:199], v[220:221], 0, s[0:1]
	s_barrier
	ds_read_b128 v[166:169], v148 offset:49152
	ds_read_b128 v[170:173], v148 offset:50176
	ds_read_b128 v[174:177], v148 offset:51200
	ds_read_b128 v[178:181], v148 offset:52224
	ds_read_b128 v[182:185], v148 offset:53248
	ds_read_b128 v[186:189], v148 offset:54272
	ds_read_b128 v[190:193], v148 offset:55296
	ds_read_b128 v[194:197], v148 offset:56320
	global_load_lds_dwordx4 v[198:199], off
	v_lshl_add_u64 v[198:199], v[222:223], 0, s[0:1]
	s_mov_b32 m0, s36
	s_nop 0
	global_load_lds_dwordx4 v[198:199], off
	s_barrier
; #define PG8_STAGE(bufoff, gbase, voff) do { _Pragma("unroll") for (int _i = 0; _i < 2; ++_i) \
;         __builtin_amdgcn_global_load_lds((const unsigned*)((const char*)(gbase) + (voff)[_i]), (LAS unsigned*)(lds + (bufoff) + ldsw + _i * 8192), 16, 0, 0); } while (0)
; #define PG8_LDA(dst, b, h) do { _Pragma("unroll") for (int m = 0; m < 4; ++m) _Pragma("unroll") for (int k = 0; k < 2; ++k) dst[m][k] = *(const LAS bf16x8*)(lds + PG8_SA(b, h) + aoff + m * 2048 + k * 1024); } while (0)
; #define PG8_LDB(dst, b, h) do { _Pragma("unroll") for (int n = 0; n < 2; ++n) _Pragma("unroll") for (int k = 0; k < 2; ++k) dst[n][k] = *(const LAS bf16x8*)(lds + PG8_SB(b, h) + boff + n * 2048 + k * 1024); } while (0)
; #define PG8_WAIT_V(n) asm volatile("s_waitcnt vmcnt(" #n ")" ::: "memory")
; #define PG8_WAIT_L(n) asm volatile("s_waitcnt lgkmcnt(" #n ")" ::: "memory")
; #define PG8_BAR __builtin_amdgcn_s_barrier()
; #define PG8_SCHED __builtin_amdgcn_sched_barrier(0)
; template <class Epi, class Sched>
; __device__ __forceinline__ void gemm_phase(LAS unsigned char* lds, const Gemm g, const Sched& S, const Epi& E) {
;     ...
;             PG8_LDB(B0, 0, 0); PG8_SCHED; PG8_LDA(At, 0, 0); PG8_STAGE(PG8_SA(1, 1), a1 + hstep, voffA);
;             PG8_WAIT_L(8); PG8_BAR; PG8_WAIT_L(0); PG8_MMA(0, 0, At, B0); PG8_BAR; PG8_SCHED;
;             PG8_LDB(B1, 0, 1); PG8_STAGE(PG8_SB(0, 0), b2, voffB);
;             PG8_BAR; PG8_WAIT_L(0); PG8_MMA(0, 1, At, B1); PG8_BAR;
;             PG8_LDA(At, 0, 1); PG8_STAGE(PG8_SA(0, 0), a2, voffA);
;             PG8_BAR; PG8_WAIT_L(0); PG8_MMA(1, 0, At, B0); PG8_BAR; PG8_SCHED;
;             PG8_STAGE(PG8_SB(0, 1), b2 + hstep, voffB);
;             PG8_WAIT_V(6); PG8_BAR; PG8_MMA(1, 1, At, B1); PG8_BAR;
;             PG8_LDB(B0, 1, 0); PG8_SCHED; PG8_LDA(At, 1, 0); PG8_STAGE(PG8_SA(0, 1), a2 + hstep, voffA);
;             PG8_WAIT_L(8); PG8_BAR; PG8_WAIT_L(0); PG8_MMA(0, 0, At, B0); PG8_BAR; PG8_SCHED;
;             PG8_LDB(B1, 1, 1); PG8_STAGE(PG8_SB(1, 0), b3, voffB);
;             PG8_BAR; PG8_WAIT_L(0); PG8_MMA(0, 1, At, B1); PG8_BAR;
;             PG8_LDA(At, 1, 1); PG8_STAGE(PG8_SA(1, 0), a3, voffA);
;             PG8_BAR; PG8_WAIT_L(0); PG8_MMA(1, 0, At, B0); PG8_BAR; PG8_SCHED;
;             PG8_STAGE(PG8_SB(1, 1), b3 + hstep, voffB);
;             PG8_WAIT_V(6); PG8_BAR; PG8_MMA(1, 1, At, B1); PG8_BAR;
	s_waitcnt lgkmcnt(0)
	s_setprio 1
	s_waitcnt lgkmcnt(0)
	v_mfma_f32_16x16x32_bf16 v[60:63], v[150:153], v[166:169], v[60:63]
	v_mfma_f32_16x16x32_bf16 v[56:59], v[158:161], v[166:169], v[56:59]
	v_mfma_f32_16x16x32_bf16 v[44:47], v[150:153], v[174:177], v[44:47]
	v_mfma_f32_16x16x32_bf16 v[40:43], v[158:161], v[174:177], v[40:43]
	v_mfma_f32_16x16x32_bf16 v[28:31], v[150:153], v[182:185], v[28:31]
	v_mfma_f32_16x16x32_bf16 v[24:27], v[158:161], v[182:185], v[24:27]
	v_mfma_f32_16x16x32_bf16 v[12:15], v[150:153], v[190:193], v[12:15]
	v_mfma_f32_16x16x32_bf16 v[8:11], v[158:161], v[190:193], v[8:11]
	v_mfma_f32_16x16x32_bf16 v[60:63], v[154:157], v[170:173], v[60:63]
	v_mfma_f32_16x16x32_bf16 v[56:59], v[162:165], v[170:173], v[56:59]
	v_mfma_f32_16x16x32_bf16 v[44:47], v[154:157], v[178:181], v[44:47]
	v_mfma_f32_16x16x32_bf16 v[40:43], v[162:165], v[178:181], v[40:43]
	v_mfma_f32_16x16x32_bf16 v[28:31], v[154:157], v[186:189], v[28:31]
	v_mfma_f32_16x16x32_bf16 v[24:27], v[162:165], v[186:189], v[24:27]
	v_mfma_f32_16x16x32_bf16 v[12:15], v[154:157], v[194:197], v[12:15]
	v_mfma_f32_16x16x32_bf16 v[8:11], v[162:165], v[194:197], v[8:11]
	s_setprio 0
	s_barrier
	s_add_u32 s18, s18, 0x40080
	s_addc_u32 s19, s19, 0
	s_add_i32 s20, s20, s25
	s_mov_b32 m0, s20
	s_nop 0
	global_load_lds_dwordx4 v132, s[18:19]
	s_add_i32 m0, s20, 0x2000
	s_nop 0
	global_load_lds_dwordx4 v128, s[18:19]
	s_waitcnt vmcnt(8)
	s_barrier
	s_setprio 1
	v_mfma_f32_16x16x32_bf16 v[52:55], v[202:205], v[166:169], v[52:55]
	v_mfma_f32_16x16x32_bf16 v[48:51], v[210:213], v[166:169], v[48:51]
	v_mfma_f32_16x16x32_bf16 v[36:39], v[202:205], v[174:177], v[36:39]
	v_mfma_f32_16x16x32_bf16 v[32:35], v[210:213], v[174:177], v[32:35]
	v_mfma_f32_16x16x32_bf16 v[20:23], v[202:205], v[182:185], v[20:23]
	v_mfma_f32_16x16x32_bf16 v[16:19], v[210:213], v[182:185], v[16:19]
	v_mfma_f32_16x16x32_bf16 v[4:7], v[202:205], v[190:193], v[4:7]
	v_mfma_f32_16x16x32_bf16 v[0:3], v[210:213], v[190:193], v[0:3]
	v_mfma_f32_16x16x32_bf16 v[52:55], v[206:209], v[170:173], v[52:55]
	v_mfma_f32_16x16x32_bf16 v[48:51], v[214:217], v[170:173], v[48:51]
	v_mfma_f32_16x16x32_bf16 v[36:39], v[206:209], v[178:181], v[36:39]
	v_mfma_f32_16x16x32_bf16 v[32:35], v[214:217], v[178:181], v[32:35]
	v_mfma_f32_16x16x32_bf16 v[20:23], v[206:209], v[186:189], v[20:23]
	v_mfma_f32_16x16x32_bf16 v[16:19], v[214:217], v[186:189], v[16:19]
	v_mfma_f32_16x16x32_bf16 v[4:7], v[206:209], v[194:197], v[4:7]
	v_mfma_f32_16x16x32_bf16 v[0:3], v[214:217], v[194:197], v[0:3]
	s_setprio 0
	s_add_i32 s46, s46, 2
	s_add_u32 s16, s16, 0x100
	s_addc_u32 s17, s17, 0
	s_add_u32 s44, s44, 0x100
	s_addc_u32 s45, s45, 0
	s_cmp_gt_u32 s46, 13
	s_barrier
.LBB0_1021:
	ds_read_b128 v[150:153], v147
	ds_read_b128 v[154:157], v147 offset:1024
	ds_read_b128 v[158:161], v147 offset:2048
	ds_read_b128 v[162:165], v147 offset:3072
	s_add_u32 s18, s16, 0xfffc0080
	s_addc_u32 s19, s17, -1
	s_cmp_eq_u32 s46, 12
	s_cselect_b32 s21, s7, s19
	s_cselect_b32 s20, s42, s18
	s_cselect_b32 s19, s5, s45
	s_cselect_b32 s18, s43, s44
	s_add_i32 m0, s15, 0xc000
	ds_read_b128 v[166:169], v148
	ds_read_b128 v[170:173], v148 offset:1024
	ds_read_b128 v[174:177], v148 offset:2048
	ds_read_b128 v[178:181], v148 offset:3072
	ds_read_b128 v[182:185], v148 offset:4096
	ds_read_b128 v[186:189], v148 offset:5120
	ds_read_b128 v[190:193], v148 offset:6144
	ds_read_b128 v[194:197], v148 offset:7168
	global_load_lds_dwordx4 v136, s[16:17]
	s_add_i32 m0, s15, 0xe000
	s_nop 0
	global_load_lds_dwordx4 v138, s[16:17]
	s_waitcnt lgkmcnt(8)
	s_waitcnt vmcnt(8)
	s_barrier
	s_waitcnt lgkmcnt(0)
	s_setprio 1
	s_waitcnt lgkmcnt(0)
	v_mfma_f32_16x16x32_bf16 v[124:127], v[150:153], v[166:169], v[124:127]
	v_mfma_f32_16x16x32_bf16 v[116:119], v[158:161], v[166:169], v[116:119]
	v_mfma_f32_16x16x32_bf16 v[108:111], v[150:153], v[174:177], v[108:111]
	v_mfma_f32_16x16x32_bf16 v[100:103], v[158:161], v[174:177], v[100:103]
	v_mfma_f32_16x16x32_bf16 v[92:95], v[150:153], v[182:185], v[92:95]
	v_mfma_f32_16x16x32_bf16 v[84:87], v[158:161], v[182:185], v[84:87]
	v_mfma_f32_16x16x32_bf16 v[76:79], v[150:153], v[190:193], v[76:79]
	v_mfma_f32_16x16x32_bf16 v[68:71], v[158:161], v[190:193], v[68:71]
	v_mfma_f32_16x16x32_bf16 v[124:127], v[154:157], v[170:173], v[124:127]
	v_mfma_f32_16x16x32_bf16 v[116:119], v[162:165], v[170:173], v[116:119]
	v_mfma_f32_16x16x32_bf16 v[108:111], v[154:157], v[178:181], v[108:111]
	v_mfma_f32_16x16x32_bf16 v[100:103], v[162:165], v[178:181], v[100:103]
	v_mfma_f32_16x16x32_bf16 v[92:95], v[154:157], v[186:189], v[92:95]
	v_mfma_f32_16x16x32_bf16 v[84:87], v[162:165], v[186:189], v[84:87]
	v_mfma_f32_16x16x32_bf16 v[76:79], v[154:157], v[194:197], v[76:79]
	v_mfma_f32_16x16x32_bf16 v[68:71], v[162:165], v[194:197], v[68:71]
	s_setprio 0
	s_barrier
	s_add_i32 s47, s38, s25
	s_mov_b32 m0, s47
	ds_read_b128 v[202:205], v149
	ds_read_b128 v[206:209], v149 offset:1024
	ds_read_b128 v[210:213], v149 offset:2048
	ds_read_b128 v[214:217], v149 offset:3072
	global_load_lds_dwordx4 v132, s[18:19]
	s_add_i32 m0, s47, 0x2000
	s_nop 0
	global_load_lds_dwordx4 v128, s[18:19]
	s_waitcnt vmcnt(8)
	s_barrier
; #define PG8_STAGE(bufoff, gbase, voff) do { _Pragma("unroll") for (int _i = 0; _i < 2; ++_i) \
;         __builtin_amdgcn_global_load_lds((const unsigned*)((const char*)(gbase) + (voff)[_i]), (LAS unsigned*)(lds + (bufoff) + ldsw + _i * 8192), 16, 0, 0); } while (0)
; #define PG8_LDA(dst, b, h) do { _Pragma("unroll") for (int m = 0; m < 4; ++m) _Pragma("unroll") for (int k = 0; k < 2; ++k) dst[m][k] = *(const LAS bf16x8*)(lds + PG8_SA(b, h) + aoff + m * 2048 + k * 1024); } while (0)
; #define PG8_LDB(dst, b, h) do { _Pragma("unroll") for (int n = 0; n < 2; ++n) _Pragma("unroll") for (int k = 0; k < 2; ++k) dst[n][k] = *(const LAS bf16x8*)(lds + PG8_SB(b, h) + boff + n * 2048 + k * 1024); } while (0)
; #define PG8_MMA(ai, bj, At, Bt) do { __builtin_amdgcn_s_setprio(1); _Pragma("unroll") for (int m = 0; m < 4; ++m) _Pragma("unroll") for (int n = 0; n < 2; ++n) _Pragma("unroll") for (int k = 0; k < 2; ++k) \
;         acc[ai][bj][m][n] = __builtin_amdgcn_mfma_f32_16x16x32_bf16(Bt[n][k], At[m][k], acc[ai][bj][m][n], 0, 0, 0); __builtin_amdgcn_s_setprio(0); } while (0)
; #define PG8_WAIT_V(n) asm volatile("s_waitcnt vmcnt(" #n ")" ::: "memory")
; #define PG8_WAIT_L(n) asm volatile("s_waitcnt lgkmcnt(" #n ")" ::: "memory")
; #define PG8_BAR __builtin_amdgcn_s_barrier()
; #define PG8_SCHED __builtin_amdgcn_sched_barrier(0)
; template <class Epi, class Sched>
; __device__ __forceinline__ void gemm_phase(LAS unsigned char* lds, const Gemm g, const Sched& S, const Epi& E) {
;     ...
;             PG8_LDB(B1, 0, 1); PG8_STAGE(PG8_SB(0, 0), b2, voffB);
;             PG8_BAR; PG8_WAIT_L(0); PG8_MMA(0, 1, At, B1); PG8_BAR;
;             PG8_LDA(At, 0, 1); PG8_STAGE(PG8_SA(0, 0), a2, voffA);
;             PG8_BAR; PG8_WAIT_L(0); PG8_MMA(1, 0, At, B0); PG8_BAR; PG8_SCHED;
;             PG8_STAGE(PG8_SB(0, 1), b2 + hstep, voffB);
;             PG8_WAIT_V(6); PG8_BAR; PG8_MMA(1, 1, At, B1); PG8_BAR;
;             PG8_LDB(B0, 1, 0); PG8_SCHED; PG8_LDA(At, 1, 0); PG8_STAGE(PG8_SA(0, 1), a2 + hstep, voffA);
;             PG8_WAIT_L(8); PG8_BAR; PG8_WAIT_L(0); PG8_MMA(0, 0, At, B0); PG8_BAR; PG8_SCHED;
;             PG8_LDB(B1, 1, 1); PG8_STAGE(PG8_SB(1, 0), b3, voffB);
;             PG8_BAR; PG8_WAIT_L(0); PG8_MMA(0, 1, At, B1); PG8_BAR;
;             PG8_LDA(At, 1, 1); PG8_STAGE(PG8_SA(1, 0), a3, voffA);
	s_waitcnt lgkmcnt(0)
	s_setprio 1
	s_waitcnt lgkmcnt(0)
	v_mfma_f32_16x16x32_bf16 v[120:123], v[202:205], v[166:169], v[120:123]
	v_mfma_f32_16x16x32_bf16 v[112:115], v[210:213], v[166:169], v[112:115]
	v_mfma_f32_16x16x32_bf16 v[104:107], v[202:205], v[174:177], v[104:107]
	v_mfma_f32_16x16x32_bf16 v[96:99], v[210:213], v[174:177], v[96:99]
	v_mfma_f32_16x16x32_bf16 v[88:91], v[202:205], v[182:185], v[88:91]
	v_mfma_f32_16x16x32_bf16 v[80:83], v[210:213], v[182:185], v[80:83]
	v_mfma_f32_16x16x32_bf16 v[72:75], v[202:205], v[190:193], v[72:75]
	v_mfma_f32_16x16x32_bf16 v[64:67], v[210:213], v[190:193], v[64:67]
	v_mfma_f32_16x16x32_bf16 v[120:123], v[206:209], v[170:173], v[120:123]
	v_mfma_f32_16x16x32_bf16 v[112:115], v[214:217], v[170:173], v[112:115]
	v_mfma_f32_16x16x32_bf16 v[104:107], v[206:209], v[178:181], v[104:107]
	v_mfma_f32_16x16x32_bf16 v[96:99], v[214:217], v[178:181], v[96:99]
	v_mfma_f32_16x16x32_bf16 v[88:91], v[206:209], v[186:189], v[88:91]
	v_mfma_f32_16x16x32_bf16 v[80:83], v[214:217], v[186:189], v[80:83]
	v_mfma_f32_16x16x32_bf16 v[72:75], v[206:209], v[194:197], v[72:75]
	v_mfma_f32_16x16x32_bf16 v[64:67], v[214:217], v[194:197], v[64:67]
	s_setprio 0
	s_mov_b32 m0, s15
	v_lshl_add_u64 v[220:221], s[20:21], 0, v[134:135]
	s_barrier
	ds_read_b128 v[166:169], v148 offset:16384
	ds_read_b128 v[170:173], v148 offset:17408
	ds_read_b128 v[174:177], v148 offset:18432
	ds_read_b128 v[178:181], v148 offset:19456
	ds_read_b128 v[182:185], v148 offset:20480
	ds_read_b128 v[186:189], v148 offset:21504
	ds_read_b128 v[190:193], v148 offset:22528
	ds_read_b128 v[194:197], v148 offset:23552
	global_load_lds_dwordx4 v134, s[20:21]
	v_lshl_add_u64 v[222:223], s[20:21], 0, v[130:131]
	s_mov_b32 m0, s28
	s_nop 0
	global_load_lds_dwordx4 v130, s[20:21]
	s_barrier
	s_waitcnt lgkmcnt(0)
	s_setprio 1
	s_waitcnt lgkmcnt(0)
	v_mfma_f32_16x16x32_bf16 v[60:63], v[150:153], v[166:169], v[60:63]
	v_mfma_f32_16x16x32_bf16 v[56:59], v[158:161], v[166:169], v[56:59]
	v_mfma_f32_16x16x32_bf16 v[44:47], v[150:153], v[174:177], v[44:47]
	v_mfma_f32_16x16x32_bf16 v[40:43], v[158:161], v[174:177], v[40:43]
	v_mfma_f32_16x16x32_bf16 v[28:31], v[150:153], v[182:185], v[28:31]
	v_mfma_f32_16x16x32_bf16 v[24:27], v[158:161], v[182:185], v[24:27]
	v_mfma_f32_16x16x32_bf16 v[12:15], v[150:153], v[190:193], v[12:15]
	v_mfma_f32_16x16x32_bf16 v[8:11], v[158:161], v[190:193], v[8:11]
	v_mfma_f32_16x16x32_bf16 v[60:63], v[154:157], v[170:173], v[60:63]
	v_mfma_f32_16x16x32_bf16 v[56:59], v[162:165], v[170:173], v[56:59]
	v_mfma_f32_16x16x32_bf16 v[44:47], v[154:157], v[178:181], v[44:47]
	v_mfma_f32_16x16x32_bf16 v[40:43], v[162:165], v[178:181], v[40:43]
	v_mfma_f32_16x16x32_bf16 v[28:31], v[154:157], v[186:189], v[28:31]
	v_mfma_f32_16x16x32_bf16 v[24:27], v[162:165], v[186:189], v[24:27]
	v_mfma_f32_16x16x32_bf16 v[12:15], v[154:157], v[194:197], v[12:15]
	v_mfma_f32_16x16x32_bf16 v[8:11], v[162:165], v[194:197], v[8:11]
	s_setprio 0
	s_barrier
	s_add_u32 s48, s18, 0x40000
	s_addc_u32 s49, s19, 0
	s_add_i32 s47, s39, s25
	s_mov_b32 m0, s47
	s_nop 0
	global_load_lds_dwordx4 v132, s[48:49]
	s_add_i32 m0, s47, 0x2000
	s_nop 0
	global_load_lds_dwordx4 v128, s[48:49]
	s_add_u32 s20, s20, 0x40000
	s_addc_u32 s21, s21, 0
	s_mov_b32 m0, s29
	s_nop 0
	global_load_lds_dwordx4 v134, s[20:21]
	s_mov_b32 m0, s30
	s_nop 0
	global_load_lds_dwordx4 v130, s[20:21]
	s_waitcnt vmcnt(10)
	s_barrier
	s_setprio 1
	v_mfma_f32_16x16x32_bf16 v[52:55], v[202:205], v[166:169], v[52:55]
	v_mfma_f32_16x16x32_bf16 v[48:51], v[210:213], v[166:169], v[48:51]
	v_mfma_f32_16x16x32_bf16 v[36:39], v[202:205], v[174:177], v[36:39]
	v_mfma_f32_16x16x32_bf16 v[32:35], v[210:213], v[174:177], v[32:35]
	v_mfma_f32_16x16x32_bf16 v[20:23], v[202:205], v[182:185], v[20:23]
	v_mfma_f32_16x16x32_bf16 v[16:19], v[210:213], v[182:185], v[16:19]
	v_mfma_f32_16x16x32_bf16 v[4:7], v[202:205], v[190:193], v[4:7]
	v_mfma_f32_16x16x32_bf16 v[0:3], v[210:213], v[190:193], v[0:3]
	v_mfma_f32_16x16x32_bf16 v[52:55], v[206:209], v[170:173], v[52:55]
	v_mfma_f32_16x16x32_bf16 v[48:51], v[214:217], v[170:173], v[48:51]
	v_mfma_f32_16x16x32_bf16 v[36:39], v[206:209], v[178:181], v[36:39]
	v_mfma_f32_16x16x32_bf16 v[32:35], v[214:217], v[178:181], v[32:35]
	v_mfma_f32_16x16x32_bf16 v[20:23], v[206:209], v[186:189], v[20:23]
	v_mfma_f32_16x16x32_bf16 v[16:19], v[214:217], v[186:189], v[16:19]
	v_mfma_f32_16x16x32_bf16 v[4:7], v[206:209], v[194:197], v[4:7]
	v_mfma_f32_16x16x32_bf16 v[0:3], v[214:217], v[194:197], v[0:3]
	s_setprio 0
	s_add_i32 s47, 0, 0x18000
	v_add_u32_e32 v162, s47, v146
	s_barrier
	ds_read_b128 v[150:153], v162
	ds_read_b128 v[154:157], v162 offset:1024
	ds_read_b128 v[158:161], v162 offset:2048
	ds_read_b128 v[162:165], v162 offset:3072
	ds_read_b128 v[166:169], v148 offset:32768
	ds_read_b128 v[170:173], v148 offset:33792
	ds_read_b128 v[174:177], v148 offset:34816
	ds_read_b128 v[178:181], v148 offset:35840
	ds_read_b128 v[182:185], v148 offset:36864
	ds_read_b128 v[186:189], v148 offset:37888
	ds_read_b128 v[190:193], v148 offset:38912
	ds_read_b128 v[194:197], v148 offset:39936
	s_waitcnt lgkmcnt(8)
	s_waitcnt vmcnt(8)
	s_barrier
; #define PG8_STAGE(bufoff, gbase, voff) do { _Pragma("unroll") for (int _i = 0; _i < 2; ++_i) \
;         __builtin_amdgcn_global_load_lds((const unsigned*)((const char*)(gbase) + (voff)[_i]), (LAS unsigned*)(lds + (bufoff) + ldsw + _i * 8192), 16, 0, 0); } while (0)
; #define PG8_LDA(dst, b, h) do { _Pragma("unroll") for (int m = 0; m < 4; ++m) _Pragma("unroll") for (int k = 0; k < 2; ++k) dst[m][k] = *(const LAS bf16x8*)(lds + PG8_SA(b, h) + aoff + m * 2048 + k * 1024); } while (0)
; #define PG8_LDB(dst, b, h) do { _Pragma("unroll") for (int n = 0; n < 2; ++n) _Pragma("unroll") for (int k = 0; k < 2; ++k) dst[n][k] = *(const LAS bf16x8*)(lds + PG8_SB(b, h) + boff + n * 2048 + k * 1024); } while (0)
; #define PG8_MMA(ai, bj, At, Bt) do { __builtin_amdgcn_s_setprio(1); _Pragma("unroll") for (int m = 0; m < 4; ++m) _Pragma("unroll") for (int n = 0; n < 2; ++n) _Pragma("unroll") for (int k = 0; k < 2; ++k) \
;         acc[ai][bj][m][n] = __builtin_amdgcn_mfma_f32_16x16x32_bf16(Bt[n][k], At[m][k], acc[ai][bj][m][n], 0, 0, 0); __builtin_amdgcn_s_setprio(0); } while (0)
; #define PG8_WAIT_V(n) asm volatile("s_waitcnt vmcnt(" #n ")" ::: "memory")
; #define PG8_WAIT_L(n) asm volatile("s_waitcnt lgkmcnt(" #n ")" ::: "memory")
; #define PG8_BAR __builtin_amdgcn_s_barrier()
; template <class Epi, class Sched>
; __device__ __forceinline__ void gemm_phase(LAS unsigned char* lds, const Gemm g, const Sched& S, const Epi& E) {
;     ...
;             PG8_LDA(At, 0, 1); PG8_STAGE(PG8_SA(0, 0), a2, voffA);
;             PG8_BAR; PG8_WAIT_L(0); PG8_MMA(1, 0, At, B0); PG8_BAR; PG8_SCHED;
;             PG8_STAGE(PG8_SB(0, 1), b2 + hstep, voffB);
;             PG8_WAIT_V(6); PG8_BAR; PG8_MMA(1, 1, At, B1); PG8_BAR;
;             PG8_LDB(B0, 1, 0); PG8_SCHED; PG8_LDA(At, 1, 0); PG8_STAGE(PG8_SA(0, 1), a2 + hstep, voffA);
;             PG8_WAIT_L(8); PG8_BAR; PG8_WAIT_L(0); PG8_MMA(0, 0, At, B0); PG8_BAR; PG8_SCHED;
;             PG8_LDB(B1, 1, 1); PG8_STAGE(PG8_SB(1, 0), b3, voffB);
;             PG8_BAR; PG8_WAIT_L(0); PG8_MMA(0, 1, At, B1); PG8_BAR;
;             PG8_LDA(At, 1, 1); PG8_STAGE(PG8_SA(1, 0), a3, voffA);
;             PG8_BAR; PG8_WAIT_L(0); PG8_MMA(1, 0, At, B0); PG8_BAR; PG8_SCHED;
;             PG8_STAGE(PG8_SB(1, 1), b3 + hstep, voffB);
;             PG8_WAIT_V(6); PG8_BAR; PG8_MMA(1, 1, At, B1); PG8_BAR;
;         }
	s_waitcnt lgkmcnt(0)
	s_setprio 1
	s_waitcnt lgkmcnt(0)
	v_mfma_f32_16x16x32_bf16 v[124:127], v[150:153], v[166:169], v[124:127]
	v_mfma_f32_16x16x32_bf16 v[116:119], v[158:161], v[166:169], v[116:119]
	v_mfma_f32_16x16x32_bf16 v[108:111], v[150:153], v[174:177], v[108:111]
	v_mfma_f32_16x16x32_bf16 v[100:103], v[158:161], v[174:177], v[100:103]
	v_mfma_f32_16x16x32_bf16 v[92:95], v[150:153], v[182:185], v[92:95]
	v_mfma_f32_16x16x32_bf16 v[84:87], v[158:161], v[182:185], v[84:87]
	v_mfma_f32_16x16x32_bf16 v[76:79], v[150:153], v[190:193], v[76:79]
	v_mfma_f32_16x16x32_bf16 v[68:71], v[158:161], v[190:193], v[68:71]
	v_mfma_f32_16x16x32_bf16 v[124:127], v[154:157], v[170:173], v[124:127]
	v_mfma_f32_16x16x32_bf16 v[116:119], v[162:165], v[170:173], v[116:119]
	v_mfma_f32_16x16x32_bf16 v[108:111], v[154:157], v[178:181], v[108:111]
	v_mfma_f32_16x16x32_bf16 v[100:103], v[162:165], v[178:181], v[100:103]
	v_mfma_f32_16x16x32_bf16 v[92:95], v[154:157], v[186:189], v[92:95]
	v_mfma_f32_16x16x32_bf16 v[84:87], v[162:165], v[186:189], v[84:87]
	v_mfma_f32_16x16x32_bf16 v[76:79], v[154:157], v[194:197], v[76:79]
	v_mfma_f32_16x16x32_bf16 v[68:71], v[162:165], v[194:197], v[68:71]
	s_setprio 0
	s_barrier
	s_add_i32 s20, 0, 0x1c000
	s_add_i32 s21, s47, s25
	v_add_u32_e32 v214, s20, v146
	s_add_u32 s0, s18, 0x80
	s_addc_u32 s1, s19, 0
	s_mov_b32 m0, s21
	ds_read_b128 v[202:205], v214
	ds_read_b128 v[206:209], v214 offset:1024
	ds_read_b128 v[210:213], v214 offset:2048
	ds_read_b128 v[214:217], v214 offset:3072
	global_load_lds_dwordx4 v132, s[0:1]
	s_add_i32 m0, s21, 0x2000
	s_nop 0
	global_load_lds_dwordx4 v128, s[0:1]
	s_waitcnt vmcnt(8)
	s_barrier
	s_waitcnt lgkmcnt(0)
	s_setprio 1
	s_waitcnt lgkmcnt(0)
	v_mfma_f32_16x16x32_bf16 v[120:123], v[202:205], v[166:169], v[120:123]
	v_mfma_f32_16x16x32_bf16 v[112:115], v[210:213], v[166:169], v[112:115]
	v_mfma_f32_16x16x32_bf16 v[104:107], v[202:205], v[174:177], v[104:107]
	v_mfma_f32_16x16x32_bf16 v[96:99], v[210:213], v[174:177], v[96:99]
	v_mfma_f32_16x16x32_bf16 v[88:91], v[202:205], v[182:185], v[88:91]
	v_mfma_f32_16x16x32_bf16 v[80:83], v[210:213], v[182:185], v[80:83]
	v_mfma_f32_16x16x32_bf16 v[72:75], v[202:205], v[190:193], v[72:75]
	v_mfma_f32_16x16x32_bf16 v[64:67], v[210:213], v[190:193], v[64:67]
	v_mfma_f32_16x16x32_bf16 v[120:123], v[206:209], v[170:173], v[120:123]
	v_mfma_f32_16x16x32_bf16 v[112:115], v[214:217], v[170:173], v[112:115]
	v_mfma_f32_16x16x32_bf16 v[104:107], v[206:209], v[178:181], v[104:107]
	v_mfma_f32_16x16x32_bf16 v[96:99], v[214:217], v[178:181], v[96:99]
	v_mfma_f32_16x16x32_bf16 v[88:91], v[206:209], v[186:189], v[88:91]
	v_mfma_f32_16x16x32_bf16 v[80:83], v[214:217], v[186:189], v[80:83]
	v_mfma_f32_16x16x32_bf16 v[72:75], v[206:209], v[194:197], v[72:75]
	v_mfma_f32_16x16x32_bf16 v[64:67], v[214:217], v[194:197], v[64:67]
	s_setprio 0
	s_mov_b32 m0, s35
	s_mov_b64 s[0:1], 0x80
	v_lshl_add_u64 v[198:199], v[220:221], 0, s[0:1]
	s_barrier
	ds_read_b128 v[166:169], v148 offset:49152
	ds_read_b128 v[170:173], v148 offset:50176
	ds_read_b128 v[174:177], v148 offset:51200
	ds_read_b128 v[178:181], v148 offset:52224
	ds_read_b128 v[182:185], v148 offset:53248
	ds_read_b128 v[186:189], v148 offset:54272
	ds_read_b128 v[190:193], v148 offset:55296
	ds_read_b128 v[194:197], v148 offset:56320
	global_load_lds_dwordx4 v[198:199], off
	v_lshl_add_u64 v[198:199], v[222:223], 0, s[0:1]
	s_mov_b32 m0, s36
	s_nop 0
	global_load_lds_dwordx4 v[198:199], off
	s_barrier
	s_waitcnt lgkmcnt(0)
	s_setprio 1
	s_waitcnt lgkmcnt(0)
	v_mfma_f32_16x16x32_bf16 v[60:63], v[150:153], v[166:169], v[60:63]
	v_mfma_f32_16x16x32_bf16 v[56:59], v[158:161], v[166:169], v[56:59]
	v_mfma_f32_16x16x32_bf16 v[44:47], v[150:153], v[174:177], v[44:47]
	v_mfma_f32_16x16x32_bf16 v[40:43], v[158:161], v[174:177], v[40:43]
	v_mfma_f32_16x16x32_bf16 v[28:31], v[150:153], v[182:185], v[28:31]
	v_mfma_f32_16x16x32_bf16 v[24:27], v[158:161], v[182:185], v[24:27]
	v_mfma_f32_16x16x32_bf16 v[12:15], v[150:153], v[190:193], v[12:15]
	v_mfma_f32_16x16x32_bf16 v[8:11], v[158:161], v[190:193], v[8:11]
	v_mfma_f32_16x16x32_bf16 v[60:63], v[154:157], v[170:173], v[60:63]
	v_mfma_f32_16x16x32_bf16 v[56:59], v[162:165], v[170:173], v[56:59]
	v_mfma_f32_16x16x32_bf16 v[44:47], v[154:157], v[178:181], v[44:47]
	v_mfma_f32_16x16x32_bf16 v[40:43], v[162:165], v[178:181], v[40:43]
	v_mfma_f32_16x16x32_bf16 v[28:31], v[154:157], v[186:189], v[28:31]
	v_mfma_f32_16x16x32_bf16 v[24:27], v[162:165], v[186:189], v[24:27]
	v_mfma_f32_16x16x32_bf16 v[12:15], v[154:157], v[194:197], v[12:15]
	v_mfma_f32_16x16x32_bf16 v[8:11], v[162:165], v[194:197], v[8:11]
	s_setprio 0
	s_barrier
	s_add_u32 s18, s18, 0x40080
	s_addc_u32 s19, s19, 0
	s_add_i32 s20, s20, s25
	s_mov_b32 m0, s20
	s_nop 0
	global_load_lds_dwordx4 v132, s[18:19]
	s_add_i32 m0, s20, 0x2000
	s_nop 0
	global_load_lds_dwordx4 v128, s[18:19]
	s_waitcnt vmcnt(8)
	s_barrier
	s_setprio 1
	v_mfma_f32_16x16x32_bf16 v[52:55], v[202:205], v[166:169], v[52:55]
	v_mfma_f32_16x16x32_bf16 v[48:51], v[210:213], v[166:169], v[48:51]
	v_mfma_f32_16x16x32_bf16 v[36:39], v[202:205], v[174:177], v[36:39]
	v_mfma_f32_16x16x32_bf16 v[32:35], v[210:213], v[174:177], v[32:35]
	v_mfma_f32_16x16x32_bf16 v[20:23], v[202:205], v[182:185], v[20:23]
	v_mfma_f32_16x16x32_bf16 v[16:19], v[210:213], v[182:185], v[16:19]
	v_mfma_f32_16x16x32_bf16 v[4:7], v[202:205], v[190:193], v[4:7]
	v_mfma_f32_16x16x32_bf16 v[0:3], v[210:213], v[190:193], v[0:3]
	v_mfma_f32_16x16x32_bf16 v[52:55], v[206:209], v[170:173], v[52:55]
	v_mfma_f32_16x16x32_bf16 v[48:51], v[214:217], v[170:173], v[48:51]
	v_mfma_f32_16x16x32_bf16 v[36:39], v[206:209], v[178:181], v[36:39]
	v_mfma_f32_16x16x32_bf16 v[32:35], v[214:217], v[178:181], v[32:35]
	v_mfma_f32_16x16x32_bf16 v[20:23], v[206:209], v[186:189], v[20:23]
	v_mfma_f32_16x16x32_bf16 v[16:19], v[214:217], v[186:189], v[16:19]
	v_mfma_f32_16x16x32_bf16 v[4:7], v[206:209], v[194:197], v[4:7]
	v_mfma_f32_16x16x32_bf16 v[0:3], v[214:217], v[194:197], v[0:3]
	s_setprio 0
	s_add_i32 s46, s46, 2
	s_add_u32 s16, s16, 0x100
	s_addc_u32 s17, s17, 0
	s_add_u32 s44, s44, 0x100
	s_addc_u32 s45, s45, 0
	s_cmp_gt_u32 s46, 13
	s_cbranch_scc1 .Lconc_last_g11
	s_barrier
	s_branch .LBB0_1021

; #define PG8_STAGE(bufoff, gbase, voff) do { _Pragma("unroll") for (int _i = 0; _i < 2; ++_i) \
;         __builtin_amdgcn_global_load_lds((const unsigned*)((const char*)(gbase) + (voff)[_i]), (LAS unsigned*)(lds + (bufoff) + ldsw + _i * 8192), 16, 0, 0); } while (0)
; #define PG8_LDA(dst, b, h) do { _Pragma("unroll") for (int m = 0; m < 4; ++m) _Pragma("unroll") for (int k = 0; k < 2; ++k) dst[m][k] = *(const LAS bf16x8*)(lds + PG8_SA(b, h) + aoff + m * 2048 + k * 1024); } while (0)
; #define PG8_LDB(dst, b, h) do { _Pragma("unroll") for (int n = 0; n < 2; ++n) _Pragma("unroll") for (int k = 0; k < 2; ++k) dst[n][k] = *(const LAS bf16x8*)(lds + PG8_SB(b, h) + boff + n * 2048 + k * 1024); } while (0)
; #define PG8_MMA(ai, bj, At, Bt) do { __builtin_amdgcn_s_setprio(1); _Pragma("unroll") for (int m = 0; m < 4; ++m) _Pragma("unroll") for (int n = 0; n < 2; ++n) _Pragma("unroll") for (int k = 0; k < 2; ++k) \
;         acc[ai][bj][m][n] = __builtin_amdgcn_mfma_f32_16x16x32_bf16(Bt[n][k], At[m][k], acc[ai][bj][m][n], 0, 0, 0); __builtin_amdgcn_s_setprio(0); } while (0)
; #define PG8_WAIT_V(n) asm volatile("s_waitcnt vmcnt(" #n ")" ::: "memory")
; #define PG8_WAIT_L(n) asm volatile("s_waitcnt lgkmcnt(" #n ")" ::: "memory")
; template <class Epi, class Sched>
; __device__ __forceinline__ void gemm_phase(LAS unsigned char* lds, const Gemm g, const Sched& S, const Epi& E) {
;     ...
;         for (int t = 0; t < nt; t += 2) {
;             const bool last = (t == nt - 2);
;             const char* a1 = cA + (size_t)(t + 1) * kstep;
;             const char* a2 = last ? nA : cA + (size_t)(t + 2) * kstep; const char* b2 = last ? nB : cB + (size_t)(t + 2) * kstep;
;             const char* a3 = a2 + kstep; const char* b3 = b2 + kstep;
;             PG8_LDB(B0, 0, 0); PG8_SCHED; PG8_LDA(At, 0, 0); PG8_STAGE(PG8_SA(1, 1), a1 + hstep, voffA);
;             PG8_WAIT_L(8); PG8_BAR; PG8_WAIT_L(0); PG8_MMA(0, 0, At, B0); PG8_BAR; PG8_SCHED;
;             PG8_LDB(B1, 0, 1); PG8_STAGE(PG8_SB(0, 0), b2, voffB);
;             PG8_BAR; PG8_WAIT_L(0); PG8_MMA(0, 1, At, B1); PG8_BAR;
;             PG8_LDA(At, 0, 1); PG8_STAGE(PG8_SA(0, 0), a2, voffA);
;             PG8_BAR; PG8_WAIT_L(0); PG8_MMA(1, 0, At, B0); PG8_BAR; PG8_SCHED;
;             PG8_STAGE(PG8_SB(0, 1), b2 + hstep, voffB);
;             PG8_WAIT_V(6); PG8_BAR; PG8_MMA(1, 1, At, B1); PG8_BAR;
.LBB0_1096:
	s_add_u32 s54, s24, 0x100
	s_addc_u32 s55, s25, 0
	s_mov_b32 s56, -2
	ds_read_b128 v[128:131], v241
	ds_read_b128 v[132:135], v241 offset:1024
	ds_read_b128 v[136:139], v241 offset:2048
	ds_read_b128 v[140:143], v241 offset:3072
	s_add_u32 s24, s22, 0x100
	s_addc_u32 s25, s23, 0
	s_cmp_eq_u32 s56, 40
	s_cselect_b32 s29, s5, s25
	s_cselect_b32 s28, s4, s24
	s_cselect_b32 s27, s7, s55
	s_cselect_b32 s26, s6, s54
	v_lshl_add_u64 v[176:177], s[22:23], 0, v[196:197]
	s_add_i32 m0, s35, 0xc000
	ds_read_b128 v[144:147], v242
	ds_read_b128 v[148:151], v242 offset:1024
	ds_read_b128 v[152:155], v242 offset:2048
	ds_read_b128 v[156:159], v242 offset:3072
	ds_read_b128 v[160:163], v242 offset:4096
	ds_read_b128 v[164:167], v242 offset:5120
	ds_read_b128 v[168:171], v242 offset:6144
	ds_read_b128 v[172:175], v242 offset:7168
	global_load_lds_dwordx4 v[176:177], off
	v_lshl_add_u64 v[176:177], s[22:23], 0, v[198:199]
	s_add_i32 m0, s35, 0xe000
	s_nop 0
	global_load_lds_dwordx4 v[176:177], off
	s_waitcnt lgkmcnt(8)
	s_waitcnt vmcnt(8)
	s_barrier
	s_waitcnt lgkmcnt(0)
	s_setprio 1
	s_waitcnt lgkmcnt(0)
	v_mfma_f32_16x16x32_bf16 v[124:127], v[128:131], v[144:147], 0
	v_mfma_f32_16x16x32_bf16 v[120:123], v[136:139], v[144:147], 0
	v_mfma_f32_16x16x32_bf16 v[108:111], v[128:131], v[152:155], 0
	v_mfma_f32_16x16x32_bf16 v[104:107], v[136:139], v[152:155], 0
	v_mfma_f32_16x16x32_bf16 v[92:95], v[128:131], v[160:163], 0
	v_mfma_f32_16x16x32_bf16 v[88:91], v[136:139], v[160:163], 0
	v_mfma_f32_16x16x32_bf16 v[76:79], v[128:131], v[168:171], 0
	v_mfma_f32_16x16x32_bf16 v[72:75], v[136:139], v[168:171], 0
	v_mfma_f32_16x16x32_bf16 v[124:127], v[132:135], v[148:151], v[124:127]
	v_mfma_f32_16x16x32_bf16 v[120:123], v[140:143], v[148:151], v[120:123]
	v_mfma_f32_16x16x32_bf16 v[108:111], v[132:135], v[156:159], v[108:111]
	v_mfma_f32_16x16x32_bf16 v[104:107], v[140:143], v[156:159], v[104:107]
	v_mfma_f32_16x16x32_bf16 v[92:95], v[132:135], v[164:167], v[92:95]
	v_mfma_f32_16x16x32_bf16 v[88:91], v[140:143], v[164:167], v[88:91]
	v_mfma_f32_16x16x32_bf16 v[76:79], v[132:135], v[172:175], v[76:79]
	v_mfma_f32_16x16x32_bf16 v[72:75], v[140:143], v[172:175], v[72:75]
	s_setprio 0
	s_barrier
	s_add_i32 s22, s48, s34
	s_mov_b32 m0, s22
	ds_read_b128 v[176:179], v243
	ds_read_b128 v[180:183], v243 offset:1024
	ds_read_b128 v[184:187], v243 offset:2048
	ds_read_b128 v[206:209], v243 offset:3072
	global_load_lds_dwordx4 v190, s[26:27]
	s_add_i32 m0, s22, 0x2000
	s_nop 0
	global_load_lds_dwordx4 v194, s[26:27]
	s_waitcnt vmcnt(8)
	s_barrier
	s_waitcnt lgkmcnt(0)
	s_setprio 1
	s_waitcnt lgkmcnt(0)
	v_mfma_f32_16x16x32_bf16 v[116:119], v[176:179], v[144:147], 0
	v_mfma_f32_16x16x32_bf16 v[112:115], v[184:187], v[144:147], 0
	v_mfma_f32_16x16x32_bf16 v[100:103], v[176:179], v[152:155], 0
	v_mfma_f32_16x16x32_bf16 v[96:99], v[184:187], v[152:155], 0
	v_mfma_f32_16x16x32_bf16 v[84:87], v[176:179], v[160:163], 0
	v_mfma_f32_16x16x32_bf16 v[80:83], v[184:187], v[160:163], 0
	v_mfma_f32_16x16x32_bf16 v[68:71], v[176:179], v[168:171], 0
	v_mfma_f32_16x16x32_bf16 v[64:67], v[184:187], v[168:171], 0
	v_mfma_f32_16x16x32_bf16 v[116:119], v[180:183], v[148:151], v[116:119]
	v_mfma_f32_16x16x32_bf16 v[112:115], v[206:209], v[148:151], v[112:115]
	v_mfma_f32_16x16x32_bf16 v[100:103], v[180:183], v[156:159], v[100:103]
	v_mfma_f32_16x16x32_bf16 v[96:99], v[206:209], v[156:159], v[96:99]
	v_mfma_f32_16x16x32_bf16 v[84:87], v[180:183], v[164:167], v[84:87]
	v_mfma_f32_16x16x32_bf16 v[80:83], v[206:209], v[164:167], v[80:83]
	v_mfma_f32_16x16x32_bf16 v[68:71], v[180:183], v[172:175], v[68:71]
	v_mfma_f32_16x16x32_bf16 v[64:67], v[206:209], v[172:175], v[64:67]
	s_setprio 0
	s_mov_b32 m0, s35
	v_lshl_add_u64 v[214:215], s[28:29], 0, v[188:189]
	s_barrier
	ds_read_b128 v[144:147], v242 offset:16384
	ds_read_b128 v[148:151], v242 offset:17408
	ds_read_b128 v[152:155], v242 offset:18432
	ds_read_b128 v[156:159], v242 offset:19456
	ds_read_b128 v[160:163], v242 offset:20480
	ds_read_b128 v[164:167], v242 offset:21504
	ds_read_b128 v[168:171], v242 offset:22528
	ds_read_b128 v[172:175], v242 offset:23552
	global_load_lds_dwordx4 v188, s[28:29]
	v_lshl_add_u64 v[216:217], s[28:29], 0, v[192:193]
	s_mov_b32 m0, s36
	s_nop 0
	global_load_lds_dwordx4 v192, s[28:29]
	s_barrier
	s_waitcnt lgkmcnt(0)
	s_setprio 1
	s_waitcnt lgkmcnt(0)
	v_mfma_f32_16x16x32_bf16 v[60:63], v[128:131], v[144:147], 0
	v_mfma_f32_16x16x32_bf16 v[56:59], v[136:139], v[144:147], 0
	v_mfma_f32_16x16x32_bf16 v[44:47], v[128:131], v[152:155], 0
	v_mfma_f32_16x16x32_bf16 v[40:43], v[136:139], v[152:155], 0
	v_mfma_f32_16x16x32_bf16 v[28:31], v[128:131], v[160:163], 0
	v_mfma_f32_16x16x32_bf16 v[24:27], v[136:139], v[160:163], 0
	v_mfma_f32_16x16x32_bf16 v[12:15], v[128:131], v[168:171], 0
	v_mfma_f32_16x16x32_bf16 v[8:11], v[136:139], v[168:171], 0
	v_mfma_f32_16x16x32_bf16 v[60:63], v[132:135], v[148:151], v[60:63]
	v_mfma_f32_16x16x32_bf16 v[56:59], v[140:143], v[148:151], v[56:59]
	v_mfma_f32_16x16x32_bf16 v[44:47], v[132:135], v[156:159], v[44:47]
	v_mfma_f32_16x16x32_bf16 v[40:43], v[140:143], v[156:159], v[40:43]
	v_mfma_f32_16x16x32_bf16 v[28:31], v[132:135], v[164:167], v[28:31]
	v_mfma_f32_16x16x32_bf16 v[24:27], v[140:143], v[164:167], v[24:27]
	v_mfma_f32_16x16x32_bf16 v[12:15], v[132:135], v[172:175], v[12:15]
	v_mfma_f32_16x16x32_bf16 v[8:11], v[140:143], v[172:175], v[8:11]
	s_setprio 0
	s_barrier
; #define PG8_STAGE(bufoff, gbase, voff) do { _Pragma("unroll") for (int _i = 0; _i < 2; ++_i) \
;         __builtin_amdgcn_global_load_lds((const unsigned*)((const char*)(gbase) + (voff)[_i]), (LAS unsigned*)(lds + (bufoff) + ldsw + _i * 8192), 16, 0, 0); } while (0)
; #define PG8_LDA(dst, b, h) do { _Pragma("unroll") for (int m = 0; m < 4; ++m) _Pragma("unroll") for (int k = 0; k < 2; ++k) dst[m][k] = *(const LAS bf16x8*)(lds + PG8_SA(b, h) + aoff + m * 2048 + k * 1024); } while (0)
; #define PG8_LDB(dst, b, h) do { _Pragma("unroll") for (int n = 0; n < 2; ++n) _Pragma("unroll") for (int k = 0; k < 2; ++k) dst[n][k] = *(const LAS bf16x8*)(lds + PG8_SB(b, h) + boff + n * 2048 + k * 1024); } while (0)
; #define PG8_MMA(ai, bj, At, Bt) do { __builtin_amdgcn_s_setprio(1); _Pragma("unroll") for (int m = 0; m < 4; ++m) _Pragma("unroll") for (int n = 0; n < 2; ++n) _Pragma("unroll") for (int k = 0; k < 2; ++k) \
;         acc[ai][bj][m][n] = __builtin_amdgcn_mfma_f32_16x16x32_bf16(Bt[n][k], At[m][k], acc[ai][bj][m][n], 0, 0, 0); __builtin_amdgcn_s_setprio(0); } while (0)
; #define PG8_WAIT_V(n) asm volatile("s_waitcnt vmcnt(" #n ")" ::: "memory")
; #define PG8_WAIT_L(n) asm volatile("s_waitcnt lgkmcnt(" #n ")" ::: "memory")
; #define PG8_BAR __builtin_amdgcn_s_barrier()
; #define PG8_SCHED __builtin_amdgcn_sched_barrier(0)
; template <class Epi, class Sched>
; __device__ __forceinline__ void gemm_phase(LAS unsigned char* lds, const Gemm g, const Sched& S, const Epi& E) {
;     ...
;             PG8_LDB(B1, 0, 1); PG8_STAGE(PG8_SB(0, 0), b2, voffB);
;             PG8_BAR; PG8_WAIT_L(0); PG8_MMA(0, 1, At, B1); PG8_BAR;
;             PG8_LDA(At, 0, 1); PG8_STAGE(PG8_SA(0, 0), a2, voffA);
;             PG8_BAR; PG8_WAIT_L(0); PG8_MMA(1, 0, At, B0); PG8_BAR; PG8_SCHED;
;             PG8_STAGE(PG8_SB(0, 1), b2 + hstep, voffB);
;             PG8_WAIT_V(6); PG8_BAR; PG8_MMA(1, 1, At, B1); PG8_BAR;
;             PG8_LDB(B0, 1, 0); PG8_SCHED; PG8_LDA(At, 1, 0); PG8_STAGE(PG8_SA(0, 1), a2 + hstep, voffA);
;             PG8_WAIT_L(8); PG8_BAR; PG8_WAIT_L(0); PG8_MMA(0, 0, At, B0); PG8_BAR; PG8_SCHED;
;             PG8_LDB(B1, 1, 1); PG8_STAGE(PG8_SB(1, 0), b3, voffB);
;             PG8_BAR; PG8_WAIT_L(0); PG8_MMA(0, 1, At, B1); PG8_BAR;
;             PG8_LDA(At, 1, 1); PG8_STAGE(PG8_SA(1, 0), a3, voffA);
	s_add_u32 s22, s26, 0xb0000
	s_addc_u32 s23, s27, 0
	s_add_i32 s57, s49, s34
	s_mov_b32 m0, s57
	s_nop 0
	global_load_lds_dwordx4 v190, s[22:23]
	s_add_i32 m0, s57, 0x2000
	s_nop 0
	global_load_lds_dwordx4 v194, s[22:23]
	s_add_u32 s22, s28, 0xb0000
	s_addc_u32 s23, s29, 0
	s_mov_b32 m0, s37
	s_nop 0
	global_load_lds_dwordx4 v188, s[22:23]
	s_mov_b32 m0, s38
	s_nop 0
	global_load_lds_dwordx4 v192, s[22:23]
	s_waitcnt vmcnt(10)
	s_barrier
	s_setprio 1
	v_mfma_f32_16x16x32_bf16 v[52:55], v[176:179], v[144:147], 0
	v_mfma_f32_16x16x32_bf16 v[48:51], v[184:187], v[144:147], 0
	v_mfma_f32_16x16x32_bf16 v[36:39], v[176:179], v[152:155], 0
	v_mfma_f32_16x16x32_bf16 v[32:35], v[184:187], v[152:155], 0
	v_mfma_f32_16x16x32_bf16 v[20:23], v[176:179], v[160:163], 0
	v_mfma_f32_16x16x32_bf16 v[16:19], v[184:187], v[160:163], 0
	v_mfma_f32_16x16x32_bf16 v[4:7], v[176:179], v[168:171], 0
	v_mfma_f32_16x16x32_bf16 v[0:3], v[184:187], v[168:171], 0
	v_mfma_f32_16x16x32_bf16 v[52:55], v[180:183], v[148:151], v[52:55]
	v_mfma_f32_16x16x32_bf16 v[48:51], v[206:209], v[148:151], v[48:51]
	v_mfma_f32_16x16x32_bf16 v[36:39], v[180:183], v[156:159], v[36:39]
	v_mfma_f32_16x16x32_bf16 v[32:35], v[206:209], v[156:159], v[32:35]
	v_mfma_f32_16x16x32_bf16 v[20:23], v[180:183], v[164:167], v[20:23]
	v_mfma_f32_16x16x32_bf16 v[16:19], v[206:209], v[164:167], v[16:19]
	v_mfma_f32_16x16x32_bf16 v[4:7], v[180:183], v[172:175], v[4:7]
	v_mfma_f32_16x16x32_bf16 v[0:3], v[206:209], v[172:175], v[0:3]
	s_setprio 0
	s_add_i32 s57, 0, 0x18000
	v_add_u32_e32 v140, s57, v240
	s_barrier
	ds_read_b128 v[128:131], v140
	ds_read_b128 v[132:135], v140 offset:1024
	ds_read_b128 v[136:139], v140 offset:2048
	ds_read_b128 v[140:143], v140 offset:3072
	ds_read_b128 v[144:147], v242 offset:32768
	ds_read_b128 v[148:151], v242 offset:33792
	ds_read_b128 v[152:155], v242 offset:34816
	ds_read_b128 v[156:159], v242 offset:35840
	ds_read_b128 v[160:163], v242 offset:36864
	ds_read_b128 v[164:167], v242 offset:37888
	ds_read_b128 v[168:171], v242 offset:38912
	ds_read_b128 v[172:175], v242 offset:39936
	s_waitcnt lgkmcnt(8)
	s_waitcnt vmcnt(8)
	s_barrier
	s_waitcnt lgkmcnt(0)
	s_setprio 1
	s_waitcnt lgkmcnt(0)
	v_mfma_f32_16x16x32_bf16 v[124:127], v[128:131], v[144:147], v[124:127]
	v_mfma_f32_16x16x32_bf16 v[120:123], v[136:139], v[144:147], v[120:123]
	v_mfma_f32_16x16x32_bf16 v[108:111], v[128:131], v[152:155], v[108:111]
	v_mfma_f32_16x16x32_bf16 v[104:107], v[136:139], v[152:155], v[104:107]
	v_mfma_f32_16x16x32_bf16 v[92:95], v[128:131], v[160:163], v[92:95]
	v_mfma_f32_16x16x32_bf16 v[88:91], v[136:139], v[160:163], v[88:91]
	v_mfma_f32_16x16x32_bf16 v[76:79], v[128:131], v[168:171], v[76:79]
	v_mfma_f32_16x16x32_bf16 v[72:75], v[136:139], v[168:171], v[72:75]
	v_mfma_f32_16x16x32_bf16 v[124:127], v[132:135], v[148:151], v[124:127]
	v_mfma_f32_16x16x32_bf16 v[120:123], v[140:143], v[148:151], v[120:123]
	v_mfma_f32_16x16x32_bf16 v[108:111], v[132:135], v[156:159], v[108:111]
	v_mfma_f32_16x16x32_bf16 v[104:107], v[140:143], v[156:159], v[104:107]
	v_mfma_f32_16x16x32_bf16 v[92:95], v[132:135], v[164:167], v[92:95]
	v_mfma_f32_16x16x32_bf16 v[88:91], v[140:143], v[164:167], v[88:91]
	v_mfma_f32_16x16x32_bf16 v[76:79], v[132:135], v[172:175], v[76:79]
	v_mfma_f32_16x16x32_bf16 v[72:75], v[140:143], v[172:175], v[72:75]
	s_setprio 0
	s_barrier
	s_add_i32 s28, 0, 0x1c000
	s_add_i32 s22, s57, s34
	v_add_u32_e32 v206, s28, v240
	s_add_u32 s0, s26, 0x80
	s_addc_u32 s1, s27, 0
	s_mov_b32 m0, s22
	ds_read_b128 v[176:179], v206
	ds_read_b128 v[180:183], v206 offset:1024
	ds_read_b128 v[184:187], v206 offset:2048
	ds_read_b128 v[206:209], v206 offset:3072
	global_load_lds_dwordx4 v190, s[0:1]
	s_add_i32 m0, s22, 0x2000
	s_nop 0
	global_load_lds_dwordx4 v194, s[0:1]
	s_waitcnt vmcnt(8)
	s_barrier
	s_waitcnt lgkmcnt(0)
	s_setprio 1
	s_waitcnt lgkmcnt(0)
	v_mfma_f32_16x16x32_bf16 v[116:119], v[176:179], v[144:147], v[116:119]
	v_mfma_f32_16x16x32_bf16 v[112:115], v[184:187], v[144:147], v[112:115]
	v_mfma_f32_16x16x32_bf16 v[100:103], v[176:179], v[152:155], v[100:103]
	v_mfma_f32_16x16x32_bf16 v[96:99], v[184:187], v[152:155], v[96:99]
	v_mfma_f32_16x16x32_bf16 v[84:87], v[176:179], v[160:163], v[84:87]
	v_mfma_f32_16x16x32_bf16 v[80:83], v[184:187], v[160:163], v[80:83]
	v_mfma_f32_16x16x32_bf16 v[68:71], v[176:179], v[168:171], v[68:71]
	v_mfma_f32_16x16x32_bf16 v[64:67], v[184:187], v[168:171], v[64:67]
	v_mfma_f32_16x16x32_bf16 v[116:119], v[180:183], v[148:151], v[116:119]
	v_mfma_f32_16x16x32_bf16 v[112:115], v[206:209], v[148:151], v[112:115]
	v_mfma_f32_16x16x32_bf16 v[100:103], v[180:183], v[156:159], v[100:103]
	v_mfma_f32_16x16x32_bf16 v[96:99], v[206:209], v[156:159], v[96:99]
	v_mfma_f32_16x16x32_bf16 v[84:87], v[180:183], v[164:167], v[84:87]
	v_mfma_f32_16x16x32_bf16 v[80:83], v[206:209], v[164:167], v[80:83]
	v_mfma_f32_16x16x32_bf16 v[68:71], v[180:183], v[172:175], v[68:71]
	v_mfma_f32_16x16x32_bf16 v[64:67], v[206:209], v[172:175], v[64:67]
	s_setprio 0
	s_mov_b32 m0, s44
	s_mov_b64 s[0:1], 0x80
	v_lshl_add_u64 v[210:211], v[214:215], 0, s[0:1]
	s_barrier
	ds_read_b128 v[144:147], v242 offset:49152
	ds_read_b128 v[148:151], v242 offset:50176
	ds_read_b128 v[152:155], v242 offset:51200
	ds_read_b128 v[156:159], v242 offset:52224
	ds_read_b128 v[160:163], v242 offset:53248
	ds_read_b128 v[164:167], v242 offset:54272
	ds_read_b128 v[168:171], v242 offset:55296
	ds_read_b128 v[172:175], v242 offset:56320
	global_load_lds_dwordx4 v[210:211], off
	v_lshl_add_u64 v[210:211], v[216:217], 0, s[0:1]
	s_mov_b32 m0, s45
	s_nop 0
	global_load_lds_dwordx4 v[210:211], off
	s_barrier
; #define PG8_STAGE(bufoff, gbase, voff) do { _Pragma("unroll") for (int _i = 0; _i < 2; ++_i) \
;         __builtin_amdgcn_global_load_lds((const unsigned*)((const char*)(gbase) + (voff)[_i]), (LAS unsigned*)(lds + (bufoff) + ldsw + _i * 8192), 16, 0, 0); } while (0)
; #define PG8_LDA(dst, b, h) do { _Pragma("unroll") for (int m = 0; m < 4; ++m) _Pragma("unroll") for (int k = 0; k < 2; ++k) dst[m][k] = *(const LAS bf16x8*)(lds + PG8_SA(b, h) + aoff + m * 2048 + k * 1024); } while (0)
; #define PG8_LDB(dst, b, h) do { _Pragma("unroll") for (int n = 0; n < 2; ++n) _Pragma("unroll") for (int k = 0; k < 2; ++k) dst[n][k] = *(const LAS bf16x8*)(lds + PG8_SB(b, h) + boff + n * 2048 + k * 1024); } while (0)
; #define PG8_WAIT_V(n) asm volatile("s_waitcnt vmcnt(" #n ")" ::: "memory")
; #define PG8_WAIT_L(n) asm volatile("s_waitcnt lgkmcnt(" #n ")" ::: "memory")
; #define PG8_BAR __builtin_amdgcn_s_barrier()
; #define PG8_SCHED __builtin_amdgcn_sched_barrier(0)
; template <class Epi, class Sched>
; __device__ __forceinline__ void gemm_phase(LAS unsigned char* lds, const Gemm g, const Sched& S, const Epi& E) {
;     ...
;             PG8_LDB(B0, 0, 0); PG8_SCHED; PG8_LDA(At, 0, 0); PG8_STAGE(PG8_SA(1, 1), a1 + hstep, voffA);
;             PG8_WAIT_L(8); PG8_BAR; PG8_WAIT_L(0); PG8_MMA(0, 0, At, B0); PG8_BAR; PG8_SCHED;
;             PG8_LDB(B1, 0, 1); PG8_STAGE(PG8_SB(0, 0), b2, voffB);
;             PG8_BAR; PG8_WAIT_L(0); PG8_MMA(0, 1, At, B1); PG8_BAR;
;             PG8_LDA(At, 0, 1); PG8_STAGE(PG8_SA(0, 0), a2, voffA);
;             PG8_BAR; PG8_WAIT_L(0); PG8_MMA(1, 0, At, B0); PG8_BAR; PG8_SCHED;
;             PG8_STAGE(PG8_SB(0, 1), b2 + hstep, voffB);
;             PG8_WAIT_V(6); PG8_BAR; PG8_MMA(1, 1, At, B1); PG8_BAR;
;             PG8_LDB(B0, 1, 0); PG8_SCHED; PG8_LDA(At, 1, 0); PG8_STAGE(PG8_SA(0, 1), a2 + hstep, voffA);
;             PG8_WAIT_L(8); PG8_BAR; PG8_WAIT_L(0); PG8_MMA(0, 0, At, B0); PG8_BAR; PG8_SCHED;
;             PG8_LDB(B1, 1, 1); PG8_STAGE(PG8_SB(1, 0), b3, voffB);
;             PG8_BAR; PG8_WAIT_L(0); PG8_MMA(0, 1, At, B1); PG8_BAR;
;             PG8_LDA(At, 1, 1); PG8_STAGE(PG8_SA(1, 0), a3, voffA);
;             PG8_BAR; PG8_WAIT_L(0); PG8_MMA(1, 0, At, B0); PG8_BAR; PG8_SCHED;
;             PG8_STAGE(PG8_SB(1, 1), b3 + hstep, voffB);
;             PG8_WAIT_V(6); PG8_BAR; PG8_MMA(1, 1, At, B1); PG8_BAR;
	s_waitcnt lgkmcnt(0)
	s_setprio 1
	s_waitcnt lgkmcnt(0)
	v_mfma_f32_16x16x32_bf16 v[60:63], v[128:131], v[144:147], v[60:63]
	v_mfma_f32_16x16x32_bf16 v[56:59], v[136:139], v[144:147], v[56:59]
	v_mfma_f32_16x16x32_bf16 v[44:47], v[128:131], v[152:155], v[44:47]
	v_mfma_f32_16x16x32_bf16 v[40:43], v[136:139], v[152:155], v[40:43]
	v_mfma_f32_16x16x32_bf16 v[28:31], v[128:131], v[160:163], v[28:31]
	v_mfma_f32_16x16x32_bf16 v[24:27], v[136:139], v[160:163], v[24:27]
	v_mfma_f32_16x16x32_bf16 v[12:15], v[128:131], v[168:171], v[12:15]
	v_mfma_f32_16x16x32_bf16 v[8:11], v[136:139], v[168:171], v[8:11]
	v_mfma_f32_16x16x32_bf16 v[60:63], v[132:135], v[148:151], v[60:63]
	v_mfma_f32_16x16x32_bf16 v[56:59], v[140:143], v[148:151], v[56:59]
	v_mfma_f32_16x16x32_bf16 v[44:47], v[132:135], v[156:159], v[44:47]
	v_mfma_f32_16x16x32_bf16 v[40:43], v[140:143], v[156:159], v[40:43]
	v_mfma_f32_16x16x32_bf16 v[28:31], v[132:135], v[164:167], v[28:31]
	v_mfma_f32_16x16x32_bf16 v[24:27], v[140:143], v[164:167], v[24:27]
	v_mfma_f32_16x16x32_bf16 v[12:15], v[132:135], v[172:175], v[12:15]
	v_mfma_f32_16x16x32_bf16 v[8:11], v[140:143], v[172:175], v[8:11]
	s_setprio 0
	s_barrier
	s_add_u32 s22, s26, 0xb0080
	s_addc_u32 s23, s27, 0
	s_add_i32 s26, s28, s34
	s_mov_b32 m0, s26
	s_nop 0
	global_load_lds_dwordx4 v190, s[22:23]
	s_add_i32 m0, s26, 0x2000
	s_nop 0
	global_load_lds_dwordx4 v194, s[22:23]
	s_waitcnt vmcnt(8)
	s_barrier
	s_setprio 1
	v_mfma_f32_16x16x32_bf16 v[52:55], v[176:179], v[144:147], v[52:55]
	v_mfma_f32_16x16x32_bf16 v[48:51], v[184:187], v[144:147], v[48:51]
	v_mfma_f32_16x16x32_bf16 v[36:39], v[176:179], v[152:155], v[36:39]
	v_mfma_f32_16x16x32_bf16 v[32:35], v[184:187], v[152:155], v[32:35]
	v_mfma_f32_16x16x32_bf16 v[20:23], v[176:179], v[160:163], v[20:23]
	v_mfma_f32_16x16x32_bf16 v[16:19], v[184:187], v[160:163], v[16:19]
	v_mfma_f32_16x16x32_bf16 v[4:7], v[176:179], v[168:171], v[4:7]
	v_mfma_f32_16x16x32_bf16 v[0:3], v[184:187], v[168:171], v[0:3]
	v_mfma_f32_16x16x32_bf16 v[52:55], v[180:183], v[148:151], v[52:55]
	v_mfma_f32_16x16x32_bf16 v[48:51], v[206:209], v[148:151], v[48:51]
	v_mfma_f32_16x16x32_bf16 v[36:39], v[180:183], v[156:159], v[36:39]
	v_mfma_f32_16x16x32_bf16 v[32:35], v[206:209], v[156:159], v[32:35]
	v_mfma_f32_16x16x32_bf16 v[20:23], v[180:183], v[164:167], v[20:23]
	v_mfma_f32_16x16x32_bf16 v[16:19], v[206:209], v[164:167], v[16:19]
	v_mfma_f32_16x16x32_bf16 v[4:7], v[180:183], v[172:175], v[4:7]
	v_mfma_f32_16x16x32_bf16 v[0:3], v[206:209], v[172:175], v[0:3]
	s_setprio 0
	s_add_i32 s56, s56, 2
	s_add_u32 s54, s54, 0x100
	s_addc_u32 s55, s55, 0
	s_cmp_gt_u32 s56, 41
	s_mov_b64 s[22:23], s[24:25]
	s_barrier
.LBB0_1097:
	ds_read_b128 v[128:131], v241
	ds_read_b128 v[132:135], v241 offset:1024
	ds_read_b128 v[136:139], v241 offset:2048
	ds_read_b128 v[140:143], v241 offset:3072
	s_add_u32 s24, s22, 0x100
	s_addc_u32 s25, s23, 0
	s_cmp_eq_u32 s56, 40
	s_cselect_b32 s29, s5, s25
	s_cselect_b32 s28, s4, s24
	s_cselect_b32 s27, s7, s55
	s_cselect_b32 s26, s6, s54
	v_lshl_add_u64 v[176:177], s[22:23], 0, v[196:197]
	s_add_i32 m0, s35, 0xc000
	ds_read_b128 v[144:147], v242
	ds_read_b128 v[148:151], v242 offset:1024
	ds_read_b128 v[152:155], v242 offset:2048
	ds_read_b128 v[156:159], v242 offset:3072
	ds_read_b128 v[160:163], v242 offset:4096
	ds_read_b128 v[164:167], v242 offset:5120
	ds_read_b128 v[168:171], v242 offset:6144
	ds_read_b128 v[172:175], v242 offset:7168
	global_load_lds_dwordx4 v[176:177], off
	v_lshl_add_u64 v[176:177], s[22:23], 0, v[198:199]
	s_add_i32 m0, s35, 0xe000
	s_nop 0
	global_load_lds_dwordx4 v[176:177], off
	s_waitcnt lgkmcnt(8)
	s_waitcnt vmcnt(8)
	s_barrier
	s_waitcnt lgkmcnt(0)
	s_setprio 1
	s_waitcnt lgkmcnt(0)
	v_mfma_f32_16x16x32_bf16 v[124:127], v[128:131], v[144:147], v[124:127]
	v_mfma_f32_16x16x32_bf16 v[120:123], v[136:139], v[144:147], v[120:123]
	v_mfma_f32_16x16x32_bf16 v[108:111], v[128:131], v[152:155], v[108:111]
	v_mfma_f32_16x16x32_bf16 v[104:107], v[136:139], v[152:155], v[104:107]
	v_mfma_f32_16x16x32_bf16 v[92:95], v[128:131], v[160:163], v[92:95]
	v_mfma_f32_16x16x32_bf16 v[88:91], v[136:139], v[160:163], v[88:91]
	v_mfma_f32_16x16x32_bf16 v[76:79], v[128:131], v[168:171], v[76:79]
	v_mfma_f32_16x16x32_bf16 v[72:75], v[136:139], v[168:171], v[72:75]
	v_mfma_f32_16x16x32_bf16 v[124:127], v[132:135], v[148:151], v[124:127]
	v_mfma_f32_16x16x32_bf16 v[120:123], v[140:143], v[148:151], v[120:123]
	v_mfma_f32_16x16x32_bf16 v[108:111], v[132:135], v[156:159], v[108:111]
	v_mfma_f32_16x16x32_bf16 v[104:107], v[140:143], v[156:159], v[104:107]
	v_mfma_f32_16x16x32_bf16 v[92:95], v[132:135], v[164:167], v[92:95]
	v_mfma_f32_16x16x32_bf16 v[88:91], v[140:143], v[164:167], v[88:91]
	v_mfma_f32_16x16x32_bf16 v[76:79], v[132:135], v[172:175], v[76:79]
	v_mfma_f32_16x16x32_bf16 v[72:75], v[140:143], v[172:175], v[72:75]
	s_setprio 0
	s_barrier
	s_add_i32 s22, s48, s34
	s_mov_b32 m0, s22
	ds_read_b128 v[176:179], v243
	ds_read_b128 v[180:183], v243 offset:1024
	ds_read_b128 v[184:187], v243 offset:2048
	ds_read_b128 v[206:209], v243 offset:3072
	global_load_lds_dwordx4 v190, s[26:27]
	s_add_i32 m0, s22, 0x2000
	s_nop 0
	global_load_lds_dwordx4 v194, s[26:27]
	s_waitcnt vmcnt(8)
	s_barrier
; #define PG8_STAGE(bufoff, gbase, voff) do { _Pragma("unroll") for (int _i = 0; _i < 2; ++_i) \
;         __builtin_amdgcn_global_load_lds((const unsigned*)((const char*)(gbase) + (voff)[_i]), (LAS unsigned*)(lds + (bufoff) + ldsw + _i * 8192), 16, 0, 0); } while (0)
; #define PG8_LDA(dst, b, h) do { _Pragma("unroll") for (int m = 0; m < 4; ++m) _Pragma("unroll") for (int k = 0; k < 2; ++k) dst[m][k] = *(const LAS bf16x8*)(lds + PG8_SA(b, h) + aoff + m * 2048 + k * 1024); } while (0)
; #define PG8_LDB(dst, b, h) do { _Pragma("unroll") for (int n = 0; n < 2; ++n) _Pragma("unroll") for (int k = 0; k < 2; ++k) dst[n][k] = *(const LAS bf16x8*)(lds + PG8_SB(b, h) + boff + n * 2048 + k * 1024); } while (0)
; #define PG8_MMA(ai, bj, At, Bt) do { __builtin_amdgcn_s_setprio(1); _Pragma("unroll") for (int m = 0; m < 4; ++m) _Pragma("unroll") for (int n = 0; n < 2; ++n) _Pragma("unroll") for (int k = 0; k < 2; ++k) \
;         acc[ai][bj][m][n] = __builtin_amdgcn_mfma_f32_16x16x32_bf16(Bt[n][k], At[m][k], acc[ai][bj][m][n], 0, 0, 0); __builtin_amdgcn_s_setprio(0); } while (0)
; #define PG8_WAIT_V(n) asm volatile("s_waitcnt vmcnt(" #n ")" ::: "memory")
; #define PG8_WAIT_L(n) asm volatile("s_waitcnt lgkmcnt(" #n ")" ::: "memory")
; #define PG8_BAR __builtin_amdgcn_s_barrier()
; #define PG8_SCHED __builtin_amdgcn_sched_barrier(0)
; template <class Epi, class Sched>
; __device__ __forceinline__ void gemm_phase(LAS unsigned char* lds, const Gemm g, const Sched& S, const Epi& E) {
;     ...
;             PG8_LDB(B1, 0, 1); PG8_STAGE(PG8_SB(0, 0), b2, voffB);
;             PG8_BAR; PG8_WAIT_L(0); PG8_MMA(0, 1, At, B1); PG8_BAR;
;             PG8_LDA(At, 0, 1); PG8_STAGE(PG8_SA(0, 0), a2, voffA);
;             PG8_BAR; PG8_WAIT_L(0); PG8_MMA(1, 0, At, B0); PG8_BAR; PG8_SCHED;
;             PG8_STAGE(PG8_SB(0, 1), b2 + hstep, voffB);
;             PG8_WAIT_V(6); PG8_BAR; PG8_MMA(1, 1, At, B1); PG8_BAR;
;             PG8_LDB(B0, 1, 0); PG8_SCHED; PG8_LDA(At, 1, 0); PG8_STAGE(PG8_SA(0, 1), a2 + hstep, voffA);
;             PG8_WAIT_L(8); PG8_BAR; PG8_WAIT_L(0); PG8_MMA(0, 0, At, B0); PG8_BAR; PG8_SCHED;
;             PG8_LDB(B1, 1, 1); PG8_STAGE(PG8_SB(1, 0), b3, voffB);
;             PG8_BAR; PG8_WAIT_L(0); PG8_MMA(0, 1, At, B1); PG8_BAR;
;             PG8_LDA(At, 1, 1); PG8_STAGE(PG8_SA(1, 0), a3, voffA);
	s_waitcnt lgkmcnt(0)
	s_setprio 1
	s_waitcnt lgkmcnt(0)
	v_mfma_f32_16x16x32_bf16 v[116:119], v[176:179], v[144:147], v[116:119]
	v_mfma_f32_16x16x32_bf16 v[112:115], v[184:187], v[144:147], v[112:115]
	v_mfma_f32_16x16x32_bf16 v[100:103], v[176:179], v[152:155], v[100:103]
	v_mfma_f32_16x16x32_bf16 v[96:99], v[184:187], v[152:155], v[96:99]
	v_mfma_f32_16x16x32_bf16 v[84:87], v[176:179], v[160:163], v[84:87]
	v_mfma_f32_16x16x32_bf16 v[80:83], v[184:187], v[160:163], v[80:83]
	v_mfma_f32_16x16x32_bf16 v[68:71], v[176:179], v[168:171], v[68:71]
	v_mfma_f32_16x16x32_bf16 v[64:67], v[184:187], v[168:171], v[64:67]
	v_mfma_f32_16x16x32_bf16 v[116:119], v[180:183], v[148:151], v[116:119]
	v_mfma_f32_16x16x32_bf16 v[112:115], v[206:209], v[148:151], v[112:115]
	v_mfma_f32_16x16x32_bf16 v[100:103], v[180:183], v[156:159], v[100:103]
	v_mfma_f32_16x16x32_bf16 v[96:99], v[206:209], v[156:159], v[96:99]
	v_mfma_f32_16x16x32_bf16 v[84:87], v[180:183], v[164:167], v[84:87]
	v_mfma_f32_16x16x32_bf16 v[80:83], v[206:209], v[164:167], v[80:83]
	v_mfma_f32_16x16x32_bf16 v[68:71], v[180:183], v[172:175], v[68:71]
	v_mfma_f32_16x16x32_bf16 v[64:67], v[206:209], v[172:175], v[64:67]
	s_setprio 0
	s_mov_b32 m0, s35
	v_lshl_add_u64 v[214:215], s[28:29], 0, v[188:189]
	s_barrier
	ds_read_b128 v[144:147], v242 offset:16384
	ds_read_b128 v[148:151], v242 offset:17408
	ds_read_b128 v[152:155], v242 offset:18432
	ds_read_b128 v[156:159], v242 offset:19456
	ds_read_b128 v[160:163], v242 offset:20480
	ds_read_b128 v[164:167], v242 offset:21504
	ds_read_b128 v[168:171], v242 offset:22528
	ds_read_b128 v[172:175], v242 offset:23552
	global_load_lds_dwordx4 v188, s[28:29]
	v_lshl_add_u64 v[216:217], s[28:29], 0, v[192:193]
	s_mov_b32 m0, s36
	s_nop 0
	global_load_lds_dwordx4 v192, s[28:29]
	s_barrier
	s_waitcnt lgkmcnt(0)
	s_setprio 1
	s_waitcnt lgkmcnt(0)
	v_mfma_f32_16x16x32_bf16 v[60:63], v[128:131], v[144:147], v[60:63]
	v_mfma_f32_16x16x32_bf16 v[56:59], v[136:139], v[144:147], v[56:59]
	v_mfma_f32_16x16x32_bf16 v[44:47], v[128:131], v[152:155], v[44:47]
	v_mfma_f32_16x16x32_bf16 v[40:43], v[136:139], v[152:155], v[40:43]
	v_mfma_f32_16x16x32_bf16 v[28:31], v[128:131], v[160:163], v[28:31]
	v_mfma_f32_16x16x32_bf16 v[24:27], v[136:139], v[160:163], v[24:27]
	v_mfma_f32_16x16x32_bf16 v[12:15], v[128:131], v[168:171], v[12:15]
	v_mfma_f32_16x16x32_bf16 v[8:11], v[136:139], v[168:171], v[8:11]
	v_mfma_f32_16x16x32_bf16 v[60:63], v[132:135], v[148:151], v[60:63]
	v_mfma_f32_16x16x32_bf16 v[56:59], v[140:143], v[148:151], v[56:59]
	v_mfma_f32_16x16x32_bf16 v[44:47], v[132:135], v[156:159], v[44:47]
	v_mfma_f32_16x16x32_bf16 v[40:43], v[140:143], v[156:159], v[40:43]
	v_mfma_f32_16x16x32_bf16 v[28:31], v[132:135], v[164:167], v[28:31]
	v_mfma_f32_16x16x32_bf16 v[24:27], v[140:143], v[164:167], v[24:27]
	v_mfma_f32_16x16x32_bf16 v[12:15], v[132:135], v[172:175], v[12:15]
	v_mfma_f32_16x16x32_bf16 v[8:11], v[140:143], v[172:175], v[8:11]
	s_setprio 0
	s_barrier
	s_add_u32 s22, s26, 0xb0000
	s_addc_u32 s23, s27, 0
	s_add_i32 s57, s49, s34
	s_mov_b32 m0, s57
	s_nop 0
	global_load_lds_dwordx4 v190, s[22:23]
	s_add_i32 m0, s57, 0x2000
	s_nop 0
	global_load_lds_dwordx4 v194, s[22:23]
	s_add_u32 s22, s28, 0xb0000
	s_addc_u32 s23, s29, 0
	s_mov_b32 m0, s37
	s_nop 0
	global_load_lds_dwordx4 v188, s[22:23]
	s_mov_b32 m0, s38
	s_nop 0
	global_load_lds_dwordx4 v192, s[22:23]
	s_waitcnt vmcnt(10)
	s_barrier
	s_setprio 1
	v_mfma_f32_16x16x32_bf16 v[52:55], v[176:179], v[144:147], v[52:55]
	v_mfma_f32_16x16x32_bf16 v[48:51], v[184:187], v[144:147], v[48:51]
	v_mfma_f32_16x16x32_bf16 v[36:39], v[176:179], v[152:155], v[36:39]
	v_mfma_f32_16x16x32_bf16 v[32:35], v[184:187], v[152:155], v[32:35]
	v_mfma_f32_16x16x32_bf16 v[20:23], v[176:179], v[160:163], v[20:23]
	v_mfma_f32_16x16x32_bf16 v[16:19], v[184:187], v[160:163], v[16:19]
	v_mfma_f32_16x16x32_bf16 v[4:7], v[176:179], v[168:171], v[4:7]
	v_mfma_f32_16x16x32_bf16 v[0:3], v[184:187], v[168:171], v[0:3]
	v_mfma_f32_16x16x32_bf16 v[52:55], v[180:183], v[148:151], v[52:55]
	v_mfma_f32_16x16x32_bf16 v[48:51], v[206:209], v[148:151], v[48:51]
	v_mfma_f32_16x16x32_bf16 v[36:39], v[180:183], v[156:159], v[36:39]
	v_mfma_f32_16x16x32_bf16 v[32:35], v[206:209], v[156:159], v[32:35]
	v_mfma_f32_16x16x32_bf16 v[20:23], v[180:183], v[164:167], v[20:23]
	v_mfma_f32_16x16x32_bf16 v[16:19], v[206:209], v[164:167], v[16:19]
	v_mfma_f32_16x16x32_bf16 v[4:7], v[180:183], v[172:175], v[4:7]
	v_mfma_f32_16x16x32_bf16 v[0:3], v[206:209], v[172:175], v[0:3]
	s_setprio 0
	s_add_i32 s57, 0, 0x18000
	v_add_u32_e32 v140, s57, v240
	s_barrier
	ds_read_b128 v[128:131], v140
	ds_read_b128 v[132:135], v140 offset:1024
	ds_read_b128 v[136:139], v140 offset:2048
	ds_read_b128 v[140:143], v140 offset:3072
	ds_read_b128 v[144:147], v242 offset:32768
	ds_read_b128 v[148:151], v242 offset:33792
	ds_read_b128 v[152:155], v242 offset:34816
	ds_read_b128 v[156:159], v242 offset:35840
	ds_read_b128 v[160:163], v242 offset:36864
	ds_read_b128 v[164:167], v242 offset:37888
	ds_read_b128 v[168:171], v242 offset:38912
	ds_read_b128 v[172:175], v242 offset:39936
	s_waitcnt lgkmcnt(8)
	s_waitcnt vmcnt(8)
	s_barrier
; #define PG8_STAGE(bufoff, gbase, voff) do { _Pragma("unroll") for (int _i = 0; _i < 2; ++_i) \
;         __builtin_amdgcn_global_load_lds((const unsigned*)((const char*)(gbase) + (voff)[_i]), (LAS unsigned*)(lds + (bufoff) + ldsw + _i * 8192), 16, 0, 0); } while (0)
; #define PG8_LDA(dst, b, h) do { _Pragma("unroll") for (int m = 0; m < 4; ++m) _Pragma("unroll") for (int k = 0; k < 2; ++k) dst[m][k] = *(const LAS bf16x8*)(lds + PG8_SA(b, h) + aoff + m * 2048 + k * 1024); } while (0)
; #define PG8_LDB(dst, b, h) do { _Pragma("unroll") for (int n = 0; n < 2; ++n) _Pragma("unroll") for (int k = 0; k < 2; ++k) dst[n][k] = *(const LAS bf16x8*)(lds + PG8_SB(b, h) + boff + n * 2048 + k * 1024); } while (0)
; #define PG8_MMA(ai, bj, At, Bt) do { __builtin_amdgcn_s_setprio(1); _Pragma("unroll") for (int m = 0; m < 4; ++m) _Pragma("unroll") for (int n = 0; n < 2; ++n) _Pragma("unroll") for (int k = 0; k < 2; ++k) \
;         acc[ai][bj][m][n] = __builtin_amdgcn_mfma_f32_16x16x32_bf16(Bt[n][k], At[m][k], acc[ai][bj][m][n], 0, 0, 0); __builtin_amdgcn_s_setprio(0); } while (0)
; #define PG8_WAIT_V(n) asm volatile("s_waitcnt vmcnt(" #n ")" ::: "memory")
; #define PG8_WAIT_L(n) asm volatile("s_waitcnt lgkmcnt(" #n ")" ::: "memory")
; #define PG8_BAR __builtin_amdgcn_s_barrier()
; template <class Epi, class Sched>
; __device__ __forceinline__ void gemm_phase(LAS unsigned char* lds, const Gemm g, const Sched& S, const Epi& E) {
;     ...
;             PG8_LDA(At, 0, 1); PG8_STAGE(PG8_SA(0, 0), a2, voffA);
;             PG8_BAR; PG8_WAIT_L(0); PG8_MMA(1, 0, At, B0); PG8_BAR; PG8_SCHED;
;             PG8_STAGE(PG8_SB(0, 1), b2 + hstep, voffB);
;             PG8_WAIT_V(6); PG8_BAR; PG8_MMA(1, 1, At, B1); PG8_BAR;
;             PG8_LDB(B0, 1, 0); PG8_SCHED; PG8_LDA(At, 1, 0); PG8_STAGE(PG8_SA(0, 1), a2 + hstep, voffA);
;             PG8_WAIT_L(8); PG8_BAR; PG8_WAIT_L(0); PG8_MMA(0, 0, At, B0); PG8_BAR; PG8_SCHED;
;             PG8_LDB(B1, 1, 1); PG8_STAGE(PG8_SB(1, 0), b3, voffB);
;             PG8_BAR; PG8_WAIT_L(0); PG8_MMA(0, 1, At, B1); PG8_BAR;
;             PG8_LDA(At, 1, 1); PG8_STAGE(PG8_SA(1, 0), a3, voffA);
;             PG8_BAR; PG8_WAIT_L(0); PG8_MMA(1, 0, At, B0); PG8_BAR; PG8_SCHED;
;             PG8_STAGE(PG8_SB(1, 1), b3 + hstep, voffB);
;             PG8_WAIT_V(6); PG8_BAR; PG8_MMA(1, 1, At, B1); PG8_BAR;
;         }
	s_waitcnt lgkmcnt(0)
	s_setprio 1
	s_waitcnt lgkmcnt(0)
	v_mfma_f32_16x16x32_bf16 v[124:127], v[128:131], v[144:147], v[124:127]
	v_mfma_f32_16x16x32_bf16 v[120:123], v[136:139], v[144:147], v[120:123]
	v_mfma_f32_16x16x32_bf16 v[108:111], v[128:131], v[152:155], v[108:111]
	v_mfma_f32_16x16x32_bf16 v[104:107], v[136:139], v[152:155], v[104:107]
	v_mfma_f32_16x16x32_bf16 v[92:95], v[128:131], v[160:163], v[92:95]
	v_mfma_f32_16x16x32_bf16 v[88:91], v[136:139], v[160:163], v[88:91]
	v_mfma_f32_16x16x32_bf16 v[76:79], v[128:131], v[168:171], v[76:79]
	v_mfma_f32_16x16x32_bf16 v[72:75], v[136:139], v[168:171], v[72:75]
	v_mfma_f32_16x16x32_bf16 v[124:127], v[132:135], v[148:151], v[124:127]
	v_mfma_f32_16x16x32_bf16 v[120:123], v[140:143], v[148:151], v[120:123]
	v_mfma_f32_16x16x32_bf16 v[108:111], v[132:135], v[156:159], v[108:111]
	v_mfma_f32_16x16x32_bf16 v[104:107], v[140:143], v[156:159], v[104:107]
	v_mfma_f32_16x16x32_bf16 v[92:95], v[132:135], v[164:167], v[92:95]
	v_mfma_f32_16x16x32_bf16 v[88:91], v[140:143], v[164:167], v[88:91]
	v_mfma_f32_16x16x32_bf16 v[76:79], v[132:135], v[172:175], v[76:79]
	v_mfma_f32_16x16x32_bf16 v[72:75], v[140:143], v[172:175], v[72:75]
	s_setprio 0
	s_barrier
	s_add_i32 s28, 0, 0x1c000
	s_add_i32 s22, s57, s34
	v_add_u32_e32 v206, s28, v240
	s_add_u32 s0, s26, 0x80
	s_addc_u32 s1, s27, 0
	s_mov_b32 m0, s22
	ds_read_b128 v[176:179], v206
	ds_read_b128 v[180:183], v206 offset:1024
	ds_read_b128 v[184:187], v206 offset:2048
	ds_read_b128 v[206:209], v206 offset:3072
	global_load_lds_dwordx4 v190, s[0:1]
	s_add_i32 m0, s22, 0x2000
	s_nop 0
	global_load_lds_dwordx4 v194, s[0:1]
	s_waitcnt vmcnt(8)
	s_barrier
	s_waitcnt lgkmcnt(0)
	s_setprio 1
	s_waitcnt lgkmcnt(0)
	v_mfma_f32_16x16x32_bf16 v[116:119], v[176:179], v[144:147], v[116:119]
	v_mfma_f32_16x16x32_bf16 v[112:115], v[184:187], v[144:147], v[112:115]
	v_mfma_f32_16x16x32_bf16 v[100:103], v[176:179], v[152:155], v[100:103]
	v_mfma_f32_16x16x32_bf16 v[96:99], v[184:187], v[152:155], v[96:99]
	v_mfma_f32_16x16x32_bf16 v[84:87], v[176:179], v[160:163], v[84:87]
	v_mfma_f32_16x16x32_bf16 v[80:83], v[184:187], v[160:163], v[80:83]
	v_mfma_f32_16x16x32_bf16 v[68:71], v[176:179], v[168:171], v[68:71]
	v_mfma_f32_16x16x32_bf16 v[64:67], v[184:187], v[168:171], v[64:67]
	v_mfma_f32_16x16x32_bf16 v[116:119], v[180:183], v[148:151], v[116:119]
	v_mfma_f32_16x16x32_bf16 v[112:115], v[206:209], v[148:151], v[112:115]
	v_mfma_f32_16x16x32_bf16 v[100:103], v[180:183], v[156:159], v[100:103]
	v_mfma_f32_16x16x32_bf16 v[96:99], v[206:209], v[156:159], v[96:99]
	v_mfma_f32_16x16x32_bf16 v[84:87], v[180:183], v[164:167], v[84:87]
	v_mfma_f32_16x16x32_bf16 v[80:83], v[206:209], v[164:167], v[80:83]
	v_mfma_f32_16x16x32_bf16 v[68:71], v[180:183], v[172:175], v[68:71]
	v_mfma_f32_16x16x32_bf16 v[64:67], v[206:209], v[172:175], v[64:67]
	s_setprio 0
	s_mov_b32 m0, s44
	s_mov_b64 s[0:1], 0x80
	v_lshl_add_u64 v[210:211], v[214:215], 0, s[0:1]
	s_barrier
	ds_read_b128 v[144:147], v242 offset:49152
	ds_read_b128 v[148:151], v242 offset:50176
	ds_read_b128 v[152:155], v242 offset:51200
	ds_read_b128 v[156:159], v242 offset:52224
	ds_read_b128 v[160:163], v242 offset:53248
	ds_read_b128 v[164:167], v242 offset:54272
	ds_read_b128 v[168:171], v242 offset:55296
	ds_read_b128 v[172:175], v242 offset:56320
	global_load_lds_dwordx4 v[210:211], off
	v_lshl_add_u64 v[210:211], v[216:217], 0, s[0:1]
	s_mov_b32 m0, s45
	s_nop 0
	global_load_lds_dwordx4 v[210:211], off
	s_barrier
	s_waitcnt lgkmcnt(0)
	s_setprio 1
	s_waitcnt lgkmcnt(0)
	v_mfma_f32_16x16x32_bf16 v[60:63], v[128:131], v[144:147], v[60:63]
	v_mfma_f32_16x16x32_bf16 v[56:59], v[136:139], v[144:147], v[56:59]
	v_mfma_f32_16x16x32_bf16 v[44:47], v[128:131], v[152:155], v[44:47]
	v_mfma_f32_16x16x32_bf16 v[40:43], v[136:139], v[152:155], v[40:43]
	v_mfma_f32_16x16x32_bf16 v[28:31], v[128:131], v[160:163], v[28:31]
	v_mfma_f32_16x16x32_bf16 v[24:27], v[136:139], v[160:163], v[24:27]
	v_mfma_f32_16x16x32_bf16 v[12:15], v[128:131], v[168:171], v[12:15]
	v_mfma_f32_16x16x32_bf16 v[8:11], v[136:139], v[168:171], v[8:11]
	v_mfma_f32_16x16x32_bf16 v[60:63], v[132:135], v[148:151], v[60:63]
	v_mfma_f32_16x16x32_bf16 v[56:59], v[140:143], v[148:151], v[56:59]
	v_mfma_f32_16x16x32_bf16 v[44:47], v[132:135], v[156:159], v[44:47]
	v_mfma_f32_16x16x32_bf16 v[40:43], v[140:143], v[156:159], v[40:43]
	v_mfma_f32_16x16x32_bf16 v[28:31], v[132:135], v[164:167], v[28:31]
	v_mfma_f32_16x16x32_bf16 v[24:27], v[140:143], v[164:167], v[24:27]
	v_mfma_f32_16x16x32_bf16 v[12:15], v[132:135], v[172:175], v[12:15]
	v_mfma_f32_16x16x32_bf16 v[8:11], v[140:143], v[172:175], v[8:11]
	s_setprio 0
	s_barrier
	s_add_u32 s22, s26, 0xb0080
	s_addc_u32 s23, s27, 0
	s_add_i32 s26, s28, s34
	s_mov_b32 m0, s26
	s_nop 0
	global_load_lds_dwordx4 v190, s[22:23]
	s_add_i32 m0, s26, 0x2000
	s_nop 0
	global_load_lds_dwordx4 v194, s[22:23]
	s_waitcnt vmcnt(8)
	s_barrier
	s_setprio 1
	v_mfma_f32_16x16x32_bf16 v[52:55], v[176:179], v[144:147], v[52:55]
	v_mfma_f32_16x16x32_bf16 v[48:51], v[184:187], v[144:147], v[48:51]
	v_mfma_f32_16x16x32_bf16 v[36:39], v[176:179], v[152:155], v[36:39]
	v_mfma_f32_16x16x32_bf16 v[32:35], v[184:187], v[152:155], v[32:35]
	v_mfma_f32_16x16x32_bf16 v[20:23], v[176:179], v[160:163], v[20:23]
	v_mfma_f32_16x16x32_bf16 v[16:19], v[184:187], v[160:163], v[16:19]
	v_mfma_f32_16x16x32_bf16 v[4:7], v[176:179], v[168:171], v[4:7]
	v_mfma_f32_16x16x32_bf16 v[0:3], v[184:187], v[168:171], v[0:3]
	v_mfma_f32_16x16x32_bf16 v[52:55], v[180:183], v[148:151], v[52:55]
	v_mfma_f32_16x16x32_bf16 v[48:51], v[206:209], v[148:151], v[48:51]
	v_mfma_f32_16x16x32_bf16 v[36:39], v[180:183], v[156:159], v[36:39]
	v_mfma_f32_16x16x32_bf16 v[32:35], v[206:209], v[156:159], v[32:35]
	v_mfma_f32_16x16x32_bf16 v[20:23], v[180:183], v[164:167], v[20:23]
	v_mfma_f32_16x16x32_bf16 v[16:19], v[206:209], v[164:167], v[16:19]
	v_mfma_f32_16x16x32_bf16 v[4:7], v[180:183], v[172:175], v[4:7]
	v_mfma_f32_16x16x32_bf16 v[0:3], v[206:209], v[172:175], v[0:3]
	s_setprio 0
	s_add_i32 s56, s56, 2
	s_add_u32 s54, s54, 0x100
	s_addc_u32 s55, s55, 0
	s_cmp_gt_u32 s56, 41
	s_mov_b64 s[22:23], s[24:25]
	s_barrier
; __device__ __forceinline__ unsigned cvt_pk_bf16(float lo, float hi) { unsigned r; asm volatile("v_cvt_pk_bf16_f32 %0, %1, %2" : "=v"(r) : "v"(lo), "v"(hi)); return r; }
; __device__ __forceinline__ float bf_lo(unsigned u) { return __uint_as_float(u << 16); }
; __device__ __forceinline__ float bf_hi(unsigned u) { return __uint_as_float(u & 0xffff0000u); }
; #define PG8_WAIT_V(n) asm volatile("s_waitcnt vmcnt(" #n ")" ::: "memory")
; template <class Epi, class Sched>
; __device__ __forceinline__ void gemm_phase(LAS unsigned char* lds, const Gemm g, const Sched& S, const Epi& E) {
;     ...
;             PG8_WAIT_V(6); PG8_BAR; PG8_MMA(1, 1, At, B1); PG8_BAR;
;         }
;         E(acc, cur, wr, wc, fr, fq);
;         if (!has_next) break;
;     __device__ __forceinline__ void operator()(const AccT& acc, const Unit& u, int wr, int wc, int fr, int fq) const {
;     ...
;         const int rowt = u.pm * 256; const int b = rowt >> 11;
;         const bf16_t* res = res_b + (size_t)rowt * DM; bf16_t* out = hb + (size_t)rowt * DM;
;         const int col0 = u.pn * 256 + wc * 32 + 8 * fq;
;         f32x4 gv[2][2];
; #pragma unroll
;         for (int bj = 0; bj < 2; ++bj)
; #pragma unroll
;             for (int n = 0; n < 2; ++n) gv[bj][n] = *(const f32x4*)(gate + (size_t)b * NMOD + col0 + bj * 128 + n * 4) * gs;
;         u32x4 r[2][4][2];
; #pragma unroll
;         for (int ai = 0; ai < 2; ++ai)
; #pragma unroll
;             for (int m = 0; m < 4; ++m)
; #pragma unroll
;                 for (int bj = 0; bj < 2; ++bj) r[ai][m][bj] = *(const u32x4*)(res + (size_t)(wr * 64 + fr + ai * 128 + m * 16) * DM + col0 + bj * 128);
; #pragma unroll
;         for (int ai = 0; ai < 2; ++ai)
; #pragma unroll
;             for (int m = 0; m < 4; ++m)
; #pragma unroll
;                 for (int bj = 0; bj < 2; ++bj) {
;                     const u32x4 q = r[ai][m][bj];
;                     const f32x4 r0 = {bf_lo(q.x), bf_hi(q.x), bf_lo(q.y), bf_hi(q.y)}, r1 = {bf_lo(q.z), bf_hi(q.z), bf_lo(q.w), bf_hi(q.w)};
;                     const f32x4 h0 = r0 + gv[bj][0] * acc[ai][bj][m][0], h1 = r1 + gv[bj][1] * acc[ai][bj][m][1];
;                     u32x4 w; w.x = cvt_pk_bf16(h0[0], h0[1]); w.y = cvt_pk_bf16(h0[2], h0[3]); w.z = cvt_pk_bf16(h1[0], h1[1]); w.w = cvt_pk_bf16(h1[2], h1[3]);
;                     *(u32x4*)(out + (size_t)(wr * 64 + fr + ai * 128 + m * 16) * DM + col0 + bj * 128) = w;
	s_cbranch_scc0 .LBB0_1097
	s_lshl_b32 s25, s52, 8
	v_mov_b32_e32 v140, v239
	v_mov_b32_e32 v128, v238
	s_lshl_b32 s22, s53, 8
	s_ashr_i32 s24, s53, 3
	s_or_b32 s25, s25, s43
	s_ashr_i32 s23, s22, 31
	v_lshl_add_u32 v136, v128, 3, s25
	s_mul_hi_i32 s25, s24, 0x9000
	s_mul_i32 s24, s24, 0x9000
	s_add_u32 s24, s40, s24
	s_addc_u32 s25, s41, s25
	v_ashrrev_i32_e32 v137, 31, v136
	v_lshl_add_u64 v[138:139], v[136:137], 2, s[24:25]
	global_load_dwordx4 v[128:131], v[138:139], off offset:16
	global_load_dwordx4 v[132:135], v[138:139], off
	s_lshl_b64 s[22:23], s[22:23], 11
	s_add_u32 s24, s80, s22
	s_addc_u32 s25, s81, s23
	v_lshlrev_b64 v[226:227], 1, v[136:137]
	s_add_u32 s22, s96, s22
	s_addc_u32 s23, s97, s23
	s_and_b64 vcc, exec, s[2:3]
	s_mov_b32 s52, s50
	s_mov_b32 s53, s51
	s_waitcnt vmcnt(0)
	v_pk_mul_f32 v[216:217], v[130:131], 0.5 op_sel_hi:[1,0]
	v_pk_mul_f32 v[220:221], v[134:135], 0.5 op_sel_hi:[1,0]
	v_pk_mul_f32 v[218:219], v[132:133], 0.5 op_sel_hi:[1,0]
	v_pk_mul_f32 v[214:215], v[128:129], 0.5 op_sel_hi:[1,0]
	global_load_dwordx4 v[128:131], v[138:139], off offset:528
	global_load_dwordx4 v[132:135], v[138:139], off offset:512
	s_waitcnt vmcnt(0)
	v_pk_mul_f32 v[206:207], v[128:129], 0.5 op_sel_hi:[1,0]
	v_add_u32_e32 v128, s42, v140
	v_ashrrev_i32_e32 v129, 31, v128
	v_pk_mul_f32 v[208:209], v[130:131], 0.5 op_sel_hi:[1,0]
	v_lshl_add_u64 v[130:131], s[24:25], 0, v[226:227]
	v_lshlrev_b64 v[248:249], 11, v[128:129]
	v_lshl_add_u64 v[128:129], v[130:131], 0, v[248:249]
	global_load_dwordx4 v[244:247], v[128:129], off
	global_load_dwordx4 v[184:187], v[128:129], off offset:256
	v_lshl_add_u64 v[236:237], v[248:249], 0, s[8:9]
	v_lshl_add_u64 v[128:129], v[130:131], 0, v[236:237]
	global_load_dwordx4 v[180:183], v[128:129], off
	global_load_dwordx4 v[176:179], v[128:129], off offset:256
	v_lshl_add_u64 v[234:235], v[248:249], 0, s[10:11]
	v_lshl_add_u64 v[128:129], v[130:131], 0, v[234:235]
	global_load_dwordx4 v[172:175], v[128:129], off
	global_load_dwordx4 v[168:171], v[128:129], off offset:256
	v_lshl_add_u64 v[232:233], v[248:249], 0, s[12:13]
	v_lshl_add_u64 v[128:129], v[130:131], 0, v[232:233]
	global_load_dwordx4 v[164:167], v[128:129], off
	global_load_dwordx4 v[160:163], v[128:129], off offset:256
	v_lshl_add_u64 v[230:231], v[248:249], 0, s[14:15]
	v_lshl_add_u64 v[128:129], v[130:131], 0, v[230:231]
	global_load_dwordx4 v[156:159], v[128:129], off
	global_load_dwordx4 v[152:155], v[128:129], off offset:256
	v_lshl_add_u64 v[228:229], v[248:249], 0, s[16:17]
	v_lshl_add_u64 v[128:129], v[130:131], 0, v[228:229]
	global_load_dwordx4 v[148:151], v[128:129], off
	global_load_dwordx4 v[144:147], v[128:129], off offset:256
	v_lshl_add_u64 v[224:225], v[248:249], 0, s[18:19]
	v_lshl_add_u64 v[128:129], v[130:131], 0, v[224:225]
	global_load_dwordx4 v[140:143], v[128:129], off
	global_load_dwordx4 v[136:139], v[128:129], off offset:256
	v_lshl_add_u64 v[222:223], v[248:249], 0, s[20:21]
	v_lshl_add_u64 v[128:129], v[130:131], 0, v[222:223]
	v_pk_mul_f32 v[212:213], v[134:135], 0.5 op_sel_hi:[1,0]
	v_pk_mul_f32 v[210:211], v[132:133], 0.5 op_sel_hi:[1,0]
	global_load_dwordx4 v[132:135], v[128:129], off
	s_nop 0
	global_load_dwordx4 v[128:131], v[128:129], off offset:256
	v_lshl_add_u64 v[226:227], s[22:23], 0, v[226:227]
	v_lshl_add_u64 v[248:249], v[226:227], 0, v[248:249]
	s_mov_b64 s[24:25], s[6:7]
	s_mov_b64 s[22:23], s[4:5]
	s_waitcnt vmcnt(0)
	v_lshlrev_b32_e32 v250, 16, v244
	v_and_b32_e32 v251, 0xffff0000, v244
	v_lshlrev_b32_e32 v244, 16, v245
	v_and_b32_e32 v245, 0xffff0000, v245
	v_lshlrev_b32_e32 v252, 16, v246
	v_and_b32_e32 v253, 0xffff0000, v246
	v_lshlrev_b32_e32 v246, 16, v247
	v_and_b32_e32 v247, 0xffff0000, v247
	v_pk_fma_f32 v[126:127], v[126:127], v[220:221], v[244:245]
	v_pk_fma_f32 v[124:125], v[124:125], v[218:219], v[250:251]
	v_pk_fma_f32 v[244:245], v[122:123], v[216:217], v[246:247]
	v_pk_fma_f32 v[122:123], v[120:121], v[214:215], v[252:253]
	v_cvt_pk_bf16_f32 v120, v124, v125
	v_cvt_pk_bf16_f32 v121, v126, v127
	v_lshlrev_b32_e32 v124, 16, v186
	v_cvt_pk_bf16_f32 v122, v122, v123
	v_cvt_pk_bf16_f32 v123, v244, v245
	global_store_dwordx4 v[248:249], v[120:123], off
	v_and_b32_e32 v125, 0xffff0000, v186
	v_lshlrev_b32_e32 v126, 16, v187
	v_lshlrev_b32_e32 v120, 16, v184
	v_and_b32_e32 v121, 0xffff0000, v184
	v_and_b32_e32 v127, 0xffff0000, v187
	v_lshlrev_b32_e32 v122, 16, v185
	v_and_b32_e32 v123, 0xffff0000, v185
	v_pk_fma_f32 v[116:117], v[116:117], v[210:211], v[120:121]
	v_pk_fma_f32 v[120:121], v[114:115], v[208:209], v[126:127]
	v_pk_fma_f32 v[114:115], v[112:113], v[206:207], v[124:125]
	v_pk_fma_f32 v[118:119], v[118:119], v[212:213], v[122:123]
	v_cvt_pk_bf16_f32 v112, v116, v117
	v_lshlrev_b32_e32 v116, 16, v181
	v_cvt_pk_bf16_f32 v113, v118, v119
	v_cvt_pk_bf16_f32 v114, v114, v115
	v_cvt_pk_bf16_f32 v115, v120, v121
	global_store_dwordx4 v[248:249], v[112:115], off offset:256
	v_and_b32_e32 v117, 0xffff0000, v181
	v_lshlrev_b32_e32 v118, 16, v182
	v_lshlrev_b32_e32 v114, 16, v180
	v_and_b32_e32 v115, 0xffff0000, v180
	v_and_b32_e32 v119, 0xffff0000, v182
	v_lshlrev_b32_e32 v120, 16, v183
	v_and_b32_e32 v121, 0xffff0000, v183
	v_lshl_add_u64 v[112:113], v[226:227], 0, v[236:237]
	v_pk_fma_f32 v[110:111], v[110:111], v[220:221], v[116:117]
	v_pk_fma_f32 v[108:109], v[108:109], v[218:219], v[114:115]
	v_pk_fma_f32 v[114:115], v[106:107], v[216:217], v[120:121]
	v_pk_fma_f32 v[106:107], v[104:105], v[214:215], v[118:119]
	v_cvt_pk_bf16_f32 v104, v108, v109
	v_cvt_pk_bf16_f32 v105, v110, v111
	v_lshlrev_b32_e32 v108, 16, v178
	v_cvt_pk_bf16_f32 v106, v106, v107
	v_cvt_pk_bf16_f32 v107, v114, v115
; __device__ __forceinline__ unsigned cvt_pk_bf16(float lo, float hi) { unsigned r; asm volatile("v_cvt_pk_bf16_f32 %0, %1, %2" : "=v"(r) : "v"(lo), "v"(hi)); return r; }
; __device__ __forceinline__ float bf_lo(unsigned u) { return __uint_as_float(u << 16); }
; __device__ __forceinline__ float bf_hi(unsigned u) { return __uint_as_float(u & 0xffff0000u); }
;     __device__ __forceinline__ void operator()(const AccT& acc, const Unit& u, int wr, int wc, int fr, int fq) const {
;     ...
;         for (int ai = 0; ai < 2; ++ai)
; #pragma unroll
;             for (int m = 0; m < 4; ++m)
; #pragma unroll
;                 for (int bj = 0; bj < 2; ++bj) {
;                     const u32x4 q = r[ai][m][bj];
;                     const f32x4 r0 = {bf_lo(q.x), bf_hi(q.x), bf_lo(q.y), bf_hi(q.y)}, r1 = {bf_lo(q.z), bf_hi(q.z), bf_lo(q.w), bf_hi(q.w)};
;                     const f32x4 h0 = r0 + gv[bj][0] * acc[ai][bj][m][0], h1 = r1 + gv[bj][1] * acc[ai][bj][m][1];
;                     u32x4 w; w.x = cvt_pk_bf16(h0[0], h0[1]); w.y = cvt_pk_bf16(h0[2], h0[3]); w.z = cvt_pk_bf16(h1[0], h1[1]); w.w = cvt_pk_bf16(h1[2], h1[3]);
;                     *(u32x4*)(out + (size_t)(wr * 64 + fr + ai * 128 + m * 16) * DM + col0 + bj * 128) = w;
	global_store_dwordx4 v[112:113], v[104:107], off
	v_and_b32_e32 v109, 0xffff0000, v178
	v_lshlrev_b32_e32 v110, 16, v179
	v_lshlrev_b32_e32 v104, 16, v176
	v_and_b32_e32 v105, 0xffff0000, v176
	v_and_b32_e32 v111, 0xffff0000, v179
	v_lshlrev_b32_e32 v106, 16, v177
	v_and_b32_e32 v107, 0xffff0000, v177
	v_pk_fma_f32 v[100:101], v[100:101], v[210:211], v[104:105]
	v_pk_fma_f32 v[104:105], v[98:99], v[208:209], v[110:111]
	v_pk_fma_f32 v[98:99], v[96:97], v[206:207], v[108:109]
	v_pk_fma_f32 v[102:103], v[102:103], v[212:213], v[106:107]
	v_cvt_pk_bf16_f32 v96, v100, v101
	v_lshlrev_b32_e32 v100, 16, v173
	v_cvt_pk_bf16_f32 v97, v102, v103
	v_cvt_pk_bf16_f32 v98, v98, v99
	v_cvt_pk_bf16_f32 v99, v104, v105
	global_store_dwordx4 v[112:113], v[96:99], off offset:256
	v_and_b32_e32 v101, 0xffff0000, v173
	v_lshlrev_b32_e32 v102, 16, v174
	v_lshlrev_b32_e32 v98, 16, v172
	v_and_b32_e32 v99, 0xffff0000, v172
	v_and_b32_e32 v103, 0xffff0000, v174
	v_lshlrev_b32_e32 v104, 16, v175
	v_and_b32_e32 v105, 0xffff0000, v175
	v_lshl_add_u64 v[96:97], v[226:227], 0, v[234:235]
	v_pk_fma_f32 v[94:95], v[94:95], v[220:221], v[100:101]
	v_pk_fma_f32 v[92:93], v[92:93], v[218:219], v[98:99]
	v_pk_fma_f32 v[98:99], v[90:91], v[216:217], v[104:105]
	v_pk_fma_f32 v[90:91], v[88:89], v[214:215], v[102:103]
	v_cvt_pk_bf16_f32 v88, v92, v93
	v_cvt_pk_bf16_f32 v89, v94, v95
	v_lshlrev_b32_e32 v92, 16, v170
	v_cvt_pk_bf16_f32 v90, v90, v91
	v_cvt_pk_bf16_f32 v91, v98, v99
	global_store_dwordx4 v[96:97], v[88:91], off
	v_and_b32_e32 v93, 0xffff0000, v170
	v_lshlrev_b32_e32 v94, 16, v171
	v_lshlrev_b32_e32 v88, 16, v168
	v_and_b32_e32 v89, 0xffff0000, v168
	v_and_b32_e32 v95, 0xffff0000, v171
	v_lshlrev_b32_e32 v90, 16, v169
	v_and_b32_e32 v91, 0xffff0000, v169
	v_pk_fma_f32 v[84:85], v[84:85], v[210:211], v[88:89]
	v_pk_fma_f32 v[88:89], v[82:83], v[208:209], v[94:95]
	v_pk_fma_f32 v[82:83], v[80:81], v[206:207], v[92:93]
	v_pk_fma_f32 v[86:87], v[86:87], v[212:213], v[90:91]
	v_cvt_pk_bf16_f32 v80, v84, v85
	v_lshlrev_b32_e32 v84, 16, v165
	v_cvt_pk_bf16_f32 v81, v86, v87
	v_cvt_pk_bf16_f32 v82, v82, v83
	v_cvt_pk_bf16_f32 v83, v88, v89
	global_store_dwordx4 v[96:97], v[80:83], off offset:256
	v_and_b32_e32 v85, 0xffff0000, v165
	v_lshlrev_b32_e32 v86, 16, v166
	v_lshlrev_b32_e32 v82, 16, v164
	v_and_b32_e32 v83, 0xffff0000, v164
	v_and_b32_e32 v87, 0xffff0000, v166
	v_lshlrev_b32_e32 v88, 16, v167
	v_and_b32_e32 v89, 0xffff0000, v167
	v_lshl_add_u64 v[80:81], v[226:227], 0, v[232:233]
	v_pk_fma_f32 v[78:79], v[78:79], v[220:221], v[84:85]
	v_pk_fma_f32 v[76:77], v[76:77], v[218:219], v[82:83]
	v_pk_fma_f32 v[82:83], v[74:75], v[216:217], v[88:89]
	v_pk_fma_f32 v[74:75], v[72:73], v[214:215], v[86:87]
	v_cvt_pk_bf16_f32 v72, v76, v77
	v_cvt_pk_bf16_f32 v73, v78, v79
	v_lshlrev_b32_e32 v76, 16, v162
	v_cvt_pk_bf16_f32 v74, v74, v75
	v_cvt_pk_bf16_f32 v75, v82, v83
	global_store_dwordx4 v[80:81], v[72:75], off
	v_and_b32_e32 v77, 0xffff0000, v162
	v_lshlrev_b32_e32 v78, 16, v163
	v_lshlrev_b32_e32 v72, 16, v160
	v_and_b32_e32 v73, 0xffff0000, v160
	v_and_b32_e32 v79, 0xffff0000, v163
	v_lshlrev_b32_e32 v74, 16, v161
	v_and_b32_e32 v75, 0xffff0000, v161
	v_pk_fma_f32 v[68:69], v[68:69], v[210:211], v[72:73]
	v_pk_fma_f32 v[72:73], v[66:67], v[208:209], v[78:79]
	v_pk_fma_f32 v[66:67], v[64:65], v[206:207], v[76:77]
	v_pk_fma_f32 v[70:71], v[70:71], v[212:213], v[74:75]
	v_cvt_pk_bf16_f32 v64, v68, v69
	v_lshlrev_b32_e32 v68, 16, v157
	v_cvt_pk_bf16_f32 v65, v70, v71
	v_cvt_pk_bf16_f32 v66, v66, v67
	v_cvt_pk_bf16_f32 v67, v72, v73
	global_store_dwordx4 v[80:81], v[64:67], off offset:256
	v_and_b32_e32 v69, 0xffff0000, v157
	v_lshlrev_b32_e32 v70, 16, v158
	v_lshlrev_b32_e32 v66, 16, v156
	v_and_b32_e32 v67, 0xffff0000, v156
	v_and_b32_e32 v71, 0xffff0000, v158
	v_lshlrev_b32_e32 v72, 16, v159
	v_and_b32_e32 v73, 0xffff0000, v159
	v_lshl_add_u64 v[64:65], v[226:227], 0, v[230:231]
	v_pk_fma_f32 v[62:63], v[62:63], v[220:221], v[68:69]
	v_pk_fma_f32 v[60:61], v[60:61], v[218:219], v[66:67]
	v_pk_fma_f32 v[66:67], v[58:59], v[216:217], v[72:73]
	v_pk_fma_f32 v[58:59], v[56:57], v[214:215], v[70:71]
	v_cvt_pk_bf16_f32 v56, v60, v61
	v_cvt_pk_bf16_f32 v57, v62, v63
	v_lshlrev_b32_e32 v60, 16, v154
	v_cvt_pk_bf16_f32 v58, v58, v59
	v_cvt_pk_bf16_f32 v59, v66, v67
	global_store_dwordx4 v[64:65], v[56:59], off
	v_and_b32_e32 v61, 0xffff0000, v154
	v_lshlrev_b32_e32 v62, 16, v155
	v_lshlrev_b32_e32 v56, 16, v152
	v_and_b32_e32 v57, 0xffff0000, v152
	v_and_b32_e32 v63, 0xffff0000, v155
	v_lshlrev_b32_e32 v58, 16, v153
	v_and_b32_e32 v59, 0xffff0000, v153
	v_pk_fma_f32 v[52:53], v[52:53], v[210:211], v[56:57]
; __device__ __forceinline__ unsigned cvt_pk_bf16(float lo, float hi) { unsigned r; asm volatile("v_cvt_pk_bf16_f32 %0, %1, %2" : "=v"(r) : "v"(lo), "v"(hi)); return r; }
; __device__ __forceinline__ float bf_lo(unsigned u) { return __uint_as_float(u << 16); }
; __device__ __forceinline__ float bf_hi(unsigned u) { return __uint_as_float(u & 0xffff0000u); }
; #define PG8_WAIT_V(n) asm volatile("s_waitcnt vmcnt(" #n ")" ::: "memory")
; #define PG8_BAR __builtin_amdgcn_s_barrier()
; template <class Epi, class Sched>
; __device__ __forceinline__ void gemm_phase(LAS unsigned char* lds, const Gemm g, const Sched& S, const Epi& E) {
;     ...
;         if (!has_next) break;
; #pragma unroll
;         for (int a = 0; a < 2; ++a)
; #pragma unroll
;             for (int b = 0; b < 2; ++b)
; #pragma unroll
;                 for (int m = 0; m < 4; ++m)
; #pragma unroll
;                     for (int n = 0; n < 2; ++n) acc[a][b][m][n] = (f32x4){0.f, 0.f, 0.f, 0.f};
;         cur = nxt; cA = nA; cB = nB; ++ui;
;     }
;     PG8_WAIT_V(0);
;     if (wr == 0) PG8_BAR;
;     PG8_BAR;
;     __device__ __forceinline__ void operator()(const AccT& acc, const Unit& u, int wr, int wc, int fr, int fq) const {
;     ...
;         for (int ai = 0; ai < 2; ++ai)
; #pragma unroll
;             for (int m = 0; m < 4; ++m)
; #pragma unroll
;                 for (int bj = 0; bj < 2; ++bj) {
;                     const u32x4 q = r[ai][m][bj];
;                     const f32x4 r0 = {bf_lo(q.x), bf_hi(q.x), bf_lo(q.y), bf_hi(q.y)}, r1 = {bf_lo(q.z), bf_hi(q.z), bf_lo(q.w), bf_hi(q.w)};
;                     const f32x4 h0 = r0 + gv[bj][0] * acc[ai][bj][m][0], h1 = r1 + gv[bj][1] * acc[ai][bj][m][1];
;                     u32x4 w; w.x = cvt_pk_bf16(h0[0], h0[1]); w.y = cvt_pk_bf16(h0[2], h0[3]); w.z = cvt_pk_bf16(h1[0], h1[1]); w.w = cvt_pk_bf16(h1[2], h1[3]);
;                     *(u32x4*)(out + (size_t)(wr * 64 + fr + ai * 128 + m * 16) * DM + col0 + bj * 128) = w;
	v_pk_fma_f32 v[56:57], v[50:51], v[208:209], v[62:63]
	v_pk_fma_f32 v[50:51], v[48:49], v[206:207], v[60:61]
	v_pk_fma_f32 v[54:55], v[54:55], v[212:213], v[58:59]
	v_cvt_pk_bf16_f32 v48, v52, v53
	v_lshlrev_b32_e32 v52, 16, v149
	v_cvt_pk_bf16_f32 v49, v54, v55
	v_cvt_pk_bf16_f32 v50, v50, v51
	v_cvt_pk_bf16_f32 v51, v56, v57
	global_store_dwordx4 v[64:65], v[48:51], off offset:256
	v_and_b32_e32 v53, 0xffff0000, v149
	v_lshlrev_b32_e32 v54, 16, v150
	v_lshlrev_b32_e32 v50, 16, v148
	v_and_b32_e32 v51, 0xffff0000, v148
	v_and_b32_e32 v55, 0xffff0000, v150
	v_lshlrev_b32_e32 v56, 16, v151
	v_and_b32_e32 v57, 0xffff0000, v151
	v_lshl_add_u64 v[48:49], v[226:227], 0, v[228:229]
	v_pk_fma_f32 v[46:47], v[46:47], v[220:221], v[52:53]
	v_pk_fma_f32 v[44:45], v[44:45], v[218:219], v[50:51]
	v_pk_fma_f32 v[50:51], v[42:43], v[216:217], v[56:57]
	v_pk_fma_f32 v[42:43], v[40:41], v[214:215], v[54:55]
	v_cvt_pk_bf16_f32 v40, v44, v45
	v_cvt_pk_bf16_f32 v41, v46, v47
	v_lshlrev_b32_e32 v44, 16, v146
	v_cvt_pk_bf16_f32 v42, v42, v43
	v_cvt_pk_bf16_f32 v43, v50, v51
	global_store_dwordx4 v[48:49], v[40:43], off
	v_and_b32_e32 v45, 0xffff0000, v146
	v_lshlrev_b32_e32 v46, 16, v147
	v_lshlrev_b32_e32 v40, 16, v144
	v_and_b32_e32 v41, 0xffff0000, v144
	v_and_b32_e32 v47, 0xffff0000, v147
	v_lshlrev_b32_e32 v42, 16, v145
	v_and_b32_e32 v43, 0xffff0000, v145
	v_pk_fma_f32 v[36:37], v[36:37], v[210:211], v[40:41]
	v_pk_fma_f32 v[40:41], v[34:35], v[208:209], v[46:47]
	v_pk_fma_f32 v[34:35], v[32:33], v[206:207], v[44:45]
	v_pk_fma_f32 v[38:39], v[38:39], v[212:213], v[42:43]
	v_cvt_pk_bf16_f32 v32, v36, v37
	v_lshlrev_b32_e32 v36, 16, v141
	v_cvt_pk_bf16_f32 v33, v38, v39
	v_cvt_pk_bf16_f32 v34, v34, v35
	v_cvt_pk_bf16_f32 v35, v40, v41
	global_store_dwordx4 v[48:49], v[32:35], off offset:256
	v_and_b32_e32 v37, 0xffff0000, v141
	v_lshlrev_b32_e32 v38, 16, v142
	v_lshlrev_b32_e32 v34, 16, v140
	v_and_b32_e32 v35, 0xffff0000, v140
	v_and_b32_e32 v39, 0xffff0000, v142
	v_lshlrev_b32_e32 v40, 16, v143
	v_and_b32_e32 v41, 0xffff0000, v143
	v_lshl_add_u64 v[32:33], v[226:227], 0, v[224:225]
	v_pk_fma_f32 v[30:31], v[30:31], v[220:221], v[36:37]
	v_pk_fma_f32 v[28:29], v[28:29], v[218:219], v[34:35]
	v_pk_fma_f32 v[34:35], v[26:27], v[216:217], v[40:41]
	v_pk_fma_f32 v[26:27], v[24:25], v[214:215], v[38:39]
	v_cvt_pk_bf16_f32 v24, v28, v29
	v_cvt_pk_bf16_f32 v25, v30, v31
	v_lshlrev_b32_e32 v28, 16, v138
	v_cvt_pk_bf16_f32 v26, v26, v27
	v_cvt_pk_bf16_f32 v27, v34, v35
	global_store_dwordx4 v[32:33], v[24:27], off
	v_and_b32_e32 v29, 0xffff0000, v138
	v_lshlrev_b32_e32 v30, 16, v139
	v_lshlrev_b32_e32 v24, 16, v136
	v_and_b32_e32 v25, 0xffff0000, v136
	v_and_b32_e32 v31, 0xffff0000, v139
	v_lshlrev_b32_e32 v26, 16, v137
	v_and_b32_e32 v27, 0xffff0000, v137
	v_pk_fma_f32 v[20:21], v[20:21], v[210:211], v[24:25]
	v_pk_fma_f32 v[24:25], v[18:19], v[208:209], v[30:31]
	v_pk_fma_f32 v[18:19], v[16:17], v[206:207], v[28:29]
	v_pk_fma_f32 v[22:23], v[22:23], v[212:213], v[26:27]
	v_cvt_pk_bf16_f32 v16, v20, v21
	v_lshlrev_b32_e32 v20, 16, v133
	v_cvt_pk_bf16_f32 v17, v22, v23
	v_cvt_pk_bf16_f32 v18, v18, v19
	v_cvt_pk_bf16_f32 v19, v24, v25
	global_store_dwordx4 v[32:33], v[16:19], off offset:256
	v_and_b32_e32 v21, 0xffff0000, v133
	v_lshlrev_b32_e32 v22, 16, v134
	v_lshlrev_b32_e32 v18, 16, v132
	v_and_b32_e32 v19, 0xffff0000, v132
	v_and_b32_e32 v23, 0xffff0000, v134
	v_lshlrev_b32_e32 v24, 16, v135
	v_and_b32_e32 v25, 0xffff0000, v135
	v_lshl_add_u64 v[16:17], v[226:227], 0, v[222:223]
	v_pk_fma_f32 v[14:15], v[14:15], v[220:221], v[20:21]
	v_pk_fma_f32 v[12:13], v[12:13], v[218:219], v[18:19]
	v_pk_fma_f32 v[18:19], v[10:11], v[216:217], v[24:25]
	v_pk_fma_f32 v[10:11], v[8:9], v[214:215], v[22:23]
	v_cvt_pk_bf16_f32 v8, v12, v13
	v_cvt_pk_bf16_f32 v9, v14, v15
	v_lshlrev_b32_e32 v12, 16, v130
	v_cvt_pk_bf16_f32 v10, v10, v11
	v_cvt_pk_bf16_f32 v11, v18, v19
	global_store_dwordx4 v[16:17], v[8:11], off
	v_and_b32_e32 v13, 0xffff0000, v130
	v_lshlrev_b32_e32 v14, 16, v131
	v_lshlrev_b32_e32 v8, 16, v128
	v_and_b32_e32 v9, 0xffff0000, v128
	v_and_b32_e32 v15, 0xffff0000, v131
	v_lshlrev_b32_e32 v10, 16, v129
	v_and_b32_e32 v11, 0xffff0000, v129
	v_pk_fma_f32 v[4:5], v[4:5], v[210:211], v[8:9]
	v_pk_fma_f32 v[8:9], v[2:3], v[208:209], v[14:15]
	v_pk_fma_f32 v[2:3], v[0:1], v[206:207], v[12:13]
	v_pk_fma_f32 v[6:7], v[6:7], v[212:213], v[10:11]
	v_cvt_pk_bf16_f32 v0, v4, v5
	s_nop 0
	v_cvt_pk_bf16_f32 v1, v6, v7
	v_cvt_pk_bf16_f32 v2, v2, v3
	v_cvt_pk_bf16_f32 v3, v8, v9
	global_store_dwordx4 v[16:17], v[0:3], off offset:256
	s_cbranch_vccz .LBB0_1086
	s_waitcnt vmcnt(0)
	s_cmpk_gt_u32 s30, 0xff
	s_cbranch_scc1 .LBB0_1101
	s_barrier
